# speedup vs baseline: 1.0233x; 1.0059x over previous
; DEVI int RSI(int row) { return ((row >> 3) << 5) | (row & 7); }
; DEVI float sigmoidf_(float x) { return fminf(__builtin_amdgcn_rcpf(1.f + __builtin_amdgcn_exp2f(-LOG2E * x)), 1.f); }
;     ...
;       for (int ks = 0; ks < nslab; ++ks) {
; #pragma unroll
;         for (int i = 0; i < 4; ++i) {
;           f32x4 a = *(const f32x4*)(tf + (long)ks * MS * DM + (i * 64 + lane) * 8), b = *(const f32x4*)(tf + (long)ks * MS * DM + (i * 64 + lane) * 8 + 4);
; #pragma unroll
;           for (int j = 0; j < 4; ++j) { tv[i * 8 + j] += a[j]; tv[i * 8 + 4 + j] += b[j]; }
;         }
;       }
;       if (Ug) {
;         const float sc = rsg[RSI(row)];
; #pragma unroll
;         for (int i = 0; i < 4; ++i) {
;           const u32x4 w = *reinterpret_cast<const u32x4*>(Ug + (long)row * DM + (i * 64 + lane) * 8);
; #pragma unroll
;           for (int j = 0; j < 4; ++j) { tv[i * 8 + 2 * j] = __uint_as_float(w[j] << 16) * sigmoidf_(tv[i * 8 + 2 * j] * sc);
;             tv[i * 8 + 2 * j + 1] = __uint_as_float(w[j] & 0xffff0000u) * sigmoidf_(tv[i * 8 + 2 * j + 1] * sc); }
;         }
;       }
.LBB0_33:
	v_lshl_add_u64 v[46:47], v[44:45], 0, s[68:69]
	global_load_dwordx4 v[72:75], v[46:47], off
	global_load_dwordx4 v[76:79], v[46:47], off offset:16
	s_add_u32 s68, s68, 0x400000
	s_addc_u32 s69, s69, 0
	s_cmp_lg_u32 s68, 0x2000000
	s_waitcnt vmcnt(0) lgkmcnt(0)
	v_pk_add_f32 v[36:37], v[36:37], v[72:73]
	v_pk_add_f32 v[30:31], v[30:31], v[76:77]
	v_pk_add_f32 v[34:35], v[34:35], v[74:75]
	v_pk_add_f32 v[28:29], v[28:29], v[78:79]
	global_load_dwordx4 v[72:75], v[46:47], off offset:2048
	global_load_dwordx4 v[76:79], v[46:47], off offset:2064
	v_add_co_u32_e32 v46, vcc, s4, v46
	s_waitcnt vmcnt(0) lgkmcnt(0)
	v_pk_add_f32 v[42:43], v[42:43], v[72:73]
	v_addc_co_u32_e32 v47, vcc, 0, v47, vcc
	v_pk_add_f32 v[2:3], v[2:3], v[76:77]
	v_pk_add_f32 v[40:41], v[40:41], v[74:75]
	v_pk_add_f32 v[0:1], v[0:1], v[78:79]
	global_load_dwordx4 v[72:75], v[46:47], off
	global_load_dwordx4 v[76:79], v[46:47], off offset:16
	s_waitcnt vmcnt(0) lgkmcnt(0)
	v_pk_add_f32 v[60:61], v[60:61], v[72:73]
	v_pk_add_f32 v[56:57], v[56:57], v[76:77]
	v_pk_add_f32 v[58:59], v[58:59], v[74:75]
	v_pk_add_f32 v[54:55], v[54:55], v[78:79]
	global_load_dwordx4 v[72:75], v[46:47], off offset:2048
	global_load_dwordx4 v[76:79], v[46:47], off offset:2064
	s_waitcnt vmcnt(0) lgkmcnt(0)
	v_pk_add_f32 v[52:53], v[52:53], v[72:73]
	v_pk_add_f32 v[48:49], v[48:49], v[76:77]
	v_pk_add_f32 v[50:51], v[50:51], v[74:75]
	v_pk_add_f32 v[38:39], v[38:39], v[78:79]
	s_cbranch_scc1 .LBB0_33
	v_lshlrev_b32_e32 v5, 2, v4
	s_mov_b32 s4, 0x7fffffe0
	v_and_or_b32 v44, v5, s4, v70
	v_mov_b32_e32 v45, v33
	v_lshl_add_u64 v[44:45], v[44:45], 2, s[24:25]
	global_load_dword v5, v[44:45], off
	v_lshl_add_u64 v[62:63], v[26:27], 1, v[14:15]
	global_load_dwordx4 v[44:47], v[62:63], off
	s_waitcnt vmcnt(0) lgkmcnt(0)
	v_mul_f32_e32 v21, v36, v5
	v_mul_f32_e32 v21, 0xbfb8aa3b, v21
	v_exp_f32_e32 v21, v21
	v_lshlrev_b32_e32 v72, 16, v44
	v_and_b32_e32 v73, 0xffff0000, v44
	v_mul_f32_e32 v2, v2, v5
	v_add_f32_e32 v21, 1.0, v21
	v_rcp_f32_e32 v21, v21
	v_mul_f32_e32 v3, v3, v5
	v_mul_f32_e32 v2, 0xbfb8aa3b, v2
	v_mul_f32_e32 v3, 0xbfb8aa3b, v3
	v_min_f32_e32 v36, 1.0, v21
	v_mul_f32_e32 v21, v37, v5
	v_mul_f32_e32 v21, 0xbfb8aa3b, v21
	v_exp_f32_e32 v21, v21
	v_mul_f32_e32 v0, v0, v5
	v_mul_f32_e32 v1, v1, v5
	v_exp_f32_e32 v2, v2
	v_add_f32_e32 v21, 1.0, v21
	v_rcp_f32_e32 v21, v21
	v_exp_f32_e32 v3, v3
	v_mul_f32_e32 v0, 0xbfb8aa3b, v0
	v_mul_f32_e32 v1, 0xbfb8aa3b, v1
	v_min_f32_e32 v37, 1.0, v21
	v_mul_f32_e32 v21, v34, v5
	v_mul_f32_e32 v21, 0xbfb8aa3b, v21
	v_exp_f32_e32 v21, v21
	v_pk_mul_f32 v[36:37], v[36:37], v[72:73]
	global_load_dwordx4 v[72:75], v[62:63], off offset:1024
	v_exp_f32_e32 v0, v0
	v_add_f32_e32 v21, 1.0, v21
	v_rcp_f32_e32 v21, v21
	v_exp_f32_e32 v1, v1
	v_lshlrev_b32_e32 v44, 16, v45
	v_and_b32_e32 v45, 0xffff0000, v45
	v_min_f32_e32 v34, 1.0, v21
	v_mul_f32_e32 v21, v35, v5
	v_mul_f32_e32 v21, 0xbfb8aa3b, v21
	v_exp_f32_e32 v21, v21
	v_add_f32_e32 v2, 1.0, v2
	v_add_f32_e32 v3, 1.0, v3
	v_rcp_f32_e32 v2, v2
	v_add_f32_e32 v21, 1.0, v21
	v_rcp_f32_e32 v21, v21
	v_rcp_f32_e32 v3, v3
	v_add_f32_e32 v0, 1.0, v0
	v_add_f32_e32 v1, 1.0, v1
	v_min_f32_e32 v35, 1.0, v21
	v_mul_f32_e32 v21, v30, v5
	v_mul_f32_e32 v21, 0xbfb8aa3b, v21
	v_exp_f32_e32 v21, v21
	v_pk_mul_f32 v[34:35], v[34:35], v[44:45]
	v_lshlrev_b32_e32 v44, 16, v46
	v_and_b32_e32 v45, 0xffff0000, v46
	v_add_f32_e32 v21, 1.0, v21
	v_rcp_f32_e32 v21, v21
	v_rcp_f32_e32 v0, v0
	v_rcp_f32_e32 v1, v1
	v_min_f32_e32 v2, 1.0, v2
	v_min_f32_e32 v30, 1.0, v21
	v_mul_f32_e32 v21, v31, v5
	v_mul_f32_e32 v21, 0xbfb8aa3b, v21
	v_exp_f32_e32 v21, v21
	v_min_f32_e32 v3, 1.0, v3
	v_min_f32_e32 v0, 1.0, v0
	v_min_f32_e32 v1, 1.0, v1
	v_add_f32_e32 v21, 1.0, v21
	v_rcp_f32_e32 v21, v21
	s_nop 0
	v_min_f32_e32 v31, 1.0, v21
	v_mul_f32_e32 v21, v28, v5
	v_mul_f32_e32 v21, 0xbfb8aa3b, v21
	v_exp_f32_e32 v21, v21
	v_pk_mul_f32 v[30:31], v[30:31], v[44:45]
	v_lshlrev_b32_e32 v44, 16, v47
	v_and_b32_e32 v45, 0xffff0000, v47
	v_add_f32_e32 v21, 1.0, v21
	v_rcp_f32_e32 v21, v21
	s_nop 0
	v_min_f32_e32 v28, 1.0, v21
	v_mul_f32_e32 v21, v29, v5
	v_mul_f32_e32 v21, 0xbfb8aa3b, v21
	v_exp_f32_e32 v21, v21
	s_nop 0
	v_add_f32_e32 v21, 1.0, v21
	v_rcp_f32_e32 v21, v21
	s_nop 0
	v_min_f32_e32 v29, 1.0, v21
	v_mul_f32_e32 v21, v42, v5
	v_mul_f32_e32 v21, 0xbfb8aa3b, v21
	v_exp_f32_e32 v21, v21
	v_pk_mul_f32 v[28:29], v[28:29], v[44:45]
	v_add_f32_e32 v21, 1.0, v21
	v_rcp_f32_e32 v21, v21
	s_waitcnt vmcnt(0) lgkmcnt(0)
	v_lshlrev_b32_e32 v44, 16, v72
	v_min_f32_e32 v42, 1.0, v21
	v_mul_f32_e32 v21, v43, v5
	v_mul_f32_e32 v21, 0xbfb8aa3b, v21
	v_exp_f32_e32 v21, v21
	v_and_b32_e32 v45, 0xffff0000, v72
	v_add_f32_e32 v21, 1.0, v21
	v_rcp_f32_e32 v21, v21
	s_nop 0
	v_min_f32_e32 v43, 1.0, v21
	v_mul_f32_e32 v21, v40, v5
	v_mul_f32_e32 v21, 0xbfb8aa3b, v21
	v_exp_f32_e32 v21, v21
	v_pk_mul_f32 v[46:47], v[42:43], v[44:45]
	v_lshlrev_b32_e32 v42, 16, v73
	v_and_b32_e32 v43, 0xffff0000, v73
	v_add_f32_e32 v21, 1.0, v21
	v_rcp_f32_e32 v21, v21
	s_nop 0
	v_min_f32_e32 v40, 1.0, v21
	v_mul_f32_e32 v21, v41, v5
	v_mul_f32_e32 v21, 0xbfb8aa3b, v21
	v_exp_f32_e32 v21, v21
	s_nop 0
	v_add_f32_e32 v21, 1.0, v21
	v_rcp_f32_e32 v21, v21
	s_nop 0
	v_min_f32_e32 v41, 1.0, v21
	v_pk_mul_f32 v[44:45], v[40:41], v[42:43]
	v_lshlrev_b32_e32 v40, 16, v74
	v_and_b32_e32 v41, 0xffff0000, v74
	v_pk_mul_f32 v[42:43], v[2:3], v[40:41]
	v_lshlrev_b32_e32 v2, 16, v75
	v_and_b32_e32 v3, 0xffff0000, v75
	v_pk_mul_f32 v[40:41], v[0:1], v[2:3]
	global_load_dwordx4 v[0:3], v[62:63], off offset:2048
	v_mul_f32_e32 v21, v60, v5
	v_mul_f32_e32 v21, 0xbfb8aa3b, v21
	v_exp_f32_e32 v21, v21
	s_waitcnt vmcnt(0) lgkmcnt(0)
; DEVI int RSI(int row) { return ((row >> 3) << 5) | (row & 7); }
; DEVI float sigmoidf_(float x) { return fminf(__builtin_amdgcn_rcpf(1.f + __builtin_amdgcn_exp2f(-LOG2E * x)), 1.f); }
;     ...
;     if (row < MP || Tf == nullptr) {
; #pragma unroll
;       for (int i = 0; i < 4; ++i) {
;         u32x4 w = *reinterpret_cast<const u32x4*>(tr + (i * 64 + lane) * 8);
; #pragma unroll
;         for (int j = 0; j < 4; ++j) { tv[i * 8 + 2 * j] = __uint_as_float(w[j] << 16); tv[i * 8 + 2 * j + 1] = __uint_as_float(w[j] & 0xffff0000u); }
;       }
;     ...
;       if (Ug) {
;         const float sc = rsg[RSI(row)];
; #pragma unroll
;         for (int i = 0; i < 4; ++i) {
;           const u32x4 w = *reinterpret_cast<const u32x4*>(Ug + (long)row * DM + (i * 64 + lane) * 8);
; #pragma unroll
;           for (int j = 0; j < 4; ++j) { tv[i * 8 + 2 * j] = __uint_as_float(w[j] << 16) * sigmoidf_(tv[i * 8 + 2 * j] * sc);
;             tv[i * 8 + 2 * j + 1] = __uint_as_float(w[j] & 0xffff0000u) * sigmoidf_(tv[i * 8 + 2 * j + 1] * sc); }
;         }
;       }
	v_lshlrev_b32_e32 v72, 16, v0
	v_and_b32_e32 v73, 0xffff0000, v0
	v_mul_f32_e32 v0, v58, v5
	v_mul_f32_e32 v0, 0xbfb8aa3b, v0
	v_exp_f32_e32 v0, v0
	v_add_f32_e32 v21, 1.0, v21
	v_rcp_f32_e32 v21, v21
	v_add_f32_e32 v0, 1.0, v0
	v_rcp_f32_e32 v0, v0
	v_min_f32_e32 v60, 1.0, v21
	v_mul_f32_e32 v21, v61, v5
	v_mul_f32_e32 v21, 0xbfb8aa3b, v21
	v_min_f32_e32 v58, 1.0, v0
	v_mul_f32_e32 v0, v59, v5
	v_mul_f32_e32 v0, 0xbfb8aa3b, v0
	v_exp_f32_e32 v0, v0
	v_exp_f32_e32 v21, v21
	v_add_f32_e32 v0, 1.0, v0
	v_rcp_f32_e32 v0, v0
	v_add_f32_e32 v21, 1.0, v21
	v_rcp_f32_e32 v21, v21
	v_min_f32_e32 v59, 1.0, v0
	v_lshlrev_b32_e32 v0, 16, v1
	v_and_b32_e32 v1, 0xffff0000, v1
	v_pk_mul_f32 v[58:59], v[58:59], v[0:1]
	v_mul_f32_e32 v0, v56, v5
	v_mul_f32_e32 v1, v57, v5
	v_mul_f32_e32 v0, 0xbfb8aa3b, v0
	v_mul_f32_e32 v1, 0xbfb8aa3b, v1
	v_exp_f32_e32 v0, v0
	v_exp_f32_e32 v1, v1
	v_lshlrev_b32_e32 v56, 16, v2
	v_and_b32_e32 v57, 0xffff0000, v2
	v_add_f32_e32 v0, 1.0, v0
	v_add_f32_e32 v1, 1.0, v1
	v_rcp_f32_e32 v0, v0
	v_rcp_f32_e32 v1, v1
	v_lshlrev_b32_e32 v2, 16, v3
	v_and_b32_e32 v3, 0xffff0000, v3
	v_min_f32_e32 v0, 1.0, v0
	v_min_f32_e32 v1, 1.0, v1
	v_pk_mul_f32 v[56:57], v[0:1], v[56:57]
	v_mul_f32_e32 v0, v54, v5
	v_mul_f32_e32 v1, v55, v5
	v_mul_f32_e32 v0, 0xbfb8aa3b, v0
	v_mul_f32_e32 v1, 0xbfb8aa3b, v1
	v_exp_f32_e32 v0, v0
	v_exp_f32_e32 v1, v1
	v_min_f32_e32 v61, 1.0, v21
	v_mul_f32_e32 v21, v52, v5
	v_add_f32_e32 v0, 1.0, v0
	v_add_f32_e32 v1, 1.0, v1
	v_rcp_f32_e32 v0, v0
	v_rcp_f32_e32 v1, v1
	v_mul_f32_e32 v21, 0xbfb8aa3b, v21
	v_exp_f32_e32 v21, v21
	v_min_f32_e32 v0, 1.0, v0
	v_min_f32_e32 v1, 1.0, v1
	v_pk_mul_f32 v[54:55], v[0:1], v[2:3]
	global_load_dwordx4 v[0:3], v[62:63], off offset:3072
	v_add_f32_e32 v21, 1.0, v21
	v_rcp_f32_e32 v21, v21
	v_pk_mul_f32 v[60:61], v[60:61], v[72:73]
	v_min_f32_e32 v52, 1.0, v21
	v_mul_f32_e32 v21, v53, v5
	v_mul_f32_e32 v21, 0xbfb8aa3b, v21
	v_exp_f32_e32 v21, v21
	s_waitcnt vmcnt(0) lgkmcnt(0)
	v_lshlrev_b32_e32 v62, 16, v0
	v_and_b32_e32 v63, 0xffff0000, v0
	v_mul_f32_e32 v0, v50, v5
	v_mul_f32_e32 v0, 0xbfb8aa3b, v0
	v_exp_f32_e32 v0, v0
	v_add_f32_e32 v21, 1.0, v21
	v_rcp_f32_e32 v21, v21
	v_add_f32_e32 v0, 1.0, v0
	v_rcp_f32_e32 v0, v0
	v_min_f32_e32 v53, 1.0, v21
	v_mul_f32_e32 v21, v48, v5
	v_mul_f32_e32 v21, 0xbfb8aa3b, v21
	v_min_f32_e32 v50, 1.0, v0
	v_mul_f32_e32 v0, v51, v5
	v_mul_f32_e32 v0, 0xbfb8aa3b, v0
	v_exp_f32_e32 v0, v0
	v_exp_f32_e32 v21, v21
	v_pk_mul_f32 v[52:53], v[52:53], v[62:63]
	v_add_f32_e32 v0, 1.0, v0
	v_rcp_f32_e32 v0, v0
	v_add_f32_e32 v21, 1.0, v21
	v_rcp_f32_e32 v21, v21
	v_min_f32_e32 v51, 1.0, v0
	v_lshlrev_b32_e32 v0, 16, v1
	v_and_b32_e32 v1, 0xffff0000, v1
	v_pk_mul_f32 v[0:1], v[50:51], v[0:1]
	v_lshlrev_b32_e32 v50, 16, v2
	v_and_b32_e32 v51, 0xffff0000, v2
	v_mul_f32_e32 v2, v38, v5
	v_mul_f32_e32 v2, 0xbfb8aa3b, v2
	v_exp_f32_e32 v2, v2
	v_min_f32_e32 v48, 1.0, v21
	v_mul_f32_e32 v21, v49, v5
	v_mul_f32_e32 v21, 0xbfb8aa3b, v21
	v_add_f32_e32 v2, 1.0, v2
	v_rcp_f32_e32 v2, v2
	v_exp_f32_e32 v21, v21
	v_min_f32_e32 v38, 1.0, v2
	v_mul_f32_e32 v2, v39, v5
	v_mul_f32_e32 v2, 0xbfb8aa3b, v2
	v_exp_f32_e32 v2, v2
	v_add_f32_e32 v21, 1.0, v21
	v_rcp_f32_e32 v21, v21
	v_add_f32_e32 v2, 1.0, v2
	v_rcp_f32_e32 v2, v2
	v_min_f32_e32 v49, 1.0, v21
	v_pk_mul_f32 v[48:49], v[48:49], v[50:51]
	v_min_f32_e32 v39, 1.0, v2
	v_lshlrev_b32_e32 v2, 16, v3
	v_and_b32_e32 v3, 0xffff0000, v3
	v_pk_mul_f32 v[2:3], v[38:39], v[2:3]
.LBB0_35:
	s_andn2_saveexec_b64 s[8:9], s[38:39]
	s_cbranch_execz .LBB0_37
	v_lshl_add_u64 v[28:29], v[26:27], 1, v[6:7]
	global_load_dwordx4 v[0:3], v[28:29], off
	global_load_dwordx4 v[38:41], v[28:29], off offset:1024
	global_load_dwordx4 v[48:51], v[28:29], off offset:2048
	global_load_dwordx4 v[72:75], v[28:29], off offset:3072
	s_waitcnt vmcnt(0) lgkmcnt(0)
	v_lshlrev_b32_e32 v36, 16, v0
	v_and_b32_e32 v37, 0xffff0000, v0
	v_lshlrev_b32_e32 v34, 16, v1
	v_and_b32_e32 v35, 0xffff0000, v1
	v_lshlrev_b32_e32 v30, 16, v2
	v_and_b32_e32 v31, 0xffff0000, v2
	v_lshlrev_b32_e32 v28, 16, v3
	v_and_b32_e32 v29, 0xffff0000, v3
	v_lshlrev_b32_e32 v46, 16, v38
	v_and_b32_e32 v47, 0xffff0000, v38
	v_lshlrev_b32_e32 v44, 16, v39
	v_and_b32_e32 v45, 0xffff0000, v39
	v_lshlrev_b32_e32 v42, 16, v40
	v_and_b32_e32 v43, 0xffff0000, v40
	v_lshlrev_b32_e32 v40, 16, v41
	v_and_b32_e32 v41, 0xffff0000, v41
	v_lshlrev_b32_e32 v60, 16, v48
	v_and_b32_e32 v61, 0xffff0000, v48
	v_lshlrev_b32_e32 v58, 16, v49
	v_and_b32_e32 v59, 0xffff0000, v49
	v_lshlrev_b32_e32 v56, 16, v50
	v_and_b32_e32 v57, 0xffff0000, v50
	v_lshlrev_b32_e32 v54, 16, v51
	v_and_b32_e32 v55, 0xffff0000, v51
	v_lshlrev_b32_e32 v52, 16, v72
	v_and_b32_e32 v53, 0xffff0000, v72
	v_lshlrev_b32_e32 v0, 16, v73
	v_and_b32_e32 v1, 0xffff0000, v73
	v_lshlrev_b32_e32 v48, 16, v74
	v_and_b32_e32 v49, 0xffff0000, v74
	v_lshlrev_b32_e32 v2, 16, v75
	v_and_b32_e32 v3, 0xffff0000, v75
;     ...
; #pragma unroll
;     for (int i = 0; i < 32; ++i) ss += tv[i] * tv[i];
;     ss = wave_sum(ss, lane);
;     const float rs = rsqrtf(ss * (1.f / DM) + EPS);
;     float s2 = 0.f;
; #pragma unroll
;     for (int i = 0; i < 4; ++i) {
;       const int c = (i * 64 + lane) * 8;
;       f32x4 x0, x1;
;       if (xin_b) { const u32x4 w = *reinterpret_cast<const u32x4*>(xin_b + (long)row * DM + c);
;         x0 = f32x4{__uint_as_float(w[0] << 16), __uint_as_float(w[0] & 0xffff0000u), __uint_as_float(w[1] << 16), __uint_as_float(w[1] & 0xffff0000u)};
;         x1 = f32x4{__uint_as_float(w[2] << 16), __uint_as_float(w[2] & 0xffff0000u), __uint_as_float(w[3] << 16), __uint_as_float(w[3] & 0xffff0000u)}; }
;       else { x0 = *(const f32x4*)(xr + c); x1 = *(const f32x4*)(xr + c + 4); }
;       f32x4 g0 = *(const f32x4*)(g + c), g1 = *(const f32x4*)(g + c + 4);
;       f32x4 o0, o1;
; #pragma unroll
;       for (int j = 0; j < 4; ++j) { o0[j] = x0[j] + tv[i * 8 + j] * rs * g0[j]; o1[j] = x1[j] + tv[i * 8 + 4 + j] * rs * g1[j];
;         s2 += o0[j] * o0[j] + o1[j] * o1[j]; }
;       if (y) { *(f32x4*)(y + (long)row * DM + c) = o0; *(f32x4*)(y + (long)row * DM + c + 4) = o1; }
.LBB0_37:
	s_or_b64 exec, exec, s[8:9]
	v_mul_f32_e32 v5, v37, v37
	v_fmac_f32_e32 v5, v36, v36
	v_fmac_f32_e32 v5, v34, v34
	v_fmac_f32_e32 v5, v35, v35
	v_fmac_f32_e32 v5, v30, v30
	v_fmac_f32_e32 v5, v31, v31
	v_fmac_f32_e32 v5, v28, v28
	v_fmac_f32_e32 v5, v29, v29
	v_fmac_f32_e32 v5, v46, v46
	v_fmac_f32_e32 v5, v47, v47
	v_fmac_f32_e32 v5, v44, v44
	v_fmac_f32_e32 v5, v45, v45
	v_fmac_f32_e32 v5, v42, v42
	v_fmac_f32_e32 v5, v43, v43
	v_fmac_f32_e32 v5, v40, v40
	v_fmac_f32_e32 v5, v41, v41
	v_fmac_f32_e32 v5, v60, v60
	v_fmac_f32_e32 v5, v61, v61
	v_fmac_f32_e32 v5, v58, v58
	v_fmac_f32_e32 v5, v59, v59
	v_fmac_f32_e32 v5, v56, v56
	v_fmac_f32_e32 v5, v57, v57
	v_fmac_f32_e32 v5, v54, v54
	v_fmac_f32_e32 v5, v55, v55
	v_fmac_f32_e32 v5, v52, v52
	v_fmac_f32_e32 v5, v53, v53
	v_fmac_f32_e32 v5, v0, v0
	v_fmac_f32_e32 v5, v1, v1
	v_fmac_f32_e32 v5, v48, v48
	v_fmac_f32_e32 v5, v49, v49
	v_fmac_f32_e32 v5, v2, v2
	v_fmac_f32_e32 v5, v3, v3
	s_waitcnt lgkmcnt(0)
	ds_bpermute_b32 v21, v64, v5
	s_andn2_b64 vcc, exec, s[84:85]
	s_waitcnt lgkmcnt(0)
	v_add_f32_e32 v5, v5, v21
	ds_bpermute_b32 v21, v65, v5
	s_waitcnt lgkmcnt(0)
	v_add_f32_e32 v5, v5, v21
	ds_bpermute_b32 v21, v66, v5
	s_waitcnt lgkmcnt(0)
	v_add_f32_e32 v5, v5, v21
	ds_bpermute_b32 v21, v67, v5
	s_waitcnt lgkmcnt(0)
	v_add_f32_e32 v5, v5, v21
	ds_bpermute_b32 v21, v68, v5
	s_waitcnt lgkmcnt(0)
	v_add_f32_e32 v5, v5, v21
	ds_bpermute_b32 v21, v69, v5
	s_cbranch_vccnz .LBB0_30
	v_readlane_b32 s8, v255, 13
	v_readlane_b32 s9, v255, 14
	global_load_dwordx4 v[72:75], v[8:9], off offset:16
	global_load_dwordx4 v[76:79], v[8:9], off
	v_lshl_add_u64 v[50:51], v[26:27], 2, s[8:9]
	v_lshl_add_u64 v[26:27], v[26:27], 1, v[16:17]
	global_load_dwordx4 v[80:83], v[26:27], off
	s_waitcnt lgkmcnt(0)
	v_add_f32_e32 v5, v5, v21
	v_fmamk_f32 v5, v5, 0x3a000000, v186
	s_mov_b32 s4, 0x800000
	v_cmp_gt_f32_e32 vcc, s4, v5
	v_mul_f32_e32 v21, 0x4b800000, v5
	v_mov_b32_e32 v23, v33
	v_cndmask_b32_e32 v5, v5, v21, vcc
	v_rsq_f32_e32 v5, v5
	v_mov_b32_e32 v25, v33
	v_mul_f32_e32 v21, 0x45800000, v5
	v_cndmask_b32_e32 v38, v5, v21, vcc
	v_pk_mul_f32 v[36:37], v[36:37], v[38:39] op_sel_hi:[1,0]
	v_pk_mul_f32 v[34:35], v[34:35], v[38:39] op_sel_hi:[1,0]
	v_mov_b32_e32 v21, v33
	v_pk_mul_f32 v[30:31], v[30:31], v[38:39] op_sel_hi:[1,0]
	v_lshl_add_u64 v[62:63], v[50:51], 0, v[20:21]
	v_pk_mul_f32 v[28:29], v[28:29], v[38:39] op_sel_hi:[1,0]
	v_pk_mul_f32 v[46:47], v[46:47], v[38:39] op_sel_hi:[1,0]
	v_pk_mul_f32 v[44:45], v[44:45], v[38:39] op_sel_hi:[1,0]
	v_pk_mul_f32 v[42:43], v[42:43], v[38:39] op_sel_hi:[1,0]
	v_pk_mul_f32 v[40:41], v[40:41], v[38:39] op_sel_hi:[1,0]
	v_pk_mul_f32 v[0:1], v[0:1], v[38:39] op_sel_hi:[1,0]
	v_pk_mul_f32 v[2:3], v[2:3], v[38:39] op_sel_hi:[1,0]
	s_waitcnt vmcnt(0)
	v_lshlrev_b32_e32 v84, 16, v80
	v_and_b32_e32 v85, 0xffff0000, v80
	v_pk_fma_f32 v[76:77], v[36:37], v[76:77], v[84:85]
	v_lshlrev_b32_e32 v36, 16, v81
	v_and_b32_e32 v37, 0xffff0000, v81
	v_pk_fma_f32 v[78:79], v[34:35], v[78:79], v[36:37]
	v_lshlrev_b32_e32 v34, 16, v82
	v_and_b32_e32 v35, 0xffff0000, v82
	v_pk_fma_f32 v[34:35], v[30:31], v[72:73], v[34:35]
	v_lshlrev_b32_e32 v30, 16, v83
	v_and_b32_e32 v31, 0xffff0000, v83
	v_pk_fma_f32 v[36:37], v[28:29], v[74:75], v[30:31]
	global_store_dwordx4 v[62:63], v[76:79], off
	global_store_dwordx4 v[62:63], v[34:37], off offset:16
	global_load_dwordx4 v[28:31], v[8:9], off offset:2064
	s_nop 0
	global_load_dwordx4 v[34:37], v[8:9], off offset:2048
	global_load_dwordx4 v[72:75], v[26:27], off offset:1024
	s_waitcnt vmcnt(0) lgkmcnt(0)
	v_lshlrev_b32_e32 v76, 16, v72
	v_and_b32_e32 v77, 0xffff0000, v72
	v_pk_fma_f32 v[34:35], v[46:47], v[34:35], v[76:77]
	v_lshlrev_b32_e32 v46, 16, v73
	v_and_b32_e32 v47, 0xffff0000, v73
	v_pk_fma_f32 v[36:37], v[44:45], v[36:37], v[46:47]
	v_lshlrev_b32_e32 v44, 16, v74
	v_and_b32_e32 v45, 0xffff0000, v74
	v_pk_fma_f32 v[28:29], v[42:43], v[28:29], v[44:45]
	v_lshlrev_b32_e32 v42, 16, v75
	v_and_b32_e32 v43, 0xffff0000, v75
	v_pk_fma_f32 v[30:31], v[40:41], v[30:31], v[42:43]
	global_store_dwordx4 v[62:63], v[34:37], off offset:2048
	global_store_dwordx4 v[62:63], v[28:31], off offset:2064
	global_load_dwordx4 v[28:31], v[10:11], off offset:16
	s_nop 0
	global_load_dwordx4 v[34:37], v[10:11], off
	global_load_dwordx4 v[40:43], v[26:27], off offset:2048
	v_pk_mul_f32 v[46:47], v[60:61], v[38:39] op_sel_hi:[1,0]
	v_lshl_add_u64 v[44:45], v[50:51], 0, v[22:23]
	s_waitcnt vmcnt(0) lgkmcnt(0)
	v_lshlrev_b32_e32 v60, 16, v40
	v_and_b32_e32 v61, 0xffff0000, v40
	v_pk_fma_f32 v[34:35], v[46:47], v[34:35], v[60:61]
	v_pk_mul_f32 v[46:47], v[58:59], v[38:39] op_sel_hi:[1,0]
	v_lshlrev_b32_e32 v40, 16, v41
	v_and_b32_e32 v41, 0xffff0000, v41
	v_pk_fma_f32 v[36:37], v[46:47], v[36:37], v[40:41]
	v_pk_mul_f32 v[40:41], v[56:57], v[38:39] op_sel_hi:[1,0]
	v_lshlrev_b32_e32 v46, 16, v42
	v_and_b32_e32 v47, 0xffff0000, v42
	v_pk_fma_f32 v[28:29], v[40:41], v[28:29], v[46:47]
	v_pk_mul_f32 v[40:41], v[54:55], v[38:39] op_sel_hi:[1,0]
	v_lshlrev_b32_e32 v42, 16, v43
	v_and_b32_e32 v43, 0xffff0000, v43
	v_pk_fma_f32 v[30:31], v[40:41], v[30:31], v[42:43]
	global_store_dwordx4 v[44:45], v[34:37], off
	global_store_dwordx4 v[44:45], v[28:31], off offset:16
	global_load_dwordx4 v[28:31], v[12:13], off offset:16
	s_nop 0
	global_load_dwordx4 v[34:37], v[12:13], off
	global_load_dwordx4 v[40:43], v[26:27], off offset:3072
	v_pk_mul_f32 v[26:27], v[52:53], v[38:39] op_sel_hi:[1,0]
	v_lshl_add_u64 v[44:45], v[50:51], 0, v[24:25]
	s_waitcnt vmcnt(0) lgkmcnt(0)
	v_lshlrev_b32_e32 v46, 16, v40
	v_and_b32_e32 v47, 0xffff0000, v40
	v_pk_fma_f32 v[34:35], v[26:27], v[34:35], v[46:47]
	v_lshlrev_b32_e32 v26, 16, v41
	v_and_b32_e32 v27, 0xffff0000, v41
	v_pk_fma_f32 v[36:37], v[0:1], v[36:37], v[26:27]
	v_pk_mul_f32 v[0:1], v[48:49], v[38:39] op_sel_hi:[1,0]
	v_lshlrev_b32_e32 v26, 16, v42
	v_and_b32_e32 v27, 0xffff0000, v42
	v_pk_fma_f32 v[0:1], v[0:1], v[28:29], v[26:27]
	v_lshlrev_b32_e32 v26, 16, v43
	v_and_b32_e32 v27, 0xffff0000, v43
	v_pk_fma_f32 v[2:3], v[2:3], v[30:31], v[26:27]
	global_store_dwordx4 v[44:45], v[34:37], off
	global_store_dwordx4 v[44:45], v[0:3], off offset:16
	s_branch .LBB0_30

;     ...
;     if (row < MP || Tf == nullptr) {
; #pragma unroll
;       for (int i = 0; i < 4; ++i) {
;         u32x4 w = *reinterpret_cast<const u32x4*>(tr + (i * 64 + lane) * 8);
; #pragma unroll
;         for (int j = 0; j < 4; ++j) { tv[i * 8 + 2 * j] = __uint_as_float(w[j] << 16); tv[i * 8 + 2 * j + 1] = __uint_as_float(w[j] & 0xffff0000u); }
;       }
;     ...
;       for (int ks = 0; ks < nslab; ++ks) {
; #pragma unroll
;         for (int i = 0; i < 4; ++i) {
;           f32x4 a = *(const f32x4*)(tf + (long)ks * MS * DM + (i * 64 + lane) * 8), b = *(const f32x4*)(tf + (long)ks * MS * DM + (i * 64 + lane) * 8 + 4);
; #pragma unroll
;           for (int j = 0; j < 4; ++j) { tv[i * 8 + j] += a[j]; tv[i * 8 + 4 + j] += b[j]; }
;         }
;       }
;     ...
; #pragma unroll
;     for (int i = 0; i < 32; ++i) ss += tv[i] * tv[i];
;     ss = wave_sum(ss, lane);
.LBB0_50:
	v_lshl_add_u64 v[82:83], v[12:13], 0, s[8:9]
	v_add_co_u32_e64 v94, s[0:1], s4, v82
	global_load_dwordx4 v[66:69], v[82:83], off offset:2064
	global_load_dwordx4 v[70:73], v[82:83], off offset:2048
	global_load_dwordx4 v[74:77], v[82:83], off
	global_load_dwordx4 v[78:81], v[82:83], off offset:16
	v_addc_co_u32_e64 v95, s[0:1], 0, v83, s[0:1]
	global_load_dwordx4 v[82:85], v[94:95], off offset:2064
	global_load_dwordx4 v[86:89], v[94:95], off offset:2048
	global_load_dwordx4 v[90:93], v[94:95], off offset:16
	s_nop 0
	global_load_dwordx4 v[94:97], v[94:95], off
	s_add_u32 s8, s8, 0x400000
	s_addc_u32 s9, s9, 0
	s_cmp_lg_u32 s8, 0x4000000
	s_waitcnt vmcnt(0) lgkmcnt(0)
	v_pk_add_f32 v[16:17], v[16:17], v[68:69]
	v_pk_add_f32 v[20:21], v[20:21], v[66:67]
	v_pk_add_f32 v[14:15], v[14:15], v[72:73]
	v_pk_add_f32 v[18:19], v[18:19], v[70:71]
	v_pk_add_f32 v[24:25], v[24:25], v[80:81]
	v_pk_add_f32 v[56:57], v[56:57], v[78:79]
	v_pk_add_f32 v[22:23], v[22:23], v[76:77]
	v_pk_add_f32 v[26:27], v[26:27], v[74:75]
	v_pk_add_f32 v[30:31], v[30:31], v[84:85]
	v_pk_add_f32 v[4:5], v[4:5], v[88:89]
	v_pk_add_f32 v[2:3], v[2:3], v[92:93]
	v_pk_add_f32 v[0:1], v[0:1], v[96:97]
	v_pk_add_f32 v[28:29], v[28:29], v[82:83]
	v_pk_add_f32 v[6:7], v[6:7], v[86:87]
	v_pk_add_f32 v[10:11], v[10:11], v[90:91]
	v_pk_add_f32 v[8:9], v[8:9], v[94:95]
	s_cbranch_scc1 .LBB0_50
.LBB0_51:
	s_or_saveexec_b64 s[0:1], s[38:39]
	v_ashrrev_i32_e32 v12, 31, v42
	v_cndmask_b32_e64 v43, 0, v12, s[6:7]
	v_lshlrev_b64 v[12:13], 11, v[42:43]
	s_xor_b64 exec, exec, s[0:1]
	s_cbranch_execz .LBB0_53
	v_lshl_add_u64 v[8:9], v[12:13], 1, v[44:45]
	s_waitcnt lgkmcnt(0)
	global_load_dwordx4 v[0:3], v[8:9], off
	global_load_dwordx4 v[4:7], v[8:9], off offset:1024
	global_load_dwordx4 v[28:31], v[8:9], off offset:2048
	global_load_dwordx4 v[66:69], v[8:9], off offset:3072
	s_waitcnt vmcnt(0) lgkmcnt(0)
	v_lshlrev_b32_e32 v26, 16, v0
	v_and_b32_e32 v27, 0xffff0000, v0
	v_lshlrev_b32_e32 v22, 16, v1
	v_and_b32_e32 v23, 0xffff0000, v1
	v_lshlrev_b32_e32 v56, 16, v2
	v_and_b32_e32 v57, 0xffff0000, v2
	v_lshlrev_b32_e32 v24, 16, v3
	v_and_b32_e32 v25, 0xffff0000, v3
	v_lshlrev_b32_e32 v18, 16, v4
	v_and_b32_e32 v19, 0xffff0000, v4
	v_lshlrev_b32_e32 v14, 16, v5
	v_and_b32_e32 v15, 0xffff0000, v5
	v_lshlrev_b32_e32 v20, 16, v6
	v_and_b32_e32 v21, 0xffff0000, v6
	v_lshlrev_b32_e32 v16, 16, v7
	v_and_b32_e32 v17, 0xffff0000, v7
	v_lshlrev_b32_e32 v8, 16, v28
	v_and_b32_e32 v9, 0xffff0000, v28
	v_lshlrev_b32_e32 v0, 16, v29
	v_and_b32_e32 v1, 0xffff0000, v29
	v_lshlrev_b32_e32 v10, 16, v30
	v_and_b32_e32 v11, 0xffff0000, v30
	v_lshlrev_b32_e32 v2, 16, v31
	v_and_b32_e32 v3, 0xffff0000, v31
	v_lshlrev_b32_e32 v6, 16, v66
	v_and_b32_e32 v7, 0xffff0000, v66
	v_lshlrev_b32_e32 v4, 16, v67
	v_and_b32_e32 v5, 0xffff0000, v67
	v_lshlrev_b32_e32 v28, 16, v68
	v_and_b32_e32 v29, 0xffff0000, v68
	v_lshlrev_b32_e32 v30, 16, v69
	v_and_b32_e32 v31, 0xffff0000, v69
.LBB0_53:
	s_or_b64 exec, exec, s[0:1]
	v_mul_f32_e32 v43, v27, v27
	v_fmac_f32_e32 v43, v26, v26
	v_fmac_f32_e32 v43, v22, v22
	v_fmac_f32_e32 v43, v23, v23
	v_fmac_f32_e32 v43, v56, v56
	v_fmac_f32_e32 v43, v57, v57
	v_fmac_f32_e32 v43, v24, v24
	v_fmac_f32_e32 v43, v25, v25
	v_fmac_f32_e32 v43, v18, v18
	v_fmac_f32_e32 v43, v19, v19
	v_fmac_f32_e32 v43, v14, v14
	v_fmac_f32_e32 v43, v15, v15
	v_fmac_f32_e32 v43, v20, v20
	s_waitcnt lgkmcnt(0)
	v_fmac_f32_e32 v43, v21, v21
	v_fmac_f32_e32 v43, v16, v16
	v_fmac_f32_e32 v43, v17, v17
	v_fmac_f32_e32 v43, v8, v8
	v_fmac_f32_e32 v43, v9, v9
	v_fmac_f32_e32 v43, v0, v0
	v_fmac_f32_e32 v43, v1, v1
	v_fmac_f32_e32 v43, v10, v10
	v_fmac_f32_e32 v43, v11, v11
	v_fmac_f32_e32 v43, v2, v2
	v_fmac_f32_e32 v43, v3, v3
	v_fmac_f32_e32 v43, v6, v6
	v_fmac_f32_e32 v43, v7, v7
	v_fmac_f32_e32 v43, v4, v4
	v_fmac_f32_e32 v43, v5, v5
	v_pk_mul_f32 v[68:69], v[28:29], v[28:29]
	v_pk_mul_f32 v[66:67], v[30:31], v[30:31]
	v_add_f32_e32 v43, v68, v43
	v_add_f32_e32 v43, v69, v43
	v_add_f32_e32 v43, v66, v43
	v_lshl_add_u64 v[12:13], v[12:13], 1, v[52:53]
	v_add_f32_e32 v43, v67, v43
	global_load_dwordx4 v[66:69], v[12:13], off
	ds_bpermute_b32 v65, v58, v43
	s_mov_b32 s0, 0x800000
	s_waitcnt lgkmcnt(0)
	v_add_f32_e32 v43, v43, v65
	ds_bpermute_b32 v65, v59, v43
	s_waitcnt lgkmcnt(0)
	v_add_f32_e32 v43, v43, v65
	ds_bpermute_b32 v65, v60, v43
	s_waitcnt lgkmcnt(0)
	v_add_f32_e32 v43, v43, v65
	ds_bpermute_b32 v65, v61, v43
	s_waitcnt lgkmcnt(0)
	v_add_f32_e32 v43, v43, v65
	ds_bpermute_b32 v65, v62, v43
	s_waitcnt lgkmcnt(0)
	v_add_f32_e32 v43, v43, v65
	ds_bpermute_b32 v65, v63, v43
	s_waitcnt lgkmcnt(0)
	v_add_f32_e32 v43, v43, v65
	v_fmamk_f32 v43, v43, 0x3a000000, v186
	v_cmp_gt_f32_e64 s[0:1], s0, v43
	v_mul_f32_e32 v65, 0x4b800000, v43
	s_waitcnt vmcnt(0)
; DEVI int RSI(int row) { return ((row >> 3) << 5) | (row & 7); }
;     ...
;     const float rs = rsqrtf(ss * (1.f / DM) + EPS);
;     float s2 = 0.f;
; #pragma unroll
;     for (int i = 0; i < 4; ++i) {
;       const int c = (i * 64 + lane) * 8;
;       f32x4 x0, x1;
;       if (xin_b) { const u32x4 w = *reinterpret_cast<const u32x4*>(xin_b + (long)row * DM + c);
;         x0 = f32x4{__uint_as_float(w[0] << 16), __uint_as_float(w[0] & 0xffff0000u), __uint_as_float(w[1] << 16), __uint_as_float(w[1] & 0xffff0000u)};
;         x1 = f32x4{__uint_as_float(w[2] << 16), __uint_as_float(w[2] & 0xffff0000u), __uint_as_float(w[3] << 16), __uint_as_float(w[3] & 0xffff0000u)}; }
;       else { x0 = *(const f32x4*)(xr + c); x1 = *(const f32x4*)(xr + c + 4); }
;       f32x4 g0 = *(const f32x4*)(g + c), g1 = *(const f32x4*)(g + c + 4);
;       f32x4 o0, o1;
; #pragma unroll
;       for (int j = 0; j < 4; ++j) { o0[j] = x0[j] + tv[i * 8 + j] * rs * g0[j]; o1[j] = x1[j] + tv[i * 8 + 4 + j] * rs * g1[j];
;         s2 += o0[j] * o0[j] + o1[j] * o1[j]; }
;       if (y) { *(f32x4*)(y + (long)row * DM + c) = o0; *(f32x4*)(y + (long)row * DM + c + 4) = o1; }
;       if (yb) { u32x4 w = {cvtpk(o0[0], o0[1]), cvtpk(o0[2], o0[3]), cvtpk(o1[0], o1[1]), cvtpk(o1[2], o1[3])};
;         *reinterpret_cast<u32x4*>(yb + (long)row * DM + c) = w; }
;     }
;     if (rs_out) { s2 = wave_sum(s2, lane); if (lane == 0) rs_out[RSI(row)] = rsqrtf(s2 * (1.f / DM) + EPS); }
	v_lshlrev_b32_e32 v70, 16, v67
	v_cndmask_b32_e64 v43, v43, v65, s[0:1]
	v_rsq_f32_e32 v43, v43
	v_lshlrev_b32_e32 v71, 16, v68
	v_and_b32_e32 v68, 0xffff0000, v68
	v_and_b32_e32 v67, 0xffff0000, v67
	v_mul_f32_e32 v65, 0x45800000, v43
	v_cndmask_b32_e64 v43, v43, v65, s[0:1]
	v_lshlrev_b32_e32 v65, 16, v66
	v_and_b32_e32 v66, 0xffff0000, v66
	v_mul_f32_e32 v26, v26, v43
	v_mul_f32_e32 v27, v27, v43
	v_fmac_f32_e32 v65, v34, v26
	v_mul_f32_e32 v26, v56, v43
	v_fmac_f32_e32 v66, v35, v27
	v_mul_f32_e32 v27, v57, v43
	v_mul_f32_e32 v22, v22, v43
	v_lshlrev_b32_e32 v72, 16, v69
	v_fmac_f32_e32 v71, v38, v26
	v_fmac_f32_e32 v68, v39, v27
	v_fmac_f32_e32 v70, v36, v22
	v_mul_f32_e32 v22, v24, v43
	v_mul_f32_e32 v23, v23, v43
	v_and_b32_e32 v69, 0xffff0000, v69
	v_mul_f32_e32 v26, v71, v71
	v_mul_f32_e32 v27, v68, v68
	v_fmac_f32_e32 v72, v40, v22
	v_fmac_f32_e32 v67, v37, v23
	v_mul_f32_e32 v23, v25, v43
	v_fmac_f32_e32 v26, v65, v65
	v_fmac_f32_e32 v27, v66, v66
	v_mul_f32_e32 v22, v72, v72
	v_fmac_f32_e32 v69, v41, v23
	v_add_f32_e32 v26, v26, v27
	v_fmac_f32_e32 v22, v70, v70
	v_mul_f32_e32 v23, v69, v69
	v_add_f32_e32 v22, v22, v26
	v_fmac_f32_e32 v23, v67, v67
	v_add_f32_e32 v26, v23, v22
	v_cvt_pk_bf16_f32 v22, v65, v66
	v_cvt_pk_bf16_f32 v23, v70, v67
	v_cvt_pk_bf16_f32 v24, v71, v68
	v_cvt_pk_bf16_f32 v25, v72, v69
	global_store_dwordx4 v[12:13], v[22:25], off
	global_load_dwordx4 v[22:25], v[12:13], off offset:1024
	v_mul_f32_e32 v18, v18, v43
	v_mul_f32_e32 v19, v19, v43
	v_mul_f32_e32 v14, v14, v43
	v_mul_f32_e32 v15, v15, v43
	v_mul_f32_e32 v8, v8, v43
	v_mul_f32_e32 v9, v9, v43
	v_mul_f32_e32 v0, v0, v43
	v_mul_f32_e32 v1, v1, v43
	v_mul_f32_e32 v6, v6, v43
	s_waitcnt vmcnt(0) lgkmcnt(0)
	v_lshlrev_b32_e32 v27, 16, v22
	v_and_b32_e32 v56, 0xffff0000, v22
	v_lshlrev_b32_e32 v57, 16, v23
	v_and_b32_e32 v65, 0xffff0000, v23
	v_lshlrev_b32_e32 v70, 16, v24
	v_and_b32_e32 v71, 0xffff0000, v24
	v_lshlrev_b32_e32 v72, 16, v25
	v_and_b32_e32 v73, 0xffff0000, v25
	global_load_dwordx4 v[22:25], v[46:47], off offset:2064
	global_load_dwordx4 v[66:69], v[46:47], off offset:2048
	s_waitcnt vmcnt(0)
	v_fmac_f32_e32 v27, v66, v18
	v_mul_f32_e32 v18, v20, v43
	v_fmac_f32_e32 v70, v22, v18
	v_fmac_f32_e32 v56, v67, v19
	v_mul_f32_e32 v19, v21, v43
	v_mul_f32_e32 v18, v70, v70
	v_fmac_f32_e32 v71, v23, v19
	v_fmac_f32_e32 v57, v68, v14
	v_mul_f32_e32 v14, v16, v43
	v_fmac_f32_e32 v18, v27, v27
	v_mul_f32_e32 v19, v71, v71
	v_fmac_f32_e32 v72, v24, v14
	v_fmac_f32_e32 v65, v69, v15
	v_mul_f32_e32 v15, v17, v43
	v_add_f32_e32 v18, v18, v26
	v_fmac_f32_e32 v19, v56, v56
	v_mul_f32_e32 v14, v72, v72
	v_fmac_f32_e32 v73, v25, v15
	v_add_f32_e32 v18, v19, v18
	v_fmac_f32_e32 v14, v57, v57
	v_mul_f32_e32 v15, v73, v73
	v_add_f32_e32 v14, v14, v18
	v_fmac_f32_e32 v15, v65, v65
	v_add_f32_e32 v22, v15, v14
	v_cvt_pk_bf16_f32 v14, v27, v56
	v_cvt_pk_bf16_f32 v15, v57, v65
	v_cvt_pk_bf16_f32 v16, v70, v71
	v_cvt_pk_bf16_f32 v17, v72, v73
	global_store_dwordx4 v[12:13], v[14:17], off offset:1024
	global_load_dwordx4 v[14:17], v[12:13], off offset:2048
	s_waitcnt vmcnt(0) lgkmcnt(0)
	v_lshlrev_b32_e32 v23, 16, v14
	v_and_b32_e32 v24, 0xffff0000, v14
	v_lshlrev_b32_e32 v25, 16, v15
	v_and_b32_e32 v26, 0xffff0000, v15
	v_lshlrev_b32_e32 v27, 16, v16
	v_and_b32_e32 v56, 0xffff0000, v16
	v_lshlrev_b32_e32 v57, 16, v17
	v_and_b32_e32 v65, 0xffff0000, v17
	global_load_dwordx4 v[14:17], v[48:49], off offset:16
	global_load_dwordx4 v[18:21], v[48:49], off
	s_waitcnt vmcnt(0)
	v_fmac_f32_e32 v23, v18, v8
	v_mul_f32_e32 v8, v10, v43
	v_fmac_f32_e32 v27, v14, v8
	v_fmac_f32_e32 v24, v19, v9
	v_mul_f32_e32 v9, v11, v43
	v_mul_f32_e32 v8, v27, v27
	v_fmac_f32_e32 v56, v15, v9
	v_fmac_f32_e32 v25, v20, v0
	v_mul_f32_e32 v0, v2, v43
	v_fmac_f32_e32 v8, v23, v23
	v_mul_f32_e32 v9, v56, v56
	v_fmac_f32_e32 v57, v16, v0
	v_fmac_f32_e32 v26, v21, v1
	v_mul_f32_e32 v1, v3, v43
	v_add_f32_e32 v8, v8, v22
	v_fmac_f32_e32 v9, v24, v24
	v_mul_f32_e32 v0, v57, v57
	v_fmac_f32_e32 v65, v17, v1
	v_add_f32_e32 v8, v9, v8
	v_fmac_f32_e32 v0, v25, v25
	v_mul_f32_e32 v1, v65, v65
	v_add_f32_e32 v0, v0, v8
	v_fmac_f32_e32 v1, v26, v26
	v_add_f32_e32 v14, v1, v0
	v_cvt_pk_bf16_f32 v0, v23, v24
	v_cvt_pk_bf16_f32 v1, v25, v26
	v_cvt_pk_bf16_f32 v2, v27, v56
	v_cvt_pk_bf16_f32 v3, v57, v65
	global_store_dwordx4 v[12:13], v[0:3], off offset:2048
	global_load_dwordx4 v[0:3], v[12:13], off offset:3072
	s_waitcnt vmcnt(0) lgkmcnt(0)
	v_lshlrev_b32_e32 v15, 16, v0
	v_and_b32_e32 v16, 0xffff0000, v0
	v_lshlrev_b32_e32 v17, 16, v1
	v_and_b32_e32 v18, 0xffff0000, v1
	v_lshlrev_b32_e32 v19, 16, v2
	v_and_b32_e32 v20, 0xffff0000, v2
	v_lshlrev_b32_e32 v21, 16, v3
	v_and_b32_e32 v22, 0xffff0000, v3
	global_load_dwordx4 v[0:3], v[50:51], off offset:16
	global_load_dwordx4 v[8:11], v[50:51], off
	s_waitcnt vmcnt(0)
	v_fmac_f32_e32 v15, v8, v6
	v_mul_f32_e32 v6, v28, v43
	v_fmac_f32_e32 v19, v0, v6
	v_mul_f32_e32 v6, v7, v43
	v_fmac_f32_e32 v16, v9, v6
	v_mul_f32_e32 v6, v29, v43
	v_mul_f32_e32 v0, v19, v19
	v_fmac_f32_e32 v20, v1, v6
	v_fmac_f32_e32 v0, v15, v15
	v_mul_f32_e32 v1, v20, v20
	v_add_f32_e32 v0, v0, v14
	v_fmac_f32_e32 v1, v16, v16
	v_add_f32_e32 v0, v1, v0
	v_mul_f32_e32 v1, v4, v43
	v_fmac_f32_e32 v17, v10, v1
	v_mul_f32_e32 v1, v30, v43
	v_fmac_f32_e32 v21, v2, v1
	v_mul_f32_e32 v1, v21, v21
	v_fmac_f32_e32 v1, v17, v17
	v_add_f32_e32 v0, v1, v0
	v_mul_f32_e32 v1, v5, v43
	v_fmac_f32_e32 v18, v11, v1
	v_mul_f32_e32 v1, v31, v43
	v_fmac_f32_e32 v22, v3, v1
	v_mul_f32_e32 v1, v22, v22
	v_fmac_f32_e32 v1, v18, v18
	v_add_f32_e32 v4, v1, v0
	v_cvt_pk_bf16_f32 v0, v15, v16
	v_cvt_pk_bf16_f32 v1, v17, v18
	v_cvt_pk_bf16_f32 v2, v19, v20
	v_cvt_pk_bf16_f32 v3, v21, v22
	global_store_dwordx4 v[12:13], v[0:3], off offset:3072
	ds_bpermute_b32 v0, v58, v4
	s_waitcnt lgkmcnt(0)
	v_add_f32_e32 v0, v4, v0
	ds_bpermute_b32 v1, v59, v0
	s_waitcnt lgkmcnt(0)
	v_add_f32_e32 v0, v0, v1
	ds_bpermute_b32 v1, v60, v0
	s_waitcnt lgkmcnt(0)
	v_add_f32_e32 v0, v0, v1
	ds_bpermute_b32 v1, v61, v0
	s_waitcnt lgkmcnt(0)
	v_add_f32_e32 v0, v0, v1
	ds_bpermute_b32 v1, v62, v0
	s_waitcnt lgkmcnt(0)
	v_add_f32_e32 v0, v0, v1
	ds_bpermute_b32 v1, v63, v0
	s_and_saveexec_b64 s[6:7], vcc
	s_cbranch_execz .LBB0_47
	s_waitcnt lgkmcnt(0)
	v_add_f32_e32 v0, v0, v1
	v_fmamk_f32 v0, v0, 0x3a000000, v186
	s_mov_b32 s0, 0x800000
	v_mul_f32_e32 v1, 0x4b800000, v0
	v_cmp_gt_f32_e64 s[0:1], s0, v0
	s_movk_i32 s4, 0xffe0
	s_nop 0
	v_cndmask_b32_e64 v0, v0, v1, s[0:1]
	v_rsq_f32_e32 v1, v0
	v_lshlrev_b32_e32 v0, 2, v42
	v_and_or_b32 v0, v0, s4, v64
	v_mul_f32_e32 v2, 0x45800000, v1
	v_cndmask_b32_e64 v2, v1, v2, s[0:1]
	v_ashrrev_i32_e32 v1, 31, v0
	v_lshl_add_u64 v[0:1], v[0:1], 2, s[16:17]
	global_store_dword v[0:1], v2, off
	s_branch .LBB0_47
; DEVI float sigmoidf_(float x) { return fminf(__builtin_amdgcn_rcpf(1.f + __builtin_amdgcn_exp2f(-LOG2E * x)), 1.f); }
; #define EPI_HALF(AI, ...) _Pragma("unroll") for(int bj=0;bj<2;++bj) _Pragma("unroll") for(int m=0;m<4;++m) _Pragma("unroll") for(int n=0;n<2;++n) { \
;     const int ai=(AI); const int row=brow+ai*128+wr*64+m*16+fq*4; const int col=bcol+bj*128+wc*32+n*16+fr; \
;     f32x4& v=acc[ai][bj][m][n]; __VA_ARGS__ }
; #define EPI_SC4(ARR) float sc4[2][2]; _Pragma("unroll") for(int bj=0;bj<2;++bj) _Pragma("unroll") for(int n=0;n<2;++n) sc4[bj][n]=(ARR)[RSI(bcol+bj*128+wc*32+n*16+fr)];
; DEVI void run_phase(const int ph, const Params& P, char* shmc, const int wave_u) {
;     ...
;       EPI_SC4(rs2)
; #pragma unroll
;       for (int ah = 0; ah < 2; ++ah) {
;         u32x2 uu[2][4][2];
;         EPI_HALF(ah, { (void)v; uu[bj][m][n] = *reinterpret_cast<const u32x2*>(ub + (long)col * 2048 + row); })
;         EPI_HALF(ah, { const float sc = sc4[bj][n]; const u32x2 u = uu[bj][m][n];
;           st_bf4(T + (long)col * 2048 + row, __uint_as_float(u[0] << 16) * sigmoidf_(v[0] * sc), __uint_as_float(u[0] & 0xffff0000u) * sigmoidf_(v[1] * sc),
;                  __uint_as_float(u[1] << 16) * sigmoidf_(v[2] * sc), __uint_as_float(u[1] & 0xffff0000u) * sigmoidf_(v[3] * sc)); })
.LBB0_55:
	s_or_b64 exec, exec, s[8:9]
	v_mbcnt_lo_u32_b32 v222, -1, 0
	v_mbcnt_hi_u32_b32 v222, -1, v222
	v_bfe_u32 v222, v222, 4, 1
	v_mul_u32_u24_e32 v222, 24, v222
	v_mov_b32_e32 v223, 0
	v_mbcnt_lo_u32_b32 v131, -1, 0
	v_mbcnt_hi_u32_b32 v131, -1, v131
	s_movk_i32 s1, 0xfda0
	v_or_b32_e32 v134, s5, v131
	v_lshrrev_b32_e32 v130, 1, v134
	v_and_b32_e32 v32, 15, v131
	v_and_b32_e32 v130, 0x60, v130
	v_or3_b32 v130, v32, v130, s6
	v_and_b32_e32 v32, 7, v131
	v_lshlrev_b32_e32 v132, 2, v130
	v_and_or_b32 v132, v132, s1, v32
	v_ashrrev_i32_e32 v133, 31, v132
	v_lshl_add_u64 v[132:133], v[132:133], 2, s[24:25]
	global_load_dword v194, v[132:133], off
	global_load_dword v193, v[132:133], off offset:256
	global_load_dword v192, v[132:133], off offset:2048
	global_load_dword v32, v[132:133], off offset:2304
	v_ashrrev_i32_e32 v132, 2, v134
	v_and_b32_e32 v132, 0xffffffc0, v132
	v_add_u32_e32 v132, s0, v132
	v_lshrrev_b32_e32 v131, 2, v131
	v_and_or_b32 v138, v131, 12, v132
	v_ashrrev_i32_e32 v139, 31, v138
	v_ashrrev_i32_e32 v131, 31, v130
	v_lshlrev_b64 v[166:167], 1, v[138:139]
	v_lshlrev_b64 v[136:137], 12, v[130:131]
	v_lshl_add_u64 v[142:143], s[82:83], 0, v[166:167]
	v_lshl_add_u64 v[134:135], v[142:143], 0, v[136:137]
	global_load_dwordx2 v[180:181], v[134:135], off
	v_or_b32_e32 v134, 16, v130
	v_ashrrev_i32_e32 v135, 31, v134
	v_lshlrev_b64 v[134:135], 12, v[134:135]
	v_lshl_add_u64 v[140:141], v[142:143], 0, v[134:135]
	global_load_dwordx2 v[178:179], v[140:141], off
	v_or_b32_e32 v140, 16, v138
	v_ashrrev_i32_e32 v141, 31, v140
	v_lshl_add_u64 v[148:149], s[82:83], 0, v[136:137]
	v_lshlrev_b64 v[152:153], 1, v[140:141]
	v_lshl_add_u64 v[140:141], v[148:149], 0, v[152:153]
	global_load_dwordx2 v[176:177], v[140:141], off
	v_lshl_add_u64 v[150:151], s[82:83], 0, v[134:135]
	v_lshl_add_u64 v[140:141], v[150:151], 0, v[152:153]
	global_load_dwordx2 v[174:175], v[140:141], off
	v_or_b32_e32 v140, 32, v138
	v_ashrrev_i32_e32 v141, 31, v140
	v_lshlrev_b64 v[144:145], 1, v[140:141]
	v_lshl_add_u64 v[140:141], v[148:149], 0, v[144:145]
	global_load_dwordx2 v[172:173], v[140:141], off
	v_lshl_add_u64 v[140:141], v[150:151], 0, v[144:145]
	v_or_b32_e32 v132, 48, v138
	global_load_dwordx2 v[170:171], v[140:141], off
	v_ashrrev_i32_e32 v133, 31, v132
	v_lshlrev_b64 v[140:141], 1, v[132:133]
	v_lshl_add_u64 v[132:133], v[148:149], 0, v[140:141]
	global_load_dwordx2 v[168:169], v[132:133], off
	v_lshl_add_u64 v[132:133], v[150:151], 0, v[140:141]
	global_load_dwordx2 v[164:165], v[132:133], off
	v_or_b32_e32 v132, 0x80, v130
	v_ashrrev_i32_e32 v133, 31, v132
	v_lshlrev_b64 v[132:133], 12, v[132:133]
	v_lshl_add_u64 v[148:149], v[142:143], 0, v[132:133]
	global_load_dwordx2 v[162:163], v[148:149], off
	v_or_b32_e32 v130, 0x90, v130
	v_ashrrev_i32_e32 v131, 31, v130
	v_lshlrev_b64 v[130:131], 12, v[130:131]
	v_lshl_add_u64 v[142:143], v[142:143], 0, v[130:131]
	global_load_dwordx2 v[160:161], v[142:143], off
	v_lshl_add_u64 v[142:143], s[82:83], 0, v[132:133]
	v_lshl_add_u64 v[148:149], v[142:143], 0, v[152:153]
	global_load_dwordx2 v[158:159], v[148:149], off
	v_lshl_add_u64 v[182:183], s[82:83], 0, v[130:131]
	v_lshl_add_u64 v[148:149], v[182:183], 0, v[152:153]
	global_load_dwordx2 v[156:157], v[148:149], off
	v_lshl_add_u64 v[148:149], v[142:143], 0, v[144:145]
	global_load_dwordx2 v[154:155], v[148:149], off
	v_lshl_add_u64 v[148:149], v[182:183], 0, v[144:145]
	global_load_dwordx2 v[150:151], v[148:149], off
	v_lshl_add_u64 v[142:143], v[142:143], 0, v[140:141]
	global_load_dwordx2 v[148:149], v[142:143], off
	v_lshl_add_u64 v[142:143], v[182:183], 0, v[140:141]
	global_load_dwordx2 v[142:143], v[142:143], off
	v_lshl_add_u64 v[166:167], s[12:13], 0, v[166:167]
	v_lshl_add_u64 v[182:183], v[166:167], 0, v[136:137]
	v_readlane_b32 s0, v254, 26
	s_add_i32 s84, s84, s0
	s_cmpk_gt_i32 s84, 0x1ff
	v_readlane_b32 s1, v254, 27
	s_waitcnt vmcnt(0) lgkmcnt(0)
	v_mul_f32_e32 v126, v126, v194
	v_mul_f32_e32 v126, 0xbfb8aa3b, v126
	v_mul_f32_e32 v127, v127, v194
	v_exp_f32_e32 v126, v126
	v_mul_f32_e32 v127, 0xbfb8aa3b, v127
	v_mul_f32_e32 v128, v128, v194
	v_exp_f32_e32 v127, v127
	v_mul_f32_e32 v128, 0xbfb8aa3b, v128
	v_mul_f32_e32 v129, v129, v194
	v_exp_f32_e32 v128, v128
	v_mul_f32_e32 v129, 0xbfb8aa3b, v129
	v_mul_f32_e32 v122, v122, v193
	v_exp_f32_e32 v129, v129
	v_mul_f32_e32 v122, 0xbfb8aa3b, v122
	v_mul_f32_e32 v123, v123, v193
	v_add_f32_e32 v126, 1.0, v126
	v_exp_f32_e32 v122, v122
	v_mul_f32_e32 v123, 0xbfb8aa3b, v123
	v_mul_f32_e32 v124, v124, v193
	v_rcp_f32_e32 v126, v126
	v_add_f32_e32 v127, 1.0, v127
	v_exp_f32_e32 v123, v123
	v_mul_f32_e32 v124, 0xbfb8aa3b, v124
	v_mul_f32_e32 v125, v125, v193
	v_rcp_f32_e32 v127, v127
	v_add_f32_e32 v128, 1.0, v128
	v_exp_f32_e32 v124, v124
	v_mul_f32_e32 v125, 0xbfb8aa3b, v125
	v_mul_f32_e32 v118, v118, v194
	v_rcp_f32_e32 v128, v128
	v_add_f32_e32 v129, 1.0, v129
	v_exp_f32_e32 v125, v125
	v_mul_f32_e32 v118, 0xbfb8aa3b, v118
	v_mul_f32_e32 v119, v119, v194
	v_rcp_f32_e32 v129, v129
	v_add_f32_e32 v122, 1.0, v122
	v_exp_f32_e32 v118, v118
	v_mul_f32_e32 v119, 0xbfb8aa3b, v119
	v_mul_f32_e32 v120, v120, v194
	v_lshlrev_b32_e32 v139, 16, v180
	v_min_f32_e32 v126, 1.0, v126
	v_rcp_f32_e32 v122, v122
	v_add_f32_e32 v123, 1.0, v123
	v_exp_f32_e32 v119, v119
	v_mul_f32_e32 v120, 0xbfb8aa3b, v120
	v_mul_f32_e32 v121, v121, v194
	v_mul_f32_e32 v126, v126, v139
	v_and_b32_e32 v139, 0xffff0000, v180
	v_min_f32_e32 v127, 1.0, v127
	v_rcp_f32_e32 v123, v123
	v_add_f32_e32 v124, 1.0, v124
	v_exp_f32_e32 v120, v120
	v_mul_f32_e32 v121, 0xbfb8aa3b, v121
	v_mul_f32_e32 v114, v114, v193
	v_mul_f32_e32 v127, v127, v139
; DEVI float sigmoidf_(float x) { return fminf(__builtin_amdgcn_rcpf(1.f + __builtin_amdgcn_exp2f(-LOG2E * x)), 1.f); }
; #define EPI_HALF(AI, ...) _Pragma("unroll") for(int bj=0;bj<2;++bj) _Pragma("unroll") for(int m=0;m<4;++m) _Pragma("unroll") for(int n=0;n<2;++n) { \
;     const int ai=(AI); const int row=brow+ai*128+wr*64+m*16+fq*4; const int col=bcol+bj*128+wc*32+n*16+fr; \
;     f32x4& v=acc[ai][bj][m][n]; __VA_ARGS__ }
; DEVI void run_phase(const int ph, const Params& P, char* shmc, const int wave_u) {
;     ...
;         EPI_HALF(ah, { const float sc = sc4[bj][n]; const u32x2 u = uu[bj][m][n];
;           st_bf4(T + (long)col * 2048 + row, __uint_as_float(u[0] << 16) * sigmoidf_(v[0] * sc), __uint_as_float(u[0] & 0xffff0000u) * sigmoidf_(v[1] * sc),
;                  __uint_as_float(u[1] << 16) * sigmoidf_(v[2] * sc), __uint_as_float(u[1] & 0xffff0000u) * sigmoidf_(v[3] * sc)); })
	v_lshlrev_b32_e32 v139, 16, v181
	v_min_f32_e32 v128, 1.0, v128
	v_rcp_f32_e32 v124, v124
	v_add_f32_e32 v125, 1.0, v125
	v_exp_f32_e32 v121, v121
	v_mul_f32_e32 v114, 0xbfb8aa3b, v114
	v_mul_f32_e32 v115, v115, v193
	v_mul_f32_e32 v128, v128, v139
	v_and_b32_e32 v139, 0xffff0000, v181
	v_min_f32_e32 v129, 1.0, v129
	v_rcp_f32_e32 v125, v125
	v_add_f32_e32 v118, 1.0, v118
	v_exp_f32_e32 v114, v114
	v_mul_f32_e32 v115, 0xbfb8aa3b, v115
	v_mul_f32_e32 v116, v116, v193
	v_mul_f32_e32 v129, v129, v139
	v_cvt_pk_bf16_f32 v126, v126, v127
	v_cvt_pk_bf16_f32 v127, v128, v129
	v_lshlrev_b32_e32 v128, 16, v178
	v_min_f32_e32 v122, 1.0, v122
	v_rcp_f32_e32 v118, v118
	v_add_f32_e32 v119, 1.0, v119
	v_exp_f32_e32 v115, v115
	v_mul_f32_e32 v116, 0xbfb8aa3b, v116
	v_mul_f32_e32 v117, v117, v193
	v_mul_f32_e32 v122, v122, v128
	v_and_b32_e32 v128, 0xffff0000, v178
	v_min_f32_e32 v123, 1.0, v123
	v_rcp_f32_e32 v119, v119
	v_add_f32_e32 v120, 1.0, v120
	v_exp_f32_e32 v116, v116
	v_mul_f32_e32 v117, 0xbfb8aa3b, v117
	v_mul_f32_e32 v110, v110, v194
	v_mul_f32_e32 v123, v123, v128
	v_lshlrev_b32_e32 v128, 16, v179
	v_min_f32_e32 v124, 1.0, v124
	v_rcp_f32_e32 v120, v120
	v_add_f32_e32 v121, 1.0, v121
	v_exp_f32_e32 v117, v117
	v_mul_f32_e32 v110, 0xbfb8aa3b, v110
	v_mul_f32_e32 v111, v111, v194
	v_mov_b32_e32 v196, v126
	v_mov_b32_e32 v197, v127
	v_lshl_add_u64 v[212:213], v[182:183], 0, v[222:223]
	v_lshl_add_u64 v[126:127], v[166:167], 0, v[134:135]
	v_mul_f32_e32 v124, v124, v128
	v_and_b32_e32 v128, 0xffff0000, v179
	v_min_f32_e32 v125, 1.0, v125
	v_rcp_f32_e32 v121, v121
	v_add_f32_e32 v114, 1.0, v114
	v_exp_f32_e32 v110, v110
	v_mul_f32_e32 v111, 0xbfb8aa3b, v111
	v_mul_f32_e32 v112, v112, v194
	v_mul_f32_e32 v125, v125, v128
	v_cvt_pk_bf16_f32 v122, v122, v123
	v_cvt_pk_bf16_f32 v123, v124, v125
	v_mov_b32_e32 v200, v122
	v_mov_b32_e32 v201, v123
	v_lshl_add_u64 v[216:217], v[126:127], 0, v[222:223]
	v_lshlrev_b32_e32 v126, 16, v176
	v_min_f32_e32 v118, 1.0, v118
	v_rcp_f32_e32 v114, v114
	v_add_f32_e32 v115, 1.0, v115
	v_exp_f32_e32 v111, v111
	v_mul_f32_e32 v112, 0xbfb8aa3b, v112
	v_mul_f32_e32 v113, v113, v194
	v_mul_f32_e32 v118, v118, v126
	v_and_b32_e32 v126, 0xffff0000, v176
	v_min_f32_e32 v119, 1.0, v119
	v_rcp_f32_e32 v115, v115
	v_add_f32_e32 v116, 1.0, v116
	v_exp_f32_e32 v112, v112
	v_mul_f32_e32 v113, 0xbfb8aa3b, v113
	v_mul_f32_e32 v106, v106, v193
	v_lshl_add_u64 v[122:123], s[12:13], 0, v[136:137]
	v_mul_f32_e32 v119, v119, v126
	v_lshlrev_b32_e32 v126, 16, v177
	v_min_f32_e32 v120, 1.0, v120
	v_rcp_f32_e32 v116, v116
	v_add_f32_e32 v117, 1.0, v117
	v_exp_f32_e32 v113, v113
	v_mul_f32_e32 v106, 0xbfb8aa3b, v106
	v_mul_f32_e32 v107, v107, v193
	v_lshl_add_u64 v[124:125], v[122:123], 0, v[152:153]
	v_mul_f32_e32 v120, v120, v126
	v_and_b32_e32 v126, 0xffff0000, v177
	v_min_f32_e32 v121, 1.0, v121
	v_rcp_f32_e32 v117, v117
	v_add_f32_e32 v110, 1.0, v110
	v_exp_f32_e32 v106, v106
	v_mul_f32_e32 v107, 0xbfb8aa3b, v107
	v_mul_f32_e32 v108, v108, v193
	v_mul_f32_e32 v121, v121, v126
	v_cvt_pk_bf16_f32 v118, v118, v119
	v_cvt_pk_bf16_f32 v119, v120, v121
	v_mov_b32_e32 v198, v118
	v_mov_b32_e32 v199, v119
	s_nop 1
	v_permlane16_swap_b32_e32 v196, v198
	v_permlane16_swap_b32_e32 v197, v199
	global_store_dwordx4 v[212:213], v[196:199], off
	v_lshlrev_b32_e32 v124, 16, v174
	v_min_f32_e32 v114, 1.0, v114
	v_rcp_f32_e32 v110, v110
	v_add_f32_e32 v111, 1.0, v111
	v_exp_f32_e32 v107, v107
	v_mul_f32_e32 v108, 0xbfb8aa3b, v108
	v_mul_f32_e32 v109, v109, v193
	v_mul_f32_e32 v114, v114, v124
	v_and_b32_e32 v124, 0xffff0000, v174
	v_min_f32_e32 v115, 1.0, v115
	v_rcp_f32_e32 v111, v111
	v_add_f32_e32 v112, 1.0, v112
	v_exp_f32_e32 v108, v108
	v_mul_f32_e32 v109, 0xbfb8aa3b, v109
	v_mul_f32_e32 v102, v102, v194
	v_mul_f32_e32 v115, v115, v124
	v_lshlrev_b32_e32 v124, 16, v175
	v_min_f32_e32 v116, 1.0, v116
	v_rcp_f32_e32 v112, v112
	v_add_f32_e32 v113, 1.0, v113
	v_exp_f32_e32 v109, v109
	v_mul_f32_e32 v102, 0xbfb8aa3b, v102
	v_mul_f32_e32 v103, v103, v194
	v_mul_f32_e32 v116, v116, v124
	v_and_b32_e32 v124, 0xffff0000, v175
	v_min_f32_e32 v117, 1.0, v117
	v_rcp_f32_e32 v113, v113
	v_add_f32_e32 v106, 1.0, v106
	v_exp_f32_e32 v102, v102
	v_mul_f32_e32 v103, 0xbfb8aa3b, v103
	v_mul_f32_e32 v104, v104, v194
	v_mul_f32_e32 v117, v117, v124
	v_cvt_pk_bf16_f32 v114, v114, v115
	v_cvt_pk_bf16_f32 v115, v116, v117
	v_lshlrev_b32_e32 v116, 16, v172
	v_min_f32_e32 v110, 1.0, v110
	v_rcp_f32_e32 v106, v106
	v_add_f32_e32 v107, 1.0, v107
	v_exp_f32_e32 v103, v103
	v_mul_f32_e32 v104, 0xbfb8aa3b, v104
	v_mul_f32_e32 v105, v105, v194
	v_mul_f32_e32 v110, v110, v116
	v_and_b32_e32 v116, 0xffff0000, v172
	v_min_f32_e32 v111, 1.0, v111
	v_rcp_f32_e32 v107, v107
	v_add_f32_e32 v108, 1.0, v108
	v_exp_f32_e32 v104, v104
	v_mul_f32_e32 v105, 0xbfb8aa3b, v105
	v_mul_f32_e32 v98, v98, v193
	v_lshl_add_u64 v[118:119], s[12:13], 0, v[134:135]
	v_mul_f32_e32 v111, v111, v116
	v_lshlrev_b32_e32 v116, 16, v173
	v_min_f32_e32 v112, 1.0, v112
	v_rcp_f32_e32 v108, v108
	v_add_f32_e32 v109, 1.0, v109
	v_exp_f32_e32 v105, v105
	v_mul_f32_e32 v98, 0xbfb8aa3b, v98
	v_mul_f32_e32 v99, v99, v193
	v_lshl_add_u64 v[120:121], v[118:119], 0, v[152:153]
	v_mul_f32_e32 v112, v112, v116
	v_and_b32_e32 v116, 0xffff0000, v173
	v_min_f32_e32 v113, 1.0, v113
	v_rcp_f32_e32 v109, v109
	v_add_f32_e32 v102, 1.0, v102
	v_exp_f32_e32 v98, v98
	v_mul_f32_e32 v99, 0xbfb8aa3b, v99
	v_mul_f32_e32 v100, v100, v193
	v_mov_b32_e32 v202, v114
	v_mov_b32_e32 v203, v115
	s_nop 1
	v_permlane16_swap_b32_e32 v200, v202
	v_permlane16_swap_b32_e32 v201, v203
	global_store_dwordx4 v[216:217], v[200:203], off
; DEVI float sigmoidf_(float x) { return fminf(__builtin_amdgcn_rcpf(1.f + __builtin_amdgcn_exp2f(-LOG2E * x)), 1.f); }
; #define EPI_HALF(AI, ...) _Pragma("unroll") for(int bj=0;bj<2;++bj) _Pragma("unroll") for(int m=0;m<4;++m) _Pragma("unroll") for(int n=0;n<2;++n) { \
;     const int ai=(AI); const int row=brow+ai*128+wr*64+m*16+fq*4; const int col=bcol+bj*128+wc*32+n*16+fr; \
;     f32x4& v=acc[ai][bj][m][n]; __VA_ARGS__ }
; DEVI void run_phase(const int ph, const Params& P, char* shmc, const int wave_u) {
;     ...
;         EPI_HALF(ah, { const float sc = sc4[bj][n]; const u32x2 u = uu[bj][m][n];
;           st_bf4(T + (long)col * 2048 + row, __uint_as_float(u[0] << 16) * sigmoidf_(v[0] * sc), __uint_as_float(u[0] & 0xffff0000u) * sigmoidf_(v[1] * sc),
;                  __uint_as_float(u[1] << 16) * sigmoidf_(v[2] * sc), __uint_as_float(u[1] & 0xffff0000u) * sigmoidf_(v[3] * sc)); })
	v_mul_f32_e32 v113, v113, v116
	v_cvt_pk_bf16_f32 v110, v110, v111
	v_cvt_pk_bf16_f32 v111, v112, v113
	v_lshlrev_b32_e32 v112, 16, v170
	v_min_f32_e32 v106, 1.0, v106
	v_rcp_f32_e32 v102, v102
	v_add_f32_e32 v103, 1.0, v103
	v_exp_f32_e32 v99, v99
	v_mul_f32_e32 v100, 0xbfb8aa3b, v100
	v_mul_f32_e32 v101, v101, v193
	v_mul_f32_e32 v106, v106, v112
	v_and_b32_e32 v112, 0xffff0000, v170
	v_min_f32_e32 v107, 1.0, v107
	v_rcp_f32_e32 v103, v103
	v_add_f32_e32 v104, 1.0, v104
	v_exp_f32_e32 v100, v100
	v_mul_f32_e32 v101, 0xbfb8aa3b, v101
	v_mul_f32_e32 v94, v94, v192
	v_mul_f32_e32 v107, v107, v112
	v_lshlrev_b32_e32 v112, 16, v171
	v_min_f32_e32 v108, 1.0, v108
	v_rcp_f32_e32 v104, v104
	v_add_f32_e32 v105, 1.0, v105
	v_exp_f32_e32 v101, v101
	v_mul_f32_e32 v94, 0xbfb8aa3b, v94
	v_mul_f32_e32 v95, v95, v192
	v_lshl_add_u64 v[114:115], v[122:123], 0, v[144:145]
	v_mul_f32_e32 v108, v108, v112
	v_and_b32_e32 v112, 0xffff0000, v171
	v_min_f32_e32 v109, 1.0, v109
	v_rcp_f32_e32 v105, v105
	v_add_f32_e32 v98, 1.0, v98
	v_exp_f32_e32 v94, v94
	v_mul_f32_e32 v95, 0xbfb8aa3b, v95
	v_mul_f32_e32 v96, v96, v192
	v_mov_b32_e32 v204, v110
	v_mov_b32_e32 v205, v111
	v_lshl_add_u64 v[218:219], v[114:115], 0, v[222:223]
	v_mul_f32_e32 v109, v109, v112
	v_cvt_pk_bf16_f32 v106, v106, v107
	v_cvt_pk_bf16_f32 v107, v108, v109
	v_lshlrev_b32_e32 v108, 16, v168
	v_min_f32_e32 v102, 1.0, v102
	v_rcp_f32_e32 v98, v98
	v_add_f32_e32 v99, 1.0, v99
	v_exp_f32_e32 v95, v95
	v_mul_f32_e32 v96, 0xbfb8aa3b, v96
	v_mul_f32_e32 v97, v97, v192
	v_mul_f32_e32 v102, v102, v108
	v_and_b32_e32 v108, 0xffff0000, v168
	v_min_f32_e32 v103, 1.0, v103
	v_rcp_f32_e32 v99, v99
	v_add_f32_e32 v100, 1.0, v100
	v_exp_f32_e32 v96, v96
	v_mul_f32_e32 v97, 0xbfb8aa3b, v97
	v_mul_f32_e32 v90, v90, v32
	v_mul_f32_e32 v103, v103, v108
	v_lshlrev_b32_e32 v108, 16, v169
	v_min_f32_e32 v104, 1.0, v104
	v_rcp_f32_e32 v100, v100
	v_add_f32_e32 v101, 1.0, v101
	v_exp_f32_e32 v97, v97
	v_mul_f32_e32 v90, 0xbfb8aa3b, v90
	v_mul_f32_e32 v91, v91, v32
	v_lshl_add_u64 v[110:111], v[118:119], 0, v[144:145]
	v_mul_f32_e32 v104, v104, v108
	v_and_b32_e32 v108, 0xffff0000, v169
	v_min_f32_e32 v105, 1.0, v105
	v_rcp_f32_e32 v101, v101
	v_add_f32_e32 v94, 1.0, v94
	v_exp_f32_e32 v90, v90
	v_mul_f32_e32 v91, 0xbfb8aa3b, v91
	v_mul_f32_e32 v92, v92, v32
	v_mov_b32_e32 v208, v106
	v_mov_b32_e32 v209, v107
	v_lshl_add_u64 v[220:221], v[110:111], 0, v[222:223]
	v_mul_f32_e32 v105, v105, v108
	v_cvt_pk_bf16_f32 v102, v102, v103
	v_cvt_pk_bf16_f32 v103, v104, v105
	v_lshlrev_b32_e32 v104, 16, v164
	v_min_f32_e32 v98, 1.0, v98
	v_rcp_f32_e32 v94, v94
	v_add_f32_e32 v95, 1.0, v95
	v_exp_f32_e32 v91, v91
	v_mul_f32_e32 v92, 0xbfb8aa3b, v92
	v_mul_f32_e32 v93, v93, v32
	v_mul_f32_e32 v98, v98, v104
	v_and_b32_e32 v104, 0xffff0000, v164
	v_min_f32_e32 v99, 1.0, v99
	v_rcp_f32_e32 v95, v95
	v_add_f32_e32 v96, 1.0, v96
	v_exp_f32_e32 v92, v92
	v_mul_f32_e32 v93, 0xbfb8aa3b, v93
	v_mul_f32_e32 v86, v86, v192
	v_mul_f32_e32 v99, v99, v104
	v_lshlrev_b32_e32 v104, 16, v165
	v_min_f32_e32 v100, 1.0, v100
	v_rcp_f32_e32 v96, v96
	v_add_f32_e32 v97, 1.0, v97
	v_exp_f32_e32 v93, v93
	v_mul_f32_e32 v86, 0xbfb8aa3b, v86
	v_mul_f32_e32 v87, v87, v192
	v_lshl_add_u64 v[106:107], v[122:123], 0, v[140:141]
	v_mul_f32_e32 v100, v100, v104
	v_and_b32_e32 v104, 0xffff0000, v165
	v_min_f32_e32 v101, 1.0, v101
	v_rcp_f32_e32 v97, v97
	v_add_f32_e32 v90, 1.0, v90
	v_exp_f32_e32 v86, v86
	v_mul_f32_e32 v87, 0xbfb8aa3b, v87
	v_mul_f32_e32 v88, v88, v192
	v_mov_b32_e32 v206, v102
	v_mov_b32_e32 v207, v103
	s_nop 1
	v_permlane16_swap_b32_e32 v204, v206
	v_permlane16_swap_b32_e32 v205, v207
	global_store_dwordx4 v[218:219], v[204:207], off
	v_mul_f32_e32 v101, v101, v104
	v_cvt_pk_bf16_f32 v98, v98, v99
	v_cvt_pk_bf16_f32 v99, v100, v101
	v_lshlrev_b32_e32 v100, 16, v162
	v_min_f32_e32 v94, 1.0, v94
	v_rcp_f32_e32 v90, v90
	v_add_f32_e32 v91, 1.0, v91
	v_exp_f32_e32 v87, v87
	v_mul_f32_e32 v88, 0xbfb8aa3b, v88
	v_mul_f32_e32 v89, v89, v192
	v_mul_f32_e32 v94, v94, v100
	v_and_b32_e32 v100, 0xffff0000, v162
	v_min_f32_e32 v95, 1.0, v95
	v_rcp_f32_e32 v91, v91
	v_add_f32_e32 v92, 1.0, v92
	v_exp_f32_e32 v88, v88
	v_mul_f32_e32 v89, 0xbfb8aa3b, v89
	v_mul_f32_e32 v82, v82, v32
	v_mul_f32_e32 v95, v95, v100
	v_lshlrev_b32_e32 v100, 16, v163
	v_min_f32_e32 v96, 1.0, v96
	v_rcp_f32_e32 v92, v92
	v_add_f32_e32 v93, 1.0, v93
	v_exp_f32_e32 v89, v89
	v_mul_f32_e32 v82, 0xbfb8aa3b, v82
	v_mul_f32_e32 v83, v83, v32
	v_lshl_add_u64 v[102:103], v[118:119], 0, v[140:141]
	v_mul_f32_e32 v96, v96, v100
	v_and_b32_e32 v100, 0xffff0000, v163
	v_min_f32_e32 v97, 1.0, v97
	v_rcp_f32_e32 v93, v93
	v_add_f32_e32 v86, 1.0, v86
	v_exp_f32_e32 v82, v82
	v_mul_f32_e32 v83, 0xbfb8aa3b, v83
	v_mul_f32_e32 v84, v84, v32
	v_mov_b32_e32 v210, v98
	v_mov_b32_e32 v211, v99
	s_nop 1
	v_permlane16_swap_b32_e32 v208, v210
	v_permlane16_swap_b32_e32 v209, v211
	global_store_dwordx4 v[220:221], v[208:211], off
	v_mul_f32_e32 v97, v97, v100
	v_cvt_pk_bf16_f32 v94, v94, v95
	v_cvt_pk_bf16_f32 v95, v96, v97
	v_lshlrev_b32_e32 v96, 16, v160
	v_min_f32_e32 v90, 1.0, v90
	v_rcp_f32_e32 v86, v86
	v_add_f32_e32 v87, 1.0, v87
	v_exp_f32_e32 v83, v83
	v_mul_f32_e32 v84, 0xbfb8aa3b, v84
	v_mul_f32_e32 v85, v85, v32
	v_mul_f32_e32 v90, v90, v96
	v_and_b32_e32 v96, 0xffff0000, v160
	v_min_f32_e32 v91, 1.0, v91
	v_rcp_f32_e32 v87, v87
	v_add_f32_e32 v88, 1.0, v88
	v_exp_f32_e32 v84, v84
	v_mul_f32_e32 v85, 0xbfb8aa3b, v85
	v_mul_f32_e32 v78, v78, v192
	v_lshl_add_u64 v[98:99], v[166:167], 0, v[132:133]
	v_mul_f32_e32 v91, v91, v96
	v_lshlrev_b32_e32 v96, 16, v161
	v_min_f32_e32 v92, 1.0, v92
; DEVI float sigmoidf_(float x) { return fminf(__builtin_amdgcn_rcpf(1.f + __builtin_amdgcn_exp2f(-LOG2E * x)), 1.f); }
; #define EPI_HALF(AI, ...) _Pragma("unroll") for(int bj=0;bj<2;++bj) _Pragma("unroll") for(int m=0;m<4;++m) _Pragma("unroll") for(int n=0;n<2;++n) { \
;     const int ai=(AI); const int row=brow+ai*128+wr*64+m*16+fq*4; const int col=bcol+bj*128+wc*32+n*16+fr; \
;     f32x4& v=acc[ai][bj][m][n]; __VA_ARGS__ }
; DEVI void run_phase(const int ph, const Params& P, char* shmc, const int wave_u) {
;     ...
;         EPI_HALF(ah, { const float sc = sc4[bj][n]; const u32x2 u = uu[bj][m][n];
;           st_bf4(T + (long)col * 2048 + row, __uint_as_float(u[0] << 16) * sigmoidf_(v[0] * sc), __uint_as_float(u[0] & 0xffff0000u) * sigmoidf_(v[1] * sc),
;                  __uint_as_float(u[1] << 16) * sigmoidf_(v[2] * sc), __uint_as_float(u[1] & 0xffff0000u) * sigmoidf_(v[3] * sc)); })
	v_rcp_f32_e32 v88, v88
	v_add_f32_e32 v89, 1.0, v89
	v_exp_f32_e32 v85, v85
	v_mul_f32_e32 v78, 0xbfb8aa3b, v78
	v_mul_f32_e32 v79, v79, v192
	v_mov_b32_e32 v196, v94
	v_mov_b32_e32 v197, v95
	v_lshl_add_u64 v[212:213], v[98:99], 0, v[222:223]
	v_lshl_add_u64 v[94:95], v[166:167], 0, v[130:131]
	v_mul_f32_e32 v92, v92, v96
	v_and_b32_e32 v96, 0xffff0000, v161
	v_min_f32_e32 v93, 1.0, v93
	v_rcp_f32_e32 v89, v89
	v_add_f32_e32 v82, 1.0, v82
	v_exp_f32_e32 v78, v78
	v_mul_f32_e32 v79, 0xbfb8aa3b, v79
	v_mul_f32_e32 v80, v80, v192
	v_mul_f32_e32 v93, v93, v96
	v_cvt_pk_bf16_f32 v90, v90, v91
	v_cvt_pk_bf16_f32 v91, v92, v93
	v_mov_b32_e32 v200, v90
	v_mov_b32_e32 v201, v91
	v_lshl_add_u64 v[216:217], v[94:95], 0, v[222:223]
	v_lshlrev_b32_e32 v94, 16, v158
	v_min_f32_e32 v86, 1.0, v86
	v_rcp_f32_e32 v82, v82
	v_add_f32_e32 v83, 1.0, v83
	v_exp_f32_e32 v79, v79
	v_mul_f32_e32 v80, 0xbfb8aa3b, v80
	v_mul_f32_e32 v81, v81, v192
	v_mul_f32_e32 v86, v86, v94
	v_and_b32_e32 v94, 0xffff0000, v158
	v_min_f32_e32 v87, 1.0, v87
	v_rcp_f32_e32 v83, v83
	v_add_f32_e32 v84, 1.0, v84
	v_exp_f32_e32 v80, v80
	v_mul_f32_e32 v81, 0xbfb8aa3b, v81
	v_mul_f32_e32 v74, v74, v32
	v_lshl_add_u64 v[90:91], s[12:13], 0, v[132:133]
	v_mul_f32_e32 v87, v87, v94
	v_lshlrev_b32_e32 v94, 16, v159
	v_min_f32_e32 v88, 1.0, v88
	v_rcp_f32_e32 v84, v84
	v_add_f32_e32 v85, 1.0, v85
	v_exp_f32_e32 v81, v81
	v_mul_f32_e32 v74, 0xbfb8aa3b, v74
	v_mul_f32_e32 v75, v75, v32
	v_lshl_add_u64 v[92:93], v[90:91], 0, v[152:153]
	v_mul_f32_e32 v88, v88, v94
	v_and_b32_e32 v94, 0xffff0000, v159
	v_min_f32_e32 v89, 1.0, v89
	v_rcp_f32_e32 v85, v85
	v_add_f32_e32 v78, 1.0, v78
	v_exp_f32_e32 v74, v74
	v_mul_f32_e32 v75, 0xbfb8aa3b, v75
	v_mul_f32_e32 v76, v76, v32
	v_mul_f32_e32 v89, v89, v94
	v_cvt_pk_bf16_f32 v86, v86, v87
	v_cvt_pk_bf16_f32 v87, v88, v89
	v_mov_b32_e32 v198, v86
	v_mov_b32_e32 v199, v87
	s_nop 1
	v_permlane16_swap_b32_e32 v196, v198
	v_permlane16_swap_b32_e32 v197, v199
	global_store_dwordx4 v[212:213], v[196:199], off
	v_lshlrev_b32_e32 v92, 16, v156
	v_min_f32_e32 v82, 1.0, v82
	v_rcp_f32_e32 v78, v78
	v_add_f32_e32 v79, 1.0, v79
	v_exp_f32_e32 v75, v75
	v_mul_f32_e32 v76, 0xbfb8aa3b, v76
	v_mul_f32_e32 v77, v77, v32
	v_mul_f32_e32 v82, v82, v92
	v_and_b32_e32 v92, 0xffff0000, v156
	v_min_f32_e32 v83, 1.0, v83
	v_rcp_f32_e32 v79, v79
	v_add_f32_e32 v80, 1.0, v80
	v_exp_f32_e32 v76, v76
	v_mul_f32_e32 v77, 0xbfb8aa3b, v77
	v_mul_f32_e32 v70, v70, v192
	v_mul_f32_e32 v83, v83, v92
	v_lshlrev_b32_e32 v92, 16, v157
	v_min_f32_e32 v84, 1.0, v84
	v_rcp_f32_e32 v80, v80
	v_add_f32_e32 v81, 1.0, v81
	v_exp_f32_e32 v77, v77
	v_mul_f32_e32 v70, 0xbfb8aa3b, v70
	v_mul_f32_e32 v71, v71, v192
	v_mul_f32_e32 v84, v84, v92
	v_and_b32_e32 v92, 0xffff0000, v157
	v_min_f32_e32 v85, 1.0, v85
	v_rcp_f32_e32 v81, v81
	v_add_f32_e32 v74, 1.0, v74
	v_exp_f32_e32 v70, v70
	v_mul_f32_e32 v71, 0xbfb8aa3b, v71
	v_mul_f32_e32 v72, v72, v192
	v_mul_f32_e32 v85, v85, v92
	v_cvt_pk_bf16_f32 v82, v82, v83
	v_cvt_pk_bf16_f32 v83, v84, v85
	v_lshlrev_b32_e32 v84, 16, v154
	v_min_f32_e32 v78, 1.0, v78
	v_rcp_f32_e32 v74, v74
	v_add_f32_e32 v75, 1.0, v75
	v_exp_f32_e32 v71, v71
	v_mul_f32_e32 v72, 0xbfb8aa3b, v72
	v_mul_f32_e32 v73, v73, v192
	v_mul_f32_e32 v78, v78, v84
	v_and_b32_e32 v84, 0xffff0000, v154
	v_min_f32_e32 v79, 1.0, v79
	v_rcp_f32_e32 v75, v75
	v_add_f32_e32 v76, 1.0, v76
	v_exp_f32_e32 v72, v72
	v_mul_f32_e32 v73, 0xbfb8aa3b, v73
	v_mul_f32_e32 v66, v66, v32
	v_lshl_add_u64 v[86:87], s[12:13], 0, v[130:131]
	v_mul_f32_e32 v79, v79, v84
	v_lshlrev_b32_e32 v84, 16, v155
	v_min_f32_e32 v80, 1.0, v80
	v_rcp_f32_e32 v76, v76
	v_add_f32_e32 v77, 1.0, v77
	v_exp_f32_e32 v73, v73
	v_mul_f32_e32 v66, 0xbfb8aa3b, v66
	v_mul_f32_e32 v67, v67, v32
	v_lshl_add_u64 v[88:89], v[86:87], 0, v[152:153]
	v_mul_f32_e32 v80, v80, v84
	v_and_b32_e32 v84, 0xffff0000, v155
	v_min_f32_e32 v81, 1.0, v81
	v_rcp_f32_e32 v77, v77
	v_add_f32_e32 v70, 1.0, v70
	v_exp_f32_e32 v66, v66
	v_mul_f32_e32 v67, 0xbfb8aa3b, v67
	v_mul_f32_e32 v68, v68, v32
	v_mov_b32_e32 v202, v82
	v_mov_b32_e32 v203, v83
	s_nop 1
	v_permlane16_swap_b32_e32 v200, v202
	v_permlane16_swap_b32_e32 v201, v203
	global_store_dwordx4 v[216:217], v[200:203], off
	v_mul_f32_e32 v81, v81, v84
	v_cvt_pk_bf16_f32 v78, v78, v79
	v_cvt_pk_bf16_f32 v79, v80, v81
	v_lshlrev_b32_e32 v80, 16, v150
	v_min_f32_e32 v74, 1.0, v74
	v_rcp_f32_e32 v70, v70
	v_add_f32_e32 v71, 1.0, v71
	v_exp_f32_e32 v67, v67
	v_mul_f32_e32 v68, 0xbfb8aa3b, v68
	v_mul_f32_e32 v69, v69, v32
	v_mul_f32_e32 v74, v74, v80
	v_and_b32_e32 v80, 0xffff0000, v150
	v_min_f32_e32 v75, 1.0, v75
	v_rcp_f32_e32 v71, v71
	v_add_f32_e32 v72, 1.0, v72
	v_exp_f32_e32 v68, v68
	v_mul_f32_e32 v69, 0xbfb8aa3b, v69
	v_mul_f32_e32 v75, v75, v80
	v_lshlrev_b32_e32 v80, 16, v151
	v_min_f32_e32 v76, 1.0, v76
	v_rcp_f32_e32 v72, v72
	v_add_f32_e32 v73, 1.0, v73
	v_exp_f32_e32 v69, v69
	v_lshl_add_u64 v[82:83], v[90:91], 0, v[144:145]
	v_mul_f32_e32 v76, v76, v80
	v_and_b32_e32 v80, 0xffff0000, v151
	v_min_f32_e32 v77, 1.0, v77
	v_rcp_f32_e32 v73, v73
	v_add_f32_e32 v66, 1.0, v66
	v_mov_b32_e32 v204, v78
	v_mov_b32_e32 v205, v79
	v_lshl_add_u64 v[218:219], v[82:83], 0, v[222:223]
	v_mul_f32_e32 v77, v77, v80
	v_cvt_pk_bf16_f32 v74, v74, v75
	v_cvt_pk_bf16_f32 v75, v76, v77
	v_lshlrev_b32_e32 v76, 16, v148
	v_min_f32_e32 v70, 1.0, v70
	v_rcp_f32_e32 v66, v66
	v_add_f32_e32 v67, 1.0, v67
	v_mul_f32_e32 v70, v70, v76
	v_and_b32_e32 v76, 0xffff0000, v148
	v_min_f32_e32 v71, 1.0, v71
	v_rcp_f32_e32 v67, v67
	v_add_f32_e32 v68, 1.0, v68
	v_mul_f32_e32 v71, v71, v76
	v_lshlrev_b32_e32 v76, 16, v149
	v_min_f32_e32 v72, 1.0, v72
; DEVI float sigmoidf_(float x) { return fminf(__builtin_amdgcn_rcpf(1.f + __builtin_amdgcn_exp2f(-LOG2E * x)), 1.f); }
; #define EPI_HALF(AI, ...) _Pragma("unroll") for(int bj=0;bj<2;++bj) _Pragma("unroll") for(int m=0;m<4;++m) _Pragma("unroll") for(int n=0;n<2;++n) { \
;     const int ai=(AI); const int row=brow+ai*128+wr*64+m*16+fq*4; const int col=bcol+bj*128+wc*32+n*16+fr; \
;     f32x4& v=acc[ai][bj][m][n]; __VA_ARGS__ }
; DEVI void run_phase(const int ph, const Params& P, char* shmc, const int wave_u) {
;     ...
;       for (int ah = 0; ah < 2; ++ah) {
;         u32x2 uu[2][4][2];
;         EPI_HALF(ah, { (void)v; uu[bj][m][n] = *reinterpret_cast<const u32x2*>(ub + (long)col * 2048 + row); })
;         EPI_HALF(ah, { const float sc = sc4[bj][n]; const u32x2 u = uu[bj][m][n];
;           st_bf4(T + (long)col * 2048 + row, __uint_as_float(u[0] << 16) * sigmoidf_(v[0] * sc), __uint_as_float(u[0] & 0xffff0000u) * sigmoidf_(v[1] * sc),
;                  __uint_as_float(u[1] << 16) * sigmoidf_(v[2] * sc), __uint_as_float(u[1] & 0xffff0000u) * sigmoidf_(v[3] * sc)); })
	v_rcp_f32_e32 v68, v68
	v_add_f32_e32 v69, 1.0, v69
	v_lshl_add_u64 v[78:79], v[86:87], 0, v[144:145]
	v_mul_f32_e32 v72, v72, v76
	v_and_b32_e32 v76, 0xffff0000, v149
	v_min_f32_e32 v73, 1.0, v73
	v_rcp_f32_e32 v69, v69
	v_mov_b32_e32 v208, v74
	v_mov_b32_e32 v209, v75
	v_lshl_add_u64 v[220:221], v[78:79], 0, v[222:223]
	v_mul_f32_e32 v73, v73, v76
	v_cvt_pk_bf16_f32 v70, v70, v71
	v_cvt_pk_bf16_f32 v71, v72, v73
	v_lshlrev_b32_e32 v72, 16, v142
	v_min_f32_e32 v66, 1.0, v66
	v_mul_f32_e32 v66, v66, v72
	v_and_b32_e32 v72, 0xffff0000, v142
	v_min_f32_e32 v67, 1.0, v67
	v_lshl_add_u64 v[74:75], v[90:91], 0, v[140:141]
	v_mul_f32_e32 v67, v67, v72
	v_lshlrev_b32_e32 v72, 16, v143
	v_min_f32_e32 v68, 1.0, v68
	v_mov_b32_e32 v206, v70
	v_mov_b32_e32 v207, v71
	s_nop 1
	v_permlane16_swap_b32_e32 v204, v206
	v_permlane16_swap_b32_e32 v205, v207
	global_store_dwordx4 v[218:219], v[204:207], off
	v_lshl_add_u64 v[70:71], v[86:87], 0, v[140:141]
	v_mul_f32_e32 v68, v68, v72
	v_and_b32_e32 v72, 0xffff0000, v143
	v_min_f32_e32 v69, 1.0, v69
	v_cvt_pk_bf16_f32 v66, v66, v67
	v_mul_f32_e32 v69, v69, v72
	v_cvt_pk_bf16_f32 v67, v68, v69
	v_mov_b32_e32 v210, v66
	v_mov_b32_e32 v211, v67
	s_nop 1
	v_permlane16_swap_b32_e32 v208, v210
	v_permlane16_swap_b32_e32 v209, v211
	global_store_dwordx4 v[220:221], v[208:211], off
	v_add_u32_e32 v66, 0x80, v138
	v_ashrrev_i32_e32 v67, 31, v66
	v_add_u32_e32 v68, 0xb0, v138
	v_lshlrev_b64 v[104:105], 1, v[66:67]
	v_ashrrev_i32_e32 v69, 31, v68
	v_lshl_add_u64 v[66:67], s[82:83], 0, v[104:105]
	v_lshlrev_b64 v[86:87], 1, v[68:69]
	v_lshl_add_u64 v[68:69], v[66:67], 0, v[136:137]
	global_load_dwordx2 v[106:107], v[68:69], off
	v_lshl_add_u64 v[68:69], v[66:67], 0, v[134:135]
	global_load_dwordx2 v[102:103], v[68:69], off
	v_add_u32_e32 v68, 0x90, v138
	v_ashrrev_i32_e32 v69, 31, v68
	v_lshlrev_b64 v[100:101], 1, v[68:69]
	v_lshl_add_u64 v[68:69], s[82:83], 0, v[100:101]
	v_lshl_add_u64 v[70:71], v[68:69], 0, v[136:137]
	global_load_dwordx2 v[98:99], v[70:71], off
	v_lshl_add_u64 v[70:71], v[68:69], 0, v[134:135]
	global_load_dwordx2 v[96:97], v[70:71], off
	v_add_u32_e32 v70, 0xa0, v138
	v_ashrrev_i32_e32 v71, 31, v70
	v_lshlrev_b64 v[94:95], 1, v[70:71]
	v_lshl_add_u64 v[70:71], s[82:83], 0, v[94:95]
	v_lshl_add_u64 v[72:73], v[70:71], 0, v[136:137]
	global_load_dwordx2 v[92:93], v[72:73], off
	v_lshl_add_u64 v[72:73], v[70:71], 0, v[134:135]
	global_load_dwordx2 v[90:91], v[72:73], off
	v_lshl_add_u64 v[80:81], s[82:83], 0, v[86:87]
	v_lshl_add_u64 v[72:73], v[80:81], 0, v[136:137]
	global_load_dwordx2 v[88:89], v[72:73], off
	v_lshl_add_u64 v[72:73], v[80:81], 0, v[134:135]
	global_load_dwordx2 v[84:85], v[72:73], off
	v_lshl_add_u64 v[72:73], v[66:67], 0, v[132:133]
	global_load_dwordx2 v[82:83], v[72:73], off
	v_lshl_add_u64 v[66:67], v[66:67], 0, v[130:131]
	global_load_dwordx2 v[78:79], v[66:67], off
	v_lshl_add_u64 v[66:67], v[68:69], 0, v[132:133]
	global_load_dwordx2 v[76:77], v[66:67], off
	v_lshl_add_u64 v[66:67], v[68:69], 0, v[130:131]
	global_load_dwordx2 v[74:75], v[66:67], off
	v_lshl_add_u64 v[66:67], v[70:71], 0, v[132:133]
	global_load_dwordx2 v[72:73], v[66:67], off
	v_lshl_add_u64 v[66:67], v[70:71], 0, v[130:131]
	global_load_dwordx2 v[70:71], v[66:67], off
	v_lshl_add_u64 v[66:67], v[80:81], 0, v[132:133]
	global_load_dwordx2 v[68:69], v[66:67], off
	v_lshl_add_u64 v[66:67], v[80:81], 0, v[130:131]
	global_load_dwordx2 v[66:67], v[66:67], off
	v_mul_f32_e32 v63, v63, v194
	v_mul_f32_e32 v62, v62, v194
	v_mul_f32_e32 v63, 0xbfb8aa3b, v63
	v_mul_f32_e32 v64, v64, v194
	v_mul_f32_e32 v62, 0xbfb8aa3b, v62
	v_exp_f32_e32 v63, v63
	v_mul_f32_e32 v64, 0xbfb8aa3b, v64
	v_mul_f32_e32 v65, v65, v194
	v_exp_f32_e32 v62, v62
	v_exp_f32_e32 v64, v64
	v_mul_f32_e32 v65, 0xbfb8aa3b, v65
	v_mul_f32_e32 v58, v58, v193
	v_exp_f32_e32 v65, v65
	v_mul_f32_e32 v58, 0xbfb8aa3b, v58
	v_mul_f32_e32 v59, v59, v193
	v_exp_f32_e32 v58, v58
	v_mul_f32_e32 v59, 0xbfb8aa3b, v59
	v_mul_f32_e32 v60, v60, v193
	v_add_f32_e32 v63, 1.0, v63
	v_exp_f32_e32 v59, v59
	v_mul_f32_e32 v60, 0xbfb8aa3b, v60
	v_mul_f32_e32 v61, v61, v193
	v_add_f32_e32 v62, 1.0, v62
	v_rcp_f32_e32 v63, v63
	v_add_f32_e32 v64, 1.0, v64
	v_exp_f32_e32 v60, v60
	v_mul_f32_e32 v61, 0xbfb8aa3b, v61
	v_mul_f32_e32 v54, v54, v194
	v_rcp_f32_e32 v62, v62
	v_rcp_f32_e32 v64, v64
	v_add_f32_e32 v65, 1.0, v65
	v_exp_f32_e32 v61, v61
	v_mul_f32_e32 v54, 0xbfb8aa3b, v54
	v_mul_f32_e32 v55, v55, v194
	v_rcp_f32_e32 v65, v65
	v_add_f32_e32 v58, 1.0, v58
	v_exp_f32_e32 v54, v54
	v_mul_f32_e32 v55, 0xbfb8aa3b, v55
	v_mul_f32_e32 v56, v56, v194
	v_rcp_f32_e32 v58, v58
	v_add_f32_e32 v59, 1.0, v59
	v_exp_f32_e32 v55, v55
	v_mul_f32_e32 v56, 0xbfb8aa3b, v56
	v_mul_f32_e32 v57, v57, v194
	s_waitcnt vmcnt(0) lgkmcnt(0)
; DEVI float sigmoidf_(float x) { return fminf(__builtin_amdgcn_rcpf(1.f + __builtin_amdgcn_exp2f(-LOG2E * x)), 1.f); }
; #define EPI_HALF(AI, ...) _Pragma("unroll") for(int bj=0;bj<2;++bj) _Pragma("unroll") for(int m=0;m<4;++m) _Pragma("unroll") for(int n=0;n<2;++n) { \
;     const int ai=(AI); const int row=brow+ai*128+wr*64+m*16+fq*4; const int col=bcol+bj*128+wc*32+n*16+fr; \
;     f32x4& v=acc[ai][bj][m][n]; __VA_ARGS__ }
; DEVI void run_phase(const int ph, const Params& P, char* shmc, const int wave_u) {
;     ...
;         EPI_HALF(ah, { const float sc = sc4[bj][n]; const u32x2 u = uu[bj][m][n];
;           st_bf4(T + (long)col * 2048 + row, __uint_as_float(u[0] << 16) * sigmoidf_(v[0] * sc), __uint_as_float(u[0] & 0xffff0000u) * sigmoidf_(v[1] * sc),
;                  __uint_as_float(u[1] << 16) * sigmoidf_(v[2] * sc), __uint_as_float(u[1] & 0xffff0000u) * sigmoidf_(v[3] * sc)); })
	v_lshlrev_b32_e32 v108, 16, v106
	v_and_b32_e32 v106, 0xffff0000, v106
	v_min_f32_e32 v63, 1.0, v63
	v_rcp_f32_e32 v59, v59
	v_add_f32_e32 v60, 1.0, v60
	v_exp_f32_e32 v56, v56
	v_mul_f32_e32 v57, 0xbfb8aa3b, v57
	v_mul_f32_e32 v50, v50, v193
	v_min_f32_e32 v62, 1.0, v62
	v_mul_f32_e32 v63, v63, v106
	v_lshlrev_b32_e32 v106, 16, v107
	v_min_f32_e32 v64, 1.0, v64
	v_rcp_f32_e32 v60, v60
	v_add_f32_e32 v61, 1.0, v61
	v_exp_f32_e32 v57, v57
	v_mul_f32_e32 v50, 0xbfb8aa3b, v50
	v_mul_f32_e32 v51, v51, v193
	v_mul_f32_e32 v62, v62, v108
	v_mul_f32_e32 v64, v64, v106
	v_and_b32_e32 v106, 0xffff0000, v107
	v_min_f32_e32 v65, 1.0, v65
	v_rcp_f32_e32 v61, v61
	v_add_f32_e32 v54, 1.0, v54
	v_exp_f32_e32 v50, v50
	v_mul_f32_e32 v51, 0xbfb8aa3b, v51
	v_mul_f32_e32 v52, v52, v193
	v_mul_f32_e32 v65, v65, v106
	v_cvt_pk_bf16_f32 v62, v62, v63
	v_cvt_pk_bf16_f32 v63, v64, v65
	v_lshlrev_b32_e32 v64, 16, v102
	v_min_f32_e32 v58, 1.0, v58
	v_rcp_f32_e32 v54, v54
	v_add_f32_e32 v55, 1.0, v55
	v_exp_f32_e32 v51, v51
	v_mul_f32_e32 v52, 0xbfb8aa3b, v52
	v_mul_f32_e32 v53, v53, v193
	v_lshl_add_u64 v[80:81], s[12:13], 0, v[104:105]
	v_mul_f32_e32 v58, v58, v64
	v_and_b32_e32 v64, 0xffff0000, v102
	v_min_f32_e32 v59, 1.0, v59
	v_rcp_f32_e32 v55, v55
	v_add_f32_e32 v56, 1.0, v56
	v_exp_f32_e32 v52, v52
	v_mul_f32_e32 v53, 0xbfb8aa3b, v53
	v_mul_f32_e32 v46, v46, v194
	v_lshl_add_u64 v[104:105], v[80:81], 0, v[136:137]
	v_mul_f32_e32 v59, v59, v64
	v_lshlrev_b32_e32 v64, 16, v103
	v_min_f32_e32 v60, 1.0, v60
	v_rcp_f32_e32 v56, v56
	v_add_f32_e32 v57, 1.0, v57
	v_exp_f32_e32 v53, v53
	v_mul_f32_e32 v46, 0xbfb8aa3b, v46
	v_mul_f32_e32 v47, v47, v194
	v_mov_b32_e32 v196, v62
	v_mov_b32_e32 v197, v63
	v_lshl_add_u64 v[212:213], v[104:105], 0, v[222:223]
	v_lshl_add_u64 v[62:63], v[80:81], 0, v[134:135]
	v_mul_f32_e32 v60, v60, v64
	v_and_b32_e32 v64, 0xffff0000, v103
	v_min_f32_e32 v61, 1.0, v61
	v_rcp_f32_e32 v57, v57
	v_add_f32_e32 v50, 1.0, v50
	v_exp_f32_e32 v46, v46
	v_mul_f32_e32 v47, 0xbfb8aa3b, v47
	v_mul_f32_e32 v48, v48, v194
	v_mul_f32_e32 v61, v61, v64
	v_cvt_pk_bf16_f32 v58, v58, v59
	v_cvt_pk_bf16_f32 v59, v60, v61
	v_mov_b32_e32 v200, v58
	v_mov_b32_e32 v201, v59
	v_lshl_add_u64 v[216:217], v[62:63], 0, v[222:223]
	v_lshlrev_b32_e32 v62, 16, v98
	v_min_f32_e32 v54, 1.0, v54
	v_rcp_f32_e32 v50, v50
	v_add_f32_e32 v51, 1.0, v51
	v_exp_f32_e32 v47, v47
	v_mul_f32_e32 v48, 0xbfb8aa3b, v48
	v_mul_f32_e32 v49, v49, v194
	v_mul_f32_e32 v54, v54, v62
	v_and_b32_e32 v62, 0xffff0000, v98
	v_min_f32_e32 v55, 1.0, v55
	v_rcp_f32_e32 v51, v51
	v_add_f32_e32 v52, 1.0, v52
	v_exp_f32_e32 v48, v48
	v_mul_f32_e32 v49, 0xbfb8aa3b, v49
	v_mul_f32_e32 v42, v42, v193
	v_mul_f32_e32 v55, v55, v62
	v_lshlrev_b32_e32 v62, 16, v99
	v_min_f32_e32 v56, 1.0, v56
	v_rcp_f32_e32 v52, v52
	v_add_f32_e32 v53, 1.0, v53
	v_exp_f32_e32 v49, v49
	v_mul_f32_e32 v42, 0xbfb8aa3b, v42
	v_mul_f32_e32 v43, v43, v193
	v_mul_f32_e32 v56, v56, v62
	v_and_b32_e32 v62, 0xffff0000, v99
	v_min_f32_e32 v57, 1.0, v57
	v_rcp_f32_e32 v53, v53
	v_add_f32_e32 v46, 1.0, v46
	v_exp_f32_e32 v42, v42
	v_mul_f32_e32 v43, 0xbfb8aa3b, v43
	v_mul_f32_e32 v44, v44, v193
	v_mul_f32_e32 v57, v57, v62
	v_cvt_pk_bf16_f32 v54, v54, v55
	v_cvt_pk_bf16_f32 v55, v56, v57
	v_lshlrev_b32_e32 v56, 16, v96
	v_min_f32_e32 v50, 1.0, v50
	v_rcp_f32_e32 v46, v46
	v_add_f32_e32 v47, 1.0, v47
	v_exp_f32_e32 v43, v43
	v_mul_f32_e32 v44, 0xbfb8aa3b, v44
	v_mul_f32_e32 v45, v45, v193
	v_lshl_add_u64 v[58:59], s[12:13], 0, v[100:101]
	v_mul_f32_e32 v50, v50, v56
	v_and_b32_e32 v56, 0xffff0000, v96
	v_min_f32_e32 v51, 1.0, v51
	v_rcp_f32_e32 v47, v47
	v_add_f32_e32 v48, 1.0, v48
	v_exp_f32_e32 v44, v44
	v_mul_f32_e32 v45, 0xbfb8aa3b, v45
	v_mul_f32_e32 v38, v38, v194
	v_lshl_add_u64 v[60:61], v[58:59], 0, v[136:137]
	v_mul_f32_e32 v51, v51, v56
	v_lshlrev_b32_e32 v56, 16, v97
	v_min_f32_e32 v52, 1.0, v52
	v_rcp_f32_e32 v48, v48
	v_add_f32_e32 v49, 1.0, v49
	v_exp_f32_e32 v45, v45
	v_mul_f32_e32 v38, 0xbfb8aa3b, v38
	v_mul_f32_e32 v39, v39, v194
	v_mov_b32_e32 v198, v54
	v_mov_b32_e32 v199, v55
	s_nop 1
	v_permlane16_swap_b32_e32 v196, v198
	v_permlane16_swap_b32_e32 v197, v199
	global_store_dwordx4 v[212:213], v[196:199], off
	v_lshl_add_u64 v[54:55], v[58:59], 0, v[134:135]
	v_mul_f32_e32 v52, v52, v56
	v_and_b32_e32 v56, 0xffff0000, v97
	v_min_f32_e32 v53, 1.0, v53
	v_rcp_f32_e32 v49, v49
	v_add_f32_e32 v42, 1.0, v42
	v_exp_f32_e32 v38, v38
	v_mul_f32_e32 v39, 0xbfb8aa3b, v39
	v_mul_f32_e32 v40, v40, v194
	v_mul_f32_e32 v53, v53, v56
	v_cvt_pk_bf16_f32 v50, v50, v51
	v_cvt_pk_bf16_f32 v51, v52, v53
	v_mov_b32_e32 v202, v50
	v_mov_b32_e32 v203, v51
	s_nop 1
	v_permlane16_swap_b32_e32 v200, v202
	v_permlane16_swap_b32_e32 v201, v203
	global_store_dwordx4 v[216:217], v[200:203], off
	v_lshlrev_b32_e32 v54, 16, v92
	v_min_f32_e32 v46, 1.0, v46
	v_rcp_f32_e32 v42, v42
	v_add_f32_e32 v43, 1.0, v43
	v_exp_f32_e32 v39, v39
	v_mul_f32_e32 v40, 0xbfb8aa3b, v40
	v_mul_f32_e32 v41, v41, v194
	v_mul_f32_e32 v46, v46, v54
	v_and_b32_e32 v54, 0xffff0000, v92
	v_min_f32_e32 v47, 1.0, v47
	v_rcp_f32_e32 v43, v43
	v_add_f32_e32 v44, 1.0, v44
	v_exp_f32_e32 v40, v40
	v_mul_f32_e32 v41, 0xbfb8aa3b, v41
	v_mul_f32_e32 v34, v34, v193
	v_mul_f32_e32 v47, v47, v54
	v_lshlrev_b32_e32 v54, 16, v93
	v_min_f32_e32 v48, 1.0, v48
	v_rcp_f32_e32 v44, v44
	v_add_f32_e32 v45, 1.0, v45
	v_exp_f32_e32 v41, v41
	v_mul_f32_e32 v34, 0xbfb8aa3b, v34
	v_mul_f32_e32 v35, v35, v193
	v_mul_f32_e32 v48, v48, v54
	v_and_b32_e32 v54, 0xffff0000, v93
	v_min_f32_e32 v49, 1.0, v49
	v_rcp_f32_e32 v45, v45
	v_add_f32_e32 v38, 1.0, v38
	v_exp_f32_e32 v34, v34
	v_mul_f32_e32 v35, 0xbfb8aa3b, v35
; DEVI float sigmoidf_(float x) { return fminf(__builtin_amdgcn_rcpf(1.f + __builtin_amdgcn_exp2f(-LOG2E * x)), 1.f); }
; #define EPI_HALF(AI, ...) _Pragma("unroll") for(int bj=0;bj<2;++bj) _Pragma("unroll") for(int m=0;m<4;++m) _Pragma("unroll") for(int n=0;n<2;++n) { \
;     const int ai=(AI); const int row=brow+ai*128+wr*64+m*16+fq*4; const int col=bcol+bj*128+wc*32+n*16+fr; \
;     f32x4& v=acc[ai][bj][m][n]; __VA_ARGS__ }
; DEVI void run_phase(const int ph, const Params& P, char* shmc, const int wave_u) {
;     ...
;         EPI_HALF(ah, { const float sc = sc4[bj][n]; const u32x2 u = uu[bj][m][n];
;           st_bf4(T + (long)col * 2048 + row, __uint_as_float(u[0] << 16) * sigmoidf_(v[0] * sc), __uint_as_float(u[0] & 0xffff0000u) * sigmoidf_(v[1] * sc),
;                  __uint_as_float(u[1] << 16) * sigmoidf_(v[2] * sc), __uint_as_float(u[1] & 0xffff0000u) * sigmoidf_(v[3] * sc)); })
	v_mul_f32_e32 v36, v36, v193
	v_mul_f32_e32 v49, v49, v54
	v_cvt_pk_bf16_f32 v46, v46, v47
	v_cvt_pk_bf16_f32 v47, v48, v49
	v_lshlrev_b32_e32 v48, 16, v90
	v_min_f32_e32 v42, 1.0, v42
	v_rcp_f32_e32 v38, v38
	v_add_f32_e32 v39, 1.0, v39
	v_exp_f32_e32 v35, v35
	v_mul_f32_e32 v36, 0xbfb8aa3b, v36
	v_mul_f32_e32 v37, v37, v193
	v_lshl_add_u64 v[50:51], s[12:13], 0, v[94:95]
	v_mul_f32_e32 v42, v42, v48
	v_and_b32_e32 v48, 0xffff0000, v90
	v_min_f32_e32 v43, 1.0, v43
	v_rcp_f32_e32 v39, v39
	v_add_f32_e32 v40, 1.0, v40
	v_exp_f32_e32 v36, v36
	v_mul_f32_e32 v37, 0xbfb8aa3b, v37
	v_mul_f32_e32 v28, v28, v192
	v_lshl_add_u64 v[52:53], v[50:51], 0, v[136:137]
	v_mul_f32_e32 v43, v43, v48
	v_lshlrev_b32_e32 v48, 16, v91
	v_min_f32_e32 v44, 1.0, v44
	v_rcp_f32_e32 v40, v40
	v_add_f32_e32 v41, 1.0, v41
	v_exp_f32_e32 v37, v37
	v_mul_f32_e32 v28, 0xbfb8aa3b, v28
	v_mul_f32_e32 v29, v29, v192
	v_mov_b32_e32 v204, v46
	v_mov_b32_e32 v205, v47
	v_lshl_add_u64 v[218:219], v[52:53], 0, v[222:223]
	v_lshl_add_u64 v[46:47], v[50:51], 0, v[134:135]
	v_mul_f32_e32 v44, v44, v48
	v_and_b32_e32 v48, 0xffff0000, v91
	v_min_f32_e32 v45, 1.0, v45
	v_rcp_f32_e32 v41, v41
	v_add_f32_e32 v34, 1.0, v34
	v_exp_f32_e32 v28, v28
	v_mul_f32_e32 v29, 0xbfb8aa3b, v29
	v_mul_f32_e32 v30, v30, v192
	v_mul_f32_e32 v45, v45, v48
	v_cvt_pk_bf16_f32 v42, v42, v43
	v_cvt_pk_bf16_f32 v43, v44, v45
	v_mov_b32_e32 v208, v42
	v_mov_b32_e32 v209, v43
	v_lshl_add_u64 v[220:221], v[46:47], 0, v[222:223]
	v_lshlrev_b32_e32 v46, 16, v88
	v_min_f32_e32 v38, 1.0, v38
	v_rcp_f32_e32 v34, v34
	v_add_f32_e32 v35, 1.0, v35
	v_exp_f32_e32 v29, v29
	v_mul_f32_e32 v30, 0xbfb8aa3b, v30
	v_mul_f32_e32 v31, v31, v192
	v_mul_f32_e32 v38, v38, v46
	v_and_b32_e32 v46, 0xffff0000, v88
	v_min_f32_e32 v39, 1.0, v39
	v_rcp_f32_e32 v35, v35
	v_add_f32_e32 v36, 1.0, v36
	v_exp_f32_e32 v30, v30
	v_mul_f32_e32 v31, 0xbfb8aa3b, v31
	v_mul_f32_e32 v24, v24, v32
	v_mul_f32_e32 v39, v39, v46
	v_lshlrev_b32_e32 v46, 16, v89
	v_min_f32_e32 v40, 1.0, v40
	v_rcp_f32_e32 v36, v36
	v_add_f32_e32 v37, 1.0, v37
	v_exp_f32_e32 v31, v31
	v_mul_f32_e32 v24, 0xbfb8aa3b, v24
	v_mul_f32_e32 v25, v25, v32
	v_mul_f32_e32 v40, v40, v46
	v_and_b32_e32 v46, 0xffff0000, v89
	v_min_f32_e32 v41, 1.0, v41
	v_rcp_f32_e32 v37, v37
	v_add_f32_e32 v28, 1.0, v28
	v_exp_f32_e32 v24, v24
	v_mul_f32_e32 v25, 0xbfb8aa3b, v25
	v_mul_f32_e32 v26, v26, v32
	v_mul_f32_e32 v41, v41, v46
	v_cvt_pk_bf16_f32 v38, v38, v39
	v_cvt_pk_bf16_f32 v39, v40, v41
	v_lshlrev_b32_e32 v40, 16, v84
	v_min_f32_e32 v34, 1.0, v34
	v_rcp_f32_e32 v28, v28
	v_add_f32_e32 v29, 1.0, v29
	v_exp_f32_e32 v25, v25
	v_mul_f32_e32 v26, 0xbfb8aa3b, v26
	v_mul_f32_e32 v27, v27, v32
	v_mul_f32_e32 v34, v34, v40
	v_and_b32_e32 v40, 0xffff0000, v84
	v_min_f32_e32 v35, 1.0, v35
	v_rcp_f32_e32 v29, v29
	v_add_f32_e32 v30, 1.0, v30
	v_exp_f32_e32 v26, v26
	v_mul_f32_e32 v27, 0xbfb8aa3b, v27
	v_mul_f32_e32 v20, v20, v192
	v_lshl_add_u64 v[42:43], s[12:13], 0, v[86:87]
	v_mul_f32_e32 v35, v35, v40
	v_lshlrev_b32_e32 v40, 16, v85
	v_min_f32_e32 v36, 1.0, v36
	v_rcp_f32_e32 v30, v30
	v_add_f32_e32 v31, 1.0, v31
	v_exp_f32_e32 v27, v27
	v_mul_f32_e32 v20, 0xbfb8aa3b, v20
	v_mul_f32_e32 v21, v21, v192
	v_lshl_add_u64 v[44:45], v[42:43], 0, v[136:137]
	v_mul_f32_e32 v36, v36, v40
	v_and_b32_e32 v40, 0xffff0000, v85
	v_min_f32_e32 v37, 1.0, v37
	v_rcp_f32_e32 v31, v31
	v_add_f32_e32 v24, 1.0, v24
	v_exp_f32_e32 v20, v20
	v_mul_f32_e32 v21, 0xbfb8aa3b, v21
	v_mul_f32_e32 v22, v22, v192
	v_mov_b32_e32 v206, v38
	v_mov_b32_e32 v207, v39
	s_nop 1
	v_permlane16_swap_b32_e32 v204, v206
	v_permlane16_swap_b32_e32 v205, v207
	global_store_dwordx4 v[218:219], v[204:207], off
	v_mul_f32_e32 v37, v37, v40
	v_cvt_pk_bf16_f32 v34, v34, v35
	v_cvt_pk_bf16_f32 v35, v36, v37
	v_lshlrev_b32_e32 v36, 16, v82
	v_min_f32_e32 v28, 1.0, v28
	v_rcp_f32_e32 v24, v24
	v_add_f32_e32 v25, 1.0, v25
	v_exp_f32_e32 v21, v21
	v_mul_f32_e32 v22, 0xbfb8aa3b, v22
	v_mul_f32_e32 v23, v23, v192
	v_mul_f32_e32 v28, v28, v36
	v_and_b32_e32 v36, 0xffff0000, v82
	v_min_f32_e32 v29, 1.0, v29
	v_rcp_f32_e32 v25, v25
	v_add_f32_e32 v26, 1.0, v26
	v_exp_f32_e32 v22, v22
	v_mul_f32_e32 v23, 0xbfb8aa3b, v23
	v_mul_f32_e32 v16, v16, v32
	v_mul_f32_e32 v29, v29, v36
	v_lshlrev_b32_e32 v36, 16, v83
	v_min_f32_e32 v30, 1.0, v30
	v_rcp_f32_e32 v26, v26
	v_add_f32_e32 v27, 1.0, v27
	v_exp_f32_e32 v23, v23
	v_mul_f32_e32 v16, 0xbfb8aa3b, v16
	v_mul_f32_e32 v17, v17, v32
	v_lshl_add_u64 v[38:39], v[42:43], 0, v[134:135]
	v_mul_f32_e32 v30, v30, v36
	v_and_b32_e32 v36, 0xffff0000, v83
	v_min_f32_e32 v31, 1.0, v31
	v_rcp_f32_e32 v27, v27
	v_add_f32_e32 v20, 1.0, v20
	v_exp_f32_e32 v16, v16
	v_mul_f32_e32 v17, 0xbfb8aa3b, v17
	v_mul_f32_e32 v18, v18, v32
	v_mov_b32_e32 v210, v34
	v_mov_b32_e32 v211, v35
	s_nop 1
	v_permlane16_swap_b32_e32 v208, v210
	v_permlane16_swap_b32_e32 v209, v211
	global_store_dwordx4 v[220:221], v[208:211], off
	v_mul_f32_e32 v31, v31, v36
	v_cvt_pk_bf16_f32 v28, v28, v29
	v_cvt_pk_bf16_f32 v29, v30, v31
	v_lshlrev_b32_e32 v30, 16, v78
	v_min_f32_e32 v24, 1.0, v24
	v_rcp_f32_e32 v20, v20
	v_add_f32_e32 v21, 1.0, v21
	v_exp_f32_e32 v17, v17
	v_mul_f32_e32 v18, 0xbfb8aa3b, v18
	v_mul_f32_e32 v19, v19, v32
	v_mul_f32_e32 v24, v24, v30
	v_and_b32_e32 v30, 0xffff0000, v78
	v_min_f32_e32 v25, 1.0, v25
	v_rcp_f32_e32 v21, v21
	v_add_f32_e32 v22, 1.0, v22
	v_exp_f32_e32 v18, v18
	v_mul_f32_e32 v19, 0xbfb8aa3b, v19
	v_mul_f32_e32 v12, v12, v192
	v_mul_f32_e32 v25, v25, v30
	v_lshlrev_b32_e32 v30, 16, v79
	v_min_f32_e32 v26, 1.0, v26
	v_rcp_f32_e32 v22, v22
	v_add_f32_e32 v23, 1.0, v23
	v_exp_f32_e32 v19, v19
	v_mul_f32_e32 v12, 0xbfb8aa3b, v12
; DEVI float sigmoidf_(float x) { return fminf(__builtin_amdgcn_rcpf(1.f + __builtin_amdgcn_exp2f(-LOG2E * x)), 1.f); }
; #define EPI_HALF(AI, ...) _Pragma("unroll") for(int bj=0;bj<2;++bj) _Pragma("unroll") for(int m=0;m<4;++m) _Pragma("unroll") for(int n=0;n<2;++n) { \
;     const int ai=(AI); const int row=brow+ai*128+wr*64+m*16+fq*4; const int col=bcol+bj*128+wc*32+n*16+fr; \
;     f32x4& v=acc[ai][bj][m][n]; __VA_ARGS__ }
; DEVI void run_phase(const int ph, const Params& P, char* shmc, const int wave_u) {
;     ...
;         EPI_HALF(ah, { const float sc = sc4[bj][n]; const u32x2 u = uu[bj][m][n];
;           st_bf4(T + (long)col * 2048 + row, __uint_as_float(u[0] << 16) * sigmoidf_(v[0] * sc), __uint_as_float(u[0] & 0xffff0000u) * sigmoidf_(v[1] * sc),
;                  __uint_as_float(u[1] << 16) * sigmoidf_(v[2] * sc), __uint_as_float(u[1] & 0xffff0000u) * sigmoidf_(v[3] * sc)); })
	v_mul_f32_e32 v13, v13, v192
	v_lshl_add_u64 v[34:35], v[80:81], 0, v[132:133]
	v_mul_f32_e32 v26, v26, v30
	v_and_b32_e32 v30, 0xffff0000, v79
	v_min_f32_e32 v27, 1.0, v27
	v_rcp_f32_e32 v23, v23
	v_add_f32_e32 v16, 1.0, v16
	v_exp_f32_e32 v12, v12
	v_mul_f32_e32 v13, 0xbfb8aa3b, v13
	v_mul_f32_e32 v14, v14, v192
	v_mov_b32_e32 v196, v28
	v_mov_b32_e32 v197, v29
	v_lshl_add_u64 v[212:213], v[34:35], 0, v[222:223]
	v_mul_f32_e32 v27, v27, v30
	v_cvt_pk_bf16_f32 v24, v24, v25
	v_cvt_pk_bf16_f32 v25, v26, v27
	v_lshlrev_b32_e32 v26, 16, v76
	v_min_f32_e32 v20, 1.0, v20
	v_rcp_f32_e32 v16, v16
	v_add_f32_e32 v17, 1.0, v17
	v_exp_f32_e32 v13, v13
	v_mul_f32_e32 v14, 0xbfb8aa3b, v14
	v_mul_f32_e32 v15, v15, v192
	v_mul_f32_e32 v20, v20, v26
	v_and_b32_e32 v26, 0xffff0000, v76
	v_min_f32_e32 v21, 1.0, v21
	v_rcp_f32_e32 v17, v17
	v_add_f32_e32 v18, 1.0, v18
	v_exp_f32_e32 v14, v14
	v_mul_f32_e32 v15, 0xbfb8aa3b, v15
	v_mul_f32_e32 v8, v8, v32
	v_mul_f32_e32 v21, v21, v26
	v_lshlrev_b32_e32 v26, 16, v77
	v_min_f32_e32 v22, 1.0, v22
	v_rcp_f32_e32 v18, v18
	v_add_f32_e32 v19, 1.0, v19
	v_exp_f32_e32 v15, v15
	v_mul_f32_e32 v8, 0xbfb8aa3b, v8
	v_mul_f32_e32 v9, v9, v32
	v_lshl_add_u64 v[28:29], v[80:81], 0, v[130:131]
	v_mul_f32_e32 v22, v22, v26
	v_and_b32_e32 v26, 0xffff0000, v77
	v_min_f32_e32 v23, 1.0, v23
	v_rcp_f32_e32 v19, v19
	v_add_f32_e32 v12, 1.0, v12
	v_exp_f32_e32 v8, v8
	v_mul_f32_e32 v9, 0xbfb8aa3b, v9
	v_mul_f32_e32 v10, v10, v32
	v_mov_b32_e32 v200, v24
	v_mov_b32_e32 v201, v25
	v_lshl_add_u64 v[216:217], v[28:29], 0, v[222:223]
	v_mul_f32_e32 v23, v23, v26
	v_cvt_pk_bf16_f32 v20, v20, v21
	v_cvt_pk_bf16_f32 v21, v22, v23
	v_lshlrev_b32_e32 v22, 16, v74
	v_min_f32_e32 v16, 1.0, v16
	v_rcp_f32_e32 v12, v12
	v_add_f32_e32 v13, 1.0, v13
	v_exp_f32_e32 v9, v9
	v_mul_f32_e32 v10, 0xbfb8aa3b, v10
	v_mul_f32_e32 v11, v11, v32
	v_mul_f32_e32 v16, v16, v22
	v_and_b32_e32 v22, 0xffff0000, v74
	v_min_f32_e32 v17, 1.0, v17
	v_rcp_f32_e32 v13, v13
	v_add_f32_e32 v14, 1.0, v14
	v_exp_f32_e32 v10, v10
	v_mul_f32_e32 v11, 0xbfb8aa3b, v11
	v_mul_f32_e32 v4, v4, v192
	v_mul_f32_e32 v17, v17, v22
	v_lshlrev_b32_e32 v22, 16, v75
	v_min_f32_e32 v18, 1.0, v18
	v_rcp_f32_e32 v14, v14
	v_add_f32_e32 v15, 1.0, v15
	v_exp_f32_e32 v11, v11
	v_mul_f32_e32 v4, 0xbfb8aa3b, v4
	v_mul_f32_e32 v5, v5, v192
	v_lshl_add_u64 v[24:25], v[58:59], 0, v[132:133]
	v_mul_f32_e32 v18, v18, v22
	v_and_b32_e32 v22, 0xffff0000, v75
	v_min_f32_e32 v19, 1.0, v19
	v_rcp_f32_e32 v15, v15
	v_add_f32_e32 v8, 1.0, v8
	v_exp_f32_e32 v4, v4
	v_mul_f32_e32 v5, 0xbfb8aa3b, v5
	v_mul_f32_e32 v6, v6, v192
	v_mov_b32_e32 v198, v20
	v_mov_b32_e32 v199, v21
	s_nop 1
	v_permlane16_swap_b32_e32 v196, v198
	v_permlane16_swap_b32_e32 v197, v199
	global_store_dwordx4 v[212:213], v[196:199], off
	v_mul_f32_e32 v19, v19, v22
	v_cvt_pk_bf16_f32 v16, v16, v17
	v_cvt_pk_bf16_f32 v17, v18, v19
	v_lshlrev_b32_e32 v18, 16, v72
	v_min_f32_e32 v12, 1.0, v12
	v_rcp_f32_e32 v8, v8
	v_add_f32_e32 v9, 1.0, v9
	v_exp_f32_e32 v5, v5
	v_mul_f32_e32 v6, 0xbfb8aa3b, v6
	v_mul_f32_e32 v7, v7, v192
	v_mul_f32_e32 v12, v12, v18
	v_and_b32_e32 v18, 0xffff0000, v72
	v_min_f32_e32 v13, 1.0, v13
	v_rcp_f32_e32 v9, v9
	v_add_f32_e32 v10, 1.0, v10
	v_exp_f32_e32 v6, v6
	v_mul_f32_e32 v7, 0xbfb8aa3b, v7
	v_mul_f32_e32 v0, v0, v32
	v_mul_f32_e32 v13, v13, v18
	v_lshlrev_b32_e32 v18, 16, v73
	v_min_f32_e32 v14, 1.0, v14
	v_rcp_f32_e32 v10, v10
	v_add_f32_e32 v11, 1.0, v11
	v_exp_f32_e32 v7, v7
	v_mul_f32_e32 v0, 0xbfb8aa3b, v0
	v_mul_f32_e32 v1, v1, v32
	v_lshl_add_u64 v[20:21], v[58:59], 0, v[130:131]
	v_mul_f32_e32 v14, v14, v18
	v_and_b32_e32 v18, 0xffff0000, v73
	v_min_f32_e32 v15, 1.0, v15
	v_rcp_f32_e32 v11, v11
	v_add_f32_e32 v4, 1.0, v4
	v_exp_f32_e32 v0, v0
	v_mul_f32_e32 v1, 0xbfb8aa3b, v1
	v_mul_f32_e32 v2, v2, v32
	v_mov_b32_e32 v202, v16
	v_mov_b32_e32 v203, v17
	s_nop 1
	v_permlane16_swap_b32_e32 v200, v202
	v_permlane16_swap_b32_e32 v201, v203
	global_store_dwordx4 v[216:217], v[200:203], off
	v_mul_f32_e32 v15, v15, v18
	v_cvt_pk_bf16_f32 v12, v12, v13
	v_cvt_pk_bf16_f32 v13, v14, v15
	v_lshlrev_b32_e32 v14, 16, v70
	v_min_f32_e32 v8, 1.0, v8
	v_rcp_f32_e32 v4, v4
	v_add_f32_e32 v5, 1.0, v5
	v_exp_f32_e32 v1, v1
	v_mul_f32_e32 v2, 0xbfb8aa3b, v2
	v_mul_f32_e32 v3, v3, v32
	v_mul_f32_e32 v8, v8, v14
	v_and_b32_e32 v14, 0xffff0000, v70
	v_min_f32_e32 v9, 1.0, v9
	v_rcp_f32_e32 v5, v5
	v_add_f32_e32 v6, 1.0, v6
	v_exp_f32_e32 v2, v2
	v_mul_f32_e32 v3, 0xbfb8aa3b, v3
	v_mul_f32_e32 v9, v9, v14
	v_lshlrev_b32_e32 v14, 16, v71
	v_min_f32_e32 v10, 1.0, v10
	v_rcp_f32_e32 v6, v6
	v_add_f32_e32 v7, 1.0, v7
	v_exp_f32_e32 v3, v3
	v_lshl_add_u64 v[16:17], v[50:51], 0, v[132:133]
	v_mul_f32_e32 v10, v10, v14
	v_and_b32_e32 v14, 0xffff0000, v71
	v_min_f32_e32 v11, 1.0, v11
	v_rcp_f32_e32 v7, v7
	v_add_f32_e32 v0, 1.0, v0
	v_mov_b32_e32 v204, v12
	v_mov_b32_e32 v205, v13
	v_lshl_add_u64 v[218:219], v[16:17], 0, v[222:223]
	v_mul_f32_e32 v11, v11, v14
	v_cvt_pk_bf16_f32 v8, v8, v9
	v_cvt_pk_bf16_f32 v9, v10, v11
	v_lshlrev_b32_e32 v10, 16, v68
	v_min_f32_e32 v4, 1.0, v4
	v_rcp_f32_e32 v0, v0
	v_add_f32_e32 v1, 1.0, v1
	v_mul_f32_e32 v4, v4, v10
	v_and_b32_e32 v10, 0xffff0000, v68
	v_min_f32_e32 v5, 1.0, v5
	v_rcp_f32_e32 v1, v1
	v_add_f32_e32 v2, 1.0, v2
	v_mul_f32_e32 v5, v5, v10
	v_lshlrev_b32_e32 v10, 16, v69
	v_min_f32_e32 v6, 1.0, v6
	v_rcp_f32_e32 v2, v2
	v_add_f32_e32 v3, 1.0, v3
	v_lshl_add_u64 v[12:13], v[50:51], 0, v[130:131]
	v_mul_f32_e32 v6, v6, v10
	v_and_b32_e32 v10, 0xffff0000, v69
	v_min_f32_e32 v7, 1.0, v7
	v_rcp_f32_e32 v3, v3
	v_mov_b32_e32 v208, v8
	v_mov_b32_e32 v209, v9
	v_lshl_add_u64 v[220:221], v[12:13], 0, v[222:223]
	v_mul_f32_e32 v7, v7, v10
	v_cvt_pk_bf16_f32 v4, v4, v5
	v_cvt_pk_bf16_f32 v5, v6, v7
	v_lshlrev_b32_e32 v6, 16, v66
	v_min_f32_e32 v0, 1.0, v0
	v_mul_f32_e32 v0, v0, v6
	v_and_b32_e32 v6, 0xffff0000, v66
	v_min_f32_e32 v1, 1.0, v1
	v_lshl_add_u64 v[8:9], v[42:43], 0, v[132:133]
	v_mul_f32_e32 v1, v1, v6
	v_lshlrev_b32_e32 v6, 16, v67
	v_min_f32_e32 v2, 1.0, v2
	v_mov_b32_e32 v206, v4
	v_mov_b32_e32 v207, v5
	s_nop 1
	v_permlane16_swap_b32_e32 v204, v206
	v_permlane16_swap_b32_e32 v205, v207
	global_store_dwordx4 v[218:219], v[204:207], off
	v_lshl_add_u64 v[4:5], v[42:43], 0, v[130:131]
	v_mul_f32_e32 v2, v2, v6
	v_and_b32_e32 v6, 0xffff0000, v67
	v_min_f32_e32 v3, 1.0, v3
	v_mul_f32_e32 v3, v3, v6
	v_cvt_pk_bf16_f32 v0, v0, v1
	v_cvt_pk_bf16_f32 v1, v2, v3
	v_mov_b32_e32 v210, v0
	v_mov_b32_e32 v211, v1
	s_nop 1
	v_permlane16_swap_b32_e32 v208, v210
	v_permlane16_swap_b32_e32 v209, v211
	global_store_dwordx4 v[220:221], v[208:211], off
	s_cbranch_scc1 .LBB0_42

; #define EPI_LOOP(...) _Pragma("unroll") for(int ai=0;ai<2;++ai) _Pragma("unroll") for(int bj=0;bj<2;++bj) \
;   _Pragma("unroll") for(int m=0;m<4;++m) _Pragma("unroll") for(int n=0;n<2;++n) { \
;     const int row=brow+ai*128+wr*64+m*16+fq*4; const int col=bcol+bj*128+wc*32+n*16+fr; \
;     f32x4& v=acc[ai][bj][m][n]; __VA_ARGS__ if (n == 1 && (m & 1)) __builtin_amdgcn_sched_barrier(0); }
; DEVI void run_phase(const int ph, const Params& P, char* shmc, const int wave_u) {
;     ...
;       { GEMM_IDS
;       EPI_LOOP({ st_bf4(ub + (long)col * 2048 + row, v[0], v[1], v[2], v[3]); })
;       }
.LBB0_64:
	s_or_b64 exec, exec, s[8:9]
	v_mbcnt_lo_u32_b32 v178, -1, 0
	v_mbcnt_hi_u32_b32 v178, -1, v178
	v_bfe_u32 v178, v178, 4, 1
	v_mul_u32_u24_e32 v178, 24, v178
	v_mov_b32_e32 v179, 0
	v_mbcnt_lo_u32_b32 v32, -1, 0
	v_mbcnt_hi_u32_b32 v32, -1, v32
	v_cvt_pk_bf16_f32 v126, v126, v127
	v_cvt_pk_bf16_f32 v127, v128, v129
	s_nop 0
	v_or_b32_e32 v131, s5, v32
	v_and_b32_e32 v132, 15, v32
	v_ashrrev_i32_e32 v130, 2, v131
	v_lshrrev_b32_e32 v32, 2, v32
	v_and_b32_e32 v130, 0xffffffc0, v130
	v_and_or_b32 v32, v32, 12, s0
	v_add_u32_e32 v130, v32, v130
	v_lshrrev_b32_e32 v32, 1, v131
	v_and_b32_e32 v32, 0x60, v32
	v_or3_b32 v132, v132, v32, s6
	v_ashrrev_i32_e32 v131, 31, v130
	v_ashrrev_i32_e32 v133, 31, v132
	v_lshl_add_u64 v[134:135], v[130:131], 1, s[82:83]
	v_lshlrev_b64 v[136:137], 12, v[132:133]
	v_lshl_add_u64 v[138:139], v[134:135], 0, v[136:137]
	v_mov_b32_e32 v156, v126
	v_mov_b32_e32 v157, v127
	v_lshl_add_u64 v[142:143], v[138:139], 0, v[178:179]
	v_or_b32_e32 v126, 16, v132
	v_ashrrev_i32_e32 v127, 31, v126
	v_lshlrev_b64 v[126:127], 12, v[126:127]
	v_lshl_add_u64 v[128:129], v[134:135], 0, v[126:127]
	v_cvt_pk_bf16_f32 v122, v122, v123
	v_cvt_pk_bf16_f32 v123, v124, v125
	v_mov_b32_e32 v160, v122
	v_mov_b32_e32 v161, v123
	v_lshl_add_u64 v[172:173], v[128:129], 0, v[178:179]
	v_cvt_pk_bf16_f32 v118, v118, v119
	v_cvt_pk_bf16_f32 v119, v120, v121
	v_mov_b32_e32 v158, v118
	v_mov_b32_e32 v159, v119
	s_nop 1
	v_permlane16_swap_b32_e32 v156, v158
	v_permlane16_swap_b32_e32 v157, v159
	global_store_dwordx4 v[142:143], v[156:159], off
	v_cvt_pk_bf16_f32 v114, v114, v115
	v_cvt_pk_bf16_f32 v115, v116, v117
	v_mov_b32_e32 v162, v114
	v_mov_b32_e32 v163, v115
	s_nop 1
	v_permlane16_swap_b32_e32 v160, v162
	v_permlane16_swap_b32_e32 v161, v163
	global_store_dwordx4 v[172:173], v[160:163], off
	v_cvt_pk_bf16_f32 v110, v110, v111
	v_cvt_pk_bf16_f32 v111, v112, v113
	v_mov_b32_e32 v164, v110
	v_mov_b32_e32 v165, v111
	v_lshl_add_u64 v[174:175], v[138:139], 0, v[178:179]
	v_cvt_pk_bf16_f32 v106, v106, v107
	v_cvt_pk_bf16_f32 v107, v108, v109
	v_mov_b32_e32 v168, v106
	v_mov_b32_e32 v169, v107
	v_lshl_add_u64 v[176:177], v[128:129], 0, v[178:179]
	v_cvt_pk_bf16_f32 v102, v102, v103
	v_cvt_pk_bf16_f32 v103, v104, v105
	v_mov_b32_e32 v166, v102
	v_mov_b32_e32 v167, v103
	s_nop 1
	v_permlane16_swap_b32_e32 v164, v166
	v_permlane16_swap_b32_e32 v165, v167
	global_store_dwordx4 v[174:175], v[164:167], off offset:64
	v_cvt_pk_bf16_f32 v98, v98, v99
	v_cvt_pk_bf16_f32 v99, v100, v101
	v_mov_b32_e32 v170, v98
	v_mov_b32_e32 v171, v99
	s_nop 1
	v_permlane16_swap_b32_e32 v168, v170
	v_permlane16_swap_b32_e32 v169, v171
	global_store_dwordx4 v[176:177], v[168:171], off offset:64
	v_or_b32_e32 v98, 0x80, v132
	v_ashrrev_i32_e32 v99, 31, v98
	v_lshlrev_b64 v[98:99], 12, v[98:99]
	v_lshl_add_u64 v[100:101], v[134:135], 0, v[98:99]
	v_cvt_pk_bf16_f32 v94, v94, v95
	v_cvt_pk_bf16_f32 v95, v96, v97
	v_mov_b32_e32 v156, v94
	v_mov_b32_e32 v157, v95
	v_lshl_add_u64 v[142:143], v[100:101], 0, v[178:179]
	v_or_b32_e32 v94, 0x90, v132
	v_ashrrev_i32_e32 v95, 31, v94
	v_lshlrev_b64 v[94:95], 12, v[94:95]
	v_lshl_add_u64 v[96:97], v[134:135], 0, v[94:95]
	v_cvt_pk_bf16_f32 v90, v90, v91
	v_cvt_pk_bf16_f32 v91, v92, v93
	v_mov_b32_e32 v160, v90
	v_mov_b32_e32 v161, v91
	v_lshl_add_u64 v[172:173], v[96:97], 0, v[178:179]
	v_cvt_pk_bf16_f32 v86, v86, v87
	v_cvt_pk_bf16_f32 v87, v88, v89
	v_mov_b32_e32 v158, v86
	v_mov_b32_e32 v159, v87
	s_nop 1
	v_permlane16_swap_b32_e32 v156, v158
	v_permlane16_swap_b32_e32 v157, v159
	global_store_dwordx4 v[142:143], v[156:159], off
	v_cvt_pk_bf16_f32 v82, v82, v83
	v_cvt_pk_bf16_f32 v83, v84, v85
	v_mov_b32_e32 v162, v82
	v_mov_b32_e32 v163, v83
	s_nop 1
	v_permlane16_swap_b32_e32 v160, v162
	v_permlane16_swap_b32_e32 v161, v163
	global_store_dwordx4 v[172:173], v[160:163], off
	v_cvt_pk_bf16_f32 v78, v78, v79
	v_cvt_pk_bf16_f32 v79, v80, v81
	v_mov_b32_e32 v164, v78
	v_mov_b32_e32 v165, v79
	v_lshl_add_u64 v[174:175], v[100:101], 0, v[178:179]
	v_cvt_pk_bf16_f32 v74, v74, v75
	v_cvt_pk_bf16_f32 v75, v76, v77
	v_mov_b32_e32 v168, v74
	v_mov_b32_e32 v169, v75
	v_lshl_add_u64 v[176:177], v[96:97], 0, v[178:179]
	v_cvt_pk_bf16_f32 v70, v70, v71
	v_cvt_pk_bf16_f32 v71, v72, v73
	v_mov_b32_e32 v166, v70
	v_mov_b32_e32 v167, v71
	s_nop 1
	v_permlane16_swap_b32_e32 v164, v166
	v_permlane16_swap_b32_e32 v165, v167
	global_store_dwordx4 v[174:175], v[164:167], off offset:64
	v_cvt_pk_bf16_f32 v66, v66, v67
	v_cvt_pk_bf16_f32 v67, v68, v69
	v_mov_b32_e32 v170, v66
	v_mov_b32_e32 v171, v67
	s_nop 1
	v_permlane16_swap_b32_e32 v168, v170
	v_permlane16_swap_b32_e32 v169, v171
	global_store_dwordx4 v[176:177], v[168:171], off offset:64
	v_add_u32_e32 v66, 0x80, v130
	v_ashrrev_i32_e32 v67, 31, v66
	v_lshl_add_u64 v[66:67], v[66:67], 1, s[82:83]
	v_lshl_add_u64 v[68:69], v[66:67], 0, v[136:137]
	v_cvt_pk_bf16_f32 v62, v62, v63
	v_cvt_pk_bf16_f32 v63, v64, v65
	v_mov_b32_e32 v156, v62
	v_mov_b32_e32 v157, v63
	v_lshl_add_u64 v[142:143], v[68:69], 0, v[178:179]
	v_lshl_add_u64 v[62:63], v[66:67], 0, v[126:127]
	v_cvt_pk_bf16_f32 v58, v58, v59
	v_cvt_pk_bf16_f32 v59, v60, v61
	v_mov_b32_e32 v160, v58
	v_mov_b32_e32 v161, v59
	v_lshl_add_u64 v[172:173], v[62:63], 0, v[178:179]
	v_add_u32_e32 v58, 0x90, v130
	v_ashrrev_i32_e32 v59, 31, v58
	v_lshl_add_u64 v[58:59], v[58:59], 1, s[82:83]
	v_lshl_add_u64 v[60:61], v[58:59], 0, v[136:137]
	v_cvt_pk_bf16_f32 v54, v54, v55
	v_cvt_pk_bf16_f32 v55, v56, v57
	v_mov_b32_e32 v158, v54
	v_mov_b32_e32 v159, v55
	s_nop 1
	v_permlane16_swap_b32_e32 v156, v158
	v_permlane16_swap_b32_e32 v157, v159
; #define ACC_ZERO(acc) { float z_ = 0.f; asm volatile("" : "+v"(z_)); _Pragma("unroll") for(int ai=0;ai<2;++ai) _Pragma("unroll") for(int bj=0;bj<2;++bj) \
;   _Pragma("unroll") for(int m=0;m<4;++m) _Pragma("unroll") for(int n=0;n<2;++n) acc[ai][bj][m][n]=f32x4{z_,z_,z_,z_}; }
; #define EPI_LOOP(...) _Pragma("unroll") for(int ai=0;ai<2;++ai) _Pragma("unroll") for(int bj=0;bj<2;++bj) \
;   _Pragma("unroll") for(int m=0;m<4;++m) _Pragma("unroll") for(int n=0;n<2;++n) { \
;     const int row=brow+ai*128+wr*64+m*16+fq*4; const int col=bcol+bj*128+wc*32+n*16+fr; \
;     f32x4& v=acc[ai][bj][m][n]; __VA_ARGS__ if (n == 1 && (m & 1)) __builtin_amdgcn_sched_barrier(0); }
; DEVI void gemm_core(const bf16* __restrict__ A, const long lda, const bf16* __restrict__ Bt, const long ldb, const int K,
;                     acc_t& acc, bf16* shm, const int wave_u) {
; DEVI void run_phase(const int ph, const Params& P, char* shmc, const int wave_u) {
;     ...
;       { GEMM_IDS
;       EPI_LOOP({ st_bf4(ub + (long)col * 2048 + row, v[0], v[1], v[2], v[3]); })
;       }
;       ACC_ZERO(acc)
;       gemm_core(w_pg_t + (long)brow * 2048, 2048, xb + (long)bcol * 2048, 2048, 2048, acc, shm, wave_u);
	global_store_dwordx4 v[142:143], v[156:159], off
	v_lshl_add_u64 v[54:55], v[58:59], 0, v[126:127]
	v_cvt_pk_bf16_f32 v50, v50, v51
	v_cvt_pk_bf16_f32 v51, v52, v53
	v_mov_b32_e32 v162, v50
	v_mov_b32_e32 v163, v51
	s_nop 1
	v_permlane16_swap_b32_e32 v160, v162
	v_permlane16_swap_b32_e32 v161, v163
	global_store_dwordx4 v[172:173], v[160:163], off
	v_add_u32_e32 v50, 0xa0, v130
	v_ashrrev_i32_e32 v51, 31, v50
	v_lshl_add_u64 v[50:51], v[50:51], 1, s[82:83]
	v_lshl_add_u64 v[52:53], v[50:51], 0, v[136:137]
	v_cvt_pk_bf16_f32 v46, v46, v47
	v_cvt_pk_bf16_f32 v47, v48, v49
	v_mov_b32_e32 v164, v46
	v_mov_b32_e32 v165, v47
	v_lshl_add_u64 v[174:175], v[52:53], 0, v[178:179]
	v_lshl_add_u64 v[46:47], v[50:51], 0, v[126:127]
	v_cvt_pk_bf16_f32 v42, v42, v43
	v_cvt_pk_bf16_f32 v43, v44, v45
	v_mov_b32_e32 v168, v42
	v_mov_b32_e32 v169, v43
	v_lshl_add_u64 v[176:177], v[46:47], 0, v[178:179]
	v_add_u32_e32 v42, 0xb0, v130
	v_ashrrev_i32_e32 v43, 31, v42
	v_lshl_add_u64 v[42:43], v[42:43], 1, s[82:83]
	v_lshl_add_u64 v[44:45], v[42:43], 0, v[136:137]
	v_cvt_pk_bf16_f32 v38, v38, v39
	v_cvt_pk_bf16_f32 v39, v40, v41
	v_mov_b32_e32 v166, v38
	v_mov_b32_e32 v167, v39
	s_nop 1
	v_permlane16_swap_b32_e32 v164, v166
	v_permlane16_swap_b32_e32 v165, v167
	global_store_dwordx4 v[174:175], v[164:167], off
	v_lshl_add_u64 v[38:39], v[42:43], 0, v[126:127]
	v_cvt_pk_bf16_f32 v34, v34, v35
	v_cvt_pk_bf16_f32 v35, v36, v37
	v_mov_b32_e32 v170, v34
	v_mov_b32_e32 v171, v35
	s_nop 1
	v_permlane16_swap_b32_e32 v168, v170
	v_permlane16_swap_b32_e32 v169, v171
	global_store_dwordx4 v[176:177], v[168:171], off
	v_lshl_add_u64 v[34:35], v[66:67], 0, v[98:99]
	v_cvt_pk_bf16_f32 v28, v28, v29
	v_cvt_pk_bf16_f32 v29, v30, v31
	v_mov_b32_e32 v156, v28
	v_mov_b32_e32 v157, v29
	v_lshl_add_u64 v[142:143], v[34:35], 0, v[178:179]
	v_lshl_add_u64 v[28:29], v[66:67], 0, v[94:95]
	v_cvt_pk_bf16_f32 v24, v24, v25
	v_cvt_pk_bf16_f32 v25, v26, v27
	v_mov_b32_e32 v160, v24
	v_mov_b32_e32 v161, v25
	v_lshl_add_u64 v[172:173], v[28:29], 0, v[178:179]
	v_lshl_add_u64 v[24:25], v[58:59], 0, v[98:99]
	v_cvt_pk_bf16_f32 v20, v20, v21
	v_cvt_pk_bf16_f32 v21, v22, v23
	v_mov_b32_e32 v158, v20
	v_mov_b32_e32 v159, v21
	s_nop 1
	v_permlane16_swap_b32_e32 v156, v158
	v_permlane16_swap_b32_e32 v157, v159
	global_store_dwordx4 v[142:143], v[156:159], off
	v_lshl_add_u64 v[20:21], v[58:59], 0, v[94:95]
	v_cvt_pk_bf16_f32 v16, v16, v17
	v_cvt_pk_bf16_f32 v17, v18, v19
	v_mov_b32_e32 v162, v16
	v_mov_b32_e32 v163, v17
	s_nop 1
	v_permlane16_swap_b32_e32 v160, v162
	v_permlane16_swap_b32_e32 v161, v163
	global_store_dwordx4 v[172:173], v[160:163], off
	v_lshl_add_u64 v[16:17], v[50:51], 0, v[98:99]
	v_cvt_pk_bf16_f32 v12, v12, v13
	v_cvt_pk_bf16_f32 v13, v14, v15
	v_mov_b32_e32 v164, v12
	v_mov_b32_e32 v165, v13
	v_lshl_add_u64 v[174:175], v[16:17], 0, v[178:179]
	v_lshl_add_u64 v[12:13], v[50:51], 0, v[94:95]
	v_cvt_pk_bf16_f32 v8, v8, v9
	v_cvt_pk_bf16_f32 v9, v10, v11
	v_mov_b32_e32 v168, v8
	v_mov_b32_e32 v169, v9
	v_lshl_add_u64 v[176:177], v[12:13], 0, v[178:179]
	v_lshl_add_u64 v[8:9], v[42:43], 0, v[98:99]
	v_cvt_pk_bf16_f32 v4, v4, v5
	v_cvt_pk_bf16_f32 v5, v6, v7
	v_mov_b32_e32 v166, v4
	v_mov_b32_e32 v167, v5
	s_nop 1
	v_permlane16_swap_b32_e32 v164, v166
	v_permlane16_swap_b32_e32 v165, v167
	global_store_dwordx4 v[174:175], v[164:167], off
	v_lshl_add_u64 v[4:5], v[42:43], 0, v[94:95]
	v_cvt_pk_bf16_f32 v0, v0, v1
	v_cvt_pk_bf16_f32 v1, v2, v3
	v_mov_b32_e32 v170, v0
	v_mov_b32_e32 v171, v1
	s_nop 1
	v_permlane16_swap_b32_e32 v168, v170
	v_permlane16_swap_b32_e32 v169, v171
	global_store_dwordx4 v[176:177], v[168:171], off
	v_mov_b32_e32 v0, v33
	v_mbcnt_lo_u32_b32 v10, -1, 0
	v_mbcnt_hi_u32_b32 v10, -1, v10
	s_lshl_b64 s[8:9], s[0:1], 12
	v_or_b32_e32 v140, s5, v10
	v_bfe_i32 v2, v140, 27, 1
	v_lshlrev_b32_e32 v14, 4, v140
	v_lshrrev_b32_e32 v2, 22, v2
	v_add_u32_e32 v2, v14, v2
	v_and_b32_e32 v2, 0xfffffc00, v2
	v_sub_u32_e32 v2, v14, v2
	v_lshrrev_b32_e32 v3, 4, v2
	v_ashrrev_i32_e32 v1, 31, v140
	v_bitop3_b32 v2, v3, v2, 32 bitop3:0x6c
	v_lshrrev_b32_e32 v1, 26, v1
	v_ashrrev_i32_e32 v4, 31, v2
	v_add_u32_e32 v1, v140, v1
	v_lshrrev_b32_e32 v4, 26, v4
	v_ashrrev_i32_e32 v1, 6, v1
	v_add_u32_e32 v4, v2, v4
	v_lshlrev_b32_e32 v3, 3, v1
	v_ashrrev_i32_e32 v11, 6, v4
	v_and_b32_e32 v4, 0xc0, v4
	v_and_b32_e32 v3, 0xffff0, v3
	v_lshlrev_b32_e32 v5, 5, v1
	v_sub_u32_e32 v2, v2, v4
	v_add_u32_e32 v3, v11, v3
	v_and_b32_e32 v12, 32, v5
	v_ashrrev_i16_sdwa v2, v187, sext(v2) dst_sel:DWORD dst_unused:UNUSED_PAD src0_sel:DWORD src1_sel:BYTE_0
	v_bfe_i32 v13, v2, 0, 16
	v_lshl_or_b32 v2, v3, 11, v12
	v_add_lshl_u32 v32, v2, v13, 1
	v_add_u32_e32 v2, 0x2000, v14
	v_ashrrev_i32_e32 v3, 31, v2
	v_lshrrev_b32_e32 v3, 22, v3
	v_add_u32_e32 v3, v2, v3
	v_ashrrev_i32_e32 v15, 10, v3
	v_mul_i32_i24_e32 v3, 0x400, v15
	v_sub_u32_e32 v3, v2, v3
	v_lshrrev_b32_e32 v4, 4, v3
	v_bitop3_b32 v3, v4, v3, 32 bitop3:0x6c
	v_ashrrev_i32_e32 v5, 31, v3
	v_lshrrev_b32_e32 v5, 26, v5
	v_add_u32_e32 v5, v3, v5
	v_lshlrev_b32_e32 v4, 3, v15
	v_ashrrev_i32_e32 v16, 6, v5
	v_and_b32_e32 v5, 0xc0, v5
	v_readlane_b32 s16, v255, 21
	v_and_b32_e32 v4, 0xffff0, v4
	v_lshlrev_b32_e32 v6, 5, v15
	v_sub_u32_e32 v3, v3, v5
	v_readlane_b32 s17, v255, 22
	s_add_u32 s38, s16, s8
	v_add_u32_e32 v4, v16, v4
	v_and_b32_e32 v17, 32, v6
	v_ashrrev_i16_sdwa v3, v187, sext(v3) dst_sel:DWORD dst_unused:UNUSED_PAD src0_sel:DWORD src1_sel:BYTE_0
	s_addc_u32 s39, s17, s9
	s_lshl_b64 s[68:69], s[6:7], 12
	v_readlane_b32 s16, v255, 17
	v_add_u32_e32 v145, s33, v14
	v_bfe_i32 v18, v3, 0, 16
	v_lshl_or_b32 v3, v4, 11, v17
	v_readlane_b32 s17, v255, 18
	s_add_u32 s70, s16, s68
	v_readfirstlane_b32 s1, v145
	v_add_lshl_u32 v130, v3, v18, 1
	v_add_u32_e32 v3, s33, v2
	s_addc_u32 s71, s17, s69
	s_waitcnt vmcnt(0)
;   #define STAGE(P,BASE,LD,br,kt) do{const char* _ub=(const char*)((BASE)+(long)(br)*(LD)+(long)(kt)*BK); \
;     for(int _i=0;_i<2;++_i){int _b=tidg*16+_i*8192;int _r,_c;stage_rc(_b,_r,_c); \
;       const unsigned _vo=(unsigned)(_r*(int)(LD)+_c)*2u; \
;       __builtin_amdgcn_global_load_lds((const unsigned*)(_ub+_vo), \
;         (unsigned*)((char*)(P)+_b),16,0,0);}}while(0)
;   #define WAIT_V(n) asm volatile("s_waitcnt vmcnt(" #n ")":::"memory")
;   #define BAR __builtin_amdgcn_s_barrier()
; DEVI void gemm_core(const bf16* __restrict__ A, const long lda, const bf16* __restrict__ Bt, const long ldb, const int K,
;                     acc_t& acc, bf16* shm, const int wave_u) {
;     ...
;   int tidg = get_tid(wave_u);
;   const int wid=tidg>>6,lane=tidg&63,wr=wid>>2,wc=wid&3,fr=lane&15,fq=lane>>4;
;   bf16x8 At[4][2],B0[2][2],B1[2][2];
;   const int nt=K/BK;
;   WAIT_V(0);
;   STAGE(SB(0,0),Bt,ldb,0,0); STAGE(SA(0,0),A,lda,0,0);
;   STAGE(SB(0,1),Bt,ldb,HALF,0); STAGE(SA(0,1),A,lda,HALF,0);
;   if(wr==1)BAR;
;   WAIT_V(4); BAR;
	s_mov_b32 m0, s1
	v_readfirstlane_b32 s1, v3
	v_add_u32_e32 v149, 16, v14
	global_load_lds_dwordx4 v32, s[70:71]
	s_mov_b32 m0, s1
	v_readfirstlane_b32 s1, v149
	v_add_u32_e32 v150, 0x2000, v149
	global_load_lds_dwordx4 v130, s[70:71]
	s_mov_b32 m0, s1
	v_readfirstlane_b32 s1, v150
	v_add_u32_e32 v152, s74, v14
	global_load_lds_dwordx4 v32, s[38:39]
	s_mov_b32 m0, s1
	s_add_u32 s72, s70, 0x80000
	v_readfirstlane_b32 s1, v152
	v_add_u32_e32 v2, s74, v2
	global_load_lds_dwordx4 v130, s[38:39]
	s_addc_u32 s73, s71, 0
	s_mov_b32 m0, s1
	v_readfirstlane_b32 s1, v2
	global_load_lds_dwordx4 v32, s[72:73]
	s_mov_b32 m0, s1
	v_add_u32_e32 v153, 0x4000, v149
	global_load_lds_dwordx4 v130, s[72:73]
	s_add_u32 s72, s38, 0x80000
	v_readfirstlane_b32 s1, v153
	v_add_u32_e32 v154, 0x6000, v149
	s_addc_u32 s73, s39, 0
	s_mov_b32 m0, s1
	v_readfirstlane_b32 s1, v154
	global_load_lds_dwordx4 v32, s[72:73]
	s_mov_b32 m0, s1
	v_mov_b32_e32 v131, v33
	global_load_lds_dwordx4 v130, s[72:73]
	v_ashrrev_i32_e32 v19, 8, v140
	v_lshl_add_u64 v[8:9], s[70:71], 0, v[32:33]
	v_lshl_add_u64 v[6:7], s[70:71], 0, v[130:131]
	v_lshl_add_u64 v[4:5], s[38:39], 0, v[32:33]
	v_lshl_add_u64 v[2:3], s[38:39], 0, v[130:131]
	v_cmp_eq_u32_e32 vcc, 1, v19
	s_and_saveexec_b64 s[72:73], vcc
	s_cbranch_execz .LBB0_66
	s_barrier

; #define ACC_ZERO(acc) { float z_ = 0.f; asm volatile("" : "+v"(z_)); _Pragma("unroll") for(int ai=0;ai<2;++ai) _Pragma("unroll") for(int bj=0;bj<2;++bj) \
;   _Pragma("unroll") for(int m=0;m<4;++m) _Pragma("unroll") for(int n=0;n<2;++n) acc[ai][bj][m][n]=f32x4{z_,z_,z_,z_}; }
; #define EPI_LOOP(...) _Pragma("unroll") for(int ai=0;ai<2;++ai) _Pragma("unroll") for(int bj=0;bj<2;++bj) \
;   _Pragma("unroll") for(int m=0;m<4;++m) _Pragma("unroll") for(int n=0;n<2;++n) { \
;     const int row=brow+ai*128+wr*64+m*16+fq*4; const int col=bcol+bj*128+wc*32+n*16+fr; \
;     f32x4& v=acc[ai][bj][m][n]; __VA_ARGS__ if (n == 1 && (m & 1)) __builtin_amdgcn_sched_barrier(0); }
; DEVI void run_phase(const int ph, const Params& P, char* shmc, const int wave_u) {
;     ...
;         const int r = j / 8, ks = j % 8;
;         const int brow = (r & 7) * 256, bcol = MP + (r >> 3) * 256;
;         const int kofs = ks * 256;
;         acc_t acc; ACC_ZERO(acc)
;         gemm_core(w_pg_t + (long)brow * 2048 + kofs, 2048, xb + (long)bcol * 2048 + kofs, 2048, 256, acc, shm, wave_u);
;         GEMM_IDS
;         EPI_LOOP({ st_f4(Tp + (long)ks * MS * 2048 + (long)(col - MP) * 2048 + row, v[0], v[1], v[2], v[3]); })
.LBB0_70:
	s_or_b64 exec, exec, s[6:7]
	v_readlane_b32 s5, v255, 6
	v_mbcnt_lo_u32_b32 v32, -1, 0
	v_mbcnt_hi_u32_b32 v32, -1, v32
	s_lshl_b32 s1, s72, 3
	v_and_b32_e32 v132, 15, v32
	v_or_b32_e32 v131, s5, v32
	v_ashrrev_i32_e32 v130, 2, v131
	v_lshrrev_b32_e32 v32, 2, v32
	s_sub_i32 s6, s70, s1
	v_and_b32_e32 v130, 0xffffffc0, v130
	v_and_or_b32 v32, v32, 12, s71
	v_add_u32_e32 v130, v32, v130
	v_lshrrev_b32_e32 v32, 1, v131
	s_ashr_i32 s7, s6, 31
	v_and_b32_e32 v32, 0x60, v32
	s_lshl_b64 s[6:7], s[6:7], 22
	s_add_u32 s6, s66, s6
	v_or3_b32 v132, v132, v32, s0
	s_addc_u32 s7, s67, s7
	v_ashrrev_i32_e32 v131, 31, v130
	v_ashrrev_i32_e32 v133, 31, v132
	v_lshl_add_u64 v[130:131], v[130:131], 2, s[6:7]
	v_lshlrev_b64 v[134:135], 13, v[132:133]
	v_lshl_add_u64 v[134:135], v[130:131], 0, v[134:135]
	global_store_dwordx4 v[134:135], v[28:31], off
	s_nop 1
	v_or_b32_e32 v28, 16, v132
	v_ashrrev_i32_e32 v29, 31, v28
	v_lshlrev_b64 v[28:29], 13, v[28:29]
	v_lshl_add_u64 v[28:29], v[130:131], 0, v[28:29]
	global_store_dwordx4 v[28:29], v[0:3], off
	global_store_dwordx4 v[134:135], v[4:7], off offset:64
	global_store_dwordx4 v[28:29], v[8:11], off offset:64
	global_store_dwordx4 v[134:135], v[12:15], off offset:128
	global_store_dwordx4 v[28:29], v[16:19], off offset:128
	global_store_dwordx4 v[134:135], v[20:23], off offset:192
	global_store_dwordx4 v[28:29], v[34:37], off offset:192
	v_or_b32_e32 v0, 0x80, v132
	v_or_b32_e32 v2, 0x90, v132
	v_ashrrev_i32_e32 v1, 31, v0
	v_ashrrev_i32_e32 v3, 31, v2
	v_lshlrev_b64 v[0:1], 13, v[0:1]
	v_lshlrev_b64 v[2:3], 13, v[2:3]
	v_lshl_add_u64 v[0:1], v[130:131], 0, v[0:1]
	v_lshl_add_u64 v[2:3], v[130:131], 0, v[2:3]
	global_store_dwordx4 v[0:1], v[58:61], off
	global_store_dwordx4 v[2:3], v[24:27], off
	global_store_dwordx4 v[0:1], v[38:41], off offset:64
	global_store_dwordx4 v[2:3], v[42:45], off offset:64
	global_store_dwordx4 v[0:1], v[46:49], off offset:128
	global_store_dwordx4 v[2:3], v[50:53], off offset:128
	global_store_dwordx4 v[0:1], v[54:57], off offset:192
	global_store_dwordx4 v[2:3], v[62:65], off offset:192
	global_store_dwordx4 v[134:135], v[66:69], off offset:512
	global_store_dwordx4 v[28:29], v[70:73], off offset:512
	global_store_dwordx4 v[134:135], v[74:77], off offset:576
	global_store_dwordx4 v[28:29], v[78:81], off offset:576
	global_store_dwordx4 v[134:135], v[82:85], off offset:640
	global_store_dwordx4 v[28:29], v[86:89], off offset:640
	global_store_dwordx4 v[134:135], v[90:93], off offset:704
	global_store_dwordx4 v[28:29], v[94:97], off offset:704
	global_store_dwordx4 v[0:1], v[98:101], off offset:512
	global_store_dwordx4 v[2:3], v[102:105], off offset:512
	global_store_dwordx4 v[0:1], v[106:109], off offset:576
	global_store_dwordx4 v[2:3], v[110:113], off offset:576
	global_store_dwordx4 v[0:1], v[114:117], off offset:640
	global_store_dwordx4 v[2:3], v[118:121], off offset:640
	global_store_dwordx4 v[0:1], v[122:125], off offset:704
	global_store_dwordx4 v[2:3], v[126:129], off offset:704

; #define ACC_ZERO(acc) { float z_ = 0.f; asm volatile("" : "+v"(z_)); _Pragma("unroll") for(int ai=0;ai<2;++ai) _Pragma("unroll") for(int bj=0;bj<2;++bj) \
;   _Pragma("unroll") for(int m=0;m<4;++m) _Pragma("unroll") for(int n=0;n<2;++n) acc[ai][bj][m][n]=f32x4{z_,z_,z_,z_}; }
; #define EPI_LOOP(...) _Pragma("unroll") for(int ai=0;ai<2;++ai) _Pragma("unroll") for(int bj=0;bj<2;++bj) \
;   _Pragma("unroll") for(int m=0;m<4;++m) _Pragma("unroll") for(int n=0;n<2;++n) { \
;     const int row=brow+ai*128+wr*64+m*16+fq*4; const int col=bcol+bj*128+wc*32+n*16+fr; \
;     f32x4& v=acc[ai][bj][m][n]; __VA_ARGS__ if (n == 1 && (m & 1)) __builtin_amdgcn_sched_barrier(0); }
; DEVI void run_phase(const int ph, const Params& P, char* shmc, const int wave_u) {
;     ...
;         const int r = j - 128;
;         const int brow = (r & 7) * 256, bcol = MP + (r >> 3) * 256;
;         acc_t acc; ACC_ZERO(acc)
;         gemm_core(w_ple_t + (long)brow * 256, 256, pb + (long)bcol * 256, 256, 256, acc, shm, wave_u);
;         GEMM_IDS
;         EPI_LOOP({ st_bf4(ub + (long)col * 2048 + row, v[0], v[1], v[2], v[3]); })
.LBB0_77:
	s_or_b64 exec, exec, s[0:1]
	v_mbcnt_lo_u32_b32 v160, -1, 0
	v_mbcnt_hi_u32_b32 v160, -1, v160
	v_bfe_u32 v160, v160, 4, 1
	v_mul_u32_u24_e32 v160, 24, v160
	v_mov_b32_e32 v161, 0
	v_mbcnt_lo_u32_b32 v32, -1, 0
	v_mbcnt_hi_u32_b32 v32, -1, v32
	v_readlane_b32 s0, v254, 47
	v_or_b32_e32 v131, s5, v32
	v_and_b32_e32 v132, 15, v32
	v_ashrrev_i32_e32 v130, 2, v131
	v_lshrrev_b32_e32 v32, 2, v32
	v_and_b32_e32 v130, 0xffffffc0, v130
	v_and_or_b32 v32, v32, 12, s38
	v_add_u32_e32 v130, v32, v130
	v_lshrrev_b32_e32 v32, 1, v131
	v_and_b32_e32 v32, 0x60, v32
	v_or3_b32 v32, v132, v32, s0
	v_ashrrev_i32_e32 v131, 31, v130
	v_lshl_add_u64 v[130:131], v[130:131], 1, s[82:83]
	v_lshlrev_b64 v[132:133], 12, v[32:33]
	v_lshl_add_u64 v[132:133], v[130:131], 0, v[132:133]
	v_cvt_pk_bf16_f32 v126, v126, v127
	v_cvt_pk_bf16_f32 v127, v128, v129
	v_mov_b32_e32 v136, v126
	v_mov_b32_e32 v137, v127
	v_lshl_add_u64 v[134:135], v[132:133], 0, v[160:161]
	v_or_b32_e32 v126, 16, v32
	v_mov_b32_e32 v127, v33
	v_lshlrev_b64 v[126:127], 12, v[126:127]
	v_readlane_b32 s1, v254, 48
	v_lshl_add_u64 v[126:127], v[130:131], 0, v[126:127]
	v_cvt_pk_bf16_f32 v122, v122, v123
	v_cvt_pk_bf16_f32 v123, v124, v125
	v_mov_b32_e32 v140, v122
	v_mov_b32_e32 v141, v123
	v_lshl_add_u64 v[144:145], v[126:127], 0, v[160:161]
	v_cvt_pk_bf16_f32 v118, v118, v119
	v_cvt_pk_bf16_f32 v119, v120, v121
	v_mov_b32_e32 v138, v118
	v_mov_b32_e32 v139, v119
	s_nop 1
	v_permlane16_swap_b32_e32 v136, v138
	v_permlane16_swap_b32_e32 v137, v139
	global_store_dwordx4 v[134:135], v[136:139], off
	v_cvt_pk_bf16_f32 v114, v114, v115
	v_cvt_pk_bf16_f32 v115, v116, v117
	v_mov_b32_e32 v142, v114
	v_mov_b32_e32 v143, v115
	s_nop 1
	v_permlane16_swap_b32_e32 v140, v142
	v_permlane16_swap_b32_e32 v141, v143
	global_store_dwordx4 v[144:145], v[140:143], off
	v_cvt_pk_bf16_f32 v110, v110, v111
	v_cvt_pk_bf16_f32 v111, v112, v113
	v_mov_b32_e32 v148, v110
	v_mov_b32_e32 v149, v111
	v_lshl_add_u64 v[156:157], v[132:133], 0, v[160:161]
	v_cvt_pk_bf16_f32 v106, v106, v107
	v_cvt_pk_bf16_f32 v107, v108, v109
	v_mov_b32_e32 v152, v106
	v_mov_b32_e32 v153, v107
	v_lshl_add_u64 v[158:159], v[126:127], 0, v[160:161]
	v_cvt_pk_bf16_f32 v102, v102, v103
	v_cvt_pk_bf16_f32 v103, v104, v105
	v_mov_b32_e32 v150, v102
	v_mov_b32_e32 v151, v103
	s_nop 1
	v_permlane16_swap_b32_e32 v148, v150
	v_permlane16_swap_b32_e32 v149, v151
	global_store_dwordx4 v[156:157], v[148:151], off offset:64
	v_cvt_pk_bf16_f32 v98, v98, v99
	v_cvt_pk_bf16_f32 v99, v100, v101
	v_mov_b32_e32 v154, v98
	v_mov_b32_e32 v155, v99
	s_nop 1
	v_permlane16_swap_b32_e32 v152, v154
	v_permlane16_swap_b32_e32 v153, v155
	global_store_dwordx4 v[158:159], v[152:155], off offset:64
	v_or_b32_e32 v98, 0x80, v32
	v_mov_b32_e32 v99, v33
	v_lshlrev_b64 v[98:99], 12, v[98:99]
	v_lshl_add_u64 v[98:99], v[130:131], 0, v[98:99]
	v_cvt_pk_bf16_f32 v94, v94, v95
	v_cvt_pk_bf16_f32 v95, v96, v97
	v_or_b32_e32 v32, 0x90, v32
	v_mov_b32_e32 v136, v94
	v_mov_b32_e32 v137, v95
	v_lshl_add_u64 v[134:135], v[98:99], 0, v[160:161]
	v_lshlrev_b64 v[94:95], 12, v[32:33]
	v_lshl_add_u64 v[94:95], v[130:131], 0, v[94:95]
	v_cvt_pk_bf16_f32 v90, v90, v91
	v_cvt_pk_bf16_f32 v91, v92, v93
	v_mov_b32_e32 v140, v90
	v_mov_b32_e32 v141, v91
	v_lshl_add_u64 v[144:145], v[94:95], 0, v[160:161]
	v_cvt_pk_bf16_f32 v86, v86, v87
	v_cvt_pk_bf16_f32 v87, v88, v89
	v_mov_b32_e32 v138, v86
	v_mov_b32_e32 v139, v87
	s_nop 1
	v_permlane16_swap_b32_e32 v136, v138
	v_permlane16_swap_b32_e32 v137, v139
	global_store_dwordx4 v[134:135], v[136:139], off
	v_cvt_pk_bf16_f32 v82, v82, v83
	v_cvt_pk_bf16_f32 v83, v84, v85
	v_mov_b32_e32 v142, v82
	v_mov_b32_e32 v143, v83
	s_nop 1
	v_permlane16_swap_b32_e32 v140, v142
	v_permlane16_swap_b32_e32 v141, v143
	global_store_dwordx4 v[144:145], v[140:143], off
	v_cvt_pk_bf16_f32 v78, v78, v79
	v_cvt_pk_bf16_f32 v79, v80, v81
	v_mov_b32_e32 v148, v78
	v_mov_b32_e32 v149, v79
	v_lshl_add_u64 v[156:157], v[98:99], 0, v[160:161]
	v_cvt_pk_bf16_f32 v74, v74, v75
	v_cvt_pk_bf16_f32 v75, v76, v77
; #define ACC_ZERO(acc) { float z_ = 0.f; asm volatile("" : "+v"(z_)); _Pragma("unroll") for(int ai=0;ai<2;++ai) _Pragma("unroll") for(int bj=0;bj<2;++bj) \
;   _Pragma("unroll") for(int m=0;m<4;++m) _Pragma("unroll") for(int n=0;n<2;++n) acc[ai][bj][m][n]=f32x4{z_,z_,z_,z_}; }
; #define EPI_LOOP(...) _Pragma("unroll") for(int ai=0;ai<2;++ai) _Pragma("unroll") for(int bj=0;bj<2;++bj) \
;   _Pragma("unroll") for(int m=0;m<4;++m) _Pragma("unroll") for(int n=0;n<2;++n) { \
;     const int row=brow+ai*128+wr*64+m*16+fq*4; const int col=bcol+bj*128+wc*32+n*16+fr; \
;     f32x4& v=acc[ai][bj][m][n]; __VA_ARGS__ if (n == 1 && (m & 1)) __builtin_amdgcn_sched_barrier(0); }
; DEVI void run_phase(const int ph, const Params& P, char* shmc, const int wave_u) {
;     ...
;         const int r = j - 128;
;         const int brow = (r & 7) * 256, bcol = MP + (r >> 3) * 256;
;         acc_t acc; ACC_ZERO(acc)
;         gemm_core(w_ple_t + (long)brow * 256, 256, pb + (long)bcol * 256, 256, 256, acc, shm, wave_u);
;         GEMM_IDS
;         EPI_LOOP({ st_bf4(ub + (long)col * 2048 + row, v[0], v[1], v[2], v[3]); })
	v_mov_b32_e32 v152, v74
	v_mov_b32_e32 v153, v75
	v_lshl_add_u64 v[158:159], v[94:95], 0, v[160:161]
	v_cvt_pk_bf16_f32 v70, v70, v71
	v_cvt_pk_bf16_f32 v71, v72, v73
	v_mov_b32_e32 v150, v70
	v_mov_b32_e32 v151, v71
	s_nop 1
	v_permlane16_swap_b32_e32 v148, v150
	v_permlane16_swap_b32_e32 v149, v151
	global_store_dwordx4 v[156:157], v[148:151], off offset:64
	v_cvt_pk_bf16_f32 v62, v62, v63
	v_cvt_pk_bf16_f32 v63, v64, v65
	v_mov_b32_e32 v154, v62
	v_mov_b32_e32 v155, v63
	s_nop 1
	v_permlane16_swap_b32_e32 v152, v154
	v_permlane16_swap_b32_e32 v153, v155
	global_store_dwordx4 v[158:159], v[152:155], off offset:64
	v_cvt_pk_bf16_f32 v62, v66, v67
	v_cvt_pk_bf16_f32 v63, v68, v69
	v_mov_b32_e32 v136, v62
	v_mov_b32_e32 v137, v63
	v_lshl_add_u64 v[134:135], v[132:133], 0, v[160:161]
	v_cvt_pk_bf16_f32 v58, v58, v59
	v_cvt_pk_bf16_f32 v59, v60, v61
	v_mov_b32_e32 v140, v58
	v_mov_b32_e32 v141, v59
	v_lshl_add_u64 v[144:145], v[126:127], 0, v[160:161]
	v_cvt_pk_bf16_f32 v54, v54, v55
	v_cvt_pk_bf16_f32 v55, v56, v57
	v_mov_b32_e32 v138, v54
	v_mov_b32_e32 v139, v55
	s_nop 1
	v_permlane16_swap_b32_e32 v136, v138
	v_permlane16_swap_b32_e32 v137, v139
	global_store_dwordx4 v[134:135], v[136:139], off offset:256
	v_cvt_pk_bf16_f32 v50, v50, v51
	v_cvt_pk_bf16_f32 v51, v52, v53
	v_mov_b32_e32 v142, v50
	v_mov_b32_e32 v143, v51
	s_nop 1
	v_permlane16_swap_b32_e32 v140, v142
	v_permlane16_swap_b32_e32 v141, v143
	global_store_dwordx4 v[144:145], v[140:143], off offset:256
	v_cvt_pk_bf16_f32 v46, v46, v47
	v_cvt_pk_bf16_f32 v47, v48, v49
	v_mov_b32_e32 v148, v46
	v_mov_b32_e32 v149, v47
	v_lshl_add_u64 v[156:157], v[132:133], 0, v[160:161]
	v_cvt_pk_bf16_f32 v42, v42, v43
	v_cvt_pk_bf16_f32 v43, v44, v45
	v_mov_b32_e32 v152, v42
	v_mov_b32_e32 v153, v43
	v_lshl_add_u64 v[158:159], v[126:127], 0, v[160:161]
	v_cvt_pk_bf16_f32 v38, v38, v39
	v_cvt_pk_bf16_f32 v39, v40, v41
	v_mov_b32_e32 v150, v38
	v_mov_b32_e32 v151, v39
	s_nop 1
	v_permlane16_swap_b32_e32 v148, v150
	v_permlane16_swap_b32_e32 v149, v151
	global_store_dwordx4 v[156:157], v[148:151], off offset:320
	v_cvt_pk_bf16_f32 v34, v34, v35
	v_cvt_pk_bf16_f32 v35, v36, v37
	v_mov_b32_e32 v154, v34
	v_mov_b32_e32 v155, v35
	s_nop 1
	v_permlane16_swap_b32_e32 v152, v154
	v_permlane16_swap_b32_e32 v153, v155
	global_store_dwordx4 v[158:159], v[152:155], off offset:320
	v_cvt_pk_bf16_f32 v28, v28, v29
	v_cvt_pk_bf16_f32 v29, v30, v31
	v_mov_b32_e32 v136, v28
	v_mov_b32_e32 v137, v29
	v_lshl_add_u64 v[134:135], v[98:99], 0, v[160:161]
	v_cvt_pk_bf16_f32 v24, v24, v25
	v_cvt_pk_bf16_f32 v25, v26, v27
	v_mov_b32_e32 v140, v24
	v_mov_b32_e32 v141, v25
	v_lshl_add_u64 v[144:145], v[94:95], 0, v[160:161]
	v_cvt_pk_bf16_f32 v20, v20, v21
	v_cvt_pk_bf16_f32 v21, v22, v23
	v_mov_b32_e32 v138, v20
	v_mov_b32_e32 v139, v21
	s_nop 1
	v_permlane16_swap_b32_e32 v136, v138
	v_permlane16_swap_b32_e32 v137, v139
	global_store_dwordx4 v[134:135], v[136:139], off offset:256
	v_cvt_pk_bf16_f32 v16, v16, v17
	v_cvt_pk_bf16_f32 v17, v18, v19
	v_mov_b32_e32 v142, v16
	v_mov_b32_e32 v143, v17
	s_nop 1
	v_permlane16_swap_b32_e32 v140, v142
	v_permlane16_swap_b32_e32 v141, v143
	global_store_dwordx4 v[144:145], v[140:143], off offset:256
	v_cvt_pk_bf16_f32 v12, v12, v13
	v_cvt_pk_bf16_f32 v13, v14, v15
	v_mov_b32_e32 v148, v12
	v_mov_b32_e32 v149, v13
	v_lshl_add_u64 v[156:157], v[98:99], 0, v[160:161]
	v_cvt_pk_bf16_f32 v8, v8, v9
	v_cvt_pk_bf16_f32 v9, v10, v11
	v_mov_b32_e32 v152, v8
	v_mov_b32_e32 v153, v9
	v_lshl_add_u64 v[158:159], v[94:95], 0, v[160:161]
	v_cvt_pk_bf16_f32 v4, v4, v5
	v_cvt_pk_bf16_f32 v5, v6, v7
	v_mov_b32_e32 v150, v4
	v_mov_b32_e32 v151, v5
	s_nop 1
	v_permlane16_swap_b32_e32 v148, v150
	v_permlane16_swap_b32_e32 v149, v151
	global_store_dwordx4 v[156:157], v[148:151], off offset:320
	v_cvt_pk_bf16_f32 v0, v0, v1
	v_cvt_pk_bf16_f32 v1, v2, v3
	v_mov_b32_e32 v154, v0
	v_mov_b32_e32 v155, v1
	s_nop 1
	v_permlane16_swap_b32_e32 v152, v154
	v_permlane16_swap_b32_e32 v153, v155
	global_store_dwordx4 v[158:159], v[152:155], off offset:320
	s_mov_b64 s[0:1], 0

; #define ACC_ZERO(acc) { float z_ = 0.f; asm volatile("" : "+v"(z_)); _Pragma("unroll") for(int ai=0;ai<2;++ai) _Pragma("unroll") for(int bj=0;bj<2;++bj) \
;   _Pragma("unroll") for(int m=0;m<4;++m) _Pragma("unroll") for(int n=0;n<2;++n) acc[ai][bj][m][n]=f32x4{z_,z_,z_,z_}; }
; #define EPI_LOOP(...) _Pragma("unroll") for(int ai=0;ai<2;++ai) _Pragma("unroll") for(int bj=0;bj<2;++bj) \
;   _Pragma("unroll") for(int m=0;m<4;++m) _Pragma("unroll") for(int n=0;n<2;++n) { \
;     const int row=brow+ai*128+wr*64+m*16+fq*4; const int col=bcol+bj*128+wc*32+n*16+fr; \
;     f32x4& v=acc[ai][bj][m][n]; __VA_ARGS__ if (n == 1 && (m & 1)) __builtin_amdgcn_sched_barrier(0); }
; DEVI void run_phase(const int ph, const Params& P, char* shmc, const int wave_u) {
;     ...
;     for (int t = blockIdx.x; t < nM * nN; t += G) {
;       int pm, pn; tile_map(t, nM, nN, pm, pn);
;       const int brow = pm * 256, bcol = pn * 256;
;       acc_t acc; ACC_ZERO(acc)
;       gemm_core(w_dn_t + (long)brow * DFF, DFF, hid + (long)bcol * DFF, DFF, DFF, acc, shm, wave_u);
;       GEMM_IDS
;       EPI_LOOP({ st_bf4(T + (long)col * 2048 + row, v[0], v[1], v[2], v[3]); })
;     }
.LBB0_96:
	s_or_b64 exec, exec, s[6:7]
	v_mbcnt_lo_u32_b32 v166, -1, 0
	v_mbcnt_hi_u32_b32 v166, -1, v166
	v_bfe_u32 v166, v166, 4, 1
	v_mul_u32_u24_e32 v166, 24, v166
	v_mov_b32_e32 v167, 0
	v_mbcnt_lo_u32_b32 v32, -1, 0
	v_mbcnt_hi_u32_b32 v32, -1, v32
	v_cvt_pk_bf16_f32 v126, v126, v127
	v_cvt_pk_bf16_f32 v127, v128, v129
	s_nop 0
	v_or_b32_e32 v131, s5, v32
	v_and_b32_e32 v132, 15, v32
	v_ashrrev_i32_e32 v130, 2, v131
	v_lshrrev_b32_e32 v32, 2, v32
	v_and_b32_e32 v130, 0xffffffc0, v130
	v_and_or_b32 v32, v32, 12, s38
	v_add_u32_e32 v130, v32, v130
	v_lshrrev_b32_e32 v32, 1, v131
	v_and_b32_e32 v32, 0x60, v32
	v_or3_b32 v132, v132, v32, s68
	v_ashrrev_i32_e32 v131, 31, v130
	v_ashrrev_i32_e32 v133, 31, v132
	v_lshl_add_u64 v[134:135], v[130:131], 1, s[12:13]
	v_lshlrev_b64 v[136:137], 12, v[132:133]
	v_lshl_add_u64 v[138:139], v[134:135], 0, v[136:137]
	v_mov_b32_e32 v140, v126
	v_mov_b32_e32 v141, v127
	v_lshl_add_u64 v[144:145], v[138:139], 0, v[166:167]
	v_or_b32_e32 v126, 16, v132
	v_ashrrev_i32_e32 v127, 31, v126
	v_lshlrev_b64 v[126:127], 12, v[126:127]
	v_lshl_add_u64 v[128:129], v[134:135], 0, v[126:127]
	v_cvt_pk_bf16_f32 v122, v122, v123
	v_cvt_pk_bf16_f32 v123, v124, v125
	v_mov_b32_e32 v148, v122
	v_mov_b32_e32 v149, v123
	v_lshl_add_u64 v[160:161], v[128:129], 0, v[166:167]
	v_cvt_pk_bf16_f32 v118, v118, v119
	v_cvt_pk_bf16_f32 v119, v120, v121
	v_mov_b32_e32 v142, v118
	v_mov_b32_e32 v143, v119
	s_nop 1
	v_permlane16_swap_b32_e32 v140, v142
	v_permlane16_swap_b32_e32 v141, v143
	global_store_dwordx4 v[144:145], v[140:143], off
	v_cvt_pk_bf16_f32 v114, v114, v115
	v_cvt_pk_bf16_f32 v115, v116, v117
	v_mov_b32_e32 v150, v114
	v_mov_b32_e32 v151, v115
	s_nop 1
	v_permlane16_swap_b32_e32 v148, v150
	v_permlane16_swap_b32_e32 v149, v151
	global_store_dwordx4 v[160:161], v[148:151], off
	v_cvt_pk_bf16_f32 v110, v110, v111
	v_cvt_pk_bf16_f32 v111, v112, v113
	v_mov_b32_e32 v152, v110
	v_mov_b32_e32 v153, v111
	v_lshl_add_u64 v[162:163], v[138:139], 0, v[166:167]
	v_cvt_pk_bf16_f32 v106, v106, v107
	v_cvt_pk_bf16_f32 v107, v108, v109
	v_mov_b32_e32 v156, v106
	v_mov_b32_e32 v157, v107
	v_lshl_add_u64 v[164:165], v[128:129], 0, v[166:167]
	v_cvt_pk_bf16_f32 v102, v102, v103
	v_cvt_pk_bf16_f32 v103, v104, v105
	v_mov_b32_e32 v154, v102
	v_mov_b32_e32 v155, v103
	s_nop 1
	v_permlane16_swap_b32_e32 v152, v154
	v_permlane16_swap_b32_e32 v153, v155
	global_store_dwordx4 v[162:163], v[152:155], off offset:64
	v_cvt_pk_bf16_f32 v98, v98, v99
	v_cvt_pk_bf16_f32 v99, v100, v101
	v_mov_b32_e32 v158, v98
	v_mov_b32_e32 v159, v99
	s_nop 1
	v_permlane16_swap_b32_e32 v156, v158
	v_permlane16_swap_b32_e32 v157, v159
	global_store_dwordx4 v[164:165], v[156:159], off offset:64
	v_or_b32_e32 v98, 0x80, v132
	v_ashrrev_i32_e32 v99, 31, v98
	v_lshlrev_b64 v[98:99], 12, v[98:99]
	v_lshl_add_u64 v[100:101], v[134:135], 0, v[98:99]
	v_cvt_pk_bf16_f32 v94, v94, v95
	v_cvt_pk_bf16_f32 v95, v96, v97
	v_mov_b32_e32 v140, v94
	v_mov_b32_e32 v141, v95
	v_lshl_add_u64 v[144:145], v[100:101], 0, v[166:167]
	v_or_b32_e32 v94, 0x90, v132
	v_ashrrev_i32_e32 v95, 31, v94
	v_lshlrev_b64 v[94:95], 12, v[94:95]
	v_lshl_add_u64 v[96:97], v[134:135], 0, v[94:95]
	v_cvt_pk_bf16_f32 v90, v90, v91
	v_cvt_pk_bf16_f32 v91, v92, v93
	v_mov_b32_e32 v148, v90
	v_mov_b32_e32 v149, v91
	v_lshl_add_u64 v[160:161], v[96:97], 0, v[166:167]
	v_cvt_pk_bf16_f32 v86, v86, v87
	v_cvt_pk_bf16_f32 v87, v88, v89
	v_mov_b32_e32 v142, v86
	v_mov_b32_e32 v143, v87
	s_nop 1
	v_permlane16_swap_b32_e32 v140, v142
	v_permlane16_swap_b32_e32 v141, v143
	global_store_dwordx4 v[144:145], v[140:143], off
	v_cvt_pk_bf16_f32 v82, v82, v83
	v_cvt_pk_bf16_f32 v83, v84, v85
	v_mov_b32_e32 v150, v82
	v_mov_b32_e32 v151, v83
	s_nop 1
	v_permlane16_swap_b32_e32 v148, v150
	v_permlane16_swap_b32_e32 v149, v151
	global_store_dwordx4 v[160:161], v[148:151], off
	v_cvt_pk_bf16_f32 v78, v78, v79
	v_cvt_pk_bf16_f32 v79, v80, v81
	v_mov_b32_e32 v152, v78
	v_mov_b32_e32 v153, v79
	v_lshl_add_u64 v[162:163], v[100:101], 0, v[166:167]
	v_cvt_pk_bf16_f32 v74, v74, v75
	v_cvt_pk_bf16_f32 v75, v76, v77
	v_mov_b32_e32 v156, v74
	v_mov_b32_e32 v157, v75
	v_lshl_add_u64 v[164:165], v[96:97], 0, v[166:167]
	v_cvt_pk_bf16_f32 v70, v70, v71
	v_cvt_pk_bf16_f32 v71, v72, v73
	v_mov_b32_e32 v154, v70
	v_mov_b32_e32 v155, v71
	s_nop 1
	v_permlane16_swap_b32_e32 v152, v154
	v_permlane16_swap_b32_e32 v153, v155
	global_store_dwordx4 v[162:163], v[152:155], off offset:64
	v_cvt_pk_bf16_f32 v66, v66, v67
	v_cvt_pk_bf16_f32 v67, v68, v69
	v_mov_b32_e32 v158, v66
	v_mov_b32_e32 v159, v67
	s_nop 1
	v_permlane16_swap_b32_e32 v156, v158
	v_permlane16_swap_b32_e32 v157, v159
	global_store_dwordx4 v[164:165], v[156:159], off offset:64
; #define ACC_ZERO(acc) { float z_ = 0.f; asm volatile("" : "+v"(z_)); _Pragma("unroll") for(int ai=0;ai<2;++ai) _Pragma("unroll") for(int bj=0;bj<2;++bj) \
;   _Pragma("unroll") for(int m=0;m<4;++m) _Pragma("unroll") for(int n=0;n<2;++n) acc[ai][bj][m][n]=f32x4{z_,z_,z_,z_}; }
; #define EPI_LOOP(...) _Pragma("unroll") for(int ai=0;ai<2;++ai) _Pragma("unroll") for(int bj=0;bj<2;++bj) \
;   _Pragma("unroll") for(int m=0;m<4;++m) _Pragma("unroll") for(int n=0;n<2;++n) { \
;     const int row=brow+ai*128+wr*64+m*16+fq*4; const int col=bcol+bj*128+wc*32+n*16+fr; \
;     f32x4& v=acc[ai][bj][m][n]; __VA_ARGS__ if (n == 1 && (m & 1)) __builtin_amdgcn_sched_barrier(0); }
; DEVI void run_phase(const int ph, const Params& P, char* shmc, const int wave_u) {
;     ...
;     for (int t = blockIdx.x; t < nM * nN; t += G) {
;       int pm, pn; tile_map(t, nM, nN, pm, pn);
;       const int brow = pm * 256, bcol = pn * 256;
;       acc_t acc; ACC_ZERO(acc)
;       gemm_core(w_dn_t + (long)brow * DFF, DFF, hid + (long)bcol * DFF, DFF, DFF, acc, shm, wave_u);
;       GEMM_IDS
;       EPI_LOOP({ st_bf4(T + (long)col * 2048 + row, v[0], v[1], v[2], v[3]); })
;     }
	v_add_u32_e32 v66, 0x80, v130
	v_ashrrev_i32_e32 v67, 31, v66
	v_lshl_add_u64 v[66:67], v[66:67], 1, s[12:13]
	v_lshl_add_u64 v[68:69], v[66:67], 0, v[136:137]
	v_cvt_pk_bf16_f32 v62, v62, v63
	v_cvt_pk_bf16_f32 v63, v64, v65
	v_mov_b32_e32 v140, v62
	v_mov_b32_e32 v141, v63
	v_lshl_add_u64 v[144:145], v[68:69], 0, v[166:167]
	v_lshl_add_u64 v[62:63], v[66:67], 0, v[126:127]
	v_cvt_pk_bf16_f32 v58, v58, v59
	v_cvt_pk_bf16_f32 v59, v60, v61
	v_mov_b32_e32 v148, v58
	v_mov_b32_e32 v149, v59
	v_lshl_add_u64 v[160:161], v[62:63], 0, v[166:167]
	v_add_u32_e32 v58, 0x90, v130
	v_ashrrev_i32_e32 v59, 31, v58
	v_lshl_add_u64 v[58:59], v[58:59], 1, s[12:13]
	v_lshl_add_u64 v[60:61], v[58:59], 0, v[136:137]
	v_cvt_pk_bf16_f32 v54, v54, v55
	v_cvt_pk_bf16_f32 v55, v56, v57
	v_mov_b32_e32 v142, v54
	v_mov_b32_e32 v143, v55
	s_nop 1
	v_permlane16_swap_b32_e32 v140, v142
	v_permlane16_swap_b32_e32 v141, v143
	global_store_dwordx4 v[144:145], v[140:143], off
	v_lshl_add_u64 v[54:55], v[58:59], 0, v[126:127]
	v_cvt_pk_bf16_f32 v50, v50, v51
	v_cvt_pk_bf16_f32 v51, v52, v53
	v_mov_b32_e32 v150, v50
	v_mov_b32_e32 v151, v51
	s_nop 1
	v_permlane16_swap_b32_e32 v148, v150
	v_permlane16_swap_b32_e32 v149, v151
	global_store_dwordx4 v[160:161], v[148:151], off
	v_add_u32_e32 v50, 0xa0, v130
	v_ashrrev_i32_e32 v51, 31, v50
	v_lshl_add_u64 v[50:51], v[50:51], 1, s[12:13]
	v_lshl_add_u64 v[52:53], v[50:51], 0, v[136:137]
	v_cvt_pk_bf16_f32 v46, v46, v47
	v_cvt_pk_bf16_f32 v47, v48, v49
	v_mov_b32_e32 v152, v46
	v_mov_b32_e32 v153, v47
	v_lshl_add_u64 v[162:163], v[52:53], 0, v[166:167]
	v_lshl_add_u64 v[46:47], v[50:51], 0, v[126:127]
	v_cvt_pk_bf16_f32 v42, v42, v43
	v_cvt_pk_bf16_f32 v43, v44, v45
	v_mov_b32_e32 v156, v42
	v_mov_b32_e32 v157, v43
	v_lshl_add_u64 v[164:165], v[46:47], 0, v[166:167]
	v_add_u32_e32 v42, 0xb0, v130
	v_ashrrev_i32_e32 v43, 31, v42
	v_lshl_add_u64 v[42:43], v[42:43], 1, s[12:13]
	v_lshl_add_u64 v[44:45], v[42:43], 0, v[136:137]
	v_cvt_pk_bf16_f32 v38, v38, v39
	v_cvt_pk_bf16_f32 v39, v40, v41
	v_mov_b32_e32 v154, v38
	v_mov_b32_e32 v155, v39
	s_nop 1
	v_permlane16_swap_b32_e32 v152, v154
	v_permlane16_swap_b32_e32 v153, v155
	global_store_dwordx4 v[162:163], v[152:155], off
	v_lshl_add_u64 v[38:39], v[42:43], 0, v[126:127]
	v_cvt_pk_bf16_f32 v34, v34, v35
	v_cvt_pk_bf16_f32 v35, v36, v37
	v_mov_b32_e32 v158, v34
	v_mov_b32_e32 v159, v35
	s_nop 1
	v_permlane16_swap_b32_e32 v156, v158
	v_permlane16_swap_b32_e32 v157, v159
	global_store_dwordx4 v[164:165], v[156:159], off
	v_lshl_add_u64 v[34:35], v[66:67], 0, v[98:99]
	v_cvt_pk_bf16_f32 v28, v28, v29
	v_cvt_pk_bf16_f32 v29, v30, v31
	v_mov_b32_e32 v140, v28
	v_mov_b32_e32 v141, v29
	v_lshl_add_u64 v[144:145], v[34:35], 0, v[166:167]
	v_lshl_add_u64 v[28:29], v[66:67], 0, v[94:95]
	v_cvt_pk_bf16_f32 v24, v24, v25
	v_cvt_pk_bf16_f32 v25, v26, v27
	v_mov_b32_e32 v148, v24
	v_mov_b32_e32 v149, v25
	v_lshl_add_u64 v[160:161], v[28:29], 0, v[166:167]
	v_lshl_add_u64 v[24:25], v[58:59], 0, v[98:99]
	v_cvt_pk_bf16_f32 v20, v20, v21
	v_cvt_pk_bf16_f32 v21, v22, v23
	v_mov_b32_e32 v142, v20
	v_mov_b32_e32 v143, v21
	s_nop 1
	v_permlane16_swap_b32_e32 v140, v142
	v_permlane16_swap_b32_e32 v141, v143
	global_store_dwordx4 v[144:145], v[140:143], off
	v_lshl_add_u64 v[20:21], v[58:59], 0, v[94:95]
	v_cvt_pk_bf16_f32 v16, v16, v17
	v_cvt_pk_bf16_f32 v17, v18, v19
	v_mov_b32_e32 v150, v16
	v_mov_b32_e32 v151, v17
	s_nop 1
	v_permlane16_swap_b32_e32 v148, v150
	v_permlane16_swap_b32_e32 v149, v151
	global_store_dwordx4 v[160:161], v[148:151], off
	v_lshl_add_u64 v[16:17], v[50:51], 0, v[98:99]
	v_cvt_pk_bf16_f32 v12, v12, v13
	v_cvt_pk_bf16_f32 v13, v14, v15
	v_mov_b32_e32 v152, v12
	v_mov_b32_e32 v153, v13
	v_lshl_add_u64 v[162:163], v[16:17], 0, v[166:167]
	v_lshl_add_u64 v[12:13], v[50:51], 0, v[94:95]
	v_cvt_pk_bf16_f32 v8, v8, v9
	v_cvt_pk_bf16_f32 v9, v10, v11
	v_mov_b32_e32 v156, v8
	v_mov_b32_e32 v157, v9
	v_lshl_add_u64 v[164:165], v[12:13], 0, v[166:167]
	v_lshl_add_u64 v[8:9], v[42:43], 0, v[98:99]
	v_cvt_pk_bf16_f32 v4, v4, v5
	v_cvt_pk_bf16_f32 v5, v6, v7
	v_mov_b32_e32 v154, v4
	v_mov_b32_e32 v155, v5
	s_nop 1
	v_permlane16_swap_b32_e32 v152, v154
	v_permlane16_swap_b32_e32 v153, v155
	global_store_dwordx4 v[162:163], v[152:155], off
	v_lshl_add_u64 v[4:5], v[42:43], 0, v[94:95]
	v_cvt_pk_bf16_f32 v0, v0, v1
	v_cvt_pk_bf16_f32 v1, v2, v3
	v_mov_b32_e32 v158, v0
	v_mov_b32_e32 v159, v1
	s_nop 1
	v_permlane16_swap_b32_e32 v156, v158
	v_permlane16_swap_b32_e32 v157, v159
	global_store_dwordx4 v[164:165], v[156:159], off
	v_readlane_b32 s4, v254, 26
	s_add_i32 s75, s75, s4
	s_cmpk_gt_i32 s75, 0x1ff
	v_readlane_b32 s5, v254, 27
	s_cbranch_scc1 .LBB0_89

; #define ACC_ZERO(acc) { float z_ = 0.f; asm volatile("" : "+v"(z_)); _Pragma("unroll") for(int ai=0;ai<2;++ai) _Pragma("unroll") for(int bj=0;bj<2;++bj) \
;   _Pragma("unroll") for(int m=0;m<4;++m) _Pragma("unroll") for(int n=0;n<2;++n) acc[ai][bj][m][n]=f32x4{z_,z_,z_,z_}; }
; #define EPI_LOOP(...) _Pragma("unroll") for(int ai=0;ai<2;++ai) _Pragma("unroll") for(int bj=0;bj<2;++bj) \
;   _Pragma("unroll") for(int m=0;m<4;++m) _Pragma("unroll") for(int n=0;n<2;++n) { \
;     const int row=brow+ai*128+wr*64+m*16+fq*4; const int col=bcol+bj*128+wc*32+n*16+fr; \
;     f32x4& v=acc[ai][bj][m][n]; __VA_ARGS__ if (n == 1 && (m & 1)) __builtin_amdgcn_sched_barrier(0); }
; DEVI void run_phase(const int ph, const Params& P, char* shmc, const int wave_u) {
;     ...
;     for (int j = blockIdx.x; j < 16 * 16; j += G) {
;       const int r = j / 16, ks = j % 16;
;       const int brow = (r & 7) * 256, bcol = MP + (r >> 3) * 256;
;       const int kofs = ks * (DFF / 16);
;       acc_t acc; ACC_ZERO(acc)
;       gemm_core(w_dn_t + (long)brow * DFF + kofs, DFF, hid + (long)bcol * DFF + kofs, DFF, DFF / 16, acc, shm, wave_u);
;       GEMM_IDS
;       EPI_LOOP({ st_f4(Tp + (long)ks * MS * 2048 + (long)(col - MP) * 2048 + row, v[0], v[1], v[2], v[3]); })
;     }
.LBB0_107:
	s_or_b64 exec, exec, s[6:7]
	v_mbcnt_lo_u32_b32 v32, -1, 0
	v_mbcnt_hi_u32_b32 v32, -1, v32
	v_readlane_b32 s8, v255, 13
	v_or_b32_e32 v131, s5, v32
	v_and_b32_e32 v132, 15, v32
	v_ashrrev_i32_e32 v130, 2, v131
	v_lshrrev_b32_e32 v32, 2, v32
	v_and_b32_e32 v130, 0xffffffc0, v130
	v_and_or_b32 v32, v32, 12, s39
	v_add_u32_e32 v130, v32, v130
	v_lshrrev_b32_e32 v32, 1, v131
	s_ashr_i32 s39, s38, 31
	v_and_b32_e32 v32, 0x60, v32
	s_lshl_b64 s[6:7], s[38:39], 22
	v_readlane_b32 s9, v255, 14
	s_add_u32 s6, s8, s6
	v_or3_b32 v132, v132, v32, s73
	s_addc_u32 s7, s9, s7
	v_ashrrev_i32_e32 v131, 31, v130
	v_ashrrev_i32_e32 v133, 31, v132
	v_lshl_add_u64 v[130:131], v[130:131], 2, s[6:7]
	v_lshlrev_b64 v[134:135], 13, v[132:133]
	v_lshl_add_u64 v[134:135], v[130:131], 0, v[134:135]
	global_store_dwordx4 v[134:135], v[28:31], off
	s_nop 1
	v_or_b32_e32 v28, 16, v132
	v_ashrrev_i32_e32 v29, 31, v28
	v_lshlrev_b64 v[28:29], 13, v[28:29]
	v_lshl_add_u64 v[28:29], v[130:131], 0, v[28:29]
	global_store_dwordx4 v[28:29], v[0:3], off
	global_store_dwordx4 v[134:135], v[4:7], off offset:64
	global_store_dwordx4 v[28:29], v[8:11], off offset:64
	global_store_dwordx4 v[134:135], v[12:15], off offset:128
	global_store_dwordx4 v[28:29], v[16:19], off offset:128
	global_store_dwordx4 v[134:135], v[20:23], off offset:192
	global_store_dwordx4 v[28:29], v[34:37], off offset:192
	v_or_b32_e32 v0, 0x80, v132
	v_or_b32_e32 v2, 0x90, v132
	v_ashrrev_i32_e32 v1, 31, v0
	v_ashrrev_i32_e32 v3, 31, v2
	v_lshlrev_b64 v[0:1], 13, v[0:1]
	v_lshlrev_b64 v[2:3], 13, v[2:3]
	v_lshl_add_u64 v[0:1], v[130:131], 0, v[0:1]
	v_lshl_add_u64 v[2:3], v[130:131], 0, v[2:3]
	global_store_dwordx4 v[0:1], v[58:61], off
	global_store_dwordx4 v[2:3], v[24:27], off
	global_store_dwordx4 v[0:1], v[38:41], off offset:64
	global_store_dwordx4 v[2:3], v[42:45], off offset:64
	global_store_dwordx4 v[0:1], v[46:49], off offset:128
	global_store_dwordx4 v[2:3], v[50:53], off offset:128
	global_store_dwordx4 v[0:1], v[54:57], off offset:192
	global_store_dwordx4 v[2:3], v[62:65], off offset:192
	global_store_dwordx4 v[134:135], v[66:69], off offset:512
	global_store_dwordx4 v[28:29], v[70:73], off offset:512
	global_store_dwordx4 v[134:135], v[74:77], off offset:576
	global_store_dwordx4 v[28:29], v[78:81], off offset:576
	global_store_dwordx4 v[134:135], v[82:85], off offset:640
	global_store_dwordx4 v[28:29], v[86:89], off offset:640
	global_store_dwordx4 v[134:135], v[90:93], off offset:704
	global_store_dwordx4 v[28:29], v[94:97], off offset:704
	global_store_dwordx4 v[0:1], v[98:101], off offset:512
	global_store_dwordx4 v[2:3], v[102:105], off offset:512
	global_store_dwordx4 v[0:1], v[106:109], off offset:576
	global_store_dwordx4 v[2:3], v[110:113], off offset:576
	global_store_dwordx4 v[0:1], v[114:117], off offset:640
	global_store_dwordx4 v[2:3], v[118:121], off offset:640
	global_store_dwordx4 v[0:1], v[122:125], off offset:704
	global_store_dwordx4 v[2:3], v[126:129], off offset:704
	s_mov_b32 s16, s5
	v_readlane_b32 s4, v254, 26
	s_add_i32 s72, s72, s4
	s_cmpk_gt_i32 s72, 0xff
	v_readlane_b32 s5, v254, 27
	s_cbranch_scc1 .LBB0_90

; #define EPI_LOOP(...) _Pragma("unroll") for(int ai=0;ai<2;++ai) _Pragma("unroll") for(int bj=0;bj<2;++bj) \
;   _Pragma("unroll") for(int m=0;m<4;++m) _Pragma("unroll") for(int n=0;n<2;++n) { \
;     const int row=brow+ai*128+wr*64+m*16+fq*4; const int col=bcol+bj*128+wc*32+n*16+fr; \
;     f32x4& v=acc[ai][bj][m][n]; __VA_ARGS__ if (n == 1 && (m & 1)) __builtin_amdgcn_sched_barrier(0); }
; #define EPI_SC4(ARR) float sc4[2][2]; _Pragma("unroll") for(int bj=0;bj<2;++bj) _Pragma("unroll") for(int n=0;n<2;++n) sc4[bj][n]=(ARR)[RSI(bcol+bj*128+wc*32+n*16+fr)];
; DEVI void run_phase(const int ph, const Params& P, char* shmc, const int wave_u) {
;     ...
;       gemm_core(w_up_t + (long)brow * 2048, 2048, xb + (long)bcol * 2048, 2048, 2048, acc, shm, wave_u);
;       GEMM_IDS
;       EPI_SC4(rs1)
;       EPI_LOOP({ const float sc = sc4[bj][n]; float a = fmaxf(v[0] * sc, 0.f), b = fmaxf(v[1] * sc, 0.f), c = fmaxf(v[2] * sc, 0.f), d = fmaxf(v[3] * sc, 0.f);
;         st_bf4(hid + (long)col * DFF + row, a * a, b * b, c * c, d * d); })
;     }
.LBB0_114:
	s_or_b64 exec, exec, s[6:7]
	v_mbcnt_lo_u32_b32 v170, -1, 0
	v_mbcnt_hi_u32_b32 v170, -1, v170
	v_bfe_u32 v170, v170, 4, 1
	v_mul_u32_u24_e32 v170, 24, v170
	v_mov_b32_e32 v171, 0
	v_mbcnt_lo_u32_b32 v133, -1, 0
	v_mbcnt_hi_u32_b32 v133, -1, v133
	s_movk_i32 s4, 0xfda0
	v_or_b32_e32 v134, s5, v133
	v_lshrrev_b32_e32 v130, 1, v134
	v_and_b32_e32 v32, 15, v133
	v_and_b32_e32 v130, 0x60, v130
	v_or3_b32 v132, v32, v130, s68
	v_and_b32_e32 v32, 7, v133
	v_lshlrev_b32_e32 v130, 2, v132
	v_and_or_b32 v130, v130, s4, v32
	v_readlane_b32 s6, v255, 25
	v_ashrrev_i32_e32 v131, 31, v130
	v_readlane_b32 s7, v255, 26
	s_nop 1
	v_lshl_add_u64 v[130:131], v[130:131], 2, s[6:7]
	global_load_dword v138, v[130:131], off
	global_load_dword v137, v[130:131], off offset:256
	global_load_dword v136, v[130:131], off offset:2048
	global_load_dword v32, v[130:131], off offset:2304
	v_ashrrev_i32_e32 v130, 2, v134
	v_lshrrev_b32_e32 v131, 2, v133
	v_and_b32_e32 v130, 0xffffffc0, v130
	v_and_or_b32 v131, v131, 12, s38
	v_add_u32_e32 v130, v131, v130
	v_ashrrev_i32_e32 v131, 31, v130
	v_lshl_add_u64 v[134:135], v[130:131], 1, s[82:83]
	v_ashrrev_i32_e32 v133, 31, v132
	s_waitcnt vmcnt(0) lgkmcnt(0)
	v_mul_f32_e32 v126, v126, v138
	v_max_f32_e32 v131, 0, v126
	v_mul_f32_e32 v126, v127, v138
	v_max_f32_e32 v139, 0, v126
	v_mul_f32_e32 v126, v128, v138
	v_max_f32_e32 v140, 0, v126
	v_mul_f32_e32 v126, v129, v138
	v_max_f32_e32 v141, 0, v126
	v_lshlrev_b64 v[126:127], 14, v[132:133]
	v_mul_f32_e32 v131, v131, v131
	v_mul_f32_e32 v122, v122, v137
	v_lshl_add_u64 v[128:129], v[134:135], 0, v[126:127]
	v_mul_f32_e32 v133, v139, v139
	v_mul_f32_e32 v139, v140, v140
	v_mul_f32_e32 v141, v141, v141
	v_cvt_pk_bf16_f32 v140, v131, v133
	v_max_f32_e32 v131, 0, v122
	v_mul_f32_e32 v122, v123, v137
	v_cvt_pk_bf16_f32 v141, v139, v141
	v_mov_b32_e32 v148, v140
	v_mov_b32_e32 v149, v141
	v_lshl_add_u64 v[144:145], v[128:129], 0, v[170:171]
	v_or_b32_e32 v140, 16, v132
	v_max_f32_e32 v133, 0, v122
	v_mul_f32_e32 v122, v124, v137
	v_max_f32_e32 v139, 0, v122
	v_mul_f32_e32 v122, v125, v137
	v_ashrrev_i32_e32 v141, 31, v140
	v_mul_f32_e32 v118, v118, v138
	v_mul_f32_e32 v119, v119, v138
	v_mul_f32_e32 v114, v114, v137
	v_mul_f32_e32 v115, v115, v137
	v_max_f32_e32 v142, 0, v122
	v_lshlrev_b64 v[122:123], 14, v[140:141]
	v_max_f32_e32 v118, 0, v118
	v_max_f32_e32 v119, 0, v119
	v_mul_f32_e32 v120, v120, v138
	v_mul_f32_e32 v121, v121, v138
	v_max_f32_e32 v114, 0, v114
	v_max_f32_e32 v115, 0, v115
	v_mul_f32_e32 v116, v116, v137
	v_mul_f32_e32 v117, v117, v137
	v_lshl_add_u64 v[124:125], v[134:135], 0, v[122:123]
	v_mul_f32_e32 v141, v142, v142
	v_max_f32_e32 v120, 0, v120
	v_max_f32_e32 v121, 0, v121
	v_mul_f32_e32 v118, v118, v118
	v_mul_f32_e32 v119, v119, v119
	v_max_f32_e32 v116, 0, v116
	v_max_f32_e32 v117, 0, v117
	v_mul_f32_e32 v114, v114, v114
	v_mul_f32_e32 v115, v115, v115
	v_mul_f32_e32 v131, v131, v131
	v_mul_f32_e32 v133, v133, v133
	v_mul_f32_e32 v139, v139, v139
	v_cvt_pk_bf16_f32 v140, v131, v133
	v_cvt_pk_bf16_f32 v141, v139, v141
	v_mov_b32_e32 v152, v140
	v_mov_b32_e32 v153, v141
	v_lshl_add_u64 v[164:165], v[124:125], 0, v[170:171]
	v_mul_f32_e32 v120, v120, v120
	v_mul_f32_e32 v121, v121, v121
	v_cvt_pk_bf16_f32 v118, v118, v119
	v_cvt_pk_bf16_f32 v119, v120, v121
	v_mov_b32_e32 v150, v118
	v_mov_b32_e32 v151, v119
	s_nop 1
	v_permlane16_swap_b32_e32 v148, v150
	v_permlane16_swap_b32_e32 v149, v151
	global_store_dwordx4 v[144:145], v[148:151], off
	v_mul_f32_e32 v116, v116, v116
	v_mul_f32_e32 v117, v117, v117
	v_cvt_pk_bf16_f32 v114, v114, v115
	v_cvt_pk_bf16_f32 v115, v116, v117
	v_mov_b32_e32 v154, v114
	v_mov_b32_e32 v155, v115
	s_nop 1
	v_permlane16_swap_b32_e32 v152, v154
	v_permlane16_swap_b32_e32 v153, v155
	global_store_dwordx4 v[164:165], v[152:155], off
	v_mul_f32_e32 v110, v110, v138
	v_mul_f32_e32 v111, v111, v138
	v_mul_f32_e32 v106, v106, v137
	v_mul_f32_e32 v107, v107, v137
	v_mul_f32_e32 v102, v102, v138
	v_mul_f32_e32 v103, v103, v138
	v_mul_f32_e32 v98, v98, v137
	v_mul_f32_e32 v99, v99, v137
	v_max_f32_e32 v110, 0, v110
	v_max_f32_e32 v111, 0, v111
	v_mul_f32_e32 v112, v112, v138
	v_mul_f32_e32 v113, v113, v138
	v_max_f32_e32 v106, 0, v106
	v_max_f32_e32 v107, 0, v107
	v_mul_f32_e32 v108, v108, v137
	v_mul_f32_e32 v109, v109, v137
	v_max_f32_e32 v102, 0, v102
	v_max_f32_e32 v103, 0, v103
	v_mul_f32_e32 v104, v104, v138
	v_mul_f32_e32 v105, v105, v138
	v_max_f32_e32 v98, 0, v98
	v_max_f32_e32 v99, 0, v99
	v_mul_f32_e32 v100, v100, v137
	v_mul_f32_e32 v101, v101, v137
	v_max_f32_e32 v112, 0, v112
	v_max_f32_e32 v113, 0, v113
	v_mul_f32_e32 v110, v110, v110
	v_mul_f32_e32 v111, v111, v111
	v_max_f32_e32 v108, 0, v108
	v_max_f32_e32 v109, 0, v109
	v_mul_f32_e32 v106, v106, v106
	v_mul_f32_e32 v107, v107, v107
	v_max_f32_e32 v104, 0, v104
	v_max_f32_e32 v105, 0, v105
	v_mul_f32_e32 v102, v102, v102
	v_mul_f32_e32 v103, v103, v103
	v_max_f32_e32 v100, 0, v100
	v_max_f32_e32 v101, 0, v101
	v_mul_f32_e32 v98, v98, v98
	v_mul_f32_e32 v99, v99, v99
	v_mul_f32_e32 v112, v112, v112
	v_mul_f32_e32 v113, v113, v113
	v_cvt_pk_bf16_f32 v110, v110, v111
	v_cvt_pk_bf16_f32 v111, v112, v113
	v_mov_b32_e32 v156, v110
	v_mov_b32_e32 v157, v111
	v_lshl_add_u64 v[166:167], v[128:129], 0, v[170:171]
	v_mul_f32_e32 v108, v108, v108
	v_mul_f32_e32 v109, v109, v109
	v_cvt_pk_bf16_f32 v106, v106, v107
	v_cvt_pk_bf16_f32 v107, v108, v109
	v_mov_b32_e32 v160, v106
	v_mov_b32_e32 v161, v107
	v_lshl_add_u64 v[168:169], v[124:125], 0, v[170:171]
	v_mul_f32_e32 v104, v104, v104
	v_mul_f32_e32 v105, v105, v105
	v_cvt_pk_bf16_f32 v102, v102, v103
	v_cvt_pk_bf16_f32 v103, v104, v105
; #define EPI_LOOP(...) _Pragma("unroll") for(int ai=0;ai<2;++ai) _Pragma("unroll") for(int bj=0;bj<2;++bj) \
;   _Pragma("unroll") for(int m=0;m<4;++m) _Pragma("unroll") for(int n=0;n<2;++n) { \
;     const int row=brow+ai*128+wr*64+m*16+fq*4; const int col=bcol+bj*128+wc*32+n*16+fr; \
;     f32x4& v=acc[ai][bj][m][n]; __VA_ARGS__ if (n == 1 && (m & 1)) __builtin_amdgcn_sched_barrier(0); }
; #define EPI_SC4(ARR) float sc4[2][2]; _Pragma("unroll") for(int bj=0;bj<2;++bj) _Pragma("unroll") for(int n=0;n<2;++n) sc4[bj][n]=(ARR)[RSI(bcol+bj*128+wc*32+n*16+fr)];
; DEVI void run_phase(const int ph, const Params& P, char* shmc, const int wave_u) {
;     ...
;       EPI_SC4(rs1)
;       EPI_LOOP({ const float sc = sc4[bj][n]; float a = fmaxf(v[0] * sc, 0.f), b = fmaxf(v[1] * sc, 0.f), c = fmaxf(v[2] * sc, 0.f), d = fmaxf(v[3] * sc, 0.f);
;         st_bf4(hid + (long)col * DFF + row, a * a, b * b, c * c, d * d); })
	v_mov_b32_e32 v158, v102
	v_mov_b32_e32 v159, v103
	s_nop 1
	v_permlane16_swap_b32_e32 v156, v158
	v_permlane16_swap_b32_e32 v157, v159
	global_store_dwordx4 v[166:167], v[156:159], off offset:64
	v_mul_f32_e32 v100, v100, v100
	v_mul_f32_e32 v101, v101, v101
	v_cvt_pk_bf16_f32 v98, v98, v99
	v_cvt_pk_bf16_f32 v99, v100, v101
	v_mov_b32_e32 v162, v98
	v_mov_b32_e32 v163, v99
	s_nop 1
	v_permlane16_swap_b32_e32 v160, v162
	v_permlane16_swap_b32_e32 v161, v163
	global_store_dwordx4 v[168:169], v[160:163], off offset:64
	v_mul_f32_e32 v94, v94, v136
	v_max_f32_e32 v100, 0, v94
	v_mul_f32_e32 v94, v95, v136
	v_or_b32_e32 v98, 0x80, v132
	v_max_f32_e32 v101, 0, v94
	v_mul_f32_e32 v94, v96, v136
	v_max_f32_e32 v102, 0, v94
	v_mul_f32_e32 v94, v97, v136
	v_ashrrev_i32_e32 v99, 31, v98
	v_max_f32_e32 v103, 0, v94
	v_lshlrev_b64 v[94:95], 14, v[98:99]
	v_mul_f32_e32 v98, v100, v100
	v_mul_f32_e32 v99, v101, v101
	v_mul_f32_e32 v100, v102, v102
	v_mul_f32_e32 v90, v90, v32
	v_lshl_add_u64 v[96:97], v[134:135], 0, v[94:95]
	v_mul_f32_e32 v101, v103, v103
	v_cvt_pk_bf16_f32 v98, v98, v99
	v_cvt_pk_bf16_f32 v99, v100, v101
	v_max_f32_e32 v100, 0, v90
	v_mul_f32_e32 v90, v91, v32
	v_mov_b32_e32 v148, v98
	v_mov_b32_e32 v149, v99
	v_lshl_add_u64 v[144:145], v[96:97], 0, v[170:171]
	v_or_b32_e32 v98, 0x90, v132
	v_max_f32_e32 v101, 0, v90
	v_mul_f32_e32 v90, v92, v32
	v_max_f32_e32 v102, 0, v90
	v_mul_f32_e32 v90, v93, v32
	v_ashrrev_i32_e32 v99, 31, v98
	v_mul_f32_e32 v86, v86, v136
	v_mul_f32_e32 v87, v87, v136
	v_mul_f32_e32 v82, v82, v32
	v_mul_f32_e32 v83, v83, v32
	v_max_f32_e32 v103, 0, v90
	v_lshlrev_b64 v[90:91], 14, v[98:99]
	v_max_f32_e32 v86, 0, v86
	v_max_f32_e32 v87, 0, v87
	v_mul_f32_e32 v88, v88, v136
	v_mul_f32_e32 v89, v89, v136
	v_max_f32_e32 v82, 0, v82
	v_max_f32_e32 v83, 0, v83
	v_mul_f32_e32 v84, v84, v32
	v_mul_f32_e32 v85, v85, v32
	v_lshl_add_u64 v[92:93], v[134:135], 0, v[90:91]
	v_mul_f32_e32 v98, v100, v100
	v_mul_f32_e32 v99, v101, v101
	v_max_f32_e32 v88, 0, v88
	v_max_f32_e32 v89, 0, v89
	v_mul_f32_e32 v86, v86, v86
	v_mul_f32_e32 v87, v87, v87
	v_max_f32_e32 v84, 0, v84
	v_max_f32_e32 v85, 0, v85
	v_mul_f32_e32 v82, v82, v82
	v_mul_f32_e32 v83, v83, v83
	v_mul_f32_e32 v100, v102, v102
	v_mul_f32_e32 v101, v103, v103
	v_cvt_pk_bf16_f32 v98, v98, v99
	v_cvt_pk_bf16_f32 v99, v100, v101
	v_mov_b32_e32 v152, v98
	v_mov_b32_e32 v153, v99
	v_lshl_add_u64 v[164:165], v[92:93], 0, v[170:171]
	v_mul_f32_e32 v88, v88, v88
	v_mul_f32_e32 v89, v89, v89
	v_cvt_pk_bf16_f32 v86, v86, v87
	v_cvt_pk_bf16_f32 v87, v88, v89
	v_mov_b32_e32 v150, v86
	v_mov_b32_e32 v151, v87
	s_nop 1
	v_permlane16_swap_b32_e32 v148, v150
	v_permlane16_swap_b32_e32 v149, v151
	global_store_dwordx4 v[144:145], v[148:151], off
	v_mul_f32_e32 v84, v84, v84
	v_mul_f32_e32 v85, v85, v85
	v_cvt_pk_bf16_f32 v82, v82, v83
	v_cvt_pk_bf16_f32 v83, v84, v85
	v_mov_b32_e32 v154, v82
	v_mov_b32_e32 v155, v83
	s_nop 1
	v_permlane16_swap_b32_e32 v152, v154
	v_permlane16_swap_b32_e32 v153, v155
	global_store_dwordx4 v[164:165], v[152:155], off
	v_mul_f32_e32 v78, v78, v136
	v_mul_f32_e32 v79, v79, v136
	v_mul_f32_e32 v74, v74, v32
	v_mul_f32_e32 v75, v75, v32
	v_mul_f32_e32 v70, v70, v136
	v_mul_f32_e32 v71, v71, v136
	v_mul_f32_e32 v66, v66, v32
	v_mul_f32_e32 v67, v67, v32
	v_max_f32_e32 v78, 0, v78
	v_max_f32_e32 v79, 0, v79
	v_mul_f32_e32 v80, v80, v136
	v_mul_f32_e32 v81, v81, v136
	v_max_f32_e32 v74, 0, v74
	v_max_f32_e32 v75, 0, v75
	v_mul_f32_e32 v76, v76, v32
	v_mul_f32_e32 v77, v77, v32
	v_max_f32_e32 v70, 0, v70
	v_max_f32_e32 v71, 0, v71
	v_mul_f32_e32 v72, v72, v136
	v_mul_f32_e32 v73, v73, v136
	v_max_f32_e32 v66, 0, v66
	v_max_f32_e32 v67, 0, v67
	v_mul_f32_e32 v68, v68, v32
	v_mul_f32_e32 v69, v69, v32
	v_max_f32_e32 v80, 0, v80
	v_max_f32_e32 v81, 0, v81
	v_mul_f32_e32 v78, v78, v78
	v_mul_f32_e32 v79, v79, v79
	v_max_f32_e32 v76, 0, v76
	v_max_f32_e32 v77, 0, v77
	v_mul_f32_e32 v74, v74, v74
	v_mul_f32_e32 v75, v75, v75
	v_max_f32_e32 v72, 0, v72
	v_max_f32_e32 v73, 0, v73
	v_mul_f32_e32 v70, v70, v70
	v_mul_f32_e32 v71, v71, v71
	v_max_f32_e32 v68, 0, v68
	v_max_f32_e32 v69, 0, v69
	v_mul_f32_e32 v66, v66, v66
	v_mul_f32_e32 v67, v67, v67
	v_mul_f32_e32 v80, v80, v80
	v_mul_f32_e32 v81, v81, v81
	v_cvt_pk_bf16_f32 v78, v78, v79
	v_cvt_pk_bf16_f32 v79, v80, v81
	v_mov_b32_e32 v156, v78
	v_mov_b32_e32 v157, v79
	v_lshl_add_u64 v[166:167], v[96:97], 0, v[170:171]
	v_mul_f32_e32 v76, v76, v76
	v_mul_f32_e32 v77, v77, v77
	v_cvt_pk_bf16_f32 v74, v74, v75
	v_cvt_pk_bf16_f32 v75, v76, v77
	v_mov_b32_e32 v160, v74
	v_mov_b32_e32 v161, v75
	v_lshl_add_u64 v[168:169], v[92:93], 0, v[170:171]
	v_mul_f32_e32 v72, v72, v72
	v_mul_f32_e32 v73, v73, v73
	v_cvt_pk_bf16_f32 v70, v70, v71
	v_cvt_pk_bf16_f32 v71, v72, v73
	v_mov_b32_e32 v158, v70
	v_mov_b32_e32 v159, v71
	s_nop 1
	v_permlane16_swap_b32_e32 v156, v158
	v_permlane16_swap_b32_e32 v157, v159
	global_store_dwordx4 v[166:167], v[156:159], off offset:64
	v_mul_f32_e32 v68, v68, v68
	v_mul_f32_e32 v69, v69, v69
	v_cvt_pk_bf16_f32 v66, v66, v67
	v_cvt_pk_bf16_f32 v67, v68, v69
	v_mov_b32_e32 v162, v66
	v_mov_b32_e32 v163, v67
	s_nop 1
	v_permlane16_swap_b32_e32 v160, v162
	v_permlane16_swap_b32_e32 v161, v163
	global_store_dwordx4 v[168:169], v[160:163], off offset:64
	v_mul_f32_e32 v62, v62, v138
	v_max_f32_e32 v68, 0, v62
	v_mul_f32_e32 v62, v63, v138
	v_add_u32_e32 v66, 0x80, v130
	v_max_f32_e32 v69, 0, v62
	v_mul_f32_e32 v62, v64, v138
	v_ashrrev_i32_e32 v67, 31, v66
	v_max_f32_e32 v64, 0, v62
	v_mul_f32_e32 v62, v65, v138
	v_lshl_add_u64 v[66:67], v[66:67], 1, s[82:83]
	v_max_f32_e32 v65, 0, v62
; #define EPI_LOOP(...) _Pragma("unroll") for(int ai=0;ai<2;++ai) _Pragma("unroll") for(int bj=0;bj<2;++bj) \
;   _Pragma("unroll") for(int m=0;m<4;++m) _Pragma("unroll") for(int n=0;n<2;++n) { \
;     const int row=brow+ai*128+wr*64+m*16+fq*4; const int col=bcol+bj*128+wc*32+n*16+fr; \
;     f32x4& v=acc[ai][bj][m][n]; __VA_ARGS__ if (n == 1 && (m & 1)) __builtin_amdgcn_sched_barrier(0); }
; #define EPI_SC4(ARR) float sc4[2][2]; _Pragma("unroll") for(int bj=0;bj<2;++bj) _Pragma("unroll") for(int n=0;n<2;++n) sc4[bj][n]=(ARR)[RSI(bcol+bj*128+wc*32+n*16+fr)];
; DEVI void run_phase(const int ph, const Params& P, char* shmc, const int wave_u) {
;     ...
;       EPI_SC4(rs1)
;       EPI_LOOP({ const float sc = sc4[bj][n]; float a = fmaxf(v[0] * sc, 0.f), b = fmaxf(v[1] * sc, 0.f), c = fmaxf(v[2] * sc, 0.f), d = fmaxf(v[3] * sc, 0.f);
;         st_bf4(hid + (long)col * DFF + row, a * a, b * b, c * c, d * d); })
	v_lshl_add_u64 v[62:63], v[66:67], 0, v[126:127]
	v_mul_f32_e32 v65, v65, v65
	v_mul_f32_e32 v58, v58, v137
	v_mul_f32_e32 v68, v68, v68
	v_mul_f32_e32 v69, v69, v69
	v_mul_f32_e32 v70, v64, v64
	v_cvt_pk_bf16_f32 v64, v68, v69
	v_cvt_pk_bf16_f32 v65, v70, v65
	v_mov_b32_e32 v148, v64
	v_mov_b32_e32 v149, v65
	v_lshl_add_u64 v[144:145], v[62:63], 0, v[170:171]
	v_max_f32_e32 v62, 0, v58
	v_mul_f32_e32 v58, v59, v137
	v_max_f32_e32 v63, 0, v58
	v_mul_f32_e32 v58, v60, v137
	v_max_f32_e32 v60, 0, v58
	v_mul_f32_e32 v58, v61, v137
	v_max_f32_e32 v61, 0, v58
	v_lshl_add_u64 v[58:59], v[66:67], 0, v[122:123]
	v_mul_f32_e32 v62, v62, v62
	v_mul_f32_e32 v63, v63, v63
	v_mul_f32_e32 v64, v60, v60
	v_mul_f32_e32 v61, v61, v61
	v_cvt_pk_bf16_f32 v60, v62, v63
	v_mul_f32_e32 v54, v54, v138
	v_cvt_pk_bf16_f32 v61, v64, v61
	v_mov_b32_e32 v152, v60
	v_mov_b32_e32 v153, v61
	v_lshl_add_u64 v[164:165], v[58:59], 0, v[170:171]
	v_max_f32_e32 v60, 0, v54
	v_mul_f32_e32 v54, v55, v138
	v_add_u32_e32 v58, 0x90, v130
	v_max_f32_e32 v61, 0, v54
	v_mul_f32_e32 v54, v56, v138
	v_ashrrev_i32_e32 v59, 31, v58
	v_max_f32_e32 v56, 0, v54
	v_mul_f32_e32 v54, v57, v138
	v_lshl_add_u64 v[58:59], v[58:59], 1, s[82:83]
	v_max_f32_e32 v57, 0, v54
	v_lshl_add_u64 v[54:55], v[58:59], 0, v[126:127]
	v_mul_f32_e32 v57, v57, v57
	v_mul_f32_e32 v50, v50, v137
	v_mul_f32_e32 v60, v60, v60
	v_mul_f32_e32 v61, v61, v61
	v_mul_f32_e32 v62, v56, v56
	v_cvt_pk_bf16_f32 v56, v60, v61
	v_cvt_pk_bf16_f32 v57, v62, v57
	v_mov_b32_e32 v150, v56
	v_mov_b32_e32 v151, v57
	s_nop 1
	v_permlane16_swap_b32_e32 v148, v150
	v_permlane16_swap_b32_e32 v149, v151
	global_store_dwordx4 v[144:145], v[148:151], off
	v_max_f32_e32 v54, 0, v50
	v_mul_f32_e32 v50, v51, v137
	v_max_f32_e32 v55, 0, v50
	v_mul_f32_e32 v50, v52, v137
	v_max_f32_e32 v52, 0, v50
	v_mul_f32_e32 v50, v53, v137
	v_max_f32_e32 v53, 0, v50
	v_lshl_add_u64 v[50:51], v[58:59], 0, v[122:123]
	v_mul_f32_e32 v53, v53, v53
	v_mul_f32_e32 v54, v54, v54
	v_mul_f32_e32 v55, v55, v55
	v_mul_f32_e32 v56, v52, v52
	v_cvt_pk_bf16_f32 v52, v54, v55
	v_cvt_pk_bf16_f32 v53, v56, v53
	v_mov_b32_e32 v154, v52
	v_mov_b32_e32 v155, v53
	s_nop 1
	v_permlane16_swap_b32_e32 v152, v154
	v_permlane16_swap_b32_e32 v153, v155
	global_store_dwordx4 v[164:165], v[152:155], off
	v_mul_f32_e32 v46, v46, v138
	v_max_f32_e32 v52, 0, v46
	v_mul_f32_e32 v46, v47, v138
	v_add_u32_e32 v50, 0xa0, v130
	v_max_f32_e32 v53, 0, v46
	v_mul_f32_e32 v46, v48, v138
	v_ashrrev_i32_e32 v51, 31, v50
	v_max_f32_e32 v48, 0, v46
	v_mul_f32_e32 v46, v49, v138
	v_lshl_add_u64 v[50:51], v[50:51], 1, s[82:83]
	v_max_f32_e32 v49, 0, v46
	v_lshl_add_u64 v[46:47], v[50:51], 0, v[126:127]
	v_mul_f32_e32 v49, v49, v49
	v_mul_f32_e32 v42, v42, v137
	v_mul_f32_e32 v52, v52, v52
	v_mul_f32_e32 v53, v53, v53
	v_mul_f32_e32 v54, v48, v48
	v_cvt_pk_bf16_f32 v48, v52, v53
	v_cvt_pk_bf16_f32 v49, v54, v49
	v_mov_b32_e32 v156, v48
	v_mov_b32_e32 v157, v49
	v_lshl_add_u64 v[166:167], v[46:47], 0, v[170:171]
	v_max_f32_e32 v46, 0, v42
	v_mul_f32_e32 v42, v43, v137
	v_max_f32_e32 v47, 0, v42
	v_mul_f32_e32 v42, v44, v137
	v_max_f32_e32 v44, 0, v42
	v_mul_f32_e32 v42, v45, v137
	v_max_f32_e32 v45, 0, v42
	v_lshl_add_u64 v[42:43], v[50:51], 0, v[122:123]
	v_mul_f32_e32 v46, v46, v46
	v_mul_f32_e32 v47, v47, v47
	v_mul_f32_e32 v48, v44, v44
	v_mul_f32_e32 v45, v45, v45
	v_cvt_pk_bf16_f32 v44, v46, v47
	v_mul_f32_e32 v38, v38, v138
	v_cvt_pk_bf16_f32 v45, v48, v45
	v_mov_b32_e32 v160, v44
	v_mov_b32_e32 v161, v45
	v_lshl_add_u64 v[168:169], v[42:43], 0, v[170:171]
	v_max_f32_e32 v44, 0, v38
	v_mul_f32_e32 v38, v39, v138
	v_add_u32_e32 v42, 0xb0, v130
	v_max_f32_e32 v45, 0, v38
	v_mul_f32_e32 v38, v40, v138
	v_ashrrev_i32_e32 v43, 31, v42
	v_max_f32_e32 v40, 0, v38
	v_mul_f32_e32 v38, v41, v138
	v_lshl_add_u64 v[42:43], v[42:43], 1, s[82:83]
	v_max_f32_e32 v41, 0, v38
	v_lshl_add_u64 v[38:39], v[42:43], 0, v[126:127]
	v_mul_f32_e32 v41, v41, v41
	v_mul_f32_e32 v34, v34, v137
	v_mul_f32_e32 v44, v44, v44
	v_mul_f32_e32 v45, v45, v45
	v_mul_f32_e32 v46, v40, v40
	v_cvt_pk_bf16_f32 v40, v44, v45
	v_cvt_pk_bf16_f32 v41, v46, v41
	v_mov_b32_e32 v158, v40
	v_mov_b32_e32 v159, v41
	s_nop 1
	v_permlane16_swap_b32_e32 v156, v158
	v_permlane16_swap_b32_e32 v157, v159
	global_store_dwordx4 v[166:167], v[156:159], off
	v_max_f32_e32 v38, 0, v34
	v_mul_f32_e32 v34, v35, v137
	v_max_f32_e32 v39, 0, v34
	v_mul_f32_e32 v34, v36, v137
	v_max_f32_e32 v36, 0, v34
	v_mul_f32_e32 v34, v37, v137
	v_max_f32_e32 v37, 0, v34
	v_lshl_add_u64 v[34:35], v[42:43], 0, v[122:123]
	v_mul_f32_e32 v37, v37, v37
	v_mul_f32_e32 v38, v38, v38
	v_mul_f32_e32 v39, v39, v39
	v_mul_f32_e32 v40, v36, v36
	v_cvt_pk_bf16_f32 v36, v38, v39
	v_cvt_pk_bf16_f32 v37, v40, v37
	v_mov_b32_e32 v162, v36
	v_mov_b32_e32 v163, v37
	s_nop 1
	v_permlane16_swap_b32_e32 v160, v162
	v_permlane16_swap_b32_e32 v161, v163
; #define EPI_LOOP(...) _Pragma("unroll") for(int ai=0;ai<2;++ai) _Pragma("unroll") for(int bj=0;bj<2;++bj) \
;   _Pragma("unroll") for(int m=0;m<4;++m) _Pragma("unroll") for(int n=0;n<2;++n) { \
;     const int row=brow+ai*128+wr*64+m*16+fq*4; const int col=bcol+bj*128+wc*32+n*16+fr; \
;     f32x4& v=acc[ai][bj][m][n]; __VA_ARGS__ if (n == 1 && (m & 1)) __builtin_amdgcn_sched_barrier(0); }
; #define EPI_SC4(ARR) float sc4[2][2]; _Pragma("unroll") for(int bj=0;bj<2;++bj) _Pragma("unroll") for(int n=0;n<2;++n) sc4[bj][n]=(ARR)[RSI(bcol+bj*128+wc*32+n*16+fr)];
; DEVI void run_phase(const int ph, const Params& P, char* shmc, const int wave_u) {
;     ...
;       EPI_SC4(rs1)
;       EPI_LOOP({ const float sc = sc4[bj][n]; float a = fmaxf(v[0] * sc, 0.f), b = fmaxf(v[1] * sc, 0.f), c = fmaxf(v[2] * sc, 0.f), d = fmaxf(v[3] * sc, 0.f);
;         st_bf4(hid + (long)col * DFF + row, a * a, b * b, c * c, d * d); })
	global_store_dwordx4 v[168:169], v[160:163], off
	v_mul_f32_e32 v28, v28, v136
	v_max_f32_e32 v34, 0, v28
	v_mul_f32_e32 v28, v29, v136
	v_max_f32_e32 v35, 0, v28
	v_mul_f32_e32 v28, v30, v136
	v_max_f32_e32 v30, 0, v28
	v_mul_f32_e32 v28, v31, v136
	v_max_f32_e32 v31, 0, v28
	v_lshl_add_u64 v[28:29], v[66:67], 0, v[94:95]
	v_mul_f32_e32 v31, v31, v31
	v_mul_f32_e32 v24, v24, v32
	v_mul_f32_e32 v34, v34, v34
	v_mul_f32_e32 v35, v35, v35
	v_mul_f32_e32 v36, v30, v30
	v_cvt_pk_bf16_f32 v30, v34, v35
	v_cvt_pk_bf16_f32 v31, v36, v31
	v_mov_b32_e32 v148, v30
	v_mov_b32_e32 v149, v31
	v_lshl_add_u64 v[144:145], v[28:29], 0, v[170:171]
	v_max_f32_e32 v28, 0, v24
	v_mul_f32_e32 v24, v25, v32
	v_max_f32_e32 v29, 0, v24
	v_mul_f32_e32 v24, v26, v32
	v_max_f32_e32 v26, 0, v24
	v_mul_f32_e32 v24, v27, v32
	v_max_f32_e32 v27, 0, v24
	v_lshl_add_u64 v[24:25], v[66:67], 0, v[90:91]
	v_mul_f32_e32 v27, v27, v27
	v_mul_f32_e32 v20, v20, v136
	v_mul_f32_e32 v28, v28, v28
	v_mul_f32_e32 v29, v29, v29
	v_mul_f32_e32 v30, v26, v26
	v_cvt_pk_bf16_f32 v26, v28, v29
	v_cvt_pk_bf16_f32 v27, v30, v27
	v_mov_b32_e32 v152, v26
	v_mov_b32_e32 v153, v27
	v_lshl_add_u64 v[164:165], v[24:25], 0, v[170:171]
	v_max_f32_e32 v24, 0, v20
	v_mul_f32_e32 v20, v21, v136
	v_max_f32_e32 v25, 0, v20
	v_mul_f32_e32 v20, v22, v136
	v_max_f32_e32 v22, 0, v20
	v_mul_f32_e32 v20, v23, v136
	v_max_f32_e32 v23, 0, v20
	v_lshl_add_u64 v[20:21], v[58:59], 0, v[94:95]
	v_mul_f32_e32 v23, v23, v23
	v_mul_f32_e32 v16, v16, v32
	v_mul_f32_e32 v24, v24, v24
	v_mul_f32_e32 v25, v25, v25
	v_mul_f32_e32 v26, v22, v22
	v_cvt_pk_bf16_f32 v22, v24, v25
	v_cvt_pk_bf16_f32 v23, v26, v23
	v_mov_b32_e32 v150, v22
	v_mov_b32_e32 v151, v23
	s_nop 1
	v_permlane16_swap_b32_e32 v148, v150
	v_permlane16_swap_b32_e32 v149, v151
	global_store_dwordx4 v[144:145], v[148:151], off
	v_max_f32_e32 v20, 0, v16
	v_mul_f32_e32 v16, v17, v32
	v_max_f32_e32 v21, 0, v16
	v_mul_f32_e32 v16, v18, v32
	v_max_f32_e32 v18, 0, v16
	v_mul_f32_e32 v16, v19, v32
	v_max_f32_e32 v19, 0, v16
	v_lshl_add_u64 v[16:17], v[58:59], 0, v[90:91]
	v_mul_f32_e32 v19, v19, v19
	v_mul_f32_e32 v20, v20, v20
	v_mul_f32_e32 v21, v21, v21
	v_mul_f32_e32 v22, v18, v18
	v_cvt_pk_bf16_f32 v18, v20, v21
	v_cvt_pk_bf16_f32 v19, v22, v19
	v_mov_b32_e32 v154, v18
	v_mov_b32_e32 v155, v19
	s_nop 1
	v_permlane16_swap_b32_e32 v152, v154
	v_permlane16_swap_b32_e32 v153, v155
	global_store_dwordx4 v[164:165], v[152:155], off
	v_mul_f32_e32 v12, v12, v136
	v_max_f32_e32 v16, 0, v12
	v_mul_f32_e32 v12, v13, v136
	v_max_f32_e32 v17, 0, v12
	v_mul_f32_e32 v12, v14, v136
	v_max_f32_e32 v14, 0, v12
	v_mul_f32_e32 v12, v15, v136
	v_max_f32_e32 v15, 0, v12
	v_lshl_add_u64 v[12:13], v[50:51], 0, v[94:95]
	v_mul_f32_e32 v15, v15, v15
	v_mul_f32_e32 v8, v8, v32
	v_mul_f32_e32 v16, v16, v16
	v_mul_f32_e32 v17, v17, v17
	v_mul_f32_e32 v18, v14, v14
	v_cvt_pk_bf16_f32 v14, v16, v17
	v_cvt_pk_bf16_f32 v15, v18, v15
	v_mov_b32_e32 v156, v14
	v_mov_b32_e32 v157, v15
	v_lshl_add_u64 v[166:167], v[12:13], 0, v[170:171]
	v_max_f32_e32 v12, 0, v8
	v_mul_f32_e32 v8, v9, v32
	v_max_f32_e32 v13, 0, v8
	v_mul_f32_e32 v8, v10, v32
	v_max_f32_e32 v10, 0, v8
	v_mul_f32_e32 v8, v11, v32
	v_max_f32_e32 v11, 0, v8
	v_lshl_add_u64 v[8:9], v[50:51], 0, v[90:91]
	v_mul_f32_e32 v11, v11, v11
	v_mul_f32_e32 v4, v4, v136
	v_mul_f32_e32 v12, v12, v12
	v_mul_f32_e32 v13, v13, v13
	v_mul_f32_e32 v14, v10, v10
	v_cvt_pk_bf16_f32 v10, v12, v13
	v_cvt_pk_bf16_f32 v11, v14, v11
	v_mov_b32_e32 v160, v10
	v_mov_b32_e32 v161, v11
	v_lshl_add_u64 v[168:169], v[8:9], 0, v[170:171]
	v_max_f32_e32 v8, 0, v4
	v_mul_f32_e32 v4, v5, v136
	v_max_f32_e32 v9, 0, v4
	v_mul_f32_e32 v4, v6, v136
	v_max_f32_e32 v6, 0, v4
	v_mul_f32_e32 v4, v7, v136
	v_max_f32_e32 v7, 0, v4
	v_lshl_add_u64 v[4:5], v[42:43], 0, v[94:95]
	v_mul_f32_e32 v7, v7, v7
	v_mul_f32_e32 v0, v0, v32
	v_mul_f32_e32 v8, v8, v8
	v_mul_f32_e32 v9, v9, v9
	v_mul_f32_e32 v10, v6, v6
	v_cvt_pk_bf16_f32 v6, v8, v9
	v_cvt_pk_bf16_f32 v7, v10, v7
	v_mov_b32_e32 v158, v6
	v_mov_b32_e32 v159, v7
	s_nop 1
	v_permlane16_swap_b32_e32 v156, v158
	v_permlane16_swap_b32_e32 v157, v159
	global_store_dwordx4 v[166:167], v[156:159], off
	v_max_f32_e32 v4, 0, v0
	v_mul_f32_e32 v0, v1, v32
	v_max_f32_e32 v5, 0, v0
	v_mul_f32_e32 v0, v2, v32
	v_max_f32_e32 v2, 0, v0
	v_mul_f32_e32 v0, v3, v32
	v_max_f32_e32 v3, 0, v0
	v_lshl_add_u64 v[0:1], v[42:43], 0, v[90:91]
	v_mul_f32_e32 v3, v3, v3
	v_mul_f32_e32 v4, v4, v4
	v_mul_f32_e32 v5, v5, v5
	v_mul_f32_e32 v6, v2, v2
	v_cvt_pk_bf16_f32 v2, v4, v5
	v_cvt_pk_bf16_f32 v3, v6, v3
	v_mov_b32_e32 v162, v2
	v_mov_b32_e32 v163, v3
	s_nop 1
	v_permlane16_swap_b32_e32 v160, v162
	v_permlane16_swap_b32_e32 v161, v163
	global_store_dwordx4 v[168:169], v[160:163], off
	s_mov_b32 s16, s5
	v_readlane_b32 s4, v254, 26
	s_add_i32 s75, s75, s4
	s_cmpk_gt_i32 s75, 0x83f
	v_readlane_b32 s5, v254, 27
	s_cbranch_scc1 .LBB0_93

; template <int CM>
; DEVI void transpose_job(const float* __restrict__ src, int srcld, const float* __restrict__ g, bf16* __restrict__ dst,
;                         int K, int Ndst, unsigned short* lds, const int wave_u, const int vb, const int nvb) {
;     ...
;     { const int nn = tid >> 3, kb = (tid & 7) * 8; unsigned short e[8];
; #pragma unroll
;       for (int i = 0; i < 8; ++i) e[i] = lds[(kb + i) * 72 + nn];
;       u32x4 w = {(unsigned)e[0] | ((unsigned)e[1] << 16), (unsigned)e[2] | ((unsigned)e[3] << 16),
;                  (unsigned)e[4] | ((unsigned)e[5] << 16), (unsigned)e[6] | ((unsigned)e[7] << 16)};
;       *reinterpret_cast<u32x4*>(dst + (long)(n0 + nn) * K + k0 + kb) = w; }
;     __syncthreads();
.LBB0_122:
	s_ashr_i32 s4, s39, 31
	s_lshr_b32 s4, s4, 27
	s_add_i32 s4, s39, s4
	s_waitcnt lgkmcnt(0)
	s_barrier
	ds_read_u16 v12, v11
	ds_read_u16 v16, v11 offset:144
	ds_read_u16 v13, v11 offset:288
	ds_read_u16 v17, v11 offset:432
	ds_read_u16 v14, v11 offset:576
	ds_read_u16 v18, v11 offset:720
	ds_read_u16 v15, v11 offset:864
	ds_read_u16 v19, v11 offset:1008
	s_ashr_i32 s4, s4, 5
	s_mov_b32 s16, 0x5040100
	s_lshl_b32 s68, s4, 6
	s_waitcnt lgkmcnt(6)
	v_perm_b32 v12, v16, v12, s16
	v_add_u32_e32 v16, s8, v8
	s_lshl_b32 s4, s4, 11
	v_subrev_u32_e32 v16, s4, v16
	s_waitcnt lgkmcnt(4)
	v_perm_b32 v13, v17, v13, s16
	v_ashrrev_i32_e32 v17, 31, v16
	v_lshlrev_b64 v[16:17], 14, v[16:17]
	v_lshl_add_u64 v[16:17], s[0:1], 0, v[16:17]
	s_ashr_i32 s69, s68, 31
	v_lshl_add_u64 v[16:17], s[68:69], 1, v[16:17]
	s_waitcnt lgkmcnt(0)
	v_perm_b32 v15, v19, v15, s16
	v_perm_b32 v14, v18, v14, s16
	v_lshl_add_u64 v[16:17], v[16:17], 0, v[32:33]
	s_add_i32 s8, s8, s9
	s_andn2_b64 vcc, exec, s[6:7]
	s_mov_b32 s39, s38
	global_store_dwordx4 v[16:17], v[12:15], off
	s_waitcnt lgkmcnt(0)
	s_barrier
	s_cbranch_vccz .LBB0_126

; template <int CM>
; DEVI void transpose_job(const float* __restrict__ src, int srcld, const float* __restrict__ g, bf16* __restrict__ dst,
;                         int K, int Ndst, unsigned short* lds, const int wave_u, const int vb, const int nvb) {
;     ...
;     { const int nn = tid >> 3, kb = (tid & 7) * 8; unsigned short e[8];
; #pragma unroll
;       for (int i = 0; i < 8; ++i) e[i] = lds[(kb + i) * 72 + nn];
;       u32x4 w = {(unsigned)e[0] | ((unsigned)e[1] << 16), (unsigned)e[2] | ((unsigned)e[3] << 16),
;                  (unsigned)e[4] | ((unsigned)e[5] << 16), (unsigned)e[6] | ((unsigned)e[7] << 16)};
;       *reinterpret_cast<u32x4*>(dst + (long)(n0 + nn) * K + k0 + kb) = w; }
;     __syncthreads();
.LBB0_132:
	s_ashr_i32 s4, s39, 31
	s_waitcnt lgkmcnt(0)
	s_barrier
	ds_read_u16 v8, v13
	ds_read_u16 v14, v13 offset:144
	ds_read_u16 v15, v13 offset:288
	ds_read_u16 v18, v13 offset:432
	ds_read_u16 v16, v13 offset:576
	ds_read_u16 v19, v13 offset:720
	ds_read_u16 v17, v13 offset:864
	ds_read_u16 v20, v13 offset:1008
	s_lshr_b32 s4, s4, 27
	s_add_i32 s4, s39, s4
	s_ashr_i32 s4, s4, 5
	s_mov_b32 s16, 0x5040100
	s_lshl_b32 s68, s4, 6
	s_waitcnt lgkmcnt(6)
	v_perm_b32 v14, v14, v8, s16
	v_add_u32_e32 v8, s8, v12
	s_lshl_b32 s4, s4, 11
	s_waitcnt lgkmcnt(4)
	v_perm_b32 v15, v18, v15, s16
	v_subrev_u32_e32 v18, s4, v8
	s_waitcnt lgkmcnt(0)
	v_perm_b32 v17, v20, v17, s16
	v_perm_b32 v16, v19, v16, s16
	v_ashrrev_i32_e32 v19, 31, v18
	v_readlane_b32 s16, v255, 21
	v_lshlrev_b64 v[18:19], 12, v[18:19]
	v_readlane_b32 s17, v255, 22
	s_ashr_i32 s69, s68, 31
	s_add_i32 s8, s8, s9
	v_lshl_add_u64 v[18:19], s[16:17], 0, v[18:19]
	v_lshl_add_u64 v[18:19], s[68:69], 1, v[18:19]
	v_lshl_add_u64 v[18:19], v[18:19], 0, v[32:33]
	s_andn2_b64 vcc, exec, s[6:7]
	s_mov_b32 s39, s38
	global_store_dwordx4 v[18:19], v[14:17], off
	s_waitcnt lgkmcnt(0)
	s_barrier
	s_cbranch_vccz .LBB0_139

; template <int CM>
; DEVI void transpose_job(const float* __restrict__ src, int srcld, const float* __restrict__ g, bf16* __restrict__ dst,
;                         int K, int Ndst, unsigned short* lds, const int wave_u, const int vb, const int nvb) {
;     ...
;     { const int nn = tid >> 3, kb = (tid & 7) * 8; unsigned short e[8];
; #pragma unroll
;       for (int i = 0; i < 8; ++i) e[i] = lds[(kb + i) * 72 + nn];
;       u32x4 w = {(unsigned)e[0] | ((unsigned)e[1] << 16), (unsigned)e[2] | ((unsigned)e[3] << 16),
;                  (unsigned)e[4] | ((unsigned)e[5] << 16), (unsigned)e[6] | ((unsigned)e[7] << 16)};
;       *reinterpret_cast<u32x4*>(dst + (long)(n0 + nn) * K + k0 + kb) = w; }
;     __syncthreads();
.LBB0_142:
	s_ashr_i32 s4, s9, 31
	s_lshr_b32 s4, s4, 27
	s_add_i32 s4, s9, s4
	s_waitcnt lgkmcnt(0)
	s_barrier
	ds_read_u16 v12, v11
	ds_read_u16 v16, v11 offset:144
	ds_read_u16 v13, v11 offset:288
	ds_read_u16 v17, v11 offset:432
	ds_read_u16 v14, v11 offset:576
	ds_read_u16 v18, v11 offset:720
	ds_read_u16 v15, v11 offset:864
	ds_read_u16 v19, v11 offset:1008
	s_ashr_i32 s4, s4, 5
	s_mov_b32 s9, 0x5040100
	s_lshl_b32 s38, s4, 6
	s_waitcnt lgkmcnt(6)
	v_perm_b32 v12, v16, v12, s9
	v_add_u32_e32 v16, s7, v8
	s_lshl_b32 s4, s4, 11
	v_subrev_u32_e32 v16, s4, v16
	s_waitcnt lgkmcnt(4)
	v_perm_b32 v13, v17, v13, s9
	v_ashrrev_i32_e32 v17, 31, v16
	v_readlane_b32 s16, v255, 23
	v_lshlrev_b64 v[16:17], 9, v[16:17]
	v_readlane_b32 s17, v255, 24
	s_ashr_i32 s39, s38, 31
	s_waitcnt lgkmcnt(0)
	v_perm_b32 v15, v19, v15, s9
	v_lshl_add_u64 v[16:17], s[16:17], 0, v[16:17]
	v_lshl_add_u64 v[16:17], s[38:39], 1, v[16:17]
	v_perm_b32 v14, v18, v14, s9
	v_lshl_add_u64 v[16:17], v[16:17], 0, v[32:33]
	s_add_i32 s7, s7, s6
	s_and_b64 vcc, exec, s[0:1]
	s_mov_b32 s9, s8
	global_store_dwordx4 v[16:17], v[12:15], off
	s_waitcnt lgkmcnt(0)
	s_barrier
	s_cbranch_vccnz .LBB0_146

; DEVI int RSI(int row) { return ((row >> 3) << 5) | (row & 7); }
; DEVI float sigmoidf_(float x) { return fminf(__builtin_amdgcn_rcpf(1.f + __builtin_amdgcn_exp2f(-LOG2E * x)), 1.f); }
;     ...
;     if (row < MP || Tf == nullptr) {
; #pragma unroll
;       for (int i = 0; i < 4; ++i) {
;         u32x4 w = *reinterpret_cast<const u32x4*>(tr + (i * 64 + lane) * 8);
; #pragma unroll
;         for (int j = 0; j < 4; ++j) { tv[i * 8 + 2 * j] = __uint_as_float(w[j] << 16); tv[i * 8 + 2 * j + 1] = __uint_as_float(w[j] & 0xffff0000u); }
;       }
;     } else {
;       const float* tf = Tf + (long)(row - MP) * DM;
; #pragma unroll
;       for (int i = 0; i < 32; ++i) tv[i] = 0.f;
; #pragma unroll 1
;       for (int ks = 0; ks < nslab; ++ks) {
; #pragma unroll
;         for (int i = 0; i < 4; ++i) {
;           f32x4 a = *(const f32x4*)(tf + (long)ks * MS * DM + (i * 64 + lane) * 8), b = *(const f32x4*)(tf + (long)ks * MS * DM + (i * 64 + lane) * 8 + 4);
; #pragma unroll
;           for (int j = 0; j < 4; ++j) { tv[i * 8 + j] += a[j]; tv[i * 8 + 4 + j] += b[j]; }
;         }
;       }
;       if (Ug) {
;         const float sc = rsg[RSI(row)];
; #pragma unroll
;         for (int i = 0; i < 4; ++i) {
;           const u32x4 w = *reinterpret_cast<const u32x4*>(Ug + (long)row * DM + (i * 64 + lane) * 8);
; #pragma unroll
;           for (int j = 0; j < 4; ++j) { tv[i * 8 + 2 * j] = __uint_as_float(w[j] << 16) * sigmoidf_(tv[i * 8 + 2 * j] * sc);
;             tv[i * 8 + 2 * j + 1] = __uint_as_float(w[j] & 0xffff0000u) * sigmoidf_(tv[i * 8 + 2 * j + 1] * sc); }
;         }
;       }
;     }
; #pragma unroll
;     for (int i = 0; i < 32; ++i) ss += tv[i] * tv[i];
;     ss = wave_sum(ss, lane);
;     const float rs = rsqrtf(ss * (1.f / DM) + EPS);
;     float s2 = 0.f;
; #pragma unroll
;     for (int i = 0; i < 4; ++i) {
;       const int c = (i * 64 + lane) * 8;
.LBB0_157:
	v_lshl_add_u64 v[66:67], v[64:65], 0, s[84:85]
	s_mov_b32 s0, 0xe2c8000
	v_add_co_u32_e64 v104, s[0:1], s0, v66
	s_add_u32 s84, s84, 0x400000
	s_nop 0
	v_addc_co_u32_e64 v105, s[0:1], 0, v67, s[0:1]
	s_mov_b32 s0, 0xe2c9000
	s_nop 0
	v_add_co_u32_e64 v66, s[0:1], s0, v66
	s_addc_u32 s85, s85, 0
	s_nop 0
	v_addc_co_u32_e64 v67, s[0:1], 0, v67, s[0:1]
	global_load_dwordx4 v[76:79], v[66:67], off offset:2064
	global_load_dwordx4 v[80:83], v[66:67], off offset:2048
	global_load_dwordx4 v[84:87], v[66:67], off offset:16
	global_load_dwordx4 v[88:91], v[66:67], off
	global_load_dwordx4 v[92:95], v[104:105], off offset:2064
	global_load_dwordx4 v[96:99], v[104:105], off offset:2048
	global_load_dwordx4 v[100:103], v[104:105], off offset:16
	s_nop 0
	global_load_dwordx4 v[104:107], v[104:105], off
	s_cmp_lg_u32 s84, 0x2000000
	s_waitcnt vmcnt(0) lgkmcnt(0)
	v_pk_add_f32 v[30:31], v[30:31], v[78:79]
	v_pk_add_f32 v[12:13], v[12:13], v[82:83]
	v_pk_add_f32 v[8:9], v[8:9], v[86:87]
	v_pk_add_f32 v[4:5], v[4:5], v[90:91]
	v_pk_add_f32 v[20:21], v[20:21], v[94:95]
	v_pk_add_f32 v[16:17], v[16:17], v[98:99]
	v_pk_add_f32 v[24:25], v[24:25], v[102:103]
	v_pk_add_f32 v[0:1], v[0:1], v[106:107]
	v_pk_add_f32 v[28:29], v[28:29], v[76:77]
	v_pk_add_f32 v[14:15], v[14:15], v[80:81]
	v_pk_add_f32 v[10:11], v[10:11], v[84:85]
	v_pk_add_f32 v[6:7], v[6:7], v[88:89]
	v_pk_add_f32 v[22:23], v[22:23], v[92:93]
	v_pk_add_f32 v[18:19], v[18:19], v[96:97]
	v_pk_add_f32 v[26:27], v[26:27], v[100:101]
	v_pk_add_f32 v[2:3], v[2:3], v[104:105]
	s_cbranch_scc1 .LBB0_157
.LBB0_158:
	s_or_saveexec_b64 s[0:1], s[68:69]
	v_lshlrev_b64 v[64:65], 11, v[42:43]
	s_xor_b64 exec, exec, s[0:1]
	s_cbranch_execz .LBB0_160
	s_waitcnt lgkmcnt(0)
	v_lshl_add_u64 v[0:1], v[64:65], 1, v[44:45]
	global_load_dwordx4 v[4:7], v[0:1], off
	global_load_dwordx4 v[8:11], v[0:1], off offset:1024
	global_load_dwordx4 v[12:15], v[0:1], off offset:2048
	global_load_dwordx4 v[28:31], v[0:1], off offset:3072
	s_waitcnt vmcnt(0) lgkmcnt(0)
	v_lshlrev_b32_e32 v2, 16, v4
	v_and_b32_e32 v3, 0xffff0000, v4
	v_lshlrev_b32_e32 v0, 16, v5
	v_and_b32_e32 v1, 0xffff0000, v5
	v_lshlrev_b32_e32 v26, 16, v6
	v_and_b32_e32 v27, 0xffff0000, v6
	v_lshlrev_b32_e32 v24, 16, v7
	v_and_b32_e32 v25, 0xffff0000, v7
	v_lshlrev_b32_e32 v18, 16, v8
	v_and_b32_e32 v19, 0xffff0000, v8
	v_lshlrev_b32_e32 v16, 16, v9
	v_and_b32_e32 v17, 0xffff0000, v9
	v_lshlrev_b32_e32 v22, 16, v10
	v_and_b32_e32 v23, 0xffff0000, v10
	v_lshlrev_b32_e32 v20, 16, v11
	v_and_b32_e32 v21, 0xffff0000, v11
	v_lshlrev_b32_e32 v6, 16, v12
	v_and_b32_e32 v7, 0xffff0000, v12
	v_lshlrev_b32_e32 v4, 16, v13
	v_and_b32_e32 v5, 0xffff0000, v13
	v_lshlrev_b32_e32 v10, 16, v14
	v_and_b32_e32 v11, 0xffff0000, v14
	v_lshlrev_b32_e32 v8, 16, v15
	v_and_b32_e32 v9, 0xffff0000, v15
	v_lshlrev_b32_e32 v14, 16, v28
	v_and_b32_e32 v15, 0xffff0000, v28
	v_lshlrev_b32_e32 v12, 16, v29
	v_and_b32_e32 v13, 0xffff0000, v29
	v_lshlrev_b32_e32 v28, 16, v30
	v_and_b32_e32 v29, 0xffff0000, v30
	v_lshlrev_b32_e32 v30, 16, v31
	v_and_b32_e32 v31, 0xffff0000, v31
.LBB0_160:
	s_or_b64 exec, exec, s[0:1]
	v_mul_f32_e32 v43, v3, v3
	v_fmac_f32_e32 v43, v2, v2
	v_fmac_f32_e32 v43, v0, v0
	s_waitcnt lgkmcnt(0)
	v_fmac_f32_e32 v43, v1, v1
	v_fmac_f32_e32 v43, v26, v26
	v_fmac_f32_e32 v43, v27, v27
	v_fmac_f32_e32 v43, v24, v24
	v_fmac_f32_e32 v43, v25, v25
	v_fmac_f32_e32 v43, v18, v18
	v_fmac_f32_e32 v43, v19, v19
	v_fmac_f32_e32 v43, v16, v16
	v_fmac_f32_e32 v43, v17, v17
	v_fmac_f32_e32 v43, v22, v22
	v_fmac_f32_e32 v43, v23, v23
	v_fmac_f32_e32 v43, v20, v20
	v_fmac_f32_e32 v43, v21, v21
	v_fmac_f32_e32 v43, v6, v6
	v_fmac_f32_e32 v43, v7, v7
	v_fmac_f32_e32 v43, v4, v4
	v_fmac_f32_e32 v43, v5, v5
	v_fmac_f32_e32 v43, v10, v10
	v_fmac_f32_e32 v43, v11, v11
	v_fmac_f32_e32 v43, v8, v8
	v_fmac_f32_e32 v43, v9, v9
	v_fmac_f32_e32 v43, v14, v14
	v_fmac_f32_e32 v43, v15, v15
	v_fmac_f32_e32 v43, v12, v12
	v_fmac_f32_e32 v43, v13, v13
	v_pk_mul_f32 v[76:77], v[28:29], v[28:29]
	v_pk_mul_f32 v[66:67], v[30:31], v[30:31]
	v_add_f32_e32 v43, v76, v43
	v_add_f32_e32 v43, v77, v43
	v_add_f32_e32 v43, v66, v43
	v_add_f32_e32 v43, v67, v43
	v_lshl_add_u64 v[66:67], v[62:63], 0, v[32:33]
	global_load_dwordx4 v[76:79], v[66:67], off offset:16
	global_load_dwordx4 v[80:83], v[66:67], off
	ds_bpermute_b32 v57, v68, v43
	s_mov_b32 s0, 0x800000
	v_mov_b32_e32 v61, v33
	s_waitcnt lgkmcnt(0)
	v_add_f32_e32 v43, v43, v57
	ds_bpermute_b32 v57, v69, v43
	s_waitcnt lgkmcnt(0)
	v_add_f32_e32 v43, v43, v57
	ds_bpermute_b32 v57, v70, v43
	s_waitcnt lgkmcnt(0)
	v_add_f32_e32 v43, v43, v57
	ds_bpermute_b32 v57, v71, v43
	s_waitcnt lgkmcnt(0)
	v_add_f32_e32 v43, v43, v57
	ds_bpermute_b32 v57, v72, v43
	s_waitcnt lgkmcnt(0)
	v_add_f32_e32 v43, v43, v57
	ds_bpermute_b32 v57, v73, v43
	s_waitcnt lgkmcnt(0)
	v_add_f32_e32 v43, v43, v57
	v_fmamk_f32 v43, v43, 0x3a000000, v186
	v_cmp_gt_f32_e64 s[0:1], s0, v43
	v_mul_f32_e32 v57, 0x4b800000, v43
	s_nop 0
	v_cndmask_b32_e64 v43, v43, v57, s[0:1]
	v_rsq_f32_e32 v43, v43
	s_nop 0
	v_mul_f32_e32 v57, 0x45800000, v43
	v_cndmask_b32_e64 v43, v43, v57, s[0:1]
	v_mul_f32_e32 v26, v26, v43
	v_mul_f32_e32 v27, v27, v43
	v_mul_f32_e32 v2, v2, v43
	v_mul_f32_e32 v3, v3, v43
	v_mul_f32_e32 v0, v0, v43
	v_mul_f32_e32 v1, v1, v43
	v_mul_f32_e32 v22, v22, v43
	v_mul_f32_e32 v18, v18, v43
	v_mul_f32_e32 v23, v23, v43
	v_mul_f32_e32 v19, v19, v43
	v_mul_f32_e32 v10, v10, v43
	v_mul_f32_e32 v6, v6, v43
	v_mul_f32_e32 v11, v11, v43
	v_mul_f32_e32 v7, v7, v43
	v_mul_f32_e32 v14, v14, v43
	s_waitcnt vmcnt(0)
; DEVI int RSI(int row) { return ((row >> 3) << 5) | (row & 7); }
;     ...
;     float s2 = 0.f;
; #pragma unroll
;     for (int i = 0; i < 4; ++i) {
;       const int c = (i * 64 + lane) * 8;
;       f32x4 x0, x1;
;       if (xin_b) { const u32x4 w = *reinterpret_cast<const u32x4*>(xin_b + (long)row * DM + c);
;         x0 = f32x4{__uint_as_float(w[0] << 16), __uint_as_float(w[0] & 0xffff0000u), __uint_as_float(w[1] << 16), __uint_as_float(w[1] & 0xffff0000u)};
;         x1 = f32x4{__uint_as_float(w[2] << 16), __uint_as_float(w[2] & 0xffff0000u), __uint_as_float(w[3] << 16), __uint_as_float(w[3] & 0xffff0000u)}; }
;       else { x0 = *(const f32x4*)(xr + c); x1 = *(const f32x4*)(xr + c + 4); }
;       f32x4 g0 = *(const f32x4*)(g + c), g1 = *(const f32x4*)(g + c + 4);
;       f32x4 o0, o1;
; #pragma unroll
;       for (int j = 0; j < 4; ++j) { o0[j] = x0[j] + tv[i * 8 + j] * rs * g0[j]; o1[j] = x1[j] + tv[i * 8 + 4 + j] * rs * g1[j];
;         s2 += o0[j] * o0[j] + o1[j] * o1[j]; }
;       if (y) { *(f32x4*)(y + (long)row * DM + c) = o0; *(f32x4*)(y + (long)row * DM + c + 4) = o1; }
;       if (yb) { u32x4 w = {cvtpk(o0[0], o0[1]), cvtpk(o0[2], o0[3]), cvtpk(o1[0], o1[1]), cvtpk(o1[2], o1[3])};
;         *reinterpret_cast<u32x4*>(yb + (long)row * DM + c) = w; }
;     }
;     if (rs_out) { s2 = wave_sum(s2, lane); if (lane == 0) rs_out[RSI(row)] = rsqrtf(s2 * (1.f / DM) + EPS); }
	v_fma_f32 v26, v38, v26, v76
	v_fma_f32 v27, v39, v27, v77
	s_waitcnt vmcnt(0)
	v_fma_f32 v2, v34, v2, v80
	v_mul_f32_e32 v57, v26, v26
	v_fma_f32 v3, v35, v3, v81
	v_mul_f32_e32 v59, v27, v27
	v_fmac_f32_e32 v57, v2, v2
	v_fmac_f32_e32 v59, v3, v3
	v_add_f32_e32 v57, v57, v59
	v_fma_f32 v59, v36, v0, v82
	v_mul_f32_e32 v0, v24, v43
	v_fma_f32 v24, v40, v0, v78
	v_fmac_f32_e32 v83, v37, v1
	v_mul_f32_e32 v1, v25, v43
	v_mul_f32_e32 v0, v24, v24
	v_fmac_f32_e32 v79, v41, v1
	v_fmac_f32_e32 v0, v59, v59
	v_mul_f32_e32 v1, v79, v79
	v_add_f32_e32 v0, v0, v57
	v_fmac_f32_e32 v1, v83, v83
	v_add_f32_e32 v57, v1, v0
	v_cvt_pk_bf16_f32 v0, v2, v3
	v_cvt_pk_bf16_f32 v1, v59, v83
	v_cvt_pk_bf16_f32 v2, v26, v27
	v_cvt_pk_bf16_f32 v3, v24, v79
	v_lshl_add_u64 v[24:25], v[64:65], 1, v[52:53]
	global_store_dwordx4 v[24:25], v[0:3], off
	global_load_dwordx4 v[0:3], v[66:67], off offset:2064
	s_nop 0
	global_load_dwordx4 v[64:67], v[66:67], off offset:2048
	s_nop 0
	global_load_dwordx4 v[76:79], v[46:47], off offset:2064
	global_load_dwordx4 v[80:83], v[46:47], off offset:2048
	v_mov_b32_e32 v59, v33
	s_waitcnt vmcnt(0)
	v_fma_f32 v22, v76, v22, v0
	v_fma_f32 v18, v80, v18, v64
	v_mul_f32_e32 v0, v22, v22
	v_fma_f32 v23, v77, v23, v1
	v_fmac_f32_e32 v0, v18, v18
	v_fma_f32 v19, v81, v19, v65
	v_mul_f32_e32 v1, v23, v23
	v_add_f32_e32 v0, v0, v57
	v_fmac_f32_e32 v1, v19, v19
	v_add_f32_e32 v0, v1, v0
	v_mul_f32_e32 v1, v16, v43
	v_mul_f32_e32 v16, v20, v43
	v_fma_f32 v16, v78, v16, v2
	v_fma_f32 v1, v82, v1, v66
	v_mul_f32_e32 v2, v16, v16
	v_fmac_f32_e32 v2, v1, v1
	v_add_f32_e32 v0, v2, v0
	v_mul_f32_e32 v2, v17, v43
	v_fmac_f32_e32 v67, v83, v2
	v_mul_f32_e32 v2, v21, v43
	v_fmac_f32_e32 v3, v79, v2
	v_mul_f32_e32 v2, v3, v3
	v_fmac_f32_e32 v2, v67, v67
	v_add_f32_e32 v26, v2, v0
	v_cvt_pk_bf16_f32 v0, v18, v19
	v_cvt_pk_bf16_f32 v1, v1, v67
	v_cvt_pk_bf16_f32 v2, v22, v23
	v_cvt_pk_bf16_f32 v3, v16, v3
	global_store_dwordx4 v[24:25], v[0:3], off offset:1024
	v_lshl_add_u64 v[16:17], v[62:63], 0, v[58:59]
	global_load_dwordx4 v[0:3], v[16:17], off offset:16
	s_nop 0
	global_load_dwordx4 v[16:19], v[16:17], off
	s_nop 0
	global_load_dwordx4 v[20:23], v[48:49], off offset:16
	global_load_dwordx4 v[64:67], v[48:49], off
	s_waitcnt vmcnt(0)
	v_fma_f32 v10, v20, v10, v0
	v_fma_f32 v6, v64, v6, v16
	v_mul_f32_e32 v0, v10, v10
	v_fma_f32 v11, v21, v11, v1
	v_fmac_f32_e32 v0, v6, v6
	v_fma_f32 v7, v65, v7, v17
	v_mul_f32_e32 v1, v11, v11
	v_add_f32_e32 v0, v0, v26
	v_fmac_f32_e32 v1, v7, v7
	v_add_f32_e32 v0, v1, v0
	v_mul_f32_e32 v1, v4, v43
	v_mul_f32_e32 v4, v8, v43
	v_fma_f32 v4, v22, v4, v2
	v_fma_f32 v1, v66, v1, v18
	v_mul_f32_e32 v2, v4, v4
	v_fmac_f32_e32 v2, v1, v1
	v_add_f32_e32 v0, v2, v0
	v_mul_f32_e32 v2, v5, v43
	v_fmac_f32_e32 v19, v67, v2
	v_mul_f32_e32 v2, v9, v43
	v_fmac_f32_e32 v3, v23, v2
	v_mul_f32_e32 v2, v3, v3
	v_fmac_f32_e32 v2, v19, v19
	v_add_f32_e32 v20, v2, v0
	v_cvt_pk_bf16_f32 v0, v6, v7
	v_cvt_pk_bf16_f32 v1, v1, v19
	v_cvt_pk_bf16_f32 v2, v10, v11
	v_cvt_pk_bf16_f32 v3, v4, v3
	global_store_dwordx4 v[24:25], v[0:3], off offset:2048
	v_lshl_add_u64 v[4:5], v[62:63], 0, v[60:61]
	global_load_dwordx4 v[0:3], v[4:5], off offset:16
	s_nop 0
	global_load_dwordx4 v[4:7], v[4:5], off
	s_nop 0
	global_load_dwordx4 v[8:11], v[50:51], off offset:16
	global_load_dwordx4 v[16:19], v[50:51], off
	s_waitcnt vmcnt(0)
	v_fma_f32 v4, v16, v14, v4
	v_mul_f32_e32 v14, v28, v43
	v_fma_f32 v8, v8, v14, v0
	v_mul_f32_e32 v14, v15, v43
	v_fma_f32 v5, v17, v14, v5
	v_mul_f32_e32 v14, v29, v43
	v_mul_f32_e32 v0, v8, v8
	v_fma_f32 v9, v9, v14, v1
	v_fmac_f32_e32 v0, v4, v4
	v_mul_f32_e32 v1, v9, v9
	v_add_f32_e32 v0, v0, v20
	v_fmac_f32_e32 v1, v5, v5
	v_add_f32_e32 v0, v1, v0
	v_mul_f32_e32 v1, v12, v43
	v_fma_f32 v1, v18, v1, v6
	v_mul_f32_e32 v6, v30, v43
	v_fma_f32 v6, v10, v6, v2
	v_mul_f32_e32 v2, v6, v6
	v_fmac_f32_e32 v2, v1, v1
	v_add_f32_e32 v0, v2, v0
	v_mul_f32_e32 v2, v13, v43
	v_fmac_f32_e32 v7, v19, v2
	v_mul_f32_e32 v2, v31, v43
	v_fmac_f32_e32 v3, v11, v2
	v_mul_f32_e32 v2, v3, v3
	v_fmac_f32_e32 v2, v7, v7
	v_add_f32_e32 v10, v2, v0
	v_cvt_pk_bf16_f32 v0, v4, v5
	v_cvt_pk_bf16_f32 v1, v1, v7
	v_cvt_pk_bf16_f32 v2, v8, v9
	v_cvt_pk_bf16_f32 v3, v6, v3
	global_store_dwordx4 v[24:25], v[0:3], off offset:3072
	ds_bpermute_b32 v0, v68, v10
	s_waitcnt lgkmcnt(0)
	v_add_f32_e32 v0, v10, v0
	ds_bpermute_b32 v1, v69, v0
	s_waitcnt lgkmcnt(0)
	v_add_f32_e32 v0, v0, v1
	ds_bpermute_b32 v1, v70, v0
	s_waitcnt lgkmcnt(0)
	v_add_f32_e32 v0, v0, v1
	ds_bpermute_b32 v1, v71, v0
	s_waitcnt lgkmcnt(0)
	v_add_f32_e32 v0, v0, v1
	ds_bpermute_b32 v1, v72, v0
	s_waitcnt lgkmcnt(0)
	v_add_f32_e32 v0, v0, v1
	ds_bpermute_b32 v1, v73, v0
	s_and_saveexec_b64 s[6:7], vcc
	s_cbranch_execz .LBB0_150
	s_waitcnt lgkmcnt(0)
	v_add_f32_e32 v0, v0, v1
	v_fmamk_f32 v0, v0, 0x3a000000, v186
	s_mov_b32 s0, 0x800000
	v_mul_f32_e32 v1, 0x4b800000, v0
	v_cmp_gt_f32_e64 s[0:1], s0, v0
	s_movk_i32 s4, 0xffe0
	s_nop 0
	v_cndmask_b32_e64 v0, v0, v1, s[0:1]
	v_rsq_f32_e32 v1, v0
	v_lshlrev_b32_e32 v0, 2, v42
	v_and_or_b32 v0, v0, s4, v74
	v_mul_f32_e32 v2, 0x45800000, v1
	v_cndmask_b32_e64 v2, v1, v2, s[0:1]
	v_readlane_b32 s0, v255, 25
	v_ashrrev_i32_e32 v1, 31, v0
	v_readlane_b32 s1, v255, 26
	s_nop 1
	v_lshl_add_u64 v[0:1], v[0:1], 2, s[0:1]
	global_store_dword v[0:1], v2, off
	s_branch .LBB0_150

; #define EPI_LOOP(...) _Pragma("unroll") for(int ai=0;ai<2;++ai) _Pragma("unroll") for(int bj=0;bj<2;++bj) \
;   _Pragma("unroll") for(int m=0;m<4;++m) _Pragma("unroll") for(int n=0;n<2;++n) { \
;     const int row=brow+ai*128+wr*64+m*16+fq*4; const int col=bcol+bj*128+wc*32+n*16+fr; \
;     f32x4& v=acc[ai][bj][m][n]; __VA_ARGS__ if (n == 1 && (m & 1)) __builtin_amdgcn_sched_barrier(0); }
; DEVI void run_phase(const int ph, const Params& P, char* shmc, const int wave_u) {
;     ...
;       gemm_core(w_out_t + (long)brow * 2048, 2048, merged + (long)bcol * 2048, 2048, 2048, acc, shm, wave_u);
;       GEMM_IDS
;       EPI_LOOP({ st_bf4(T + (long)col * 2048 + row, v[0], v[1], v[2], v[3]); })
.LBB0_174:
	s_or_b64 exec, exec, s[6:7]
	v_mbcnt_lo_u32_b32 v166, -1, 0
	v_mbcnt_hi_u32_b32 v166, -1, v166
	v_bfe_u32 v166, v166, 4, 1
	v_mul_u32_u24_e32 v166, 24, v166
	v_mov_b32_e32 v167, 0
	v_mbcnt_lo_u32_b32 v32, -1, 0
	v_mbcnt_hi_u32_b32 v32, -1, v32
	v_cvt_pk_bf16_f32 v126, v126, v127
	v_cvt_pk_bf16_f32 v127, v128, v129
	s_nop 0
	v_or_b32_e32 v131, s5, v32
	v_and_b32_e32 v132, 15, v32
	v_ashrrev_i32_e32 v130, 2, v131
	v_lshrrev_b32_e32 v32, 2, v32
	v_and_b32_e32 v130, 0xffffffc0, v130
	v_and_or_b32 v32, v32, 12, s0
	v_add_u32_e32 v130, v32, v130
	v_lshrrev_b32_e32 v32, 1, v131
	v_and_b32_e32 v32, 0x60, v32
	v_or3_b32 v132, v132, v32, s8
	v_ashrrev_i32_e32 v131, 31, v130
	v_ashrrev_i32_e32 v133, 31, v132
	v_lshl_add_u64 v[134:135], v[130:131], 1, s[12:13]
	v_lshlrev_b64 v[136:137], 12, v[132:133]
	v_lshl_add_u64 v[138:139], v[134:135], 0, v[136:137]
	v_mov_b32_e32 v140, v126
	v_mov_b32_e32 v141, v127
	v_lshl_add_u64 v[144:145], v[138:139], 0, v[166:167]
	v_or_b32_e32 v126, 16, v132
	v_ashrrev_i32_e32 v127, 31, v126
	v_lshlrev_b64 v[126:127], 12, v[126:127]
	v_lshl_add_u64 v[128:129], v[134:135], 0, v[126:127]
	v_cvt_pk_bf16_f32 v122, v122, v123
	v_cvt_pk_bf16_f32 v123, v124, v125
	v_mov_b32_e32 v148, v122
	v_mov_b32_e32 v149, v123
	v_lshl_add_u64 v[160:161], v[128:129], 0, v[166:167]
	v_cvt_pk_bf16_f32 v118, v118, v119
	v_cvt_pk_bf16_f32 v119, v120, v121
	v_mov_b32_e32 v142, v118
	v_mov_b32_e32 v143, v119
	s_nop 1
	v_permlane16_swap_b32_e32 v140, v142
	v_permlane16_swap_b32_e32 v141, v143
	global_store_dwordx4 v[144:145], v[140:143], off
	v_cvt_pk_bf16_f32 v114, v114, v115
	v_cvt_pk_bf16_f32 v115, v116, v117
	v_mov_b32_e32 v150, v114
	v_mov_b32_e32 v151, v115
	s_nop 1
	v_permlane16_swap_b32_e32 v148, v150
	v_permlane16_swap_b32_e32 v149, v151
	global_store_dwordx4 v[160:161], v[148:151], off
	v_cvt_pk_bf16_f32 v110, v110, v111
	v_cvt_pk_bf16_f32 v111, v112, v113
	v_mov_b32_e32 v152, v110
	v_mov_b32_e32 v153, v111
	v_lshl_add_u64 v[162:163], v[138:139], 0, v[166:167]
	v_cvt_pk_bf16_f32 v106, v106, v107
	v_cvt_pk_bf16_f32 v107, v108, v109
	v_mov_b32_e32 v156, v106
	v_mov_b32_e32 v157, v107
	v_lshl_add_u64 v[164:165], v[128:129], 0, v[166:167]
	v_cvt_pk_bf16_f32 v102, v102, v103
	v_cvt_pk_bf16_f32 v103, v104, v105
	v_mov_b32_e32 v154, v102
	v_mov_b32_e32 v155, v103
	s_nop 1
	v_permlane16_swap_b32_e32 v152, v154
	v_permlane16_swap_b32_e32 v153, v155
	global_store_dwordx4 v[162:163], v[152:155], off offset:64
	v_cvt_pk_bf16_f32 v98, v98, v99
	v_cvt_pk_bf16_f32 v99, v100, v101
	v_mov_b32_e32 v158, v98
	v_mov_b32_e32 v159, v99
	s_nop 1
	v_permlane16_swap_b32_e32 v156, v158
	v_permlane16_swap_b32_e32 v157, v159
	global_store_dwordx4 v[164:165], v[156:159], off offset:64
	v_or_b32_e32 v98, 0x80, v132
	v_ashrrev_i32_e32 v99, 31, v98
	v_lshlrev_b64 v[98:99], 12, v[98:99]
	v_lshl_add_u64 v[100:101], v[134:135], 0, v[98:99]
	v_cvt_pk_bf16_f32 v94, v94, v95
	v_cvt_pk_bf16_f32 v95, v96, v97
	v_mov_b32_e32 v140, v94
	v_mov_b32_e32 v141, v95
	v_lshl_add_u64 v[144:145], v[100:101], 0, v[166:167]
	v_or_b32_e32 v94, 0x90, v132
	v_ashrrev_i32_e32 v95, 31, v94
	v_lshlrev_b64 v[94:95], 12, v[94:95]
	v_lshl_add_u64 v[96:97], v[134:135], 0, v[94:95]
	v_cvt_pk_bf16_f32 v90, v90, v91
	v_cvt_pk_bf16_f32 v91, v92, v93
	v_mov_b32_e32 v148, v90
	v_mov_b32_e32 v149, v91
	v_lshl_add_u64 v[160:161], v[96:97], 0, v[166:167]
	v_cvt_pk_bf16_f32 v86, v86, v87
	v_cvt_pk_bf16_f32 v87, v88, v89
	v_mov_b32_e32 v142, v86
	v_mov_b32_e32 v143, v87
	s_nop 1
	v_permlane16_swap_b32_e32 v140, v142
	v_permlane16_swap_b32_e32 v141, v143
	global_store_dwordx4 v[144:145], v[140:143], off
	v_cvt_pk_bf16_f32 v82, v82, v83
	v_cvt_pk_bf16_f32 v83, v84, v85
	v_mov_b32_e32 v150, v82
	v_mov_b32_e32 v151, v83
	s_nop 1
	v_permlane16_swap_b32_e32 v148, v150
	v_permlane16_swap_b32_e32 v149, v151
	global_store_dwordx4 v[160:161], v[148:151], off
	v_cvt_pk_bf16_f32 v78, v78, v79
	v_cvt_pk_bf16_f32 v79, v80, v81
	v_mov_b32_e32 v152, v78
	v_mov_b32_e32 v153, v79
	v_lshl_add_u64 v[162:163], v[100:101], 0, v[166:167]
	v_cvt_pk_bf16_f32 v74, v74, v75
	v_cvt_pk_bf16_f32 v75, v76, v77
	v_mov_b32_e32 v156, v74
	v_mov_b32_e32 v157, v75
	v_lshl_add_u64 v[164:165], v[96:97], 0, v[166:167]
	v_cvt_pk_bf16_f32 v70, v70, v71
	v_cvt_pk_bf16_f32 v71, v72, v73
	v_mov_b32_e32 v154, v70
	v_mov_b32_e32 v155, v71
	s_nop 1
	v_permlane16_swap_b32_e32 v152, v154
	v_permlane16_swap_b32_e32 v153, v155
	global_store_dwordx4 v[162:163], v[152:155], off offset:64
	v_cvt_pk_bf16_f32 v66, v66, v67
	v_cvt_pk_bf16_f32 v67, v68, v69
	v_mov_b32_e32 v158, v66
	v_mov_b32_e32 v159, v67
	s_nop 1
	v_permlane16_swap_b32_e32 v156, v158
	v_permlane16_swap_b32_e32 v157, v159
	global_store_dwordx4 v[164:165], v[156:159], off offset:64
; #define EPI_LOOP(...) _Pragma("unroll") for(int ai=0;ai<2;++ai) _Pragma("unroll") for(int bj=0;bj<2;++bj) \
;   _Pragma("unroll") for(int m=0;m<4;++m) _Pragma("unroll") for(int n=0;n<2;++n) { \
;     const int row=brow+ai*128+wr*64+m*16+fq*4; const int col=bcol+bj*128+wc*32+n*16+fr; \
;     f32x4& v=acc[ai][bj][m][n]; __VA_ARGS__ if (n == 1 && (m & 1)) __builtin_amdgcn_sched_barrier(0); }
; DEVI void run_phase(const int ph, const Params& P, char* shmc, const int wave_u) {
;     ...
;       gemm_core(w_out_t + (long)brow * 2048, 2048, merged + (long)bcol * 2048, 2048, 2048, acc, shm, wave_u);
;       GEMM_IDS
;       EPI_LOOP({ st_bf4(T + (long)col * 2048 + row, v[0], v[1], v[2], v[3]); })
	v_add_u32_e32 v66, 0x80, v130
	v_ashrrev_i32_e32 v67, 31, v66
	v_lshl_add_u64 v[66:67], v[66:67], 1, s[12:13]
	v_lshl_add_u64 v[68:69], v[66:67], 0, v[136:137]
	v_cvt_pk_bf16_f32 v62, v62, v63
	v_cvt_pk_bf16_f32 v63, v64, v65
	v_mov_b32_e32 v140, v62
	v_mov_b32_e32 v141, v63
	v_lshl_add_u64 v[144:145], v[68:69], 0, v[166:167]
	v_lshl_add_u64 v[62:63], v[66:67], 0, v[126:127]
	v_cvt_pk_bf16_f32 v58, v58, v59
	v_cvt_pk_bf16_f32 v59, v60, v61
	v_mov_b32_e32 v148, v58
	v_mov_b32_e32 v149, v59
	v_lshl_add_u64 v[160:161], v[62:63], 0, v[166:167]
	v_add_u32_e32 v58, 0x90, v130
	v_ashrrev_i32_e32 v59, 31, v58
	v_lshl_add_u64 v[58:59], v[58:59], 1, s[12:13]
	v_lshl_add_u64 v[60:61], v[58:59], 0, v[136:137]
	v_cvt_pk_bf16_f32 v54, v54, v55
	v_cvt_pk_bf16_f32 v55, v56, v57
	v_mov_b32_e32 v142, v54
	v_mov_b32_e32 v143, v55
	s_nop 1
	v_permlane16_swap_b32_e32 v140, v142
	v_permlane16_swap_b32_e32 v141, v143
	global_store_dwordx4 v[144:145], v[140:143], off
	v_lshl_add_u64 v[54:55], v[58:59], 0, v[126:127]
	v_cvt_pk_bf16_f32 v50, v50, v51
	v_cvt_pk_bf16_f32 v51, v52, v53
	v_mov_b32_e32 v150, v50
	v_mov_b32_e32 v151, v51
	s_nop 1
	v_permlane16_swap_b32_e32 v148, v150
	v_permlane16_swap_b32_e32 v149, v151
	global_store_dwordx4 v[160:161], v[148:151], off
	v_add_u32_e32 v50, 0xa0, v130
	v_ashrrev_i32_e32 v51, 31, v50
	v_lshl_add_u64 v[50:51], v[50:51], 1, s[12:13]
	v_lshl_add_u64 v[52:53], v[50:51], 0, v[136:137]
	v_cvt_pk_bf16_f32 v46, v46, v47
	v_cvt_pk_bf16_f32 v47, v48, v49
	v_mov_b32_e32 v152, v46
	v_mov_b32_e32 v153, v47
	v_lshl_add_u64 v[162:163], v[52:53], 0, v[166:167]
	v_lshl_add_u64 v[46:47], v[50:51], 0, v[126:127]
	v_cvt_pk_bf16_f32 v42, v42, v43
	v_cvt_pk_bf16_f32 v43, v44, v45
	v_mov_b32_e32 v156, v42
	v_mov_b32_e32 v157, v43
	v_lshl_add_u64 v[164:165], v[46:47], 0, v[166:167]
	v_add_u32_e32 v42, 0xb0, v130
	v_ashrrev_i32_e32 v43, 31, v42
	v_lshl_add_u64 v[42:43], v[42:43], 1, s[12:13]
	v_lshl_add_u64 v[44:45], v[42:43], 0, v[136:137]
	v_cvt_pk_bf16_f32 v38, v38, v39
	v_cvt_pk_bf16_f32 v39, v40, v41
	v_mov_b32_e32 v154, v38
	v_mov_b32_e32 v155, v39
	s_nop 1
	v_permlane16_swap_b32_e32 v152, v154
	v_permlane16_swap_b32_e32 v153, v155
	global_store_dwordx4 v[162:163], v[152:155], off
	v_lshl_add_u64 v[38:39], v[42:43], 0, v[126:127]
	v_cvt_pk_bf16_f32 v34, v34, v35
	v_cvt_pk_bf16_f32 v35, v36, v37
	v_mov_b32_e32 v158, v34
	v_mov_b32_e32 v159, v35
	s_nop 1
	v_permlane16_swap_b32_e32 v156, v158
	v_permlane16_swap_b32_e32 v157, v159
	global_store_dwordx4 v[164:165], v[156:159], off
	v_lshl_add_u64 v[34:35], v[66:67], 0, v[98:99]
	v_cvt_pk_bf16_f32 v28, v28, v29
	v_cvt_pk_bf16_f32 v29, v30, v31
	v_mov_b32_e32 v140, v28
	v_mov_b32_e32 v141, v29
	v_lshl_add_u64 v[144:145], v[34:35], 0, v[166:167]
	v_lshl_add_u64 v[28:29], v[66:67], 0, v[94:95]
	v_cvt_pk_bf16_f32 v24, v24, v25
	v_cvt_pk_bf16_f32 v25, v26, v27
	v_mov_b32_e32 v148, v24
	v_mov_b32_e32 v149, v25
	v_lshl_add_u64 v[160:161], v[28:29], 0, v[166:167]
	v_lshl_add_u64 v[24:25], v[58:59], 0, v[98:99]
	v_cvt_pk_bf16_f32 v20, v20, v21
	v_cvt_pk_bf16_f32 v21, v22, v23
	v_mov_b32_e32 v142, v20
	v_mov_b32_e32 v143, v21
	s_nop 1
	v_permlane16_swap_b32_e32 v140, v142
	v_permlane16_swap_b32_e32 v141, v143
	global_store_dwordx4 v[144:145], v[140:143], off
	v_lshl_add_u64 v[20:21], v[58:59], 0, v[94:95]
	v_cvt_pk_bf16_f32 v16, v16, v17
	v_cvt_pk_bf16_f32 v17, v18, v19
	v_mov_b32_e32 v150, v16
	v_mov_b32_e32 v151, v17
	s_nop 1
	v_permlane16_swap_b32_e32 v148, v150
	v_permlane16_swap_b32_e32 v149, v151
	global_store_dwordx4 v[160:161], v[148:151], off
	v_lshl_add_u64 v[16:17], v[50:51], 0, v[98:99]
	v_cvt_pk_bf16_f32 v12, v12, v13
	v_cvt_pk_bf16_f32 v13, v14, v15
	v_mov_b32_e32 v152, v12
	v_mov_b32_e32 v153, v13
	v_lshl_add_u64 v[162:163], v[16:17], 0, v[166:167]
	v_lshl_add_u64 v[12:13], v[50:51], 0, v[94:95]
	v_cvt_pk_bf16_f32 v8, v8, v9
	v_cvt_pk_bf16_f32 v9, v10, v11
	v_mov_b32_e32 v156, v8
	v_mov_b32_e32 v157, v9
	v_lshl_add_u64 v[164:165], v[12:13], 0, v[166:167]
	v_lshl_add_u64 v[8:9], v[42:43], 0, v[98:99]
	v_cvt_pk_bf16_f32 v4, v4, v5
	v_cvt_pk_bf16_f32 v5, v6, v7
	v_mov_b32_e32 v154, v4
	v_mov_b32_e32 v155, v5
	s_nop 1
	v_permlane16_swap_b32_e32 v152, v154
	v_permlane16_swap_b32_e32 v153, v155
	global_store_dwordx4 v[162:163], v[152:155], off
	v_lshl_add_u64 v[4:5], v[42:43], 0, v[94:95]
	v_cvt_pk_bf16_f32 v0, v0, v1
	v_cvt_pk_bf16_f32 v1, v2, v3
	v_mov_b32_e32 v158, v0
	v_mov_b32_e32 v159, v1
	s_nop 1
	v_permlane16_swap_b32_e32 v156, v158
	v_permlane16_swap_b32_e32 v157, v159
	global_store_dwordx4 v[164:165], v[156:159], off
	v_readlane_b32 s0, v254, 26
	s_add_i32 s75, s75, s0
	s_cmpk_gt_i32 s75, 0x1ff
	v_readlane_b32 s1, v254, 27
	s_cbranch_scc1 .LBB0_169

; #define EPI_LOOP(...) _Pragma("unroll") for(int ai=0;ai<2;++ai) _Pragma("unroll") for(int bj=0;bj<2;++bj) \
;   _Pragma("unroll") for(int m=0;m<4;++m) _Pragma("unroll") for(int n=0;n<2;++n) { \
;     const int row=brow+ai*128+wr*64+m*16+fq*4; const int col=bcol+bj*128+wc*32+n*16+fr; \
;     f32x4& v=acc[ai][bj][m][n]; __VA_ARGS__ if (n == 1 && (m & 1)) __builtin_amdgcn_sched_barrier(0); }
; DEVI void run_phase(const int ph, const Params& P, char* shmc, const int wave_u) {
;     ...
;       gemm_core(w_out_t + (long)brow * 2048 + kofs, 2048, merged + (long)bcol * 2048 + kofs, 2048, 2048 / 8, acc, shm, wave_u);
;       GEMM_IDS
;       EPI_LOOP({ st_f4(Tp + (long)ks * MS * 2048 + (long)(col - MP) * 2048 + row, v[0], v[1], v[2], v[3]); })
.LBB0_185:
	s_or_b64 exec, exec, s[6:7]
	v_readlane_b32 s5, v255, 6
	v_mbcnt_lo_u32_b32 v32, -1, 0
	v_mbcnt_hi_u32_b32 v32, -1, v32
	s_lshl_b32 s1, s69, 3
	v_and_b32_e32 v132, 15, v32
	v_or_b32_e32 v131, s5, v32
	v_ashrrev_i32_e32 v130, 2, v131
	v_lshrrev_b32_e32 v32, 2, v32
	s_sub_i32 s6, s39, s1
	v_and_b32_e32 v130, 0xffffffc0, v130
	v_and_or_b32 v32, v32, 12, s68
	v_add_u32_e32 v130, v32, v130
	v_lshrrev_b32_e32 v32, 1, v131
	s_ashr_i32 s7, s6, 31
	v_and_b32_e32 v32, 0x60, v32
	s_lshl_b64 s[6:7], s[6:7], 22
	s_add_u32 s6, s84, s6
	v_or3_b32 v132, v132, v32, s0
	s_addc_u32 s7, s85, s7
	v_ashrrev_i32_e32 v131, 31, v130
	v_ashrrev_i32_e32 v133, 31, v132
	v_lshl_add_u64 v[130:131], v[130:131], 2, s[6:7]
	v_lshlrev_b64 v[134:135], 13, v[132:133]
	v_lshl_add_u64 v[134:135], v[130:131], 0, v[134:135]
	global_store_dwordx4 v[134:135], v[28:31], off
	s_nop 1
	v_or_b32_e32 v28, 16, v132
	v_ashrrev_i32_e32 v29, 31, v28
	v_lshlrev_b64 v[28:29], 13, v[28:29]
	v_lshl_add_u64 v[28:29], v[130:131], 0, v[28:29]
	global_store_dwordx4 v[28:29], v[0:3], off
	global_store_dwordx4 v[134:135], v[4:7], off offset:64
	global_store_dwordx4 v[28:29], v[8:11], off offset:64
	global_store_dwordx4 v[134:135], v[12:15], off offset:128
	global_store_dwordx4 v[28:29], v[16:19], off offset:128
	global_store_dwordx4 v[134:135], v[20:23], off offset:192
	global_store_dwordx4 v[28:29], v[34:37], off offset:192
	v_or_b32_e32 v0, 0x80, v132
	v_or_b32_e32 v2, 0x90, v132
	v_ashrrev_i32_e32 v1, 31, v0
	v_ashrrev_i32_e32 v3, 31, v2
	v_lshlrev_b64 v[0:1], 13, v[0:1]
	v_lshlrev_b64 v[2:3], 13, v[2:3]
	v_lshl_add_u64 v[0:1], v[130:131], 0, v[0:1]
	v_lshl_add_u64 v[2:3], v[130:131], 0, v[2:3]
	global_store_dwordx4 v[0:1], v[58:61], off
	global_store_dwordx4 v[2:3], v[24:27], off
	global_store_dwordx4 v[0:1], v[38:41], off offset:64
	global_store_dwordx4 v[2:3], v[42:45], off offset:64
	global_store_dwordx4 v[0:1], v[46:49], off offset:128
	global_store_dwordx4 v[2:3], v[50:53], off offset:128
	global_store_dwordx4 v[0:1], v[54:57], off offset:192
	global_store_dwordx4 v[2:3], v[62:65], off offset:192
	global_store_dwordx4 v[134:135], v[66:69], off offset:512
	global_store_dwordx4 v[28:29], v[70:73], off offset:512
	global_store_dwordx4 v[134:135], v[74:77], off offset:576
	global_store_dwordx4 v[28:29], v[78:81], off offset:576
	global_store_dwordx4 v[134:135], v[82:85], off offset:640
	global_store_dwordx4 v[28:29], v[86:89], off offset:640
	global_store_dwordx4 v[134:135], v[90:93], off offset:704
	global_store_dwordx4 v[28:29], v[94:97], off offset:704
	global_store_dwordx4 v[0:1], v[98:101], off offset:512
	global_store_dwordx4 v[2:3], v[102:105], off offset:512
	global_store_dwordx4 v[0:1], v[106:109], off offset:576
	global_store_dwordx4 v[2:3], v[110:113], off offset:576
	global_store_dwordx4 v[0:1], v[114:117], off offset:640
	global_store_dwordx4 v[2:3], v[118:121], off offset:640
	global_store_dwordx4 v[0:1], v[122:125], off offset:704
	global_store_dwordx4 v[2:3], v[126:129], off offset:704
	v_readlane_b32 s0, v254, 26
	s_add_i32 s39, s39, s0
	v_readlane_b32 s0, v253, 8
	s_add_i32 s38, s38, s0
	s_cmpk_gt_i32 s39, 0x7f
	v_readlane_b32 s1, v254, 27
	s_cbranch_scc1 .LBB0_170

; template <int CM>
; DEVI void transpose_job(const float* __restrict__ src, int srcld, const float* __restrict__ g, bf16* __restrict__ dst,
;                         int K, int Ndst, unsigned short* lds, const int wave_u, const int vb, const int nvb) {
;     ...
;     { const int nn = tid >> 3, kb = (tid & 7) * 8; unsigned short e[8];
; #pragma unroll
;       for (int i = 0; i < 8; ++i) e[i] = lds[(kb + i) * 72 + nn];
;       u32x4 w = {(unsigned)e[0] | ((unsigned)e[1] << 16), (unsigned)e[2] | ((unsigned)e[3] << 16),
;                  (unsigned)e[4] | ((unsigned)e[5] << 16), (unsigned)e[6] | ((unsigned)e[7] << 16)};
;       *reinterpret_cast<u32x4*>(dst + (long)(n0 + nn) * K + k0 + kb) = w; }
;     __syncthreads();
.LBB0_193:
	s_ashr_i32 s4, s13, 31
	s_lshr_b32 s4, s4, 25
	s_add_i32 s4, s13, s4
	s_waitcnt lgkmcnt(0)
	s_barrier
	ds_read_u16 v8, v13
	ds_read_u16 v14, v13 offset:144
	ds_read_u16 v15, v13 offset:288
	ds_read_u16 v18, v13 offset:432
	ds_read_u16 v16, v13 offset:576
	ds_read_u16 v19, v13 offset:720
	ds_read_u16 v17, v13 offset:864
	ds_read_u16 v20, v13 offset:1008
	s_ashr_i32 s4, s4, 7
	s_mov_b32 s13, 0x5040100
	s_lshl_b32 s38, s4, 6
	s_waitcnt lgkmcnt(6)
	v_perm_b32 v14, v14, v8, s13
	v_add_u32_e32 v8, s9, v12
	s_lshl_b32 s4, s4, 13
	s_waitcnt lgkmcnt(4)
	v_perm_b32 v15, v18, v15, s13
	v_subrev_u32_e32 v18, s4, v8
	s_waitcnt lgkmcnt(2)
	v_perm_b32 v16, v19, v16, s13
	v_ashrrev_i32_e32 v19, 31, v18
	v_readlane_b32 s16, v255, 19
	v_lshlrev_b64 v[18:19], 12, v[18:19]
	v_readlane_b32 s17, v255, 20
	s_ashr_i32 s39, s38, 31
	s_waitcnt lgkmcnt(0)
	v_perm_b32 v17, v20, v17, s13
	v_lshl_add_u64 v[18:19], s[16:17], 0, v[18:19]
	v_lshl_add_u64 v[18:19], s[38:39], 1, v[18:19]
	v_lshl_add_u64 v[18:19], v[18:19], 0, v[32:33]
	s_add_i32 s9, s9, s8
	s_and_b64 vcc, exec, s[6:7]
	s_mov_b32 s13, s12
	global_store_dwordx4 v[18:19], v[14:17], off
	s_waitcnt lgkmcnt(0)
	s_barrier
	s_cbranch_vccnz .LBB0_200

; #define EPI_LOOP(...) _Pragma("unroll") for(int ai=0;ai<2;++ai) _Pragma("unroll") for(int bj=0;bj<2;++bj) \
;   _Pragma("unroll") for(int m=0;m<4;++m) _Pragma("unroll") for(int n=0;n<2;++n) { \
;     const int row=brow+ai*128+wr*64+m*16+fq*4; const int col=bcol+bj*128+wc*32+n*16+fr; \
;     f32x4& v=acc[ai][bj][m][n]; __VA_ARGS__ if (n == 1 && (m & 1)) __builtin_amdgcn_sched_barrier(0); }
; DEVI void run_phase(const int ph, const Params& P, char* shmc, const int wave_u) {
;     ...
;       GEMM_IDS
;       EPI_LOOP({ const u32x2 a = *reinterpret_cast<const u32x2*>(gates + (long)col * 4096 + br * 2048 + row);
;         st_f4(Mp + (long)sub * MS * 2048 + (long)(col - MP) * 2048 + row, v[0] * __uint_as_float(a[0] << 16), v[1] * __uint_as_float(a[0] & 0xffff0000u),
;               v[2] * __uint_as_float(a[1] << 16), v[3] * __uint_as_float(a[1] & 0xffff0000u)); })
.LBB0_208:
	s_or_b64 exec, exec, s[6:7]
	v_mbcnt_lo_u32_b32 v32, -1, 0
	v_mbcnt_hi_u32_b32 v32, -1, v32
	s_and_b32 s4, s69, 7
	v_or_b32_e32 v131, s5, v32
	v_and_b32_e32 v132, 15, v32
	v_ashrrev_i32_e32 v130, 2, v131
	v_lshrrev_b32_e32 v32, 2, v32
	v_and_b32_e32 v130, 0xffffffc0, v130
	v_and_or_b32 v32, v32, 12, s71
	v_add_u32_e32 v130, v32, v130
	v_lshrrev_b32_e32 v32, 1, v131
	v_and_b32_e32 v32, 0x60, v32
	v_or3_b32 v136, v132, v32, s0
	s_lshl_b32 s0, s70, 12
	v_readlane_b32 s6, v255, 13
	v_readlane_b32 s7, v255, 14
	s_add_u32 s0, s6, s0
	s_addc_u32 s1, s7, 0
	v_ashrrev_i32_e32 v131, 31, v130
	v_ashrrev_i32_e32 v137, 31, v136
	v_lshl_add_u64 v[138:139], v[130:131], 1, s[0:1]
	v_lshlrev_b64 v[134:135], 13, v[136:137]
	v_lshl_add_u64 v[132:133], v[138:139], 0, v[134:135]
	global_load_dwordx2 v[140:141], v[132:133], off
	s_lshl_b32 s4, s4, 22
	v_readlane_b32 s6, v255, 33
	v_readlane_b32 s7, v255, 34
	s_add_u32 s6, s6, s4
	s_addc_u32 s7, s7, 0
	v_lshl_add_u64 v[130:131], v[130:131], 2, s[6:7]
	s_brev_b32 s0, 31
	v_lshl_add_u64 v[134:135], v[130:131], 0, v[134:135]
	s_mov_b32 s1, -1
	v_lshl_add_u64 v[130:131], v[134:135], 0, s[0:1]
	s_brev_b32 s0, 31
	s_waitcnt vmcnt(0) lgkmcnt(0)
	v_lshlrev_b32_e32 v142, 16, v140
	v_and_b32_e32 v143, 0xffff0000, v140
	v_lshlrev_b32_e32 v140, 16, v141
	v_and_b32_e32 v141, 0xffff0000, v141
	v_pk_mul_f32 v[128:129], v[128:129], v[140:141]
	v_add_co_u32_e32 v140, vcc, s0, v134
	v_pk_mul_f32 v[126:127], v[126:127], v[142:143]
	s_nop 0
	v_addc_co_u32_e32 v141, vcc, -1, v135, vcc
	global_store_dwordx4 v[140:141], v[126:129], off
	s_mov_b32 s0, 0xf8020000
	s_mov_b32 s1, -1
	v_or_b32_e32 v126, 16, v136
	v_ashrrev_i32_e32 v127, 31, v126
	v_lshlrev_b64 v[126:127], 13, v[126:127]
	v_lshl_add_u64 v[126:127], v[138:139], 0, v[126:127]
	global_load_dwordx2 v[140:141], v[126:127], off
	v_lshl_add_u64 v[128:129], v[134:135], 0, s[0:1]
	s_mov_b32 s0, 0xf8020000
	s_waitcnt vmcnt(0) lgkmcnt(0)
	v_lshlrev_b32_e32 v142, 16, v140
	v_and_b32_e32 v143, 0xffff0000, v140
	v_lshlrev_b32_e32 v140, 16, v141
	v_and_b32_e32 v141, 0xffff0000, v141
	v_pk_mul_f32 v[124:125], v[124:125], v[140:141]
	v_add_co_u32_e32 v140, vcc, s0, v134
	v_pk_mul_f32 v[122:123], v[122:123], v[142:143]
	s_nop 0
	v_addc_co_u32_e32 v141, vcc, -1, v135, vcc
	global_store_dwordx4 v[140:141], v[122:125], off
	global_load_dwordx2 v[122:123], v[132:133], off offset:32
	s_waitcnt vmcnt(0) lgkmcnt(0)
	v_lshlrev_b32_e32 v124, 16, v122
	v_and_b32_e32 v125, 0xffff0000, v122
	v_lshlrev_b32_e32 v122, 16, v123
	v_and_b32_e32 v123, 0xffff0000, v123
	v_pk_mul_f32 v[118:119], v[118:119], v[124:125]
	v_pk_mul_f32 v[120:121], v[120:121], v[122:123]
	global_store_dwordx4 v[130:131], v[118:121], off offset:64
	global_load_dwordx2 v[118:119], v[126:127], off offset:32
	s_waitcnt vmcnt(0) lgkmcnt(0)
	v_lshlrev_b32_e32 v120, 16, v118
	v_and_b32_e32 v121, 0xffff0000, v118
	v_lshlrev_b32_e32 v118, 16, v119
	v_and_b32_e32 v119, 0xffff0000, v119
	v_pk_mul_f32 v[114:115], v[114:115], v[120:121]
	v_pk_mul_f32 v[116:117], v[116:117], v[118:119]
	global_store_dwordx4 v[128:129], v[114:117], off offset:64
	global_load_dwordx2 v[114:115], v[132:133], off offset:64
	s_waitcnt vmcnt(0) lgkmcnt(0)
	v_lshlrev_b32_e32 v116, 16, v114
	v_and_b32_e32 v117, 0xffff0000, v114
	v_lshlrev_b32_e32 v114, 16, v115
	v_and_b32_e32 v115, 0xffff0000, v115
	v_pk_mul_f32 v[110:111], v[110:111], v[116:117]
	v_pk_mul_f32 v[112:113], v[112:113], v[114:115]
	global_store_dwordx4 v[130:131], v[110:113], off offset:128
	global_load_dwordx2 v[110:111], v[126:127], off offset:64
	s_waitcnt vmcnt(0) lgkmcnt(0)
	v_lshlrev_b32_e32 v112, 16, v110
	v_and_b32_e32 v113, 0xffff0000, v110
	v_lshlrev_b32_e32 v110, 16, v111
	v_and_b32_e32 v111, 0xffff0000, v111
	v_pk_mul_f32 v[106:107], v[106:107], v[112:113]
	v_pk_mul_f32 v[108:109], v[108:109], v[110:111]
	global_store_dwordx4 v[128:129], v[106:109], off offset:128
	global_load_dwordx2 v[106:107], v[132:133], off offset:96
	s_waitcnt vmcnt(0) lgkmcnt(0)
	v_lshlrev_b32_e32 v108, 16, v106
	v_and_b32_e32 v109, 0xffff0000, v106
	v_lshlrev_b32_e32 v106, 16, v107
	v_and_b32_e32 v107, 0xffff0000, v107
	v_pk_mul_f32 v[102:103], v[102:103], v[108:109]
	v_pk_mul_f32 v[104:105], v[104:105], v[106:107]
	global_store_dwordx4 v[130:131], v[102:105], off offset:192
	global_load_dwordx2 v[102:103], v[126:127], off offset:96
	s_waitcnt vmcnt(0) lgkmcnt(0)
	v_lshlrev_b32_e32 v104, 16, v102
	v_and_b32_e32 v105, 0xffff0000, v102
	v_lshlrev_b32_e32 v102, 16, v103
	v_and_b32_e32 v103, 0xffff0000, v103
	v_pk_mul_f32 v[98:99], v[98:99], v[104:105]
	v_pk_mul_f32 v[100:101], v[100:101], v[102:103]
	global_store_dwordx4 v[128:129], v[98:101], off offset:192
	s_nop 1
	v_or_b32_e32 v98, 0x80, v136
	v_ashrrev_i32_e32 v99, 31, v98
	v_lshlrev_b64 v[98:99], 13, v[98:99]
	v_lshl_add_u64 v[98:99], v[138:139], 0, v[98:99]
	global_load_dwordx2 v[102:103], v[98:99], off
	s_mov_b32 s0, 0xf8100000
	v_or_b32_e32 v100, 0x90, v136
	v_add_co_u32_e32 v104, vcc, s0, v134
	v_ashrrev_i32_e32 v101, 31, v100
	s_nop 0
	v_addc_co_u32_e32 v105, vcc, -1, v135, vcc
	v_lshlrev_b64 v[100:101], 13, v[100:101]
	v_lshl_add_u64 v[100:101], v[138:139], 0, v[100:101]
	s_mov_b32 s0, 0xf8120000
	s_waitcnt vmcnt(0) lgkmcnt(0)
	v_lshlrev_b32_e32 v106, 16, v102
	v_and_b32_e32 v107, 0xffff0000, v102
	v_lshlrev_b32_e32 v102, 16, v103
	v_and_b32_e32 v103, 0xffff0000, v103
	v_pk_mul_f32 v[94:95], v[94:95], v[106:107]
	v_pk_mul_f32 v[96:97], v[96:97], v[102:103]
	global_store_dwordx4 v[104:105], v[94:97], off
	global_load_dwordx2 v[94:95], v[100:101], off
	s_waitcnt vmcnt(0) lgkmcnt(0)
; #define EPI_LOOP(...) _Pragma("unroll") for(int ai=0;ai<2;++ai) _Pragma("unroll") for(int bj=0;bj<2;++bj) \
;   _Pragma("unroll") for(int m=0;m<4;++m) _Pragma("unroll") for(int n=0;n<2;++n) { \
;     const int row=brow+ai*128+wr*64+m*16+fq*4; const int col=bcol+bj*128+wc*32+n*16+fr; \
;     f32x4& v=acc[ai][bj][m][n]; __VA_ARGS__ if (n == 1 && (m & 1)) __builtin_amdgcn_sched_barrier(0); }
; DEVI void run_phase(const int ph, const Params& P, char* shmc, const int wave_u) {
;     ...
;       GEMM_IDS
;       EPI_LOOP({ const u32x2 a = *reinterpret_cast<const u32x2*>(gates + (long)col * 4096 + br * 2048 + row);
;         st_f4(Mp + (long)sub * MS * 2048 + (long)(col - MP) * 2048 + row, v[0] * __uint_as_float(a[0] << 16), v[1] * __uint_as_float(a[0] & 0xffff0000u),
;               v[2] * __uint_as_float(a[1] << 16), v[3] * __uint_as_float(a[1] & 0xffff0000u)); })
	v_lshlrev_b32_e32 v102, 16, v94
	v_add_co_u32_e32 v96, vcc, s0, v134
	v_and_b32_e32 v103, 0xffff0000, v94
	v_lshlrev_b32_e32 v94, 16, v95
	v_and_b32_e32 v95, 0xffff0000, v95
	v_addc_co_u32_e32 v97, vcc, -1, v135, vcc
	v_pk_mul_f32 v[90:91], v[90:91], v[102:103]
	v_pk_mul_f32 v[92:93], v[92:93], v[94:95]
	global_store_dwordx4 v[96:97], v[90:93], off
	global_load_dwordx2 v[92:93], v[98:99], off offset:32
	s_mov_b32 s0, 0xf8100000
	s_mov_b32 s1, -1
	v_lshl_add_u64 v[90:91], v[134:135], 0, s[0:1]
	s_mov_b32 s0, 0xf8120000
	s_mov_b32 s1, -1
	s_waitcnt vmcnt(0) lgkmcnt(0)
	v_lshlrev_b32_e32 v94, 16, v92
	v_and_b32_e32 v95, 0xffff0000, v92
	v_lshlrev_b32_e32 v92, 16, v93
	v_and_b32_e32 v93, 0xffff0000, v93
	v_pk_mul_f32 v[86:87], v[86:87], v[94:95]
	v_pk_mul_f32 v[88:89], v[88:89], v[92:93]
	global_store_dwordx4 v[90:91], v[86:89], off offset:64
	global_load_dwordx2 v[88:89], v[100:101], off offset:32
	s_waitcnt vmcnt(0) lgkmcnt(0)
	v_lshlrev_b32_e32 v92, 16, v88
	v_and_b32_e32 v93, 0xffff0000, v88
	v_lshlrev_b32_e32 v88, 16, v89
	v_and_b32_e32 v89, 0xffff0000, v89
	v_lshl_add_u64 v[86:87], v[134:135], 0, s[0:1]
	v_pk_mul_f32 v[82:83], v[82:83], v[92:93]
	v_pk_mul_f32 v[84:85], v[84:85], v[88:89]
	global_store_dwordx4 v[86:87], v[82:85], off offset:64
	global_load_dwordx2 v[82:83], v[98:99], off offset:64
	s_waitcnt vmcnt(0) lgkmcnt(0)
	v_lshlrev_b32_e32 v84, 16, v82
	v_and_b32_e32 v85, 0xffff0000, v82
	v_lshlrev_b32_e32 v82, 16, v83
	v_and_b32_e32 v83, 0xffff0000, v83
	v_pk_mul_f32 v[78:79], v[78:79], v[84:85]
	v_pk_mul_f32 v[80:81], v[80:81], v[82:83]
	global_store_dwordx4 v[90:91], v[78:81], off offset:128
	global_load_dwordx2 v[78:79], v[100:101], off offset:64
	s_waitcnt vmcnt(0) lgkmcnt(0)
	v_lshlrev_b32_e32 v80, 16, v78
	v_and_b32_e32 v81, 0xffff0000, v78
	v_lshlrev_b32_e32 v78, 16, v79
	v_and_b32_e32 v79, 0xffff0000, v79
	v_pk_mul_f32 v[74:75], v[74:75], v[80:81]
	v_pk_mul_f32 v[76:77], v[76:77], v[78:79]
	global_store_dwordx4 v[86:87], v[74:77], off offset:128
	global_load_dwordx2 v[74:75], v[98:99], off offset:96
	s_waitcnt vmcnt(0) lgkmcnt(0)
	v_lshlrev_b32_e32 v76, 16, v74
	v_and_b32_e32 v77, 0xffff0000, v74
	v_lshlrev_b32_e32 v74, 16, v75
	v_and_b32_e32 v75, 0xffff0000, v75
	v_pk_mul_f32 v[70:71], v[70:71], v[76:77]
	v_pk_mul_f32 v[72:73], v[72:73], v[74:75]
	global_store_dwordx4 v[90:91], v[70:73], off offset:192
	global_load_dwordx2 v[70:71], v[100:101], off offset:96
	s_waitcnt vmcnt(0) lgkmcnt(0)
	v_lshlrev_b32_e32 v72, 16, v70
	v_and_b32_e32 v73, 0xffff0000, v70
	v_lshlrev_b32_e32 v70, 16, v71
	v_and_b32_e32 v71, 0xffff0000, v71
	v_pk_mul_f32 v[66:67], v[66:67], v[72:73]
	v_pk_mul_f32 v[68:69], v[68:69], v[70:71]
	global_store_dwordx4 v[86:87], v[66:69], off offset:192
	global_load_dwordx2 v[66:67], v[132:133], off offset:256
	s_waitcnt vmcnt(0) lgkmcnt(0)
	v_lshlrev_b32_e32 v68, 16, v66
	v_and_b32_e32 v69, 0xffff0000, v66
	v_lshlrev_b32_e32 v66, 16, v67
	v_and_b32_e32 v67, 0xffff0000, v67
	v_pk_mul_f32 v[62:63], v[62:63], v[68:69]
	v_pk_mul_f32 v[64:65], v[64:65], v[66:67]
	global_store_dwordx4 v[130:131], v[62:65], off offset:512
	global_load_dwordx2 v[62:63], v[126:127], off offset:256
	s_waitcnt vmcnt(0) lgkmcnt(0)
	v_lshlrev_b32_e32 v64, 16, v62
	v_and_b32_e32 v65, 0xffff0000, v62
	v_lshlrev_b32_e32 v62, 16, v63
	v_and_b32_e32 v63, 0xffff0000, v63
	v_pk_mul_f32 v[58:59], v[58:59], v[64:65]
	v_pk_mul_f32 v[60:61], v[60:61], v[62:63]
	global_store_dwordx4 v[128:129], v[58:61], off offset:512
	global_load_dwordx2 v[58:59], v[132:133], off offset:288
	s_waitcnt vmcnt(0) lgkmcnt(0)
	v_lshlrev_b32_e32 v60, 16, v58
	v_and_b32_e32 v61, 0xffff0000, v58
	v_lshlrev_b32_e32 v58, 16, v59
	v_and_b32_e32 v59, 0xffff0000, v59
	v_pk_mul_f32 v[54:55], v[54:55], v[60:61]
	v_pk_mul_f32 v[56:57], v[56:57], v[58:59]
	global_store_dwordx4 v[130:131], v[54:57], off offset:576
	global_load_dwordx2 v[54:55], v[126:127], off offset:288
	s_waitcnt vmcnt(0) lgkmcnt(0)
	v_lshlrev_b32_e32 v56, 16, v54
	v_and_b32_e32 v57, 0xffff0000, v54
	v_lshlrev_b32_e32 v54, 16, v55
	v_and_b32_e32 v55, 0xffff0000, v55
	v_pk_mul_f32 v[50:51], v[50:51], v[56:57]
	v_pk_mul_f32 v[52:53], v[52:53], v[54:55]
	global_store_dwordx4 v[128:129], v[50:53], off offset:576
	global_load_dwordx2 v[50:51], v[132:133], off offset:320
	s_waitcnt vmcnt(0) lgkmcnt(0)
; #define EPI_LOOP(...) _Pragma("unroll") for(int ai=0;ai<2;++ai) _Pragma("unroll") for(int bj=0;bj<2;++bj) \
;   _Pragma("unroll") for(int m=0;m<4;++m) _Pragma("unroll") for(int n=0;n<2;++n) { \
;     const int row=brow+ai*128+wr*64+m*16+fq*4; const int col=bcol+bj*128+wc*32+n*16+fr; \
;     f32x4& v=acc[ai][bj][m][n]; __VA_ARGS__ if (n == 1 && (m & 1)) __builtin_amdgcn_sched_barrier(0); }
; DEVI void run_phase(const int ph, const Params& P, char* shmc, const int wave_u) {
;     ...
;       GEMM_IDS
;       EPI_LOOP({ const u32x2 a = *reinterpret_cast<const u32x2*>(gates + (long)col * 4096 + br * 2048 + row);
;         st_f4(Mp + (long)sub * MS * 2048 + (long)(col - MP) * 2048 + row, v[0] * __uint_as_float(a[0] << 16), v[1] * __uint_as_float(a[0] & 0xffff0000u),
;               v[2] * __uint_as_float(a[1] << 16), v[3] * __uint_as_float(a[1] & 0xffff0000u)); })
	v_lshlrev_b32_e32 v52, 16, v50
	v_and_b32_e32 v53, 0xffff0000, v50
	v_lshlrev_b32_e32 v50, 16, v51
	v_and_b32_e32 v51, 0xffff0000, v51
	v_pk_mul_f32 v[46:47], v[46:47], v[52:53]
	v_pk_mul_f32 v[48:49], v[48:49], v[50:51]
	global_store_dwordx4 v[130:131], v[46:49], off offset:640
	global_load_dwordx2 v[46:47], v[126:127], off offset:320
	s_waitcnt vmcnt(0) lgkmcnt(0)
	v_lshlrev_b32_e32 v48, 16, v46
	v_and_b32_e32 v49, 0xffff0000, v46
	v_lshlrev_b32_e32 v46, 16, v47
	v_and_b32_e32 v47, 0xffff0000, v47
	v_pk_mul_f32 v[42:43], v[42:43], v[48:49]
	v_pk_mul_f32 v[44:45], v[44:45], v[46:47]
	global_store_dwordx4 v[128:129], v[42:45], off offset:640
	global_load_dwordx2 v[42:43], v[132:133], off offset:352
	s_waitcnt vmcnt(0) lgkmcnt(0)
	v_lshlrev_b32_e32 v44, 16, v42
	v_and_b32_e32 v45, 0xffff0000, v42
	v_lshlrev_b32_e32 v42, 16, v43
	v_and_b32_e32 v43, 0xffff0000, v43
	v_pk_mul_f32 v[38:39], v[38:39], v[44:45]
	v_pk_mul_f32 v[40:41], v[40:41], v[42:43]
	global_store_dwordx4 v[130:131], v[38:41], off offset:704
	global_load_dwordx2 v[38:39], v[126:127], off offset:352
	s_waitcnt vmcnt(0) lgkmcnt(0)
	v_lshlrev_b32_e32 v40, 16, v38
	v_and_b32_e32 v41, 0xffff0000, v38
	v_lshlrev_b32_e32 v38, 16, v39
	v_and_b32_e32 v39, 0xffff0000, v39
	v_pk_mul_f32 v[34:35], v[34:35], v[40:41]
	v_pk_mul_f32 v[36:37], v[36:37], v[38:39]
	global_store_dwordx4 v[128:129], v[34:37], off offset:704
	global_load_dwordx2 v[34:35], v[98:99], off offset:256
	s_waitcnt vmcnt(0) lgkmcnt(0)
	v_lshlrev_b32_e32 v36, 16, v34
	v_and_b32_e32 v37, 0xffff0000, v34
	v_lshlrev_b32_e32 v34, 16, v35
	v_and_b32_e32 v35, 0xffff0000, v35
	v_pk_mul_f32 v[28:29], v[28:29], v[36:37]
	v_pk_mul_f32 v[30:31], v[30:31], v[34:35]
	global_store_dwordx4 v[90:91], v[28:31], off offset:512
	global_load_dwordx2 v[28:29], v[100:101], off offset:256
	s_waitcnt vmcnt(0) lgkmcnt(0)
	v_lshlrev_b32_e32 v30, 16, v28
	v_and_b32_e32 v31, 0xffff0000, v28
	v_lshlrev_b32_e32 v28, 16, v29
	v_and_b32_e32 v29, 0xffff0000, v29
	v_pk_mul_f32 v[24:25], v[24:25], v[30:31]
	v_pk_mul_f32 v[26:27], v[26:27], v[28:29]
	global_store_dwordx4 v[86:87], v[24:27], off offset:512
	global_load_dwordx2 v[24:25], v[98:99], off offset:288
	s_waitcnt vmcnt(0) lgkmcnt(0)
	v_lshlrev_b32_e32 v26, 16, v24
	v_and_b32_e32 v27, 0xffff0000, v24
	v_lshlrev_b32_e32 v24, 16, v25
	v_and_b32_e32 v25, 0xffff0000, v25
	v_pk_mul_f32 v[20:21], v[20:21], v[26:27]
	v_pk_mul_f32 v[22:23], v[22:23], v[24:25]
	global_store_dwordx4 v[90:91], v[20:23], off offset:576
	global_load_dwordx2 v[20:21], v[100:101], off offset:288
	s_waitcnt vmcnt(0) lgkmcnt(0)
	v_lshlrev_b32_e32 v22, 16, v20
	v_and_b32_e32 v23, 0xffff0000, v20
	v_lshlrev_b32_e32 v20, 16, v21
	v_and_b32_e32 v21, 0xffff0000, v21
	v_pk_mul_f32 v[16:17], v[16:17], v[22:23]
	v_pk_mul_f32 v[18:19], v[18:19], v[20:21]
	global_store_dwordx4 v[86:87], v[16:19], off offset:576
	global_load_dwordx2 v[16:17], v[98:99], off offset:320
	s_waitcnt vmcnt(0) lgkmcnt(0)
	v_lshlrev_b32_e32 v18, 16, v16
	v_and_b32_e32 v19, 0xffff0000, v16
	v_lshlrev_b32_e32 v16, 16, v17
	v_and_b32_e32 v17, 0xffff0000, v17
	v_pk_mul_f32 v[12:13], v[12:13], v[18:19]
	v_pk_mul_f32 v[14:15], v[14:15], v[16:17]
	global_store_dwordx4 v[90:91], v[12:15], off offset:640
	global_load_dwordx2 v[12:13], v[100:101], off offset:320
	s_waitcnt vmcnt(0) lgkmcnt(0)
	v_lshlrev_b32_e32 v14, 16, v12
	v_and_b32_e32 v15, 0xffff0000, v12
	v_lshlrev_b32_e32 v12, 16, v13
	v_and_b32_e32 v13, 0xffff0000, v13
	v_pk_mul_f32 v[8:9], v[8:9], v[14:15]
	v_pk_mul_f32 v[10:11], v[10:11], v[12:13]
	global_store_dwordx4 v[86:87], v[8:11], off offset:640
	global_load_dwordx2 v[8:9], v[98:99], off offset:352
	s_waitcnt vmcnt(0) lgkmcnt(0)
	v_lshlrev_b32_e32 v10, 16, v8
	v_and_b32_e32 v11, 0xffff0000, v8
	v_lshlrev_b32_e32 v8, 16, v9
	v_and_b32_e32 v9, 0xffff0000, v9
	v_pk_mul_f32 v[4:5], v[4:5], v[10:11]
	v_pk_mul_f32 v[6:7], v[6:7], v[8:9]
	global_store_dwordx4 v[90:91], v[4:7], off offset:704
	global_load_dwordx2 v[4:5], v[100:101], off offset:352
	s_waitcnt vmcnt(0) lgkmcnt(0)
	v_lshlrev_b32_e32 v6, 16, v4
	v_and_b32_e32 v7, 0xffff0000, v4
	v_lshlrev_b32_e32 v4, 16, v5
	v_and_b32_e32 v5, 0xffff0000, v5
	v_pk_mul_f32 v[0:1], v[0:1], v[6:7]
	v_pk_mul_f32 v[2:3], v[2:3], v[4:5]
	global_store_dwordx4 v[86:87], v[0:3], off offset:704
	v_readlane_b32 s0, v254, 26
	s_add_i32 s69, s69, s0
	v_readlane_b32 s0, v253, 8
	s_add_i32 s68, s68, s0
	v_readlane_b32 s0, v253, 14
	s_add_i32 s39, s39, s0
	v_readlane_b32 s0, v253, 10
	s_add_i32 s38, s38, s0
	s_cmpk_gt_i32 s69, 0x7f
	v_readlane_b32 s1, v254, 27
	s_cbranch_scc1 .LBB0_203

; #define EPI_HALF(AI, ...) _Pragma("unroll") for(int bj=0;bj<2;++bj) _Pragma("unroll") for(int m=0;m<4;++m) _Pragma("unroll") for(int n=0;n<2;++n) { \
;     const int ai=(AI); const int row=brow+ai*128+wr*64+m*16+fq*4; const int col=bcol+bj*128+wc*32+n*16+fr; \
;     f32x4& v=acc[ai][bj][m][n]; __VA_ARGS__ }
; DEVI void run_phase(const int ph, const Params& P, char* shmc, const int wave_u) {
;     ...
;       GEMM_IDS
; #pragma unroll
;       for (int ah = 0; ah < 2; ++ah) {
;         u32x2 gb[2][4][2], tq[2][4][2];
;         EPI_HALF(ah, { (void)v; gb[bj][m][n] = *reinterpret_cast<const u32x2*>(gates + (long)col * 4096 + 2048 + row);
;           tq[bj][m][n] = *reinterpret_cast<const u32x2*>(tmp5 + (long)col * 2048 + row); })
;         EPI_HALF(ah, { const u32x2 b = gb[bj][m][n]; const u32x2 tw = tq[bj][m][n];
;           const f32x4 t0 = {__uint_as_float(tw[0] << 16), __uint_as_float(tw[0] & 0xffff0000u), __uint_as_float(tw[1] << 16), __uint_as_float(tw[1] & 0xffff0000u)};
;           st_bf4(merged + (long)col * 2048 + row, t0[0] + v[0] * __uint_as_float(b[0] << 16), t0[1] + v[1] * __uint_as_float(b[0] & 0xffff0000u),
;                  t0[2] + v[2] * __uint_as_float(b[1] << 16), t0[3] + v[3] * __uint_as_float(b[1] & 0xffff0000u)); })
;       }
.LBB0_213:
	s_or_b64 exec, exec, s[8:9]
	v_mbcnt_lo_u32_b32 v246, -1, 0
	v_mbcnt_hi_u32_b32 v246, -1, v246
	v_bfe_u32 v246, v246, 4, 1
	v_mul_u32_u24_e32 v246, 24, v246
	v_mov_b32_e32 v247, 0
	v_mbcnt_lo_u32_b32 v32, -1, 0
	v_mbcnt_hi_u32_b32 v32, -1, v32
	s_nop 0
	v_or_b32_e32 v130, s5, v32
	v_ashrrev_i32_e32 v132, 2, v130
	v_and_b32_e32 v132, 0xffffffc0, v132
	v_and_b32_e32 v131, 15, v32
	v_add_u32_e32 v132, s6, v132
	v_lshrrev_b32_e32 v32, 2, v32
	v_and_or_b32 v138, v32, 12, v132
	v_lshrrev_b32_e32 v32, 1, v130
	v_and_b32_e32 v32, 0x60, v32
	v_or3_b32 v130, v131, v32, s0
	v_ashrrev_i32_e32 v131, 31, v130
	v_readlane_b32 s6, v255, 13
	v_lshlrev_b64 v[132:133], 13, v[130:131]
	v_readlane_b32 s7, v255, 14
	s_mov_b64 s[0:1], 0x1000
	v_ashrrev_i32_e32 v139, 31, v138
	v_lshl_add_u64 v[132:133], s[6:7], 0, v[132:133]
	v_lshl_add_u64 v[140:141], v[132:133], 0, s[0:1]
	v_lshlrev_b64 v[178:179], 1, v[138:139]
	v_lshl_add_u64 v[154:155], s[84:85], 0, v[178:179]
	v_lshl_add_u64 v[132:133], v[140:141], 0, v[178:179]
	v_lshlrev_b64 v[136:137], 12, v[130:131]
	global_load_dwordx2 v[180:181], v[132:133], off
	v_lshl_add_u64 v[132:133], v[154:155], 0, v[136:137]
	global_load_dwordx2 v[182:183], v[132:133], off
	v_or_b32_e32 v132, 16, v130
	v_ashrrev_i32_e32 v133, 31, v132
	v_lshlrev_b64 v[134:135], 13, v[132:133]
	v_lshl_add_u64 v[134:135], s[6:7], 0, v[134:135]
	v_lshl_add_u64 v[142:143], v[134:135], 0, s[0:1]
	v_lshl_add_u64 v[134:135], v[142:143], 0, v[178:179]
	global_load_dwordx2 v[192:193], v[134:135], off
	v_lshlrev_b64 v[134:135], 12, v[132:133]
	v_lshl_add_u64 v[132:133], v[154:155], 0, v[134:135]
	global_load_dwordx2 v[194:195], v[132:133], off
	v_or_b32_e32 v132, 16, v138
	v_ashrrev_i32_e32 v133, 31, v132
	v_lshlrev_b64 v[156:157], 1, v[132:133]
	v_lshl_add_u64 v[132:133], v[140:141], 0, v[156:157]
	global_load_dwordx2 v[196:197], v[132:133], off
	v_lshl_add_u64 v[132:133], s[84:85], 0, v[136:137]
	v_lshl_add_u64 v[144:145], v[132:133], 0, v[156:157]
	global_load_dwordx2 v[198:199], v[144:145], off
	v_lshl_add_u64 v[144:145], v[142:143], 0, v[156:157]
	global_load_dwordx2 v[200:201], v[144:145], off
	v_lshl_add_u64 v[144:145], s[84:85], 0, v[134:135]
	v_lshl_add_u64 v[148:149], v[144:145], 0, v[156:157]
	global_load_dwordx2 v[202:203], v[148:149], off
	v_or_b32_e32 v148, 32, v138
	v_ashrrev_i32_e32 v149, 31, v148
	v_lshlrev_b64 v[152:153], 1, v[148:149]
	v_lshl_add_u64 v[148:149], v[140:141], 0, v[152:153]
	global_load_dwordx2 v[204:205], v[148:149], off
	v_lshl_add_u64 v[148:149], v[132:133], 0, v[152:153]
	global_load_dwordx2 v[206:207], v[148:149], off
	v_lshl_add_u64 v[148:149], v[142:143], 0, v[152:153]
	global_load_dwordx2 v[208:209], v[148:149], off
	v_lshl_add_u64 v[148:149], v[144:145], 0, v[152:153]
	global_load_dwordx2 v[210:211], v[148:149], off
	v_or_b32_e32 v148, 48, v138
	v_ashrrev_i32_e32 v149, 31, v148
	v_lshlrev_b64 v[150:151], 1, v[148:149]
	v_lshl_add_u64 v[132:133], v[132:133], 0, v[150:151]
	v_lshl_add_u64 v[148:149], v[140:141], 0, v[150:151]
	global_load_dwordx2 v[214:215], v[132:133], off
	v_lshl_add_u64 v[132:133], v[142:143], 0, v[150:151]
	global_load_dwordx2 v[212:213], v[148:149], off
	global_load_dwordx2 v[216:217], v[132:133], off
	v_lshl_add_u64 v[132:133], v[144:145], 0, v[150:151]
	global_load_dwordx2 v[218:219], v[132:133], off
	v_or_b32_e32 v132, 0x80, v130
	v_ashrrev_i32_e32 v133, 31, v132
	v_lshlrev_b64 v[144:145], 13, v[132:133]
	v_lshl_add_u64 v[144:145], s[6:7], 0, v[144:145]
	v_lshl_add_u64 v[144:145], v[144:145], 0, s[0:1]
	v_lshl_add_u64 v[148:149], v[144:145], 0, v[178:179]
	v_lshlrev_b64 v[132:133], 12, v[132:133]
	v_or_b32_e32 v130, 0x90, v130
	global_load_dwordx2 v[220:221], v[148:149], off
	v_lshl_add_u64 v[148:149], v[154:155], 0, v[132:133]
	v_ashrrev_i32_e32 v131, 31, v130
	global_load_dwordx2 v[222:223], v[148:149], off
	v_lshlrev_b64 v[148:149], 13, v[130:131]
	v_lshl_add_u64 v[148:149], s[6:7], 0, v[148:149]
	v_lshl_add_u64 v[148:149], v[148:149], 0, s[0:1]
	v_lshlrev_b64 v[130:131], 12, v[130:131]
	v_lshl_add_u64 v[158:159], v[148:149], 0, v[178:179]
	v_lshl_add_u64 v[154:155], v[154:155], 0, v[130:131]
	global_load_dwordx2 v[224:225], v[158:159], off
	global_load_dwordx2 v[226:227], v[154:155], off
	v_lshl_add_u64 v[154:155], v[144:145], 0, v[156:157]
	global_load_dwordx2 v[176:177], v[154:155], off
	v_lshl_add_u64 v[154:155], s[84:85], 0, v[132:133]
	v_lshl_add_u64 v[158:159], v[154:155], 0, v[156:157]
	global_load_dwordx2 v[228:229], v[158:159], off
	v_lshl_add_u64 v[158:159], v[148:149], 0, v[156:157]
	global_load_dwordx2 v[172:173], v[158:159], off
	v_lshl_add_u64 v[158:159], s[84:85], 0, v[130:131]
	v_lshl_add_u64 v[160:161], v[158:159], 0, v[156:157]
	global_load_dwordx2 v[174:175], v[160:161], off
	v_lshl_add_u64 v[160:161], v[144:145], 0, v[152:153]
	global_load_dwordx2 v[168:169], v[160:161], off
	v_lshl_add_u64 v[160:161], v[154:155], 0, v[152:153]
	global_load_dwordx2 v[170:171], v[160:161], off
	v_lshl_add_u64 v[160:161], v[148:149], 0, v[152:153]
	global_load_dwordx2 v[164:165], v[160:161], off
	v_lshl_add_u64 v[160:161], v[158:159], 0, v[152:153]
	global_load_dwordx2 v[166:167], v[160:161], off
	v_lshl_add_u64 v[154:155], v[154:155], 0, v[150:151]
	v_lshl_add_u64 v[158:159], v[158:159], 0, v[150:151]
	global_load_dwordx2 v[162:163], v[154:155], off
	s_waitcnt vmcnt(0) lgkmcnt(0)
; #define EPI_HALF(AI, ...) _Pragma("unroll") for(int bj=0;bj<2;++bj) _Pragma("unroll") for(int m=0;m<4;++m) _Pragma("unroll") for(int n=0;n<2;++n) { \
;     const int ai=(AI); const int row=brow+ai*128+wr*64+m*16+fq*4; const int col=bcol+bj*128+wc*32+n*16+fr; \
;     f32x4& v=acc[ai][bj][m][n]; __VA_ARGS__ }
; DEVI void run_phase(const int ph, const Params& P, char* shmc, const int wave_u) {
;     ...
;       GEMM_IDS
; #pragma unroll
;       for (int ah = 0; ah < 2; ++ah) {
;         u32x2 gb[2][4][2], tq[2][4][2];
;         EPI_HALF(ah, { (void)v; gb[bj][m][n] = *reinterpret_cast<const u32x2*>(gates + (long)col * 4096 + 2048 + row);
;           tq[bj][m][n] = *reinterpret_cast<const u32x2*>(tmp5 + (long)col * 2048 + row); })
;         EPI_HALF(ah, { const u32x2 b = gb[bj][m][n]; const u32x2 tw = tq[bj][m][n];
;           const f32x4 t0 = {__uint_as_float(tw[0] << 16), __uint_as_float(tw[0] & 0xffff0000u), __uint_as_float(tw[1] << 16), __uint_as_float(tw[1] & 0xffff0000u)};
;           st_bf4(merged + (long)col * 2048 + row, t0[0] + v[0] * __uint_as_float(b[0] << 16), t0[1] + v[1] * __uint_as_float(b[0] & 0xffff0000u),
;                  t0[2] + v[2] * __uint_as_float(b[1] << 16), t0[3] + v[3] * __uint_as_float(b[1] & 0xffff0000u)); })
;       }
	v_lshlrev_b32_e32 v32, 16, v182
	global_load_dwordx2 v[158:159], v[158:159], off
	v_lshl_add_u64 v[160:161], v[144:145], 0, v[150:151]
	global_load_dwordx2 v[160:161], v[160:161], off
	v_lshl_add_u64 v[154:155], v[148:149], 0, v[150:151]
	global_load_dwordx2 v[154:155], v[154:155], off
	v_lshlrev_b32_e32 v232, 16, v180
	v_and_b32_e32 v139, 0xffff0000, v182
	v_fmac_f32_e32 v32, v126, v232
	v_and_b32_e32 v126, 0xffff0000, v180
	v_lshlrev_b32_e32 v230, 16, v183
	v_fmac_f32_e32 v139, v127, v126
	v_lshlrev_b32_e32 v126, 16, v181
	v_and_b32_e32 v231, 0xffff0000, v183
	v_fmac_f32_e32 v230, v128, v126
	v_and_b32_e32 v126, 0xffff0000, v181
	v_fmac_f32_e32 v231, v129, v126
	v_cvt_pk_bf16_f32 v126, v32, v139
	v_lshlrev_b32_e32 v32, 16, v194
	v_lshlrev_b32_e32 v180, 16, v192
	v_and_b32_e32 v128, 0xffff0000, v194
	v_fmac_f32_e32 v32, v122, v180
	v_and_b32_e32 v122, 0xffff0000, v192
	v_lshl_add_u64 v[178:179], s[82:83], 0, v[178:179]
	v_lshlrev_b32_e32 v129, 16, v195
	v_fmac_f32_e32 v128, v123, v122
	v_lshlrev_b32_e32 v122, 16, v193
	v_lshl_add_u64 v[182:183], v[178:179], 0, v[136:137]
	v_cvt_pk_bf16_f32 v127, v230, v231
	v_and_b32_e32 v139, 0xffff0000, v195
	v_fmac_f32_e32 v129, v124, v122
	v_and_b32_e32 v122, 0xffff0000, v193
	v_mov_b32_e32 v236, v126
	v_mov_b32_e32 v237, v127
	v_lshl_add_u64 v[234:235], v[182:183], 0, v[246:247]
	v_lshl_add_u64 v[126:127], v[178:179], 0, v[134:135]
	v_fmac_f32_e32 v139, v125, v122
	v_cvt_pk_bf16_f32 v122, v32, v128
	v_cvt_pk_bf16_f32 v123, v129, v139
	v_lshlrev_b32_e32 v32, 16, v198
	v_lshlrev_b32_e32 v129, 16, v196
	v_mov_b32_e32 v240, v122
	v_mov_b32_e32 v241, v123
	v_lshl_add_u64 v[244:245], v[126:127], 0, v[246:247]
	v_and_b32_e32 v126, 0xffff0000, v198
	v_fmac_f32_e32 v32, v118, v129
	v_and_b32_e32 v118, 0xffff0000, v196
	v_lshlrev_b32_e32 v127, 16, v199
	v_fmac_f32_e32 v126, v119, v118
	v_lshlrev_b32_e32 v118, 16, v197
	v_and_b32_e32 v128, 0xffff0000, v199
	v_lshl_add_u64 v[122:123], s[82:83], 0, v[136:137]
	v_fmac_f32_e32 v127, v120, v118
	v_and_b32_e32 v118, 0xffff0000, v197
	v_lshl_add_u64 v[124:125], v[122:123], 0, v[156:157]
	v_fmac_f32_e32 v128, v121, v118
	v_cvt_pk_bf16_f32 v118, v32, v126
	v_cvt_pk_bf16_f32 v119, v127, v128
	v_lshlrev_b32_e32 v32, 16, v202
	v_lshlrev_b32_e32 v127, 16, v200
	v_mov_b32_e32 v238, v118
	v_mov_b32_e32 v239, v119
	s_nop 1
	v_permlane16_swap_b32_e32 v236, v238
	v_permlane16_swap_b32_e32 v237, v239
	global_store_dwordx4 v[234:235], v[236:239], off
	v_and_b32_e32 v124, 0xffff0000, v202
	v_fmac_f32_e32 v32, v114, v127
	v_and_b32_e32 v114, 0xffff0000, v200
	v_lshlrev_b32_e32 v125, 16, v203
	v_lshl_add_u64 v[118:119], s[82:83], 0, v[134:135]
	v_fmac_f32_e32 v124, v115, v114
	v_lshlrev_b32_e32 v114, 16, v201
	v_and_b32_e32 v126, 0xffff0000, v203
	v_lshl_add_u64 v[120:121], v[118:119], 0, v[156:157]
	v_fmac_f32_e32 v125, v116, v114
	v_and_b32_e32 v114, 0xffff0000, v201
	v_fmac_f32_e32 v126, v117, v114
	v_cvt_pk_bf16_f32 v114, v32, v124
	v_cvt_pk_bf16_f32 v115, v125, v126
	v_mov_b32_e32 v242, v114
	v_mov_b32_e32 v243, v115
	s_nop 1
	v_permlane16_swap_b32_e32 v240, v242
	v_permlane16_swap_b32_e32 v241, v243
	global_store_dwordx4 v[244:245], v[240:243], off
	v_lshlrev_b32_e32 v32, 16, v206
	v_lshlrev_b32_e32 v121, 16, v204
	v_and_b32_e32 v116, 0xffff0000, v206
	v_fmac_f32_e32 v32, v110, v121
	v_and_b32_e32 v110, 0xffff0000, v204
	v_lshlrev_b32_e32 v117, 16, v207
	v_fmac_f32_e32 v116, v111, v110
	v_lshlrev_b32_e32 v110, 16, v205
	v_and_b32_e32 v120, 0xffff0000, v207
	v_lshl_add_u64 v[114:115], v[122:123], 0, v[152:153]
	v_fmac_f32_e32 v117, v112, v110
	v_and_b32_e32 v110, 0xffff0000, v205
	v_fmac_f32_e32 v120, v113, v110
	v_cvt_pk_bf16_f32 v110, v32, v116
	v_cvt_pk_bf16_f32 v111, v117, v120
	v_mov_b32_e32 v236, v110
	v_mov_b32_e32 v237, v111
	v_lshl_add_u64 v[234:235], v[114:115], 0, v[246:247]
	v_lshlrev_b32_e32 v32, 16, v210
	v_lshlrev_b32_e32 v115, 16, v208
	v_and_b32_e32 v112, 0xffff0000, v210
	v_fmac_f32_e32 v32, v106, v115
	v_and_b32_e32 v106, 0xffff0000, v208
	v_lshlrev_b32_e32 v113, 16, v211
	v_fmac_f32_e32 v112, v107, v106
	v_lshlrev_b32_e32 v106, 16, v209
	v_and_b32_e32 v114, 0xffff0000, v211
	v_lshl_add_u64 v[110:111], v[118:119], 0, v[152:153]
	v_fmac_f32_e32 v113, v108, v106
	v_and_b32_e32 v106, 0xffff0000, v209
	v_fmac_f32_e32 v114, v109, v106
	v_cvt_pk_bf16_f32 v106, v32, v112
	v_cvt_pk_bf16_f32 v107, v113, v114
	v_mov_b32_e32 v240, v106
	v_mov_b32_e32 v241, v107
	v_lshl_add_u64 v[244:245], v[110:111], 0, v[246:247]
	v_lshlrev_b32_e32 v32, 16, v214
	v_lshlrev_b32_e32 v111, 16, v212
	v_and_b32_e32 v108, 0xffff0000, v214
	v_fmac_f32_e32 v32, v102, v111
	v_and_b32_e32 v102, 0xffff0000, v212
	v_lshlrev_b32_e32 v109, 16, v215
	v_fmac_f32_e32 v108, v103, v102
	v_lshlrev_b32_e32 v102, 16, v213
	v_and_b32_e32 v110, 0xffff0000, v215
	v_lshl_add_u64 v[106:107], v[122:123], 0, v[150:151]
	v_fmac_f32_e32 v109, v104, v102
	v_and_b32_e32 v102, 0xffff0000, v213
	v_fmac_f32_e32 v110, v105, v102
	v_cvt_pk_bf16_f32 v102, v32, v108
	v_cvt_pk_bf16_f32 v103, v109, v110
	v_mov_b32_e32 v238, v102
	v_mov_b32_e32 v239, v103
	s_nop 1
	v_permlane16_swap_b32_e32 v236, v238
	v_permlane16_swap_b32_e32 v237, v239
	global_store_dwordx4 v[234:235], v[236:239], off
	v_lshlrev_b32_e32 v32, 16, v218
	v_lshlrev_b32_e32 v107, 16, v216
	v_and_b32_e32 v104, 0xffff0000, v218
	v_fmac_f32_e32 v32, v98, v107
	v_and_b32_e32 v98, 0xffff0000, v216
	v_lshlrev_b32_e32 v105, 16, v219
	v_fmac_f32_e32 v104, v99, v98
	v_lshlrev_b32_e32 v98, 16, v217
	v_and_b32_e32 v106, 0xffff0000, v219
	v_lshl_add_u64 v[102:103], v[118:119], 0, v[150:151]
	v_fmac_f32_e32 v105, v100, v98
	v_and_b32_e32 v98, 0xffff0000, v217
; #define EPI_HALF(AI, ...) _Pragma("unroll") for(int bj=0;bj<2;++bj) _Pragma("unroll") for(int m=0;m<4;++m) _Pragma("unroll") for(int n=0;n<2;++n) { \
;     const int ai=(AI); const int row=brow+ai*128+wr*64+m*16+fq*4; const int col=bcol+bj*128+wc*32+n*16+fr; \
;     f32x4& v=acc[ai][bj][m][n]; __VA_ARGS__ }
; DEVI void run_phase(const int ph, const Params& P, char* shmc, const int wave_u) {
;     ...
;       GEMM_IDS
; #pragma unroll
;       for (int ah = 0; ah < 2; ++ah) {
;         u32x2 gb[2][4][2], tq[2][4][2];
;         EPI_HALF(ah, { (void)v; gb[bj][m][n] = *reinterpret_cast<const u32x2*>(gates + (long)col * 4096 + 2048 + row);
;           tq[bj][m][n] = *reinterpret_cast<const u32x2*>(tmp5 + (long)col * 2048 + row); })
;         EPI_HALF(ah, { const u32x2 b = gb[bj][m][n]; const u32x2 tw = tq[bj][m][n];
;           const f32x4 t0 = {__uint_as_float(tw[0] << 16), __uint_as_float(tw[0] & 0xffff0000u), __uint_as_float(tw[1] << 16), __uint_as_float(tw[1] & 0xffff0000u)};
;           st_bf4(merged + (long)col * 2048 + row, t0[0] + v[0] * __uint_as_float(b[0] << 16), t0[1] + v[1] * __uint_as_float(b[0] & 0xffff0000u),
;                  t0[2] + v[2] * __uint_as_float(b[1] << 16), t0[3] + v[3] * __uint_as_float(b[1] & 0xffff0000u)); })
;       }
	v_fmac_f32_e32 v106, v101, v98
	v_cvt_pk_bf16_f32 v98, v32, v104
	v_cvt_pk_bf16_f32 v99, v105, v106
	v_mov_b32_e32 v242, v98
	v_mov_b32_e32 v243, v99
	s_nop 1
	v_permlane16_swap_b32_e32 v240, v242
	v_permlane16_swap_b32_e32 v241, v243
	global_store_dwordx4 v[244:245], v[240:243], off
	v_lshlrev_b32_e32 v32, 16, v222
	v_lshlrev_b32_e32 v103, 16, v220
	v_and_b32_e32 v100, 0xffff0000, v222
	v_fmac_f32_e32 v32, v94, v103
	v_and_b32_e32 v94, 0xffff0000, v220
	v_lshlrev_b32_e32 v101, 16, v223
	v_fmac_f32_e32 v100, v95, v94
	v_lshlrev_b32_e32 v94, 16, v221
	v_and_b32_e32 v102, 0xffff0000, v223
	v_lshl_add_u64 v[98:99], v[178:179], 0, v[132:133]
	v_fmac_f32_e32 v101, v96, v94
	v_and_b32_e32 v94, 0xffff0000, v221
	v_fmac_f32_e32 v102, v97, v94
	v_cvt_pk_bf16_f32 v94, v32, v100
	v_cvt_pk_bf16_f32 v95, v101, v102
	v_mov_b32_e32 v236, v94
	v_mov_b32_e32 v237, v95
	v_lshl_add_u64 v[234:235], v[98:99], 0, v[246:247]
	v_lshlrev_b32_e32 v32, 16, v226
	v_lshlrev_b32_e32 v99, 16, v224
	v_and_b32_e32 v96, 0xffff0000, v226
	v_fmac_f32_e32 v32, v90, v99
	v_and_b32_e32 v90, 0xffff0000, v224
	v_lshlrev_b32_e32 v97, 16, v227
	v_fmac_f32_e32 v96, v91, v90
	v_lshlrev_b32_e32 v90, 16, v225
	v_and_b32_e32 v98, 0xffff0000, v227
	v_fmac_f32_e32 v97, v92, v90
	v_and_b32_e32 v90, 0xffff0000, v225
	v_lshl_add_u64 v[94:95], v[178:179], 0, v[130:131]
	v_fmac_f32_e32 v98, v93, v90
	v_cvt_pk_bf16_f32 v90, v32, v96
	v_cvt_pk_bf16_f32 v91, v97, v98
	v_lshlrev_b32_e32 v32, 16, v228
	v_lshlrev_b32_e32 v97, 16, v176
	v_mov_b32_e32 v240, v90
	v_mov_b32_e32 v241, v91
	v_lshl_add_u64 v[244:245], v[94:95], 0, v[246:247]
	v_and_b32_e32 v94, 0xffff0000, v228
	v_fmac_f32_e32 v32, v86, v97
	v_and_b32_e32 v86, 0xffff0000, v176
	v_lshlrev_b32_e32 v95, 16, v229
	v_fmac_f32_e32 v94, v87, v86
	v_lshlrev_b32_e32 v86, 16, v177
	v_and_b32_e32 v96, 0xffff0000, v229
	v_lshl_add_u64 v[90:91], s[82:83], 0, v[132:133]
	v_fmac_f32_e32 v95, v88, v86
	v_and_b32_e32 v86, 0xffff0000, v177
	v_lshl_add_u64 v[92:93], v[90:91], 0, v[156:157]
	v_fmac_f32_e32 v96, v89, v86
	v_cvt_pk_bf16_f32 v86, v32, v94
	v_cvt_pk_bf16_f32 v87, v95, v96
	v_lshlrev_b32_e32 v32, 16, v174
	v_lshlrev_b32_e32 v95, 16, v172
	v_mov_b32_e32 v238, v86
	v_mov_b32_e32 v239, v87
	s_nop 1
	v_permlane16_swap_b32_e32 v236, v238
	v_permlane16_swap_b32_e32 v237, v239
	global_store_dwordx4 v[234:235], v[236:239], off
	v_and_b32_e32 v92, 0xffff0000, v174
	v_fmac_f32_e32 v32, v82, v95
	v_and_b32_e32 v82, 0xffff0000, v172
	v_lshlrev_b32_e32 v93, 16, v175
	v_lshl_add_u64 v[86:87], s[82:83], 0, v[130:131]
	v_fmac_f32_e32 v92, v83, v82
	v_lshlrev_b32_e32 v82, 16, v173
	v_and_b32_e32 v94, 0xffff0000, v175
	v_lshl_add_u64 v[88:89], v[86:87], 0, v[156:157]
	v_fmac_f32_e32 v93, v84, v82
	v_and_b32_e32 v82, 0xffff0000, v173
	v_fmac_f32_e32 v94, v85, v82
	v_cvt_pk_bf16_f32 v82, v32, v92
	v_cvt_pk_bf16_f32 v83, v93, v94
	v_mov_b32_e32 v242, v82
	v_mov_b32_e32 v243, v83
	s_nop 1
	v_permlane16_swap_b32_e32 v240, v242
	v_permlane16_swap_b32_e32 v241, v243
	global_store_dwordx4 v[244:245], v[240:243], off
	v_lshlrev_b32_e32 v32, 16, v170
	v_lshlrev_b32_e32 v89, 16, v168
	v_and_b32_e32 v84, 0xffff0000, v170
	v_fmac_f32_e32 v32, v78, v89
	v_and_b32_e32 v78, 0xffff0000, v168
	v_lshlrev_b32_e32 v85, 16, v171
	v_fmac_f32_e32 v84, v79, v78
	v_lshlrev_b32_e32 v78, 16, v169
	v_and_b32_e32 v88, 0xffff0000, v171
	v_lshl_add_u64 v[82:83], v[90:91], 0, v[152:153]
	v_fmac_f32_e32 v85, v80, v78
	v_and_b32_e32 v78, 0xffff0000, v169
	v_fmac_f32_e32 v88, v81, v78
	v_cvt_pk_bf16_f32 v78, v32, v84
	v_cvt_pk_bf16_f32 v79, v85, v88
	v_mov_b32_e32 v236, v78
	v_mov_b32_e32 v237, v79
	v_lshl_add_u64 v[234:235], v[82:83], 0, v[246:247]
	v_lshlrev_b32_e32 v32, 16, v166
	v_lshlrev_b32_e32 v83, 16, v164
	v_and_b32_e32 v80, 0xffff0000, v166
	v_fmac_f32_e32 v32, v74, v83
	v_and_b32_e32 v74, 0xffff0000, v164
	v_lshlrev_b32_e32 v81, 16, v167
	v_fmac_f32_e32 v80, v75, v74
	v_lshlrev_b32_e32 v74, 16, v165
	v_and_b32_e32 v82, 0xffff0000, v167
	v_lshl_add_u64 v[78:79], v[86:87], 0, v[152:153]
	v_fmac_f32_e32 v81, v76, v74
	v_and_b32_e32 v74, 0xffff0000, v165
	v_fmac_f32_e32 v82, v77, v74
	v_cvt_pk_bf16_f32 v74, v32, v80
	v_cvt_pk_bf16_f32 v75, v81, v82
	v_mov_b32_e32 v240, v74
	v_mov_b32_e32 v241, v75
	v_lshl_add_u64 v[244:245], v[78:79], 0, v[246:247]
	v_lshlrev_b32_e32 v32, 16, v162
	s_waitcnt vmcnt(0) lgkmcnt(0)
; #define EPI_HALF(AI, ...) _Pragma("unroll") for(int bj=0;bj<2;++bj) _Pragma("unroll") for(int m=0;m<4;++m) _Pragma("unroll") for(int n=0;n<2;++n) { \
;     const int ai=(AI); const int row=brow+ai*128+wr*64+m*16+fq*4; const int col=bcol+bj*128+wc*32+n*16+fr; \
;     f32x4& v=acc[ai][bj][m][n]; __VA_ARGS__ }
; DEVI void run_phase(const int ph, const Params& P, char* shmc, const int wave_u) {
;     ...
;       GEMM_IDS
; #pragma unroll
;       for (int ah = 0; ah < 2; ++ah) {
;         u32x2 gb[2][4][2], tq[2][4][2];
;         EPI_HALF(ah, { (void)v; gb[bj][m][n] = *reinterpret_cast<const u32x2*>(gates + (long)col * 4096 + 2048 + row);
;           tq[bj][m][n] = *reinterpret_cast<const u32x2*>(tmp5 + (long)col * 2048 + row); })
;         EPI_HALF(ah, { const u32x2 b = gb[bj][m][n]; const u32x2 tw = tq[bj][m][n];
;           const f32x4 t0 = {__uint_as_float(tw[0] << 16), __uint_as_float(tw[0] & 0xffff0000u), __uint_as_float(tw[1] << 16), __uint_as_float(tw[1] & 0xffff0000u)};
;           st_bf4(merged + (long)col * 2048 + row, t0[0] + v[0] * __uint_as_float(b[0] << 16), t0[1] + v[1] * __uint_as_float(b[0] & 0xffff0000u),
;                  t0[2] + v[2] * __uint_as_float(b[1] << 16), t0[3] + v[3] * __uint_as_float(b[1] & 0xffff0000u)); })
;       }
	v_lshlrev_b32_e32 v79, 16, v160
	v_and_b32_e32 v76, 0xffff0000, v162
	v_fmac_f32_e32 v32, v70, v79
	v_and_b32_e32 v70, 0xffff0000, v160
	v_lshlrev_b32_e32 v77, 16, v163
	v_fmac_f32_e32 v76, v71, v70
	v_lshlrev_b32_e32 v70, 16, v161
	v_and_b32_e32 v78, 0xffff0000, v163
	v_lshl_add_u64 v[74:75], v[90:91], 0, v[150:151]
	v_fmac_f32_e32 v77, v72, v70
	v_and_b32_e32 v70, 0xffff0000, v161
	v_fmac_f32_e32 v78, v73, v70
	v_cvt_pk_bf16_f32 v70, v32, v76
	v_cvt_pk_bf16_f32 v71, v77, v78
	v_mov_b32_e32 v238, v70
	v_mov_b32_e32 v239, v71
	s_nop 1
	v_permlane16_swap_b32_e32 v236, v238
	v_permlane16_swap_b32_e32 v237, v239
	global_store_dwordx4 v[234:235], v[236:239], off
	v_lshlrev_b32_e32 v32, 16, v158
	v_lshlrev_b32_e32 v75, 16, v154
	v_and_b32_e32 v72, 0xffff0000, v158
	v_fmac_f32_e32 v32, v66, v75
	v_and_b32_e32 v66, 0xffff0000, v154
	v_lshlrev_b32_e32 v73, 16, v159
	v_fmac_f32_e32 v72, v67, v66
	v_lshlrev_b32_e32 v66, 16, v155
	v_and_b32_e32 v74, 0xffff0000, v159
	v_fmac_f32_e32 v73, v68, v66
	v_and_b32_e32 v66, 0xffff0000, v155
	v_lshl_add_u64 v[70:71], v[86:87], 0, v[150:151]
	v_fmac_f32_e32 v74, v69, v66
	v_cvt_pk_bf16_f32 v66, v32, v72
	v_cvt_pk_bf16_f32 v67, v73, v74
	v_mov_b32_e32 v242, v66
	v_mov_b32_e32 v243, v67
	s_nop 1
	v_permlane16_swap_b32_e32 v240, v242
	v_permlane16_swap_b32_e32 v241, v243
	global_store_dwordx4 v[244:245], v[240:243], off
	v_add_u32_e32 v66, 0x80, v138
	v_ashrrev_i32_e32 v67, 31, v66
	v_lshlrev_b64 v[88:89], 1, v[66:67]
	v_lshl_add_u64 v[66:67], s[84:85], 0, v[88:89]
	v_lshl_add_u64 v[68:69], v[66:67], 0, v[136:137]
	global_load_dwordx2 v[90:91], v[68:69], off
	v_lshl_add_u64 v[68:69], v[140:141], 0, v[88:89]
	global_load_dwordx2 v[92:93], v[68:69], off
	v_lshl_add_u64 v[68:69], v[142:143], 0, v[88:89]
	global_load_dwordx2 v[94:95], v[68:69], off
	v_lshl_add_u64 v[68:69], v[66:67], 0, v[134:135]
	global_load_dwordx2 v[96:97], v[68:69], off
	v_add_u32_e32 v68, 0x90, v138
	v_ashrrev_i32_e32 v69, 31, v68
	v_lshlrev_b64 v[98:99], 1, v[68:69]
	v_lshl_add_u64 v[68:69], s[84:85], 0, v[98:99]
	v_lshl_add_u64 v[70:71], v[140:141], 0, v[98:99]
	global_load_dwordx2 v[100:101], v[70:71], off
	v_lshl_add_u64 v[70:71], v[68:69], 0, v[136:137]
	global_load_dwordx2 v[102:103], v[70:71], off
	v_lshl_add_u64 v[70:71], v[142:143], 0, v[98:99]
	global_load_dwordx2 v[104:105], v[70:71], off
	v_lshl_add_u64 v[70:71], v[68:69], 0, v[134:135]
	global_load_dwordx2 v[106:107], v[70:71], off
	v_add_u32_e32 v70, 0xa0, v138
	v_ashrrev_i32_e32 v71, 31, v70
	v_lshlrev_b64 v[108:109], 1, v[70:71]
	v_lshl_add_u64 v[70:71], s[84:85], 0, v[108:109]
	v_lshl_add_u64 v[72:73], v[140:141], 0, v[108:109]
	global_load_dwordx2 v[110:111], v[72:73], off
	v_lshl_add_u64 v[72:73], v[70:71], 0, v[136:137]
	global_load_dwordx2 v[112:113], v[72:73], off
	v_lshl_add_u64 v[72:73], v[142:143], 0, v[108:109]
	global_load_dwordx2 v[114:115], v[72:73], off
	v_lshl_add_u64 v[72:73], v[70:71], 0, v[134:135]
	global_load_dwordx2 v[116:117], v[72:73], off
	v_add_u32_e32 v72, 0xb0, v138
	v_ashrrev_i32_e32 v73, 31, v72
	v_lshlrev_b64 v[118:119], 1, v[72:73]
	v_lshl_add_u64 v[120:121], s[84:85], 0, v[118:119]
	v_lshl_add_u64 v[72:73], v[140:141], 0, v[118:119]
	global_load_dwordx2 v[122:123], v[72:73], off
	v_lshl_add_u64 v[72:73], v[120:121], 0, v[136:137]
	global_load_dwordx2 v[124:125], v[72:73], off
	v_lshl_add_u64 v[72:73], v[142:143], 0, v[118:119]
	global_load_dwordx2 v[126:127], v[72:73], off
	v_lshl_add_u64 v[72:73], v[120:121], 0, v[134:135]
	global_load_dwordx2 v[128:129], v[72:73], off
	v_lshl_add_u64 v[72:73], v[144:145], 0, v[88:89]
	global_load_dwordx2 v[138:139], v[72:73], off
	v_lshl_add_u64 v[72:73], v[66:67], 0, v[132:133]
	global_load_dwordx2 v[140:141], v[72:73], off
	v_lshl_add_u64 v[66:67], v[66:67], 0, v[130:131]
	global_load_dwordx2 v[150:151], v[66:67], off
	v_lshl_add_u64 v[72:73], v[148:149], 0, v[88:89]
	global_load_dwordx2 v[142:143], v[72:73], off
	v_lshl_add_u64 v[66:67], v[144:145], 0, v[98:99]
	global_load_dwordx2 v[86:87], v[66:67], off
	v_lshl_add_u64 v[66:67], v[68:69], 0, v[132:133]
	global_load_dwordx2 v[152:153], v[66:67], off
	v_lshl_add_u64 v[66:67], v[148:149], 0, v[98:99]
	global_load_dwordx2 v[82:83], v[66:67], off
	v_lshl_add_u64 v[66:67], v[68:69], 0, v[130:131]
	global_load_dwordx2 v[84:85], v[66:67], off
	v_lshl_add_u64 v[68:69], v[120:121], 0, v[130:131]
	global_load_dwordx2 v[68:69], v[68:69], off
	v_lshl_add_u64 v[66:67], v[144:145], 0, v[108:109]
	global_load_dwordx2 v[78:79], v[66:67], off
	v_lshl_add_u64 v[66:67], v[70:71], 0, v[132:133]
	global_load_dwordx2 v[80:81], v[66:67], off
	v_lshl_add_u64 v[66:67], v[148:149], 0, v[108:109]
	global_load_dwordx2 v[74:75], v[66:67], off
	v_lshl_add_u64 v[66:67], v[70:71], 0, v[130:131]
	global_load_dwordx2 v[76:77], v[66:67], off
	v_lshl_add_u64 v[66:67], v[144:145], 0, v[118:119]
	global_load_dwordx2 v[70:71], v[66:67], off
	v_lshl_add_u64 v[66:67], v[120:121], 0, v[132:133]
	global_load_dwordx2 v[72:73], v[66:67], off
	v_lshl_add_u64 v[66:67], v[148:149], 0, v[118:119]
	global_load_dwordx2 v[66:67], v[66:67], off
	v_lshl_add_u64 v[88:89], s[82:83], 0, v[88:89]
	v_readlane_b32 s0, v254, 26
	s_add_i32 s72, s72, s0
	s_cmpk_gt_i32 s72, 0x1ff
	v_readlane_b32 s1, v254, 27
	s_waitcnt vmcnt(0) lgkmcnt(0)
; #define EPI_HALF(AI, ...) _Pragma("unroll") for(int bj=0;bj<2;++bj) _Pragma("unroll") for(int m=0;m<4;++m) _Pragma("unroll") for(int n=0;n<2;++n) { \
;     const int ai=(AI); const int row=brow+ai*128+wr*64+m*16+fq*4; const int col=bcol+bj*128+wc*32+n*16+fr; \
;     f32x4& v=acc[ai][bj][m][n]; __VA_ARGS__ }
; DEVI void run_phase(const int ph, const Params& P, char* shmc, const int wave_u) {
;     ...
;       GEMM_IDS
; #pragma unroll
;       for (int ah = 0; ah < 2; ++ah) {
;         u32x2 gb[2][4][2], tq[2][4][2];
;         EPI_HALF(ah, { (void)v; gb[bj][m][n] = *reinterpret_cast<const u32x2*>(gates + (long)col * 4096 + 2048 + row);
;           tq[bj][m][n] = *reinterpret_cast<const u32x2*>(tmp5 + (long)col * 2048 + row); })
;         EPI_HALF(ah, { const u32x2 b = gb[bj][m][n]; const u32x2 tw = tq[bj][m][n];
;           const f32x4 t0 = {__uint_as_float(tw[0] << 16), __uint_as_float(tw[0] & 0xffff0000u), __uint_as_float(tw[1] << 16), __uint_as_float(tw[1] & 0xffff0000u)};
;           st_bf4(merged + (long)col * 2048 + row, t0[0] + v[0] * __uint_as_float(b[0] << 16), t0[1] + v[1] * __uint_as_float(b[0] & 0xffff0000u),
;                  t0[2] + v[2] * __uint_as_float(b[1] << 16), t0[3] + v[3] * __uint_as_float(b[1] & 0xffff0000u)); })
;       }
	v_lshlrev_b32_e32 v32, 16, v90
	v_and_b32_e32 v120, 0xffff0000, v90
	v_lshlrev_b32_e32 v145, 16, v92
	v_fmac_f32_e32 v32, v62, v145
	v_and_b32_e32 v62, 0xffff0000, v92
	v_lshlrev_b32_e32 v121, 16, v91
	v_fmac_f32_e32 v120, v63, v62
	v_lshlrev_b32_e32 v62, 16, v93
	v_and_b32_e32 v144, 0xffff0000, v91
	v_lshl_add_u64 v[90:91], v[88:89], 0, v[136:137]
	v_fmac_f32_e32 v121, v64, v62
	v_and_b32_e32 v62, 0xffff0000, v93
	v_fmac_f32_e32 v144, v65, v62
	v_cvt_pk_bf16_f32 v62, v32, v120
	v_cvt_pk_bf16_f32 v63, v121, v144
	v_mov_b32_e32 v236, v62
	v_mov_b32_e32 v237, v63
	v_lshl_add_u64 v[234:235], v[90:91], 0, v[246:247]
	v_lshlrev_b32_e32 v32, 16, v96
	v_lshlrev_b32_e32 v91, 16, v94
	v_and_b32_e32 v64, 0xffff0000, v96
	v_fmac_f32_e32 v32, v58, v91
	v_and_b32_e32 v58, 0xffff0000, v94
	v_lshlrev_b32_e32 v65, 16, v97
	v_fmac_f32_e32 v64, v59, v58
	v_lshlrev_b32_e32 v58, 16, v95
	v_and_b32_e32 v90, 0xffff0000, v97
	v_fmac_f32_e32 v65, v60, v58
	v_and_b32_e32 v58, 0xffff0000, v95
	v_lshl_add_u64 v[62:63], v[88:89], 0, v[134:135]
	v_fmac_f32_e32 v90, v61, v58
	v_cvt_pk_bf16_f32 v58, v32, v64
	v_cvt_pk_bf16_f32 v59, v65, v90
	v_lshlrev_b32_e32 v32, 16, v102
	v_lshlrev_b32_e32 v65, 16, v100
	v_mov_b32_e32 v240, v58
	v_mov_b32_e32 v241, v59
	v_lshl_add_u64 v[244:245], v[62:63], 0, v[246:247]
	v_and_b32_e32 v62, 0xffff0000, v102
	v_fmac_f32_e32 v32, v54, v65
	v_and_b32_e32 v54, 0xffff0000, v100
	v_lshl_add_u64 v[58:59], s[82:83], 0, v[98:99]
	v_lshlrev_b32_e32 v63, 16, v103
	v_fmac_f32_e32 v62, v55, v54
	v_lshlrev_b32_e32 v54, 16, v101
	v_and_b32_e32 v64, 0xffff0000, v103
	v_lshl_add_u64 v[60:61], v[58:59], 0, v[136:137]
	v_fmac_f32_e32 v63, v56, v54
	v_and_b32_e32 v54, 0xffff0000, v101
	v_fmac_f32_e32 v64, v57, v54
	v_cvt_pk_bf16_f32 v54, v32, v62
	v_cvt_pk_bf16_f32 v55, v63, v64
	v_mov_b32_e32 v238, v54
	v_mov_b32_e32 v239, v55
	s_nop 1
	v_permlane16_swap_b32_e32 v236, v238
	v_permlane16_swap_b32_e32 v237, v239
	global_store_dwordx4 v[234:235], v[236:239], off
	v_lshlrev_b32_e32 v32, 16, v106
	v_lshlrev_b32_e32 v61, 16, v104
	v_and_b32_e32 v56, 0xffff0000, v106
	v_fmac_f32_e32 v32, v50, v61
	v_and_b32_e32 v50, 0xffff0000, v104
	v_lshlrev_b32_e32 v57, 16, v107
	v_fmac_f32_e32 v56, v51, v50
	v_lshlrev_b32_e32 v50, 16, v105
	v_and_b32_e32 v60, 0xffff0000, v107
	v_fmac_f32_e32 v57, v52, v50
	v_and_b32_e32 v50, 0xffff0000, v105
	v_lshl_add_u64 v[54:55], v[58:59], 0, v[134:135]
	v_fmac_f32_e32 v60, v53, v50
	v_cvt_pk_bf16_f32 v50, v32, v56
	v_cvt_pk_bf16_f32 v51, v57, v60
	v_lshlrev_b32_e32 v32, 16, v112
	v_lshlrev_b32_e32 v57, 16, v110
	v_mov_b32_e32 v242, v50
	v_mov_b32_e32 v243, v51
	s_nop 1
	v_permlane16_swap_b32_e32 v240, v242
	v_permlane16_swap_b32_e32 v241, v243
	global_store_dwordx4 v[244:245], v[240:243], off
	v_and_b32_e32 v54, 0xffff0000, v112
	v_fmac_f32_e32 v32, v46, v57
	v_and_b32_e32 v46, 0xffff0000, v110
	v_lshl_add_u64 v[50:51], s[82:83], 0, v[108:109]
	v_lshlrev_b32_e32 v55, 16, v113
	v_fmac_f32_e32 v54, v47, v46
	v_lshlrev_b32_e32 v46, 16, v111
	v_and_b32_e32 v56, 0xffff0000, v113
	v_lshl_add_u64 v[52:53], v[50:51], 0, v[136:137]
	v_fmac_f32_e32 v55, v48, v46
	v_and_b32_e32 v46, 0xffff0000, v111
	v_fmac_f32_e32 v56, v49, v46
	v_cvt_pk_bf16_f32 v46, v32, v54
	v_cvt_pk_bf16_f32 v47, v55, v56
	v_mov_b32_e32 v236, v46
	v_mov_b32_e32 v237, v47
	v_lshl_add_u64 v[234:235], v[52:53], 0, v[246:247]
	v_lshlrev_b32_e32 v32, 16, v116
	v_lshlrev_b32_e32 v53, 16, v114
	v_and_b32_e32 v48, 0xffff0000, v116
	v_fmac_f32_e32 v32, v42, v53
	v_and_b32_e32 v42, 0xffff0000, v114
	v_lshlrev_b32_e32 v49, 16, v117
	v_fmac_f32_e32 v48, v43, v42
	v_lshlrev_b32_e32 v42, 16, v115
	v_and_b32_e32 v52, 0xffff0000, v117
	v_fmac_f32_e32 v49, v44, v42
	v_and_b32_e32 v42, 0xffff0000, v115
	v_lshl_add_u64 v[46:47], v[50:51], 0, v[134:135]
	v_fmac_f32_e32 v52, v45, v42
	v_cvt_pk_bf16_f32 v42, v32, v48
	v_cvt_pk_bf16_f32 v43, v49, v52
	v_lshlrev_b32_e32 v32, 16, v124
	v_lshlrev_b32_e32 v49, 16, v122
	v_mov_b32_e32 v240, v42
	v_mov_b32_e32 v241, v43
	v_lshl_add_u64 v[244:245], v[46:47], 0, v[246:247]
	v_and_b32_e32 v46, 0xffff0000, v124
	v_fmac_f32_e32 v32, v38, v49
	v_and_b32_e32 v38, 0xffff0000, v122
	v_lshl_add_u64 v[42:43], s[82:83], 0, v[118:119]
	v_lshlrev_b32_e32 v47, 16, v125
	v_fmac_f32_e32 v46, v39, v38
	v_lshlrev_b32_e32 v38, 16, v123
	v_and_b32_e32 v48, 0xffff0000, v125
	v_lshl_add_u64 v[44:45], v[42:43], 0, v[136:137]
	v_fmac_f32_e32 v47, v40, v38
	v_and_b32_e32 v38, 0xffff0000, v123
	v_fmac_f32_e32 v48, v41, v38
	v_cvt_pk_bf16_f32 v38, v32, v46
	v_cvt_pk_bf16_f32 v39, v47, v48
	v_mov_b32_e32 v238, v38
	v_mov_b32_e32 v239, v39
	s_nop 1
	v_permlane16_swap_b32_e32 v236, v238
	v_permlane16_swap_b32_e32 v237, v239
	global_store_dwordx4 v[234:235], v[236:239], off
	v_lshlrev_b32_e32 v32, 16, v128
	v_lshlrev_b32_e32 v45, 16, v126
	v_and_b32_e32 v40, 0xffff0000, v128
	v_fmac_f32_e32 v32, v34, v45
	v_and_b32_e32 v34, 0xffff0000, v126
	v_lshlrev_b32_e32 v41, 16, v129
	v_fmac_f32_e32 v40, v35, v34
	v_lshlrev_b32_e32 v34, 16, v127
	v_and_b32_e32 v44, 0xffff0000, v129
	v_lshl_add_u64 v[38:39], v[42:43], 0, v[134:135]
	v_fmac_f32_e32 v41, v36, v34
	v_and_b32_e32 v34, 0xffff0000, v127
	v_fmac_f32_e32 v44, v37, v34
	v_cvt_pk_bf16_f32 v34, v32, v40
	v_cvt_pk_bf16_f32 v35, v41, v44
	v_mov_b32_e32 v242, v34
	v_mov_b32_e32 v243, v35
	s_nop 1
; #define EPI_HALF(AI, ...) _Pragma("unroll") for(int bj=0;bj<2;++bj) _Pragma("unroll") for(int m=0;m<4;++m) _Pragma("unroll") for(int n=0;n<2;++n) { \
;     const int ai=(AI); const int row=brow+ai*128+wr*64+m*16+fq*4; const int col=bcol+bj*128+wc*32+n*16+fr; \
;     f32x4& v=acc[ai][bj][m][n]; __VA_ARGS__ }
; DEVI void run_phase(const int ph, const Params& P, char* shmc, const int wave_u) {
;     ...
;       GEMM_IDS
; #pragma unroll
;       for (int ah = 0; ah < 2; ++ah) {
;         u32x2 gb[2][4][2], tq[2][4][2];
;         EPI_HALF(ah, { (void)v; gb[bj][m][n] = *reinterpret_cast<const u32x2*>(gates + (long)col * 4096 + 2048 + row);
;           tq[bj][m][n] = *reinterpret_cast<const u32x2*>(tmp5 + (long)col * 2048 + row); })
;         EPI_HALF(ah, { const u32x2 b = gb[bj][m][n]; const u32x2 tw = tq[bj][m][n];
;           const f32x4 t0 = {__uint_as_float(tw[0] << 16), __uint_as_float(tw[0] & 0xffff0000u), __uint_as_float(tw[1] << 16), __uint_as_float(tw[1] & 0xffff0000u)};
;           st_bf4(merged + (long)col * 2048 + row, t0[0] + v[0] * __uint_as_float(b[0] << 16), t0[1] + v[1] * __uint_as_float(b[0] & 0xffff0000u),
;                  t0[2] + v[2] * __uint_as_float(b[1] << 16), t0[3] + v[3] * __uint_as_float(b[1] & 0xffff0000u)); })
;       }
	v_permlane16_swap_b32_e32 v240, v242
	v_permlane16_swap_b32_e32 v241, v243
	global_store_dwordx4 v[244:245], v[240:243], off
	v_lshlrev_b32_e32 v32, 16, v140
	v_lshlrev_b32_e32 v39, 16, v138
	v_and_b32_e32 v36, 0xffff0000, v140
	v_fmac_f32_e32 v32, v28, v39
	v_and_b32_e32 v28, 0xffff0000, v138
	v_lshlrev_b32_e32 v37, 16, v141
	v_fmac_f32_e32 v36, v29, v28
	v_lshlrev_b32_e32 v28, 16, v139
	v_and_b32_e32 v38, 0xffff0000, v141
	v_lshl_add_u64 v[34:35], v[88:89], 0, v[132:133]
	v_fmac_f32_e32 v37, v30, v28
	v_and_b32_e32 v28, 0xffff0000, v139
	v_fmac_f32_e32 v38, v31, v28
	v_cvt_pk_bf16_f32 v28, v32, v36
	v_cvt_pk_bf16_f32 v29, v37, v38
	v_mov_b32_e32 v236, v28
	v_mov_b32_e32 v237, v29
	v_lshl_add_u64 v[234:235], v[34:35], 0, v[246:247]
	v_lshlrev_b32_e32 v30, 16, v150
	v_lshlrev_b32_e32 v35, 16, v142
	v_and_b32_e32 v31, 0xffff0000, v150
	v_fmac_f32_e32 v30, v24, v35
	v_and_b32_e32 v24, 0xffff0000, v142
	v_lshlrev_b32_e32 v32, 16, v151
	v_fmac_f32_e32 v31, v25, v24
	v_lshlrev_b32_e32 v24, 16, v143
	v_and_b32_e32 v34, 0xffff0000, v151
	v_fmac_f32_e32 v32, v26, v24
	v_and_b32_e32 v24, 0xffff0000, v143
	v_fmac_f32_e32 v34, v27, v24
	v_cvt_pk_bf16_f32 v24, v30, v31
	v_lshlrev_b32_e32 v26, 16, v152
	v_lshlrev_b32_e32 v30, 16, v86
	v_lshl_add_u64 v[28:29], v[88:89], 0, v[130:131]
	v_and_b32_e32 v27, 0xffff0000, v152
	v_fmac_f32_e32 v26, v20, v30
	v_and_b32_e32 v20, 0xffff0000, v86
	v_cvt_pk_bf16_f32 v25, v32, v34
	v_mov_b32_e32 v240, v24
	v_mov_b32_e32 v241, v25
	v_lshl_add_u64 v[244:245], v[28:29], 0, v[246:247]
	v_lshlrev_b32_e32 v28, 16, v153
	v_fmac_f32_e32 v27, v21, v20
	v_lshlrev_b32_e32 v20, 16, v87
	v_and_b32_e32 v29, 0xffff0000, v153
	v_fmac_f32_e32 v28, v22, v20
	v_and_b32_e32 v20, 0xffff0000, v87
	v_fmac_f32_e32 v29, v23, v20
	v_cvt_pk_bf16_f32 v20, v26, v27
	v_lshlrev_b32_e32 v22, 16, v84
	v_lshlrev_b32_e32 v26, 16, v82
	v_lshl_add_u64 v[24:25], v[58:59], 0, v[132:133]
	v_and_b32_e32 v23, 0xffff0000, v84
	v_fmac_f32_e32 v22, v16, v26
	v_and_b32_e32 v16, 0xffff0000, v82
	v_cvt_pk_bf16_f32 v21, v28, v29
	v_mov_b32_e32 v238, v20
	v_mov_b32_e32 v239, v21
	s_nop 1
	v_permlane16_swap_b32_e32 v236, v238
	v_permlane16_swap_b32_e32 v237, v239
	global_store_dwordx4 v[234:235], v[236:239], off
	v_lshlrev_b32_e32 v24, 16, v85
	v_fmac_f32_e32 v23, v17, v16
	v_lshlrev_b32_e32 v16, 16, v83
	v_and_b32_e32 v25, 0xffff0000, v85
	v_fmac_f32_e32 v24, v18, v16
	v_and_b32_e32 v16, 0xffff0000, v83
	v_fmac_f32_e32 v25, v19, v16
	v_cvt_pk_bf16_f32 v16, v22, v23
	v_lshlrev_b32_e32 v18, 16, v80
	v_lshlrev_b32_e32 v22, 16, v78
	v_lshl_add_u64 v[20:21], v[58:59], 0, v[130:131]
	v_and_b32_e32 v19, 0xffff0000, v80
	v_fmac_f32_e32 v18, v12, v22
	v_and_b32_e32 v12, 0xffff0000, v78
	v_cvt_pk_bf16_f32 v17, v24, v25
	v_mov_b32_e32 v242, v16
	v_mov_b32_e32 v243, v17
	s_nop 1
	v_permlane16_swap_b32_e32 v240, v242
	v_permlane16_swap_b32_e32 v241, v243
	global_store_dwordx4 v[244:245], v[240:243], off
	v_lshlrev_b32_e32 v20, 16, v81
	v_fmac_f32_e32 v19, v13, v12
	v_lshlrev_b32_e32 v12, 16, v79
	v_and_b32_e32 v21, 0xffff0000, v81
	v_fmac_f32_e32 v20, v14, v12
	v_and_b32_e32 v12, 0xffff0000, v79
	v_fmac_f32_e32 v21, v15, v12
	v_cvt_pk_bf16_f32 v12, v18, v19
	v_lshlrev_b32_e32 v14, 16, v76
	v_lshlrev_b32_e32 v18, 16, v74
	v_lshl_add_u64 v[16:17], v[50:51], 0, v[132:133]
	v_and_b32_e32 v15, 0xffff0000, v76
	v_fmac_f32_e32 v14, v8, v18
	v_and_b32_e32 v8, 0xffff0000, v74
	v_cvt_pk_bf16_f32 v13, v20, v21
	v_mov_b32_e32 v236, v12
	v_mov_b32_e32 v237, v13
	v_lshl_add_u64 v[234:235], v[16:17], 0, v[246:247]
	v_lshlrev_b32_e32 v16, 16, v77
	v_fmac_f32_e32 v15, v9, v8
	v_lshlrev_b32_e32 v8, 16, v75
	v_and_b32_e32 v17, 0xffff0000, v77
	v_fmac_f32_e32 v16, v10, v8
	v_and_b32_e32 v8, 0xffff0000, v75
	v_fmac_f32_e32 v17, v11, v8
	v_cvt_pk_bf16_f32 v8, v14, v15
	v_lshlrev_b32_e32 v10, 16, v72
	v_lshlrev_b32_e32 v14, 16, v70
	v_lshl_add_u64 v[12:13], v[50:51], 0, v[130:131]
	v_and_b32_e32 v11, 0xffff0000, v72
	v_fmac_f32_e32 v10, v4, v14
	v_and_b32_e32 v4, 0xffff0000, v70
	v_cvt_pk_bf16_f32 v9, v16, v17
	v_mov_b32_e32 v240, v8
	v_mov_b32_e32 v241, v9
	v_lshl_add_u64 v[244:245], v[12:13], 0, v[246:247]
	v_lshlrev_b32_e32 v12, 16, v73
	v_fmac_f32_e32 v11, v5, v4
	v_lshlrev_b32_e32 v4, 16, v71
	v_and_b32_e32 v13, 0xffff0000, v73
	v_fmac_f32_e32 v12, v6, v4
	v_and_b32_e32 v4, 0xffff0000, v71
	v_fmac_f32_e32 v13, v7, v4
	v_cvt_pk_bf16_f32 v4, v10, v11
	v_lshlrev_b32_e32 v6, 16, v68
	v_lshlrev_b32_e32 v10, 16, v66
	v_lshl_add_u64 v[8:9], v[42:43], 0, v[132:133]
	v_and_b32_e32 v7, 0xffff0000, v68
	v_fmac_f32_e32 v6, v0, v10
	v_and_b32_e32 v0, 0xffff0000, v66
	v_cvt_pk_bf16_f32 v5, v12, v13
	v_mov_b32_e32 v238, v4
	v_mov_b32_e32 v239, v5
	s_nop 1
	v_permlane16_swap_b32_e32 v236, v238
	v_permlane16_swap_b32_e32 v237, v239
	global_store_dwordx4 v[234:235], v[236:239], off
	v_lshlrev_b32_e32 v8, 16, v69
	v_fmac_f32_e32 v7, v1, v0
	v_lshlrev_b32_e32 v0, 16, v67
	v_and_b32_e32 v9, 0xffff0000, v69
	v_lshl_add_u64 v[4:5], v[42:43], 0, v[130:131]
	v_fmac_f32_e32 v8, v2, v0
	v_and_b32_e32 v0, 0xffff0000, v67
	v_fmac_f32_e32 v9, v3, v0
	v_cvt_pk_bf16_f32 v0, v6, v7
	v_cvt_pk_bf16_f32 v1, v8, v9
	v_mov_b32_e32 v242, v0
	v_mov_b32_e32 v243, v1
	s_nop 1
	v_permlane16_swap_b32_e32 v240, v242
	v_permlane16_swap_b32_e32 v241, v243
	global_store_dwordx4 v[244:245], v[240:243], off
	s_cbranch_scc1 .LBB0_204

; #define EPI_HALF(AI, ...) _Pragma("unroll") for(int bj=0;bj<2;++bj) _Pragma("unroll") for(int m=0;m<4;++m) _Pragma("unroll") for(int n=0;n<2;++n) { \
;     const int ai=(AI); const int row=brow+ai*128+wr*64+m*16+fq*4; const int col=bcol+bj*128+wc*32+n*16+fr; \
;     f32x4& v=acc[ai][bj][m][n]; __VA_ARGS__ }
; DEVI void run_phase(const int ph, const Params& P, char* shmc, const int wave_u) {
;     ...
;       { GEMM_IDS
; #pragma unroll
;       for (int ah = 0; ah < 2; ++ah) {
;         u32x2 ga[2][4][2];
;         EPI_HALF(ah, { (void)v; ga[bj][m][n] = *reinterpret_cast<const u32x2*>(gates + (long)col * 4096 + row); })
;         EPI_HALF(ah, { const u32x2 a = ga[bj][m][n];
;           st_bf4(tmp5 + (long)col * 2048 + row, v[0] * __uint_as_float(a[0] << 16), v[1] * __uint_as_float(a[0] & 0xffff0000u),
;                  v[2] * __uint_as_float(a[1] << 16), v[3] * __uint_as_float(a[1] & 0xffff0000u)); })
;       }
.LBB0_224:
	s_or_b64 exec, exec, s[70:71]
	v_mbcnt_lo_u32_b32 v224, -1, 0
	v_mbcnt_hi_u32_b32 v224, -1, v224
	v_bfe_u32 v224, v224, 4, 1
	v_mul_u32_u24_e32 v224, 24, v224
	v_mov_b32_e32 v225, 0
	v_mbcnt_lo_u32_b32 v32, -1, 0
	v_mbcnt_hi_u32_b32 v32, -1, v32
	v_readlane_b32 s16, v255, 13
	v_or_b32_e32 v130, s5, v32
	v_ashrrev_i32_e32 v132, 2, v130
	v_and_b32_e32 v132, 0xffffffc0, v132
	v_and_b32_e32 v131, 15, v32
	v_add_u32_e32 v132, s6, v132
	v_lshrrev_b32_e32 v32, 2, v32
	v_and_or_b32 v136, v32, 12, v132
	v_lshrrev_b32_e32 v32, 1, v130
	v_and_b32_e32 v32, 0x60, v32
	v_or3_b32 v132, v131, v32, s0
	v_ashrrev_i32_e32 v137, 31, v136
	v_lshlrev_b64 v[178:179], 1, v[136:137]
	v_readlane_b32 s17, v255, 14
	v_ashrrev_i32_e32 v133, 31, v132
	v_lshlrev_b64 v[130:131], 13, v[132:133]
	v_lshl_add_u64 v[142:143], s[16:17], 0, v[178:179]
	v_lshl_add_u64 v[138:139], v[142:143], 0, v[130:131]
	v_or_b32_e32 v194, 16, v132
	global_load_dwordx2 v[192:193], v[138:139], off
	v_ashrrev_i32_e32 v195, 31, v194
	v_lshlrev_b64 v[134:135], 13, v[194:195]
	v_lshl_add_u64 v[140:141], v[142:143], 0, v[134:135]
	global_load_dwordx2 v[196:197], v[140:141], off
	global_load_dwordx2 v[182:183], v[138:139], off offset:32
	global_load_dwordx2 v[176:177], v[140:141], off offset:32
	global_load_dwordx2 v[170:171], v[138:139], off offset:64
	global_load_dwordx2 v[164:165], v[140:141], off offset:64
	global_load_dwordx2 v[156:157], v[138:139], off offset:96
	global_load_dwordx2 v[152:153], v[140:141], off offset:96
	v_or_b32_e32 v162, 0x80, v132
	v_ashrrev_i32_e32 v163, 31, v162
	v_lshlrev_b64 v[138:139], 13, v[162:163]
	v_lshl_add_u64 v[148:149], v[142:143], 0, v[138:139]
	global_load_dwordx2 v[158:159], v[148:149], off
	v_or_b32_e32 v166, 0x90, v132
	v_ashrrev_i32_e32 v167, 31, v166
	v_lshlrev_b64 v[140:141], 13, v[166:167]
	v_lshl_add_u64 v[142:143], v[142:143], 0, v[140:141]
	global_load_dwordx2 v[172:173], v[142:143], off
	global_load_dwordx2 v[168:169], v[148:149], off offset:32
	global_load_dwordx2 v[160:161], v[142:143], off offset:32
	global_load_dwordx2 v[154:155], v[148:149], off offset:64
	global_load_dwordx2 v[150:151], v[142:143], off offset:64
	s_nop 0
	global_load_dwordx2 v[148:149], v[148:149], off offset:96
	s_nop 0
	global_load_dwordx2 v[142:143], v[142:143], off offset:96
	v_lshl_add_u64 v[178:179], s[84:85], 0, v[178:179]
	v_lshlrev_b64 v[132:133], 12, v[132:133]
	v_lshl_add_u64 v[198:199], v[178:179], 0, v[132:133]
	v_or_b32_e32 v180, 16, v136
	v_ashrrev_i32_e32 v181, 31, v180
	v_or_b32_e32 v174, 32, v136
	v_ashrrev_i32_e32 v175, 31, v174
	v_or_b32_e32 v144, 48, v136
	v_ashrrev_i32_e32 v145, 31, v144
	s_add_u32 s70, s68, 0x80800
	s_addc_u32 s71, s69, 0
	s_waitcnt vmcnt(0) lgkmcnt(0)
	v_lshlrev_b32_e32 v32, 16, v192
	v_mul_f32_e32 v32, v126, v32
	v_and_b32_e32 v126, 0xffff0000, v192
	v_mul_f32_e32 v126, v127, v126
	v_cvt_pk_bf16_f32 v126, v32, v126
	v_lshlrev_b32_e32 v32, 16, v196
	v_lshlrev_b32_e32 v127, 16, v193
	v_mul_f32_e32 v32, v122, v32
	v_and_b32_e32 v122, 0xffff0000, v196
	v_mul_f32_e32 v127, v128, v127
	v_and_b32_e32 v128, 0xffff0000, v193
	v_mul_f32_e32 v122, v123, v122
	v_mul_f32_e32 v128, v129, v128
	v_cvt_pk_bf16_f32 v127, v127, v128
	v_mov_b32_e32 v200, v126
	v_mov_b32_e32 v201, v127
	v_lshl_add_u64 v[216:217], v[198:199], 0, v[224:225]
	v_cvt_pk_bf16_f32 v122, v32, v122
	v_lshlrev_b32_e32 v32, 16, v182
	v_lshlrev_b64 v[126:127], 12, v[194:195]
	v_lshlrev_b32_e32 v123, 16, v197
	v_mul_f32_e32 v32, v118, v32
	v_and_b32_e32 v118, 0xffff0000, v182
	v_lshl_add_u64 v[128:129], v[178:179], 0, v[126:127]
	v_mul_f32_e32 v123, v124, v123
	v_and_b32_e32 v124, 0xffff0000, v197
	v_mul_f32_e32 v118, v119, v118
	v_mul_f32_e32 v124, v125, v124
	v_cvt_pk_bf16_f32 v123, v123, v124
	v_mov_b32_e32 v204, v122
	v_mov_b32_e32 v205, v123
	v_lshl_add_u64 v[218:219], v[128:129], 0, v[224:225]
	v_cvt_pk_bf16_f32 v118, v32, v118
	v_lshlrev_b32_e32 v32, 16, v176
	v_lshl_add_u64 v[124:125], s[84:85], 0, v[132:133]
	v_lshlrev_b64 v[122:123], 1, v[180:181]
	v_lshlrev_b32_e32 v119, 16, v183
	v_mul_f32_e32 v32, v114, v32
	v_and_b32_e32 v114, 0xffff0000, v176
	v_lshl_add_u64 v[128:129], v[124:125], 0, v[122:123]
	v_mul_f32_e32 v119, v120, v119
	v_and_b32_e32 v120, 0xffff0000, v183
	v_mul_f32_e32 v114, v115, v114
	v_mul_f32_e32 v120, v121, v120
	v_cvt_pk_bf16_f32 v119, v119, v120
	v_mov_b32_e32 v202, v118
	v_mov_b32_e32 v203, v119
	s_nop 1
	v_permlane16_swap_b32_e32 v200, v202
	v_permlane16_swap_b32_e32 v201, v203
	global_store_dwordx4 v[216:217], v[200:203], off
	v_cvt_pk_bf16_f32 v114, v32, v114
	v_lshlrev_b32_e32 v32, 16, v170
	v_lshl_add_u64 v[118:119], s[84:85], 0, v[126:127]
	v_lshlrev_b32_e32 v115, 16, v177
	v_mul_f32_e32 v32, v110, v32
	v_and_b32_e32 v110, 0xffff0000, v170
	v_lshl_add_u64 v[120:121], v[118:119], 0, v[122:123]
	v_mul_f32_e32 v115, v116, v115
	v_and_b32_e32 v116, 0xffff0000, v177
	v_mul_f32_e32 v110, v111, v110
	v_mul_f32_e32 v116, v117, v116
	v_cvt_pk_bf16_f32 v115, v115, v116
	v_mov_b32_e32 v206, v114
	v_mov_b32_e32 v207, v115
	s_nop 1
	v_permlane16_swap_b32_e32 v204, v206
	v_permlane16_swap_b32_e32 v205, v207
	global_store_dwordx4 v[218:219], v[204:207], off
	v_cvt_pk_bf16_f32 v110, v32, v110
	v_lshlrev_b32_e32 v32, 16, v164
	v_lshlrev_b64 v[114:115], 1, v[174:175]
	v_lshlrev_b32_e32 v111, 16, v171
	v_mul_f32_e32 v32, v106, v32
	v_and_b32_e32 v106, 0xffff0000, v164
	v_lshl_add_u64 v[116:117], v[124:125], 0, v[114:115]
	v_mul_f32_e32 v111, v112, v111
	v_and_b32_e32 v112, 0xffff0000, v171
	v_mul_f32_e32 v106, v107, v106
	v_mul_f32_e32 v112, v113, v112
	v_cvt_pk_bf16_f32 v111, v111, v112
	v_mov_b32_e32 v208, v110
	v_mov_b32_e32 v209, v111
; #define EPI_HALF(AI, ...) _Pragma("unroll") for(int bj=0;bj<2;++bj) _Pragma("unroll") for(int m=0;m<4;++m) _Pragma("unroll") for(int n=0;n<2;++n) { \
;     const int ai=(AI); const int row=brow+ai*128+wr*64+m*16+fq*4; const int col=bcol+bj*128+wc*32+n*16+fr; \
;     f32x4& v=acc[ai][bj][m][n]; __VA_ARGS__ }
; DEVI void run_phase(const int ph, const Params& P, char* shmc, const int wave_u) {
;     ...
;       { GEMM_IDS
; #pragma unroll
;       for (int ah = 0; ah < 2; ++ah) {
;         u32x2 ga[2][4][2];
;         EPI_HALF(ah, { (void)v; ga[bj][m][n] = *reinterpret_cast<const u32x2*>(gates + (long)col * 4096 + row); })
;         EPI_HALF(ah, { const u32x2 a = ga[bj][m][n];
;           st_bf4(tmp5 + (long)col * 2048 + row, v[0] * __uint_as_float(a[0] << 16), v[1] * __uint_as_float(a[0] & 0xffff0000u),
;                  v[2] * __uint_as_float(a[1] << 16), v[3] * __uint_as_float(a[1] & 0xffff0000u)); })
;       }
	v_lshl_add_u64 v[220:221], v[116:117], 0, v[224:225]
	v_cvt_pk_bf16_f32 v106, v32, v106
	v_lshlrev_b32_e32 v32, 16, v156
	v_lshlrev_b32_e32 v107, 16, v165
	v_mul_f32_e32 v32, v102, v32
	v_and_b32_e32 v102, 0xffff0000, v156
	v_lshl_add_u64 v[110:111], v[118:119], 0, v[114:115]
	v_mul_f32_e32 v107, v108, v107
	v_and_b32_e32 v108, 0xffff0000, v165
	v_mul_f32_e32 v102, v103, v102
	v_mul_f32_e32 v108, v109, v108
	v_cvt_pk_bf16_f32 v107, v107, v108
	v_mov_b32_e32 v212, v106
	v_mov_b32_e32 v213, v107
	v_lshl_add_u64 v[222:223], v[110:111], 0, v[224:225]
	v_cvt_pk_bf16_f32 v102, v32, v102
	v_lshlrev_b32_e32 v32, 16, v152
	v_lshlrev_b64 v[106:107], 1, v[144:145]
	v_lshlrev_b32_e32 v103, 16, v157
	v_mul_f32_e32 v32, v98, v32
	v_and_b32_e32 v98, 0xffff0000, v152
	v_lshl_add_u64 v[108:109], v[124:125], 0, v[106:107]
	v_mul_f32_e32 v103, v104, v103
	v_and_b32_e32 v104, 0xffff0000, v157
	v_mul_f32_e32 v98, v99, v98
	v_mul_f32_e32 v104, v105, v104
	v_cvt_pk_bf16_f32 v103, v103, v104
	v_mov_b32_e32 v210, v102
	v_mov_b32_e32 v211, v103
	s_nop 1
	v_permlane16_swap_b32_e32 v208, v210
	v_permlane16_swap_b32_e32 v209, v211
	global_store_dwordx4 v[220:221], v[208:211], off
	v_cvt_pk_bf16_f32 v98, v32, v98
	v_lshlrev_b32_e32 v32, 16, v158
	v_lshlrev_b32_e32 v99, 16, v153
	v_mul_f32_e32 v32, v94, v32
	v_and_b32_e32 v94, 0xffff0000, v158
	v_lshl_add_u64 v[102:103], v[118:119], 0, v[106:107]
	v_mul_f32_e32 v99, v100, v99
	v_and_b32_e32 v100, 0xffff0000, v153
	v_mul_f32_e32 v94, v95, v94
	v_mul_f32_e32 v100, v101, v100
	v_cvt_pk_bf16_f32 v99, v99, v100
	v_mov_b32_e32 v214, v98
	v_mov_b32_e32 v215, v99
	s_nop 1
	v_permlane16_swap_b32_e32 v212, v214
	v_permlane16_swap_b32_e32 v213, v215
	global_store_dwordx4 v[222:223], v[212:215], off
	v_cvt_pk_bf16_f32 v94, v32, v94
	v_lshlrev_b32_e32 v32, 16, v172
	v_lshlrev_b64 v[98:99], 12, v[162:163]
	v_lshlrev_b32_e32 v95, 16, v159
	v_mul_f32_e32 v32, v90, v32
	v_and_b32_e32 v90, 0xffff0000, v172
	v_lshl_add_u64 v[100:101], v[178:179], 0, v[98:99]
	v_mul_f32_e32 v95, v96, v95
	v_and_b32_e32 v96, 0xffff0000, v159
	v_mul_f32_e32 v90, v91, v90
	v_mul_f32_e32 v96, v97, v96
	v_cvt_pk_bf16_f32 v95, v95, v96
	v_mov_b32_e32 v200, v94
	v_mov_b32_e32 v201, v95
	v_lshl_add_u64 v[216:217], v[100:101], 0, v[224:225]
	v_cvt_pk_bf16_f32 v90, v32, v90
	v_lshlrev_b32_e32 v32, 16, v168
	v_lshlrev_b64 v[94:95], 12, v[166:167]
	v_lshlrev_b32_e32 v91, 16, v173
	v_mul_f32_e32 v32, v86, v32
	v_and_b32_e32 v86, 0xffff0000, v168
	v_lshl_add_u64 v[96:97], v[178:179], 0, v[94:95]
	v_mul_f32_e32 v91, v92, v91
	v_and_b32_e32 v92, 0xffff0000, v173
	v_mul_f32_e32 v86, v87, v86
	v_mul_f32_e32 v92, v93, v92
	v_cvt_pk_bf16_f32 v91, v91, v92
	v_mov_b32_e32 v204, v90
	v_mov_b32_e32 v205, v91
	v_lshl_add_u64 v[218:219], v[96:97], 0, v[224:225]
	v_cvt_pk_bf16_f32 v86, v32, v86
	v_lshlrev_b32_e32 v32, 16, v160
	v_lshl_add_u64 v[90:91], s[84:85], 0, v[98:99]
	v_lshlrev_b32_e32 v87, 16, v169
	v_mul_f32_e32 v32, v82, v32
	v_and_b32_e32 v82, 0xffff0000, v160
	v_lshl_add_u64 v[92:93], v[90:91], 0, v[122:123]
	v_mul_f32_e32 v87, v88, v87
	v_and_b32_e32 v88, 0xffff0000, v169
	v_mul_f32_e32 v82, v83, v82
	v_mul_f32_e32 v88, v89, v88
	v_cvt_pk_bf16_f32 v87, v87, v88
	v_mov_b32_e32 v202, v86
	v_mov_b32_e32 v203, v87
	s_nop 1
	v_permlane16_swap_b32_e32 v200, v202
	v_permlane16_swap_b32_e32 v201, v203
	global_store_dwordx4 v[216:217], v[200:203], off
	v_cvt_pk_bf16_f32 v82, v32, v82
	v_lshlrev_b32_e32 v32, 16, v154
	v_lshl_add_u64 v[86:87], s[84:85], 0, v[94:95]
	v_lshlrev_b32_e32 v83, 16, v161
	v_mul_f32_e32 v32, v78, v32
	v_and_b32_e32 v78, 0xffff0000, v154
	v_lshl_add_u64 v[88:89], v[86:87], 0, v[122:123]
	v_mul_f32_e32 v83, v84, v83
	v_and_b32_e32 v84, 0xffff0000, v161
	v_mul_f32_e32 v78, v79, v78
	v_mul_f32_e32 v84, v85, v84
	v_cvt_pk_bf16_f32 v83, v83, v84
	v_mov_b32_e32 v206, v82
	v_mov_b32_e32 v207, v83
	s_nop 1
	v_permlane16_swap_b32_e32 v204, v206
	v_permlane16_swap_b32_e32 v205, v207
	global_store_dwordx4 v[218:219], v[204:207], off
	v_cvt_pk_bf16_f32 v78, v32, v78
	v_lshlrev_b32_e32 v32, 16, v150
	v_lshlrev_b32_e32 v79, 16, v155
	v_mul_f32_e32 v32, v74, v32
	v_and_b32_e32 v74, 0xffff0000, v150
	v_lshl_add_u64 v[82:83], v[90:91], 0, v[114:115]
	v_mul_f32_e32 v79, v80, v79
	v_and_b32_e32 v80, 0xffff0000, v155
	v_mul_f32_e32 v74, v75, v74
	v_mul_f32_e32 v80, v81, v80
	v_cvt_pk_bf16_f32 v79, v79, v80
	v_mov_b32_e32 v208, v78
	v_mov_b32_e32 v209, v79
	v_lshl_add_u64 v[220:221], v[82:83], 0, v[224:225]
	v_cvt_pk_bf16_f32 v74, v32, v74
	v_lshlrev_b32_e32 v32, 16, v148
	v_lshlrev_b32_e32 v75, 16, v151
	v_mul_f32_e32 v32, v70, v32
	v_and_b32_e32 v70, 0xffff0000, v148
	v_lshl_add_u64 v[78:79], v[86:87], 0, v[114:115]
	v_mul_f32_e32 v75, v76, v75
	v_and_b32_e32 v76, 0xffff0000, v151
	v_mul_f32_e32 v70, v71, v70
	v_mul_f32_e32 v76, v77, v76
	v_cvt_pk_bf16_f32 v75, v75, v76
	v_mov_b32_e32 v212, v74
	v_mov_b32_e32 v213, v75
	v_lshl_add_u64 v[222:223], v[78:79], 0, v[224:225]
	v_lshlrev_b32_e32 v71, 16, v149
	v_cvt_pk_bf16_f32 v70, v32, v70
	v_lshlrev_b32_e32 v32, 16, v142
	v_mul_f32_e32 v71, v72, v71
	v_and_b32_e32 v72, 0xffff0000, v149
	v_mul_f32_e32 v32, v66, v32
	v_and_b32_e32 v66, 0xffff0000, v142
	v_lshl_add_u64 v[74:75], v[90:91], 0, v[106:107]
	v_mul_f32_e32 v72, v73, v72
	v_cvt_pk_bf16_f32 v71, v71, v72
	v_mul_f32_e32 v66, v67, v66
	v_lshlrev_b32_e32 v67, 16, v143
	v_mov_b32_e32 v210, v70
	v_mov_b32_e32 v211, v71
	s_nop 1
	v_permlane16_swap_b32_e32 v208, v210
	v_permlane16_swap_b32_e32 v209, v211
	global_store_dwordx4 v[220:221], v[208:211], off
	v_lshl_add_u64 v[70:71], v[86:87], 0, v[106:107]
	v_mul_f32_e32 v67, v68, v67
	v_and_b32_e32 v68, 0xffff0000, v143
; #define EPI_HALF(AI, ...) _Pragma("unroll") for(int bj=0;bj<2;++bj) _Pragma("unroll") for(int m=0;m<4;++m) _Pragma("unroll") for(int n=0;n<2;++n) { \
;     const int ai=(AI); const int row=brow+ai*128+wr*64+m*16+fq*4; const int col=bcol+bj*128+wc*32+n*16+fr; \
;     f32x4& v=acc[ai][bj][m][n]; __VA_ARGS__ }
; DEVI void run_phase(const int ph, const Params& P, char* shmc, const int wave_u) {
;     ...
;       { GEMM_IDS
; #pragma unroll
;       for (int ah = 0; ah < 2; ++ah) {
;         u32x2 ga[2][4][2];
;         EPI_HALF(ah, { (void)v; ga[bj][m][n] = *reinterpret_cast<const u32x2*>(gates + (long)col * 4096 + row); })
;         EPI_HALF(ah, { const u32x2 a = ga[bj][m][n];
;           st_bf4(tmp5 + (long)col * 2048 + row, v[0] * __uint_as_float(a[0] << 16), v[1] * __uint_as_float(a[0] & 0xffff0000u),
;                  v[2] * __uint_as_float(a[1] << 16), v[3] * __uint_as_float(a[1] & 0xffff0000u)); })
;       }
	v_cvt_pk_bf16_f32 v66, v32, v66
	v_mul_f32_e32 v68, v69, v68
	v_cvt_pk_bf16_f32 v67, v67, v68
	v_mov_b32_e32 v214, v66
	v_mov_b32_e32 v215, v67
	s_nop 1
	v_permlane16_swap_b32_e32 v212, v214
	v_permlane16_swap_b32_e32 v213, v215
	global_store_dwordx4 v[222:223], v[212:215], off
	v_add_u32_e32 v66, 0x80, v136
	v_ashrrev_i32_e32 v67, 31, v66
	v_lshlrev_b64 v[66:67], 1, v[66:67]
	v_lshl_add_u64 v[72:73], s[16:17], 0, v[66:67]
	v_lshl_add_u64 v[74:75], v[72:73], 0, v[130:131]
	global_load_dwordx2 v[74:75], v[74:75], off
	v_add_u32_e32 v78, 0x90, v136
	v_lshl_add_u64 v[76:77], v[72:73], 0, v[134:135]
	v_ashrrev_i32_e32 v79, 31, v78
	global_load_dwordx2 v[76:77], v[76:77], off
	v_lshlrev_b64 v[78:79], 1, v[78:79]
	v_lshl_add_u64 v[80:81], s[16:17], 0, v[78:79]
	v_lshl_add_u64 v[82:83], v[80:81], 0, v[130:131]
	global_load_dwordx2 v[82:83], v[82:83], off
	v_add_u32_e32 v86, 0xa0, v136
	v_lshl_add_u64 v[84:85], v[80:81], 0, v[134:135]
	v_ashrrev_i32_e32 v87, 31, v86
	global_load_dwordx2 v[84:85], v[84:85], off
	v_lshlrev_b64 v[86:87], 1, v[86:87]
	v_lshl_add_u64 v[88:89], s[16:17], 0, v[86:87]
	v_lshl_add_u64 v[90:91], v[88:89], 0, v[130:131]
	global_load_dwordx2 v[90:91], v[90:91], off
	v_add_u32_e32 v68, 0xb0, v136
	v_ashrrev_i32_e32 v69, 31, v68
	v_lshl_add_u64 v[92:93], v[88:89], 0, v[134:135]
	v_lshlrev_b64 v[68:69], 1, v[68:69]
	global_load_dwordx2 v[92:93], v[92:93], off
	v_lshl_add_u64 v[70:71], s[16:17], 0, v[68:69]
	v_lshl_add_u64 v[96:97], v[70:71], 0, v[130:131]
	global_load_dwordx2 v[96:97], v[96:97], off
	v_lshl_add_u64 v[100:101], v[70:71], 0, v[134:135]
	global_load_dwordx2 v[100:101], v[100:101], off
	v_lshl_add_u64 v[102:103], v[72:73], 0, v[138:139]
	global_load_dwordx2 v[102:103], v[102:103], off
	v_lshl_add_u64 v[72:73], v[72:73], 0, v[140:141]
	global_load_dwordx2 v[72:73], v[72:73], off
	v_lshl_add_u64 v[104:105], v[80:81], 0, v[138:139]
	global_load_dwordx2 v[104:105], v[104:105], off
	v_lshl_add_u64 v[80:81], v[80:81], 0, v[140:141]
	v_lshl_add_u64 v[106:107], v[88:89], 0, v[138:139]
	v_lshl_add_u64 v[88:89], v[88:89], 0, v[140:141]
	global_load_dwordx2 v[88:89], v[88:89], off
	v_lshl_add_u64 v[108:109], v[70:71], 0, v[138:139]
	global_load_dwordx2 v[80:81], v[80:81], off
	v_lshl_add_u64 v[70:71], v[70:71], 0, v[140:141]
	global_load_dwordx2 v[106:107], v[106:107], off
	v_lshl_add_u64 v[66:67], s[84:85], 0, v[66:67]
	global_load_dwordx2 v[108:109], v[108:109], off
	v_lshl_add_u64 v[110:111], v[66:67], 0, v[132:133]
	global_load_dwordx2 v[70:71], v[70:71], off
	s_mov_b64 s[16:17], 0x800
	v_mov_b32_e32 v131, v33
	s_waitcnt vmcnt(0) lgkmcnt(0)
	v_lshlrev_b32_e32 v32, 16, v74
	v_mul_f32_e32 v32, v62, v32
	v_and_b32_e32 v62, 0xffff0000, v74
	v_mul_f32_e32 v62, v63, v62
	v_cvt_pk_bf16_f32 v62, v32, v62
	v_lshlrev_b32_e32 v32, 16, v76
	v_lshlrev_b32_e32 v63, 16, v75
	v_mul_f32_e32 v32, v58, v32
	v_and_b32_e32 v58, 0xffff0000, v76
	v_mul_f32_e32 v63, v64, v63
	v_and_b32_e32 v64, 0xffff0000, v75
	v_mul_f32_e32 v58, v59, v58
	v_mul_f32_e32 v64, v65, v64
	v_cvt_pk_bf16_f32 v63, v63, v64
	v_mov_b32_e32 v200, v62
	v_mov_b32_e32 v201, v63
	v_lshl_add_u64 v[216:217], v[110:111], 0, v[224:225]
	v_cvt_pk_bf16_f32 v58, v32, v58
	v_lshlrev_b32_e32 v32, 16, v82
	v_lshlrev_b32_e32 v59, 16, v77
	v_mul_f32_e32 v32, v54, v32
	v_and_b32_e32 v54, 0xffff0000, v82
	v_lshl_add_u64 v[62:63], v[66:67], 0, v[126:127]
	v_mul_f32_e32 v59, v60, v59
	v_and_b32_e32 v60, 0xffff0000, v77
	v_mul_f32_e32 v54, v55, v54
	v_mul_f32_e32 v60, v61, v60
	v_cvt_pk_bf16_f32 v59, v59, v60
	v_mov_b32_e32 v204, v58
	v_mov_b32_e32 v205, v59
	v_lshl_add_u64 v[218:219], v[62:63], 0, v[224:225]
	v_cvt_pk_bf16_f32 v54, v32, v54
	v_lshlrev_b32_e32 v32, 16, v84
	v_lshl_add_u64 v[58:59], s[84:85], 0, v[78:79]
	v_lshlrev_b32_e32 v55, 16, v83
	v_mul_f32_e32 v32, v50, v32
	v_and_b32_e32 v50, 0xffff0000, v84
	v_lshl_add_u64 v[60:61], v[58:59], 0, v[132:133]
	v_mul_f32_e32 v55, v56, v55
	v_and_b32_e32 v56, 0xffff0000, v83
	v_mul_f32_e32 v50, v51, v50
	v_mul_f32_e32 v56, v57, v56
	v_cvt_pk_bf16_f32 v55, v55, v56
	v_mov_b32_e32 v202, v54
	v_mov_b32_e32 v203, v55
	s_nop 1
	v_permlane16_swap_b32_e32 v200, v202
	v_permlane16_swap_b32_e32 v201, v203
	global_store_dwordx4 v[216:217], v[200:203], off
	v_cvt_pk_bf16_f32 v50, v32, v50
	v_lshlrev_b32_e32 v32, 16, v90
	v_lshlrev_b32_e32 v51, 16, v85
	v_mul_f32_e32 v32, v46, v32
	v_and_b32_e32 v46, 0xffff0000, v90
	v_lshl_add_u64 v[54:55], v[58:59], 0, v[126:127]
	v_mul_f32_e32 v51, v52, v51
	v_and_b32_e32 v52, 0xffff0000, v85
	v_mul_f32_e32 v46, v47, v46
	v_mul_f32_e32 v52, v53, v52
	v_cvt_pk_bf16_f32 v51, v51, v52
	v_mov_b32_e32 v206, v50
	v_mov_b32_e32 v207, v51
	s_nop 1
	v_permlane16_swap_b32_e32 v204, v206
	v_permlane16_swap_b32_e32 v205, v207
	global_store_dwordx4 v[218:219], v[204:207], off
	v_cvt_pk_bf16_f32 v46, v32, v46
	v_lshlrev_b32_e32 v32, 16, v92
	v_lshl_add_u64 v[50:51], s[84:85], 0, v[86:87]
	v_lshlrev_b32_e32 v47, 16, v91
	v_mul_f32_e32 v32, v42, v32
	v_and_b32_e32 v42, 0xffff0000, v92
	v_lshl_add_u64 v[52:53], v[50:51], 0, v[132:133]
	v_mul_f32_e32 v47, v48, v47
	v_and_b32_e32 v48, 0xffff0000, v91
	v_mul_f32_e32 v42, v43, v42
	v_mul_f32_e32 v48, v49, v48
	v_cvt_pk_bf16_f32 v47, v47, v48
	v_mov_b32_e32 v208, v46
	v_mov_b32_e32 v209, v47
	v_lshl_add_u64 v[220:221], v[52:53], 0, v[224:225]
	v_cvt_pk_bf16_f32 v42, v32, v42
	v_lshlrev_b32_e32 v32, 16, v96
	v_lshlrev_b32_e32 v43, 16, v93
	v_mul_f32_e32 v32, v38, v32
	v_and_b32_e32 v38, 0xffff0000, v96
	v_lshl_add_u64 v[46:47], v[50:51], 0, v[126:127]
	v_mul_f32_e32 v43, v44, v43
	v_and_b32_e32 v44, 0xffff0000, v93
	v_mul_f32_e32 v38, v39, v38
	v_mul_f32_e32 v44, v45, v44
;   #define WAIT_V(n) asm volatile("s_waitcnt vmcnt(" #n ")":::"memory")
; #define EPI_HALF(AI, ...) _Pragma("unroll") for(int bj=0;bj<2;++bj) _Pragma("unroll") for(int m=0;m<4;++m) _Pragma("unroll") for(int n=0;n<2;++n) { \
;     const int ai=(AI); const int row=brow+ai*128+wr*64+m*16+fq*4; const int col=bcol+bj*128+wc*32+n*16+fr; \
;     f32x4& v=acc[ai][bj][m][n]; __VA_ARGS__ }
; DEVI void gemm_core(const bf16* __restrict__ A, const long lda, const bf16* __restrict__ Bt, const long ldb, const int K,
;                     acc_t& acc, bf16* shm, const int wave_u) {
;     ...
;   int tidg = get_tid(wave_u);
;   const int wid=tidg>>6,lane=tidg&63,wr=wid>>2,wc=wid&3,fr=lane&15,fq=lane>>4;
;   bf16x8 At[4][2],B0[2][2],B1[2][2];
;   const int nt=K/BK;
;   WAIT_V(0);
; DEVI void run_phase(const int ph, const Params& P, char* shmc, const int wave_u) {
;     ...
;       { GEMM_IDS
; #pragma unroll
;       for (int ah = 0; ah < 2; ++ah) {
;         u32x2 ga[2][4][2];
;         EPI_HALF(ah, { (void)v; ga[bj][m][n] = *reinterpret_cast<const u32x2*>(gates + (long)col * 4096 + row); })
;         EPI_HALF(ah, { const u32x2 a = ga[bj][m][n];
;           st_bf4(tmp5 + (long)col * 2048 + row, v[0] * __uint_as_float(a[0] << 16), v[1] * __uint_as_float(a[0] & 0xffff0000u),
;                  v[2] * __uint_as_float(a[1] << 16), v[3] * __uint_as_float(a[1] & 0xffff0000u)); })
;       }
	v_cvt_pk_bf16_f32 v43, v43, v44
	v_mov_b32_e32 v212, v42
	v_mov_b32_e32 v213, v43
	v_lshl_add_u64 v[222:223], v[46:47], 0, v[224:225]
	v_cvt_pk_bf16_f32 v38, v32, v38
	v_lshlrev_b32_e32 v32, 16, v100
	v_lshl_add_u64 v[42:43], s[84:85], 0, v[68:69]
	v_lshlrev_b32_e32 v39, 16, v97
	v_mul_f32_e32 v32, v34, v32
	v_and_b32_e32 v34, 0xffff0000, v100
	v_lshl_add_u64 v[44:45], v[42:43], 0, v[132:133]
	v_mul_f32_e32 v39, v40, v39
	v_and_b32_e32 v40, 0xffff0000, v97
	v_mul_f32_e32 v34, v35, v34
	v_mul_f32_e32 v40, v41, v40
	v_cvt_pk_bf16_f32 v39, v39, v40
	v_mov_b32_e32 v210, v38
	v_mov_b32_e32 v211, v39
	s_nop 1
	v_permlane16_swap_b32_e32 v208, v210
	v_permlane16_swap_b32_e32 v209, v211
	global_store_dwordx4 v[220:221], v[208:211], off
	v_cvt_pk_bf16_f32 v34, v32, v34
	v_lshlrev_b32_e32 v32, 16, v102
	v_mul_f32_e32 v28, v28, v32
	v_and_b32_e32 v32, 0xffff0000, v102
	v_lshlrev_b32_e32 v35, 16, v101
	v_mul_f32_e32 v29, v29, v32
	v_lshlrev_b32_e32 v32, 16, v103
	v_lshl_add_u64 v[38:39], v[42:43], 0, v[126:127]
	v_mul_f32_e32 v35, v36, v35
	v_and_b32_e32 v36, 0xffff0000, v101
	v_mul_f32_e32 v30, v30, v32
	v_and_b32_e32 v32, 0xffff0000, v103
	v_mul_f32_e32 v36, v37, v36
	v_cvt_pk_bf16_f32 v35, v35, v36
	v_mov_b32_e32 v214, v34
	v_mov_b32_e32 v215, v35
	s_nop 1
	v_permlane16_swap_b32_e32 v212, v214
	v_permlane16_swap_b32_e32 v213, v215
	global_store_dwordx4 v[222:223], v[212:215], off
	v_mul_f32_e32 v31, v31, v32
	v_cvt_pk_bf16_f32 v28, v28, v29
	v_cvt_pk_bf16_f32 v29, v30, v31
	v_lshlrev_b32_e32 v30, 16, v72
	v_mul_f32_e32 v24, v24, v30
	v_and_b32_e32 v30, 0xffff0000, v72
	v_mul_f32_e32 v25, v25, v30
	v_lshlrev_b32_e32 v30, 16, v73
	v_lshl_add_u64 v[34:35], v[66:67], 0, v[98:99]
	v_mul_f32_e32 v26, v26, v30
	v_and_b32_e32 v30, 0xffff0000, v73
	v_mov_b32_e32 v200, v28
	v_mov_b32_e32 v201, v29
	v_lshl_add_u64 v[216:217], v[34:35], 0, v[224:225]
	v_mul_f32_e32 v27, v27, v30
	v_cvt_pk_bf16_f32 v24, v24, v25
	v_cvt_pk_bf16_f32 v25, v26, v27
	v_lshlrev_b32_e32 v26, 16, v104
	v_mul_f32_e32 v20, v20, v26
	v_and_b32_e32 v26, 0xffff0000, v104
	v_mul_f32_e32 v21, v21, v26
	v_lshlrev_b32_e32 v26, 16, v105
	v_lshl_add_u64 v[28:29], v[66:67], 0, v[94:95]
	v_mul_f32_e32 v22, v22, v26
	v_and_b32_e32 v26, 0xffff0000, v105
	v_mov_b32_e32 v204, v24
	v_mov_b32_e32 v205, v25
	v_lshl_add_u64 v[218:219], v[28:29], 0, v[224:225]
	v_mul_f32_e32 v23, v23, v26
	v_cvt_pk_bf16_f32 v20, v20, v21
	v_cvt_pk_bf16_f32 v21, v22, v23
	v_lshlrev_b32_e32 v22, 16, v80
	v_mul_f32_e32 v16, v16, v22
	v_and_b32_e32 v22, 0xffff0000, v80
	v_mul_f32_e32 v17, v17, v22
	v_lshlrev_b32_e32 v22, 16, v81
	v_lshl_add_u64 v[24:25], v[58:59], 0, v[98:99]
	v_mul_f32_e32 v18, v18, v22
	v_and_b32_e32 v22, 0xffff0000, v81
	v_mov_b32_e32 v202, v20
	v_mov_b32_e32 v203, v21
	s_nop 1
	v_permlane16_swap_b32_e32 v200, v202
	v_permlane16_swap_b32_e32 v201, v203
	global_store_dwordx4 v[216:217], v[200:203], off
	v_mul_f32_e32 v19, v19, v22
	v_cvt_pk_bf16_f32 v16, v16, v17
	v_cvt_pk_bf16_f32 v17, v18, v19
	v_lshlrev_b32_e32 v18, 16, v106
	v_mul_f32_e32 v12, v12, v18
	v_and_b32_e32 v18, 0xffff0000, v106
	v_mul_f32_e32 v13, v13, v18
	v_lshlrev_b32_e32 v18, 16, v107
	v_lshl_add_u64 v[20:21], v[58:59], 0, v[94:95]
	v_mul_f32_e32 v14, v14, v18
	v_and_b32_e32 v18, 0xffff0000, v107
	v_mov_b32_e32 v206, v16
	v_mov_b32_e32 v207, v17
	s_nop 1
	v_permlane16_swap_b32_e32 v204, v206
	v_permlane16_swap_b32_e32 v205, v207
	global_store_dwordx4 v[218:219], v[204:207], off
	v_mul_f32_e32 v15, v15, v18
	v_cvt_pk_bf16_f32 v12, v12, v13
	v_cvt_pk_bf16_f32 v13, v14, v15
	v_lshlrev_b32_e32 v14, 16, v88
	v_mul_f32_e32 v8, v8, v14
	v_and_b32_e32 v14, 0xffff0000, v88
	v_mul_f32_e32 v9, v9, v14
	v_lshlrev_b32_e32 v14, 16, v89
	v_lshl_add_u64 v[16:17], v[50:51], 0, v[98:99]
	v_mul_f32_e32 v10, v10, v14
	v_and_b32_e32 v14, 0xffff0000, v89
	v_mov_b32_e32 v208, v12
	v_mov_b32_e32 v209, v13
	v_lshl_add_u64 v[220:221], v[16:17], 0, v[224:225]
	v_mul_f32_e32 v11, v11, v14
	v_cvt_pk_bf16_f32 v8, v8, v9
	v_cvt_pk_bf16_f32 v9, v10, v11
	v_lshlrev_b32_e32 v10, 16, v108
	v_mul_f32_e32 v4, v4, v10
	v_and_b32_e32 v10, 0xffff0000, v108
	v_mul_f32_e32 v5, v5, v10
	v_lshlrev_b32_e32 v10, 16, v109
	v_lshl_add_u64 v[12:13], v[50:51], 0, v[94:95]
	v_mul_f32_e32 v6, v6, v10
	v_and_b32_e32 v10, 0xffff0000, v109
	v_mov_b32_e32 v212, v8
	v_mov_b32_e32 v213, v9
	v_lshl_add_u64 v[222:223], v[12:13], 0, v[224:225]
	v_mul_f32_e32 v7, v7, v10
	v_cvt_pk_bf16_f32 v4, v4, v5
	v_cvt_pk_bf16_f32 v5, v6, v7
	v_lshlrev_b32_e32 v6, 16, v70
	v_mul_f32_e32 v0, v0, v6
	v_and_b32_e32 v6, 0xffff0000, v70
	v_lshl_add_u64 v[8:9], v[42:43], 0, v[98:99]
	v_mul_f32_e32 v1, v1, v6
	v_lshlrev_b32_e32 v6, 16, v71
	v_mov_b32_e32 v210, v4
	v_mov_b32_e32 v211, v5
	s_nop 1
	v_permlane16_swap_b32_e32 v208, v210
	v_permlane16_swap_b32_e32 v209, v211
	global_store_dwordx4 v[220:221], v[208:211], off
	v_lshl_add_u64 v[4:5], v[42:43], 0, v[94:95]
	v_mul_f32_e32 v2, v2, v6
	v_and_b32_e32 v6, 0xffff0000, v71
	v_cvt_pk_bf16_f32 v0, v0, v1
	v_mul_f32_e32 v3, v3, v6
	v_cvt_pk_bf16_f32 v1, v2, v3
	v_mov_b32_e32 v214, v0
	v_mov_b32_e32 v215, v1
	s_nop 1
	v_permlane16_swap_b32_e32 v212, v214
	v_permlane16_swap_b32_e32 v213, v215
	global_store_dwordx4 v[222:223], v[212:215], off
	v_mov_b32_e32 v0, v33
	v_mbcnt_lo_u32_b32 v10, -1, 0
	v_mbcnt_hi_u32_b32 v10, -1, v10
	s_waitcnt vmcnt(0)
;   #define STAGE(P,BASE,LD,br,kt) do{const char* _ub=(const char*)((BASE)+(long)(br)*(LD)+(long)(kt)*BK); \
;     for(int _i=0;_i<2;++_i){int _b=tidg*16+_i*8192;int _r,_c;stage_rc(_b,_r,_c); \
;       const unsigned _vo=(unsigned)(_r*(int)(LD)+_c)*2u; \
;       __builtin_amdgcn_global_load_lds((const unsigned*)(_ub+_vo), \
;         (unsigned*)((char*)(P)+_b),16,0,0);}}while(0)
;   #define WAIT_V(n) asm volatile("s_waitcnt vmcnt(" #n ")":::"memory")
;   #define BAR __builtin_amdgcn_s_barrier()
; DEVI void gemm_core(const bf16* __restrict__ A, const long lda, const bf16* __restrict__ Bt, const long ldb, const int K,
;                     acc_t& acc, bf16* shm, const int wave_u) {
;     ...
;   int tidg = get_tid(wave_u);
;   const int wid=tidg>>6,lane=tidg&63,wr=wid>>2,wc=wid&3,fr=lane&15,fq=lane>>4;
;   bf16x8 At[4][2],B0[2][2],B1[2][2];
;   const int nt=K/BK;
;   WAIT_V(0);
;   STAGE(SB(0,0),Bt,ldb,0,0); STAGE(SA(0,0),A,lda,0,0);
;   STAGE(SB(0,1),Bt,ldb,HALF,0); STAGE(SA(0,1),A,lda,HALF,0);
;   if(wr==1)BAR;
	s_nop 0
	v_or_b32_e32 v140, s5, v10
	v_bfe_i32 v2, v140, 27, 1
	v_lshlrev_b32_e32 v14, 4, v140
	v_lshrrev_b32_e32 v2, 22, v2
	v_add_u32_e32 v2, v14, v2
	v_and_b32_e32 v2, 0xfffffc00, v2
	v_sub_u32_e32 v2, v14, v2
	v_lshrrev_b32_e32 v3, 4, v2
	v_ashrrev_i32_e32 v1, 31, v140
	v_bitop3_b32 v2, v3, v2, 32 bitop3:0x6c
	v_lshrrev_b32_e32 v1, 26, v1
	v_ashrrev_i32_e32 v4, 31, v2
	v_add_u32_e32 v1, v140, v1
	v_lshrrev_b32_e32 v4, 26, v4
	v_ashrrev_i32_e32 v1, 6, v1
	v_add_u32_e32 v4, v2, v4
	v_lshlrev_b32_e32 v3, 3, v1
	v_ashrrev_i32_e32 v11, 6, v4
	v_and_b32_e32 v4, 0xc0, v4
	v_and_b32_e32 v3, 0xffff0, v3
	v_lshlrev_b32_e32 v5, 5, v1
	v_sub_u32_e32 v2, v2, v4
	v_add_u32_e32 v3, v11, v3
	v_and_b32_e32 v12, 32, v5
	v_ashrrev_i16_sdwa v2, v187, sext(v2) dst_sel:DWORD dst_unused:UNUSED_PAD src0_sel:DWORD src1_sel:BYTE_0
	v_bfe_i32 v13, v2, 0, 16
	v_lshl_or_b32 v2, v3, 11, v12
	v_add_lshl_u32 v32, v2, v13, 1
	v_add_u32_e32 v145, s33, v14
	v_lshl_add_u64 v[2:3], s[68:69], 0, v[32:33]
	v_readfirstlane_b32 s1, v145
	v_lshl_add_u64 v[4:5], v[2:3], 0, s[16:17]
	s_mov_b32 m0, s1
	v_add_u32_e32 v22, 0x2000, v14
	global_load_lds_dwordx4 v[4:5], off
	v_ashrrev_i32_e32 v4, 31, v22
	v_lshrrev_b32_e32 v4, 22, v4
	v_add_u32_e32 v4, v22, v4
	v_ashrrev_i32_e32 v15, 10, v4
	v_mul_i32_i24_e32 v4, 0x400, v15
	v_sub_u32_e32 v4, v22, v4
	v_lshrrev_b32_e32 v5, 4, v4
	v_bitop3_b32 v4, v5, v4, 32 bitop3:0x6c
	v_ashrrev_i32_e32 v6, 31, v4
	v_lshrrev_b32_e32 v6, 26, v6
	v_add_u32_e32 v6, v4, v6
	v_lshlrev_b32_e32 v5, 3, v15
	v_ashrrev_i32_e32 v16, 6, v6
	v_and_b32_e32 v6, 0xc0, v6
	v_and_b32_e32 v5, 0xffff0, v5
	v_lshlrev_b32_e32 v7, 5, v15
	v_sub_u32_e32 v4, v4, v6
	v_add_u32_e32 v5, v16, v5
	v_and_b32_e32 v17, 32, v7
	v_ashrrev_i16_sdwa v4, v187, sext(v4) dst_sel:DWORD dst_unused:UNUSED_PAD src0_sel:DWORD src1_sel:BYTE_0
	v_bfe_i32 v18, v4, 0, 16
	v_lshl_or_b32 v4, v5, 11, v17
	v_add_lshl_u32 v130, v4, v18, 1
	v_add_u32_e32 v8, s33, v22
	v_lshl_add_u64 v[4:5], s[68:69], 0, v[130:131]
	v_readfirstlane_b32 s1, v8
	v_lshl_add_u64 v[6:7], v[4:5], 0, s[16:17]
	s_mov_b32 m0, s1
	v_add_u32_e32 v149, 16, v14
	global_load_lds_dwordx4 v[6:7], off
	v_lshl_add_u64 v[6:7], s[8:9], 0, v[32:33]
	v_readfirstlane_b32 s1, v149
	v_lshl_add_u64 v[8:9], v[6:7], 0, s[16:17]
	s_mov_b32 m0, s1
	v_add_u32_e32 v150, 0x2000, v149
	global_load_lds_dwordx4 v[8:9], off
	v_lshl_add_u64 v[8:9], s[8:9], 0, v[130:131]
	v_readfirstlane_b32 s1, v150
	v_lshl_add_u64 v[20:21], v[8:9], 0, s[16:17]
	s_mov_b32 m0, s1
	v_add_u32_e32 v151, s74, v14
	global_load_lds_dwordx4 v[20:21], off
	v_readfirstlane_b32 s1, v151
	v_add_u32_e32 v20, s74, v22
	s_mov_b32 m0, s1
	v_readfirstlane_b32 s1, v20
	global_load_lds_dwordx4 v32, s[70:71]
	s_mov_b32 m0, s1
	v_add_u32_e32 v153, 0x4000, v149
	global_load_lds_dwordx4 v130, s[70:71]
	s_add_u32 s70, s8, 0x80800
	v_readfirstlane_b32 s1, v153
	v_add_u32_e32 v154, 0x6000, v149
	s_addc_u32 s71, s9, 0
	s_mov_b32 m0, s1
	v_readfirstlane_b32 s1, v154
	global_load_lds_dwordx4 v32, s[70:71]
	s_mov_b32 m0, s1
	v_ashrrev_i32_e32 v19, 8, v140
	global_load_lds_dwordx4 v130, s[70:71]
	v_cmp_eq_u32_e32 vcc, 1, v19
	s_and_saveexec_b64 s[70:71], vcc
	s_cbranch_execz .LBB0_226
	s_barrier

; DEVI int v_rd_base(int lane) { return ((lane & 3) << 3) | (((lane >> 2) & 3) << 6) | (((lane >> 4) & 1) << 5) | (((lane >> 5) & 1) << 8); }
; template <bool MLA> ...
;     ...
;   int tid = get_tid(wave_u);
;   const int wid = tid >> 6, lane = tid & 63, r32 = lane & 31, hi = lane >> 5;
;   char* V_lds = lds; char* K_lds = lds + 2 * SHM_V;
;   float* al_l = (float*)(lds + 2 * SHM_V + 2 * SHM_K) + wid * 64;
;   const int first = wid * 32; const bool wact = first < nrows;
;   const int lastv = min(first + 31, nrows - 1);
;   const int rowc = min(first + r32, nrows - 1);
;   const int qpos = qpos0 + rowc;
;   int bound, bmax, bmin;
;   if (MLA) { bound = min(64 * (qpos / 64 + 1), nk); bmax = min(64 * ((qpos0 + lastv) / 64 + 1), nk); bmin = min(64 * ((qpos0 + first) / 64 + 1), nk); }
;   else { bound = qpos; bmax = qpos0 + lastv; bmin = qpos0 + first; }
;   if (!wact) bmax = 0;
;   bf16x8 qr[ND0];
;   { const bf16* Qw = Qb + (long)rowc * ldq + hi * 8;
; #pragma unroll
;     for (int d0 = 0; d0 < ND0; ++d0) qr[d0] = *reinterpret_cast<const bf16x8*>(Qw + d0 * 16); }
;   f32x16 o[4];
; #pragma unroll
;   for (int d = 0; d < 4; ++d)
; #pragma unroll
;     for (int r = 0; r < 16; ++r) o[d][r] = 0.f;
;   float m_reg = -1e30f, l_reg = 0.f, Rsum = 1.f;
;   const int vb0 = (int)(uintptr_t)V_lds + v_rd_base(lane);
;   int kq4[4];
; #pragma unroll
;   for (int k = 0; k < 4; ++k) kq4[k] = ((((r32 & 7) ^ hi) ^ (k << 1)) << 4);
;     ...
;   int kt = nkt - 1;
;   TILE_DMA(kt * 64, 0);
; DEVI void run_phase(const int ph, const Params& P, char* shmc, const int wave_u) {
;     ...
;         const int c = it - 1024; const int type = c >> 7, b = (c >> 3) & 15, h = c & 7;
;         const long tok0 = MP + (long)b * DSEQ; const long kb0 = (long)b * SKS;
;         if (type == 0)
;           attn_item<false>(sbq + tok0 * 1024 + h * 128, 1024, sbk_s + kb0 * 1024 + h * 128, 1024, nullptr,
;                            sbv_s + kb0 * 1024 + h * 128, 1024, ocat + tok0 * 2048 + h * 128, 2048, PAST, DSEQ, PAST + DSEQ, 17, shmc, wave_u);
;         else
;           attn_item<true>(qm + tok0 * 1536 + h * 192, 1536, kn_s + kb0 * 1024 + h * 128, 1024, kr_s + kb0 * 64,
;                           vm_s + kb0 * 1024 + h * 128, 1024, ocat + tok0 * 2048 + 1024 + h * 128, 2048, PAST, DSEQ, PAST + DSEQ, 17, shmc, wave_u);
.LBB0_232:
	s_cmpk_gt_i32 s71, 0x3ff
	s_mov_b64 s[0:1], -1
	s_cbranch_scc0 .LBB0_342
	s_bfe_u32 s73, s71, 0x40003
	s_lshl_b32 s72, s73, 5
	s_and_b32 s75, s71, 7
	s_bitset1_b32 s72, 14
	s_and_b32 s0, s71, 0x7fffff80
	s_cmpk_lg_i32 s0, 0x400
	s_mul_i32 s22, s73, 0x110000
	s_mov_b64 s[0:1], -1
	s_cbranch_scc0 .LBB0_296
	s_mul_i32 s0, s72, 0xc00
	v_readlane_b32 s6, v255, 17
	v_readlane_b32 s7, v255, 18
	s_add_u32 s0, s6, s0
	s_addc_u32 s1, s7, 0
	s_mul_i32 s6, s75, 0x180
	s_add_u32 s0, s0, s6
	s_addc_u32 s1, s1, 0
	s_lshl_b32 s6, s22, 1
	v_readlane_b32 s4, v255, 38
	s_add_u32 s7, s4, s6
	v_readlane_b32 s4, v255, 39
	s_addc_u32 s8, s4, 0
	s_lshl_b32 s9, s75, 8
	s_add_u32 s38, s7, s9
	s_addc_u32 s39, s8, 0
	s_mul_i32 s7, s73, 0x22000
	s_add_u32 s68, s18, s7
	s_addc_u32 s69, s19, 0
	v_readlane_b32 s4, v255, 42
	s_add_u32 s6, s4, s6
	v_readlane_b32 s4, v255, 43
	s_waitcnt vmcnt(0) lgkmcnt(0)
	v_mbcnt_lo_u32_b32 v1, -1, 0
	v_mbcnt_hi_u32_b32 v1, -1, v1
	s_addc_u32 s7, s4, 0
	v_or_b32_e32 v31, s5, v1
	v_ashrrev_i32_e32 v30, 1, v31
	s_movk_i32 s4, 0xffe0
	v_bfi_b32 v0, s4, v30, v1
	v_bfe_u32 v9, v1, 5, 1
	v_min_i32_e32 v34, 31, v0
	v_mov_b64_e32 v[2:3], s[0:1]
	s_movk_i32 s0, 0xc00
	v_mad_i64_i32 v[2:3], s[0:1], v34, s0, v[2:3]
	v_lshlrev_b32_e32 v32, 4, v9
	v_lshl_add_u64 v[2:3], v[2:3], 0, v[32:33]
	global_load_dwordx4 v[98:101], v[2:3], off
	global_load_dwordx4 v[102:105], v[2:3], off offset:32
	global_load_dwordx4 v[106:109], v[2:3], off offset:64
	global_load_dwordx4 v[110:113], v[2:3], off offset:96
	global_load_dwordx4 v[114:117], v[2:3], off offset:128
	global_load_dwordx4 v[118:121], v[2:3], off offset:160
	global_load_dwordx4 v[122:125], v[2:3], off offset:192
	global_load_dwordx4 v[126:129], v[2:3], off offset:224
	global_load_dwordx4 v[130:133], v[2:3], off offset:256
	global_load_dwordx4 v[134:137], v[2:3], off offset:288
	global_load_dwordx4 v[138:141], v[2:3], off offset:320
	global_load_dwordx4 v[142:145], v[2:3], off offset:352
	v_mov_b32_e32 v2, s5
	s_movk_i32 s0, 0x60
	v_lshlrev_b32_e32 v0, 3, v31
	v_bitop3_b32 v2, v1, s0, v2 bitop3:0xc8
	v_and_or_b32 v0, v0, 24, v2
	v_lshrrev_b32_e32 v2, 1, v31
	v_bfe_u32 v24, v31, 2, 2
	v_and_b32_e32 v25, 8, v2
	s_movk_i32 s0, 0x400
	v_lshlrev_b32_e32 v2, 1, v0
	v_ashrrev_i32_e32 v0, 4, v31
	s_add_u32 s6, s6, s9
	v_or3_b32 v4, v25, v24, s0
	v_and_b32_e32 v26, -16, v0
	v_lshrrev_b32_e32 v0, 1, v0
	s_addc_u32 s7, s7, 0
	v_lshlrev_b32_e32 v8, 4, v31
	v_mov_b32_e32 v3, v33
	v_and_b32_e32 v27, 4, v0
	v_add_u32_e32 v0, v4, v26
	v_lshl_add_u64 v[148:149], s[6:7], 0, v[2:3]
	v_or_b32_e32 v2, v0, v27
	v_add_u32_e32 v12, 0x2000, v8
	v_ashrrev_i32_e32 v3, 31, v2
	v_add_u32_e32 v153, 16, v8
	v_ashrrev_i32_e32 v0, 8, v12
	v_lshlrev_b64 v[2:3], 11, v[2:3]
	v_readfirstlane_b32 s0, v153
	v_and_b32_e32 v28, -16, v0
	v_lshrrev_b32_e32 v0, 1, v0
	v_lshl_add_u64 v[2:3], v[148:149], 0, v[2:3]
	s_mov_b32 m0, s0
	v_and_b32_e32 v29, 4, v0
	v_add_u32_e32 v0, v4, v28
	global_load_lds_dwordx4 v[2:3], off
	v_or_b32_e32 v2, v0, v29
	v_ashrrev_i32_e32 v3, 31, v2
	v_add_u32_e32 v0, 0x2000, v153
	v_lshlrev_b64 v[2:3], 11, v[2:3]
	v_readfirstlane_b32 s0, v0
	v_lshl_add_u64 v[2:3], v[148:149], 0, v[2:3]
	s_mov_b32 m0, s0
	s_mov_b32 s0, 0x2aaaaaab
	global_load_lds_dwordx4 v[2:3], off
	v_mul_hi_i32 v0, v31, s0
	v_lshrrev_b32_e32 v2, 31, v0
	v_ashrrev_i32_e32 v0, 2, v0
	v_add_u32_e32 v0, v0, v2
	s_movk_i32 s0, 0xfe80
	v_mad_u64_u32 v[2:3], s[0:1], v0, s0, v[8:9]
	v_lshlrev_b32_e32 v3, 4, v0
	s_movk_i32 s0, 0x70
	v_bitop3_b32 v6, v2, v3, s0 bitop3:0x78
	s_movk_i32 s0, 0xff
	v_add_u32_e32 v10, 0x400, v0
	v_cmp_gt_i32_e32 vcc, s95, v6
	v_cmp_lt_i32_e64 s[0:1], s0, v6
	v_ashrrev_i32_e32 v11, 31, v10
	v_add_u32_e32 v4, 0xffffff00, v6
	s_and_saveexec_b64 s[6:7], s[0:1]
	s_xor_b64 s[0:1], exec, s[6:7]
	v_lshlrev_b64 v[2:3], 7, v[10:11]
	v_lshl_add_u64 v[2:3], s[68:69], 0, v[2:3]
	v_mov_b32_e32 v5, v33
	v_lshl_add_u64 v[2:3], v[2:3], 0, v[4:5]
	s_or_saveexec_b64 s[0:1], s[0:1]
	v_ashrrev_i32_e32 v6, 1, v6
	v_ashrrev_i32_e32 v7, 31, v6
	s_xor_b64 exec, exec, s[0:1]
	v_lshlrev_b64 v[2:3], 11, v[10:11]
	v_lshl_add_u64 v[2:3], s[38:39], 0, v[2:3]
	v_lshl_add_u64 v[2:3], v[6:7], 1, v[2:3]
	s_or_b64 exec, exec, s[0:1]
	v_add_u32_e32 v5, 0x8000, v153
	s_movk_i32 s4, 0xff
	v_readfirstlane_b32 s0, v5
	s_mov_b32 m0, s0
	s_mov_b32 s0, 0x2aaaaaab
	global_load_lds_dwordx4 v[2:3], off
	v_mul_hi_i32 v2, v12, s0
	v_lshrrev_b32_e32 v3, 31, v2
	v_ashrrev_i32_e32 v2, 6, v2
	v_add_u32_e32 v2, v2, v3
	s_movk_i32 s0, 0xfe80
	v_mad_i32_i24 v3, v2, s0, v12
	v_lshlrev_b32_e32 v5, 4, v2
	s_movk_i32 s0, 0x70
	v_bitop3_b32 v3, v3, v5, s0 bitop3:0x78
	v_add_u32_e32 v16, 0x400, v2
	v_cmp_gt_i32_e64 s[0:1], s95, v3
	v_cmp_lt_i32_e64 s[6:7], s4, v3
	v_ashrrev_i32_e32 v17, 31, v16
	v_add_u32_e32 v10, 0xffffff00, v3
	s_and_saveexec_b64 s[8:9], s[6:7]
	s_xor_b64 s[6:7], exec, s[8:9]
	v_lshlrev_b64 v[12:13], 7, v[16:17]
	v_lshl_add_u64 v[12:13], s[68:69], 0, v[12:13]
	v_mov_b32_e32 v11, v33
	v_lshl_add_u64 v[14:15], v[12:13], 0, v[10:11]
	s_or_saveexec_b64 s[6:7], s[6:7]
	v_ashrrev_i32_e32 v12, 1, v3
	v_ashrrev_i32_e32 v13, 31, v12
	s_xor_b64 exec, exec, s[6:7]
	v_lshlrev_b64 v[14:15], 11, v[16:17]
	v_lshl_add_u64 v[14:15], s[38:39], 0, v[14:15]
	v_lshl_add_u64 v[14:15], v[12:13], 1, v[14:15]
	s_or_b64 exec, exec, s[6:7]
	v_add_u32_e32 v3, 0xa000, v153
	s_mov_b32 s4, 0x2aaaaaab
	v_readfirstlane_b32 s6, v3
	s_mov_b32 m0, s6
	v_add_u32_e32 v3, 0x4000, v8
	global_load_lds_dwordx4 v[14:15], off
	v_mul_hi_i32 v5, v3, s4
	v_lshrrev_b32_e32 v8, 31, v5
	v_ashrrev_i32_e32 v5, 6, v5
	v_add_u32_e32 v8, v5, v8
	s_movk_i32 s4, 0xfe80
	v_mad_i32_i24 v3, v8, s4, v3
	v_lshlrev_b32_e32 v5, 4, v8
; DEVI int v_rd_base(int lane) { return ((lane & 3) << 3) | (((lane >> 2) & 3) << 6) | (((lane >> 4) & 1) << 5) | (((lane >> 5) & 1) << 8); }
; template <bool MLA> ...
;     ...
;   float* al_l = (float*)(lds + 2 * SHM_V + 2 * SHM_K) + wid * 64;
;   const int first = wid * 32; const bool wact = first < nrows;
;   const int lastv = min(first + 31, nrows - 1);
;   const int rowc = min(first + r32, nrows - 1);
;   const int qpos = qpos0 + rowc;
;   int bound, bmax, bmin;
;   if (MLA) { bound = min(64 * (qpos / 64 + 1), nk); bmax = min(64 * ((qpos0 + lastv) / 64 + 1), nk); bmin = min(64 * ((qpos0 + first) / 64 + 1), nk); }
;   else { bound = qpos; bmax = qpos0 + lastv; bmin = qpos0 + first; }
;   if (!wact) bmax = 0;
;   bf16x8 qr[ND0];
;   { const bf16* Qw = Qb + (long)rowc * ldq + hi * 8;
; #pragma unroll
;     for (int d0 = 0; d0 < ND0; ++d0) qr[d0] = *reinterpret_cast<const bf16x8*>(Qw + d0 * 16); }
;   f32x16 o[4];
; #pragma unroll
;   for (int d = 0; d < 4; ++d)
; #pragma unroll
;     for (int r = 0; r < 16; ++r) o[d][r] = 0.f;
;   float m_reg = -1e30f, l_reg = 0.f, Rsum = 1.f;
;   const int vb0 = (int)(uintptr_t)V_lds + v_rd_base(lane);
;   int kq4[4];
; #pragma unroll
;   for (int k = 0; k < 4; ++k) kq4[k] = ((((r32 & 7) ^ hi) ^ (k << 1)) << 4);
;     ...
;   int kt = nkt - 1;
	s_movk_i32 s4, 0x70
	v_bitop3_b32 v3, v3, v5, s4 bitop3:0x78
	s_movk_i32 s4, 0xff
	v_add_u32_e32 v20, 0x400, v8
	v_add_u32_e32 v22, 0xffffff00, v3
	v_cmp_gt_i32_e64 s[12:13], s95, v3
	v_cmp_lt_i32_e64 s[6:7], s4, v3
	v_ashrrev_i32_e32 v21, 31, v20
	v_lshrrev_b32_e32 v14, 1, v22
	s_and_saveexec_b64 s[8:9], s[6:7]
	s_xor_b64 s[6:7], exec, s[8:9]
	v_lshlrev_b64 v[16:17], 7, v[20:21]
	v_lshl_add_u64 v[16:17], s[68:69], 0, v[16:17]
	v_mov_b32_e32 v23, v33
	v_mov_b32_e32 v15, v33
	v_lshl_add_u64 v[18:19], v[16:17], 0, v[22:23]
	v_lshrrev_b32_e32 v16, 1, v3
	v_mov_b32_e32 v17, v33
	s_or_saveexec_b64 s[6:7], s[6:7]
	s_lshl_b32 s93, s75, 7
	v_mov_b64_e32 v[150:151], 7
	s_xor_b64 exec, exec, s[6:7]
	v_lshlrev_b64 v[16:17], 11, v[20:21]
	v_lshl_add_u64 v[18:19], s[38:39], 0, v[16:17]
	v_ashrrev_i32_e32 v16, 1, v3
	v_ashrrev_i32_e32 v17, 31, v16
	v_lshl_add_u64 v[18:19], v[16:17], 1, v[18:19]
	v_mov_b32_e32 v15, v33
	v_mov_b64_e32 v[150:151], 11
	s_or_b64 exec, exec, s[6:7]
	v_or_b32_e32 v11, 31, v30
	v_add_u32_e32 v20, 0x400, v34
	v_min_i32_e32 v11, 31, v11
	v_ashrrev_i32_e32 v21, 31, v20
	v_lshrrev_b32_e32 v21, 26, v21
	v_add_u32_e32 v11, 0x400, v11
	v_add_u32_e32 v20, v20, v21
	v_ashrrev_i32_e32 v21, 31, v11
	v_and_b32_e32 v157, 0xffffffe0, v30
	v_lshrrev_b32_e32 v21, 26, v21
	v_add_u32_e32 v11, v11, v21
	v_add_u32_e32 v21, 0x400, v157
	v_ashrrev_i32_e32 v22, 31, v21
	v_lshrrev_b32_e32 v22, 26, v22
	v_add_u32_e32 v21, v21, v22
	v_and_b32_e32 v21, 0xffffffc0, v21
	v_and_b32_e32 v3, 63, v1
	v_and_b32_e32 v5, 0x3fffffc0, v31
	v_add_u32_e32 v21, 64, v21
	v_min_i32_e32 v173, 0x420, v21
	v_lshl_add_u32 v163, v5, 2, s74
	v_lshlrev_b32_e32 v5, 4, v3
	v_bitop3_b32 v21, v9, v1, 7 bitop3:0x78
	v_lshlrev_b32_e32 v175, 4, v21
	v_and_b32_e32 v21, 0xc0, v5
	v_add_u32_e32 v5, 0xc000, v153
	v_and_b32_e32 v11, 0xffffffc0, v11
	v_readfirstlane_b32 s8, v5
	s_mov_b32 m0, s8
	v_min_i32_e32 v11, 0x3e0, v11
	global_load_lds_dwordx4 v[18:19], off
	v_add_u32_e32 v11, 64, v11
	v_cmp_gt_i32_e64 s[6:7], 32, v30
	v_lshl_add_u64 v[12:13], v[12:13], 1, s[38:39]
	v_and_b32_e32 v151, 31, v1
	v_cndmask_b32_e64 v174, 0, v11, s[6:7]
	v_lshlrev_b32_e32 v11, 1, v3
	v_and_b32_e32 v18, 32, v11
	v_mov_b32_e32 v11, v33
	v_lshl_add_u64 v[10:11], s[68:69], 0, v[10:11]
	v_lshlrev_b32_e32 v22, 3, v3
	v_cndmask_b32_e64 v156, 7, 11, s[0:1]
	v_cndmask_b32_e64 v159, v11, v13, s[0:1]
	v_cndmask_b32_e64 v158, v10, v12, s[0:1]
	s_movk_i32 s0, 0x118
	s_cmp_lg_u32 16, -1
	v_and_b32_e32 v1, 32, v1
	v_cmp_gt_u32_e64 s[8:9], 32, v3
	v_and_or_b32 v3, v22, s0, v18
	s_cselect_b32 s0, 16, 0
	v_lshrrev_b32_e32 v1, 3, v1
	v_lshlrev_b32_e32 v171, 2, v9
	v_lshl_add_u32 v182, v9, 4, v163
	v_add3_u32 v222, v21, s0, v3
	v_or_b32_e32 v162, 0x400, v1
	v_ashrrev_i32_e32 v9, 31, v8
	s_mov_b64 s[0:1], 0x3c0
	v_ashrrev_i32_e32 v3, 31, v2
	v_ashrrev_i32_e32 v1, 31, v0
	v_and_b32_e32 v20, 0xffffffc0, v20
	v_mov_b32_e32 v5, v33
	v_lshl_add_u64 v[14:15], v[14:15], 1, s[68:69]
	v_lshl_add_u64 v[16:17], v[16:17], 1, s[38:39]
	v_lshl_add_u64 v[164:165], v[8:9], 0, s[0:1]
	v_lshl_add_u64 v[166:167], v[2:3], 0, s[0:1]
	v_lshl_add_u64 v[168:169], v[0:1], 0, s[0:1]
	v_add3_u32 v0, v28, v25, v29
	s_movk_i32 s0, 0x3c0
	v_min_i32_e32 v20, 0x3e0, v20
	v_lshl_add_u64 v[4:5], s[68:69], 0, v[4:5]
	v_lshl_add_u64 v[6:7], v[6:7], 1, s[38:39]
	v_cndmask_b32_e64 v161, v15, v17, s[12:13]
	v_cndmask_b32_e64 v160, v14, v16, s[12:13]
	v_add3_u32 v170, v0, v24, s0
	v_add3_u32 v0, v26, v25, v27
	v_mov_b32_e32 v14, v33
	v_mov_b32_e32 v15, v33
	v_add_u32_e32 v180, 64, v20
	s_movk_i32 s4, 0x180
	v_cndmask_b32_e32 v155, v5, v7, vcc
	v_cndmask_b32_e32 v154, v4, v6, vcc
	v_add_u32_e32 v183, 32, v20
	v_add_u32_e32 v192, 63, v20
	v_or_b32_e32 v193, 31, v20
	v_add_u32_e32 v194, 62, v20
	v_or_b32_e32 v195, 30, v20
	v_add_u32_e32 v196, 61, v20
	v_or_b32_e32 v197, 29, v20
	v_add_u32_e32 v198, 56, v20
	v_or_b32_e32 v199, 24, v20
	v_add_u32_e32 v200, 55, v20
	v_or_b32_e32 v201, 23, v20
	v_add_u32_e32 v202, 54, v20
	v_or_b32_e32 v203, 22, v20
	v_add_u32_e32 v204, 53, v20
	v_or_b32_e32 v205, 21, v20
	v_add_u32_e32 v206, 48, v20
	v_or_b32_e32 v207, 16, v20
	v_add_u32_e32 v208, 47, v20
	v_or_b32_e32 v209, 15, v20
	v_add_u32_e32 v210, 46, v20
	v_or_b32_e32 v211, 14, v20
	v_add_u32_e32 v212, 45, v20
	v_or_b32_e32 v213, 13, v20
	v_add_u32_e32 v214, 40, v20
	v_or_b32_e32 v215, 8, v20
	v_add_u32_e32 v216, 39, v20
	v_or_b32_e32 v217, 7, v20
	v_add_u32_e32 v218, 38, v20
	v_or_b32_e32 v219, 6, v20
	v_add_u32_e32 v220, 37, v20
	v_or_b32_e32 v221, 5, v20
	v_add3_u32 v172, v0, v24, s0
	v_mov_b32_e32 v0, v33
	v_mov_b32_e32 v1, v33
	v_mov_b32_e32 v2, v33
	v_mov_b32_e32 v3, v33
	v_mov_b32_e32 v4, v33
	v_mov_b32_e32 v5, v33
	v_mov_b32_e32 v6, v33
	v_mov_b32_e32 v7, v33
	v_mov_b32_e32 v8, v33
	v_mov_b32_e32 v9, v33
	v_mov_b32_e32 v10, v33
	v_mov_b32_e32 v11, v33
	v_mov_b32_e32 v12, v33
	v_mov_b32_e32 v13, v33
	v_mov_b64_e32 v[64:65], v[14:15]
	v_mov_b64_e32 v[48:49], v[14:15]
	v_mov_b64_e32 v[30:31], v[14:15]
	s_mov_b32 s92, 0
	v_xor_b32_e32 v176, 32, v175
	v_xor_b32_e32 v177, 64, v175
	v_xor_b32_e32 v178, 0x60, v175
	v_mad_u32_u24 v181, v151, s4, 16
	v_lshl_add_u32 v179, v151, 2, v163
	v_cndmask_b32_e64 v152, 7, 11, vcc
	v_mov_b32_e32 v224, 0
	v_mov_b32_e32 v223, 0xf149f2ca
	s_mov_b64 s[0:1], 0
	v_mov_b64_e32 v[62:63], v[12:13]
	v_mov_b64_e32 v[60:61], v[10:11]
	v_mov_b64_e32 v[58:59], v[8:9]
	v_mov_b64_e32 v[56:57], v[6:7]
	v_mov_b64_e32 v[54:55], v[4:5]
	v_mov_b64_e32 v[52:53], v[2:3]
	v_mov_b64_e32 v[50:51], v[0:1]
	v_mov_b64_e32 v[46:47], v[12:13]
	v_mov_b64_e32 v[44:45], v[10:11]
	v_mov_b64_e32 v[42:43], v[8:9]
	v_mov_b64_e32 v[40:41], v[6:7]
	v_mov_b64_e32 v[38:39], v[4:5]
	v_mov_b64_e32 v[36:37], v[2:3]
	v_mov_b64_e32 v[34:35], v[0:1]
	v_mov_b64_e32 v[28:29], v[12:13]
	v_mov_b64_e32 v[26:27], v[10:11]
	v_mov_b64_e32 v[24:25], v[8:9]
	v_mov_b64_e32 v[22:23], v[6:7]
	v_mov_b64_e32 v[20:21], v[4:5]
	v_mov_b64_e32 v[18:19], v[2:3]
	v_mov_b64_e32 v[16:17], v[0:1]
	s_waitcnt vmcnt(0)
	s_branch .LBB0_250

; DEVI int crow(int r, int hi) { return (r & 3) + 8 * (r >> 2) + 4 * hi; }
; template <bool MLA> ...
;     ...
;   if (wact) {
;     float rli[16];
;     if (MLA) {
;       if (hi == 0) al_l[r32] = l_reg;
;       asm volatile("s_waitcnt lgkmcnt(0)" ::: "memory");
; #pragma unroll
;       for (int r = 0; r < 16; ++r) rli[r] = __builtin_amdgcn_rcpf(al_l[crow(r, hi)]);
;     } else {
; #pragma unroll
;       for (int r = 0; r < 16; ++r) rli[r] = 1.f;
;     }
; #pragma unroll
;     for (int r = 0; r < 16; ++r) { const int orow = first + crow(r, hi);
;       if (orow < nrows) {
; #pragma unroll
;         for (int d0 = 0; d0 < 4; ++d0) Ob[(long)orow * ldo + d0 * 32 + r32] = __float2bfloat16(o[d0][r] * rli[r]); } }
.LBB0_260:
	s_and_saveexec_b64 s[0:1], s[6:7]
	s_cbranch_execz .LBB0_295
	s_and_saveexec_b64 s[6:7], s[8:9]
	ds_write_b32 v179, v224
	s_or_b64 exec, exec, s[6:7]
	s_waitcnt lgkmcnt(0)
	v_add_u32_e32 v81, v163, v32
	ds_read2_b32 v[82:83], v81 offset0:1 offset1:2
	ds_read_b32 v86, v81 offset:12
	ds_read_b128 v[74:77], v81 offset:32
	ds_read_b128 v[70:73], v81 offset:64
	ds_read_b128 v[66:69], v81 offset:96
	s_lshl_b32 s6, s72, 12
	v_readlane_b32 s4, v255, 25
	s_add_u32 s6, s4, s6
	v_readlane_b32 s4, v255, 44
	s_addc_u32 s7, s4, 0
	s_lshl_b32 s8, s93, 1
	s_add_u32 s6, s6, s8
	s_addc_u32 s7, s7, 0
	v_or_b32_e32 v80, v171, v157
	v_lshlrev_b32_e32 v32, 1, v151
	v_lshl_add_u64 v[78:79], s[6:7], 0, v[32:33]
	v_cmp_gt_i32_e32 vcc, 32, v80
	s_and_saveexec_b64 s[6:7], vcc
	s_cbranch_execz .LBB0_265
	ds_read_b32 v32, v81
	v_ashrrev_i32_e32 v81, 31, v80
	v_lshlrev_b64 v[84:85], 12, v[80:81]
	v_lshl_add_u64 v[84:85], v[78:79], 0, v[84:85]
	s_waitcnt lgkmcnt(0)
	v_rcp_f32_e32 v32, v32
	s_nop 0
	v_mul_f32_e32 v0, v0, v32
	v_mul_f32_e32 v50, v50, v32
	v_mul_f32_e32 v34, v34, v32
	v_cvt_pk_bf16_f32 v0, v0, s0
	v_cvt_pk_bf16_f32 v50, v50, s0
	global_store_short v[84:85], v0, off offset:2048
	global_store_short v[84:85], v50, off offset:2112
	v_cvt_pk_bf16_f32 v0, v34, s0
	global_store_short v[84:85], v0, off offset:2176
	v_mul_f32_e32 v0, v16, v32
	v_cvt_pk_bf16_f32 v0, v0, s0
	global_store_short v[84:85], v0, off offset:2240
.LBB0_265:
	s_or_b64 exec, exec, s[6:7]
	v_or_b32_e32 v84, 1, v80
	v_cmp_gt_i32_e32 vcc, 32, v84
	s_and_saveexec_b64 s[6:7], vcc
	s_cbranch_execz .LBB0_267
	s_waitcnt lgkmcnt(0)
	v_rcp_f32_e32 v0, v82
	v_ashrrev_i32_e32 v85, 31, v84
	v_lshlrev_b64 v[84:85], 12, v[84:85]
	v_lshl_add_u64 v[84:85], v[78:79], 0, v[84:85]
	v_mul_f32_e32 v1, v1, v0
	v_cvt_pk_bf16_f32 v1, v1, s0
	global_store_short v[84:85], v1, off offset:2048
	v_mul_f32_e32 v1, v51, v0
	v_cvt_pk_bf16_f32 v1, v1, s0
	global_store_short v[84:85], v1, off offset:2112
	v_mul_f32_e32 v1, v35, v0
	v_mul_f32_e32 v0, v17, v0
	v_cvt_pk_bf16_f32 v1, v1, s0
	v_cvt_pk_bf16_f32 v0, v0, s0
	global_store_short v[84:85], v1, off offset:2176
	global_store_short v[84:85], v0, off offset:2240
.LBB0_267:
	s_or_b64 exec, exec, s[6:7]
	v_or_b32_e32 v0, 2, v80
	v_cmp_gt_i32_e32 vcc, 32, v0
	s_and_saveexec_b64 s[6:7], vcc
	s_cbranch_execz .LBB0_269
	s_waitcnt lgkmcnt(0)
	v_rcp_f32_e32 v16, v83
	v_ashrrev_i32_e32 v1, 31, v0
	v_lshlrev_b64 v[0:1], 12, v[0:1]
	v_lshl_add_u64 v[0:1], v[78:79], 0, v[0:1]
	v_mul_f32_e32 v2, v2, v16
	v_cvt_pk_bf16_f32 v2, v2, s0
	global_store_short v[0:1], v2, off offset:2048
	v_mul_f32_e32 v2, v52, v16
	v_cvt_pk_bf16_f32 v2, v2, s0
	global_store_short v[0:1], v2, off offset:2112
	v_mul_f32_e32 v2, v36, v16
	v_cvt_pk_bf16_f32 v2, v2, s0
	global_store_short v[0:1], v2, off offset:2176
	v_mul_f32_e32 v2, v18, v16
	v_cvt_pk_bf16_f32 v2, v2, s0
	global_store_short v[0:1], v2, off offset:2240
.LBB0_269:
	s_or_b64 exec, exec, s[6:7]
	v_or_b32_e32 v0, 3, v80
	v_cmp_gt_i32_e32 vcc, 32, v0
	s_and_saveexec_b64 s[6:7], vcc
	s_cbranch_execz .LBB0_271
	s_waitcnt lgkmcnt(0)
	v_rcp_f32_e32 v2, v86
	v_ashrrev_i32_e32 v1, 31, v0
	v_lshlrev_b64 v[0:1], 12, v[0:1]
	v_lshl_add_u64 v[0:1], v[78:79], 0, v[0:1]
	v_mul_f32_e32 v3, v3, v2
	v_cvt_pk_bf16_f32 v3, v3, s0
	global_store_short v[0:1], v3, off offset:2048
	v_mul_f32_e32 v3, v53, v2
	v_cvt_pk_bf16_f32 v3, v3, s0
	global_store_short v[0:1], v3, off offset:2112
	v_mul_f32_e32 v3, v37, v2
	v_mul_f32_e32 v2, v19, v2
	v_cvt_pk_bf16_f32 v3, v3, s0
	v_cvt_pk_bf16_f32 v2, v2, s0
	global_store_short v[0:1], v3, off offset:2176
	global_store_short v[0:1], v2, off offset:2240
.LBB0_271:
	s_or_b64 exec, exec, s[6:7]
	v_or_b32_e32 v0, 8, v80
	v_cmp_gt_i32_e32 vcc, 32, v0
	s_and_saveexec_b64 s[6:7], vcc
	s_cbranch_execz .LBB0_273
	s_waitcnt lgkmcnt(0)
	v_rcp_f32_e32 v2, v74
	v_ashrrev_i32_e32 v1, 31, v0
	v_lshlrev_b64 v[0:1], 12, v[0:1]
	v_lshl_add_u64 v[0:1], v[78:79], 0, v[0:1]
	v_mul_f32_e32 v3, v4, v2
	v_cvt_pk_bf16_f32 v3, v3, s0
	global_store_short v[0:1], v3, off offset:2048
	v_mul_f32_e32 v3, v54, v2
	v_cvt_pk_bf16_f32 v3, v3, s0
	global_store_short v[0:1], v3, off offset:2112
	v_mul_f32_e32 v3, v38, v2
	v_mul_f32_e32 v2, v20, v2
	v_cvt_pk_bf16_f32 v3, v3, s0
	v_cvt_pk_bf16_f32 v2, v2, s0
	global_store_short v[0:1], v3, off offset:2176
	global_store_short v[0:1], v2, off offset:2240
.LBB0_273:
	s_or_b64 exec, exec, s[6:7]
	v_or_b32_e32 v0, 9, v80
	v_cmp_gt_i32_e32 vcc, 32, v0
	s_and_saveexec_b64 s[6:7], vcc
	s_cbranch_execz .LBB0_275
	s_waitcnt lgkmcnt(0)
	v_rcp_f32_e32 v2, v75
	v_ashrrev_i32_e32 v1, 31, v0
	v_lshlrev_b64 v[0:1], 12, v[0:1]
	v_lshl_add_u64 v[0:1], v[78:79], 0, v[0:1]
	v_mul_f32_e32 v3, v5, v2
	v_cvt_pk_bf16_f32 v3, v3, s0
	global_store_short v[0:1], v3, off offset:2048
	v_mul_f32_e32 v3, v55, v2
	v_cvt_pk_bf16_f32 v3, v3, s0
	global_store_short v[0:1], v3, off offset:2112
	v_mul_f32_e32 v3, v39, v2
	v_mul_f32_e32 v2, v21, v2
	v_cvt_pk_bf16_f32 v3, v3, s0
	v_cvt_pk_bf16_f32 v2, v2, s0
	global_store_short v[0:1], v3, off offset:2176
	global_store_short v[0:1], v2, off offset:2240
.LBB0_275:
	s_or_b64 exec, exec, s[6:7]
	v_or_b32_e32 v0, 10, v80
	v_cmp_gt_i32_e32 vcc, 32, v0
	s_and_saveexec_b64 s[6:7], vcc
	s_cbranch_execz .LBB0_277
	s_waitcnt lgkmcnt(0)
	v_rcp_f32_e32 v2, v76
	v_ashrrev_i32_e32 v1, 31, v0
	v_lshlrev_b64 v[0:1], 12, v[0:1]
	v_lshl_add_u64 v[0:1], v[78:79], 0, v[0:1]
	v_mul_f32_e32 v3, v6, v2
	v_cvt_pk_bf16_f32 v3, v3, s0
	global_store_short v[0:1], v3, off offset:2048
	v_mul_f32_e32 v3, v56, v2
	v_cvt_pk_bf16_f32 v3, v3, s0
	global_store_short v[0:1], v3, off offset:2112
	v_mul_f32_e32 v3, v40, v2
	v_mul_f32_e32 v2, v22, v2
	v_cvt_pk_bf16_f32 v3, v3, s0
	v_cvt_pk_bf16_f32 v2, v2, s0
	global_store_short v[0:1], v3, off offset:2176
	global_store_short v[0:1], v2, off offset:2240
; DEVI int crow(int r, int hi) { return (r & 3) + 8 * (r >> 2) + 4 * hi; }
; template <bool MLA> ...
;     ...
;   if (wact) {
;     float rli[16];
;     if (MLA) {
;       if (hi == 0) al_l[r32] = l_reg;
;       asm volatile("s_waitcnt lgkmcnt(0)" ::: "memory");
; #pragma unroll
;       for (int r = 0; r < 16; ++r) rli[r] = __builtin_amdgcn_rcpf(al_l[crow(r, hi)]);
;     } else {
; #pragma unroll
;       for (int r = 0; r < 16; ++r) rli[r] = 1.f;
;     }
; #pragma unroll
;     for (int r = 0; r < 16; ++r) { const int orow = first + crow(r, hi);
;       if (orow < nrows) {
; #pragma unroll
;         for (int d0 = 0; d0 < 4; ++d0) Ob[(long)orow * ldo + d0 * 32 + r32] = __float2bfloat16(o[d0][r] * rli[r]); } }
.LBB0_277:
	s_or_b64 exec, exec, s[6:7]
	v_or_b32_e32 v0, 11, v80
	v_cmp_gt_i32_e32 vcc, 32, v0
	s_and_saveexec_b64 s[6:7], vcc
	s_cbranch_execz .LBB0_279
	s_waitcnt lgkmcnt(0)
	v_rcp_f32_e32 v2, v77
	v_ashrrev_i32_e32 v1, 31, v0
	v_lshlrev_b64 v[0:1], 12, v[0:1]
	v_lshl_add_u64 v[0:1], v[78:79], 0, v[0:1]
	v_mul_f32_e32 v3, v7, v2
	v_cvt_pk_bf16_f32 v3, v3, s0
	global_store_short v[0:1], v3, off offset:2048
	v_mul_f32_e32 v3, v57, v2
	v_cvt_pk_bf16_f32 v3, v3, s0
	global_store_short v[0:1], v3, off offset:2112
	v_mul_f32_e32 v3, v41, v2
	v_mul_f32_e32 v2, v23, v2
	v_cvt_pk_bf16_f32 v3, v3, s0
	v_cvt_pk_bf16_f32 v2, v2, s0
	global_store_short v[0:1], v3, off offset:2176
	global_store_short v[0:1], v2, off offset:2240
.LBB0_279:
	s_or_b64 exec, exec, s[6:7]
	v_or_b32_e32 v0, 16, v80
	v_cmp_gt_i32_e32 vcc, 32, v0
	s_and_saveexec_b64 s[6:7], vcc
	s_cbranch_execz .LBB0_281
	s_waitcnt lgkmcnt(0)
	v_rcp_f32_e32 v2, v70
	v_ashrrev_i32_e32 v1, 31, v0
	v_lshlrev_b64 v[0:1], 12, v[0:1]
	v_lshl_add_u64 v[0:1], v[78:79], 0, v[0:1]
	v_mul_f32_e32 v3, v8, v2
	v_cvt_pk_bf16_f32 v3, v3, s0
	global_store_short v[0:1], v3, off offset:2048
	v_mul_f32_e32 v3, v58, v2
	v_cvt_pk_bf16_f32 v3, v3, s0
	global_store_short v[0:1], v3, off offset:2112
	v_mul_f32_e32 v3, v42, v2
	v_mul_f32_e32 v2, v24, v2
	v_cvt_pk_bf16_f32 v3, v3, s0
	v_cvt_pk_bf16_f32 v2, v2, s0
	global_store_short v[0:1], v3, off offset:2176
	global_store_short v[0:1], v2, off offset:2240
.LBB0_281:
	s_or_b64 exec, exec, s[6:7]
	v_or_b32_e32 v0, 17, v80
	v_cmp_gt_i32_e32 vcc, 32, v0
	s_and_saveexec_b64 s[6:7], vcc
	s_cbranch_execz .LBB0_283
	s_waitcnt lgkmcnt(0)
	v_rcp_f32_e32 v2, v71
	v_ashrrev_i32_e32 v1, 31, v0
	v_lshlrev_b64 v[0:1], 12, v[0:1]
	v_lshl_add_u64 v[0:1], v[78:79], 0, v[0:1]
	v_mul_f32_e32 v3, v9, v2
	v_cvt_pk_bf16_f32 v3, v3, s0
	global_store_short v[0:1], v3, off offset:2048
	v_mul_f32_e32 v3, v59, v2
	v_cvt_pk_bf16_f32 v3, v3, s0
	global_store_short v[0:1], v3, off offset:2112
	v_mul_f32_e32 v3, v43, v2
	v_mul_f32_e32 v2, v25, v2
	v_cvt_pk_bf16_f32 v3, v3, s0
	v_cvt_pk_bf16_f32 v2, v2, s0
	global_store_short v[0:1], v3, off offset:2176
	global_store_short v[0:1], v2, off offset:2240
.LBB0_283:
	s_or_b64 exec, exec, s[6:7]
	v_or_b32_e32 v0, 18, v80
	v_cmp_gt_i32_e32 vcc, 32, v0
	s_and_saveexec_b64 s[6:7], vcc
	s_cbranch_execz .LBB0_285
	s_waitcnt lgkmcnt(0)
	v_rcp_f32_e32 v2, v72
	v_ashrrev_i32_e32 v1, 31, v0
	v_lshlrev_b64 v[0:1], 12, v[0:1]
	v_lshl_add_u64 v[0:1], v[78:79], 0, v[0:1]
	v_mul_f32_e32 v3, v10, v2
	v_cvt_pk_bf16_f32 v3, v3, s0
	global_store_short v[0:1], v3, off offset:2048
	v_mul_f32_e32 v3, v60, v2
	v_cvt_pk_bf16_f32 v3, v3, s0
	global_store_short v[0:1], v3, off offset:2112
	v_mul_f32_e32 v3, v44, v2
	v_mul_f32_e32 v2, v26, v2
	v_cvt_pk_bf16_f32 v3, v3, s0
	v_cvt_pk_bf16_f32 v2, v2, s0
	global_store_short v[0:1], v3, off offset:2176
	global_store_short v[0:1], v2, off offset:2240
.LBB0_285:
	s_or_b64 exec, exec, s[6:7]
	v_or_b32_e32 v0, 19, v80
	v_cmp_gt_i32_e32 vcc, 32, v0
	s_and_saveexec_b64 s[6:7], vcc
	s_cbranch_execz .LBB0_287
	s_waitcnt lgkmcnt(0)
	v_rcp_f32_e32 v2, v73
	v_ashrrev_i32_e32 v1, 31, v0
	v_lshlrev_b64 v[0:1], 12, v[0:1]
	v_lshl_add_u64 v[0:1], v[78:79], 0, v[0:1]
	v_mul_f32_e32 v3, v11, v2
	v_cvt_pk_bf16_f32 v3, v3, s0
	global_store_short v[0:1], v3, off offset:2048
	v_mul_f32_e32 v3, v61, v2
	v_cvt_pk_bf16_f32 v3, v3, s0
	global_store_short v[0:1], v3, off offset:2112
	v_mul_f32_e32 v3, v45, v2
	v_mul_f32_e32 v2, v27, v2
	v_cvt_pk_bf16_f32 v3, v3, s0
	v_cvt_pk_bf16_f32 v2, v2, s0
	global_store_short v[0:1], v3, off offset:2176
	global_store_short v[0:1], v2, off offset:2240
.LBB0_287:
	s_or_b64 exec, exec, s[6:7]
	v_or_b32_e32 v0, 24, v80
	v_cmp_gt_i32_e32 vcc, 32, v0
	s_and_saveexec_b64 s[6:7], vcc
	s_cbranch_execz .LBB0_289
	s_waitcnt lgkmcnt(0)
	v_rcp_f32_e32 v2, v66
	v_ashrrev_i32_e32 v1, 31, v0
	v_lshlrev_b64 v[0:1], 12, v[0:1]
	v_lshl_add_u64 v[0:1], v[78:79], 0, v[0:1]
	v_mul_f32_e32 v3, v12, v2
	v_cvt_pk_bf16_f32 v3, v3, s0
	global_store_short v[0:1], v3, off offset:2048
	v_mul_f32_e32 v3, v62, v2
	v_cvt_pk_bf16_f32 v3, v3, s0
	global_store_short v[0:1], v3, off offset:2112
	v_mul_f32_e32 v3, v46, v2
	v_mul_f32_e32 v2, v28, v2
	v_cvt_pk_bf16_f32 v3, v3, s0
	v_cvt_pk_bf16_f32 v2, v2, s0
	global_store_short v[0:1], v3, off offset:2176
	global_store_short v[0:1], v2, off offset:2240
.LBB0_289:
	s_or_b64 exec, exec, s[6:7]
	v_or_b32_e32 v0, 25, v80
	v_cmp_gt_i32_e32 vcc, 32, v0
	s_and_saveexec_b64 s[6:7], vcc
	s_cbranch_execz .LBB0_291
	s_waitcnt lgkmcnt(0)
	v_rcp_f32_e32 v2, v67
	v_ashrrev_i32_e32 v1, 31, v0
	v_lshlrev_b64 v[0:1], 12, v[0:1]
	v_lshl_add_u64 v[0:1], v[78:79], 0, v[0:1]
	v_mul_f32_e32 v3, v13, v2
	v_cvt_pk_bf16_f32 v3, v3, s0
	global_store_short v[0:1], v3, off offset:2048
	v_mul_f32_e32 v3, v63, v2
	v_cvt_pk_bf16_f32 v3, v3, s0
	global_store_short v[0:1], v3, off offset:2112
	v_mul_f32_e32 v3, v47, v2
	v_mul_f32_e32 v2, v29, v2
	v_cvt_pk_bf16_f32 v3, v3, s0
	v_cvt_pk_bf16_f32 v2, v2, s0
	global_store_short v[0:1], v3, off offset:2176
	global_store_short v[0:1], v2, off offset:2240
.LBB0_291:
	s_or_b64 exec, exec, s[6:7]
	v_or_b32_e32 v0, 26, v80
	v_cmp_gt_i32_e32 vcc, 32, v0
	s_and_saveexec_b64 s[6:7], vcc
	s_cbranch_execz .LBB0_293
	s_waitcnt lgkmcnt(0)
	v_rcp_f32_e32 v2, v68
	v_ashrrev_i32_e32 v1, 31, v0
	v_lshlrev_b64 v[0:1], 12, v[0:1]
	v_lshl_add_u64 v[0:1], v[78:79], 0, v[0:1]
	v_mul_f32_e32 v3, v14, v2
	v_cvt_pk_bf16_f32 v3, v3, s0
	global_store_short v[0:1], v3, off offset:2048
	v_mul_f32_e32 v3, v64, v2
	v_cvt_pk_bf16_f32 v3, v3, s0
	global_store_short v[0:1], v3, off offset:2112
	v_mul_f32_e32 v3, v48, v2
	v_mul_f32_e32 v2, v30, v2
	v_cvt_pk_bf16_f32 v3, v3, s0
	v_cvt_pk_bf16_f32 v2, v2, s0
	global_store_short v[0:1], v3, off offset:2176
	global_store_short v[0:1], v2, off offset:2240
.LBB0_293:
	s_or_b64 exec, exec, s[6:7]
	v_or_b32_e32 v0, 27, v80
	v_cmp_gt_i32_e32 vcc, 32, v0
	s_and_b64 exec, exec, vcc
	s_cbranch_execz .LBB0_295
	s_waitcnt lgkmcnt(0)
	v_rcp_f32_e32 v2, v69
	v_ashrrev_i32_e32 v1, 31, v0
	v_lshlrev_b64 v[0:1], 12, v[0:1]
	v_lshl_add_u64 v[0:1], v[78:79], 0, v[0:1]
	v_mul_f32_e32 v3, v15, v2
	v_cvt_pk_bf16_f32 v3, v3, s0
	global_store_short v[0:1], v3, off offset:2048
	v_mul_f32_e32 v3, v65, v2
	v_cvt_pk_bf16_f32 v3, v3, s0
	global_store_short v[0:1], v3, off offset:2112
	v_mul_f32_e32 v3, v49, v2
	v_mul_f32_e32 v2, v31, v2
	v_cvt_pk_bf16_f32 v3, v3, s0
	v_cvt_pk_bf16_f32 v2, v2, s0
	global_store_short v[0:1], v3, off offset:2176
	global_store_short v[0:1], v2, off offset:2240

; template <bool MLA> ...
;     ...
;   int tid = get_tid(wave_u);
;   const int wid = tid >> 6, lane = tid & 63, r32 = lane & 31, hi = lane >> 5;
;   char* V_lds = lds; char* K_lds = lds + 2 * SHM_V;
;   float* al_l = (float*)(lds + 2 * SHM_V + 2 * SHM_K) + wid * 64;
;   const int first = wid * 32; const bool wact = first < nrows;
;   const int lastv = min(first + 31, nrows - 1);
;   const int rowc = min(first + r32, nrows - 1);
;   const int qpos = qpos0 + rowc;
;   int bound, bmax, bmin;
;   if (MLA) { bound = min(64 * (qpos / 64 + 1), nk); bmax = min(64 * ((qpos0 + lastv) / 64 + 1), nk); bmin = min(64 * ((qpos0 + first) / 64 + 1), nk); }
;   else { bound = qpos; bmax = qpos0 + lastv; bmin = qpos0 + first; }
;   if (!wact) bmax = 0;
; DEVI void run_phase(const int ph, const Params& P, char* shmc, const int wave_u) {
;     ...
;         const int c = it - 1024; const int type = c >> 7, b = (c >> 3) & 15, h = c & 7;
;         const long tok0 = MP + (long)b * DSEQ; const long kb0 = (long)b * SKS;
;         if (type == 0)
;           attn_item<false>(sbq + tok0 * 1024 + h * 128, 1024, sbk_s + kb0 * 1024 + h * 128, 1024, nullptr,
;                            sbv_s + kb0 * 1024 + h * 128, 1024, ocat + tok0 * 2048 + h * 128, 2048, PAST, DSEQ, PAST + DSEQ, 17, shmc, wave_u);
;         else
;           attn_item<true>(qm + tok0 * 1536 + h * 192, 1536, kn_s + kb0 * 1024 + h * 128, 1024, kr_s + kb0 * 64,
;                           vm_s + kb0 * 1024 + h * 128, 1024, ocat + tok0 * 2048 + 1024 + h * 128, 2048, PAST, DSEQ, PAST + DSEQ, 17, shmc, wave_u);
.LBB0_296:
	s_and_b64 vcc, exec, s[0:1]
	s_cbranch_vccz .LBB0_341
	s_and_b32 s0, s70, 7
	s_lshl_b32 s8, s0, 8
	s_lshl_b32 s0, s72, 11
	s_add_u32 s0, s82, s0
	s_addc_u32 s1, s83, 0
	s_lshl_b32 s38, s75, 7
	s_lshl_b32 s9, s75, 8
	s_add_u32 s6, s0, s9
	s_addc_u32 s7, s1, 0
	s_lshl_b32 s12, s22, 1
	v_readlane_b32 s0, v255, 29
	s_add_u32 s0, s0, s12
	v_readlane_b32 s1, v255, 30
	s_addc_u32 s1, s1, 0
	s_add_u32 s0, s0, s9
	s_addc_u32 s1, s1, 0
	v_readlane_b32 s4, v255, 31
	s_add_u32 s12, s4, s12
	v_readlane_b32 s4, v255, 32
	v_mbcnt_lo_u32_b32 v12, -1, 0
	v_mbcnt_hi_u32_b32 v12, -1, v12
	s_addc_u32 s13, s4, 0
	s_waitcnt vmcnt(0)
	v_or_b32_e32 v4, s5, v12
	v_ashrrev_i32_e32 v5, 1, v4
	s_movk_i32 s4, 0xffe0
	v_bfi_b32 v0, s4, v5, v12
	v_min_i32_e32 v0, 31, v0
	s_waitcnt lgkmcnt(0)
; DEVI int v_rd_base(int lane) { return ((lane & 3) << 3) | (((lane >> 2) & 3) << 6) | (((lane >> 4) & 1) << 5) | (((lane >> 5) & 1) << 8); }
; template <bool MLA> ...
;     ...
;   bf16x8 qr[ND0];
;   { const bf16* Qw = Qb + (long)rowc * ldq + hi * 8;
; #pragma unroll
;     for (int d0 = 0; d0 < ND0; ++d0) qr[d0] = *reinterpret_cast<const bf16x8*>(Qw + d0 * 16); }
;   f32x16 o[4];
; #pragma unroll
;   for (int d = 0; d < 4; ++d)
; #pragma unroll
;     for (int r = 0; r < 16; ++r) o[d][r] = 0.f;
;   float m_reg = -1e30f, l_reg = 0.f, Rsum = 1.f;
;   const int vb0 = (int)(uintptr_t)V_lds + v_rd_base(lane);
;   int kq4[4];
; #pragma unroll
;   for (int k = 0; k < 4; ++k) kq4[k] = ((((r32 & 7) ^ hi) ^ (k << 1)) << 4);
;     ...
;   int kt = nkt - 1;
;   TILE_DMA(kt * 64, 0);
	v_ashrrev_i32_e32 v1, 31, v0
	v_bfe_u32 v14, v12, 5, 1
	v_lshlrev_b64 v[2:3], 11, v[0:1]
	v_lshl_add_u64 v[2:3], s[6:7], 0, v[2:3]
	v_lshlrev_b32_e32 v32, 4, v14
	v_lshl_add_u64 v[2:3], v[2:3], 0, v[32:33]
	global_load_dwordx4 v[112:115], v[2:3], off
	global_load_dwordx4 v[116:119], v[2:3], off offset:32
	global_load_dwordx4 v[120:123], v[2:3], off offset:64
	global_load_dwordx4 v[124:127], v[2:3], off offset:96
	global_load_dwordx4 v[128:131], v[2:3], off offset:128
	global_load_dwordx4 v[132:135], v[2:3], off offset:160
	global_load_dwordx4 v[136:139], v[2:3], off offset:192
	global_load_dwordx4 v[140:143], v[2:3], off offset:224
	v_bitop3_b32 v2, v14, v12, 7 bitop3:0x78
	v_mov_b32_e32 v3, s5
	s_movk_i32 s4, 0x60
	v_lshlrev_b32_e32 v181, 4, v2
	v_lshlrev_b32_e32 v2, 3, v4
	v_bitop3_b32 v3, v12, s4, v3 bitop3:0xc8
	v_and_or_b32 v2, v2, 24, v3
	v_lshrrev_b32_e32 v3, 1, v4
	s_movk_i32 s39, 0x400
	v_bfe_u32 v16, v4, 2, 2
	v_and_b32_e32 v17, 8, v3
	v_lshlrev_b32_e32 v32, 1, v2
	v_ashrrev_i32_e32 v2, 4, v4
	v_or3_b32 v6, v17, v16, s39
	v_and_b32_e32 v18, -16, v2
	v_lshrrev_b32_e32 v2, 1, v2
	v_and_b32_e32 v19, 4, v2
	v_add_u32_e32 v2, v6, v18
	s_add_u32 s12, s12, s9
	v_and_b32_e32 v179, 0xffffffe0, v5
	v_or_b32_e32 v1, 31, v5
	v_cmp_gt_i32_e32 vcc, 32, v5
	v_lshlrev_b32_e32 v5, 4, v4
	v_or_b32_e32 v2, v2, v19
	s_addc_u32 s13, s13, 0
	v_ashrrev_i32_e32 v3, 31, v2
	v_add_u32_e32 v183, 16, v5
	v_lshl_add_u64 v[144:145], s[12:13], 0, v[32:33]
	v_lshlrev_b64 v[2:3], 11, v[2:3]
	v_readfirstlane_b32 s6, v183
	v_lshl_add_u64 v[2:3], v[144:145], 0, v[2:3]
	s_mov_b32 m0, s6
	v_add_u32_e32 v8, 0x2000, v5
	global_load_lds_dwordx4 v[2:3], off
	v_ashrrev_i32_e32 v2, 8, v8
	v_and_b32_e32 v20, -16, v2
	v_lshrrev_b32_e32 v2, 1, v2
	v_and_b32_e32 v21, 4, v2
	v_add_u32_e32 v2, v6, v20
	v_or_b32_e32 v2, v2, v21
	v_ashrrev_i32_e32 v3, 31, v2
	v_add_u32_e32 v6, 0x2000, v183
	v_lshlrev_b64 v[2:3], 11, v[2:3]
	v_readfirstlane_b32 s6, v6
	v_lshl_add_u64 v[2:3], v[144:145], 0, v[2:3]
	s_mov_b32 m0, s6
	s_movk_i32 s4, 0x70
	global_load_lds_dwordx4 v[2:3], off
	v_ashrrev_i32_e32 v2, 31, v4
	v_lshrrev_b32_e32 v2, 28, v2
	v_add_u32_e32 v3, v4, v2
	v_ashrrev_i32_e32 v2, 4, v3
	v_lshlrev_b32_e32 v4, 8, v2
	v_sub_u32_e32 v4, v5, v4
	v_bitop3_b32 v6, v4, v3, s4 bitop3:0x78
	v_ashrrev_i32_e32 v3, 31, v2
	v_ashrrev_i32_e32 v6, 1, v6
	v_lshlrev_b64 v[2:3], 11, v[2:3]
	v_ashrrev_i32_e32 v7, 31, v6
	v_lshl_add_u64 v[4:5], s[0:1], 0, v[2:3]
	v_lshlrev_b64 v[6:7], 1, v[6:7]
	v_add_u32_e32 v9, 0x8000, v183
	v_lshl_add_u64 v[4:5], v[4:5], 0, v[6:7]
	s_mov_b64 s[12:13], 0x200000
	v_readfirstlane_b32 s6, v9
	v_lshl_add_u64 v[4:5], v[4:5], 0, s[12:13]
	s_mov_b32 m0, s6
	v_add_u32_e32 v22, 0xa000, v183
	global_load_lds_dwordx4 v[4:5], off
	v_ashrrev_i32_e32 v4, 31, v8
	v_add_u32_sdwa v5, v8, v4 dst_sel:DWORD dst_unused:UNUSED_PAD src0_sel:DWORD src1_sel:BYTE_3
	v_ashrrev_i32_e32 v4, 8, v5
	v_and_b32_e32 v5, 0xffffff00, v5
	v_sub_u32_e32 v5, v8, v5
	v_lshlrev_b32_e32 v8, 4, v4
	v_bitop3_b32 v10, v5, v8, s4 bitop3:0x78
	v_ashrrev_i32_e32 v5, 31, v4
	v_ashrrev_i32_e32 v10, 1, v10
	v_lshlrev_b64 v[4:5], 11, v[4:5]
	v_ashrrev_i32_e32 v11, 31, v10
	v_lshl_add_u64 v[8:9], s[0:1], 0, v[4:5]
	v_lshlrev_b64 v[10:11], 1, v[10:11]
	v_lshl_add_u64 v[8:9], v[8:9], 0, v[10:11]
	v_readfirstlane_b32 s0, v22
	v_lshl_add_u64 v[8:9], v[8:9], 0, s[12:13]
	s_mov_b32 m0, s0
	v_min_i32_e32 v1, 31, v1
	global_load_lds_dwordx4 v[8:9], off
	v_add_u32_e32 v1, 0x400, v1
	v_lshlrev_b32_e32 v15, 1, v12
	v_cndmask_b32_e32 v180, 0, v1, vcc
	v_lshlrev_b32_e32 v1, 4, v12
	v_lshlrev_b32_e32 v8, 3, v12
	v_and_b32_e32 v9, 32, v15
	s_movk_i32 s0, 0x118
	s_cmp_lg_u32 16, -1
	v_and_b32_e32 v1, 0xc0, v1
	v_add_u32_e32 v149, 0x3de, v0
	v_add_u32_e32 v148, 0x3e0, v0
	v_add_u32_e32 v151, 0x3dd, v0
	v_add_u32_e32 v150, 0x3df, v0
	v_add_u32_e32 v153, 0x3d6, v0
	v_add_u32_e32 v152, 0x3d8, v0
	v_add_u32_e32 v155, 0x3d5, v0
	v_add_u32_e32 v154, 0x3d7, v0
	v_add_u32_e32 v197, 0x3d0, v0
	v_add_u32_e32 v198, 0x3cf, v0
	v_add_u32_e32 v199, 0x3ce, v0
	v_add_u32_e32 v200, 0x3cd, v0
	v_add_u32_e32 v157, 0x3c6, v0
	v_add_u32_e32 v156, 0x3c8, v0
	v_add_u32_e32 v159, 0x3c5, v0
	v_add_u32_e32 v158, 0x3c7, v0
	v_add_u32_e32 v161, 0x3fe, v0
	v_add_u32_e32 v160, 0x400, v0
	v_add_u32_e32 v163, 0x3fd, v0
	v_add_u32_e32 v162, 0x3ff, v0
	v_add_u32_e32 v165, 0x3f8, v0
	v_add_u32_e32 v164, 0x3f0, v0
	v_add_u32_e32 v167, 0x3f7, v0
	v_add_u32_e32 v166, 0x3ef, v0
	v_add_u32_e32 v169, 0x3f6, v0
	v_add_u32_e32 v168, 0x3ee, v0
	v_add_u32_e32 v171, 0x3f5, v0
	v_add_u32_e32 v170, 0x3ed, v0
	v_add_u32_e32 v201, 0x3e8, v0
	v_add_u32_e32 v202, 0x3e7, v0
	v_add_u32_e32 v203, 0x3e6, v0
	v_add_u32_e32 v204, 0x3e5, v0
	v_and_or_b32 v0, v8, s0, v9
	s_cselect_b32 s0, 16, 0
	v_add3_u32 v205, v1, s0, v0
	v_mad_u64_u32 v[0:1], s[0:1], s73, v189, v[4:5]
	v_or_b32_e32 v0, s8, v0
	v_lshl_add_u64 v[0:1], v[0:1], 0, v[10:11]
	v_lshl_add_u64 v[172:173], s[20:21], 0, v[0:1]
	v_mad_u64_u32 v[0:1], s[0:1], s73, v189, v[2:3]
	v_or_b32_e32 v0, s8, v0
	v_lshl_add_u64 v[0:1], v[0:1], 0, v[6:7]
	v_lshl_add_u64 v[174:175], s[20:21], 0, v[0:1]
	v_or_b32_e32 v0, v20, v17
	v_and_b32_e32 v13, 63, v12
	v_or3_b32 v206, v0, v21, v16
	v_or_b32_e32 v0, v18, v17
	v_mov_b32_e32 v32, v33
	v_mov_b32_e32 v46, v33
	v_mov_b32_e32 v47, v33
	v_and_b32_e32 v178, 31, v12
	v_cmp_gt_u32_e64 s[6:7], 32, v13
	v_lshlrev_b32_e32 v192, 2, v14
	v_or3_b32 v207, v0, v19, v16
	v_mov_b32_e32 v34, v33
	v_mov_b32_e32 v35, v33
	v_mov_b32_e32 v36, v33
	v_mov_b32_e32 v37, v33
	v_mov_b32_e32 v38, v33
	v_mov_b32_e32 v39, v33
	v_mov_b32_e32 v40, v33
	v_mov_b32_e32 v41, v33
	v_mov_b32_e32 v42, v33
	v_mov_b32_e32 v43, v33
	v_mov_b32_e32 v44, v33
	v_mov_b32_e32 v45, v33
	v_mov_b64_e32 v[62:63], v[46:47]
	v_mov_b64_e32 v[78:79], v[46:47]
	v_mov_b64_e32 v[0:1], v[32:33]
	v_mov_b64_e32 v[16:17], v[32:33]
	s_mov_b32 s68, 0
	v_xor_b32_e32 v182, 32, v181
	v_xor_b32_e32 v193, 64, v181
	v_xor_b32_e32 v194, 0x60, v181
	v_lshl_add_u32 v195, v178, 8, 16
	v_add_u32_e32 v196, 0x3c0, v179
	v_mov_b32_e32 v177, 1.0
	v_mov_b64_e32 v[60:61], v[44:45]
	v_mov_b64_e32 v[58:59], v[42:43]
	v_mov_b64_e32 v[56:57], v[40:41]
	v_mov_b64_e32 v[54:55], v[38:39]
	v_mov_b64_e32 v[52:53], v[36:37]
	v_mov_b64_e32 v[50:51], v[34:35]
	v_mov_b64_e32 v[48:49], v[32:33]
	v_mov_b64_e32 v[76:77], v[44:45]
	v_mov_b64_e32 v[74:75], v[42:43]
	v_mov_b64_e32 v[72:73], v[40:41]
	v_mov_b64_e32 v[70:71], v[38:39]
	v_mov_b64_e32 v[68:69], v[36:37]
	v_mov_b64_e32 v[66:67], v[34:35]
	v_mov_b64_e32 v[64:65], v[32:33]
	v_mov_b64_e32 v[2:3], v[34:35]
	v_mov_b64_e32 v[4:5], v[36:37]
	v_mov_b64_e32 v[6:7], v[38:39]
	v_mov_b64_e32 v[8:9], v[40:41]
	v_mov_b64_e32 v[10:11], v[42:43]
	v_mov_b64_e32 v[12:13], v[44:45]
	v_mov_b64_e32 v[14:15], v[46:47]
	v_mov_b64_e32 v[18:19], v[34:35]
	v_mov_b64_e32 v[20:21], v[36:37]
	v_mov_b64_e32 v[22:23], v[38:39]
	v_mov_b64_e32 v[24:25], v[40:41]
	v_mov_b64_e32 v[26:27], v[42:43]
	v_mov_b64_e32 v[28:29], v[44:45]
	v_mov_b64_e32 v[30:31], v[46:47]
	s_waitcnt vmcnt(0)
	s_branch .LBB0_300

; DEVI int crow(int r, int hi) { return (r & 3) + 8 * (r >> 2) + 4 * hi; }
; template <bool MLA> ...
;     ...
; #pragma unroll
;       for (int r = 0; r < 16; ++r) rli[r] = 1.f;
;     }
; #pragma unroll
;     for (int r = 0; r < 16; ++r) { const int orow = first + crow(r, hi);
;       if (orow < nrows) {
; #pragma unroll
;         for (int d0 = 0; d0 < 4; ++d0) Ob[(long)orow * ldo + d0 * 32 + r32] = __float2bfloat16(o[d0][r] * rli[r]); } }
.LBB0_307:
	s_and_saveexec_b64 s[0:1], vcc
	s_cbranch_execz .LBB0_340
	s_lshl_b32 s6, s72, 12
	v_readlane_b32 s4, v255, 25
	s_add_u32 s6, s4, s6
	v_readlane_b32 s4, v255, 44
	s_addc_u32 s7, s4, 0
	s_lshl_b32 s8, s38, 1
	s_add_u32 s6, s6, s8
	s_addc_u32 s7, s7, 0
	v_or_b32_e32 v36, v192, v179
	v_lshlrev_b32_e32 v32, 1, v178
	v_lshl_add_u64 v[34:35], s[6:7], 0, v[32:33]
	v_cmp_gt_i32_e32 vcc, 32, v36
	s_and_saveexec_b64 s[6:7], vcc
	s_cbranch_execz .LBB0_310
	v_ashrrev_i32_e32 v37, 31, v36
	v_lshlrev_b64 v[38:39], 12, v[36:37]
	v_cvt_pk_bf16_f32 v32, v48, s0
	v_lshl_add_u64 v[38:39], v[34:35], 0, v[38:39]
	v_cvt_pk_bf16_f32 v40, v64, s0
	v_cvt_pk_bf16_f32 v0, v0, s0
	v_cvt_pk_bf16_f32 v16, v16, s0
	global_store_short v[38:39], v32, off
	global_store_short v[38:39], v40, off offset:64
	global_store_short v[38:39], v0, off offset:128
	global_store_short v[38:39], v16, off offset:192
.LBB0_310:
	s_or_b64 exec, exec, s[6:7]
	v_or_b32_e32 v38, 1, v36
	v_cmp_gt_i32_e32 vcc, 32, v38
	s_and_saveexec_b64 s[6:7], vcc
	s_cbranch_execz .LBB0_312
	v_ashrrev_i32_e32 v39, 31, v38
	v_lshlrev_b64 v[38:39], 12, v[38:39]
	v_cvt_pk_bf16_f32 v0, v49, s0
	v_lshl_add_u64 v[38:39], v[34:35], 0, v[38:39]
	v_cvt_pk_bf16_f32 v16, v65, s0
	v_cvt_pk_bf16_f32 v1, v1, s0
	v_cvt_pk_bf16_f32 v17, v17, s0
	global_store_short v[38:39], v0, off
	global_store_short v[38:39], v16, off offset:64
	global_store_short v[38:39], v1, off offset:128
	global_store_short v[38:39], v17, off offset:192
.LBB0_312:
	s_or_b64 exec, exec, s[6:7]
	v_or_b32_e32 v0, 2, v36
	v_cmp_gt_i32_e32 vcc, 32, v0
	s_and_saveexec_b64 s[6:7], vcc
	s_cbranch_execz .LBB0_314
	v_ashrrev_i32_e32 v1, 31, v0
	v_lshlrev_b64 v[0:1], 12, v[0:1]
	v_cvt_pk_bf16_f32 v16, v50, s0
	v_lshl_add_u64 v[0:1], v[34:35], 0, v[0:1]
	v_cvt_pk_bf16_f32 v17, v66, s0
	v_cvt_pk_bf16_f32 v2, v2, s0
	v_cvt_pk_bf16_f32 v18, v18, s0
	global_store_short v[0:1], v16, off
	global_store_short v[0:1], v17, off offset:64
	global_store_short v[0:1], v2, off offset:128
	global_store_short v[0:1], v18, off offset:192
.LBB0_314:
	s_or_b64 exec, exec, s[6:7]
	v_or_b32_e32 v0, 3, v36
	v_cmp_gt_i32_e32 vcc, 32, v0
	s_and_saveexec_b64 s[6:7], vcc
	s_cbranch_execz .LBB0_316
	v_ashrrev_i32_e32 v1, 31, v0
	v_lshlrev_b64 v[0:1], 12, v[0:1]
	v_cvt_pk_bf16_f32 v2, v51, s0
	v_lshl_add_u64 v[0:1], v[34:35], 0, v[0:1]
	v_cvt_pk_bf16_f32 v16, v67, s0
	v_cvt_pk_bf16_f32 v3, v3, s0
	v_cvt_pk_bf16_f32 v17, v19, s0
	global_store_short v[0:1], v2, off
	global_store_short v[0:1], v16, off offset:64
	global_store_short v[0:1], v3, off offset:128
	global_store_short v[0:1], v17, off offset:192
.LBB0_316:
	s_or_b64 exec, exec, s[6:7]
	v_or_b32_e32 v0, 8, v36
	v_cmp_gt_i32_e32 vcc, 32, v0
	s_and_saveexec_b64 s[6:7], vcc
	s_cbranch_execz .LBB0_318
	v_ashrrev_i32_e32 v1, 31, v0
	v_lshlrev_b64 v[0:1], 12, v[0:1]
	v_cvt_pk_bf16_f32 v2, v52, s0
	v_lshl_add_u64 v[0:1], v[34:35], 0, v[0:1]
	v_cvt_pk_bf16_f32 v3, v68, s0
	v_cvt_pk_bf16_f32 v4, v4, s0
	v_cvt_pk_bf16_f32 v16, v20, s0
	global_store_short v[0:1], v2, off
	global_store_short v[0:1], v3, off offset:64
	global_store_short v[0:1], v4, off offset:128
	global_store_short v[0:1], v16, off offset:192
.LBB0_318:
	s_or_b64 exec, exec, s[6:7]
	v_or_b32_e32 v0, 9, v36
	v_cmp_gt_i32_e32 vcc, 32, v0
	s_and_saveexec_b64 s[6:7], vcc
	s_cbranch_execz .LBB0_320
	v_ashrrev_i32_e32 v1, 31, v0
	v_lshlrev_b64 v[0:1], 12, v[0:1]
	v_cvt_pk_bf16_f32 v2, v53, s0
	v_lshl_add_u64 v[0:1], v[34:35], 0, v[0:1]
	v_cvt_pk_bf16_f32 v3, v69, s0
	v_cvt_pk_bf16_f32 v4, v5, s0
	v_cvt_pk_bf16_f32 v5, v21, s0
	global_store_short v[0:1], v2, off
	global_store_short v[0:1], v3, off offset:64
	global_store_short v[0:1], v4, off offset:128
	global_store_short v[0:1], v5, off offset:192
.LBB0_320:
	s_or_b64 exec, exec, s[6:7]
	v_or_b32_e32 v0, 10, v36
	v_cmp_gt_i32_e32 vcc, 32, v0
	s_and_saveexec_b64 s[6:7], vcc
	s_cbranch_execz .LBB0_322
	v_ashrrev_i32_e32 v1, 31, v0
	v_lshlrev_b64 v[0:1], 12, v[0:1]
	v_cvt_pk_bf16_f32 v2, v54, s0
	v_lshl_add_u64 v[0:1], v[34:35], 0, v[0:1]
	v_cvt_pk_bf16_f32 v3, v70, s0
	v_cvt_pk_bf16_f32 v4, v6, s0
	v_cvt_pk_bf16_f32 v5, v22, s0
	global_store_short v[0:1], v2, off
	global_store_short v[0:1], v3, off offset:64
	global_store_short v[0:1], v4, off offset:128
	global_store_short v[0:1], v5, off offset:192
.LBB0_322:
	s_or_b64 exec, exec, s[6:7]
	v_or_b32_e32 v0, 11, v36
	v_cmp_gt_i32_e32 vcc, 32, v0
	s_and_saveexec_b64 s[6:7], vcc
	s_cbranch_execz .LBB0_324
	v_ashrrev_i32_e32 v1, 31, v0
	v_lshlrev_b64 v[0:1], 12, v[0:1]
	v_cvt_pk_bf16_f32 v2, v55, s0
	v_lshl_add_u64 v[0:1], v[34:35], 0, v[0:1]
	v_cvt_pk_bf16_f32 v3, v71, s0
	v_cvt_pk_bf16_f32 v4, v7, s0
	v_cvt_pk_bf16_f32 v5, v23, s0
	global_store_short v[0:1], v2, off
	global_store_short v[0:1], v3, off offset:64
	global_store_short v[0:1], v4, off offset:128
	global_store_short v[0:1], v5, off offset:192
; DEVI int crow(int r, int hi) { return (r & 3) + 8 * (r >> 2) + 4 * hi; }
; template <bool MLA> ...
;     ...
; #pragma unroll
;     for (int r = 0; r < 16; ++r) { const int orow = first + crow(r, hi);
;       if (orow < nrows) {
; #pragma unroll
;         for (int d0 = 0; d0 < 4; ++d0) Ob[(long)orow * ldo + d0 * 32 + r32] = __float2bfloat16(o[d0][r] * rli[r]); } }
.LBB0_324:
	s_or_b64 exec, exec, s[6:7]
	v_or_b32_e32 v0, 16, v36
	v_cmp_gt_i32_e32 vcc, 32, v0
	s_and_saveexec_b64 s[6:7], vcc
	s_cbranch_execz .LBB0_326
	v_ashrrev_i32_e32 v1, 31, v0
	v_lshlrev_b64 v[0:1], 12, v[0:1]
	v_cvt_pk_bf16_f32 v2, v56, s0
	v_lshl_add_u64 v[0:1], v[34:35], 0, v[0:1]
	v_cvt_pk_bf16_f32 v3, v72, s0
	v_cvt_pk_bf16_f32 v4, v8, s0
	v_cvt_pk_bf16_f32 v5, v24, s0
	global_store_short v[0:1], v2, off
	global_store_short v[0:1], v3, off offset:64
	global_store_short v[0:1], v4, off offset:128
	global_store_short v[0:1], v5, off offset:192
.LBB0_326:
	s_or_b64 exec, exec, s[6:7]
	v_or_b32_e32 v0, 17, v36
	v_cmp_gt_i32_e32 vcc, 32, v0
	s_and_saveexec_b64 s[6:7], vcc
	s_cbranch_execz .LBB0_328
	v_ashrrev_i32_e32 v1, 31, v0
	v_lshlrev_b64 v[0:1], 12, v[0:1]
	v_cvt_pk_bf16_f32 v2, v57, s0
	v_lshl_add_u64 v[0:1], v[34:35], 0, v[0:1]
	v_cvt_pk_bf16_f32 v3, v73, s0
	v_cvt_pk_bf16_f32 v4, v9, s0
	v_cvt_pk_bf16_f32 v5, v25, s0
	global_store_short v[0:1], v2, off
	global_store_short v[0:1], v3, off offset:64
	global_store_short v[0:1], v4, off offset:128
	global_store_short v[0:1], v5, off offset:192
.LBB0_328:
	s_or_b64 exec, exec, s[6:7]
	v_or_b32_e32 v0, 18, v36
	v_cmp_gt_i32_e32 vcc, 32, v0
	s_and_saveexec_b64 s[6:7], vcc
	s_cbranch_execz .LBB0_330
	v_ashrrev_i32_e32 v1, 31, v0
	v_lshlrev_b64 v[0:1], 12, v[0:1]
	v_cvt_pk_bf16_f32 v2, v58, s0
	v_lshl_add_u64 v[0:1], v[34:35], 0, v[0:1]
	v_cvt_pk_bf16_f32 v3, v74, s0
	v_cvt_pk_bf16_f32 v4, v10, s0
	v_cvt_pk_bf16_f32 v5, v26, s0
	global_store_short v[0:1], v2, off
	global_store_short v[0:1], v3, off offset:64
	global_store_short v[0:1], v4, off offset:128
	global_store_short v[0:1], v5, off offset:192
.LBB0_330:
	s_or_b64 exec, exec, s[6:7]
	v_or_b32_e32 v0, 19, v36
	v_cmp_gt_i32_e32 vcc, 32, v0
	s_and_saveexec_b64 s[6:7], vcc
	s_cbranch_execz .LBB0_332
	v_ashrrev_i32_e32 v1, 31, v0
	v_lshlrev_b64 v[0:1], 12, v[0:1]
	v_cvt_pk_bf16_f32 v2, v59, s0
	v_lshl_add_u64 v[0:1], v[34:35], 0, v[0:1]
	v_cvt_pk_bf16_f32 v3, v75, s0
	v_cvt_pk_bf16_f32 v4, v11, s0
	v_cvt_pk_bf16_f32 v5, v27, s0
	global_store_short v[0:1], v2, off
	global_store_short v[0:1], v3, off offset:64
	global_store_short v[0:1], v4, off offset:128
	global_store_short v[0:1], v5, off offset:192
.LBB0_332:
	s_or_b64 exec, exec, s[6:7]
	v_or_b32_e32 v0, 24, v36
	v_cmp_gt_i32_e32 vcc, 32, v0
	s_and_saveexec_b64 s[6:7], vcc
	s_cbranch_execz .LBB0_334
	v_ashrrev_i32_e32 v1, 31, v0
	v_lshlrev_b64 v[0:1], 12, v[0:1]
	v_cvt_pk_bf16_f32 v2, v60, s0
	v_lshl_add_u64 v[0:1], v[34:35], 0, v[0:1]
	v_cvt_pk_bf16_f32 v3, v76, s0
	v_cvt_pk_bf16_f32 v4, v12, s0
	v_cvt_pk_bf16_f32 v5, v28, s0
	global_store_short v[0:1], v2, off
	global_store_short v[0:1], v3, off offset:64
	global_store_short v[0:1], v4, off offset:128
	global_store_short v[0:1], v5, off offset:192
.LBB0_334:
	s_or_b64 exec, exec, s[6:7]
	v_or_b32_e32 v0, 25, v36
	v_cmp_gt_i32_e32 vcc, 32, v0
	s_and_saveexec_b64 s[6:7], vcc
	s_cbranch_execz .LBB0_336
	v_ashrrev_i32_e32 v1, 31, v0
	v_lshlrev_b64 v[0:1], 12, v[0:1]
	v_cvt_pk_bf16_f32 v2, v61, s0
	v_lshl_add_u64 v[0:1], v[34:35], 0, v[0:1]
	v_cvt_pk_bf16_f32 v3, v77, s0
	v_cvt_pk_bf16_f32 v4, v13, s0
	v_cvt_pk_bf16_f32 v5, v29, s0
	global_store_short v[0:1], v2, off
	global_store_short v[0:1], v3, off offset:64
	global_store_short v[0:1], v4, off offset:128
	global_store_short v[0:1], v5, off offset:192
.LBB0_336:
	s_or_b64 exec, exec, s[6:7]
	v_or_b32_e32 v0, 26, v36
	v_cmp_gt_i32_e32 vcc, 32, v0
	s_and_saveexec_b64 s[6:7], vcc
	s_cbranch_execz .LBB0_338
	v_ashrrev_i32_e32 v1, 31, v0
	v_lshlrev_b64 v[0:1], 12, v[0:1]
	v_cvt_pk_bf16_f32 v2, v62, s0
	v_lshl_add_u64 v[0:1], v[34:35], 0, v[0:1]
	v_cvt_pk_bf16_f32 v3, v78, s0
	v_cvt_pk_bf16_f32 v4, v14, s0
	v_cvt_pk_bf16_f32 v5, v30, s0
	global_store_short v[0:1], v2, off
	global_store_short v[0:1], v3, off offset:64
	global_store_short v[0:1], v4, off offset:128
	global_store_short v[0:1], v5, off offset:192
.LBB0_338:
	s_or_b64 exec, exec, s[6:7]
	v_or_b32_e32 v0, 27, v36
	v_cmp_gt_i32_e32 vcc, 32, v0
	s_and_b64 exec, exec, vcc
	s_cbranch_execz .LBB0_340
	v_ashrrev_i32_e32 v1, 31, v0
	v_lshlrev_b64 v[0:1], 12, v[0:1]
	v_cvt_pk_bf16_f32 v2, v63, s0
	v_lshl_add_u64 v[0:1], v[34:35], 0, v[0:1]
	v_cvt_pk_bf16_f32 v3, v79, s0
	v_cvt_pk_bf16_f32 v4, v15, s0
	v_cvt_pk_bf16_f32 v5, v31, s0
	global_store_short v[0:1], v2, off
	global_store_short v[0:1], v3, off offset:64
	global_store_short v[0:1], v4, off offset:128
	global_store_short v[0:1], v5, off offset:192

; DEVI int v_rd_base(int lane) { return ((lane & 3) << 3) | (((lane >> 2) & 3) << 6) | (((lane >> 4) & 1) << 5) | (((lane >> 5) & 1) << 8); }
; template <bool MLA> ...
;     ...
;   bf16x8 qr[ND0];
;   { const bf16* Qw = Qb + (long)rowc * ldq + hi * 8;
; #pragma unroll
;     for (int d0 = 0; d0 < ND0; ++d0) qr[d0] = *reinterpret_cast<const bf16x8*>(Qw + d0 * 16); }
;   f32x16 o[4];
; #pragma unroll
;   for (int d = 0; d < 4; ++d)
; #pragma unroll
;     for (int r = 0; r < 16; ++r) o[d][r] = 0.f;
;   float m_reg = -1e30f, l_reg = 0.f, Rsum = 1.f;
;   const int vb0 = (int)(uintptr_t)V_lds + v_rd_base(lane);
;   int kq4[4];
; #pragma unroll
;   for (int k = 0; k < 4; ++k) kq4[k] = ((((r32 & 7) ^ hi) ^ (k << 1)) << 4);
; DEVI void run_phase(const int ph, const Params& P, char* shmc, const int wave_u) {
;     ...
;     for (int it = blockIdx.x; it < 1280; it += G) {
;       if (it < 1024) {
;         const int r = it >> 8, w = it & 255, p = w >> 6, c = w & 63;
;         const int qb = (r == 0) ? 15 - p : (r == 1) ? 8 + p : (r == 2) ? 7 - p : p;
;         const int type = c >> 5, b = (c >> 3) & 3, h = c & 7;
;         const long tok0 = (long)b * SEQ; const int q0 = qb * 256;
;         if (type == 0)
;           attn_item<false>(sbq + (tok0 + q0) * 1024 + h * 128, 1024, sbk_p + tok0 * 1024 + h * 128, 1024, nullptr,
;                            sbv_p + tok0 * 1024 + h * 128, 1024, ocat + (tok0 + q0) * 2048 + h * 128, 2048, q0, 256, SEQ, 4 * qb + 4, shmc, wave_u);
;         else
;           attn_item<true>(qm + (tok0 + q0) * 1536 + h * 192, 1536, kn_p + tok0 * 1024 + h * 128, 1024, kr_p + tok0 * 64,
;                           vm_p + tok0 * 1024 + h * 128, 1024, ocat + (tok0 + q0) * 2048 + 1024 + h * 128, 2048, q0, 256, SEQ, 4 * qb + 4, shmc, wave_u);
.LBB0_351:
	s_lshl_b32 s0, s71, 9
	s_and_b32 s6, s0, 0x3000
	s_lshl_b32 s72, s73, 8
	v_readlane_b32 s8, v254, 47
	v_readlane_b32 s9, v254, 48
	s_add_i32 s8, s72, s6
	s_and_b32 s75, s71, 7
	s_and_b32 s0, s71, 32
	v_writelane_b32 v254, s8, 47
	s_lshl_b32 s92, s6, 10
	s_cmp_lg_u32 s0, 0
	v_writelane_b32 v254, s9, 48
	s_mov_b64 s[0:1], -1
	s_cbranch_scc0 .LBB0_424
	v_readlane_b32 s8, v254, 47
	v_readlane_b32 s9, v254, 48
	s_mul_hi_u32 s0, s8, 0xc00
	s_mul_i32 s1, s8, 0xc00
	v_readlane_b32 s8, v255, 17
	v_readlane_b32 s9, v255, 18
	s_add_u32 s1, s8, s1
	s_addc_u32 s7, s9, s0
	s_mul_i32 s0, s75, 0x180
	s_add_u32 s0, s1, s0
	s_addc_u32 s1, s7, 0
	s_lshl_b32 s7, s92, 1
	v_readlane_b32 s4, v255, 35
	s_add_u32 s8, s4, s7
	v_readlane_b32 s4, v255, 37
	s_addc_u32 s9, s4, 0
	s_lshl_b32 s12, s75, 8
	s_add_u32 s38, s8, s12
	s_addc_u32 s39, s9, 0
	s_lshl_b32 s6, s6, 7
	s_add_u32 s68, s16, s6
	s_addc_u32 s69, s17, 0
	v_readlane_b32 s4, v255, 40
	s_add_u32 s6, s4, s7
	v_readlane_b32 s4, v255, 41
	v_mbcnt_lo_u32_b32 v26, -1, 0
	v_mbcnt_hi_u32_b32 v26, -1, v26
	s_addc_u32 s7, s4, 0
	v_or_b32_e32 v27, s5, v26
	v_ashrrev_i32_e32 v28, 1, v27
	s_movk_i32 s4, 0xffe0
	s_waitcnt vmcnt(0)
	v_bfi_b32 v0, s4, v28, v26
	v_bfe_u32 v23, v26, 5, 1
	v_min_i32_e32 v29, 0xff, v0
	s_waitcnt lgkmcnt(0)
	v_mov_b64_e32 v[0:1], s[0:1]
	s_movk_i32 s0, 0xc00
	v_mad_i64_i32 v[0:1], s[0:1], v29, s0, v[0:1]
	v_lshlrev_b32_e32 v32, 4, v23
	v_lshl_add_u64 v[0:1], v[0:1], 0, v[32:33]
	global_load_dwordx4 v[142:145], v[0:1], off
	global_load_dwordx4 v[138:141], v[0:1], off offset:32
	global_load_dwordx4 v[134:137], v[0:1], off offset:64
	global_load_dwordx4 v[130:133], v[0:1], off offset:96
	global_load_dwordx4 v[126:129], v[0:1], off offset:128
	global_load_dwordx4 v[122:125], v[0:1], off offset:160
	global_load_dwordx4 v[118:121], v[0:1], off offset:192
	global_load_dwordx4 v[114:117], v[0:1], off offset:224
	global_load_dwordx4 v[110:113], v[0:1], off offset:256
	global_load_dwordx4 v[106:109], v[0:1], off offset:288
	global_load_dwordx4 v[102:105], v[0:1], off offset:320
	global_load_dwordx4 v[98:101], v[0:1], off offset:352
	v_mov_b32_e32 v1, s5
	s_movk_i32 s0, 0x60
	s_add_u32 s6, s6, s12
	v_lshlrev_b32_e32 v0, 3, v27
	v_bitop3_b32 v1, v26, s0, v1 bitop3:0xc8
	s_addc_u32 s7, s7, 0
	s_lshl_b32 s8, s73, 2
	v_and_or_b32 v0, v0, 24, v1
	v_lshrrev_b32_e32 v1, 1, v27
	s_or_b32 s93, s8, 3
	v_and_b32_e32 v19, 8, v1
	v_lshlrev_b32_e32 v0, 1, v0
	v_mov_b32_e32 v1, v33
	v_bfe_u32 v18, v27, 2, 2
	s_lshl_b32 s8, s93, 6
	v_lshl_add_u64 v[148:149], s[6:7], 0, v[0:1]
	v_ashrrev_i32_e32 v0, 4, v27
	v_or3_b32 v2, v19, v18, s8
	v_and_b32_e32 v20, -16, v0
	v_lshrrev_b32_e32 v0, 1, v0
	v_and_b32_e32 v21, 4, v0
	v_add_u32_e32 v0, v2, v20
	v_lshlrev_b32_e32 v8, 4, v27
	v_or_b32_e32 v0, v0, v21
	v_ashrrev_i32_e32 v1, 31, v0
	v_add_u32_e32 v209, 16, v8
	v_lshlrev_b64 v[0:1], 11, v[0:1]
	v_readfirstlane_b32 s0, v209
	v_lshl_add_u64 v[0:1], v[148:149], 0, v[0:1]
	s_mov_b32 m0, s0
	v_add_u32_e32 v9, 0x2000, v8
	global_load_lds_dwordx4 v[0:1], off
	v_ashrrev_i32_e32 v0, 8, v9
	v_and_b32_e32 v22, -16, v0
	v_lshrrev_b32_e32 v0, 1, v0
	v_and_b32_e32 v24, 4, v0
	v_add_u32_e32 v0, v2, v22
	v_or_b32_e32 v0, v0, v24
	v_ashrrev_i32_e32 v1, 31, v0
	v_add_u32_e32 v2, 0x2000, v209
	v_lshlrev_b64 v[0:1], 11, v[0:1]
	v_readfirstlane_b32 s0, v2
	v_lshl_add_u64 v[0:1], v[148:149], 0, v[0:1]
	s_mov_b32 m0, s0
	s_mov_b32 s0, 0x2aaaaaab
	global_load_lds_dwordx4 v[0:1], off
	v_mul_hi_i32 v0, v27, s0
	v_lshrrev_b32_e32 v1, 31, v0
	v_ashrrev_i32_e32 v0, 2, v0
	v_add_u32_e32 v25, v0, v1
	s_movk_i32 s0, 0xfe80
	v_mad_u64_u32 v[0:1], s[0:1], v25, s0, v[8:9]
	v_lshlrev_b32_e32 v1, 4, v25
	s_movk_i32 s0, 0x70
	v_bitop3_b32 v2, v0, v1, s0 bitop3:0x78
	s_movk_i32 s0, 0xff
	v_add_u32_e32 v6, s8, v25
	v_cmp_gt_i32_e32 vcc, s95, v2
	v_cmp_lt_i32_e64 s[0:1], s0, v2
	v_ashrrev_i32_e32 v7, 31, v6
	v_add_u32_e32 v0, 0xffffff00, v2
	s_and_saveexec_b64 s[6:7], s[0:1]
	s_xor_b64 s[0:1], exec, s[6:7]
	v_lshlrev_b64 v[4:5], 7, v[6:7]
	v_lshl_add_u64 v[4:5], s[68:69], 0, v[4:5]
	v_mov_b32_e32 v1, v33
	v_lshl_add_u64 v[4:5], v[4:5], 0, v[0:1]
	s_or_saveexec_b64 s[0:1], s[0:1]
	v_ashrrev_i32_e32 v2, 1, v2
	v_ashrrev_i32_e32 v3, 31, v2
	s_xor_b64 exec, exec, s[0:1]
	v_lshlrev_b64 v[4:5], 11, v[6:7]
	v_lshl_add_u64 v[4:5], s[38:39], 0, v[4:5]
	v_lshl_add_u64 v[4:5], v[2:3], 1, v[4:5]
	s_or_b64 exec, exec, s[0:1]
	v_add_u32_e32 v1, 0x8000, v209
	s_movk_i32 s6, 0xff
	v_readfirstlane_b32 s0, v1
	s_mov_b32 m0, s0
	s_mov_b32 s0, 0x2aaaaaab
	global_load_lds_dwordx4 v[4:5], off
	v_mul_hi_i32 v1, v9, s0
	v_lshrrev_b32_e32 v4, 31, v1
	v_ashrrev_i32_e32 v1, 6, v1
	v_add_u32_e32 v30, v1, v4
	s_movk_i32 s0, 0xfe80
	v_mad_i32_i24 v1, v30, s0, v9
	v_lshlrev_b32_e32 v4, 4, v30
	s_movk_i32 s0, 0x70
	v_bitop3_b32 v1, v1, v4, s0 bitop3:0x78
	v_add_u32_e32 v12, s8, v30
	s_movk_i32 s4, 0x100
	v_cmp_gt_i32_e64 s[0:1], s95, v1
	v_cmp_lt_i32_e64 s[6:7], s6, v1
	v_ashrrev_i32_e32 v13, 31, v12
	v_add_u32_e32 v4, 0xffffff00, v1
	s_and_saveexec_b64 s[12:13], s[6:7]
	s_xor_b64 s[6:7], exec, s[12:13]
	v_lshlrev_b64 v[6:7], 7, v[12:13]
	v_lshl_add_u64 v[6:7], s[68:69], 0, v[6:7]
	v_mov_b32_e32 v5, v33
	v_lshl_add_u64 v[10:11], v[6:7], 0, v[4:5]
	s_or_saveexec_b64 s[6:7], s[6:7]
	v_ashrrev_i32_e32 v6, 1, v1
	v_ashrrev_i32_e32 v7, 31, v6
	s_xor_b64 exec, exec, s[6:7]
	v_lshlrev_b64 v[10:11], 11, v[12:13]
	v_lshl_add_u64 v[10:11], s[38:39], 0, v[10:11]
	v_lshl_add_u64 v[10:11], v[6:7], 1, v[10:11]
	s_or_b64 exec, exec, s[6:7]
	v_add_u32_e32 v1, 0xa000, v209
	s_nop 0
	v_readfirstlane_b32 s6, v1
	s_mov_b32 m0, s6
	v_add_u32_e32 v1, 0x4000, v8
	global_load_lds_dwordx4 v[10:11], off
; DEVI int v_rd_base(int lane) { return ((lane & 3) << 3) | (((lane >> 2) & 3) << 6) | (((lane >> 4) & 1) << 5) | (((lane >> 5) & 1) << 8); }
; template <bool MLA> ...
;     ...
;   float* al_l = (float*)(lds + 2 * SHM_V + 2 * SHM_K) + wid * 64;
;   const int first = wid * 32; const bool wact = first < nrows;
;   const int lastv = min(first + 31, nrows - 1);
;   const int rowc = min(first + r32, nrows - 1);
;   const int qpos = qpos0 + rowc;
;   int bound, bmax, bmin;
;   if (MLA) { bound = min(64 * (qpos / 64 + 1), nk); bmax = min(64 * ((qpos0 + lastv) / 64 + 1), nk); bmin = min(64 * ((qpos0 + first) / 64 + 1), nk); }
;   else { bound = qpos; bmax = qpos0 + lastv; bmin = qpos0 + first; }
;   if (!wact) bmax = 0;
;   bf16x8 qr[ND0];
;   { const bf16* Qw = Qb + (long)rowc * ldq + hi * 8;
; #pragma unroll
;     for (int d0 = 0; d0 < ND0; ++d0) qr[d0] = *reinterpret_cast<const bf16x8*>(Qw + d0 * 16); }
;   f32x16 o[4];
; #pragma unroll
;   for (int d = 0; d < 4; ++d)
; #pragma unroll
;     for (int r = 0; r < 16; ++r) o[d][r] = 0.f;
;   float m_reg = -1e30f, l_reg = 0.f, Rsum = 1.f;
;   const int vb0 = (int)(uintptr_t)V_lds + v_rd_base(lane);
;   int kq4[4];
; #pragma unroll
;   for (int k = 0; k < 4; ++k) kq4[k] = ((((r32 & 7) ^ hi) ^ (k << 1)) << 4);
;     ...
;   int kt = nkt - 1;
;   TILE_DMA(kt * 64, 0);
	s_mov_b32 s6, 0x2aaaaaab
	v_mul_hi_i32 v5, v1, s6
	v_lshrrev_b32_e32 v8, 31, v5
	v_ashrrev_i32_e32 v5, 6, v5
	v_add_u32_e32 v31, v5, v8
	s_movk_i32 s6, 0xfe80
	v_mad_i32_i24 v1, v31, s6, v1
	v_lshlrev_b32_e32 v5, 4, v31
	s_movk_i32 s6, 0x70
	v_bitop3_b32 v1, v1, v5, s6 bitop3:0x78
	v_cmp_gt_i32_e64 s[12:13], s4, v1
	s_movk_i32 s4, 0xff
	v_add_u32_e32 v14, s8, v31
	v_add_u32_e32 v16, 0xffffff00, v1
	v_cmp_lt_i32_e64 s[6:7], s4, v1
	v_ashrrev_i32_e32 v15, 31, v14
	v_lshrrev_b32_e32 v8, 1, v16
	s_and_saveexec_b64 s[8:9], s[6:7]
	s_xor_b64 s[6:7], exec, s[8:9]
	v_lshlrev_b64 v[10:11], 7, v[14:15]
	v_lshl_add_u64 v[10:11], s[68:69], 0, v[10:11]
	v_mov_b32_e32 v17, v33
	v_mov_b32_e32 v9, v33
	v_lshl_add_u64 v[12:13], v[10:11], 0, v[16:17]
	v_lshrrev_b32_e32 v10, 1, v1
	v_mov_b32_e32 v11, v33
	s_or_saveexec_b64 s[6:7], s[6:7]
	s_lshl_b32 s22, s75, 7
	v_mov_b64_e32 v[150:151], 7
	s_xor_b64 exec, exec, s[6:7]
	v_lshlrev_b64 v[10:11], 11, v[14:15]
	v_lshl_add_u64 v[12:13], s[38:39], 0, v[10:11]
	v_ashrrev_i32_e32 v10, 1, v1
	v_ashrrev_i32_e32 v11, 31, v10
	v_lshl_add_u64 v[12:13], v[10:11], 1, v[12:13]
	v_mov_b32_e32 v9, v33
	v_mov_b64_e32 v[150:151], 11
	s_or_b64 exec, exec, s[6:7]
	v_or_b32_e32 v14, 31, v28
	v_add_u32_e32 v15, s72, v29
	v_min_i32_e32 v14, 0xff, v14
	v_ashrrev_i32_e32 v16, 31, v15
	v_lshrrev_b32_e32 v16, 26, v16
	v_add_u32_e32 v14, s72, v14
	v_add_u32_e32 v15, v15, v16
	v_ashrrev_i32_e32 v16, 31, v14
	v_and_b32_e32 v153, 0xffffffe0, v28
	v_lshrrev_b32_e32 v16, 26, v16
	v_add_u32_e32 v14, v14, v16
	v_add_u32_e32 v16, s72, v153
	v_ashrrev_i32_e32 v17, 31, v16
	v_lshrrev_b32_e32 v17, 26, v17
	v_add_u32_e32 v16, v16, v17
	v_add_u32_e32 v17, 0xc000, v209
	v_and_b32_e32 v1, 63, v26
	v_readfirstlane_b32 s8, v17
	s_mov_b32 m0, s8
	v_and_b32_e32 v5, 0x3fffffc0, v27
	global_load_lds_dwordx4 v[12:13], off
	v_and_b32_e32 v16, 0xffffffc0, v16
	v_and_b32_e32 v14, 0xffffffc0, v14
	v_add_u32_e32 v208, 64, v16
	v_lshl_add_u32 v157, v5, 2, s74
	v_lshlrev_b32_e32 v5, 4, v1
	v_bitop3_b32 v16, v23, v26, 7 bitop3:0x78
	v_min_i32_e32 v14, 0xfc0, v14
	s_movk_i32 s95, 0x100
	v_lshlrev_b32_e32 v213, 4, v16
	v_and_b32_e32 v16, 0xc0, v5
	v_lshlrev_b32_e32 v5, 3, v1
	v_add_u32_e32 v14, 64, v14
	v_cmp_gt_i32_e64 s[6:7], s95, v153
	v_and_b32_e32 v12, 0x118, v5
	v_mov_b32_e32 v5, v33
	v_cndmask_b32_e64 v215, 0, v14, s[6:7]
	v_lshlrev_b32_e32 v14, 1, v1
	v_lshl_add_u64 v[4:5], s[68:69], 0, v[4:5]
	v_lshl_add_u64 v[6:7], v[6:7], 1, s[38:39]
	s_cmp_lg_u32 16, -1
	v_and_or_b32 v12, v14, 32, v12
	v_cndmask_b32_e64 v156, 7, 11, s[0:1]
	v_cndmask_b32_e64 v159, v5, v7, s[0:1]
	v_cndmask_b32_e64 v158, v4, v6, s[0:1]
	s_cselect_b32 s0, 16, 0
	v_lshlrev_b32_e32 v162, 2, v23
	v_cmp_gt_u32_e64 s[8:9], 32, v1
	v_mov_b32_e32 v1, v33
	v_add3_u32 v164, v16, s0, v12
	s_add_i32 s0, s72, 0xc0
	v_and_b32_e32 v15, 0xffffffc0, v15
	v_lshl_add_u64 v[0:1], s[68:69], 0, v[0:1]
	v_lshl_add_u64 v[2:3], v[2:3], 1, s[38:39]
	v_add_u32_e32 v217, s0, v162
	s_add_i32 s0, s72, 0x80
	v_min_i32_e32 v15, 0xfc0, v15
	v_cndmask_b32_e32 v154, v0, v2, vcc
	v_add3_u32 v0, s0, v22, v19
	v_add_u32_e32 v192, 64, v15
	v_lshl_add_u64 v[8:9], v[8:9], 1, s[68:69]
	v_lshl_add_u64 v[10:11], v[10:11], 1, s[38:39]
	v_or_b32_e32 v207, 32, v15
	v_or_b32_e32 v206, 63, v15
	v_or_b32_e32 v205, 31, v15
	v_or_b32_e32 v204, 62, v15
	v_or_b32_e32 v203, 30, v15
	v_or_b32_e32 v202, 61, v15
	v_or_b32_e32 v201, 29, v15
	v_or_b32_e32 v200, 56, v15
	v_or_b32_e32 v199, 24, v15
	v_or_b32_e32 v198, 55, v15
	v_or_b32_e32 v197, 23, v15
	v_or_b32_e32 v196, 54, v15
	v_or_b32_e32 v195, 22, v15
	v_or_b32_e32 v194, 53, v15
	v_or_b32_e32 v193, 21, v15
	v_or_b32_e32 v183, 48, v15
	v_or_b32_e32 v182, 16, v15
	v_or_b32_e32 v181, 47, v15
	v_or_b32_e32 v180, 15, v15
	v_or_b32_e32 v179, 46, v15
	v_or_b32_e32 v178, 14, v15
	v_or_b32_e32 v177, 45, v15
	v_or_b32_e32 v176, 13, v15
	v_or_b32_e32 v175, 40, v15
	v_or_b32_e32 v174, 8, v15
	v_or_b32_e32 v173, 39, v15
	v_or_b32_e32 v172, 7, v15
	v_or_b32_e32 v171, 38, v15
	v_or_b32_e32 v170, 6, v15
	v_or_b32_e32 v169, 37, v15
	v_or_b32_e32 v168, 5, v15
	v_add3_u32 v221, v0, v24, v18
	v_add3_u32 v0, s0, v20, v19
	v_mov_b32_e32 v14, v33
	v_mov_b32_e32 v15, v33
	v_and_b32_e32 v151, 31, v26
	s_movk_i32 s4, 0x180
	v_lshl_add_u32 v165, v23, 4, v157
	v_cndmask_b32_e32 v155, v1, v3, vcc
	v_cndmask_b32_e64 v161, v9, v11, s[12:13]
	v_cndmask_b32_e64 v160, v8, v10, s[12:13]
	v_add_u32_e32 v218, s0, v31
	v_add_u32_e32 v219, s0, v30
	v_add_u32_e32 v220, s0, v25
	v_add3_u32 v222, v0, v21, v18
	v_mov_b32_e32 v0, v33
	v_mov_b32_e32 v1, v33
	v_mov_b32_e32 v2, v33
	v_mov_b32_e32 v3, v33
	v_mov_b32_e32 v4, v33
	v_mov_b32_e32 v5, v33
	v_mov_b32_e32 v6, v33
	v_mov_b32_e32 v7, v33
	v_mov_b32_e32 v8, v33
	v_mov_b32_e32 v9, v33
	v_mov_b32_e32 v10, v33
	v_mov_b32_e32 v11, v33
	v_mov_b32_e32 v12, v33
	v_mov_b32_e32 v13, v33
	v_mov_b64_e32 v[64:65], v[14:15]
	v_mov_b64_e32 v[48:49], v[14:15]
	v_mov_b64_e32 v[30:31], v[14:15]
	v_min_i32_e32 v214, 0x1000, v208
	s_mov_b32 s94, 0
	v_xor_b32_e32 v212, 32, v213
	v_xor_b32_e32 v211, 64, v213
	v_xor_b32_e32 v210, 0x60, v213
	v_mad_u32_u24 v216, v151, s4, 16
	v_lshl_add_u32 v163, v151, 2, v157
	v_cndmask_b32_e64 v152, 7, 11, vcc
	v_mov_b32_e32 v166, 0
	v_mov_b32_e32 v167, 0xf149f2ca
	v_mov_b64_e32 v[62:63], v[12:13]
	v_mov_b64_e32 v[60:61], v[10:11]
	v_mov_b64_e32 v[58:59], v[8:9]
	v_mov_b64_e32 v[56:57], v[6:7]
	v_mov_b64_e32 v[54:55], v[4:5]
	v_mov_b64_e32 v[52:53], v[2:3]
	v_mov_b64_e32 v[50:51], v[0:1]
	v_mov_b64_e32 v[46:47], v[12:13]
	v_mov_b64_e32 v[44:45], v[10:11]
	v_mov_b64_e32 v[42:43], v[8:9]
	v_mov_b64_e32 v[40:41], v[6:7]
	v_mov_b64_e32 v[38:39], v[4:5]
	v_mov_b64_e32 v[36:37], v[2:3]
	v_mov_b64_e32 v[34:35], v[0:1]
	v_mov_b64_e32 v[28:29], v[12:13]
	v_mov_b64_e32 v[26:27], v[10:11]
	v_mov_b64_e32 v[24:25], v[8:9]
	v_mov_b64_e32 v[22:23], v[6:7]
	v_mov_b64_e32 v[20:21], v[4:5]
	v_mov_b64_e32 v[18:19], v[2:3]
	v_mov_b64_e32 v[16:17], v[0:1]
	s_mov_b32 s38, 0
	s_waitcnt vmcnt(0)
	s_branch .LBB0_368

; DEVI int crow(int r, int hi) { return (r & 3) + 8 * (r >> 2) + 4 * hi; }
; template <bool MLA> ...
;     ...
;   if (wact) {
;     float rli[16];
;     if (MLA) {
;       if (hi == 0) al_l[r32] = l_reg;
;       asm volatile("s_waitcnt lgkmcnt(0)" ::: "memory");
; #pragma unroll
;       for (int r = 0; r < 16; ++r) rli[r] = __builtin_amdgcn_rcpf(al_l[crow(r, hi)]);
;     } else {
; #pragma unroll
;       for (int r = 0; r < 16; ++r) rli[r] = 1.f;
;     }
; #pragma unroll
;     for (int r = 0; r < 16; ++r) { const int orow = first + crow(r, hi);
;       if (orow < nrows) {
; #pragma unroll
;         for (int d0 = 0; d0 < 4; ++d0) Ob[(long)orow * ldo + d0 * 32 + r32] = __float2bfloat16(o[d0][r] * rli[r]); } }
.LBB0_388:
	s_or_b64 exec, exec, s[0:1]
	s_and_saveexec_b64 s[0:1], s[6:7]
	s_cbranch_execz .LBB0_423
	s_and_saveexec_b64 s[6:7], s[8:9]
	ds_write_b32 v163, v166
	s_or_b64 exec, exec, s[6:7]
	s_waitcnt lgkmcnt(0)
	v_add_u32_e32 v81, v157, v32
	v_readlane_b32 s6, v254, 47
	ds_read2_b32 v[82:83], v81 offset0:1 offset1:2
	ds_read_b32 v86, v81 offset:12
	ds_read_b128 v[74:77], v81 offset:32
	ds_read_b128 v[70:73], v81 offset:64
	ds_read_b128 v[66:69], v81 offset:96
	v_readlane_b32 s7, v254, 48
	s_lshl_b64 s[6:7], s[6:7], 12
	v_readlane_b32 s4, v255, 25
	s_add_u32 s6, s4, s6
	v_readlane_b32 s4, v255, 44
	s_addc_u32 s7, s4, s7
	s_lshl_b32 s8, s22, 1
	s_add_u32 s6, s6, s8
	s_addc_u32 s7, s7, 0
	v_or_b32_e32 v80, v162, v153
	v_lshlrev_b32_e32 v32, 1, v151
	v_lshl_add_u64 v[78:79], s[6:7], 0, v[32:33]
	v_cmp_gt_i32_e32 vcc, s95, v80
	s_and_saveexec_b64 s[6:7], vcc
	s_cbranch_execz .LBB0_393
	ds_read_b32 v32, v81
	v_ashrrev_i32_e32 v81, 31, v80
	v_lshlrev_b64 v[84:85], 12, v[80:81]
	v_lshl_add_u64 v[84:85], v[78:79], 0, v[84:85]
	s_waitcnt lgkmcnt(0)
	v_rcp_f32_e32 v32, v32
	s_nop 0
	v_mul_f32_e32 v0, v0, v32
	v_mul_f32_e32 v50, v50, v32
	v_mul_f32_e32 v34, v34, v32
	v_cvt_pk_bf16_f32 v0, v0, s0
	v_cvt_pk_bf16_f32 v50, v50, s0
	global_store_short v[84:85], v0, off offset:2048
	global_store_short v[84:85], v50, off offset:2112
	v_cvt_pk_bf16_f32 v0, v34, s0
	global_store_short v[84:85], v0, off offset:2176
	v_mul_f32_e32 v0, v16, v32
	v_cvt_pk_bf16_f32 v0, v0, s0
	global_store_short v[84:85], v0, off offset:2240
.LBB0_393:
	s_or_b64 exec, exec, s[6:7]
	v_or_b32_e32 v84, 1, v80
	v_cmp_gt_i32_e32 vcc, s95, v84
	s_and_saveexec_b64 s[6:7], vcc
	s_cbranch_execz .LBB0_395
	s_waitcnt lgkmcnt(0)
	v_rcp_f32_e32 v0, v82
	v_ashrrev_i32_e32 v85, 31, v84
	v_lshlrev_b64 v[84:85], 12, v[84:85]
	v_lshl_add_u64 v[84:85], v[78:79], 0, v[84:85]
	v_mul_f32_e32 v1, v1, v0
	v_cvt_pk_bf16_f32 v1, v1, s0
	global_store_short v[84:85], v1, off offset:2048
	v_mul_f32_e32 v1, v51, v0
	v_cvt_pk_bf16_f32 v1, v1, s0
	global_store_short v[84:85], v1, off offset:2112
	v_mul_f32_e32 v1, v35, v0
	v_mul_f32_e32 v0, v17, v0
	v_cvt_pk_bf16_f32 v1, v1, s0
	v_cvt_pk_bf16_f32 v0, v0, s0
	global_store_short v[84:85], v1, off offset:2176
	global_store_short v[84:85], v0, off offset:2240
.LBB0_395:
	s_or_b64 exec, exec, s[6:7]
	v_or_b32_e32 v0, 2, v80
	v_cmp_gt_i32_e32 vcc, s95, v0
	s_and_saveexec_b64 s[6:7], vcc
	s_cbranch_execz .LBB0_397
	s_waitcnt lgkmcnt(0)
	v_rcp_f32_e32 v16, v83
	v_ashrrev_i32_e32 v1, 31, v0
	v_lshlrev_b64 v[0:1], 12, v[0:1]
	v_lshl_add_u64 v[0:1], v[78:79], 0, v[0:1]
	v_mul_f32_e32 v2, v2, v16
	v_cvt_pk_bf16_f32 v2, v2, s0
	global_store_short v[0:1], v2, off offset:2048
	v_mul_f32_e32 v2, v52, v16
	v_cvt_pk_bf16_f32 v2, v2, s0
	global_store_short v[0:1], v2, off offset:2112
	v_mul_f32_e32 v2, v36, v16
	v_cvt_pk_bf16_f32 v2, v2, s0
	global_store_short v[0:1], v2, off offset:2176
	v_mul_f32_e32 v2, v18, v16
	v_cvt_pk_bf16_f32 v2, v2, s0
	global_store_short v[0:1], v2, off offset:2240
.LBB0_397:
	s_or_b64 exec, exec, s[6:7]
	v_or_b32_e32 v0, 3, v80
	v_cmp_gt_i32_e32 vcc, s95, v0
	s_and_saveexec_b64 s[6:7], vcc
	s_cbranch_execz .LBB0_399
	s_waitcnt lgkmcnt(0)
	v_rcp_f32_e32 v2, v86
	v_ashrrev_i32_e32 v1, 31, v0
	v_lshlrev_b64 v[0:1], 12, v[0:1]
	v_lshl_add_u64 v[0:1], v[78:79], 0, v[0:1]
	v_mul_f32_e32 v3, v3, v2
	v_cvt_pk_bf16_f32 v3, v3, s0
	global_store_short v[0:1], v3, off offset:2048
	v_mul_f32_e32 v3, v53, v2
	v_cvt_pk_bf16_f32 v3, v3, s0
	global_store_short v[0:1], v3, off offset:2112
	v_mul_f32_e32 v3, v37, v2
	v_mul_f32_e32 v2, v19, v2
	v_cvt_pk_bf16_f32 v3, v3, s0
	v_cvt_pk_bf16_f32 v2, v2, s0
	global_store_short v[0:1], v3, off offset:2176
	global_store_short v[0:1], v2, off offset:2240
.LBB0_399:
	s_or_b64 exec, exec, s[6:7]
	v_or_b32_e32 v0, 8, v80
	v_cmp_gt_i32_e32 vcc, s95, v0
	s_and_saveexec_b64 s[6:7], vcc
	s_cbranch_execz .LBB0_401
	s_waitcnt lgkmcnt(0)
	v_rcp_f32_e32 v2, v74
	v_ashrrev_i32_e32 v1, 31, v0
	v_lshlrev_b64 v[0:1], 12, v[0:1]
	v_lshl_add_u64 v[0:1], v[78:79], 0, v[0:1]
	v_mul_f32_e32 v3, v4, v2
	v_cvt_pk_bf16_f32 v3, v3, s0
	global_store_short v[0:1], v3, off offset:2048
	v_mul_f32_e32 v3, v54, v2
	v_cvt_pk_bf16_f32 v3, v3, s0
	global_store_short v[0:1], v3, off offset:2112
	v_mul_f32_e32 v3, v38, v2
	v_mul_f32_e32 v2, v20, v2
	v_cvt_pk_bf16_f32 v3, v3, s0
	v_cvt_pk_bf16_f32 v2, v2, s0
	global_store_short v[0:1], v3, off offset:2176
	global_store_short v[0:1], v2, off offset:2240
.LBB0_401:
	s_or_b64 exec, exec, s[6:7]
	v_or_b32_e32 v0, 9, v80
	v_cmp_gt_i32_e32 vcc, s95, v0
	s_and_saveexec_b64 s[6:7], vcc
	s_cbranch_execz .LBB0_403
	s_waitcnt lgkmcnt(0)
	v_rcp_f32_e32 v2, v75
	v_ashrrev_i32_e32 v1, 31, v0
	v_lshlrev_b64 v[0:1], 12, v[0:1]
	v_lshl_add_u64 v[0:1], v[78:79], 0, v[0:1]
	v_mul_f32_e32 v3, v5, v2
	v_cvt_pk_bf16_f32 v3, v3, s0
	global_store_short v[0:1], v3, off offset:2048
	v_mul_f32_e32 v3, v55, v2
	v_cvt_pk_bf16_f32 v3, v3, s0
	global_store_short v[0:1], v3, off offset:2112
	v_mul_f32_e32 v3, v39, v2
	v_mul_f32_e32 v2, v21, v2
	v_cvt_pk_bf16_f32 v3, v3, s0
	v_cvt_pk_bf16_f32 v2, v2, s0
	global_store_short v[0:1], v3, off offset:2176
	global_store_short v[0:1], v2, off offset:2240
.LBB0_403:
	s_or_b64 exec, exec, s[6:7]
	v_or_b32_e32 v0, 10, v80
	v_cmp_gt_i32_e32 vcc, s95, v0
	s_and_saveexec_b64 s[6:7], vcc
	s_cbranch_execz .LBB0_405
	s_waitcnt lgkmcnt(0)
	v_rcp_f32_e32 v2, v76
	v_ashrrev_i32_e32 v1, 31, v0
	v_lshlrev_b64 v[0:1], 12, v[0:1]
	v_lshl_add_u64 v[0:1], v[78:79], 0, v[0:1]
	v_mul_f32_e32 v3, v6, v2
	v_cvt_pk_bf16_f32 v3, v3, s0
	global_store_short v[0:1], v3, off offset:2048
	v_mul_f32_e32 v3, v56, v2
	v_cvt_pk_bf16_f32 v3, v3, s0
	global_store_short v[0:1], v3, off offset:2112
	v_mul_f32_e32 v3, v40, v2
	v_mul_f32_e32 v2, v22, v2
	v_cvt_pk_bf16_f32 v3, v3, s0
	v_cvt_pk_bf16_f32 v2, v2, s0
	global_store_short v[0:1], v3, off offset:2176
	global_store_short v[0:1], v2, off offset:2240
; DEVI int crow(int r, int hi) { return (r & 3) + 8 * (r >> 2) + 4 * hi; }
; template <bool MLA> ...
;     ...
; #pragma unroll
;     for (int r = 0; r < 16; ++r) { const int orow = first + crow(r, hi);
;       if (orow < nrows) {
; #pragma unroll
;         for (int d0 = 0; d0 < 4; ++d0) Ob[(long)orow * ldo + d0 * 32 + r32] = __float2bfloat16(o[d0][r] * rli[r]); } }
.LBB0_405:
	s_or_b64 exec, exec, s[6:7]
	v_or_b32_e32 v0, 11, v80
	v_cmp_gt_i32_e32 vcc, s95, v0
	s_and_saveexec_b64 s[6:7], vcc
	s_cbranch_execz .LBB0_407
	s_waitcnt lgkmcnt(0)
	v_rcp_f32_e32 v2, v77
	v_ashrrev_i32_e32 v1, 31, v0
	v_lshlrev_b64 v[0:1], 12, v[0:1]
	v_lshl_add_u64 v[0:1], v[78:79], 0, v[0:1]
	v_mul_f32_e32 v3, v7, v2
	v_cvt_pk_bf16_f32 v3, v3, s0
	global_store_short v[0:1], v3, off offset:2048
	v_mul_f32_e32 v3, v57, v2
	v_cvt_pk_bf16_f32 v3, v3, s0
	global_store_short v[0:1], v3, off offset:2112
	v_mul_f32_e32 v3, v41, v2
	v_mul_f32_e32 v2, v23, v2
	v_cvt_pk_bf16_f32 v3, v3, s0
	v_cvt_pk_bf16_f32 v2, v2, s0
	global_store_short v[0:1], v3, off offset:2176
	global_store_short v[0:1], v2, off offset:2240
.LBB0_407:
	s_or_b64 exec, exec, s[6:7]
	v_or_b32_e32 v0, 16, v80
	v_cmp_gt_i32_e32 vcc, s95, v0
	s_and_saveexec_b64 s[6:7], vcc
	s_cbranch_execz .LBB0_409
	s_waitcnt lgkmcnt(0)
	v_rcp_f32_e32 v2, v70
	v_ashrrev_i32_e32 v1, 31, v0
	v_lshlrev_b64 v[0:1], 12, v[0:1]
	v_lshl_add_u64 v[0:1], v[78:79], 0, v[0:1]
	v_mul_f32_e32 v3, v8, v2
	v_cvt_pk_bf16_f32 v3, v3, s0
	global_store_short v[0:1], v3, off offset:2048
	v_mul_f32_e32 v3, v58, v2
	v_cvt_pk_bf16_f32 v3, v3, s0
	global_store_short v[0:1], v3, off offset:2112
	v_mul_f32_e32 v3, v42, v2
	v_mul_f32_e32 v2, v24, v2
	v_cvt_pk_bf16_f32 v3, v3, s0
	v_cvt_pk_bf16_f32 v2, v2, s0
	global_store_short v[0:1], v3, off offset:2176
	global_store_short v[0:1], v2, off offset:2240
.LBB0_409:
	s_or_b64 exec, exec, s[6:7]
	v_or_b32_e32 v0, 17, v80
	v_cmp_gt_i32_e32 vcc, s95, v0
	s_and_saveexec_b64 s[6:7], vcc
	s_cbranch_execz .LBB0_411
	s_waitcnt lgkmcnt(0)
	v_rcp_f32_e32 v2, v71
	v_ashrrev_i32_e32 v1, 31, v0
	v_lshlrev_b64 v[0:1], 12, v[0:1]
	v_lshl_add_u64 v[0:1], v[78:79], 0, v[0:1]
	v_mul_f32_e32 v3, v9, v2
	v_cvt_pk_bf16_f32 v3, v3, s0
	global_store_short v[0:1], v3, off offset:2048
	v_mul_f32_e32 v3, v59, v2
	v_cvt_pk_bf16_f32 v3, v3, s0
	global_store_short v[0:1], v3, off offset:2112
	v_mul_f32_e32 v3, v43, v2
	v_mul_f32_e32 v2, v25, v2
	v_cvt_pk_bf16_f32 v3, v3, s0
	v_cvt_pk_bf16_f32 v2, v2, s0
	global_store_short v[0:1], v3, off offset:2176
	global_store_short v[0:1], v2, off offset:2240
.LBB0_411:
	s_or_b64 exec, exec, s[6:7]
	v_or_b32_e32 v0, 18, v80
	v_cmp_gt_i32_e32 vcc, s95, v0
	s_and_saveexec_b64 s[6:7], vcc
	s_cbranch_execz .LBB0_413
	s_waitcnt lgkmcnt(0)
	v_rcp_f32_e32 v2, v72
	v_ashrrev_i32_e32 v1, 31, v0
	v_lshlrev_b64 v[0:1], 12, v[0:1]
	v_lshl_add_u64 v[0:1], v[78:79], 0, v[0:1]
	v_mul_f32_e32 v3, v10, v2
	v_cvt_pk_bf16_f32 v3, v3, s0
	global_store_short v[0:1], v3, off offset:2048
	v_mul_f32_e32 v3, v60, v2
	v_cvt_pk_bf16_f32 v3, v3, s0
	global_store_short v[0:1], v3, off offset:2112
	v_mul_f32_e32 v3, v44, v2
	v_mul_f32_e32 v2, v26, v2
	v_cvt_pk_bf16_f32 v3, v3, s0
	v_cvt_pk_bf16_f32 v2, v2, s0
	global_store_short v[0:1], v3, off offset:2176
	global_store_short v[0:1], v2, off offset:2240
.LBB0_413:
	s_or_b64 exec, exec, s[6:7]
	v_or_b32_e32 v0, 19, v80
	v_cmp_gt_i32_e32 vcc, s95, v0
	s_and_saveexec_b64 s[6:7], vcc
	s_cbranch_execz .LBB0_415
	s_waitcnt lgkmcnt(0)
	v_rcp_f32_e32 v2, v73
	v_ashrrev_i32_e32 v1, 31, v0
	v_lshlrev_b64 v[0:1], 12, v[0:1]
	v_lshl_add_u64 v[0:1], v[78:79], 0, v[0:1]
	v_mul_f32_e32 v3, v11, v2
	v_cvt_pk_bf16_f32 v3, v3, s0
	global_store_short v[0:1], v3, off offset:2048
	v_mul_f32_e32 v3, v61, v2
	v_cvt_pk_bf16_f32 v3, v3, s0
	global_store_short v[0:1], v3, off offset:2112
	v_mul_f32_e32 v3, v45, v2
	v_mul_f32_e32 v2, v27, v2
	v_cvt_pk_bf16_f32 v3, v3, s0
	v_cvt_pk_bf16_f32 v2, v2, s0
	global_store_short v[0:1], v3, off offset:2176
	global_store_short v[0:1], v2, off offset:2240
.LBB0_415:
	s_or_b64 exec, exec, s[6:7]
	v_or_b32_e32 v0, 24, v80
	v_cmp_gt_i32_e32 vcc, s95, v0
	s_and_saveexec_b64 s[6:7], vcc
	s_cbranch_execz .LBB0_417
	s_waitcnt lgkmcnt(0)
	v_rcp_f32_e32 v2, v66
	v_ashrrev_i32_e32 v1, 31, v0
	v_lshlrev_b64 v[0:1], 12, v[0:1]
	v_lshl_add_u64 v[0:1], v[78:79], 0, v[0:1]
	v_mul_f32_e32 v3, v12, v2
	v_cvt_pk_bf16_f32 v3, v3, s0
	global_store_short v[0:1], v3, off offset:2048
	v_mul_f32_e32 v3, v62, v2
	v_cvt_pk_bf16_f32 v3, v3, s0
	global_store_short v[0:1], v3, off offset:2112
	v_mul_f32_e32 v3, v46, v2
	v_mul_f32_e32 v2, v28, v2
	v_cvt_pk_bf16_f32 v3, v3, s0
	v_cvt_pk_bf16_f32 v2, v2, s0
	global_store_short v[0:1], v3, off offset:2176
	global_store_short v[0:1], v2, off offset:2240
.LBB0_417:
	s_or_b64 exec, exec, s[6:7]
	v_or_b32_e32 v0, 25, v80
	v_cmp_gt_i32_e32 vcc, s95, v0
	s_and_saveexec_b64 s[6:7], vcc
	s_cbranch_execz .LBB0_419
	s_waitcnt lgkmcnt(0)
	v_rcp_f32_e32 v2, v67
	v_ashrrev_i32_e32 v1, 31, v0
	v_lshlrev_b64 v[0:1], 12, v[0:1]
	v_lshl_add_u64 v[0:1], v[78:79], 0, v[0:1]
	v_mul_f32_e32 v3, v13, v2
	v_cvt_pk_bf16_f32 v3, v3, s0
	global_store_short v[0:1], v3, off offset:2048
	v_mul_f32_e32 v3, v63, v2
	v_cvt_pk_bf16_f32 v3, v3, s0
	global_store_short v[0:1], v3, off offset:2112
	v_mul_f32_e32 v3, v47, v2
	v_mul_f32_e32 v2, v29, v2
	v_cvt_pk_bf16_f32 v3, v3, s0
	v_cvt_pk_bf16_f32 v2, v2, s0
	global_store_short v[0:1], v3, off offset:2176
	global_store_short v[0:1], v2, off offset:2240
.LBB0_419:
	s_or_b64 exec, exec, s[6:7]
	v_or_b32_e32 v0, 26, v80
	v_cmp_gt_i32_e32 vcc, s95, v0
	s_and_saveexec_b64 s[6:7], vcc
	s_cbranch_execz .LBB0_421
	s_waitcnt lgkmcnt(0)
	v_rcp_f32_e32 v2, v68
	v_ashrrev_i32_e32 v1, 31, v0
	v_lshlrev_b64 v[0:1], 12, v[0:1]
	v_lshl_add_u64 v[0:1], v[78:79], 0, v[0:1]
	v_mul_f32_e32 v3, v14, v2
	v_cvt_pk_bf16_f32 v3, v3, s0
	global_store_short v[0:1], v3, off offset:2048
	v_mul_f32_e32 v3, v64, v2
	v_cvt_pk_bf16_f32 v3, v3, s0
	global_store_short v[0:1], v3, off offset:2112
	v_mul_f32_e32 v3, v48, v2
	v_mul_f32_e32 v2, v30, v2
	v_cvt_pk_bf16_f32 v3, v3, s0
	v_cvt_pk_bf16_f32 v2, v2, s0
	global_store_short v[0:1], v3, off offset:2176
	global_store_short v[0:1], v2, off offset:2240
.LBB0_421:
	s_or_b64 exec, exec, s[6:7]
	v_or_b32_e32 v0, 27, v80
	v_cmp_gt_i32_e32 vcc, s95, v0
	s_and_b64 exec, exec, vcc
	s_cbranch_execz .LBB0_423
	s_waitcnt lgkmcnt(0)
	v_rcp_f32_e32 v2, v69
	v_ashrrev_i32_e32 v1, 31, v0
	v_lshlrev_b64 v[0:1], 12, v[0:1]
	v_lshl_add_u64 v[0:1], v[78:79], 0, v[0:1]
	v_mul_f32_e32 v3, v15, v2
	v_cvt_pk_bf16_f32 v3, v3, s0
	global_store_short v[0:1], v3, off offset:2048
	v_mul_f32_e32 v3, v65, v2
	v_cvt_pk_bf16_f32 v3, v3, s0
	global_store_short v[0:1], v3, off offset:2112
	v_mul_f32_e32 v3, v49, v2
	v_mul_f32_e32 v2, v31, v2
	v_cvt_pk_bf16_f32 v3, v3, s0
	v_cvt_pk_bf16_f32 v2, v2, s0
	global_store_short v[0:1], v3, off offset:2176
	global_store_short v[0:1], v2, off offset:2240

; DEVI int v_rd_base(int lane) { return ((lane & 3) << 3) | (((lane >> 2) & 3) << 6) | (((lane >> 4) & 1) << 5) | (((lane >> 5) & 1) << 8); }
; template <bool MLA> ...
;     ...
;   bf16x8 qr[ND0];
;   { const bf16* Qw = Qb + (long)rowc * ldq + hi * 8;
; #pragma unroll
;     for (int d0 = 0; d0 < ND0; ++d0) qr[d0] = *reinterpret_cast<const bf16x8*>(Qw + d0 * 16); }
;   f32x16 o[4];
; #pragma unroll
;   for (int d = 0; d < 4; ++d)
; #pragma unroll
;     for (int r = 0; r < 16; ++r) o[d][r] = 0.f;
;   float m_reg = -1e30f, l_reg = 0.f, Rsum = 1.f;
;   const int vb0 = (int)(uintptr_t)V_lds + v_rd_base(lane);
;   int kq4[4];
; #pragma unroll
;   for (int k = 0; k < 4; ++k) kq4[k] = ((((r32 & 7) ^ hi) ^ (k << 1)) << 4);
;     ...
;   int kt = nkt - 1;
;   TILE_DMA(kt * 64, 0);
; DEVI void run_phase(const int ph, const Params& P, char* shmc, const int wave_u) {
;     ...
;           attn_item<false>(sbq + (tok0 + q0) * 1024 + h * 128, 1024, sbk_p + tok0 * 1024 + h * 128, 1024, nullptr,
;                            sbv_p + tok0 * 1024 + h * 128, 1024, ocat + (tok0 + q0) * 2048 + h * 128, 2048, q0, 256, SEQ, 4 * qb + 4, shmc, wave_u);
.LBB0_424:
	s_and_b64 vcc, exec, s[0:1]
	s_cbranch_vccz .LBB0_231
	v_readlane_b32 s0, v254, 47
	v_readlane_b32 s1, v254, 48
	s_lshl_b64 s[0:1], s[0:1], 11
	s_add_u32 s0, s82, s0
	s_addc_u32 s1, s83, s1
	s_lshl_b32 s38, s75, 7
	s_lshl_b32 s8, s75, 8
	s_add_u32 s6, s0, s8
	v_mbcnt_lo_u32_b32 v8, -1, 0
	v_mbcnt_hi_u32_b32 v8, -1, v8
	s_addc_u32 s7, s1, 0
	s_waitcnt vmcnt(0)
	v_or_b32_e32 v4, s5, v8
	s_lshl_b32 s9, s92, 1
	v_readlane_b32 s0, v255, 27
	v_ashrrev_i32_e32 v10, 1, v4
	s_movk_i32 s4, 0xffe0
	s_add_u32 s0, s0, s9
	v_readlane_b32 s1, v255, 28
	v_bfi_b32 v0, s4, v10, v8
	s_addc_u32 s1, s1, 0
	v_min_i32_e32 v0, 0xff, v0
	s_add_u32 s0, s0, s8
	s_waitcnt lgkmcnt(0)
	v_ashrrev_i32_e32 v1, 31, v0
	s_addc_u32 s1, s1, 0
	v_bfe_u32 v9, v8, 5, 1
	v_lshlrev_b64 v[2:3], 11, v[0:1]
	s_add_u32 s9, s84, s9
	v_lshl_add_u64 v[2:3], s[6:7], 0, v[2:3]
	v_lshlrev_b32_e32 v32, 4, v9
	s_addc_u32 s12, s85, 0
	v_lshl_add_u64 v[2:3], v[2:3], 0, v[32:33]
	s_add_u32 s8, s9, s8
	global_load_dwordx4 v[112:115], v[2:3], off
	global_load_dwordx4 v[116:119], v[2:3], off offset:32
	global_load_dwordx4 v[120:123], v[2:3], off offset:64
	global_load_dwordx4 v[124:127], v[2:3], off offset:96
	global_load_dwordx4 v[128:131], v[2:3], off offset:128
	global_load_dwordx4 v[132:135], v[2:3], off offset:160
	global_load_dwordx4 v[136:139], v[2:3], off offset:192
	global_load_dwordx4 v[140:143], v[2:3], off offset:224
	v_mov_b32_e32 v3, s5
	s_movk_i32 s4, 0x60
	s_addc_u32 s9, s12, 0
	s_lshl_b32 s12, s73, 2
	v_lshlrev_b32_e32 v2, 3, v4
	v_bitop3_b32 v3, v8, s4, v3 bitop3:0xc8
	s_or_b32 s39, s12, 3
	v_and_or_b32 v2, v2, 24, v3
	v_lshrrev_b32_e32 v3, 1, v4
	v_bfe_u32 v11, v4, 2, 2
	v_and_b32_e32 v12, 8, v3
	s_lshl_b32 s6, s39, 6
	v_lshlrev_b32_e32 v32, 1, v2
	v_ashrrev_i32_e32 v2, 4, v4
	v_or3_b32 v5, v12, v11, s6
	v_and_b32_e32 v13, -16, v2
	v_lshrrev_b32_e32 v2, 1, v2
	v_and_b32_e32 v14, 4, v2
	v_add_u32_e32 v2, v5, v13
	v_lshlrev_b32_e32 v1, 4, v4
	v_or_b32_e32 v2, v2, v14
	v_ashrrev_i32_e32 v3, 31, v2
	v_add_u32_e32 v156, 16, v1
	v_lshl_add_u64 v[144:145], s[8:9], 0, v[32:33]
	v_lshlrev_b64 v[2:3], 11, v[2:3]
	v_readfirstlane_b32 s7, v156
	v_lshl_add_u64 v[2:3], v[144:145], 0, v[2:3]
	s_mov_b32 m0, s7
	v_add_u32_e32 v6, 0x2000, v1
	global_load_lds_dwordx4 v[2:3], off
	v_ashrrev_i32_e32 v2, 8, v6
	v_and_b32_e32 v15, -16, v2
	v_lshrrev_b32_e32 v2, 1, v2
	v_and_b32_e32 v16, 4, v2
	v_add_u32_e32 v2, v5, v15
	v_or_b32_e32 v2, v2, v16
	v_ashrrev_i32_e32 v3, 31, v2
	v_add_u32_e32 v5, 0x2000, v156
	v_lshlrev_b64 v[2:3], 11, v[2:3]
	v_readfirstlane_b32 s7, v5
	v_lshl_add_u64 v[2:3], v[144:145], 0, v[2:3]
	s_mov_b32 m0, s7
	s_movk_i32 s4, 0x70
	global_load_lds_dwordx4 v[2:3], off
	v_ashrrev_i32_e32 v2, 31, v4
	v_lshrrev_b32_e32 v2, 28, v2
	v_add_u32_e32 v2, v4, v2
	v_ashrrev_i32_e32 v17, 4, v2
	v_lshlrev_b32_e32 v3, 8, v17
	v_sub_u32_e32 v1, v1, v3
	v_bitop3_b32 v1, v1, v2, s4 bitop3:0x78
	v_add_u32_e32 v2, s6, v17
	v_ashrrev_i32_e32 v3, 31, v2
	v_ashrrev_i32_e32 v4, 1, v1
	v_add_u32_e32 v1, 0x8000, v156
	v_lshlrev_b64 v[2:3], 11, v[2:3]
	v_ashrrev_i32_e32 v5, 31, v4
	v_readfirstlane_b32 s7, v1
	v_ashrrev_i32_e32 v1, 31, v6
	v_lshl_add_u64 v[2:3], s[0:1], 0, v[2:3]
	v_lshlrev_b64 v[4:5], 1, v[4:5]
	v_add_u32_sdwa v1, v6, v1 dst_sel:DWORD dst_unused:UNUSED_PAD src0_sel:DWORD src1_sel:BYTE_3
	v_lshl_add_u64 v[2:3], v[2:3], 0, v[4:5]
	s_mov_b32 m0, s7
	v_ashrrev_i32_e32 v18, 8, v1
	v_and_b32_e32 v1, 0xffffff00, v1
	global_load_lds_dwordx4 v[2:3], off
	v_sub_u32_e32 v1, v6, v1
	v_lshlrev_b32_e32 v2, 4, v18
	v_bitop3_b32 v1, v1, v2, s4 bitop3:0x78
	v_add_u32_e32 v2, s6, v18
	v_ashrrev_i32_e32 v3, 31, v2
	v_ashrrev_i32_e32 v6, 1, v1
	v_lshlrev_b64 v[2:3], 11, v[2:3]
	v_ashrrev_i32_e32 v7, 31, v6
	v_add_u32_e32 v1, 0xa000, v156
	v_lshl_add_u64 v[2:3], s[0:1], 0, v[2:3]
	v_lshlrev_b64 v[6:7], 1, v[6:7]
	v_readfirstlane_b32 s6, v1
	v_lshl_add_u64 v[2:3], v[2:3], 0, v[6:7]
	s_mov_b32 m0, s6
	v_add_u32_e32 v148, s72, v0
	global_load_lds_dwordx4 v[2:3], off
	v_or_b32_e32 v0, 31, v10
	v_and_b32_e32 v158, 0xffffffe0, v10
	v_min_i32_e32 v0, 0xff, v0
	v_add_u32_e32 v0, s72, v0
	v_cmp_gt_i32_e32 vcc, s95, v158
	v_lshlrev_b32_e32 v2, 1, v8
	v_bitop3_b32 v3, v9, v8, 7 bitop3:0x78
	v_and_b32_e32 v1, 63, v8
	v_cndmask_b32_e32 v161, 0, v0, vcc
	v_lshlrev_b32_e32 v0, 4, v8
	v_lshlrev_b32_e32 v162, 4, v3
	v_lshlrev_b32_e32 v3, 3, v8
	v_and_b32_e32 v2, 32, v2
	v_lshl_add_u64 v[150:151], s[0:1], 0, v[4:5]
	v_lshl_add_u64 v[152:153], s[0:1], 0, v[6:7]
	s_movk_i32 s0, 0x118
	s_cmp_lg_u32 16, -1
	v_and_b32_e32 v0, 0xc0, v0
	v_cmp_gt_u32_e64 s[6:7], 32, v1
	v_and_or_b32 v1, v3, s0, v2
	s_cselect_b32 s0, 16, 0
	v_add3_u32 v167, v0, s0, v1
	s_add_i32 s0, s72, 0x80
	v_add3_u32 v0, s0, v15, v12
	v_add3_u32 v171, v0, v16, v11
	v_add3_u32 v0, s0, v13, v12
	v_mov_b32_e32 v32, v33
	v_mov_b32_e32 v46, v33
	v_mov_b32_e32 v47, v33
	v_and_b32_e32 v157, 31, v8
	v_lshlrev_b32_e32 v159, 2, v9
	v_add_u32_e32 v169, s0, v18
	v_add_u32_e32 v170, s0, v17
	v_add3_u32 v172, v0, v14, v11
	v_mov_b32_e32 v34, v33
	v_mov_b32_e32 v35, v33
	v_mov_b32_e32 v36, v33
	v_mov_b32_e32 v37, v33
	v_mov_b32_e32 v38, v33
	v_mov_b32_e32 v39, v33
	v_mov_b32_e32 v40, v33
	v_mov_b32_e32 v41, v33
	v_mov_b32_e32 v42, v33
	v_mov_b32_e32 v43, v33
	v_mov_b32_e32 v44, v33
	v_mov_b32_e32 v45, v33
	v_mov_b64_e32 v[62:63], v[46:47]
	v_mov_b64_e32 v[78:79], v[46:47]
	v_mov_b64_e32 v[0:1], v[32:33]
	v_mov_b64_e32 v[16:17], v[32:33]
	v_add_u32_e32 v160, s72, v158
	s_mov_b32 s68, 0
	v_xor_b32_e32 v163, 32, v162
	v_xor_b32_e32 v164, 64, v162
	v_xor_b32_e32 v165, 0x60, v162
	v_lshl_add_u32 v166, v157, 8, 16
	v_mov_b32_e32 v149, v148
	v_add_u32_e32 v168, s72, v159
	v_mov_b32_e32 v155, 1.0
	v_mov_b64_e32 v[60:61], v[44:45]
	v_mov_b64_e32 v[58:59], v[42:43]
	v_mov_b64_e32 v[56:57], v[40:41]
	v_mov_b64_e32 v[54:55], v[38:39]
	v_mov_b64_e32 v[52:53], v[36:37]
	v_mov_b64_e32 v[50:51], v[34:35]
	v_mov_b64_e32 v[48:49], v[32:33]
	v_mov_b64_e32 v[76:77], v[44:45]
	v_mov_b64_e32 v[74:75], v[42:43]
	v_mov_b64_e32 v[72:73], v[40:41]
	v_mov_b64_e32 v[70:71], v[38:39]
	v_mov_b64_e32 v[68:69], v[36:37]
	v_mov_b64_e32 v[66:67], v[34:35]
	v_mov_b64_e32 v[64:65], v[32:33]
	v_mov_b64_e32 v[2:3], v[34:35]
	v_mov_b64_e32 v[4:5], v[36:37]
	v_mov_b64_e32 v[6:7], v[38:39]
	v_mov_b64_e32 v[8:9], v[40:41]
	v_mov_b64_e32 v[10:11], v[42:43]
	v_mov_b64_e32 v[12:13], v[44:45]
	v_mov_b64_e32 v[14:15], v[46:47]
	v_mov_b64_e32 v[18:19], v[34:35]
	v_mov_b64_e32 v[20:21], v[36:37]
	v_mov_b64_e32 v[22:23], v[38:39]
	v_mov_b64_e32 v[24:25], v[40:41]
	v_mov_b64_e32 v[26:27], v[42:43]
	v_mov_b64_e32 v[28:29], v[44:45]
	v_mov_b64_e32 v[30:31], v[46:47]
	s_mov_b32 s69, 0
	s_waitcnt vmcnt(0)
	s_branch .LBB0_428

; DEVI int crow(int r, int hi) { return (r & 3) + 8 * (r >> 2) + 4 * hi; }
; template <bool MLA> ...
;     ...
; #pragma unroll
;       for (int r = 0; r < 16; ++r) rli[r] = 1.f;
;     }
; #pragma unroll
;     for (int r = 0; r < 16; ++r) { const int orow = first + crow(r, hi);
;       if (orow < nrows) {
; #pragma unroll
;         for (int d0 = 0; d0 < 4; ++d0) Ob[(long)orow * ldo + d0 * 32 + r32] = __float2bfloat16(o[d0][r] * rli[r]); } }
.LBB0_435:
	s_and_saveexec_b64 s[0:1], vcc
	s_cbranch_execz .LBB0_230
	v_readlane_b32 s6, v254, 47
	v_readlane_b32 s7, v254, 48
	s_lshl_b64 s[6:7], s[6:7], 12
	v_readlane_b32 s4, v255, 25
	s_add_u32 s6, s4, s6
	v_readlane_b32 s4, v255, 44
	s_addc_u32 s7, s4, s7
	s_lshl_b32 s8, s38, 1
	s_add_u32 s6, s6, s8
	s_addc_u32 s7, s7, 0
	v_or_b32_e32 v36, v159, v158
	v_lshlrev_b32_e32 v32, 1, v157
	v_lshl_add_u64 v[34:35], s[6:7], 0, v[32:33]
	v_cmp_gt_i32_e32 vcc, s95, v36
	s_and_saveexec_b64 s[6:7], vcc
	s_cbranch_execz .LBB0_438
	v_ashrrev_i32_e32 v37, 31, v36
	v_lshlrev_b64 v[38:39], 12, v[36:37]
	v_cvt_pk_bf16_f32 v32, v48, s0
	v_lshl_add_u64 v[38:39], v[34:35], 0, v[38:39]
	v_cvt_pk_bf16_f32 v40, v64, s0
	v_cvt_pk_bf16_f32 v0, v0, s0
	v_cvt_pk_bf16_f32 v16, v16, s0
	global_store_short v[38:39], v32, off
	global_store_short v[38:39], v40, off offset:64
	global_store_short v[38:39], v0, off offset:128
	global_store_short v[38:39], v16, off offset:192
.LBB0_438:
	s_or_b64 exec, exec, s[6:7]
	v_or_b32_e32 v38, 1, v36
	v_cmp_gt_i32_e32 vcc, s95, v38
	s_and_saveexec_b64 s[6:7], vcc
	s_cbranch_execz .LBB0_440
	v_ashrrev_i32_e32 v39, 31, v38
	v_lshlrev_b64 v[38:39], 12, v[38:39]
	v_cvt_pk_bf16_f32 v0, v49, s0
	v_lshl_add_u64 v[38:39], v[34:35], 0, v[38:39]
	v_cvt_pk_bf16_f32 v16, v65, s0
	v_cvt_pk_bf16_f32 v1, v1, s0
	v_cvt_pk_bf16_f32 v17, v17, s0
	global_store_short v[38:39], v0, off
	global_store_short v[38:39], v16, off offset:64
	global_store_short v[38:39], v1, off offset:128
	global_store_short v[38:39], v17, off offset:192
.LBB0_440:
	s_or_b64 exec, exec, s[6:7]
	v_or_b32_e32 v0, 2, v36
	v_cmp_gt_i32_e32 vcc, s95, v0
	s_and_saveexec_b64 s[6:7], vcc
	s_cbranch_execz .LBB0_442
	v_ashrrev_i32_e32 v1, 31, v0
	v_lshlrev_b64 v[0:1], 12, v[0:1]
	v_cvt_pk_bf16_f32 v16, v50, s0
	v_lshl_add_u64 v[0:1], v[34:35], 0, v[0:1]
	v_cvt_pk_bf16_f32 v17, v66, s0
	v_cvt_pk_bf16_f32 v2, v2, s0
	v_cvt_pk_bf16_f32 v18, v18, s0
	global_store_short v[0:1], v16, off
	global_store_short v[0:1], v17, off offset:64
	global_store_short v[0:1], v2, off offset:128
	global_store_short v[0:1], v18, off offset:192
.LBB0_442:
	s_or_b64 exec, exec, s[6:7]
	v_or_b32_e32 v0, 3, v36
	v_cmp_gt_i32_e32 vcc, s95, v0
	s_and_saveexec_b64 s[6:7], vcc
	s_cbranch_execz .LBB0_444
	v_ashrrev_i32_e32 v1, 31, v0
	v_lshlrev_b64 v[0:1], 12, v[0:1]
	v_cvt_pk_bf16_f32 v2, v51, s0
	v_lshl_add_u64 v[0:1], v[34:35], 0, v[0:1]
	v_cvt_pk_bf16_f32 v16, v67, s0
	v_cvt_pk_bf16_f32 v3, v3, s0
	v_cvt_pk_bf16_f32 v17, v19, s0
	global_store_short v[0:1], v2, off
	global_store_short v[0:1], v16, off offset:64
	global_store_short v[0:1], v3, off offset:128
	global_store_short v[0:1], v17, off offset:192
.LBB0_444:
	s_or_b64 exec, exec, s[6:7]
	v_or_b32_e32 v0, 8, v36
	v_cmp_gt_i32_e32 vcc, s95, v0
	s_and_saveexec_b64 s[6:7], vcc
	s_cbranch_execz .LBB0_446
	v_ashrrev_i32_e32 v1, 31, v0
	v_lshlrev_b64 v[0:1], 12, v[0:1]
	v_cvt_pk_bf16_f32 v2, v52, s0
	v_lshl_add_u64 v[0:1], v[34:35], 0, v[0:1]
	v_cvt_pk_bf16_f32 v3, v68, s0
	v_cvt_pk_bf16_f32 v4, v4, s0
	v_cvt_pk_bf16_f32 v16, v20, s0
	global_store_short v[0:1], v2, off
	global_store_short v[0:1], v3, off offset:64
	global_store_short v[0:1], v4, off offset:128
	global_store_short v[0:1], v16, off offset:192
.LBB0_446:
	s_or_b64 exec, exec, s[6:7]
	v_or_b32_e32 v0, 9, v36
	v_cmp_gt_i32_e32 vcc, s95, v0
	s_and_saveexec_b64 s[6:7], vcc
	s_cbranch_execz .LBB0_448
	v_ashrrev_i32_e32 v1, 31, v0
	v_lshlrev_b64 v[0:1], 12, v[0:1]
	v_cvt_pk_bf16_f32 v2, v53, s0
	v_lshl_add_u64 v[0:1], v[34:35], 0, v[0:1]
	v_cvt_pk_bf16_f32 v3, v69, s0
	v_cvt_pk_bf16_f32 v4, v5, s0
	v_cvt_pk_bf16_f32 v5, v21, s0
	global_store_short v[0:1], v2, off
	global_store_short v[0:1], v3, off offset:64
	global_store_short v[0:1], v4, off offset:128
	global_store_short v[0:1], v5, off offset:192
.LBB0_448:
	s_or_b64 exec, exec, s[6:7]
	v_or_b32_e32 v0, 10, v36
	v_cmp_gt_i32_e32 vcc, s95, v0
	s_and_saveexec_b64 s[6:7], vcc
	s_cbranch_execz .LBB0_450
	v_ashrrev_i32_e32 v1, 31, v0
	v_lshlrev_b64 v[0:1], 12, v[0:1]
	v_cvt_pk_bf16_f32 v2, v54, s0
	v_lshl_add_u64 v[0:1], v[34:35], 0, v[0:1]
	v_cvt_pk_bf16_f32 v3, v70, s0
	v_cvt_pk_bf16_f32 v4, v6, s0
	v_cvt_pk_bf16_f32 v5, v22, s0
	global_store_short v[0:1], v2, off
	global_store_short v[0:1], v3, off offset:64
	global_store_short v[0:1], v4, off offset:128
	global_store_short v[0:1], v5, off offset:192
.LBB0_450:
	s_or_b64 exec, exec, s[6:7]
	v_or_b32_e32 v0, 11, v36
	v_cmp_gt_i32_e32 vcc, s95, v0
	s_and_saveexec_b64 s[6:7], vcc
	s_cbranch_execz .LBB0_452
	v_ashrrev_i32_e32 v1, 31, v0
	v_lshlrev_b64 v[0:1], 12, v[0:1]
	v_cvt_pk_bf16_f32 v2, v55, s0
	v_lshl_add_u64 v[0:1], v[34:35], 0, v[0:1]
	v_cvt_pk_bf16_f32 v3, v71, s0
	v_cvt_pk_bf16_f32 v4, v7, s0
	v_cvt_pk_bf16_f32 v5, v23, s0
	global_store_short v[0:1], v2, off
	global_store_short v[0:1], v3, off offset:64
	global_store_short v[0:1], v4, off offset:128
	global_store_short v[0:1], v5, off offset:192
; DEVI int crow(int r, int hi) { return (r & 3) + 8 * (r >> 2) + 4 * hi; }
; template <bool MLA> ...
;     ...
; #pragma unroll
;     for (int r = 0; r < 16; ++r) { const int orow = first + crow(r, hi);
;       if (orow < nrows) {
; #pragma unroll
;         for (int d0 = 0; d0 < 4; ++d0) Ob[(long)orow * ldo + d0 * 32 + r32] = __float2bfloat16(o[d0][r] * rli[r]); } }
.LBB0_452:
	s_or_b64 exec, exec, s[6:7]
	v_or_b32_e32 v0, 16, v36
	v_cmp_gt_i32_e32 vcc, s95, v0
	s_and_saveexec_b64 s[6:7], vcc
	s_cbranch_execz .LBB0_454
	v_ashrrev_i32_e32 v1, 31, v0
	v_lshlrev_b64 v[0:1], 12, v[0:1]
	v_cvt_pk_bf16_f32 v2, v56, s0
	v_lshl_add_u64 v[0:1], v[34:35], 0, v[0:1]
	v_cvt_pk_bf16_f32 v3, v72, s0
	v_cvt_pk_bf16_f32 v4, v8, s0
	v_cvt_pk_bf16_f32 v5, v24, s0
	global_store_short v[0:1], v2, off
	global_store_short v[0:1], v3, off offset:64
	global_store_short v[0:1], v4, off offset:128
	global_store_short v[0:1], v5, off offset:192
.LBB0_454:
	s_or_b64 exec, exec, s[6:7]
	v_or_b32_e32 v0, 17, v36
	v_cmp_gt_i32_e32 vcc, s95, v0
	s_and_saveexec_b64 s[6:7], vcc
	s_cbranch_execz .LBB0_456
	v_ashrrev_i32_e32 v1, 31, v0
	v_lshlrev_b64 v[0:1], 12, v[0:1]
	v_cvt_pk_bf16_f32 v2, v57, s0
	v_lshl_add_u64 v[0:1], v[34:35], 0, v[0:1]
	v_cvt_pk_bf16_f32 v3, v73, s0
	v_cvt_pk_bf16_f32 v4, v9, s0
	v_cvt_pk_bf16_f32 v5, v25, s0
	global_store_short v[0:1], v2, off
	global_store_short v[0:1], v3, off offset:64
	global_store_short v[0:1], v4, off offset:128
	global_store_short v[0:1], v5, off offset:192
.LBB0_456:
	s_or_b64 exec, exec, s[6:7]
	v_or_b32_e32 v0, 18, v36
	v_cmp_gt_i32_e32 vcc, s95, v0
	s_and_saveexec_b64 s[6:7], vcc
	s_cbranch_execz .LBB0_458
	v_ashrrev_i32_e32 v1, 31, v0
	v_lshlrev_b64 v[0:1], 12, v[0:1]
	v_cvt_pk_bf16_f32 v2, v58, s0
	v_lshl_add_u64 v[0:1], v[34:35], 0, v[0:1]
	v_cvt_pk_bf16_f32 v3, v74, s0
	v_cvt_pk_bf16_f32 v4, v10, s0
	v_cvt_pk_bf16_f32 v5, v26, s0
	global_store_short v[0:1], v2, off
	global_store_short v[0:1], v3, off offset:64
	global_store_short v[0:1], v4, off offset:128
	global_store_short v[0:1], v5, off offset:192
.LBB0_458:
	s_or_b64 exec, exec, s[6:7]
	v_or_b32_e32 v0, 19, v36
	v_cmp_gt_i32_e32 vcc, s95, v0
	s_and_saveexec_b64 s[6:7], vcc
	s_cbranch_execz .LBB0_460
	v_ashrrev_i32_e32 v1, 31, v0
	v_lshlrev_b64 v[0:1], 12, v[0:1]
	v_cvt_pk_bf16_f32 v2, v59, s0
	v_lshl_add_u64 v[0:1], v[34:35], 0, v[0:1]
	v_cvt_pk_bf16_f32 v3, v75, s0
	v_cvt_pk_bf16_f32 v4, v11, s0
	v_cvt_pk_bf16_f32 v5, v27, s0
	global_store_short v[0:1], v2, off
	global_store_short v[0:1], v3, off offset:64
	global_store_short v[0:1], v4, off offset:128
	global_store_short v[0:1], v5, off offset:192
.LBB0_460:
	s_or_b64 exec, exec, s[6:7]
	v_or_b32_e32 v0, 24, v36
	v_cmp_gt_i32_e32 vcc, s95, v0
	s_and_saveexec_b64 s[6:7], vcc
	s_cbranch_execz .LBB0_462
	v_ashrrev_i32_e32 v1, 31, v0
	v_lshlrev_b64 v[0:1], 12, v[0:1]
	v_cvt_pk_bf16_f32 v2, v60, s0
	v_lshl_add_u64 v[0:1], v[34:35], 0, v[0:1]
	v_cvt_pk_bf16_f32 v3, v76, s0
	v_cvt_pk_bf16_f32 v4, v12, s0
	v_cvt_pk_bf16_f32 v5, v28, s0
	global_store_short v[0:1], v2, off
	global_store_short v[0:1], v3, off offset:64
	global_store_short v[0:1], v4, off offset:128
	global_store_short v[0:1], v5, off offset:192
.LBB0_462:
	s_or_b64 exec, exec, s[6:7]
	v_or_b32_e32 v0, 25, v36
	v_cmp_gt_i32_e32 vcc, s95, v0
	s_and_saveexec_b64 s[6:7], vcc
	s_cbranch_execz .LBB0_464
	v_ashrrev_i32_e32 v1, 31, v0
	v_lshlrev_b64 v[0:1], 12, v[0:1]
	v_cvt_pk_bf16_f32 v2, v61, s0
	v_lshl_add_u64 v[0:1], v[34:35], 0, v[0:1]
	v_cvt_pk_bf16_f32 v3, v77, s0
	v_cvt_pk_bf16_f32 v4, v13, s0
	v_cvt_pk_bf16_f32 v5, v29, s0
	global_store_short v[0:1], v2, off
	global_store_short v[0:1], v3, off offset:64
	global_store_short v[0:1], v4, off offset:128
	global_store_short v[0:1], v5, off offset:192
.LBB0_464:
	s_or_b64 exec, exec, s[6:7]
	v_or_b32_e32 v0, 26, v36
	v_cmp_gt_i32_e32 vcc, s95, v0
	s_and_saveexec_b64 s[6:7], vcc
	s_cbranch_execz .LBB0_466
	v_ashrrev_i32_e32 v1, 31, v0
	v_lshlrev_b64 v[0:1], 12, v[0:1]
	v_cvt_pk_bf16_f32 v2, v62, s0
	v_lshl_add_u64 v[0:1], v[34:35], 0, v[0:1]
	v_cvt_pk_bf16_f32 v3, v78, s0
	v_cvt_pk_bf16_f32 v4, v14, s0
	v_cvt_pk_bf16_f32 v5, v30, s0
	global_store_short v[0:1], v2, off
	global_store_short v[0:1], v3, off offset:64
	global_store_short v[0:1], v4, off offset:128
	global_store_short v[0:1], v5, off offset:192
.LBB0_466:
	s_or_b64 exec, exec, s[6:7]
	v_or_b32_e32 v0, 27, v36
	v_cmp_gt_i32_e32 vcc, s95, v0
	s_and_b64 exec, exec, vcc
	s_cbranch_execz .LBB0_230
	v_ashrrev_i32_e32 v1, 31, v0
	v_lshlrev_b64 v[0:1], 12, v[0:1]
	v_cvt_pk_bf16_f32 v2, v63, s0
	v_lshl_add_u64 v[0:1], v[34:35], 0, v[0:1]
	v_cvt_pk_bf16_f32 v3, v79, s0
	v_cvt_pk_bf16_f32 v4, v15, s0
	v_cvt_pk_bf16_f32 v5, v31, s0
	global_store_short v[0:1], v2, off
	global_store_short v[0:1], v3, off offset:64
	global_store_short v[0:1], v4, off offset:128
	global_store_short v[0:1], v5, off offset:192
	s_branch .LBB0_230

; DEVI void run_phase(const int ph, const Params& P, char* shmc, const int wave_u) {
;     ...
;     { int tidr = get_tid(wave_u); const int wid = tidr >> 6, lane = tidr & 63;
;       for (int row = blockIdx.x * 8 + wid; row < MT; row += G * 8) {
;         float* r = row < MP ? out + O_CKV_P + (long)row * 512 : out + O_CKV_S + (long)(row - MP) * 512;
;         f32x4 a = *(f32x4*)(r + lane * 8), b = *(f32x4*)(r + lane * 8 + 4);
;         float ss = 0.f;
; #pragma unroll
;         for (int j = 0; j < 4; ++j) ss += a[j] * a[j] + b[j] * b[j];
;         ss = wave_sum(ss, lane); const float rs = rsqrtf(ss * (1.f / 512) + EPS);
;         f32x4 g0 = *(const f32x4*)(P.g_kv + lane * 8), g1 = *(const f32x4*)(P.g_kv + lane * 8 + 4);
; #pragma unroll
;         for (int j = 0; j < 4; ++j) { a[j] = a[j] * rs * g0[j]; b[j] = b[j] * rs * g1[j]; }
;         *(f32x4*)(r + lane * 8) = a; *(f32x4*)(r + lane * 8 + 4) = b;
;         u32x4 w = {cvtpk(a[0], a[1]), cvtpk(a[2], a[3]), cvtpk(b[0], b[1]), cvtpk(b[2], b[3])};
;         *reinterpret_cast<u32x4*>(ckva + (long)row * 512 + lane * 8) = w;
;       } }
.LBB0_477:
	s_or_b64 exec, exec, s[8:9]
	v_lshl_add_u64 v[10:11], v[10:11], 0, v[32:33]
	global_load_dwordx4 v[18:21], v[10:11], off
	global_load_dwordx4 v[22:25], v[10:11], off offset:16
	s_mov_b32 s4, 0x800000
	v_readlane_b32 s8, v254, 31
	v_readlane_b32 s9, v254, 32
	v_lshlrev_b64 v[8:9], 10, v[8:9]
	v_lshl_add_u64 v[8:9], v[2:3], 0, v[8:9]
	v_lshl_add_u64 v[0:1], v[0:1], 0, s[8:9]
	v_readlane_b32 s8, v253, 19
	v_readlane_b32 s9, v253, 20
	s_waitcnt vmcnt(0) lgkmcnt(0)
	v_pk_mul_f32 v[28:29], v[22:23], v[22:23]
	v_pk_mul_f32 v[26:27], v[24:25], v[24:25]
	v_pk_fma_f32 v[28:29], v[18:19], v[18:19], v[28:29]
	v_pk_fma_f32 v[26:27], v[20:21], v[20:21], v[26:27]
	v_add_f32_e32 v28, v28, v29
	v_add_f32_e32 v26, v26, v28
	v_add_f32_e32 v26, v27, v26
	ds_bpermute_b32 v27, v12, v26
	v_lshl_add_u64 v[6:7], v[6:7], 0, s[8:9]
	s_waitcnt lgkmcnt(0)
	v_add_f32_e32 v26, v26, v27
	ds_bpermute_b32 v27, v13, v26
	s_waitcnt lgkmcnt(0)
	v_add_f32_e32 v26, v26, v27
	ds_bpermute_b32 v27, v14, v26
	s_waitcnt lgkmcnt(0)
	v_add_f32_e32 v26, v26, v27
	ds_bpermute_b32 v27, v15, v26
	s_waitcnt lgkmcnt(0)
	v_add_f32_e32 v26, v26, v27
	ds_bpermute_b32 v27, v16, v26
	s_waitcnt lgkmcnt(0)
	v_add_f32_e32 v26, v26, v27
	ds_bpermute_b32 v27, v17, v26
	s_waitcnt lgkmcnt(0)
	v_add_f32_e32 v26, v26, v27
	v_fmamk_f32 v26, v26, 0x3b000000, v186
	v_cmp_gt_f32_e32 vcc, s4, v26
	v_mul_f32_e32 v27, 0x4b800000, v26
	s_movk_i32 s4, 0x41ff
	v_cndmask_b32_e32 v26, v26, v27, vcc
	v_rsq_f32_e32 v26, v26
	s_nop 0
	v_mul_f32_e32 v27, 0x45800000, v26
	v_cndmask_b32_e32 v30, v26, v27, vcc
	global_load_dwordx4 v[26:29], v[4:5], off offset:16
	global_load_dwordx4 v[34:37], v[4:5], off
	v_pk_mul_f32 v[18:19], v[18:19], v[30:31] op_sel_hi:[1,0]
	v_pk_mul_f32 v[20:21], v[20:21], v[30:31] op_sel_hi:[1,0]
	v_cmp_lt_i32_e32 vcc, s4, v0
	v_pk_mul_f32 v[22:23], v[22:23], v[30:31] op_sel_hi:[1,0]
	v_pk_mul_f32 v[24:25], v[24:25], v[30:31] op_sel_hi:[1,0]
	s_or_b64 s[38:39], vcc, s[38:39]
	s_waitcnt vmcnt(1)
	v_pk_mul_f32 v[22:23], v[26:27], v[22:23]
	s_waitcnt vmcnt(0)
	v_pk_mul_f32 v[18:19], v[34:35], v[18:19]
	v_pk_mul_f32 v[20:21], v[36:37], v[20:21]
	v_pk_mul_f32 v[24:25], v[28:29], v[24:25]
	global_store_dwordx4 v[10:11], v[18:21], off
	global_store_dwordx4 v[10:11], v[22:25], off offset:16
	s_nop 0
	v_cvt_pk_bf16_f32 v18, v18, v19
	v_cvt_pk_bf16_f32 v19, v20, v21
	v_cvt_pk_bf16_f32 v20, v22, v23
	v_cvt_pk_bf16_f32 v21, v24, v25
	global_store_dwordx4 v[8:9], v[18:21], off
	s_andn2_b64 exec, exec, s[38:39]
	s_cbranch_execz .LBB0_789

; #define EPI_LOOP(...) _Pragma("unroll") for(int ai=0;ai<2;++ai) _Pragma("unroll") for(int bj=0;bj<2;++bj) \
;   _Pragma("unroll") for(int m=0;m<4;++m) _Pragma("unroll") for(int n=0;n<2;++n) { \
;     const int row=brow+ai*128+wr*64+m*16+fq*4; const int col=bcol+bj*128+wc*32+n*16+fr; \
;     f32x4& v=acc[ai][bj][m][n]; __VA_ARGS__ if (n == 1 && (m & 1)) __builtin_amdgcn_sched_barrier(0); }
; DEVI void run_phase(const int ph, const Params& P, char* shmc, const int wave_u) {
;     ...
;       GEMM_IDS
;       const bool isk = brow < 1024; const int fb = isk ? 0 : 1024;
;       bf16* dp = isk ? kn_p : vm_p; bf16* ds = isk ? kn_s : vm_s;
;       EPI_LOOP({ const int f = row - fb; long drow; bf16* d;
;         if (col < MP) { d = dp; drow = col; }
;         else if (col < MT) { const int s = col - MP; d = ds; drow = (long)(s >> 5) * SKS + 1024 + (s & 31); }
;         else { const int c = col - MT; d = ds; drow = (long)(c >> 10) * SKS + (c & 1023); }
.LBB0_489:
	s_or_b64 exec, exec, s[0:1]
	v_mbcnt_lo_u32_b32 v164, -1, 0
	v_mbcnt_hi_u32_b32 v164, -1, v164
	v_bfe_u32 v164, v164, 4, 1
	v_mul_u32_u24_e32 v164, 24, v164
	v_mov_b32_e32 v165, 0
	s_cmp_lt_u32 s71, 4
	s_cselect_b64 s[6:7], -1, 0
	s_and_b64 s[0:1], s[6:7], exec
	v_readlane_b32 s0, v255, 37
	v_readlane_b32 s1, v255, 41
	s_cselect_b32 s39, s0, s1
	v_readlane_b32 s0, v255, 35
	v_readlane_b32 s1, v255, 40
	v_mbcnt_lo_u32_b32 v130, -1, 0
	v_mbcnt_hi_u32_b32 v130, -1, v130
	s_cselect_b32 s38, s0, s1
	v_or_b32_e32 v131, s5, v130
	v_readlane_b32 s0, v255, 39
	v_readlane_b32 s1, v255, 43
	s_cselect_b32 s1, s0, s1
	v_readlane_b32 s0, v255, 38
	v_readlane_b32 s4, v255, 42
	v_lshrrev_b32_e32 v32, 1, v131
	s_cselect_b32 s0, s0, s4
	v_and_b32_e32 v32, 0x60, v32
	s_cmpk_gt_u32 s70, 0x3fff
	v_and_b32_e32 v135, 15, v130
	v_or_b32_e32 v134, s70, v32
	s_cselect_b64 s[8:9], -1, 0
	v_or_b32_e32 v32, v134, v135
	s_and_b64 vcc, exec, s[8:9]
	s_cbranch_vccz .LBB0_495
	s_cmpk_gt_u32 s70, 0x41ff
	s_mov_b64 s[68:69], -1
	s_cbranch_scc0 .LBB0_492
	v_add_u32_e32 v132, 0xffffbe00, v32
	v_lshrrev_b32_e32 v136, 10, v132
	v_and_b32_e32 v132, 0x36f, v132
	v_mov_b32_e32 v133, v33
	s_movk_i32 s4, 0x440
	v_mad_u64_u32 v[132:133], s[68:69], v136, s4, v[132:133]
	s_mov_b64 s[68:69], 0

; #define EPI_LOOP(...) _Pragma("unroll") for(int ai=0;ai<2;++ai) _Pragma("unroll") for(int bj=0;bj<2;++bj) \
;   _Pragma("unroll") for(int m=0;m<4;++m) _Pragma("unroll") for(int n=0;n<2;++n) { \
;     const int row=brow+ai*128+wr*64+m*16+fq*4; const int col=bcol+bj*128+wc*32+n*16+fr; \
;     f32x4& v=acc[ai][bj][m][n]; __VA_ARGS__ if (n == 1 && (m & 1)) __builtin_amdgcn_sched_barrier(0); }
; DEVI void run_phase(const int ph, const Params& P, char* shmc, const int wave_u) {
;     ...
;       EPI_LOOP({ const int f = row - fb; long drow; bf16* d;
;         if (col < MP) { d = dp; drow = col; }
;         else if (col < MT) { const int s = col - MP; d = ds; drow = (long)(s >> 5) * SKS + 1024 + (s & 31); }
;         else { const int c = col - MT; d = ds; drow = (long)(c >> 10) * SKS + (c & 1023); }
;         st_bf4(d + drow * 1024 + f, v[0], v[1], v[2], v[3]); })
.LBB0_497:
	s_lshl_b32 s71, s71, 8
	s_and_b64 s[6:7], s[6:7], exec
	s_cselect_b32 s6, 0, 0xfffffc00
	v_ashrrev_i32_e32 v131, 2, v131
	v_lshrrev_b32_e32 v130, 2, v130
	s_add_i32 s6, s6, s71
	v_and_b32_e32 v131, 0xffffffc0, v131
	v_and_or_b32 v130, v130, 12, s6
	v_add_u32_e32 v130, v130, v131
	v_lshlrev_b64 v[132:133], 11, v[132:133]
	v_ashrrev_i32_e32 v131, 31, v130
	v_lshl_add_u64 v[132:133], s[68:69], 0, v[132:133]
	v_lshl_add_u64 v[132:133], v[130:131], 1, v[132:133]
	v_cvt_pk_bf16_f32 v126, v126, v127
	v_cvt_pk_bf16_f32 v127, v128, v129
	v_mov_b32_e32 v140, v126
	v_mov_b32_e32 v141, v127
	v_lshl_add_u64 v[138:139], v[132:133], 0, v[164:165]
	v_cndmask_b32_e64 v126, 0, 1, s[8:9]
	v_or_b32_e32 v136, 16, v135
	v_cmp_ne_u32_e64 s[6:7], 1, v126
	s_andn2_b64 vcc, exec, s[8:9]
	v_or_b32_e32 v126, 16, v32
	s_cbranch_vccnz .LBB0_503
	s_cmpk_lt_u32 s70, 0x4200
	s_mov_b64 s[8:9], -1
	s_cbranch_scc1 .LBB0_500
	v_add_u32_e32 v127, 0xffffbe10, v32
	v_lshrrev_b32_e32 v132, 10, v127
	v_and_b32_e32 v128, 0x37f, v127
	v_mov_b32_e32 v129, v33
	s_movk_i32 s4, 0x440
	v_mad_u64_u32 v[128:129], s[8:9], v132, s4, v[128:129]
	s_mov_b64 s[8:9], 0

; #define EPI_LOOP(...) _Pragma("unroll") for(int ai=0;ai<2;++ai) _Pragma("unroll") for(int bj=0;bj<2;++bj) \
;   _Pragma("unroll") for(int m=0;m<4;++m) _Pragma("unroll") for(int n=0;n<2;++n) { \
;     const int row=brow+ai*128+wr*64+m*16+fq*4; const int col=bcol+bj*128+wc*32+n*16+fr; \
;     f32x4& v=acc[ai][bj][m][n]; __VA_ARGS__ if (n == 1 && (m & 1)) __builtin_amdgcn_sched_barrier(0); }
; DEVI void run_phase(const int ph, const Params& P, char* shmc, const int wave_u) {
;     ...
;       EPI_LOOP({ const int f = row - fb; long drow; bf16* d;
;         if (col < MP) { d = dp; drow = col; }
;         else if (col < MT) { const int s = col - MP; d = ds; drow = (long)(s >> 5) * SKS + 1024 + (s & 31); }
;         else { const int c = col - MT; d = ds; drow = (long)(c >> 10) * SKS + (c & 1023); }
;         st_bf4(d + drow * 1024 + f, v[0], v[1], v[2], v[3]); })
.LBB0_505:
	v_lshlrev_b64 v[128:129], 11, v[128:129]
	v_lshl_add_u64 v[128:129], s[8:9], 0, v[128:129]
	v_lshl_add_u64 v[128:129], v[130:131], 1, v[128:129]
	s_and_b64 vcc, exec, s[6:7]
	v_cvt_pk_bf16_f32 v122, v122, v123
	v_cvt_pk_bf16_f32 v123, v124, v125
	v_mov_b32_e32 v148, v122
	v_mov_b32_e32 v149, v123
	v_lshl_add_u64 v[144:145], v[128:129], 0, v[164:165]
	s_cbranch_vccnz .LBB0_511
	s_cmpk_lt_u32 s70, 0x4200
	s_mov_b64 s[8:9], -1
	s_cbranch_scc1 .LBB0_508
	v_add_u32_e32 v122, 0xffffbe00, v32
	v_lshrrev_b32_e32 v124, 10, v122
	v_and_b32_e32 v122, 0x36f, v122
	v_mov_b32_e32 v123, v33
	s_movk_i32 s4, 0x440
	v_mad_u64_u32 v[122:123], s[8:9], v124, s4, v[122:123]
	s_mov_b64 s[8:9], 0

; #define EPI_LOOP(...) _Pragma("unroll") for(int ai=0;ai<2;++ai) _Pragma("unroll") for(int bj=0;bj<2;++bj) \
;   _Pragma("unroll") for(int m=0;m<4;++m) _Pragma("unroll") for(int n=0;n<2;++n) { \
;     const int row=brow+ai*128+wr*64+m*16+fq*4; const int col=bcol+bj*128+wc*32+n*16+fr; \
;     f32x4& v=acc[ai][bj][m][n]; __VA_ARGS__ if (n == 1 && (m & 1)) __builtin_amdgcn_sched_barrier(0); }
; DEVI void run_phase(const int ph, const Params& P, char* shmc, const int wave_u) {
;     ...
;       EPI_LOOP({ const int f = row - fb; long drow; bf16* d;
;         if (col < MP) { d = dp; drow = col; }
;         else if (col < MT) { const int s = col - MP; d = ds; drow = (long)(s >> 5) * SKS + 1024 + (s & 31); }
;         else { const int c = col - MT; d = ds; drow = (long)(c >> 10) * SKS + (c & 1023); }
;         st_bf4(d + drow * 1024 + f, v[0], v[1], v[2], v[3]); })
.LBB0_513:
	v_lshlrev_b64 v[122:123], 11, v[122:123]
	v_lshl_add_u64 v[122:123], s[8:9], 0, v[122:123]
	v_lshl_add_u64 v[122:123], v[130:131], 1, v[122:123]
	s_and_b64 vcc, exec, s[6:7]
	v_cvt_pk_bf16_f32 v118, v118, v119
	v_cvt_pk_bf16_f32 v119, v120, v121
	v_mov_b32_e32 v142, v118
	v_mov_b32_e32 v143, v119
	s_nop 1
	v_permlane16_swap_b32_e32 v140, v142
	v_permlane16_swap_b32_e32 v141, v143
	global_store_dwordx4 v[138:139], v[140:143], off
	s_cbranch_vccnz .LBB0_519
	s_cmpk_lt_u32 s70, 0x4200
	s_mov_b64 s[8:9], -1
	s_cbranch_scc1 .LBB0_516
	v_add_u32_e32 v118, 0xffffbe10, v32
	v_lshrrev_b32_e32 v120, 10, v118
	v_and_b32_e32 v118, 0x37f, v118
	v_mov_b32_e32 v119, v33
	s_movk_i32 s4, 0x440
	v_mad_u64_u32 v[118:119], s[8:9], v120, s4, v[118:119]
	s_mov_b64 s[8:9], 0

; #define EPI_LOOP(...) _Pragma("unroll") for(int ai=0;ai<2;++ai) _Pragma("unroll") for(int bj=0;bj<2;++bj) \
;   _Pragma("unroll") for(int m=0;m<4;++m) _Pragma("unroll") for(int n=0;n<2;++n) { \
;     const int row=brow+ai*128+wr*64+m*16+fq*4; const int col=bcol+bj*128+wc*32+n*16+fr; \
;     f32x4& v=acc[ai][bj][m][n]; __VA_ARGS__ if (n == 1 && (m & 1)) __builtin_amdgcn_sched_barrier(0); }
; DEVI void run_phase(const int ph, const Params& P, char* shmc, const int wave_u) {
;     ...
;       EPI_LOOP({ const int f = row - fb; long drow; bf16* d;
;         if (col < MP) { d = dp; drow = col; }
;         else if (col < MT) { const int s = col - MP; d = ds; drow = (long)(s >> 5) * SKS + 1024 + (s & 31); }
;         else { const int c = col - MT; d = ds; drow = (long)(c >> 10) * SKS + (c & 1023); }
;         st_bf4(d + drow * 1024 + f, v[0], v[1], v[2], v[3]); })
.LBB0_521:
	v_lshlrev_b64 v[118:119], 11, v[118:119]
	v_lshl_add_u64 v[118:119], s[8:9], 0, v[118:119]
	v_lshl_add_u64 v[118:119], v[130:131], 1, v[118:119]
	v_cvt_pk_bf16_f32 v114, v114, v115
	v_cvt_pk_bf16_f32 v115, v116, v117
	v_mov_b32_e32 v150, v114
	v_mov_b32_e32 v151, v115
	s_nop 1
	v_permlane16_swap_b32_e32 v148, v150
	v_permlane16_swap_b32_e32 v149, v151
	global_store_dwordx4 v[144:145], v[148:151], off
	s_and_b64 vcc, exec, s[6:7]
	s_cbranch_vccnz .LBB0_527
	s_cmpk_lt_u32 s70, 0x4200
	s_mov_b64 s[8:9], -1
	s_cbranch_scc1 .LBB0_524
	v_add_u32_e32 v114, 0xffffbe00, v32
	v_lshrrev_b32_e32 v116, 10, v114
	v_and_b32_e32 v114, 0x36f, v114
	v_mov_b32_e32 v115, v33
	s_movk_i32 s4, 0x440
	v_mad_u64_u32 v[114:115], s[8:9], v116, s4, v[114:115]
	s_mov_b64 s[8:9], 0

; #define EPI_LOOP(...) _Pragma("unroll") for(int ai=0;ai<2;++ai) _Pragma("unroll") for(int bj=0;bj<2;++bj) \
;   _Pragma("unroll") for(int m=0;m<4;++m) _Pragma("unroll") for(int n=0;n<2;++n) { \
;     const int row=brow+ai*128+wr*64+m*16+fq*4; const int col=bcol+bj*128+wc*32+n*16+fr; \
;     f32x4& v=acc[ai][bj][m][n]; __VA_ARGS__ if (n == 1 && (m & 1)) __builtin_amdgcn_sched_barrier(0); }
; DEVI void run_phase(const int ph, const Params& P, char* shmc, const int wave_u) {
;     ...
;       EPI_LOOP({ const int f = row - fb; long drow; bf16* d;
;         if (col < MP) { d = dp; drow = col; }
;         else if (col < MT) { const int s = col - MP; d = ds; drow = (long)(s >> 5) * SKS + 1024 + (s & 31); }
;         else { const int c = col - MT; d = ds; drow = (long)(c >> 10) * SKS + (c & 1023); }
;         st_bf4(d + drow * 1024 + f, v[0], v[1], v[2], v[3]); })
.LBB0_529:
	v_lshlrev_b64 v[114:115], 11, v[114:115]
	v_lshl_add_u64 v[114:115], s[8:9], 0, v[114:115]
	v_lshl_add_u64 v[114:115], v[130:131], 1, v[114:115]
	s_and_b64 vcc, exec, s[6:7]
	v_cvt_pk_bf16_f32 v110, v110, v111
	v_cvt_pk_bf16_f32 v111, v112, v113
	v_mov_b32_e32 v152, v110
	v_mov_b32_e32 v153, v111
	v_lshl_add_u64 v[160:161], v[114:115], 0, v[164:165]
	s_cbranch_vccnz .LBB0_535
	s_cmpk_lt_u32 s70, 0x4200
	s_mov_b64 s[8:9], -1
	s_cbranch_scc1 .LBB0_532
	v_add_u32_e32 v110, 0xffffbe10, v32
	v_lshrrev_b32_e32 v112, 10, v110
	v_and_b32_e32 v110, 0x37f, v110
	v_mov_b32_e32 v111, v33
	s_movk_i32 s4, 0x440
	v_mad_u64_u32 v[110:111], s[8:9], v112, s4, v[110:111]
	s_mov_b64 s[8:9], 0

; #define EPI_LOOP(...) _Pragma("unroll") for(int ai=0;ai<2;++ai) _Pragma("unroll") for(int bj=0;bj<2;++bj) \
;   _Pragma("unroll") for(int m=0;m<4;++m) _Pragma("unroll") for(int n=0;n<2;++n) { \
;     const int row=brow+ai*128+wr*64+m*16+fq*4; const int col=bcol+bj*128+wc*32+n*16+fr; \
;     f32x4& v=acc[ai][bj][m][n]; __VA_ARGS__ if (n == 1 && (m & 1)) __builtin_amdgcn_sched_barrier(0); }
; DEVI void run_phase(const int ph, const Params& P, char* shmc, const int wave_u) {
;     ...
;       EPI_LOOP({ const int f = row - fb; long drow; bf16* d;
;         if (col < MP) { d = dp; drow = col; }
;         else if (col < MT) { const int s = col - MP; d = ds; drow = (long)(s >> 5) * SKS + 1024 + (s & 31); }
;         else { const int c = col - MT; d = ds; drow = (long)(c >> 10) * SKS + (c & 1023); }
;         st_bf4(d + drow * 1024 + f, v[0], v[1], v[2], v[3]); })
.LBB0_537:
	v_lshlrev_b64 v[110:111], 11, v[110:111]
	v_lshl_add_u64 v[110:111], s[8:9], 0, v[110:111]
	v_lshl_add_u64 v[110:111], v[130:131], 1, v[110:111]
	s_and_b64 vcc, exec, s[6:7]
	v_cvt_pk_bf16_f32 v106, v106, v107
	v_cvt_pk_bf16_f32 v107, v108, v109
	v_mov_b32_e32 v156, v106
	v_mov_b32_e32 v157, v107
	v_lshl_add_u64 v[162:163], v[110:111], 0, v[164:165]
	s_cbranch_vccnz .LBB0_543
	s_cmpk_lt_u32 s70, 0x4200
	s_mov_b64 s[8:9], -1
	s_cbranch_scc1 .LBB0_540
	v_add_u32_e32 v106, 0xffffbe00, v32
	v_lshrrev_b32_e32 v108, 10, v106
	v_and_b32_e32 v106, 0x36f, v106
	v_mov_b32_e32 v107, v33
	s_movk_i32 s4, 0x440
	v_mad_u64_u32 v[106:107], s[8:9], v108, s4, v[106:107]
	s_mov_b64 s[8:9], 0

; #define EPI_LOOP(...) _Pragma("unroll") for(int ai=0;ai<2;++ai) _Pragma("unroll") for(int bj=0;bj<2;++bj) \
;   _Pragma("unroll") for(int m=0;m<4;++m) _Pragma("unroll") for(int n=0;n<2;++n) { \
;     const int row=brow+ai*128+wr*64+m*16+fq*4; const int col=bcol+bj*128+wc*32+n*16+fr; \
;     f32x4& v=acc[ai][bj][m][n]; __VA_ARGS__ if (n == 1 && (m & 1)) __builtin_amdgcn_sched_barrier(0); }
; DEVI void run_phase(const int ph, const Params& P, char* shmc, const int wave_u) {
;     ...
;       EPI_LOOP({ const int f = row - fb; long drow; bf16* d;
;         if (col < MP) { d = dp; drow = col; }
;         else if (col < MT) { const int s = col - MP; d = ds; drow = (long)(s >> 5) * SKS + 1024 + (s & 31); }
;         else { const int c = col - MT; d = ds; drow = (long)(c >> 10) * SKS + (c & 1023); }
;         st_bf4(d + drow * 1024 + f, v[0], v[1], v[2], v[3]); })
.LBB0_545:
	v_lshlrev_b64 v[106:107], 11, v[106:107]
	v_lshl_add_u64 v[106:107], s[8:9], 0, v[106:107]
	v_lshl_add_u64 v[106:107], v[130:131], 1, v[106:107]
	s_and_b64 vcc, exec, s[6:7]
	v_cvt_pk_bf16_f32 v102, v102, v103
	v_cvt_pk_bf16_f32 v103, v104, v105
	v_mov_b32_e32 v154, v102
	v_mov_b32_e32 v155, v103
	s_nop 1
	v_permlane16_swap_b32_e32 v152, v154
	v_permlane16_swap_b32_e32 v153, v155
	global_store_dwordx4 v[160:161], v[152:155], off offset:64
	s_cbranch_vccnz .LBB0_551
	s_cmpk_lt_u32 s70, 0x4200
	s_mov_b64 s[8:9], -1
	s_cbranch_scc1 .LBB0_548
	v_add_u32_e32 v102, 0xffffbe10, v32
	v_lshrrev_b32_e32 v104, 10, v102
	v_and_b32_e32 v102, 0x37f, v102
	v_mov_b32_e32 v103, v33
	s_movk_i32 s4, 0x440
	v_mad_u64_u32 v[102:103], s[8:9], v104, s4, v[102:103]
	s_mov_b64 s[8:9], 0

; #define EPI_LOOP(...) _Pragma("unroll") for(int ai=0;ai<2;++ai) _Pragma("unroll") for(int bj=0;bj<2;++bj) \
;   _Pragma("unroll") for(int m=0;m<4;++m) _Pragma("unroll") for(int n=0;n<2;++n) { \
;     const int row=brow+ai*128+wr*64+m*16+fq*4; const int col=bcol+bj*128+wc*32+n*16+fr; \
;     f32x4& v=acc[ai][bj][m][n]; __VA_ARGS__ if (n == 1 && (m & 1)) __builtin_amdgcn_sched_barrier(0); }
; DEVI void run_phase(const int ph, const Params& P, char* shmc, const int wave_u) {
;     ...
;       EPI_LOOP({ const int f = row - fb; long drow; bf16* d;
;         if (col < MP) { d = dp; drow = col; }
;         else if (col < MT) { const int s = col - MP; d = ds; drow = (long)(s >> 5) * SKS + 1024 + (s & 31); }
;         else { const int c = col - MT; d = ds; drow = (long)(c >> 10) * SKS + (c & 1023); }
;         st_bf4(d + drow * 1024 + f, v[0], v[1], v[2], v[3]); })
.LBB0_553:
	v_lshlrev_b64 v[102:103], 11, v[102:103]
	v_lshl_add_u64 v[102:103], s[8:9], 0, v[102:103]
	v_lshl_add_u64 v[102:103], v[130:131], 1, v[102:103]
	v_cvt_pk_bf16_f32 v98, v98, v99
	v_cvt_pk_bf16_f32 v99, v100, v101
	v_mov_b32_e32 v158, v98
	v_mov_b32_e32 v159, v99
	s_nop 1
	v_permlane16_swap_b32_e32 v156, v158
	v_permlane16_swap_b32_e32 v157, v159
	global_store_dwordx4 v[162:163], v[156:159], off offset:64
	s_and_b64 vcc, exec, s[6:7]
	v_or_b32_e32 v98, 0x80, v32
	s_cbranch_vccnz .LBB0_559
	s_cmpk_lt_u32 s70, 0x4200
	s_mov_b64 s[8:9], -1
	s_cbranch_scc1 .LBB0_556
	v_add_u32_e32 v99, 0xffffbe80, v32
	v_lshrrev_b32_e32 v102, 10, v99
	v_and_b32_e32 v100, 0x3ef, v99
	v_mov_b32_e32 v101, v33
	s_movk_i32 s4, 0x440
	v_mad_u64_u32 v[100:101], s[8:9], v102, s4, v[100:101]
	s_mov_b64 s[8:9], 0

; #define EPI_LOOP(...) _Pragma("unroll") for(int ai=0;ai<2;++ai) _Pragma("unroll") for(int bj=0;bj<2;++bj) \
;   _Pragma("unroll") for(int m=0;m<4;++m) _Pragma("unroll") for(int n=0;n<2;++n) { \
;     const int row=brow+ai*128+wr*64+m*16+fq*4; const int col=bcol+bj*128+wc*32+n*16+fr; \
;     f32x4& v=acc[ai][bj][m][n]; __VA_ARGS__ if (n == 1 && (m & 1)) __builtin_amdgcn_sched_barrier(0); }
; DEVI void run_phase(const int ph, const Params& P, char* shmc, const int wave_u) {
;     ...
;       EPI_LOOP({ const int f = row - fb; long drow; bf16* d;
;         if (col < MP) { d = dp; drow = col; }
;         else if (col < MT) { const int s = col - MP; d = ds; drow = (long)(s >> 5) * SKS + 1024 + (s & 31); }
;         else { const int c = col - MT; d = ds; drow = (long)(c >> 10) * SKS + (c & 1023); }
;         st_bf4(d + drow * 1024 + f, v[0], v[1], v[2], v[3]); })
.LBB0_561:
	v_lshlrev_b64 v[100:101], 11, v[100:101]
	v_lshl_add_u64 v[100:101], s[8:9], 0, v[100:101]
	v_lshl_add_u64 v[100:101], v[130:131], 1, v[100:101]
	v_cvt_pk_bf16_f32 v94, v94, v95
	v_cvt_pk_bf16_f32 v95, v96, v97
	v_mov_b32_e32 v140, v94
	v_mov_b32_e32 v141, v95
	v_lshl_add_u64 v[138:139], v[100:101], 0, v[164:165]
	s_and_b64 vcc, exec, s[6:7]
	v_or_b32_e32 v94, 0x90, v32
	s_cbranch_vccnz .LBB0_567
	s_cmpk_lt_u32 s70, 0x4200
	s_mov_b64 s[8:9], -1
	s_cbranch_scc1 .LBB0_564
	v_add_u32_e32 v95, 0xffffbe90, v32
	v_lshrrev_b32_e32 v99, 10, v95
	v_and_b32_e32 v96, 0x3ff, v95
	v_mov_b32_e32 v97, v33
	s_movk_i32 s4, 0x440
	v_mad_u64_u32 v[96:97], s[8:9], v99, s4, v[96:97]
	s_mov_b64 s[8:9], 0

; #define EPI_LOOP(...) _Pragma("unroll") for(int ai=0;ai<2;++ai) _Pragma("unroll") for(int bj=0;bj<2;++bj) \
;   _Pragma("unroll") for(int m=0;m<4;++m) _Pragma("unroll") for(int n=0;n<2;++n) { \
;     const int row=brow+ai*128+wr*64+m*16+fq*4; const int col=bcol+bj*128+wc*32+n*16+fr; \
;     f32x4& v=acc[ai][bj][m][n]; __VA_ARGS__ if (n == 1 && (m & 1)) __builtin_amdgcn_sched_barrier(0); }
; DEVI void run_phase(const int ph, const Params& P, char* shmc, const int wave_u) {
;     ...
;       EPI_LOOP({ const int f = row - fb; long drow; bf16* d;
;         if (col < MP) { d = dp; drow = col; }
;         else if (col < MT) { const int s = col - MP; d = ds; drow = (long)(s >> 5) * SKS + 1024 + (s & 31); }
;         else { const int c = col - MT; d = ds; drow = (long)(c >> 10) * SKS + (c & 1023); }
;         st_bf4(d + drow * 1024 + f, v[0], v[1], v[2], v[3]); })
.LBB0_569:
	v_lshlrev_b64 v[96:97], 11, v[96:97]
	v_lshl_add_u64 v[96:97], s[8:9], 0, v[96:97]
	v_lshl_add_u64 v[96:97], v[130:131], 1, v[96:97]
	s_and_b64 vcc, exec, s[6:7]
	v_cvt_pk_bf16_f32 v90, v90, v91
	v_cvt_pk_bf16_f32 v91, v92, v93
	v_mov_b32_e32 v148, v90
	v_mov_b32_e32 v149, v91
	v_lshl_add_u64 v[144:145], v[96:97], 0, v[164:165]
	s_cbranch_vccnz .LBB0_575
	s_cmpk_lt_u32 s70, 0x4200
	s_mov_b64 s[8:9], -1
	s_cbranch_scc1 .LBB0_572
	v_add_u32_e32 v90, 0xffffbe80, v32
	v_lshrrev_b32_e32 v92, 10, v90
	v_and_b32_e32 v90, 0x3ef, v90
	v_mov_b32_e32 v91, v33
	s_movk_i32 s4, 0x440
	v_mad_u64_u32 v[90:91], s[8:9], v92, s4, v[90:91]
	s_mov_b64 s[8:9], 0

; #define EPI_LOOP(...) _Pragma("unroll") for(int ai=0;ai<2;++ai) _Pragma("unroll") for(int bj=0;bj<2;++bj) \
;   _Pragma("unroll") for(int m=0;m<4;++m) _Pragma("unroll") for(int n=0;n<2;++n) { \
;     const int row=brow+ai*128+wr*64+m*16+fq*4; const int col=bcol+bj*128+wc*32+n*16+fr; \
;     f32x4& v=acc[ai][bj][m][n]; __VA_ARGS__ if (n == 1 && (m & 1)) __builtin_amdgcn_sched_barrier(0); }
; DEVI void run_phase(const int ph, const Params& P, char* shmc, const int wave_u) {
;     ...
;       EPI_LOOP({ const int f = row - fb; long drow; bf16* d;
;         if (col < MP) { d = dp; drow = col; }
;         else if (col < MT) { const int s = col - MP; d = ds; drow = (long)(s >> 5) * SKS + 1024 + (s & 31); }
;         else { const int c = col - MT; d = ds; drow = (long)(c >> 10) * SKS + (c & 1023); }
;         st_bf4(d + drow * 1024 + f, v[0], v[1], v[2], v[3]); })
.LBB0_577:
	v_lshlrev_b64 v[90:91], 11, v[90:91]
	v_lshl_add_u64 v[90:91], s[8:9], 0, v[90:91]
	v_lshl_add_u64 v[90:91], v[130:131], 1, v[90:91]
	s_and_b64 vcc, exec, s[6:7]
	v_cvt_pk_bf16_f32 v86, v86, v87
	v_cvt_pk_bf16_f32 v87, v88, v89
	v_mov_b32_e32 v142, v86
	v_mov_b32_e32 v143, v87
	s_nop 1
	v_permlane16_swap_b32_e32 v140, v142
	v_permlane16_swap_b32_e32 v141, v143
	global_store_dwordx4 v[138:139], v[140:143], off
	s_cbranch_vccnz .LBB0_583
	s_cmpk_lt_u32 s70, 0x4200
	s_mov_b64 s[8:9], -1
	s_cbranch_scc1 .LBB0_580
	v_add_u32_e32 v86, 0xffffbe90, v32
	v_lshrrev_b32_e32 v88, 10, v86
	v_and_b32_e32 v86, 0x3ff, v86
	v_mov_b32_e32 v87, v33
	s_movk_i32 s4, 0x440
	v_mad_u64_u32 v[86:87], s[8:9], v88, s4, v[86:87]
	s_mov_b64 s[8:9], 0

; #define EPI_LOOP(...) _Pragma("unroll") for(int ai=0;ai<2;++ai) _Pragma("unroll") for(int bj=0;bj<2;++bj) \
;   _Pragma("unroll") for(int m=0;m<4;++m) _Pragma("unroll") for(int n=0;n<2;++n) { \
;     const int row=brow+ai*128+wr*64+m*16+fq*4; const int col=bcol+bj*128+wc*32+n*16+fr; \
;     f32x4& v=acc[ai][bj][m][n]; __VA_ARGS__ if (n == 1 && (m & 1)) __builtin_amdgcn_sched_barrier(0); }
; DEVI void run_phase(const int ph, const Params& P, char* shmc, const int wave_u) {
;     ...
;       EPI_LOOP({ const int f = row - fb; long drow; bf16* d;
;         if (col < MP) { d = dp; drow = col; }
;         else if (col < MT) { const int s = col - MP; d = ds; drow = (long)(s >> 5) * SKS + 1024 + (s & 31); }
;         else { const int c = col - MT; d = ds; drow = (long)(c >> 10) * SKS + (c & 1023); }
;         st_bf4(d + drow * 1024 + f, v[0], v[1], v[2], v[3]); })
.LBB0_585:
	v_lshlrev_b64 v[86:87], 11, v[86:87]
	v_lshl_add_u64 v[86:87], s[8:9], 0, v[86:87]
	v_lshl_add_u64 v[86:87], v[130:131], 1, v[86:87]
	v_cvt_pk_bf16_f32 v82, v82, v83
	v_cvt_pk_bf16_f32 v83, v84, v85
	v_mov_b32_e32 v150, v82
	v_mov_b32_e32 v151, v83
	s_nop 1
	v_permlane16_swap_b32_e32 v148, v150
	v_permlane16_swap_b32_e32 v149, v151
	global_store_dwordx4 v[144:145], v[148:151], off
	s_and_b64 vcc, exec, s[6:7]
	s_cbranch_vccnz .LBB0_591
	s_cmpk_lt_u32 s70, 0x4200
	s_mov_b64 s[8:9], -1
	s_cbranch_scc1 .LBB0_588
	v_add_u32_e32 v82, 0xffffbe80, v32
	v_lshrrev_b32_e32 v84, 10, v82
	v_and_b32_e32 v82, 0x3ef, v82
	v_mov_b32_e32 v83, v33
	s_movk_i32 s4, 0x440
	v_mad_u64_u32 v[82:83], s[8:9], v84, s4, v[82:83]
	s_mov_b64 s[8:9], 0

; #define EPI_LOOP(...) _Pragma("unroll") for(int ai=0;ai<2;++ai) _Pragma("unroll") for(int bj=0;bj<2;++bj) \
;   _Pragma("unroll") for(int m=0;m<4;++m) _Pragma("unroll") for(int n=0;n<2;++n) { \
;     const int row=brow+ai*128+wr*64+m*16+fq*4; const int col=bcol+bj*128+wc*32+n*16+fr; \
;     f32x4& v=acc[ai][bj][m][n]; __VA_ARGS__ if (n == 1 && (m & 1)) __builtin_amdgcn_sched_barrier(0); }
; DEVI void run_phase(const int ph, const Params& P, char* shmc, const int wave_u) {
;     ...
;       EPI_LOOP({ const int f = row - fb; long drow; bf16* d;
;         if (col < MP) { d = dp; drow = col; }
;         else if (col < MT) { const int s = col - MP; d = ds; drow = (long)(s >> 5) * SKS + 1024 + (s & 31); }
;         else { const int c = col - MT; d = ds; drow = (long)(c >> 10) * SKS + (c & 1023); }
;         st_bf4(d + drow * 1024 + f, v[0], v[1], v[2], v[3]); })
.LBB0_593:
	v_lshlrev_b64 v[82:83], 11, v[82:83]
	v_lshl_add_u64 v[82:83], s[8:9], 0, v[82:83]
	v_lshl_add_u64 v[82:83], v[130:131], 1, v[82:83]
	s_and_b64 vcc, exec, s[6:7]
	v_cvt_pk_bf16_f32 v78, v78, v79
	v_cvt_pk_bf16_f32 v79, v80, v81
	v_mov_b32_e32 v152, v78
	v_mov_b32_e32 v153, v79
	v_lshl_add_u64 v[160:161], v[82:83], 0, v[164:165]
	s_cbranch_vccnz .LBB0_599
	s_cmpk_lt_u32 s70, 0x4200
	s_mov_b64 s[8:9], -1
	s_cbranch_scc1 .LBB0_596
	v_add_u32_e32 v78, 0xffffbe90, v32
	v_lshrrev_b32_e32 v80, 10, v78
	v_and_b32_e32 v78, 0x3ff, v78
	v_mov_b32_e32 v79, v33
	s_movk_i32 s4, 0x440
	v_mad_u64_u32 v[78:79], s[8:9], v80, s4, v[78:79]
	s_mov_b64 s[8:9], 0

; #define EPI_LOOP(...) _Pragma("unroll") for(int ai=0;ai<2;++ai) _Pragma("unroll") for(int bj=0;bj<2;++bj) \
;   _Pragma("unroll") for(int m=0;m<4;++m) _Pragma("unroll") for(int n=0;n<2;++n) { \
;     const int row=brow+ai*128+wr*64+m*16+fq*4; const int col=bcol+bj*128+wc*32+n*16+fr; \
;     f32x4& v=acc[ai][bj][m][n]; __VA_ARGS__ if (n == 1 && (m & 1)) __builtin_amdgcn_sched_barrier(0); }
; DEVI void run_phase(const int ph, const Params& P, char* shmc, const int wave_u) {
;     ...
;       EPI_LOOP({ const int f = row - fb; long drow; bf16* d;
;         if (col < MP) { d = dp; drow = col; }
;         else if (col < MT) { const int s = col - MP; d = ds; drow = (long)(s >> 5) * SKS + 1024 + (s & 31); }
;         else { const int c = col - MT; d = ds; drow = (long)(c >> 10) * SKS + (c & 1023); }
;         st_bf4(d + drow * 1024 + f, v[0], v[1], v[2], v[3]); })
.LBB0_601:
	v_lshlrev_b64 v[78:79], 11, v[78:79]
	v_lshl_add_u64 v[78:79], s[8:9], 0, v[78:79]
	v_lshl_add_u64 v[78:79], v[130:131], 1, v[78:79]
	s_and_b64 vcc, exec, s[6:7]
	v_cvt_pk_bf16_f32 v74, v74, v75
	v_cvt_pk_bf16_f32 v75, v76, v77
	v_mov_b32_e32 v156, v74
	v_mov_b32_e32 v157, v75
	v_lshl_add_u64 v[162:163], v[78:79], 0, v[164:165]
	s_cbranch_vccnz .LBB0_607
	s_cmpk_lt_u32 s70, 0x4200
	s_mov_b64 s[8:9], -1
	s_cbranch_scc1 .LBB0_604
	v_add_u32_e32 v74, 0xffffbe80, v32
	v_lshrrev_b32_e32 v76, 10, v74
	v_and_b32_e32 v74, 0x3ef, v74
	v_mov_b32_e32 v75, v33
	s_movk_i32 s4, 0x440
	v_mad_u64_u32 v[74:75], s[8:9], v76, s4, v[74:75]
	s_mov_b64 s[8:9], 0

; #define EPI_LOOP(...) _Pragma("unroll") for(int ai=0;ai<2;++ai) _Pragma("unroll") for(int bj=0;bj<2;++bj) \
;   _Pragma("unroll") for(int m=0;m<4;++m) _Pragma("unroll") for(int n=0;n<2;++n) { \
;     const int row=brow+ai*128+wr*64+m*16+fq*4; const int col=bcol+bj*128+wc*32+n*16+fr; \
;     f32x4& v=acc[ai][bj][m][n]; __VA_ARGS__ if (n == 1 && (m & 1)) __builtin_amdgcn_sched_barrier(0); }
; DEVI void run_phase(const int ph, const Params& P, char* shmc, const int wave_u) {
;     ...
;       EPI_LOOP({ const int f = row - fb; long drow; bf16* d;
;         if (col < MP) { d = dp; drow = col; }
;         else if (col < MT) { const int s = col - MP; d = ds; drow = (long)(s >> 5) * SKS + 1024 + (s & 31); }
;         else { const int c = col - MT; d = ds; drow = (long)(c >> 10) * SKS + (c & 1023); }
;         st_bf4(d + drow * 1024 + f, v[0], v[1], v[2], v[3]); })
.LBB0_609:
	v_lshlrev_b64 v[74:75], 11, v[74:75]
	v_lshl_add_u64 v[74:75], s[8:9], 0, v[74:75]
	v_lshl_add_u64 v[74:75], v[130:131], 1, v[74:75]
	s_and_b64 vcc, exec, s[6:7]
	v_cvt_pk_bf16_f32 v70, v70, v71
	v_cvt_pk_bf16_f32 v71, v72, v73
	v_mov_b32_e32 v154, v70
	v_mov_b32_e32 v155, v71
	s_nop 1
	v_permlane16_swap_b32_e32 v152, v154
	v_permlane16_swap_b32_e32 v153, v155
	global_store_dwordx4 v[160:161], v[152:155], off offset:64
	s_cbranch_vccnz .LBB0_615
	s_cmpk_lt_u32 s70, 0x4200
	s_mov_b64 s[8:9], -1
	s_cbranch_scc1 .LBB0_612
	v_add_u32_e32 v70, 0xffffbe90, v32
	v_lshrrev_b32_e32 v72, 10, v70
	v_and_b32_e32 v70, 0x3ff, v70
	v_mov_b32_e32 v71, v33
	s_movk_i32 s4, 0x440
	v_mad_u64_u32 v[70:71], s[8:9], v72, s4, v[70:71]
	s_mov_b64 s[8:9], 0

; #define EPI_LOOP(...) _Pragma("unroll") for(int ai=0;ai<2;++ai) _Pragma("unroll") for(int bj=0;bj<2;++bj) \
;   _Pragma("unroll") for(int m=0;m<4;++m) _Pragma("unroll") for(int n=0;n<2;++n) { \
;     const int row=brow+ai*128+wr*64+m*16+fq*4; const int col=bcol+bj*128+wc*32+n*16+fr; \
;     f32x4& v=acc[ai][bj][m][n]; __VA_ARGS__ if (n == 1 && (m & 1)) __builtin_amdgcn_sched_barrier(0); }
; DEVI void run_phase(const int ph, const Params& P, char* shmc, const int wave_u) {
;     ...
;       EPI_LOOP({ const int f = row - fb; long drow; bf16* d;
;         if (col < MP) { d = dp; drow = col; }
;         else if (col < MT) { const int s = col - MP; d = ds; drow = (long)(s >> 5) * SKS + 1024 + (s & 31); }
;         else { const int c = col - MT; d = ds; drow = (long)(c >> 10) * SKS + (c & 1023); }
;         st_bf4(d + drow * 1024 + f, v[0], v[1], v[2], v[3]); })
.LBB0_617:
	v_lshlrev_b64 v[70:71], 11, v[70:71]
	v_lshl_add_u64 v[70:71], s[8:9], 0, v[70:71]
	v_lshl_add_u64 v[70:71], v[130:131], 1, v[70:71]
	v_cvt_pk_bf16_f32 v66, v66, v67
	v_cvt_pk_bf16_f32 v67, v68, v69
	v_mov_b32_e32 v158, v66
	v_mov_b32_e32 v159, v67
	s_nop 1
	v_permlane16_swap_b32_e32 v156, v158
	v_permlane16_swap_b32_e32 v157, v159
	global_store_dwordx4 v[162:163], v[156:159], off offset:64
	s_and_b64 vcc, exec, s[6:7]
	s_cbranch_vccnz .LBB0_623
	s_cmpk_lt_u32 s70, 0x4200
	s_mov_b64 s[8:9], -1
	s_cbranch_scc1 .LBB0_620
	v_add_u32_e32 v66, 0xffffbe00, v32
	v_lshrrev_b32_e32 v68, 10, v66
	v_and_b32_e32 v66, 0x36f, v66
	v_mov_b32_e32 v67, v33
	s_movk_i32 s4, 0x440
	v_mad_u64_u32 v[66:67], s[8:9], v68, s4, v[66:67]
	s_mov_b64 s[8:9], 0

; #define EPI_LOOP(...) _Pragma("unroll") for(int ai=0;ai<2;++ai) _Pragma("unroll") for(int bj=0;bj<2;++bj) \
;   _Pragma("unroll") for(int m=0;m<4;++m) _Pragma("unroll") for(int n=0;n<2;++n) { \
;     const int row=brow+ai*128+wr*64+m*16+fq*4; const int col=bcol+bj*128+wc*32+n*16+fr; \
;     f32x4& v=acc[ai][bj][m][n]; __VA_ARGS__ if (n == 1 && (m & 1)) __builtin_amdgcn_sched_barrier(0); }
; DEVI void run_phase(const int ph, const Params& P, char* shmc, const int wave_u) {
;     ...
;       EPI_LOOP({ const int f = row - fb; long drow; bf16* d;
;         if (col < MP) { d = dp; drow = col; }
;         else if (col < MT) { const int s = col - MP; d = ds; drow = (long)(s >> 5) * SKS + 1024 + (s & 31); }
;         else { const int c = col - MT; d = ds; drow = (long)(c >> 10) * SKS + (c & 1023); }
;         st_bf4(d + drow * 1024 + f, v[0], v[1], v[2], v[3]); })
.LBB0_625:
	v_lshlrev_b64 v[66:67], 11, v[66:67]
	v_lshl_add_u64 v[66:67], s[8:9], 0, v[66:67]
	v_lshl_add_u64 v[66:67], v[130:131], 1, v[66:67]
	s_and_b64 vcc, exec, s[6:7]
	v_cvt_pk_bf16_f32 v62, v62, v63
	v_cvt_pk_bf16_f32 v63, v64, v65
	v_mov_b32_e32 v140, v62
	v_mov_b32_e32 v141, v63
	v_lshl_add_u64 v[138:139], v[66:67], 0, v[164:165]
	s_cbranch_vccnz .LBB0_631
	s_cmpk_lt_u32 s70, 0x4200
	s_mov_b64 s[8:9], -1
	s_cbranch_scc1 .LBB0_628
	v_add_u32_e32 v62, 0xffffbe10, v32
	v_lshrrev_b32_e32 v64, 10, v62
	v_and_b32_e32 v62, 0x37f, v62
	v_mov_b32_e32 v63, v33
	s_movk_i32 s4, 0x440
	v_mad_u64_u32 v[62:63], s[8:9], v64, s4, v[62:63]
	s_mov_b64 s[8:9], 0

; #define EPI_LOOP(...) _Pragma("unroll") for(int ai=0;ai<2;++ai) _Pragma("unroll") for(int bj=0;bj<2;++bj) \
;   _Pragma("unroll") for(int m=0;m<4;++m) _Pragma("unroll") for(int n=0;n<2;++n) { \
;     const int row=brow+ai*128+wr*64+m*16+fq*4; const int col=bcol+bj*128+wc*32+n*16+fr; \
;     f32x4& v=acc[ai][bj][m][n]; __VA_ARGS__ if (n == 1 && (m & 1)) __builtin_amdgcn_sched_barrier(0); }
; DEVI void run_phase(const int ph, const Params& P, char* shmc, const int wave_u) {
;     ...
;       EPI_LOOP({ const int f = row - fb; long drow; bf16* d;
;         if (col < MP) { d = dp; drow = col; }
;         else if (col < MT) { const int s = col - MP; d = ds; drow = (long)(s >> 5) * SKS + 1024 + (s & 31); }
;         else { const int c = col - MT; d = ds; drow = (long)(c >> 10) * SKS + (c & 1023); }
;         st_bf4(d + drow * 1024 + f, v[0], v[1], v[2], v[3]); })
.LBB0_633:
	v_lshlrev_b64 v[62:63], 11, v[62:63]
	v_lshl_add_u64 v[62:63], s[8:9], 0, v[62:63]
	v_lshl_add_u64 v[62:63], v[130:131], 1, v[62:63]
	s_and_b64 vcc, exec, s[6:7]
	v_cvt_pk_bf16_f32 v58, v58, v59
	v_cvt_pk_bf16_f32 v59, v60, v61
	v_mov_b32_e32 v148, v58
	v_mov_b32_e32 v149, v59
	v_lshl_add_u64 v[144:145], v[62:63], 0, v[164:165]
	s_cbranch_vccnz .LBB0_639
	s_cmpk_lt_u32 s70, 0x4200
	s_mov_b64 s[8:9], -1
	s_cbranch_scc1 .LBB0_636
	v_add_u32_e32 v58, 0xffffbe00, v32
	v_lshrrev_b32_e32 v60, 10, v58
	v_and_b32_e32 v58, 0x36f, v58
	v_mov_b32_e32 v59, v33
	s_movk_i32 s4, 0x440
	v_mad_u64_u32 v[58:59], s[8:9], v60, s4, v[58:59]
	s_mov_b64 s[8:9], 0

; #define EPI_LOOP(...) _Pragma("unroll") for(int ai=0;ai<2;++ai) _Pragma("unroll") for(int bj=0;bj<2;++bj) \
;   _Pragma("unroll") for(int m=0;m<4;++m) _Pragma("unroll") for(int n=0;n<2;++n) { \
;     const int row=brow+ai*128+wr*64+m*16+fq*4; const int col=bcol+bj*128+wc*32+n*16+fr; \
;     f32x4& v=acc[ai][bj][m][n]; __VA_ARGS__ if (n == 1 && (m & 1)) __builtin_amdgcn_sched_barrier(0); }
; DEVI void run_phase(const int ph, const Params& P, char* shmc, const int wave_u) {
;     ...
;       EPI_LOOP({ const int f = row - fb; long drow; bf16* d;
;         if (col < MP) { d = dp; drow = col; }
;         else if (col < MT) { const int s = col - MP; d = ds; drow = (long)(s >> 5) * SKS + 1024 + (s & 31); }
;         else { const int c = col - MT; d = ds; drow = (long)(c >> 10) * SKS + (c & 1023); }
;         st_bf4(d + drow * 1024 + f, v[0], v[1], v[2], v[3]); })
.LBB0_641:
	v_lshlrev_b64 v[58:59], 11, v[58:59]
	v_lshl_add_u64 v[58:59], s[8:9], 0, v[58:59]
	v_lshl_add_u64 v[58:59], v[130:131], 1, v[58:59]
	s_and_b64 vcc, exec, s[6:7]
	v_cvt_pk_bf16_f32 v54, v54, v55
	v_cvt_pk_bf16_f32 v55, v56, v57
	v_mov_b32_e32 v142, v54
	v_mov_b32_e32 v143, v55
	s_nop 1
	v_permlane16_swap_b32_e32 v140, v142
	v_permlane16_swap_b32_e32 v141, v143
	global_store_dwordx4 v[138:139], v[140:143], off offset:256
	s_cbranch_vccnz .LBB0_647
	s_cmpk_lt_u32 s70, 0x4200
	s_mov_b64 s[8:9], -1
	s_cbranch_scc1 .LBB0_644
	v_add_u32_e32 v54, 0xffffbe10, v32
	v_lshrrev_b32_e32 v56, 10, v54
	v_and_b32_e32 v54, 0x37f, v54
	v_mov_b32_e32 v55, v33
	s_movk_i32 s4, 0x440
	v_mad_u64_u32 v[54:55], s[8:9], v56, s4, v[54:55]
	s_mov_b64 s[8:9], 0

; #define EPI_LOOP(...) _Pragma("unroll") for(int ai=0;ai<2;++ai) _Pragma("unroll") for(int bj=0;bj<2;++bj) \
;   _Pragma("unroll") for(int m=0;m<4;++m) _Pragma("unroll") for(int n=0;n<2;++n) { \
;     const int row=brow+ai*128+wr*64+m*16+fq*4; const int col=bcol+bj*128+wc*32+n*16+fr; \
;     f32x4& v=acc[ai][bj][m][n]; __VA_ARGS__ if (n == 1 && (m & 1)) __builtin_amdgcn_sched_barrier(0); }
; DEVI void run_phase(const int ph, const Params& P, char* shmc, const int wave_u) {
;     ...
;       EPI_LOOP({ const int f = row - fb; long drow; bf16* d;
;         if (col < MP) { d = dp; drow = col; }
;         else if (col < MT) { const int s = col - MP; d = ds; drow = (long)(s >> 5) * SKS + 1024 + (s & 31); }
;         else { const int c = col - MT; d = ds; drow = (long)(c >> 10) * SKS + (c & 1023); }
;         st_bf4(d + drow * 1024 + f, v[0], v[1], v[2], v[3]); })
.LBB0_649:
	v_lshlrev_b64 v[54:55], 11, v[54:55]
	v_lshl_add_u64 v[54:55], s[8:9], 0, v[54:55]
	v_lshl_add_u64 v[54:55], v[130:131], 1, v[54:55]
	v_cvt_pk_bf16_f32 v50, v50, v51
	v_cvt_pk_bf16_f32 v51, v52, v53
	v_mov_b32_e32 v150, v50
	v_mov_b32_e32 v151, v51
	s_nop 1
	v_permlane16_swap_b32_e32 v148, v150
	v_permlane16_swap_b32_e32 v149, v151
	global_store_dwordx4 v[144:145], v[148:151], off offset:256
	s_and_b64 vcc, exec, s[6:7]
	s_cbranch_vccnz .LBB0_655
	s_cmpk_lt_u32 s70, 0x4200
	s_mov_b64 s[8:9], -1
	s_cbranch_scc1 .LBB0_652
	v_add_u32_e32 v50, 0xffffbe00, v32
	v_lshrrev_b32_e32 v52, 10, v50
	v_and_b32_e32 v50, 0x36f, v50
	v_mov_b32_e32 v51, v33
	s_movk_i32 s4, 0x440
	v_mad_u64_u32 v[50:51], s[8:9], v52, s4, v[50:51]
	s_mov_b64 s[8:9], 0

; #define EPI_LOOP(...) _Pragma("unroll") for(int ai=0;ai<2;++ai) _Pragma("unroll") for(int bj=0;bj<2;++bj) \
;   _Pragma("unroll") for(int m=0;m<4;++m) _Pragma("unroll") for(int n=0;n<2;++n) { \
;     const int row=brow+ai*128+wr*64+m*16+fq*4; const int col=bcol+bj*128+wc*32+n*16+fr; \
;     f32x4& v=acc[ai][bj][m][n]; __VA_ARGS__ if (n == 1 && (m & 1)) __builtin_amdgcn_sched_barrier(0); }
; DEVI void run_phase(const int ph, const Params& P, char* shmc, const int wave_u) {
;     ...
;       EPI_LOOP({ const int f = row - fb; long drow; bf16* d;
;         if (col < MP) { d = dp; drow = col; }
;         else if (col < MT) { const int s = col - MP; d = ds; drow = (long)(s >> 5) * SKS + 1024 + (s & 31); }
;         else { const int c = col - MT; d = ds; drow = (long)(c >> 10) * SKS + (c & 1023); }
;         st_bf4(d + drow * 1024 + f, v[0], v[1], v[2], v[3]); })
.LBB0_657:
	v_lshlrev_b64 v[50:51], 11, v[50:51]
	v_lshl_add_u64 v[50:51], s[8:9], 0, v[50:51]
	v_lshl_add_u64 v[50:51], v[130:131], 1, v[50:51]
	s_and_b64 vcc, exec, s[6:7]
	v_cvt_pk_bf16_f32 v46, v46, v47
	v_cvt_pk_bf16_f32 v47, v48, v49
	v_mov_b32_e32 v152, v46
	v_mov_b32_e32 v153, v47
	v_lshl_add_u64 v[160:161], v[50:51], 0, v[164:165]
	s_cbranch_vccnz .LBB0_663
	s_cmpk_lt_u32 s70, 0x4200
	s_mov_b64 s[8:9], -1
	s_cbranch_scc1 .LBB0_660
	v_add_u32_e32 v46, 0xffffbe10, v32
	v_lshrrev_b32_e32 v48, 10, v46
	v_and_b32_e32 v46, 0x37f, v46
	v_mov_b32_e32 v47, v33
	s_movk_i32 s4, 0x440
	v_mad_u64_u32 v[46:47], s[8:9], v48, s4, v[46:47]
	s_mov_b64 s[8:9], 0

; #define EPI_LOOP(...) _Pragma("unroll") for(int ai=0;ai<2;++ai) _Pragma("unroll") for(int bj=0;bj<2;++bj) \
;   _Pragma("unroll") for(int m=0;m<4;++m) _Pragma("unroll") for(int n=0;n<2;++n) { \
;     const int row=brow+ai*128+wr*64+m*16+fq*4; const int col=bcol+bj*128+wc*32+n*16+fr; \
;     f32x4& v=acc[ai][bj][m][n]; __VA_ARGS__ if (n == 1 && (m & 1)) __builtin_amdgcn_sched_barrier(0); }
; DEVI void run_phase(const int ph, const Params& P, char* shmc, const int wave_u) {
;     ...
;       EPI_LOOP({ const int f = row - fb; long drow; bf16* d;
;         if (col < MP) { d = dp; drow = col; }
;         else if (col < MT) { const int s = col - MP; d = ds; drow = (long)(s >> 5) * SKS + 1024 + (s & 31); }
;         else { const int c = col - MT; d = ds; drow = (long)(c >> 10) * SKS + (c & 1023); }
;         st_bf4(d + drow * 1024 + f, v[0], v[1], v[2], v[3]); })
.LBB0_665:
	v_lshlrev_b64 v[46:47], 11, v[46:47]
	v_lshl_add_u64 v[46:47], s[8:9], 0, v[46:47]
	v_lshl_add_u64 v[46:47], v[130:131], 1, v[46:47]
	s_and_b64 vcc, exec, s[6:7]
	v_cvt_pk_bf16_f32 v42, v42, v43
	v_cvt_pk_bf16_f32 v43, v44, v45
	v_mov_b32_e32 v156, v42
	v_mov_b32_e32 v157, v43
	v_lshl_add_u64 v[162:163], v[46:47], 0, v[164:165]
	s_cbranch_vccnz .LBB0_671
	s_cmpk_lt_u32 s70, 0x4200
	s_mov_b64 s[8:9], -1
	s_cbranch_scc1 .LBB0_668
	v_add_u32_e32 v42, 0xffffbe00, v32
	v_lshrrev_b32_e32 v44, 10, v42
	v_and_b32_e32 v42, 0x36f, v42
	v_mov_b32_e32 v43, v33
	s_movk_i32 s4, 0x440
	v_mad_u64_u32 v[42:43], s[8:9], v44, s4, v[42:43]
	s_mov_b64 s[8:9], 0

; #define EPI_LOOP(...) _Pragma("unroll") for(int ai=0;ai<2;++ai) _Pragma("unroll") for(int bj=0;bj<2;++bj) \
;   _Pragma("unroll") for(int m=0;m<4;++m) _Pragma("unroll") for(int n=0;n<2;++n) { \
;     const int row=brow+ai*128+wr*64+m*16+fq*4; const int col=bcol+bj*128+wc*32+n*16+fr; \
;     f32x4& v=acc[ai][bj][m][n]; __VA_ARGS__ if (n == 1 && (m & 1)) __builtin_amdgcn_sched_barrier(0); }
; DEVI void run_phase(const int ph, const Params& P, char* shmc, const int wave_u) {
;     ...
;       EPI_LOOP({ const int f = row - fb; long drow; bf16* d;
;         if (col < MP) { d = dp; drow = col; }
;         else if (col < MT) { const int s = col - MP; d = ds; drow = (long)(s >> 5) * SKS + 1024 + (s & 31); }
;         else { const int c = col - MT; d = ds; drow = (long)(c >> 10) * SKS + (c & 1023); }
;         st_bf4(d + drow * 1024 + f, v[0], v[1], v[2], v[3]); })
.LBB0_673:
	v_lshlrev_b64 v[42:43], 11, v[42:43]
	v_lshl_add_u64 v[42:43], s[8:9], 0, v[42:43]
	v_lshl_add_u64 v[42:43], v[130:131], 1, v[42:43]
	s_and_b64 vcc, exec, s[6:7]
	v_cvt_pk_bf16_f32 v38, v38, v39
	v_cvt_pk_bf16_f32 v39, v40, v41
	v_mov_b32_e32 v154, v38
	v_mov_b32_e32 v155, v39
	s_nop 1
	v_permlane16_swap_b32_e32 v152, v154
	v_permlane16_swap_b32_e32 v153, v155
	global_store_dwordx4 v[160:161], v[152:155], off offset:320
	s_cbranch_vccnz .LBB0_679
	s_cmpk_lt_u32 s70, 0x4200
	s_mov_b64 s[8:9], -1
	s_cbranch_scc1 .LBB0_676
	v_add_u32_e32 v38, 0xffffbe10, v32
	v_lshrrev_b32_e32 v40, 10, v38
	v_and_b32_e32 v38, 0x37f, v38
	v_mov_b32_e32 v39, v33
	s_movk_i32 s4, 0x440
	v_mad_u64_u32 v[126:127], s[8:9], v40, s4, v[38:39]
	s_mov_b64 s[8:9], 0

; #define EPI_LOOP(...) _Pragma("unroll") for(int ai=0;ai<2;++ai) _Pragma("unroll") for(int bj=0;bj<2;++bj) \
;   _Pragma("unroll") for(int m=0;m<4;++m) _Pragma("unroll") for(int n=0;n<2;++n) { \
;     const int row=brow+ai*128+wr*64+m*16+fq*4; const int col=bcol+bj*128+wc*32+n*16+fr; \
;     f32x4& v=acc[ai][bj][m][n]; __VA_ARGS__ if (n == 1 && (m & 1)) __builtin_amdgcn_sched_barrier(0); }
; DEVI void run_phase(const int ph, const Params& P, char* shmc, const int wave_u) {
;     ...
;       EPI_LOOP({ const int f = row - fb; long drow; bf16* d;
;         if (col < MP) { d = dp; drow = col; }
;         else if (col < MT) { const int s = col - MP; d = ds; drow = (long)(s >> 5) * SKS + 1024 + (s & 31); }
;         else { const int c = col - MT; d = ds; drow = (long)(c >> 10) * SKS + (c & 1023); }
;         st_bf4(d + drow * 1024 + f, v[0], v[1], v[2], v[3]); })
.LBB0_681:
	v_lshlrev_b64 v[38:39], 11, v[126:127]
	v_lshl_add_u64 v[38:39], s[8:9], 0, v[38:39]
	v_lshl_add_u64 v[38:39], v[130:131], 1, v[38:39]
	v_cvt_pk_bf16_f32 v34, v34, v35
	v_cvt_pk_bf16_f32 v35, v36, v37
	v_mov_b32_e32 v158, v34
	v_mov_b32_e32 v159, v35
	s_nop 1
	v_permlane16_swap_b32_e32 v156, v158
	v_permlane16_swap_b32_e32 v157, v159
	global_store_dwordx4 v[162:163], v[156:159], off offset:320
	s_and_b64 vcc, exec, s[6:7]
	s_cbranch_vccnz .LBB0_687
	s_cmpk_lt_u32 s70, 0x4200
	s_mov_b64 s[8:9], -1
	s_cbranch_scc1 .LBB0_684
	v_add_u32_e32 v34, 0xffffbe80, v32
	v_lshrrev_b32_e32 v36, 10, v34
	v_and_b32_e32 v34, 0x3ef, v34
	v_mov_b32_e32 v35, v33
	s_movk_i32 s4, 0x440
	v_mad_u64_u32 v[34:35], s[8:9], v36, s4, v[34:35]
	s_mov_b64 s[8:9], 0

; #define EPI_LOOP(...) _Pragma("unroll") for(int ai=0;ai<2;++ai) _Pragma("unroll") for(int bj=0;bj<2;++bj) \
;   _Pragma("unroll") for(int m=0;m<4;++m) _Pragma("unroll") for(int n=0;n<2;++n) { \
;     const int row=brow+ai*128+wr*64+m*16+fq*4; const int col=bcol+bj*128+wc*32+n*16+fr; \
;     f32x4& v=acc[ai][bj][m][n]; __VA_ARGS__ if (n == 1 && (m & 1)) __builtin_amdgcn_sched_barrier(0); }
; DEVI void run_phase(const int ph, const Params& P, char* shmc, const int wave_u) {
;     ...
;       EPI_LOOP({ const int f = row - fb; long drow; bf16* d;
;         if (col < MP) { d = dp; drow = col; }
;         else if (col < MT) { const int s = col - MP; d = ds; drow = (long)(s >> 5) * SKS + 1024 + (s & 31); }
;         else { const int c = col - MT; d = ds; drow = (long)(c >> 10) * SKS + (c & 1023); }
;         st_bf4(d + drow * 1024 + f, v[0], v[1], v[2], v[3]); })
.LBB0_689:
	v_lshlrev_b64 v[34:35], 11, v[34:35]
	v_lshl_add_u64 v[34:35], s[8:9], 0, v[34:35]
	v_lshl_add_u64 v[34:35], v[130:131], 1, v[34:35]
	s_and_b64 vcc, exec, s[6:7]
	v_cvt_pk_bf16_f32 v28, v28, v29
	v_cvt_pk_bf16_f32 v29, v30, v31
	v_mov_b32_e32 v140, v28
	v_mov_b32_e32 v141, v29
	v_lshl_add_u64 v[138:139], v[34:35], 0, v[164:165]
	s_cbranch_vccnz .LBB0_695
	s_cmpk_lt_u32 s70, 0x4200
	s_mov_b64 s[8:9], -1
	s_cbranch_scc1 .LBB0_692
	v_add_u32_e32 v28, 0xffffbe90, v32
	v_lshrrev_b32_e32 v30, 10, v28
	v_and_b32_e32 v28, 0x3ff, v28
	v_mov_b32_e32 v29, v33
	s_movk_i32 s4, 0x440
	v_mad_u64_u32 v[28:29], s[8:9], v30, s4, v[28:29]
	s_mov_b64 s[8:9], 0

; #define EPI_LOOP(...) _Pragma("unroll") for(int ai=0;ai<2;++ai) _Pragma("unroll") for(int bj=0;bj<2;++bj) \
;   _Pragma("unroll") for(int m=0;m<4;++m) _Pragma("unroll") for(int n=0;n<2;++n) { \
;     const int row=brow+ai*128+wr*64+m*16+fq*4; const int col=bcol+bj*128+wc*32+n*16+fr; \
;     f32x4& v=acc[ai][bj][m][n]; __VA_ARGS__ if (n == 1 && (m & 1)) __builtin_amdgcn_sched_barrier(0); }
; DEVI void run_phase(const int ph, const Params& P, char* shmc, const int wave_u) {
;     ...
;       EPI_LOOP({ const int f = row - fb; long drow; bf16* d;
;         if (col < MP) { d = dp; drow = col; }
;         else if (col < MT) { const int s = col - MP; d = ds; drow = (long)(s >> 5) * SKS + 1024 + (s & 31); }
;         else { const int c = col - MT; d = ds; drow = (long)(c >> 10) * SKS + (c & 1023); }
;         st_bf4(d + drow * 1024 + f, v[0], v[1], v[2], v[3]); })
.LBB0_697:
	v_lshlrev_b64 v[28:29], 11, v[28:29]
	v_lshl_add_u64 v[28:29], s[8:9], 0, v[28:29]
	v_lshl_add_u64 v[28:29], v[130:131], 1, v[28:29]
	s_and_b64 vcc, exec, s[6:7]
	v_cvt_pk_bf16_f32 v24, v24, v25
	v_cvt_pk_bf16_f32 v25, v26, v27
	v_mov_b32_e32 v148, v24
	v_mov_b32_e32 v149, v25
	v_lshl_add_u64 v[144:145], v[28:29], 0, v[164:165]
	s_cbranch_vccnz .LBB0_703
	s_cmpk_lt_u32 s70, 0x4200
	s_mov_b64 s[8:9], -1
	s_cbranch_scc1 .LBB0_700
	v_add_u32_e32 v24, 0xffffbe80, v32
	v_lshrrev_b32_e32 v26, 10, v24
	v_and_b32_e32 v24, 0x3ef, v24
	v_mov_b32_e32 v25, v33
	s_movk_i32 s4, 0x440
	v_mad_u64_u32 v[24:25], s[8:9], v26, s4, v[24:25]
	s_mov_b64 s[8:9], 0

; #define EPI_LOOP(...) _Pragma("unroll") for(int ai=0;ai<2;++ai) _Pragma("unroll") for(int bj=0;bj<2;++bj) \
;   _Pragma("unroll") for(int m=0;m<4;++m) _Pragma("unroll") for(int n=0;n<2;++n) { \
;     const int row=brow+ai*128+wr*64+m*16+fq*4; const int col=bcol+bj*128+wc*32+n*16+fr; \
;     f32x4& v=acc[ai][bj][m][n]; __VA_ARGS__ if (n == 1 && (m & 1)) __builtin_amdgcn_sched_barrier(0); }
; DEVI void run_phase(const int ph, const Params& P, char* shmc, const int wave_u) {
;     ...
;       EPI_LOOP({ const int f = row - fb; long drow; bf16* d;
;         if (col < MP) { d = dp; drow = col; }
;         else if (col < MT) { const int s = col - MP; d = ds; drow = (long)(s >> 5) * SKS + 1024 + (s & 31); }
;         else { const int c = col - MT; d = ds; drow = (long)(c >> 10) * SKS + (c & 1023); }
;         st_bf4(d + drow * 1024 + f, v[0], v[1], v[2], v[3]); })
.LBB0_705:
	v_lshlrev_b64 v[24:25], 11, v[24:25]
	v_lshl_add_u64 v[24:25], s[8:9], 0, v[24:25]
	v_lshl_add_u64 v[24:25], v[130:131], 1, v[24:25]
	s_and_b64 vcc, exec, s[6:7]
	v_cvt_pk_bf16_f32 v20, v20, v21
	v_cvt_pk_bf16_f32 v21, v22, v23
	v_mov_b32_e32 v142, v20
	v_mov_b32_e32 v143, v21
	s_nop 1
	v_permlane16_swap_b32_e32 v140, v142
	v_permlane16_swap_b32_e32 v141, v143
	global_store_dwordx4 v[138:139], v[140:143], off offset:256
	s_cbranch_vccnz .LBB0_711
	s_cmpk_lt_u32 s70, 0x4200
	s_mov_b64 s[8:9], -1
	s_cbranch_scc1 .LBB0_708
	v_add_u32_e32 v20, 0xffffbe90, v32
	v_lshrrev_b32_e32 v22, 10, v20
	v_and_b32_e32 v20, 0x3ff, v20
	v_mov_b32_e32 v21, v33
	s_movk_i32 s4, 0x440
	v_mad_u64_u32 v[20:21], s[8:9], v22, s4, v[20:21]
	s_mov_b64 s[8:9], 0

; #define EPI_LOOP(...) _Pragma("unroll") for(int ai=0;ai<2;++ai) _Pragma("unroll") for(int bj=0;bj<2;++bj) \
;   _Pragma("unroll") for(int m=0;m<4;++m) _Pragma("unroll") for(int n=0;n<2;++n) { \
;     const int row=brow+ai*128+wr*64+m*16+fq*4; const int col=bcol+bj*128+wc*32+n*16+fr; \
;     f32x4& v=acc[ai][bj][m][n]; __VA_ARGS__ if (n == 1 && (m & 1)) __builtin_amdgcn_sched_barrier(0); }
; DEVI void run_phase(const int ph, const Params& P, char* shmc, const int wave_u) {
;     ...
;       EPI_LOOP({ const int f = row - fb; long drow; bf16* d;
;         if (col < MP) { d = dp; drow = col; }
;         else if (col < MT) { const int s = col - MP; d = ds; drow = (long)(s >> 5) * SKS + 1024 + (s & 31); }
;         else { const int c = col - MT; d = ds; drow = (long)(c >> 10) * SKS + (c & 1023); }
;         st_bf4(d + drow * 1024 + f, v[0], v[1], v[2], v[3]); })
.LBB0_713:
	v_lshlrev_b64 v[20:21], 11, v[20:21]
	v_lshl_add_u64 v[20:21], s[8:9], 0, v[20:21]
	v_lshl_add_u64 v[20:21], v[130:131], 1, v[20:21]
	v_cvt_pk_bf16_f32 v16, v16, v17
	v_cvt_pk_bf16_f32 v17, v18, v19
	v_mov_b32_e32 v150, v16
	v_mov_b32_e32 v151, v17
	s_nop 1
	v_permlane16_swap_b32_e32 v148, v150
	v_permlane16_swap_b32_e32 v149, v151
	global_store_dwordx4 v[144:145], v[148:151], off offset:256
	s_and_b64 vcc, exec, s[6:7]
	s_cbranch_vccnz .LBB0_719
	s_cmpk_lt_u32 s70, 0x4200
	s_mov_b64 s[8:9], -1
	s_cbranch_scc1 .LBB0_716
	v_add_u32_e32 v16, 0xffffbe80, v32
	v_lshrrev_b32_e32 v18, 10, v16
	v_and_b32_e32 v16, 0x3ef, v16
	v_mov_b32_e32 v17, v33
	s_movk_i32 s4, 0x440
	v_mad_u64_u32 v[16:17], s[8:9], v18, s4, v[16:17]
	s_mov_b64 s[8:9], 0

; #define EPI_LOOP(...) _Pragma("unroll") for(int ai=0;ai<2;++ai) _Pragma("unroll") for(int bj=0;bj<2;++bj) \
;   _Pragma("unroll") for(int m=0;m<4;++m) _Pragma("unroll") for(int n=0;n<2;++n) { \
;     const int row=brow+ai*128+wr*64+m*16+fq*4; const int col=bcol+bj*128+wc*32+n*16+fr; \
;     f32x4& v=acc[ai][bj][m][n]; __VA_ARGS__ if (n == 1 && (m & 1)) __builtin_amdgcn_sched_barrier(0); }
; DEVI void run_phase(const int ph, const Params& P, char* shmc, const int wave_u) {
;     ...
;       EPI_LOOP({ const int f = row - fb; long drow; bf16* d;
;         if (col < MP) { d = dp; drow = col; }
;         else if (col < MT) { const int s = col - MP; d = ds; drow = (long)(s >> 5) * SKS + 1024 + (s & 31); }
;         else { const int c = col - MT; d = ds; drow = (long)(c >> 10) * SKS + (c & 1023); }
;         st_bf4(d + drow * 1024 + f, v[0], v[1], v[2], v[3]); })
.LBB0_721:
	v_lshlrev_b64 v[16:17], 11, v[16:17]
	v_lshl_add_u64 v[16:17], s[8:9], 0, v[16:17]
	v_lshl_add_u64 v[16:17], v[130:131], 1, v[16:17]
	s_and_b64 vcc, exec, s[6:7]
	v_cvt_pk_bf16_f32 v12, v12, v13
	v_cvt_pk_bf16_f32 v13, v14, v15
	v_mov_b32_e32 v152, v12
	v_mov_b32_e32 v153, v13
	v_lshl_add_u64 v[160:161], v[16:17], 0, v[164:165]
	s_cbranch_vccnz .LBB0_727
	s_cmpk_lt_u32 s70, 0x4200
	s_mov_b64 s[8:9], -1
	s_cbranch_scc1 .LBB0_724
	v_add_u32_e32 v12, 0xffffbe90, v32
	v_lshrrev_b32_e32 v14, 10, v12
	v_and_b32_e32 v12, 0x3ff, v12
	v_mov_b32_e32 v13, v33
	s_movk_i32 s4, 0x440
	v_mad_u64_u32 v[12:13], s[8:9], v14, s4, v[12:13]
	s_mov_b64 s[8:9], 0

; #define EPI_LOOP(...) _Pragma("unroll") for(int ai=0;ai<2;++ai) _Pragma("unroll") for(int bj=0;bj<2;++bj) \
;   _Pragma("unroll") for(int m=0;m<4;++m) _Pragma("unroll") for(int n=0;n<2;++n) { \
;     const int row=brow+ai*128+wr*64+m*16+fq*4; const int col=bcol+bj*128+wc*32+n*16+fr; \
;     f32x4& v=acc[ai][bj][m][n]; __VA_ARGS__ if (n == 1 && (m & 1)) __builtin_amdgcn_sched_barrier(0); }
; DEVI void run_phase(const int ph, const Params& P, char* shmc, const int wave_u) {
;     ...
;       EPI_LOOP({ const int f = row - fb; long drow; bf16* d;
;         if (col < MP) { d = dp; drow = col; }
;         else if (col < MT) { const int s = col - MP; d = ds; drow = (long)(s >> 5) * SKS + 1024 + (s & 31); }
;         else { const int c = col - MT; d = ds; drow = (long)(c >> 10) * SKS + (c & 1023); }
;         st_bf4(d + drow * 1024 + f, v[0], v[1], v[2], v[3]); })
.LBB0_729:
	v_lshlrev_b64 v[12:13], 11, v[12:13]
	v_lshl_add_u64 v[12:13], s[8:9], 0, v[12:13]
	v_lshl_add_u64 v[12:13], v[130:131], 1, v[12:13]
	s_and_b64 vcc, exec, s[6:7]
	v_cvt_pk_bf16_f32 v8, v8, v9
	v_cvt_pk_bf16_f32 v9, v10, v11
	v_mov_b32_e32 v156, v8
	v_mov_b32_e32 v157, v9
	v_lshl_add_u64 v[162:163], v[12:13], 0, v[164:165]
	s_cbranch_vccnz .LBB0_735
	s_cmpk_lt_u32 s70, 0x4200
	s_mov_b64 s[8:9], -1
	s_cbranch_scc1 .LBB0_732
	v_add_u32_e32 v8, 0xffffbe80, v32
	v_lshrrev_b32_e32 v10, 10, v8
	v_and_b32_e32 v8, 0x3ef, v8
	v_mov_b32_e32 v9, v33
	s_movk_i32 s4, 0x440
	v_mad_u64_u32 v[98:99], s[8:9], v10, s4, v[8:9]
	s_mov_b64 s[8:9], 0

; #define EPI_LOOP(...) _Pragma("unroll") for(int ai=0;ai<2;++ai) _Pragma("unroll") for(int bj=0;bj<2;++bj) \
;   _Pragma("unroll") for(int m=0;m<4;++m) _Pragma("unroll") for(int n=0;n<2;++n) { \
;     const int row=brow+ai*128+wr*64+m*16+fq*4; const int col=bcol+bj*128+wc*32+n*16+fr; \
;     f32x4& v=acc[ai][bj][m][n]; __VA_ARGS__ if (n == 1 && (m & 1)) __builtin_amdgcn_sched_barrier(0); }
; DEVI void run_phase(const int ph, const Params& P, char* shmc, const int wave_u) {
;     ...
;       EPI_LOOP({ const int f = row - fb; long drow; bf16* d;
;         if (col < MP) { d = dp; drow = col; }
;         else if (col < MT) { const int s = col - MP; d = ds; drow = (long)(s >> 5) * SKS + 1024 + (s & 31); }
;         else { const int c = col - MT; d = ds; drow = (long)(c >> 10) * SKS + (c & 1023); }
;         st_bf4(d + drow * 1024 + f, v[0], v[1], v[2], v[3]); })
.LBB0_737:
	v_lshlrev_b64 v[8:9], 11, v[98:99]
	v_lshl_add_u64 v[8:9], s[8:9], 0, v[8:9]
	v_lshl_add_u64 v[8:9], v[130:131], 1, v[8:9]
	s_and_b64 vcc, exec, s[6:7]
	v_cvt_pk_bf16_f32 v4, v4, v5
	v_cvt_pk_bf16_f32 v5, v6, v7
	v_mov_b32_e32 v154, v4
	v_mov_b32_e32 v155, v5
	s_nop 1
	v_permlane16_swap_b32_e32 v152, v154
	v_permlane16_swap_b32_e32 v153, v155
	global_store_dwordx4 v[160:161], v[152:155], off offset:320
	s_cbranch_vccnz .LBB0_743
	s_cmpk_lt_u32 s70, 0x4200
	s_mov_b64 s[6:7], -1
	s_cbranch_scc1 .LBB0_740
	v_add_u32_e32 v4, 0xffffbe90, v32
	v_lshrrev_b32_e32 v5, 10, v4
	v_and_b32_e32 v32, 0x3ff, v4
	s_movk_i32 s4, 0x440
	v_mad_u64_u32 v[94:95], s[6:7], v5, s4, v[32:33]
	s_mov_b64 s[6:7], 0

; #define EPI_LOOP(...) _Pragma("unroll") for(int ai=0;ai<2;++ai) _Pragma("unroll") for(int bj=0;bj<2;++bj) \
;   _Pragma("unroll") for(int m=0;m<4;++m) _Pragma("unroll") for(int n=0;n<2;++n) { \
;     const int row=brow+ai*128+wr*64+m*16+fq*4; const int col=bcol+bj*128+wc*32+n*16+fr; \
;     f32x4& v=acc[ai][bj][m][n]; __VA_ARGS__ if (n == 1 && (m & 1)) __builtin_amdgcn_sched_barrier(0); }
; DEVI void run_phase(const int ph, const Params& P, char* shmc, const int wave_u) {
;     ...
;       EPI_LOOP({ const int f = row - fb; long drow; bf16* d;
;         if (col < MP) { d = dp; drow = col; }
;         else if (col < MT) { const int s = col - MP; d = ds; drow = (long)(s >> 5) * SKS + 1024 + (s & 31); }
;         else { const int c = col - MT; d = ds; drow = (long)(c >> 10) * SKS + (c & 1023); }
;         st_bf4(d + drow * 1024 + f, v[0], v[1], v[2], v[3]); })
.LBB0_745:
	v_lshlrev_b64 v[4:5], 11, v[94:95]
	v_lshl_add_u64 v[4:5], s[0:1], 0, v[4:5]
	v_lshl_add_u64 v[4:5], v[130:131], 1, v[4:5]
	v_cvt_pk_bf16_f32 v0, v0, v1
	v_cvt_pk_bf16_f32 v1, v2, v3
	v_mov_b32_e32 v158, v0
	v_mov_b32_e32 v159, v1
	s_nop 1
	v_permlane16_swap_b32_e32 v156, v158
	v_permlane16_swap_b32_e32 v157, v159
	global_store_dwordx4 v[162:163], v[156:159], off offset:320
	s_mov_b64 s[0:1], 0

; DEVI int RSI(int row) { return ((row >> 3) << 5) | (row & 7); }
; DEVI void run_phase(const int ph, const Params& P, char* shmc, const int wave_u) {
;     ...
;       for (int ai = 0; ai < 2; ++ai) {
;         const int gb = brow + ai * 128 + wr * 64; const int h = gb / 192, c0 = gb % 192;
; #pragma unroll
;         for (int bj = 0; bj < 2; ++bj)
; #pragma unroll
;           for (int n = 0; n < 2; ++n) {
;             const int col = bcol + bj * 128 + wc * 32 + n * 16 + fr;
;             const float sc = rsqrtf(ssq[RSI(col)] * (1.f / 512) + EPS) * MLA_C;
;             bf16* qrow = qm + (long)col * 1536 + h * 192;
;             if (c0 < 128) {
; #pragma unroll
;               for (int m = 0; m < 4; ++m) { const f32x4 v = acc[ai][bj][m][n];
;                 st_bf4(qrow + c0 + m * 16 + fq * 4, v[0] * sc, v[1] * sc, v[2] * sc, v[3] * sc); }
;               __builtin_amdgcn_sched_barrier(0);
;             } else {
;               const int s = col - MP; const int pos = samp ? PAST + (s & 31) : (col & (SEQ - 1));
; #pragma unroll
;               for (int pr = 0; pr < 2; ++pr) {
;                 const f32x4 x1 = acc[ai][bj][2 * pr][n], x2 = acc[ai][bj][2 * pr + 1][n];
;                 float y1[4], y2[4];
; #pragma unroll
;                 for (int j = 0; j < 4; ++j) { const int i = pr * 16 + fq * 4 + j; float c, sn; rope_cs(pos, i, c, sn);
;                   const float a = x1[j] * sc, b = x2[j] * sc; y1[j] = a * c - b * sn; y2[j] = a * sn + b * c; }
.LBB0_757:
	s_or_b64 exec, exec, s[8:9]
	v_mbcnt_lo_u32_b32 v32, -1, 0
	v_mbcnt_hi_u32_b32 v32, -1, v32
	s_mov_b32 s1, 0x2aaaaaab
	v_or_b32_e32 v130, s5, v32
	v_ashrrev_i32_e32 v131, 2, v130
	v_and_b32_e32 v131, 0xffffffc0, v131
	v_and_b32_e32 v156, 15, v32
	v_add_u32_e32 v151, s6, v131
	v_and_b32_e32 v153, 7, v32
	v_lshrrev_b32_e32 v32, 2, v32
	v_lshrrev_b32_e32 v130, 1, v130
	v_and_b32_e32 v135, 12, v32
	v_mul_hi_i32 v32, v151, s1
	v_and_b32_e32 v132, 0x60, v130
	v_lshrrev_b32_e32 v130, 31, v32
	v_lshrrev_b32_e32 v32, 5, v32
	v_add_u32_e32 v32, v32, v130
	s_movk_i32 s1, 0xc0
	v_mul_lo_u32 v130, v32, s1
	v_readlane_b32 s6, v255, 17
	v_or3_b32 v154, s0, v132, v156
	v_sub_u32_e32 v134, v151, v130
	v_ashrrev_i32_e32 v131, 31, v130
	v_readlane_b32 s7, v255, 18
	s_movk_i32 s1, 0x7f
	v_lshlrev_b32_e32 v32, 2, v154
	s_movk_i32 s0, 0xfda0
	v_lshl_add_u64 v[136:137], v[130:131], 1, s[6:7]
	v_cmp_lt_i32_e64 s[6:7], s1, v134
	v_and_or_b32 v130, v32, s0, v153
	v_readlane_b32 s0, v255, 25
	v_ashrrev_i32_e32 v131, 31, v130
	v_readlane_b32 s1, v255, 26
	s_cmp_gt_i32 s75, 63
	s_cselect_b64 vcc, -1, 0
	v_lshl_add_u64 v[132:133], v[130:131], 2, s[0:1]
	global_load_dword v32, v[132:133], off
	s_mov_b32 s0, 0x800000
	v_mul_hi_i32_i24_e32 v131, 0xc00, v154
	v_or_b32_e32 v155, 0x400, v156
	v_cvt_f32_ubyte0_e32 v150, v135
	v_or_b32_e32 v149, 1, v135
	v_or_b32_e32 v148, 2, v135
	v_or_b32_e32 v145, 3, v135
	v_or_b32_e32 v144, 16, v135
	v_or_b32_e32 v142, 17, v135
	v_or_b32_e32 v139, 18, v135
	v_or_b32_e32 v143, 19, v135
	s_waitcnt vmcnt(0) lgkmcnt(0)
	v_fmamk_f32 v32, v32, 0x3b000000, v186
	v_cmp_gt_f32_e64 s[0:1], s0, v32
	v_mul_f32_e32 v130, 0x4b800000, v32
	s_nop 0
	v_cndmask_b32_e64 v32, v32, v130, s[0:1]
	v_rsq_f32_e32 v32, v32
	s_nop 0
	v_mul_f32_e32 v130, 0x45800000, v32
	v_cndmask_b32_e64 v32, v32, v130, s[0:1]
	v_mul_f32_e32 v138, 0x3dd53b94, v32
	v_mul_i32_i24_e32 v130, 0xc00, v154
	v_and_b32_e32 v32, 0xf6f, v154
	v_lshl_add_u64 v[140:141], v[136:137], 0, v[130:131]
	v_cndmask_b32_e32 v152, v32, v155, vcc
	v_lshlrev_b32_e32 v32, 1, v135
	s_and_saveexec_b64 s[0:1], s[6:7]
	s_xor_b64 s[38:39], exec, s[0:1]
	s_cbranch_execz .LBB0_759
	v_mul_f32_e32 v157, 0xbed49a78, v150
	s_mov_b32 s4, 0xc2fc0000
	v_cmp_gt_f32_e64 s[0:1], s4, v157
	v_cvt_f32_u32_e32 v135, v152
	v_mov_b32_e32 v161, v122
	v_cndmask_b32_e64 v158, 0, v191, s[0:1]
	v_fmac_f32_e32 v158, 0xbed49a78, v150
	v_exp_f32_e32 v158, v158
	v_cvt_f32_ubyte0_e32 v122, v149
	v_cndmask_b32_e64 v157, 0, v190, s[0:1]
	v_mov_b32_e32 v160, v126
	v_mul_f32_e32 v126, 0xbed49a78, v122
	v_ldexp_f32 v157, v158, v157
	v_cmp_gt_f32_e64 s[0:1], s4, v126
	v_mul_f32_e32 v157, v157, v135
	v_mul_f32_e32 v158, 0.15915494, v157
	v_cndmask_b32_e64 v126, 0, v191, s[0:1]
	v_fmac_f32_e32 v126, 0xbed49a78, v122
	v_rndne_f32_e32 v158, v158
	v_exp_f32_e32 v122, v126
	v_fmac_f32_e32 v157, 0xc0c90000, v158
	v_fmac_f32_e32 v157, 0xbafdaa22, v158
	v_mul_f32_e32 v157, 0.15915494, v157
	v_cndmask_b32_e64 v126, 0, v190, s[0:1]
	v_sin_f32_e32 v159, v157
	v_cos_f32_e32 v158, v157
	v_ldexp_f32 v122, v122, v126
	v_mul_f32_e32 v122, v122, v135
	v_mul_f32_e32 v126, 0.15915494, v122
	v_pk_mul_f32 v[160:161], v[160:161], v[138:139] op_sel_hi:[1,0]
	v_rndne_f32_e32 v126, v126
	v_pk_mul_f32 v[162:163], v[160:161], v[158:159]
	v_fmac_f32_e32 v122, 0xc0c90000, v126
	v_sub_f32_e32 v157, v162, v163
	v_mov_b32_e32 v162, v159
	v_mov_b32_e32 v163, v158
	v_fmac_f32_e32 v122, 0xbafdaa22, v126
	v_pk_mul_f32 v[158:159], v[160:161], v[162:163]
	v_mul_f32_e32 v122, 0.15915494, v122
	v_add_f32_e32 v160, v158, v159
	v_sin_f32_e32 v159, v122
	v_cos_f32_e32 v158, v122
	v_mov_b32_e32 v122, v127
	v_pk_mul_f32 v[122:123], v[122:123], v[138:139] op_sel_hi:[1,0]
	s_nop 0
	v_pk_mul_f32 v[126:127], v[122:123], v[158:159]
	s_nop 0
	v_sub_f32_e32 v161, v126, v127
	v_mov_b32_e32 v126, v159
	v_mov_b32_e32 v127, v158
	v_pk_mul_f32 v[122:123], v[122:123], v[126:127]
	v_mov_b32_e32 v126, v128
	v_add_f32_e32 v162, v122, v123
	v_cvt_f32_ubyte0_e32 v122, v148
	v_mul_f32_e32 v123, 0xbed49a78, v122
	v_cmp_gt_f32_e64 s[0:1], s4, v123
	v_mov_b32_e32 v127, v124
	v_pk_mul_f32 v[126:127], v[126:127], v[138:139] op_sel_hi:[1,0]
	v_cndmask_b32_e64 v123, 0, v191, s[0:1]
	v_fmac_f32_e32 v123, 0xbed49a78, v122
	v_exp_f32_e32 v122, v123
	v_cndmask_b32_e64 v123, 0, v190, s[0:1]
	v_mov_b32_e32 v124, v129
	v_pk_mul_f32 v[124:125], v[124:125], v[138:139] op_sel_hi:[1,0]
	v_ldexp_f32 v122, v122, v123
	v_mul_f32_e32 v122, v122, v135
	v_mul_f32_e32 v123, 0.15915494, v122
	v_rndne_f32_e32 v123, v123
	v_fmac_f32_e32 v122, 0xc0c90000, v123
	v_fmac_f32_e32 v122, 0xbafdaa22, v123
	v_mul_f32_e32 v122, 0.15915494, v122
	v_sin_f32_e32 v123, v122
	v_cos_f32_e32 v122, v122
	s_nop 0
	v_pk_mul_f32 v[158:159], v[126:127], v[122:123]
	s_nop 0
	v_sub_f32_e32 v128, v158, v159
	v_mov_b32_e32 v158, v123
	v_mov_b32_e32 v159, v122
	v_pk_mul_f32 v[122:123], v[126:127], v[158:159]
	s_nop 0
	v_add_f32_e32 v158, v122, v123
	v_cvt_f32_ubyte0_e32 v122, v145
	v_mul_f32_e32 v123, 0xbed49a78, v122
	v_cmp_gt_f32_e64 s[0:1], s4, v123
	s_nop 1
	v_cndmask_b32_e64 v123, 0, v191, s[0:1]
	v_fmac_f32_e32 v123, 0xbed49a78, v122
	v_exp_f32_e32 v122, v123
	v_cndmask_b32_e64 v123, 0, v190, s[0:1]
	v_ldexp_f32 v122, v122, v123
	v_mul_f32_e32 v122, v122, v135
	v_mul_f32_e32 v123, 0.15915494, v122
	v_rndne_f32_e32 v123, v123
	v_fmac_f32_e32 v122, 0xc0c90000, v123
	v_fmac_f32_e32 v122, 0xbafdaa22, v123
	v_mul_f32_e32 v122, 0.15915494, v122
	v_sin_f32_e32 v123, v122
	v_cos_f32_e32 v122, v122
	s_nop 0
	v_pk_mul_f32 v[126:127], v[124:125], v[122:123]
	s_nop 0
	v_sub_f32_e32 v129, v126, v127
	v_mov_b32_e32 v126, v123
	v_mov_b32_e32 v127, v122
; DEVI void run_phase(const int ph, const Params& P, char* shmc, const int wave_u) {
;     ...
;             if (c0 < 128) {
; #pragma unroll
;               for (int m = 0; m < 4; ++m) { const f32x4 v = acc[ai][bj][m][n];
;                 st_bf4(qrow + c0 + m * 16 + fq * 4, v[0] * sc, v[1] * sc, v[2] * sc, v[3] * sc); }
;               __builtin_amdgcn_sched_barrier(0);
;             } else {
;               const int s = col - MP; const int pos = samp ? PAST + (s & 31) : (col & (SEQ - 1));
; #pragma unroll
;               for (int pr = 0; pr < 2; ++pr) {
;                 const f32x4 x1 = acc[ai][bj][2 * pr][n], x2 = acc[ai][bj][2 * pr + 1][n];
;                 float y1[4], y2[4];
; #pragma unroll
;                 for (int j = 0; j < 4; ++j) { const int i = pr * 16 + fq * 4 + j; float c, sn; rope_cs(pos, i, c, sn);
;                   const float a = x1[j] * sc, b = x2[j] * sc; y1[j] = a * c - b * sn; y2[j] = a * sn + b * c; }
;                 const int i0 = pr * 16 + fq * 4;
;                 st_bf4(qrow + 128 + i0, y1[0], y1[1], y1[2], y1[3]); st_bf4(qrow + 160 + i0, y2[0], y2[1], y2[2], y2[3]);
;                 __builtin_amdgcn_sched_barrier(0);
	v_pk_mul_f32 v[122:123], v[124:125], v[126:127]
	v_cvt_pk_bf16_f32 v124, v157, v161
	v_cvt_pk_bf16_f32 v125, v128, v129
	s_nop 0
	v_add_f32_e32 v126, v122, v123
	v_lshl_add_u64 v[122:123], v[140:141], 0, v[32:33]
	global_store_dwordx2 v[122:123], v[124:125], off offset:256
	v_cvt_pk_bf16_f32 v124, v160, v162
	v_cvt_pk_bf16_f32 v125, v158, v126
	global_store_dwordx2 v[122:123], v[124:125], off offset:320
	v_cvt_f32_ubyte0_e32 v124, v144
	v_mul_f32_e32 v125, 0xbed49a78, v124
	v_cmp_gt_f32_e64 s[0:1], s4, v125
	v_mov_b32_e32 v127, v114
	v_cvt_f32_ubyte0_e32 v114, v142
	v_cndmask_b32_e64 v125, 0, v191, s[0:1]
	v_fmac_f32_e32 v125, 0xbed49a78, v124
	v_exp_f32_e32 v124, v125
	v_cndmask_b32_e64 v125, 0, v190, s[0:1]
	v_mov_b32_e32 v126, v118
	v_mul_f32_e32 v118, 0xbed49a78, v114
	v_ldexp_f32 v124, v124, v125
	v_cmp_gt_f32_e64 s[0:1], s4, v118
	v_mul_f32_e32 v124, v124, v135
	v_mul_f32_e32 v125, 0.15915494, v124
	v_cndmask_b32_e64 v118, 0, v191, s[0:1]
	v_fmac_f32_e32 v118, 0xbed49a78, v114
	v_rndne_f32_e32 v125, v125
	v_exp_f32_e32 v114, v118
	v_fmac_f32_e32 v124, 0xc0c90000, v125
	v_fmac_f32_e32 v124, 0xbafdaa22, v125
	v_mul_f32_e32 v124, 0.15915494, v124
	v_cndmask_b32_e64 v118, 0, v190, s[0:1]
	v_sin_f32_e32 v125, v124
	v_cos_f32_e32 v124, v124
	v_ldexp_f32 v114, v114, v118
	v_mul_f32_e32 v114, v114, v135
	v_mul_f32_e32 v118, 0.15915494, v114
	v_pk_mul_f32 v[126:127], v[126:127], v[138:139] op_sel_hi:[1,0]
	v_rndne_f32_e32 v118, v118
	v_pk_mul_f32 v[128:129], v[126:127], v[124:125]
	v_fmac_f32_e32 v114, 0xc0c90000, v118
	v_sub_f32_e32 v140, v128, v129
	v_mov_b32_e32 v128, v125
	v_mov_b32_e32 v129, v124
	v_fmac_f32_e32 v114, 0xbafdaa22, v118
	v_pk_mul_f32 v[124:125], v[126:127], v[128:129]
	v_mul_f32_e32 v114, 0.15915494, v114
	v_add_f32_e32 v126, v124, v125
	v_sin_f32_e32 v125, v114
	v_cos_f32_e32 v124, v114
	v_mov_b32_e32 v114, v119
	v_pk_mul_f32 v[114:115], v[114:115], v[138:139] op_sel_hi:[1,0]
	s_nop 0
	v_pk_mul_f32 v[118:119], v[114:115], v[124:125]
	s_nop 0
	v_sub_f32_e32 v127, v118, v119
	v_mov_b32_e32 v118, v125
	v_mov_b32_e32 v119, v124
	v_pk_mul_f32 v[114:115], v[114:115], v[118:119]
	v_mov_b32_e32 v118, v120
	v_add_f32_e32 v128, v114, v115
	v_cvt_f32_ubyte0_e32 v114, v139
	v_mul_f32_e32 v115, 0xbed49a78, v114
	v_cmp_gt_f32_e64 s[0:1], s4, v115
	v_mov_b32_e32 v119, v116
	v_pk_mul_f32 v[118:119], v[118:119], v[138:139] op_sel_hi:[1,0]
	v_cndmask_b32_e64 v115, 0, v191, s[0:1]
	v_fmac_f32_e32 v115, 0xbed49a78, v114
	v_exp_f32_e32 v114, v115
	v_cndmask_b32_e64 v115, 0, v190, s[0:1]
	v_mov_b32_e32 v116, v121
	v_pk_mul_f32 v[116:117], v[116:117], v[138:139] op_sel_hi:[1,0]
	v_ldexp_f32 v114, v114, v115
	v_mul_f32_e32 v114, v114, v135
	v_mul_f32_e32 v115, 0.15915494, v114
	v_rndne_f32_e32 v115, v115
	v_fmac_f32_e32 v114, 0xc0c90000, v115
	v_fmac_f32_e32 v114, 0xbafdaa22, v115
	v_mul_f32_e32 v114, 0.15915494, v114
	v_sin_f32_e32 v115, v114
	v_cos_f32_e32 v114, v114
	s_nop 0
	v_pk_mul_f32 v[124:125], v[118:119], v[114:115]
	s_nop 0
	v_sub_f32_e32 v120, v124, v125
	v_mov_b32_e32 v124, v115
	v_mov_b32_e32 v125, v114
	v_pk_mul_f32 v[114:115], v[118:119], v[124:125]
	s_nop 0
	v_add_f32_e32 v124, v114, v115
	v_cvt_f32_ubyte0_e32 v114, v143
	v_mul_f32_e32 v115, 0xbed49a78, v114
	v_cmp_gt_f32_e64 s[0:1], s4, v115
	s_nop 1
	v_cndmask_b32_e64 v115, 0, v191, s[0:1]
	v_fmac_f32_e32 v115, 0xbed49a78, v114
	v_exp_f32_e32 v114, v115
	v_cndmask_b32_e64 v115, 0, v190, s[0:1]
	v_ldexp_f32 v114, v114, v115
	v_mul_f32_e32 v114, v114, v135
	v_mul_f32_e32 v115, 0.15915494, v114
	v_rndne_f32_e32 v115, v115
	v_fmac_f32_e32 v114, 0xc0c90000, v115
	v_fmac_f32_e32 v114, 0xbafdaa22, v115
	v_mul_f32_e32 v114, 0.15915494, v114
	v_sin_f32_e32 v115, v114
	v_cos_f32_e32 v114, v114
	s_nop 0
	v_pk_mul_f32 v[118:119], v[116:117], v[114:115]
	s_nop 0
	v_sub_f32_e32 v121, v118, v119
	v_mov_b32_e32 v118, v115
	v_mov_b32_e32 v119, v114
	v_pk_mul_f32 v[114:115], v[116:117], v[118:119]
	s_nop 0
	v_add_f32_e32 v116, v114, v115
	v_cvt_pk_bf16_f32 v114, v140, v127
	v_cvt_pk_bf16_f32 v115, v120, v121
	global_store_dwordx2 v[122:123], v[114:115], off offset:288
	v_cvt_pk_bf16_f32 v114, v126, v128
	v_cvt_pk_bf16_f32 v115, v124, v116
	global_store_dwordx2 v[122:123], v[114:115], off offset:352
.LBB0_759:
	s_or_saveexec_b64 s[0:1], s[38:39]
	v_ashrrev_i32_e32 v135, 31, v134
	s_xor_b64 exec, exec, s[0:1]
	s_cbranch_execz .LBB0_761
	v_lshl_add_u64 v[140:141], v[134:135], 1, v[140:141]
	v_lshl_add_u64 v[140:141], v[140:141], 0, v[32:33]
	v_mul_f32_e32 v126, v126, v138
	v_mul_f32_e32 v127, v127, v138
	v_mul_f32_e32 v122, v122, v138
	v_mul_f32_e32 v123, v123, v138
	v_mul_f32_e32 v118, v118, v138
	v_mul_f32_e32 v119, v119, v138
	v_mul_f32_e32 v114, v114, v138
	v_mul_f32_e32 v115, v115, v138
	v_mul_f32_e32 v128, v128, v138
	v_mul_f32_e32 v129, v129, v138
	v_cvt_pk_bf16_f32 v126, v126, v127
	v_cvt_pk_bf16_f32 v127, v128, v129
	global_store_dwordx2 v[140:141], v[126:127], off
	v_mul_f32_e32 v124, v124, v138
	v_mul_f32_e32 v125, v125, v138
	v_cvt_pk_bf16_f32 v122, v122, v123
	v_cvt_pk_bf16_f32 v123, v124, v125
	global_store_dwordx2 v[140:141], v[122:123], off offset:32
	v_mul_f32_e32 v120, v120, v138
	v_mul_f32_e32 v121, v121, v138
	v_cvt_pk_bf16_f32 v118, v118, v119
	v_cvt_pk_bf16_f32 v119, v120, v121
	global_store_dwordx2 v[140:141], v[118:119], off offset:64
	v_mul_f32_e32 v116, v116, v138
	v_mul_f32_e32 v117, v117, v138
	v_cvt_pk_bf16_f32 v114, v114, v115
	v_cvt_pk_bf16_f32 v115, v116, v117
	global_store_dwordx2 v[140:141], v[114:115], off offset:96
; DEVI int RSI(int row) { return ((row >> 3) << 5) | (row & 7); }
; DEVI void run_phase(const int ph, const Params& P, char* shmc, const int wave_u) {
;     ...
;           for (int n = 0; n < 2; ++n) {
;             const int col = bcol + bj * 128 + wc * 32 + n * 16 + fr;
;             const float sc = rsqrtf(ssq[RSI(col)] * (1.f / 512) + EPS) * MLA_C;
;             bf16* qrow = qm + (long)col * 1536 + h * 192;
;             if (c0 < 128) {
; #pragma unroll
;               for (int m = 0; m < 4; ++m) { const f32x4 v = acc[ai][bj][m][n];
;                 st_bf4(qrow + c0 + m * 16 + fq * 4, v[0] * sc, v[1] * sc, v[2] * sc, v[3] * sc); }
;               __builtin_amdgcn_sched_barrier(0);
;             } else {
;               const int s = col - MP; const int pos = samp ? PAST + (s & 31) : (col & (SEQ - 1));
; #pragma unroll
;               for (int pr = 0; pr < 2; ++pr) {
;                 const f32x4 x1 = acc[ai][bj][2 * pr][n], x2 = acc[ai][bj][2 * pr + 1][n];
;                 float y1[4], y2[4];
; #pragma unroll
;                 for (int j = 0; j < 4; ++j) { const int i = pr * 16 + fq * 4 + j; float c, sn; rope_cs(pos, i, c, sn);
;                   const float a = x1[j] * sc, b = x2[j] * sc; y1[j] = a * c - b * sn; y2[j] = a * sn + b * c; }
;                 const int i0 = pr * 16 + fq * 4;
;                 st_bf4(qrow + 128 + i0, y1[0], y1[1], y1[2], y1[3]); st_bf4(qrow + 160 + i0, y2[0], y2[1], y2[2], y2[3]);
.LBB0_761:
	s_or_b64 exec, exec, s[0:1]
	v_or_b32_e32 v119, 16, v154
	v_lshlrev_b32_e32 v114, 2, v119
	s_movk_i32 s0, 0xfde0
	v_and_or_b32 v114, v114, s0, v153
	v_readlane_b32 s0, v255, 25
	v_ashrrev_i32_e32 v115, 31, v114
	v_readlane_b32 s1, v255, 26
	v_or_b32_e32 v122, 0x410, v156
	s_nop 0
	v_lshl_add_u64 v[114:115], v[114:115], 2, s[0:1]
	global_load_dword v116, v[114:115], off
	s_mov_b32 s0, 0x800000
	s_waitcnt vmcnt(0) lgkmcnt(0)
	v_fmamk_f32 v116, v116, 0x3b000000, v186
	v_cmp_gt_f32_e64 s[0:1], s0, v116
	v_mul_f32_e32 v117, 0x4b800000, v116
	s_nop 0
	v_cndmask_b32_e64 v116, v116, v117, s[0:1]
	v_rsq_f32_e32 v116, v116
	s_nop 0
	v_mul_f32_e32 v117, 0x45800000, v116
	v_cndmask_b32_e64 v116, v116, v117, s[0:1]
	v_mul_f32_e32 v118, 0x3dd53b94, v116
	v_mul_hi_i32_i24_e32 v117, 0xc00, v119
	v_mul_i32_i24_e32 v116, 0xc00, v119
	v_and_b32_e32 v119, 0xf7f, v119
	v_lshl_add_u64 v[120:121], v[136:137], 0, v[116:117]
	v_cndmask_b32_e32 v119, v119, v122, vcc
	s_and_saveexec_b64 s[0:1], s[6:7]
	s_xor_b64 s[38:39], exec, s[0:1]
	s_cbranch_execz .LBB0_763
	v_mul_f32_e32 v124, 0xbed49a78, v150
	s_mov_b32 s4, 0xc2fc0000
	v_cmp_gt_f32_e64 s[0:1], s4, v124
	v_cvt_f32_u32_e32 v123, v119
	v_mov_b32_e32 v127, v106
	v_cndmask_b32_e64 v125, 0, v191, s[0:1]
	v_fmac_f32_e32 v125, 0xbed49a78, v150
	v_exp_f32_e32 v125, v125
	v_cvt_f32_ubyte0_e32 v106, v149
	v_cndmask_b32_e64 v124, 0, v190, s[0:1]
	v_mov_b32_e32 v126, v110
	v_mul_f32_e32 v110, 0xbed49a78, v106
	v_ldexp_f32 v124, v125, v124
	v_cmp_gt_f32_e64 s[0:1], s4, v110
	v_mul_f32_e32 v124, v124, v123
	v_mul_f32_e32 v125, 0.15915494, v124
	v_cndmask_b32_e64 v110, 0, v191, s[0:1]
	v_fmac_f32_e32 v110, 0xbed49a78, v106
	v_rndne_f32_e32 v125, v125
	v_exp_f32_e32 v106, v110
	v_fmac_f32_e32 v124, 0xc0c90000, v125
	v_fmac_f32_e32 v124, 0xbafdaa22, v125
	v_mul_f32_e32 v124, 0.15915494, v124
	v_cndmask_b32_e64 v110, 0, v190, s[0:1]
	v_sin_f32_e32 v125, v124
	v_cos_f32_e32 v124, v124
	v_ldexp_f32 v106, v106, v110
	v_mul_f32_e32 v106, v106, v123
	v_mul_f32_e32 v110, 0.15915494, v106
	v_pk_mul_f32 v[126:127], v[126:127], v[118:119] op_sel_hi:[1,0]
	v_rndne_f32_e32 v110, v110
	v_pk_mul_f32 v[128:129], v[124:125], v[126:127]
	v_fmac_f32_e32 v106, 0xc0c90000, v110
	v_sub_f32_e32 v138, v128, v129
	v_mov_b32_e32 v128, v125
	v_mov_b32_e32 v129, v124
	v_fmac_f32_e32 v106, 0xbafdaa22, v110
	v_pk_mul_f32 v[124:125], v[128:129], v[126:127]
	v_mul_f32_e32 v106, 0.15915494, v106
	v_add_f32_e32 v126, v124, v125
	v_sin_f32_e32 v125, v106
	v_cos_f32_e32 v124, v106
	v_mov_b32_e32 v106, v111
	v_pk_mul_f32 v[106:107], v[106:107], v[118:119] op_sel_hi:[1,0]
	s_nop 0
	v_pk_mul_f32 v[110:111], v[124:125], v[106:107]
	s_nop 0
	v_sub_f32_e32 v127, v110, v111
	v_mov_b32_e32 v110, v125
	v_mov_b32_e32 v111, v124
	v_pk_mul_f32 v[106:107], v[110:111], v[106:107]
	v_mov_b32_e32 v110, v112
	v_add_f32_e32 v128, v106, v107
	v_cvt_f32_ubyte0_e32 v106, v148
	v_mul_f32_e32 v107, 0xbed49a78, v106
	v_cmp_gt_f32_e64 s[0:1], s4, v107
	v_mov_b32_e32 v111, v108
	v_pk_mul_f32 v[110:111], v[110:111], v[118:119] op_sel_hi:[1,0]
	v_cndmask_b32_e64 v107, 0, v191, s[0:1]
	v_fmac_f32_e32 v107, 0xbed49a78, v106
	v_exp_f32_e32 v106, v107
	v_cndmask_b32_e64 v107, 0, v190, s[0:1]
	v_mov_b32_e32 v108, v113
	v_pk_mul_f32 v[108:109], v[108:109], v[118:119] op_sel_hi:[1,0]
	v_ldexp_f32 v106, v106, v107
	v_mul_f32_e32 v106, v106, v123
	v_mul_f32_e32 v107, 0.15915494, v106
	v_rndne_f32_e32 v107, v107
	v_fmac_f32_e32 v106, 0xc0c90000, v107
	v_fmac_f32_e32 v106, 0xbafdaa22, v107
	v_mul_f32_e32 v106, 0.15915494, v106
	v_sin_f32_e32 v107, v106
	v_cos_f32_e32 v106, v106
	s_nop 0
	v_pk_mul_f32 v[124:125], v[106:107], v[110:111]
	s_nop 0
	v_sub_f32_e32 v112, v124, v125
	v_mov_b32_e32 v124, v107
	v_mov_b32_e32 v125, v106
	v_pk_mul_f32 v[106:107], v[124:125], v[110:111]
	s_nop 0
	v_add_f32_e32 v124, v106, v107
	v_cvt_f32_ubyte0_e32 v106, v145
	v_mul_f32_e32 v107, 0xbed49a78, v106
	v_cmp_gt_f32_e64 s[0:1], s4, v107
	s_nop 1
	v_cndmask_b32_e64 v107, 0, v191, s[0:1]
	v_fmac_f32_e32 v107, 0xbed49a78, v106
	v_exp_f32_e32 v106, v107
	v_cndmask_b32_e64 v107, 0, v190, s[0:1]
	v_ldexp_f32 v106, v106, v107
	v_mul_f32_e32 v106, v106, v123
	v_mul_f32_e32 v107, 0.15915494, v106
	v_rndne_f32_e32 v107, v107
	v_fmac_f32_e32 v106, 0xc0c90000, v107
	v_fmac_f32_e32 v106, 0xbafdaa22, v107
	v_mul_f32_e32 v106, 0.15915494, v106
	v_sin_f32_e32 v107, v106
	v_cos_f32_e32 v106, v106
	s_nop 0
	v_pk_mul_f32 v[110:111], v[106:107], v[108:109]
	s_nop 0
	v_sub_f32_e32 v113, v110, v111
	v_mov_b32_e32 v110, v107
	v_mov_b32_e32 v111, v106
	v_pk_mul_f32 v[106:107], v[110:111], v[108:109]
	v_cvt_pk_bf16_f32 v108, v138, v127
	v_cvt_pk_bf16_f32 v109, v112, v113
	s_nop 0
	v_add_f32_e32 v110, v106, v107
	v_lshl_add_u64 v[106:107], v[120:121], 0, v[32:33]
	global_store_dwordx2 v[106:107], v[108:109], off offset:256
	v_cvt_pk_bf16_f32 v108, v126, v128
	v_cvt_pk_bf16_f32 v109, v124, v110
	global_store_dwordx2 v[106:107], v[108:109], off offset:320
	v_cvt_f32_ubyte0_e32 v108, v144
	v_mul_f32_e32 v109, 0xbed49a78, v108
	v_cmp_gt_f32_e64 s[0:1], s4, v109
	v_mov_b32_e32 v111, v98
	v_cvt_f32_ubyte0_e32 v98, v142
	v_cndmask_b32_e64 v109, 0, v191, s[0:1]
	v_fmac_f32_e32 v109, 0xbed49a78, v108
	v_exp_f32_e32 v108, v109
	v_cndmask_b32_e64 v109, 0, v190, s[0:1]
	v_mov_b32_e32 v110, v102
	v_mul_f32_e32 v102, 0xbed49a78, v98
	v_ldexp_f32 v108, v108, v109
	v_cmp_gt_f32_e64 s[0:1], s4, v102
	v_mul_f32_e32 v108, v108, v123
	v_mul_f32_e32 v109, 0.15915494, v108
	v_cndmask_b32_e64 v102, 0, v191, s[0:1]
	v_fmac_f32_e32 v102, 0xbed49a78, v98
	v_rndne_f32_e32 v109, v109
	v_exp_f32_e32 v98, v102
	v_fmac_f32_e32 v108, 0xc0c90000, v109
; DEVI int RSI(int row) { return ((row >> 3) << 5) | (row & 7); }
; DEVI void rope_cs(int pos, int i, float& c, float& s) {
;   float fr = exp2f(-(float)i * (13.287712379549449f / 32.f));
;   float a = (float)pos * fr;
;   float n = rintf(a * 0.15915494309189535f);
;   float r = fmaf(-n, 6.28125f, a);
;   r = fmaf(-n, 0.0019353071795864769f, r);
;   s = __sinf(r); c = __cosf(r);
; DEVI void run_phase(const int ph, const Params& P, char* shmc, const int wave_u) {
;     ...
;             const float sc = rsqrtf(ssq[RSI(col)] * (1.f / 512) + EPS) * MLA_C;
;             bf16* qrow = qm + (long)col * 1536 + h * 192;
;             if (c0 < 128) {
; #pragma unroll
;               for (int m = 0; m < 4; ++m) { const f32x4 v = acc[ai][bj][m][n];
;                 st_bf4(qrow + c0 + m * 16 + fq * 4, v[0] * sc, v[1] * sc, v[2] * sc, v[3] * sc); }
;               __builtin_amdgcn_sched_barrier(0);
;             } else {
;               const int s = col - MP; const int pos = samp ? PAST + (s & 31) : (col & (SEQ - 1));
; #pragma unroll
;               for (int pr = 0; pr < 2; ++pr) {
;                 const f32x4 x1 = acc[ai][bj][2 * pr][n], x2 = acc[ai][bj][2 * pr + 1][n];
;                 float y1[4], y2[4];
; #pragma unroll
;                 for (int j = 0; j < 4; ++j) { const int i = pr * 16 + fq * 4 + j; float c, sn; rope_cs(pos, i, c, sn);
;                   const float a = x1[j] * sc, b = x2[j] * sc; y1[j] = a * c - b * sn; y2[j] = a * sn + b * c; }
;                 const int i0 = pr * 16 + fq * 4;
;                 st_bf4(qrow + 128 + i0, y1[0], y1[1], y1[2], y1[3]); st_bf4(qrow + 160 + i0, y2[0], y2[1], y2[2], y2[3]);
;                 __builtin_amdgcn_sched_barrier(0);
	v_fmac_f32_e32 v108, 0xbafdaa22, v109
	v_mul_f32_e32 v108, 0.15915494, v108
	v_cndmask_b32_e64 v102, 0, v190, s[0:1]
	v_sin_f32_e32 v109, v108
	v_cos_f32_e32 v108, v108
	v_ldexp_f32 v98, v98, v102
	v_mul_f32_e32 v98, v98, v123
	v_mul_f32_e32 v102, 0.15915494, v98
	v_pk_mul_f32 v[110:111], v[110:111], v[118:119] op_sel_hi:[1,0]
	v_rndne_f32_e32 v102, v102
	v_pk_mul_f32 v[112:113], v[108:109], v[110:111]
	v_fmac_f32_e32 v98, 0xc0c90000, v102
	v_sub_f32_e32 v120, v112, v113
	v_mov_b32_e32 v112, v109
	v_mov_b32_e32 v113, v108
	v_fmac_f32_e32 v98, 0xbafdaa22, v102
	v_pk_mul_f32 v[108:109], v[112:113], v[110:111]
	v_mul_f32_e32 v98, 0.15915494, v98
	v_add_f32_e32 v110, v108, v109
	v_sin_f32_e32 v109, v98
	v_cos_f32_e32 v108, v98
	v_mov_b32_e32 v98, v103
	v_pk_mul_f32 v[98:99], v[98:99], v[118:119] op_sel_hi:[1,0]
	s_nop 0
	v_pk_mul_f32 v[102:103], v[108:109], v[98:99]
	s_nop 0
	v_sub_f32_e32 v111, v102, v103
	v_mov_b32_e32 v102, v109
	v_mov_b32_e32 v103, v108
	v_pk_mul_f32 v[98:99], v[102:103], v[98:99]
	v_mov_b32_e32 v102, v104
	v_add_f32_e32 v112, v98, v99
	v_cvt_f32_ubyte0_e32 v98, v139
	v_mul_f32_e32 v99, 0xbed49a78, v98
	v_cmp_gt_f32_e64 s[0:1], s4, v99
	v_mov_b32_e32 v103, v100
	v_pk_mul_f32 v[102:103], v[102:103], v[118:119] op_sel_hi:[1,0]
	v_cndmask_b32_e64 v99, 0, v191, s[0:1]
	v_fmac_f32_e32 v99, 0xbed49a78, v98
	v_exp_f32_e32 v98, v99
	v_cndmask_b32_e64 v99, 0, v190, s[0:1]
	v_mov_b32_e32 v100, v105
	v_pk_mul_f32 v[100:101], v[100:101], v[118:119] op_sel_hi:[1,0]
	v_ldexp_f32 v98, v98, v99
	v_mul_f32_e32 v98, v98, v123
	v_mul_f32_e32 v99, 0.15915494, v98
	v_rndne_f32_e32 v99, v99
	v_fmac_f32_e32 v98, 0xc0c90000, v99
	v_fmac_f32_e32 v98, 0xbafdaa22, v99
	v_mul_f32_e32 v98, 0.15915494, v98
	v_sin_f32_e32 v99, v98
	v_cos_f32_e32 v98, v98
	s_nop 0
	v_pk_mul_f32 v[108:109], v[98:99], v[102:103]
	s_nop 0
	v_sub_f32_e32 v104, v108, v109
	v_mov_b32_e32 v108, v99
	v_mov_b32_e32 v109, v98
	v_pk_mul_f32 v[98:99], v[108:109], v[102:103]
	s_nop 0
	v_add_f32_e32 v108, v98, v99
	v_cvt_f32_ubyte0_e32 v98, v143
	v_mul_f32_e32 v99, 0xbed49a78, v98
	v_cmp_gt_f32_e64 s[0:1], s4, v99
	s_nop 1
	v_cndmask_b32_e64 v99, 0, v191, s[0:1]
	v_fmac_f32_e32 v99, 0xbed49a78, v98
	v_exp_f32_e32 v98, v99
	v_cndmask_b32_e64 v99, 0, v190, s[0:1]
	v_ldexp_f32 v98, v98, v99
	v_mul_f32_e32 v98, v98, v123
	v_mul_f32_e32 v99, 0.15915494, v98
	v_rndne_f32_e32 v99, v99
	v_fmac_f32_e32 v98, 0xc0c90000, v99
	v_fmac_f32_e32 v98, 0xbafdaa22, v99
	v_mul_f32_e32 v98, 0.15915494, v98
	v_sin_f32_e32 v99, v98
	v_cos_f32_e32 v98, v98
	s_nop 0
	v_pk_mul_f32 v[102:103], v[98:99], v[100:101]
	s_nop 0
	v_sub_f32_e32 v105, v102, v103
	v_mov_b32_e32 v102, v99
	v_mov_b32_e32 v103, v98
	v_pk_mul_f32 v[98:99], v[102:103], v[100:101]
	s_nop 0
	v_add_f32_e32 v100, v98, v99
	v_cvt_pk_bf16_f32 v98, v120, v111
	v_cvt_pk_bf16_f32 v99, v104, v105
	global_store_dwordx2 v[106:107], v[98:99], off offset:288
	v_cvt_pk_bf16_f32 v98, v110, v112
	v_cvt_pk_bf16_f32 v99, v108, v100
	global_store_dwordx2 v[106:107], v[98:99], off offset:352
.LBB0_763:
	s_andn2_saveexec_b64 s[0:1], s[38:39]
	s_cbranch_execz .LBB0_765
	v_lshl_add_u64 v[120:121], v[134:135], 1, v[120:121]
	v_lshl_add_u64 v[120:121], v[120:121], 0, v[32:33]
	v_mul_f32_e32 v110, v110, v118
	v_mul_f32_e32 v111, v111, v118
	v_mul_f32_e32 v106, v106, v118
	v_mul_f32_e32 v107, v107, v118
	v_mul_f32_e32 v102, v102, v118
	v_mul_f32_e32 v103, v103, v118
	v_mul_f32_e32 v98, v98, v118
	v_mul_f32_e32 v99, v99, v118
	v_mul_f32_e32 v112, v112, v118
	v_mul_f32_e32 v113, v113, v118
	v_cvt_pk_bf16_f32 v110, v110, v111
	v_cvt_pk_bf16_f32 v111, v112, v113
	global_store_dwordx2 v[120:121], v[110:111], off
	v_mul_f32_e32 v108, v108, v118
	v_mul_f32_e32 v109, v109, v118
	v_cvt_pk_bf16_f32 v106, v106, v107
	v_cvt_pk_bf16_f32 v107, v108, v109
	global_store_dwordx2 v[120:121], v[106:107], off offset:32
	v_mul_f32_e32 v104, v104, v118
	v_mul_f32_e32 v105, v105, v118
	v_cvt_pk_bf16_f32 v102, v102, v103
	v_cvt_pk_bf16_f32 v103, v104, v105
	global_store_dwordx2 v[120:121], v[102:103], off offset:64
	v_mul_f32_e32 v100, v100, v118
	v_mul_f32_e32 v101, v101, v118
	v_cvt_pk_bf16_f32 v98, v98, v99
	v_cvt_pk_bf16_f32 v99, v100, v101
	global_store_dwordx2 v[120:121], v[98:99], off offset:96
.LBB0_765:
	s_or_b64 exec, exec, s[0:1]
	v_or_b32_e32 v103, 0x80, v154
	v_lshlrev_b32_e32 v98, 2, v103
	s_movk_i32 s0, 0xffa0
	v_and_or_b32 v98, v98, s0, v153
	v_readlane_b32 s0, v255, 25
	v_ashrrev_i32_e32 v99, 31, v98
	v_readlane_b32 s1, v255, 26
	s_nop 1
	v_lshl_add_u64 v[98:99], v[98:99], 2, s[0:1]
	global_load_dword v100, v[98:99], off
	s_mov_b32 s0, 0x800000
	s_waitcnt vmcnt(0) lgkmcnt(0)
	v_fmamk_f32 v100, v100, 0x3b000000, v186
	v_cmp_gt_f32_e64 s[0:1], s0, v100
	v_mul_f32_e32 v101, 0x4b800000, v100
	s_nop 0
	v_cndmask_b32_e64 v100, v100, v101, s[0:1]
	v_rsq_f32_e32 v100, v100
	s_nop 0
	v_mul_f32_e32 v101, 0x45800000, v100
	v_cndmask_b32_e64 v100, v100, v101, s[0:1]
	v_mul_f32_e32 v102, 0x3dd53b94, v100
	v_mul_hi_i32_i24_e32 v101, 0xc00, v103
	v_mul_i32_i24_e32 v100, 0xc00, v103
	v_and_b32_e32 v103, 0xfef, v103
	v_lshl_add_u64 v[104:105], v[136:137], 0, v[100:101]
	v_cndmask_b32_e32 v103, v103, v155, vcc
	s_and_saveexec_b64 s[0:1], s[6:7]
	s_xor_b64 s[38:39], exec, s[0:1]
	s_cbranch_execz .LBB0_767
; DEVI void rope_cs(int pos, int i, float& c, float& s) {
;   float fr = exp2f(-(float)i * (13.287712379549449f / 32.f));
;   float a = (float)pos * fr;
;   float n = rintf(a * 0.15915494309189535f);
;   float r = fmaf(-n, 6.28125f, a);
;   r = fmaf(-n, 0.0019353071795864769f, r);
;   s = __sinf(r); c = __cosf(r);
; DEVI void run_phase(const int ph, const Params& P, char* shmc, const int wave_u) {
;     ...
;               const int s = col - MP; const int pos = samp ? PAST + (s & 31) : (col & (SEQ - 1));
; #pragma unroll
;               for (int pr = 0; pr < 2; ++pr) {
;                 const f32x4 x1 = acc[ai][bj][2 * pr][n], x2 = acc[ai][bj][2 * pr + 1][n];
;                 float y1[4], y2[4];
; #pragma unroll
;                 for (int j = 0; j < 4; ++j) { const int i = pr * 16 + fq * 4 + j; float c, sn; rope_cs(pos, i, c, sn);
;                   const float a = x1[j] * sc, b = x2[j] * sc; y1[j] = a * c - b * sn; y2[j] = a * sn + b * c; }
;                 const int i0 = pr * 16 + fq * 4;
;                 st_bf4(qrow + 128 + i0, y1[0], y1[1], y1[2], y1[3]); st_bf4(qrow + 160 + i0, y2[0], y2[1], y2[2], y2[3]);
;                 __builtin_amdgcn_sched_barrier(0);
	v_mul_f32_e32 v106, 0xbed49a78, v150
	s_mov_b32 s4, 0xc2fc0000
	v_cmp_gt_f32_e64 s[0:1], s4, v106
	v_cvt_f32_u32_e32 v112, v103
	v_mov_b32_e32 v109, v90
	v_cndmask_b32_e64 v107, 0, v191, s[0:1]
	v_fmac_f32_e32 v107, 0xbed49a78, v150
	v_exp_f32_e32 v107, v107
	v_cvt_f32_ubyte0_e32 v90, v149
	v_cndmask_b32_e64 v106, 0, v190, s[0:1]
	v_mov_b32_e32 v108, v94
	v_mul_f32_e32 v94, 0xbed49a78, v90
	v_ldexp_f32 v106, v107, v106
	v_cmp_gt_f32_e64 s[0:1], s4, v94
	v_mul_f32_e32 v106, v106, v112
	v_mul_f32_e32 v107, 0.15915494, v106
	v_cndmask_b32_e64 v94, 0, v191, s[0:1]
	v_fmac_f32_e32 v94, 0xbed49a78, v90
	v_rndne_f32_e32 v107, v107
	v_exp_f32_e32 v90, v94
	v_fmac_f32_e32 v106, 0xc0c90000, v107
	v_fmac_f32_e32 v106, 0xbafdaa22, v107
	v_mul_f32_e32 v106, 0.15915494, v106
	v_cndmask_b32_e64 v94, 0, v190, s[0:1]
	v_sin_f32_e32 v107, v106
	v_cos_f32_e32 v106, v106
	v_ldexp_f32 v90, v90, v94
	v_mul_f32_e32 v90, v90, v112
	v_mul_f32_e32 v94, 0.15915494, v90
	v_pk_mul_f32 v[108:109], v[108:109], v[102:103] op_sel_hi:[1,0]
	v_rndne_f32_e32 v94, v94
	v_pk_mul_f32 v[110:111], v[106:107], v[108:109]
	v_fmac_f32_e32 v90, 0xc0c90000, v94
	v_sub_f32_e32 v113, v110, v111
	v_mov_b32_e32 v110, v107
	v_mov_b32_e32 v111, v106
	v_fmac_f32_e32 v90, 0xbafdaa22, v94
	v_pk_mul_f32 v[106:107], v[110:111], v[108:109]
	v_mul_f32_e32 v90, 0.15915494, v90
	v_add_f32_e32 v108, v106, v107
	v_sin_f32_e32 v107, v90
	v_cos_f32_e32 v106, v90
	v_mov_b32_e32 v90, v95
	v_pk_mul_f32 v[90:91], v[90:91], v[102:103] op_sel_hi:[1,0]
	s_nop 0
	v_pk_mul_f32 v[94:95], v[106:107], v[90:91]
	s_nop 0
	v_sub_f32_e32 v109, v94, v95
	v_mov_b32_e32 v94, v107
	v_mov_b32_e32 v95, v106
	v_pk_mul_f32 v[90:91], v[94:95], v[90:91]
	v_mov_b32_e32 v94, v96
	v_add_f32_e32 v110, v90, v91
	v_cvt_f32_ubyte0_e32 v90, v148
	v_mul_f32_e32 v91, 0xbed49a78, v90
	v_cmp_gt_f32_e64 s[0:1], s4, v91
	v_mov_b32_e32 v95, v92
	v_pk_mul_f32 v[94:95], v[94:95], v[102:103] op_sel_hi:[1,0]
	v_cndmask_b32_e64 v91, 0, v191, s[0:1]
	v_fmac_f32_e32 v91, 0xbed49a78, v90
	v_exp_f32_e32 v90, v91
	v_cndmask_b32_e64 v91, 0, v190, s[0:1]
	v_mov_b32_e32 v92, v97
	v_pk_mul_f32 v[92:93], v[92:93], v[102:103] op_sel_hi:[1,0]
	v_ldexp_f32 v90, v90, v91
	v_mul_f32_e32 v90, v90, v112
	v_mul_f32_e32 v91, 0.15915494, v90
	v_rndne_f32_e32 v91, v91
	v_fmac_f32_e32 v90, 0xc0c90000, v91
	v_fmac_f32_e32 v90, 0xbafdaa22, v91
	v_mul_f32_e32 v90, 0.15915494, v90
	v_sin_f32_e32 v91, v90
	v_cos_f32_e32 v90, v90
	s_nop 0
	v_pk_mul_f32 v[106:107], v[90:91], v[94:95]
	s_nop 0
	v_sub_f32_e32 v96, v106, v107
	v_mov_b32_e32 v106, v91
	v_mov_b32_e32 v107, v90
	v_pk_mul_f32 v[90:91], v[106:107], v[94:95]
	s_nop 0
	v_add_f32_e32 v106, v90, v91
	v_cvt_f32_ubyte0_e32 v90, v145
	v_mul_f32_e32 v91, 0xbed49a78, v90
	v_cmp_gt_f32_e64 s[0:1], s4, v91
	s_nop 1
	v_cndmask_b32_e64 v91, 0, v191, s[0:1]
	v_fmac_f32_e32 v91, 0xbed49a78, v90
	v_exp_f32_e32 v90, v91
	v_cndmask_b32_e64 v91, 0, v190, s[0:1]
	v_ldexp_f32 v90, v90, v91
	v_mul_f32_e32 v90, v90, v112
	v_mul_f32_e32 v91, 0.15915494, v90
	v_rndne_f32_e32 v91, v91
	v_fmac_f32_e32 v90, 0xc0c90000, v91
	v_fmac_f32_e32 v90, 0xbafdaa22, v91
	v_mul_f32_e32 v90, 0.15915494, v90
	v_sin_f32_e32 v91, v90
	v_cos_f32_e32 v90, v90
	s_nop 0
	v_pk_mul_f32 v[94:95], v[90:91], v[92:93]
	s_nop 0
	v_sub_f32_e32 v97, v94, v95
	v_mov_b32_e32 v94, v91
	v_mov_b32_e32 v95, v90
	v_pk_mul_f32 v[90:91], v[94:95], v[92:93]
	v_cvt_pk_bf16_f32 v92, v113, v109
	v_cvt_pk_bf16_f32 v93, v96, v97
	s_nop 0
	v_add_f32_e32 v94, v90, v91
	v_lshl_add_u64 v[90:91], v[104:105], 0, v[32:33]
	global_store_dwordx2 v[90:91], v[92:93], off offset:256
	v_cvt_pk_bf16_f32 v92, v108, v110
	v_cvt_pk_bf16_f32 v93, v106, v94
	global_store_dwordx2 v[90:91], v[92:93], off offset:320
	v_cvt_f32_ubyte0_e32 v92, v144
	v_mul_f32_e32 v93, 0xbed49a78, v92
	v_cmp_gt_f32_e64 s[0:1], s4, v93
	v_mov_b32_e32 v95, v82
	v_cvt_f32_ubyte0_e32 v82, v142
	v_cndmask_b32_e64 v93, 0, v191, s[0:1]
	v_fmac_f32_e32 v93, 0xbed49a78, v92
	v_exp_f32_e32 v92, v93
	v_cndmask_b32_e64 v93, 0, v190, s[0:1]
	v_mov_b32_e32 v94, v86
	v_mul_f32_e32 v86, 0xbed49a78, v82
	v_ldexp_f32 v92, v92, v93
	v_cmp_gt_f32_e64 s[0:1], s4, v86
	v_mul_f32_e32 v92, v92, v112
	v_mul_f32_e32 v93, 0.15915494, v92
	v_cndmask_b32_e64 v86, 0, v191, s[0:1]
	v_fmac_f32_e32 v86, 0xbed49a78, v82
	v_rndne_f32_e32 v93, v93
	v_exp_f32_e32 v82, v86
	v_fmac_f32_e32 v92, 0xc0c90000, v93
	v_fmac_f32_e32 v92, 0xbafdaa22, v93
	v_mul_f32_e32 v92, 0.15915494, v92
	v_cndmask_b32_e64 v86, 0, v190, s[0:1]
	v_sin_f32_e32 v93, v92
	v_cos_f32_e32 v92, v92
	v_ldexp_f32 v82, v82, v86
	v_mul_f32_e32 v82, v82, v112
	v_mul_f32_e32 v86, 0.15915494, v82
	v_pk_mul_f32 v[94:95], v[94:95], v[102:103] op_sel_hi:[1,0]
	v_rndne_f32_e32 v86, v86
	v_pk_mul_f32 v[96:97], v[92:93], v[94:95]
	v_fmac_f32_e32 v82, 0xc0c90000, v86
	v_sub_f32_e32 v104, v96, v97
	v_mov_b32_e32 v96, v93
	v_mov_b32_e32 v97, v92
	v_fmac_f32_e32 v82, 0xbafdaa22, v86
	v_pk_mul_f32 v[92:93], v[96:97], v[94:95]
	v_mul_f32_e32 v82, 0.15915494, v82
	v_add_f32_e32 v94, v92, v93
	v_sin_f32_e32 v93, v82
	v_cos_f32_e32 v92, v82
	v_mov_b32_e32 v82, v87
	v_pk_mul_f32 v[82:83], v[82:83], v[102:103] op_sel_hi:[1,0]
	s_nop 0
	v_pk_mul_f32 v[86:87], v[92:93], v[82:83]
	s_nop 0
	v_sub_f32_e32 v95, v86, v87
	v_mov_b32_e32 v86, v93
	v_mov_b32_e32 v87, v92
	v_pk_mul_f32 v[82:83], v[86:87], v[82:83]
	v_mov_b32_e32 v86, v88
	v_add_f32_e32 v96, v82, v83
	v_cvt_f32_ubyte0_e32 v82, v139
	v_mul_f32_e32 v83, 0xbed49a78, v82
	v_cmp_gt_f32_e64 s[0:1], s4, v83
	v_mov_b32_e32 v87, v84
	v_pk_mul_f32 v[86:87], v[86:87], v[102:103] op_sel_hi:[1,0]
	v_cndmask_b32_e64 v83, 0, v191, s[0:1]
	v_fmac_f32_e32 v83, 0xbed49a78, v82
; DEVI int RSI(int row) { return ((row >> 3) << 5) | (row & 7); }
; DEVI void rope_cs(int pos, int i, float& c, float& s) {
;   float fr = exp2f(-(float)i * (13.287712379549449f / 32.f));
;   float a = (float)pos * fr;
;   float n = rintf(a * 0.15915494309189535f);
;   float r = fmaf(-n, 6.28125f, a);
;   r = fmaf(-n, 0.0019353071795864769f, r);
;   s = __sinf(r); c = __cosf(r);
; DEVI void run_phase(const int ph, const Params& P, char* shmc, const int wave_u) {
;     ...
;             const float sc = rsqrtf(ssq[RSI(col)] * (1.f / 512) + EPS) * MLA_C;
;             bf16* qrow = qm + (long)col * 1536 + h * 192;
;             if (c0 < 128) {
; #pragma unroll
;               for (int m = 0; m < 4; ++m) { const f32x4 v = acc[ai][bj][m][n];
;                 st_bf4(qrow + c0 + m * 16 + fq * 4, v[0] * sc, v[1] * sc, v[2] * sc, v[3] * sc); }
;               __builtin_amdgcn_sched_barrier(0);
;             } else {
;               const int s = col - MP; const int pos = samp ? PAST + (s & 31) : (col & (SEQ - 1));
; #pragma unroll
;               for (int pr = 0; pr < 2; ++pr) {
;                 const f32x4 x1 = acc[ai][bj][2 * pr][n], x2 = acc[ai][bj][2 * pr + 1][n];
;                 float y1[4], y2[4];
; #pragma unroll
;                 for (int j = 0; j < 4; ++j) { const int i = pr * 16 + fq * 4 + j; float c, sn; rope_cs(pos, i, c, sn);
;                   const float a = x1[j] * sc, b = x2[j] * sc; y1[j] = a * c - b * sn; y2[j] = a * sn + b * c; }
;                 const int i0 = pr * 16 + fq * 4;
;                 st_bf4(qrow + 128 + i0, y1[0], y1[1], y1[2], y1[3]); st_bf4(qrow + 160 + i0, y2[0], y2[1], y2[2], y2[3]);
;                 __builtin_amdgcn_sched_barrier(0);
	v_exp_f32_e32 v82, v83
	v_cndmask_b32_e64 v83, 0, v190, s[0:1]
	v_mov_b32_e32 v84, v89
	v_pk_mul_f32 v[84:85], v[84:85], v[102:103] op_sel_hi:[1,0]
	v_ldexp_f32 v82, v82, v83
	v_mul_f32_e32 v82, v82, v112
	v_mul_f32_e32 v83, 0.15915494, v82
	v_rndne_f32_e32 v83, v83
	v_fmac_f32_e32 v82, 0xc0c90000, v83
	v_fmac_f32_e32 v82, 0xbafdaa22, v83
	v_mul_f32_e32 v82, 0.15915494, v82
	v_sin_f32_e32 v83, v82
	v_cos_f32_e32 v82, v82
	s_nop 0
	v_pk_mul_f32 v[92:93], v[82:83], v[86:87]
	s_nop 0
	v_sub_f32_e32 v88, v92, v93
	v_mov_b32_e32 v92, v83
	v_mov_b32_e32 v93, v82
	v_pk_mul_f32 v[82:83], v[92:93], v[86:87]
	s_nop 0
	v_add_f32_e32 v92, v82, v83
	v_cvt_f32_ubyte0_e32 v82, v143
	v_mul_f32_e32 v83, 0xbed49a78, v82
	v_cmp_gt_f32_e64 s[0:1], s4, v83
	s_nop 1
	v_cndmask_b32_e64 v83, 0, v191, s[0:1]
	v_fmac_f32_e32 v83, 0xbed49a78, v82
	v_exp_f32_e32 v82, v83
	v_cndmask_b32_e64 v83, 0, v190, s[0:1]
	v_ldexp_f32 v82, v82, v83
	v_mul_f32_e32 v82, v82, v112
	v_mul_f32_e32 v83, 0.15915494, v82
	v_rndne_f32_e32 v83, v83
	v_fmac_f32_e32 v82, 0xc0c90000, v83
	v_fmac_f32_e32 v82, 0xbafdaa22, v83
	v_mul_f32_e32 v82, 0.15915494, v82
	v_sin_f32_e32 v83, v82
	v_cos_f32_e32 v82, v82
	s_nop 0
	v_pk_mul_f32 v[86:87], v[82:83], v[84:85]
	s_nop 0
	v_sub_f32_e32 v89, v86, v87
	v_mov_b32_e32 v86, v83
	v_mov_b32_e32 v87, v82
	v_pk_mul_f32 v[82:83], v[86:87], v[84:85]
	s_nop 0
	v_add_f32_e32 v84, v82, v83
	v_cvt_pk_bf16_f32 v82, v104, v95
	v_cvt_pk_bf16_f32 v83, v88, v89
	global_store_dwordx2 v[90:91], v[82:83], off offset:288
	v_cvt_pk_bf16_f32 v82, v94, v96
	v_cvt_pk_bf16_f32 v83, v92, v84
	global_store_dwordx2 v[90:91], v[82:83], off offset:352
.LBB0_767:
	s_andn2_saveexec_b64 s[0:1], s[38:39]
	s_cbranch_execz .LBB0_769
	v_lshl_add_u64 v[104:105], v[134:135], 1, v[104:105]
	v_lshl_add_u64 v[104:105], v[104:105], 0, v[32:33]
	v_mul_f32_e32 v94, v94, v102
	v_mul_f32_e32 v95, v95, v102
	v_mul_f32_e32 v90, v90, v102
	v_mul_f32_e32 v91, v91, v102
	v_mul_f32_e32 v86, v86, v102
	v_mul_f32_e32 v87, v87, v102
	v_mul_f32_e32 v82, v82, v102
	v_mul_f32_e32 v83, v83, v102
	v_mul_f32_e32 v96, v96, v102
	v_mul_f32_e32 v97, v97, v102
	v_cvt_pk_bf16_f32 v94, v94, v95
	v_cvt_pk_bf16_f32 v95, v96, v97
	global_store_dwordx2 v[104:105], v[94:95], off
	v_mul_f32_e32 v92, v92, v102
	v_mul_f32_e32 v93, v93, v102
	v_cvt_pk_bf16_f32 v90, v90, v91
	v_cvt_pk_bf16_f32 v91, v92, v93
	global_store_dwordx2 v[104:105], v[90:91], off offset:32
	v_mul_f32_e32 v88, v88, v102
	v_mul_f32_e32 v89, v89, v102
	v_cvt_pk_bf16_f32 v86, v86, v87
	v_cvt_pk_bf16_f32 v87, v88, v89
	global_store_dwordx2 v[104:105], v[86:87], off offset:64
	v_mul_f32_e32 v84, v84, v102
	v_mul_f32_e32 v85, v85, v102
	v_cvt_pk_bf16_f32 v82, v82, v83
	v_cvt_pk_bf16_f32 v83, v84, v85
	global_store_dwordx2 v[104:105], v[82:83], off offset:96
.LBB0_769:
	s_or_b64 exec, exec, s[0:1]
	v_or_b32_e32 v86, 0x90, v154
	v_lshlrev_b32_e32 v82, 2, v86
	s_movk_i32 s0, 0xffe0
	v_and_or_b32 v82, v82, s0, v153
	v_readlane_b32 s0, v255, 25
	v_ashrrev_i32_e32 v83, 31, v82
	v_readlane_b32 s1, v255, 26
	v_and_b32_e32 v90, 0xfff, v86
	s_nop 0
	v_lshl_add_u64 v[84:85], v[82:83], 2, s[0:1]
	global_load_dword v82, v[84:85], off
	s_mov_b32 s0, 0x800000
	v_mul_hi_i32_i24_e32 v83, 0xc00, v86
	s_waitcnt vmcnt(0) lgkmcnt(0)
	v_fmamk_f32 v82, v82, 0x3b000000, v186
	v_mul_f32_e32 v87, 0x4b800000, v82
	v_cmp_gt_f32_e64 s[0:1], s0, v82
	s_nop 1
	v_cndmask_b32_e64 v82, v82, v87, s[0:1]
	v_rsq_f32_e32 v87, v82
	v_mul_i32_i24_e32 v82, 0xc00, v86
	v_lshl_add_u64 v[88:89], v[136:137], 0, v[82:83]
	v_mul_f32_e32 v86, 0x45800000, v87
	v_cndmask_b32_e64 v86, v87, v86, s[0:1]
	v_mul_f32_e32 v86, 0x3dd53b94, v86
	v_cndmask_b32_e32 v87, v90, v122, vcc
	s_and_saveexec_b64 s[0:1], s[6:7]
	s_xor_b64 s[0:1], exec, s[0:1]
	s_cbranch_execz .LBB0_771
	v_mul_f32_e32 v90, 0xbed49a78, v150
	s_mov_b32 s4, 0xc2fc0000
	v_cmp_gt_f32_e32 vcc, s4, v90
	v_cvt_f32_u32_e32 v96, v87
	v_mov_b32_e32 v93, v74
	v_cndmask_b32_e32 v91, 0, v191, vcc
	v_fmac_f32_e32 v91, 0xbed49a78, v150
	v_exp_f32_e32 v91, v91
	v_cvt_f32_ubyte0_e32 v74, v149
	v_cndmask_b32_e32 v90, 0, v190, vcc
	v_mov_b32_e32 v92, v78
	v_mul_f32_e32 v78, 0xbed49a78, v74
	v_ldexp_f32 v90, v91, v90
	v_cmp_gt_f32_e32 vcc, s4, v78
	v_mul_f32_e32 v90, v90, v96
	v_mul_f32_e32 v91, 0.15915494, v90
	v_cndmask_b32_e32 v78, 0, v191, vcc
	v_fmac_f32_e32 v78, 0xbed49a78, v74
	v_rndne_f32_e32 v91, v91
	v_exp_f32_e32 v74, v78
	v_fmac_f32_e32 v90, 0xc0c90000, v91
	v_fmac_f32_e32 v90, 0xbafdaa22, v91
	v_mul_f32_e32 v90, 0.15915494, v90
	v_cndmask_b32_e32 v78, 0, v190, vcc
	v_sin_f32_e32 v91, v90
	v_cos_f32_e32 v90, v90
	v_ldexp_f32 v74, v74, v78
	v_mul_f32_e32 v74, v74, v96
	v_mul_f32_e32 v78, 0.15915494, v74
	v_pk_mul_f32 v[92:93], v[92:93], v[86:87] op_sel_hi:[1,0]
	v_rndne_f32_e32 v78, v78
	v_pk_mul_f32 v[94:95], v[90:91], v[92:93]
	v_fmac_f32_e32 v74, 0xc0c90000, v78
	v_sub_f32_e32 v97, v94, v95
	v_mov_b32_e32 v94, v91
	v_mov_b32_e32 v95, v90
	v_fmac_f32_e32 v74, 0xbafdaa22, v78
	v_pk_mul_f32 v[90:91], v[94:95], v[92:93]
	v_mul_f32_e32 v74, 0.15915494, v74
	v_add_f32_e32 v92, v90, v91
	v_sin_f32_e32 v91, v74
	v_cos_f32_e32 v90, v74
	v_mov_b32_e32 v74, v79
	v_pk_mul_f32 v[74:75], v[74:75], v[86:87] op_sel_hi:[1,0]
	s_nop 0
	v_pk_mul_f32 v[78:79], v[90:91], v[74:75]
	s_nop 0
	v_sub_f32_e32 v93, v78, v79
	v_mov_b32_e32 v78, v91
	v_mov_b32_e32 v79, v90
	v_pk_mul_f32 v[74:75], v[78:79], v[74:75]
	v_mov_b32_e32 v78, v80
	v_add_f32_e32 v94, v74, v75
	v_cvt_f32_ubyte0_e32 v74, v148
	v_mul_f32_e32 v75, 0xbed49a78, v74
	v_cmp_gt_f32_e32 vcc, s4, v75
	v_mov_b32_e32 v79, v76
	v_pk_mul_f32 v[78:79], v[78:79], v[86:87] op_sel_hi:[1,0]
	v_cndmask_b32_e32 v75, 0, v191, vcc
; DEVI void rope_cs(int pos, int i, float& c, float& s) {
;   float fr = exp2f(-(float)i * (13.287712379549449f / 32.f));
;   float a = (float)pos * fr;
;   float n = rintf(a * 0.15915494309189535f);
;   float r = fmaf(-n, 6.28125f, a);
;   r = fmaf(-n, 0.0019353071795864769f, r);
;   s = __sinf(r); c = __cosf(r);
; DEVI void run_phase(const int ph, const Params& P, char* shmc, const int wave_u) {
;     ...
;               const int s = col - MP; const int pos = samp ? PAST + (s & 31) : (col & (SEQ - 1));
; #pragma unroll
;               for (int pr = 0; pr < 2; ++pr) {
;                 const f32x4 x1 = acc[ai][bj][2 * pr][n], x2 = acc[ai][bj][2 * pr + 1][n];
;                 float y1[4], y2[4];
; #pragma unroll
;                 for (int j = 0; j < 4; ++j) { const int i = pr * 16 + fq * 4 + j; float c, sn; rope_cs(pos, i, c, sn);
;                   const float a = x1[j] * sc, b = x2[j] * sc; y1[j] = a * c - b * sn; y2[j] = a * sn + b * c; }
;                 const int i0 = pr * 16 + fq * 4;
;                 st_bf4(qrow + 128 + i0, y1[0], y1[1], y1[2], y1[3]); st_bf4(qrow + 160 + i0, y2[0], y2[1], y2[2], y2[3]);
;                 __builtin_amdgcn_sched_barrier(0);
	v_fmac_f32_e32 v75, 0xbed49a78, v74
	v_exp_f32_e32 v74, v75
	v_cndmask_b32_e32 v75, 0, v190, vcc
	v_mov_b32_e32 v76, v81
	v_pk_mul_f32 v[76:77], v[76:77], v[86:87] op_sel_hi:[1,0]
	v_ldexp_f32 v74, v74, v75
	v_mul_f32_e32 v74, v74, v96
	v_mul_f32_e32 v75, 0.15915494, v74
	v_rndne_f32_e32 v75, v75
	v_fmac_f32_e32 v74, 0xc0c90000, v75
	v_fmac_f32_e32 v74, 0xbafdaa22, v75
	v_mul_f32_e32 v74, 0.15915494, v74
	v_sin_f32_e32 v75, v74
	v_cos_f32_e32 v74, v74
	s_nop 0
	v_pk_mul_f32 v[90:91], v[74:75], v[78:79]
	s_nop 0
	v_sub_f32_e32 v80, v90, v91
	v_mov_b32_e32 v90, v75
	v_mov_b32_e32 v91, v74
	v_pk_mul_f32 v[74:75], v[90:91], v[78:79]
	s_nop 0
	v_add_f32_e32 v90, v74, v75
	v_cvt_f32_ubyte0_e32 v74, v145
	v_mul_f32_e32 v75, 0xbed49a78, v74
	v_cmp_gt_f32_e32 vcc, s4, v75
	s_nop 1
	v_cndmask_b32_e32 v75, 0, v191, vcc
	v_fmac_f32_e32 v75, 0xbed49a78, v74
	v_exp_f32_e32 v74, v75
	v_cndmask_b32_e32 v75, 0, v190, vcc
	v_ldexp_f32 v74, v74, v75
	v_mul_f32_e32 v74, v74, v96
	v_mul_f32_e32 v75, 0.15915494, v74
	v_rndne_f32_e32 v75, v75
	v_fmac_f32_e32 v74, 0xc0c90000, v75
	v_fmac_f32_e32 v74, 0xbafdaa22, v75
	v_mul_f32_e32 v74, 0.15915494, v74
	v_sin_f32_e32 v75, v74
	v_cos_f32_e32 v74, v74
	s_nop 0
	v_pk_mul_f32 v[78:79], v[74:75], v[76:77]
	s_nop 0
	v_sub_f32_e32 v81, v78, v79
	v_mov_b32_e32 v78, v75
	v_mov_b32_e32 v79, v74
	v_pk_mul_f32 v[74:75], v[78:79], v[76:77]
	v_cvt_pk_bf16_f32 v76, v97, v93
	v_cvt_pk_bf16_f32 v77, v80, v81
	s_nop 0
	v_add_f32_e32 v78, v74, v75
	v_lshl_add_u64 v[74:75], v[88:89], 0, v[32:33]
	global_store_dwordx2 v[74:75], v[76:77], off offset:256
	v_cvt_pk_bf16_f32 v76, v92, v94
	v_cvt_pk_bf16_f32 v77, v90, v78
	global_store_dwordx2 v[74:75], v[76:77], off offset:320
	v_cvt_f32_ubyte0_e32 v76, v144
	v_mul_f32_e32 v77, 0xbed49a78, v76
	v_cmp_gt_f32_e32 vcc, s4, v77
	v_mov_b32_e32 v79, v66
	v_cvt_f32_ubyte0_e32 v66, v142
	v_cndmask_b32_e32 v77, 0, v191, vcc
	v_fmac_f32_e32 v77, 0xbed49a78, v76
	v_exp_f32_e32 v76, v77
	v_cndmask_b32_e32 v77, 0, v190, vcc
	v_mov_b32_e32 v78, v70
	v_mul_f32_e32 v70, 0xbed49a78, v66
	v_ldexp_f32 v76, v76, v77
	v_cmp_gt_f32_e32 vcc, s4, v70
	v_mul_f32_e32 v76, v76, v96
	v_mul_f32_e32 v77, 0.15915494, v76
	v_cndmask_b32_e32 v70, 0, v191, vcc
	v_fmac_f32_e32 v70, 0xbed49a78, v66
	v_rndne_f32_e32 v77, v77
	v_exp_f32_e32 v66, v70
	v_fmac_f32_e32 v76, 0xc0c90000, v77
	v_fmac_f32_e32 v76, 0xbafdaa22, v77
	v_mul_f32_e32 v76, 0.15915494, v76
	v_cndmask_b32_e32 v70, 0, v190, vcc
	v_sin_f32_e32 v77, v76
	v_cos_f32_e32 v76, v76
	v_ldexp_f32 v66, v66, v70
	v_mul_f32_e32 v66, v66, v96
	v_mul_f32_e32 v70, 0.15915494, v66
	v_pk_mul_f32 v[78:79], v[78:79], v[86:87] op_sel_hi:[1,0]
	v_rndne_f32_e32 v70, v70
	v_pk_mul_f32 v[80:81], v[76:77], v[78:79]
	v_fmac_f32_e32 v66, 0xc0c90000, v70
	v_sub_f32_e32 v88, v80, v81
	v_mov_b32_e32 v80, v77
	v_mov_b32_e32 v81, v76
	v_fmac_f32_e32 v66, 0xbafdaa22, v70
	v_pk_mul_f32 v[76:77], v[80:81], v[78:79]
	v_mul_f32_e32 v66, 0.15915494, v66
	v_add_f32_e32 v78, v76, v77
	v_sin_f32_e32 v77, v66
	v_cos_f32_e32 v76, v66
	v_mov_b32_e32 v66, v71
	v_pk_mul_f32 v[66:67], v[66:67], v[86:87] op_sel_hi:[1,0]
	s_nop 0
	v_pk_mul_f32 v[70:71], v[76:77], v[66:67]
	s_nop 0
	v_sub_f32_e32 v79, v70, v71
	v_mov_b32_e32 v70, v77
	v_mov_b32_e32 v71, v76
	v_pk_mul_f32 v[66:67], v[70:71], v[66:67]
	v_mov_b32_e32 v70, v72
	v_add_f32_e32 v80, v66, v67
	v_cvt_f32_ubyte0_e32 v66, v139
	v_mul_f32_e32 v67, 0xbed49a78, v66
	v_cmp_gt_f32_e32 vcc, s4, v67
	v_mov_b32_e32 v71, v68
	v_pk_mul_f32 v[70:71], v[70:71], v[86:87] op_sel_hi:[1,0]
	v_cndmask_b32_e32 v67, 0, v191, vcc
	v_fmac_f32_e32 v67, 0xbed49a78, v66
	v_exp_f32_e32 v66, v67
	v_cndmask_b32_e32 v67, 0, v190, vcc
	v_mov_b32_e32 v68, v73
	v_pk_mul_f32 v[68:69], v[68:69], v[86:87] op_sel_hi:[1,0]
	v_ldexp_f32 v66, v66, v67
	v_mul_f32_e32 v66, v66, v96
	v_mul_f32_e32 v67, 0.15915494, v66
	v_rndne_f32_e32 v67, v67
	v_fmac_f32_e32 v66, 0xc0c90000, v67
	v_fmac_f32_e32 v66, 0xbafdaa22, v67
	v_mul_f32_e32 v66, 0.15915494, v66
	v_sin_f32_e32 v67, v66
	v_cos_f32_e32 v66, v66
	s_nop 0
	v_pk_mul_f32 v[76:77], v[66:67], v[70:71]
	s_nop 0
	v_sub_f32_e32 v72, v76, v77
	v_mov_b32_e32 v76, v67
	v_mov_b32_e32 v77, v66
	v_pk_mul_f32 v[66:67], v[76:77], v[70:71]
	s_nop 0
	v_add_f32_e32 v76, v66, v67
	v_cvt_f32_ubyte0_e32 v66, v143
	v_mul_f32_e32 v67, 0xbed49a78, v66
	v_cmp_gt_f32_e32 vcc, s4, v67
	s_nop 1
	v_cndmask_b32_e32 v67, 0, v191, vcc
	v_fmac_f32_e32 v67, 0xbed49a78, v66
	v_exp_f32_e32 v66, v67
	v_cndmask_b32_e32 v67, 0, v190, vcc
	v_ldexp_f32 v66, v66, v67
	v_mul_f32_e32 v66, v66, v96
	v_mul_f32_e32 v67, 0.15915494, v66
	v_rndne_f32_e32 v67, v67
	v_fmac_f32_e32 v66, 0xc0c90000, v67
	v_fmac_f32_e32 v66, 0xbafdaa22, v67
	v_mul_f32_e32 v66, 0.15915494, v66
	v_sin_f32_e32 v67, v66
	v_cos_f32_e32 v66, v66
	s_nop 0
	v_pk_mul_f32 v[70:71], v[66:67], v[68:69]
	s_nop 0
	v_sub_f32_e32 v73, v70, v71
	v_mov_b32_e32 v70, v67
	v_mov_b32_e32 v71, v66
	v_pk_mul_f32 v[66:67], v[70:71], v[68:69]
	s_nop 0
	v_add_f32_e32 v68, v66, v67
	v_cvt_pk_bf16_f32 v66, v88, v79
	v_cvt_pk_bf16_f32 v67, v72, v73
	global_store_dwordx2 v[74:75], v[66:67], off offset:288
	v_cvt_pk_bf16_f32 v66, v78, v80
	v_cvt_pk_bf16_f32 v67, v76, v68
	global_store_dwordx2 v[74:75], v[66:67], off offset:352
; DEVI int RSI(int row) { return ((row >> 3) << 5) | (row & 7); }
; DEVI void rope_cs(int pos, int i, float& c, float& s) {
;   float fr = exp2f(-(float)i * (13.287712379549449f / 32.f));
;   float a = (float)pos * fr;
;   float n = rintf(a * 0.15915494309189535f);
;   float r = fmaf(-n, 6.28125f, a);
;   r = fmaf(-n, 0.0019353071795864769f, r);
;   s = __sinf(r); c = __cosf(r);
; DEVI void run_phase(const int ph, const Params& P, char* shmc, const int wave_u) {
;     ...
;       for (int ai = 0; ai < 2; ++ai) {
;         const int gb = brow + ai * 128 + wr * 64; const int h = gb / 192, c0 = gb % 192;
; #pragma unroll
;         for (int bj = 0; bj < 2; ++bj)
; #pragma unroll
;           for (int n = 0; n < 2; ++n) {
;             const int col = bcol + bj * 128 + wc * 32 + n * 16 + fr;
;             const float sc = rsqrtf(ssq[RSI(col)] * (1.f / 512) + EPS) * MLA_C;
;             bf16* qrow = qm + (long)col * 1536 + h * 192;
;             if (c0 < 128) {
; #pragma unroll
;               for (int m = 0; m < 4; ++m) { const f32x4 v = acc[ai][bj][m][n];
;                 st_bf4(qrow + c0 + m * 16 + fq * 4, v[0] * sc, v[1] * sc, v[2] * sc, v[3] * sc); }
;               __builtin_amdgcn_sched_barrier(0);
;             } else {
;               const int s = col - MP; const int pos = samp ? PAST + (s & 31) : (col & (SEQ - 1));
; #pragma unroll
;               for (int pr = 0; pr < 2; ++pr) {
;                 const f32x4 x1 = acc[ai][bj][2 * pr][n], x2 = acc[ai][bj][2 * pr + 1][n];
;                 float y1[4], y2[4];
; #pragma unroll
;                 for (int j = 0; j < 4; ++j) { const int i = pr * 16 + fq * 4 + j; float c, sn; rope_cs(pos, i, c, sn);
;                   const float a = x1[j] * sc, b = x2[j] * sc; y1[j] = a * c - b * sn; y2[j] = a * sn + b * c; }
;                 const int i0 = pr * 16 + fq * 4;
;                 st_bf4(qrow + 128 + i0, y1[0], y1[1], y1[2], y1[3]); st_bf4(qrow + 160 + i0, y2[0], y2[1], y2[2], y2[3]);
;                 __builtin_amdgcn_sched_barrier(0);
.LBB0_771:
	s_andn2_saveexec_b64 s[0:1], s[0:1]
	s_cbranch_execz .LBB0_773
	v_lshl_add_u64 v[88:89], v[134:135], 1, v[88:89]
	v_lshl_add_u64 v[88:89], v[88:89], 0, v[32:33]
	v_mul_f32_e32 v78, v78, v86
	v_mul_f32_e32 v79, v79, v86
	v_mul_f32_e32 v74, v74, v86
	v_mul_f32_e32 v75, v75, v86
	v_mul_f32_e32 v70, v70, v86
	v_mul_f32_e32 v71, v71, v86
	v_mul_f32_e32 v66, v66, v86
	v_mul_f32_e32 v67, v67, v86
	v_mul_f32_e32 v80, v80, v86
	v_mul_f32_e32 v81, v81, v86
	v_cvt_pk_bf16_f32 v78, v78, v79
	v_cvt_pk_bf16_f32 v79, v80, v81
	global_store_dwordx2 v[88:89], v[78:79], off
	v_mul_f32_e32 v76, v76, v86
	v_mul_f32_e32 v77, v77, v86
	v_cvt_pk_bf16_f32 v74, v74, v75
	v_cvt_pk_bf16_f32 v75, v76, v77
	global_store_dwordx2 v[88:89], v[74:75], off offset:32
	v_mul_f32_e32 v72, v72, v86
	v_mul_f32_e32 v73, v73, v86
	v_cvt_pk_bf16_f32 v70, v70, v71
	v_cvt_pk_bf16_f32 v71, v72, v73
	global_store_dwordx2 v[88:89], v[70:71], off offset:64
	v_mul_f32_e32 v68, v68, v86
	v_mul_f32_e32 v69, v69, v86
	v_cvt_pk_bf16_f32 v66, v66, v67
	v_cvt_pk_bf16_f32 v67, v68, v69
	global_store_dwordx2 v[88:89], v[66:67], off offset:96
.LBB0_773:
	s_or_b64 exec, exec, s[0:1]
	global_load_dword v67, v[132:133], off
	v_add_u32_e32 v66, 0x80, v151
	s_mov_b32 s0, 0x2aaaaaab
	v_mul_hi_i32 v68, v66, s0
	v_lshrrev_b32_e32 v69, 31, v68
	v_lshrrev_b32_e32 v68, 5, v68
	v_add_u32_e32 v68, v68, v69
	s_movk_i32 s0, 0xc0
	v_mul_lo_u32 v68, v68, s0
	s_mov_b32 s0, 0x800000
	v_readlane_b32 s6, v255, 17
	v_readlane_b32 s7, v255, 18
	v_sub_u32_e32 v66, v66, v68
	s_movk_i32 s4, 0x7f
	v_cmp_lt_i32_e32 vcc, s4, v66
	s_waitcnt vmcnt(0) lgkmcnt(0)
	v_fmamk_f32 v67, v67, 0x3b000000, v186
	v_mul_f32_e32 v69, 0x4b800000, v67
	v_cmp_gt_f32_e64 s[0:1], s0, v67
	s_nop 1
	v_cndmask_b32_e64 v67, v67, v69, s[0:1]
	v_rsq_f32_e32 v67, v67
	v_ashrrev_i32_e32 v69, 31, v68
	v_lshl_add_u64 v[68:69], v[68:69], 1, s[6:7]
	v_lshl_add_u64 v[72:73], v[68:69], 0, v[130:131]
	v_mul_f32_e32 v70, 0x45800000, v67
	v_cndmask_b32_e64 v67, v67, v70, s[0:1]
	v_mul_f32_e32 v70, 0x3dd53b94, v67
	s_and_saveexec_b64 s[0:1], vcc
	s_xor_b64 s[6:7], exec, s[0:1]
	s_cbranch_execz .LBB0_775
	v_mul_f32_e32 v71, 0xbed49a78, v150
	s_mov_b32 s4, 0xc2fc0000
	v_cmp_gt_f32_e64 s[0:1], s4, v71
	v_cvt_f32_u32_e32 v67, v152
	v_mov_b32_e32 v77, v58
	v_cndmask_b32_e64 v74, 0, v191, s[0:1]
	v_fmac_f32_e32 v74, 0xbed49a78, v150
	v_exp_f32_e32 v74, v74
	v_cvt_f32_ubyte0_e32 v58, v149
	v_cndmask_b32_e64 v71, 0, v190, s[0:1]
	v_mov_b32_e32 v76, v62
	v_mul_f32_e32 v62, 0xbed49a78, v58
	v_ldexp_f32 v71, v74, v71
	v_cmp_gt_f32_e64 s[0:1], s4, v62
	v_mul_f32_e32 v71, v71, v67
	v_mul_f32_e32 v74, 0.15915494, v71
	v_cndmask_b32_e64 v62, 0, v191, s[0:1]
	v_fmac_f32_e32 v62, 0xbed49a78, v58
	v_rndne_f32_e32 v74, v74
	v_exp_f32_e32 v58, v62
	v_fmac_f32_e32 v71, 0xc0c90000, v74
	v_fmac_f32_e32 v71, 0xbafdaa22, v74
	v_mul_f32_e32 v71, 0.15915494, v71
	v_cndmask_b32_e64 v62, 0, v190, s[0:1]
	v_sin_f32_e32 v75, v71
	v_cos_f32_e32 v74, v71
	v_ldexp_f32 v58, v58, v62
	v_mul_f32_e32 v58, v58, v67
	v_mul_f32_e32 v62, 0.15915494, v58
	v_pk_mul_f32 v[76:77], v[76:77], v[70:71] op_sel_hi:[1,0]
	v_rndne_f32_e32 v62, v62
	v_pk_mul_f32 v[78:79], v[74:75], v[76:77]
	v_fmac_f32_e32 v58, 0xc0c90000, v62
	v_sub_f32_e32 v71, v78, v79
	v_mov_b32_e32 v78, v75
	v_mov_b32_e32 v79, v74
	v_fmac_f32_e32 v58, 0xbafdaa22, v62
	v_pk_mul_f32 v[74:75], v[78:79], v[76:77]
	v_mul_f32_e32 v58, 0.15915494, v58
	v_add_f32_e32 v76, v74, v75
	v_sin_f32_e32 v75, v58
	v_cos_f32_e32 v74, v58
	v_mov_b32_e32 v58, v63
	v_pk_mul_f32 v[58:59], v[58:59], v[70:71] op_sel_hi:[1,0]
	s_nop 0
	v_pk_mul_f32 v[62:63], v[74:75], v[58:59]
	s_nop 0
	v_sub_f32_e32 v77, v62, v63
	v_mov_b32_e32 v62, v75
	v_mov_b32_e32 v63, v74
	v_pk_mul_f32 v[58:59], v[62:63], v[58:59]
	v_mov_b32_e32 v62, v64
	v_add_f32_e32 v78, v58, v59
	v_cvt_f32_ubyte0_e32 v58, v148
	v_mul_f32_e32 v59, 0xbed49a78, v58
	v_cmp_gt_f32_e64 s[0:1], s4, v59
	v_mov_b32_e32 v63, v60
	v_pk_mul_f32 v[62:63], v[62:63], v[70:71] op_sel_hi:[1,0]
	v_cndmask_b32_e64 v59, 0, v191, s[0:1]
	v_fmac_f32_e32 v59, 0xbed49a78, v58
	v_exp_f32_e32 v58, v59
	v_cndmask_b32_e64 v59, 0, v190, s[0:1]
	v_mov_b32_e32 v60, v65
	v_pk_mul_f32 v[60:61], v[60:61], v[70:71] op_sel_hi:[1,0]
	v_ldexp_f32 v58, v58, v59
	v_mul_f32_e32 v58, v58, v67
	v_mul_f32_e32 v59, 0.15915494, v58
	v_rndne_f32_e32 v59, v59
	v_fmac_f32_e32 v58, 0xc0c90000, v59
	v_fmac_f32_e32 v58, 0xbafdaa22, v59
	v_mul_f32_e32 v58, 0.15915494, v58
	v_sin_f32_e32 v59, v58
	v_cos_f32_e32 v58, v58
	s_nop 0
	v_pk_mul_f32 v[74:75], v[58:59], v[62:63]
	s_nop 0
	v_sub_f32_e32 v64, v74, v75
	v_mov_b32_e32 v74, v59
	v_mov_b32_e32 v75, v58
	v_pk_mul_f32 v[58:59], v[74:75], v[62:63]
	s_nop 0
	v_add_f32_e32 v74, v58, v59
	v_cvt_f32_ubyte0_e32 v58, v145
	v_mul_f32_e32 v59, 0xbed49a78, v58
	v_cmp_gt_f32_e64 s[0:1], s4, v59
	s_nop 1
	v_cndmask_b32_e64 v59, 0, v191, s[0:1]
	v_fmac_f32_e32 v59, 0xbed49a78, v58
	v_exp_f32_e32 v58, v59
	v_cndmask_b32_e64 v59, 0, v190, s[0:1]
	v_ldexp_f32 v58, v58, v59
	v_mul_f32_e32 v58, v58, v67
	v_mul_f32_e32 v59, 0.15915494, v58
	v_rndne_f32_e32 v59, v59
	v_fmac_f32_e32 v58, 0xc0c90000, v59
	v_fmac_f32_e32 v58, 0xbafdaa22, v59
	v_mul_f32_e32 v58, 0.15915494, v58
	v_sin_f32_e32 v59, v58
	v_cos_f32_e32 v58, v58
	s_nop 0
	v_pk_mul_f32 v[62:63], v[58:59], v[60:61]
	s_nop 0
	v_sub_f32_e32 v65, v62, v63
	v_mov_b32_e32 v62, v59
	v_mov_b32_e32 v63, v58
	v_pk_mul_f32 v[58:59], v[62:63], v[60:61]
	v_cvt_pk_bf16_f32 v60, v71, v77
	v_cvt_pk_bf16_f32 v61, v64, v65
	s_nop 0
	v_add_f32_e32 v62, v58, v59
	v_lshl_add_u64 v[58:59], v[72:73], 0, v[32:33]
	global_store_dwordx2 v[58:59], v[60:61], off offset:256
; DEVI void rope_cs(int pos, int i, float& c, float& s) {
;   float fr = exp2f(-(float)i * (13.287712379549449f / 32.f));
;   float a = (float)pos * fr;
;   float n = rintf(a * 0.15915494309189535f);
;   float r = fmaf(-n, 6.28125f, a);
;   r = fmaf(-n, 0.0019353071795864769f, r);
;   s = __sinf(r); c = __cosf(r);
; DEVI void run_phase(const int ph, const Params& P, char* shmc, const int wave_u) {
;     ...
;             if (c0 < 128) {
; #pragma unroll
;               for (int m = 0; m < 4; ++m) { const f32x4 v = acc[ai][bj][m][n];
;                 st_bf4(qrow + c0 + m * 16 + fq * 4, v[0] * sc, v[1] * sc, v[2] * sc, v[3] * sc); }
;               __builtin_amdgcn_sched_barrier(0);
;             } else {
;               const int s = col - MP; const int pos = samp ? PAST + (s & 31) : (col & (SEQ - 1));
; #pragma unroll
;               for (int pr = 0; pr < 2; ++pr) {
;                 const f32x4 x1 = acc[ai][bj][2 * pr][n], x2 = acc[ai][bj][2 * pr + 1][n];
;                 float y1[4], y2[4];
; #pragma unroll
;                 for (int j = 0; j < 4; ++j) { const int i = pr * 16 + fq * 4 + j; float c, sn; rope_cs(pos, i, c, sn);
;                   const float a = x1[j] * sc, b = x2[j] * sc; y1[j] = a * c - b * sn; y2[j] = a * sn + b * c; }
;                 const int i0 = pr * 16 + fq * 4;
;                 st_bf4(qrow + 128 + i0, y1[0], y1[1], y1[2], y1[3]); st_bf4(qrow + 160 + i0, y2[0], y2[1], y2[2], y2[3]);
;                 __builtin_amdgcn_sched_barrier(0);
	v_cvt_pk_bf16_f32 v60, v76, v78
	v_cvt_pk_bf16_f32 v61, v74, v62
	global_store_dwordx2 v[58:59], v[60:61], off offset:320
	v_cvt_f32_ubyte0_e32 v60, v144
	v_mul_f32_e32 v61, 0xbed49a78, v60
	v_cmp_gt_f32_e64 s[0:1], s4, v61
	v_mov_b32_e32 v63, v50
	v_cvt_f32_ubyte0_e32 v50, v142
	v_cndmask_b32_e64 v61, 0, v191, s[0:1]
	v_fmac_f32_e32 v61, 0xbed49a78, v60
	v_exp_f32_e32 v60, v61
	v_cndmask_b32_e64 v61, 0, v190, s[0:1]
	v_mov_b32_e32 v62, v54
	v_mul_f32_e32 v54, 0xbed49a78, v50
	v_ldexp_f32 v60, v60, v61
	v_cmp_gt_f32_e64 s[0:1], s4, v54
	v_mul_f32_e32 v60, v60, v67
	v_mul_f32_e32 v61, 0.15915494, v60
	v_cndmask_b32_e64 v54, 0, v191, s[0:1]
	v_fmac_f32_e32 v54, 0xbed49a78, v50
	v_rndne_f32_e32 v61, v61
	v_exp_f32_e32 v50, v54
	v_fmac_f32_e32 v60, 0xc0c90000, v61
	v_fmac_f32_e32 v60, 0xbafdaa22, v61
	v_mul_f32_e32 v60, 0.15915494, v60
	v_cndmask_b32_e64 v54, 0, v190, s[0:1]
	v_sin_f32_e32 v61, v60
	v_cos_f32_e32 v60, v60
	v_ldexp_f32 v50, v50, v54
	v_mul_f32_e32 v50, v50, v67
	v_mul_f32_e32 v54, 0.15915494, v50
	v_pk_mul_f32 v[62:63], v[62:63], v[70:71] op_sel_hi:[1,0]
	v_rndne_f32_e32 v54, v54
	v_pk_mul_f32 v[64:65], v[60:61], v[62:63]
	v_fmac_f32_e32 v50, 0xc0c90000, v54
	v_sub_f32_e32 v71, v64, v65
	v_mov_b32_e32 v64, v61
	v_mov_b32_e32 v65, v60
	v_fmac_f32_e32 v50, 0xbafdaa22, v54
	v_pk_mul_f32 v[60:61], v[64:65], v[62:63]
	v_mul_f32_e32 v50, 0.15915494, v50
	v_add_f32_e32 v62, v60, v61
	v_sin_f32_e32 v61, v50
	v_cos_f32_e32 v60, v50
	v_mov_b32_e32 v50, v55
	v_pk_mul_f32 v[50:51], v[50:51], v[70:71] op_sel_hi:[1,0]
	s_nop 0
	v_pk_mul_f32 v[54:55], v[60:61], v[50:51]
	s_nop 0
	v_sub_f32_e32 v63, v54, v55
	v_mov_b32_e32 v54, v61
	v_mov_b32_e32 v55, v60
	v_pk_mul_f32 v[50:51], v[54:55], v[50:51]
	v_mov_b32_e32 v54, v56
	v_add_f32_e32 v64, v50, v51
	v_cvt_f32_ubyte0_e32 v50, v139
	v_mul_f32_e32 v51, 0xbed49a78, v50
	v_cmp_gt_f32_e64 s[0:1], s4, v51
	v_mov_b32_e32 v55, v52
	v_pk_mul_f32 v[54:55], v[54:55], v[70:71] op_sel_hi:[1,0]
	v_cndmask_b32_e64 v51, 0, v191, s[0:1]
	v_fmac_f32_e32 v51, 0xbed49a78, v50
	v_exp_f32_e32 v50, v51
	v_cndmask_b32_e64 v51, 0, v190, s[0:1]
	v_mov_b32_e32 v52, v57
	v_pk_mul_f32 v[52:53], v[52:53], v[70:71] op_sel_hi:[1,0]
	v_ldexp_f32 v50, v50, v51
	v_mul_f32_e32 v50, v50, v67
	v_mul_f32_e32 v51, 0.15915494, v50
	v_rndne_f32_e32 v51, v51
	v_fmac_f32_e32 v50, 0xc0c90000, v51
	v_fmac_f32_e32 v50, 0xbafdaa22, v51
	v_mul_f32_e32 v50, 0.15915494, v50
	v_sin_f32_e32 v51, v50
	v_cos_f32_e32 v50, v50
	s_nop 0
	v_pk_mul_f32 v[60:61], v[50:51], v[54:55]
	s_nop 0
	v_sub_f32_e32 v56, v60, v61
	v_mov_b32_e32 v60, v51
	v_mov_b32_e32 v61, v50
	v_pk_mul_f32 v[50:51], v[60:61], v[54:55]
	s_nop 0
	v_add_f32_e32 v60, v50, v51
	v_cvt_f32_ubyte0_e32 v50, v143
	v_mul_f32_e32 v51, 0xbed49a78, v50
	v_cmp_gt_f32_e64 s[0:1], s4, v51
	s_nop 1
	v_cndmask_b32_e64 v51, 0, v191, s[0:1]
	v_fmac_f32_e32 v51, 0xbed49a78, v50
	v_exp_f32_e32 v50, v51
	v_cndmask_b32_e64 v51, 0, v190, s[0:1]
	v_ldexp_f32 v50, v50, v51
	v_mul_f32_e32 v50, v50, v67
	v_mul_f32_e32 v51, 0.15915494, v50
	v_rndne_f32_e32 v51, v51
	v_fmac_f32_e32 v50, 0xc0c90000, v51
	v_fmac_f32_e32 v50, 0xbafdaa22, v51
	v_mul_f32_e32 v50, 0.15915494, v50
	v_sin_f32_e32 v51, v50
	v_cos_f32_e32 v50, v50
	s_nop 0
	v_pk_mul_f32 v[54:55], v[50:51], v[52:53]
	s_nop 0
	v_sub_f32_e32 v57, v54, v55
	v_mov_b32_e32 v54, v51
	v_mov_b32_e32 v55, v50
	v_pk_mul_f32 v[50:51], v[54:55], v[52:53]
	s_nop 0
	v_add_f32_e32 v52, v50, v51
	v_cvt_pk_bf16_f32 v50, v71, v63
	v_cvt_pk_bf16_f32 v51, v56, v57
	global_store_dwordx2 v[58:59], v[50:51], off offset:288
	v_cvt_pk_bf16_f32 v50, v62, v64
	v_cvt_pk_bf16_f32 v51, v60, v52
	global_store_dwordx2 v[58:59], v[50:51], off offset:352
.LBB0_775:
	s_or_saveexec_b64 s[0:1], s[6:7]
	v_ashrrev_i32_e32 v67, 31, v66
	s_xor_b64 exec, exec, s[0:1]
	s_cbranch_execz .LBB0_777
	v_lshl_add_u64 v[72:73], v[66:67], 1, v[72:73]
	v_lshl_add_u64 v[72:73], v[72:73], 0, v[32:33]
	v_mul_f32_e32 v62, v62, v70
	v_mul_f32_e32 v63, v63, v70
	v_mul_f32_e32 v58, v58, v70
	v_mul_f32_e32 v59, v59, v70
	v_mul_f32_e32 v54, v54, v70
	v_mul_f32_e32 v55, v55, v70
	v_mul_f32_e32 v50, v50, v70
	v_mul_f32_e32 v51, v51, v70
	v_mul_f32_e32 v64, v64, v70
	v_mul_f32_e32 v65, v65, v70
	v_cvt_pk_bf16_f32 v62, v62, v63
	v_cvt_pk_bf16_f32 v63, v64, v65
	global_store_dwordx2 v[72:73], v[62:63], off
	v_mul_f32_e32 v60, v60, v70
	v_mul_f32_e32 v61, v61, v70
	v_cvt_pk_bf16_f32 v58, v58, v59
	v_cvt_pk_bf16_f32 v59, v60, v61
	global_store_dwordx2 v[72:73], v[58:59], off offset:32
	v_mul_f32_e32 v56, v56, v70
	v_mul_f32_e32 v57, v57, v70
	v_cvt_pk_bf16_f32 v54, v54, v55
	v_cvt_pk_bf16_f32 v55, v56, v57
	global_store_dwordx2 v[72:73], v[54:55], off offset:64
	v_mul_f32_e32 v52, v52, v70
	v_mul_f32_e32 v53, v53, v70
	v_cvt_pk_bf16_f32 v50, v50, v51
	v_cvt_pk_bf16_f32 v51, v52, v53
	global_store_dwordx2 v[72:73], v[50:51], off offset:96
; DEVI int RSI(int row) { return ((row >> 3) << 5) | (row & 7); }
; DEVI void rope_cs(int pos, int i, float& c, float& s) {
;   float fr = exp2f(-(float)i * (13.287712379549449f / 32.f));
;   float a = (float)pos * fr;
;   float n = rintf(a * 0.15915494309189535f);
;   float r = fmaf(-n, 6.28125f, a);
;   r = fmaf(-n, 0.0019353071795864769f, r);
;   s = __sinf(r); c = __cosf(r);
; DEVI void run_phase(const int ph, const Params& P, char* shmc, const int wave_u) {
;     ...
;             const float sc = rsqrtf(ssq[RSI(col)] * (1.f / 512) + EPS) * MLA_C;
;             bf16* qrow = qm + (long)col * 1536 + h * 192;
;             if (c0 < 128) {
; #pragma unroll
;               for (int m = 0; m < 4; ++m) { const f32x4 v = acc[ai][bj][m][n];
;                 st_bf4(qrow + c0 + m * 16 + fq * 4, v[0] * sc, v[1] * sc, v[2] * sc, v[3] * sc); }
;               __builtin_amdgcn_sched_barrier(0);
;             } else {
;               const int s = col - MP; const int pos = samp ? PAST + (s & 31) : (col & (SEQ - 1));
; #pragma unroll
;               for (int pr = 0; pr < 2; ++pr) {
;                 const f32x4 x1 = acc[ai][bj][2 * pr][n], x2 = acc[ai][bj][2 * pr + 1][n];
;                 float y1[4], y2[4];
; #pragma unroll
;                 for (int j = 0; j < 4; ++j) { const int i = pr * 16 + fq * 4 + j; float c, sn; rope_cs(pos, i, c, sn);
;                   const float a = x1[j] * sc, b = x2[j] * sc; y1[j] = a * c - b * sn; y2[j] = a * sn + b * c; }
;                 const int i0 = pr * 16 + fq * 4;
;                 st_bf4(qrow + 128 + i0, y1[0], y1[1], y1[2], y1[3]); st_bf4(qrow + 160 + i0, y2[0], y2[1], y2[2], y2[3]);
;                 __builtin_amdgcn_sched_barrier(0);
.LBB0_777:
	s_or_b64 exec, exec, s[0:1]
	global_load_dword v50, v[114:115], off
	s_mov_b32 s0, 0x800000
	v_lshl_add_u64 v[52:53], v[68:69], 0, v[116:117]
	s_waitcnt vmcnt(0) lgkmcnt(0)
	v_fmamk_f32 v50, v50, 0x3b000000, v186
	v_mul_f32_e32 v51, 0x4b800000, v50
	v_cmp_gt_f32_e64 s[0:1], s0, v50
	s_nop 1
	v_cndmask_b32_e64 v50, v50, v51, s[0:1]
	v_rsq_f32_e32 v50, v50
	s_nop 0
	v_mul_f32_e32 v51, 0x45800000, v50
	v_cndmask_b32_e64 v50, v50, v51, s[0:1]
	v_mul_f32_e32 v50, 0x3dd53b94, v50
	s_and_saveexec_b64 s[0:1], vcc
	s_xor_b64 s[6:7], exec, s[0:1]
	s_cbranch_execz .LBB0_779
	v_mul_f32_e32 v54, 0xbed49a78, v150
	s_mov_b32 s4, 0xc2fc0000
	v_cmp_gt_f32_e64 s[0:1], s4, v54
	v_cvt_f32_u32_e32 v51, v119
	v_mov_b32_e32 v57, v42
	v_cndmask_b32_e64 v55, 0, v191, s[0:1]
	v_fmac_f32_e32 v55, 0xbed49a78, v150
	v_exp_f32_e32 v55, v55
	v_cvt_f32_ubyte0_e32 v42, v149
	v_cndmask_b32_e64 v54, 0, v190, s[0:1]
	v_mov_b32_e32 v56, v46
	v_mul_f32_e32 v46, 0xbed49a78, v42
	v_ldexp_f32 v54, v55, v54
	v_cmp_gt_f32_e64 s[0:1], s4, v46
	v_mul_f32_e32 v54, v54, v51
	v_mul_f32_e32 v55, 0.15915494, v54
	v_cndmask_b32_e64 v46, 0, v191, s[0:1]
	v_fmac_f32_e32 v46, 0xbed49a78, v42
	v_rndne_f32_e32 v55, v55
	v_exp_f32_e32 v42, v46
	v_fmac_f32_e32 v54, 0xc0c90000, v55
	v_fmac_f32_e32 v54, 0xbafdaa22, v55
	v_mul_f32_e32 v54, 0.15915494, v54
	v_cndmask_b32_e64 v46, 0, v190, s[0:1]
	v_sin_f32_e32 v55, v54
	v_cos_f32_e32 v54, v54
	v_ldexp_f32 v42, v42, v46
	v_mul_f32_e32 v42, v42, v51
	v_mul_f32_e32 v46, 0.15915494, v42
	v_pk_mul_f32 v[56:57], v[56:57], v[50:51] op_sel_hi:[1,0]
	v_rndne_f32_e32 v46, v46
	v_pk_mul_f32 v[58:59], v[54:55], v[56:57]
	v_fmac_f32_e32 v42, 0xc0c90000, v46
	v_sub_f32_e32 v60, v58, v59
	v_mov_b32_e32 v58, v55
	v_mov_b32_e32 v59, v54
	v_fmac_f32_e32 v42, 0xbafdaa22, v46
	v_pk_mul_f32 v[54:55], v[58:59], v[56:57]
	v_mul_f32_e32 v42, 0.15915494, v42
	v_add_f32_e32 v56, v54, v55
	v_sin_f32_e32 v55, v42
	v_cos_f32_e32 v54, v42
	v_mov_b32_e32 v42, v47
	v_pk_mul_f32 v[42:43], v[42:43], v[50:51] op_sel_hi:[1,0]
	s_nop 0
	v_pk_mul_f32 v[46:47], v[54:55], v[42:43]
	s_nop 0
	v_sub_f32_e32 v57, v46, v47
	v_mov_b32_e32 v46, v55
	v_mov_b32_e32 v47, v54
	v_pk_mul_f32 v[42:43], v[46:47], v[42:43]
	v_mov_b32_e32 v46, v48
	v_add_f32_e32 v58, v42, v43
	v_cvt_f32_ubyte0_e32 v42, v148
	v_mul_f32_e32 v43, 0xbed49a78, v42
	v_cmp_gt_f32_e64 s[0:1], s4, v43
	v_mov_b32_e32 v47, v44
	v_pk_mul_f32 v[46:47], v[46:47], v[50:51] op_sel_hi:[1,0]
	v_cndmask_b32_e64 v43, 0, v191, s[0:1]
	v_fmac_f32_e32 v43, 0xbed49a78, v42
	v_exp_f32_e32 v42, v43
	v_cndmask_b32_e64 v43, 0, v190, s[0:1]
	v_mov_b32_e32 v44, v49
	v_pk_mul_f32 v[44:45], v[44:45], v[50:51] op_sel_hi:[1,0]
	v_ldexp_f32 v42, v42, v43
	v_mul_f32_e32 v42, v42, v51
	v_mul_f32_e32 v43, 0.15915494, v42
	v_rndne_f32_e32 v43, v43
	v_fmac_f32_e32 v42, 0xc0c90000, v43
	v_fmac_f32_e32 v42, 0xbafdaa22, v43
	v_mul_f32_e32 v42, 0.15915494, v42
	v_sin_f32_e32 v43, v42
	v_cos_f32_e32 v42, v42
	s_nop 0
	v_pk_mul_f32 v[54:55], v[42:43], v[46:47]
	s_nop 0
	v_sub_f32_e32 v48, v54, v55
	v_mov_b32_e32 v54, v43
	v_mov_b32_e32 v55, v42
	v_pk_mul_f32 v[42:43], v[54:55], v[46:47]
	s_nop 0
	v_add_f32_e32 v54, v42, v43
	v_cvt_f32_ubyte0_e32 v42, v145
	v_mul_f32_e32 v43, 0xbed49a78, v42
	v_cmp_gt_f32_e64 s[0:1], s4, v43
	s_nop 1
	v_cndmask_b32_e64 v43, 0, v191, s[0:1]
	v_fmac_f32_e32 v43, 0xbed49a78, v42
	v_exp_f32_e32 v42, v43
	v_cndmask_b32_e64 v43, 0, v190, s[0:1]
	v_ldexp_f32 v42, v42, v43
	v_mul_f32_e32 v42, v42, v51
	v_mul_f32_e32 v43, 0.15915494, v42
	v_rndne_f32_e32 v43, v43
	v_fmac_f32_e32 v42, 0xc0c90000, v43
	v_fmac_f32_e32 v42, 0xbafdaa22, v43
	v_mul_f32_e32 v42, 0.15915494, v42
	v_sin_f32_e32 v43, v42
	v_cos_f32_e32 v42, v42
	s_nop 0
	v_pk_mul_f32 v[46:47], v[42:43], v[44:45]
	s_nop 0
	v_sub_f32_e32 v49, v46, v47
	v_mov_b32_e32 v46, v43
	v_mov_b32_e32 v47, v42
	v_pk_mul_f32 v[42:43], v[46:47], v[44:45]
	v_cvt_pk_bf16_f32 v44, v60, v57
	v_cvt_pk_bf16_f32 v45, v48, v49
	s_nop 0
	v_add_f32_e32 v46, v42, v43
	v_lshl_add_u64 v[42:43], v[52:53], 0, v[32:33]
	global_store_dwordx2 v[42:43], v[44:45], off offset:256
	v_cvt_pk_bf16_f32 v44, v56, v58
	v_cvt_pk_bf16_f32 v45, v54, v46
	global_store_dwordx2 v[42:43], v[44:45], off offset:320
	v_cvt_f32_ubyte0_e32 v44, v144
	v_mul_f32_e32 v45, 0xbed49a78, v44
	v_cmp_gt_f32_e64 s[0:1], s4, v45
	v_mov_b32_e32 v47, v34
	v_cvt_f32_ubyte0_e32 v34, v142
	v_cndmask_b32_e64 v45, 0, v191, s[0:1]
	v_fmac_f32_e32 v45, 0xbed49a78, v44
	v_exp_f32_e32 v44, v45
	v_cndmask_b32_e64 v45, 0, v190, s[0:1]
	v_mov_b32_e32 v46, v38
	v_mul_f32_e32 v38, 0xbed49a78, v34
	v_ldexp_f32 v44, v44, v45
	v_cmp_gt_f32_e64 s[0:1], s4, v38
	v_mul_f32_e32 v44, v44, v51
	v_mul_f32_e32 v45, 0.15915494, v44
	v_cndmask_b32_e64 v38, 0, v191, s[0:1]
	v_fmac_f32_e32 v38, 0xbed49a78, v34
	v_rndne_f32_e32 v45, v45
	v_exp_f32_e32 v34, v38
	v_fmac_f32_e32 v44, 0xc0c90000, v45
	v_fmac_f32_e32 v44, 0xbafdaa22, v45
	v_mul_f32_e32 v44, 0.15915494, v44
	v_cndmask_b32_e64 v38, 0, v190, s[0:1]
	v_sin_f32_e32 v45, v44
	v_cos_f32_e32 v44, v44
	v_ldexp_f32 v34, v34, v38
	v_mul_f32_e32 v34, v34, v51
	v_mul_f32_e32 v38, 0.15915494, v34
	v_pk_mul_f32 v[46:47], v[46:47], v[50:51] op_sel_hi:[1,0]
	v_rndne_f32_e32 v38, v38
	v_pk_mul_f32 v[48:49], v[44:45], v[46:47]
	v_fmac_f32_e32 v34, 0xc0c90000, v38
	v_sub_f32_e32 v52, v48, v49
	v_mov_b32_e32 v48, v45
	v_mov_b32_e32 v49, v44
	v_fmac_f32_e32 v34, 0xbafdaa22, v38
	v_pk_mul_f32 v[44:45], v[48:49], v[46:47]
	v_mul_f32_e32 v34, 0.15915494, v34
	v_add_f32_e32 v46, v44, v45
	v_sin_f32_e32 v45, v34
	v_cos_f32_e32 v44, v34
	v_mov_b32_e32 v34, v39
	v_pk_mul_f32 v[34:35], v[34:35], v[50:51] op_sel_hi:[1,0]
	s_nop 0
; DEVI int RSI(int row) { return ((row >> 3) << 5) | (row & 7); }
; DEVI void rope_cs(int pos, int i, float& c, float& s) {
;   float fr = exp2f(-(float)i * (13.287712379549449f / 32.f));
;   float a = (float)pos * fr;
;   float n = rintf(a * 0.15915494309189535f);
;   float r = fmaf(-n, 6.28125f, a);
;   r = fmaf(-n, 0.0019353071795864769f, r);
;   s = __sinf(r); c = __cosf(r);
; DEVI void run_phase(const int ph, const Params& P, char* shmc, const int wave_u) {
;     ...
;             const float sc = rsqrtf(ssq[RSI(col)] * (1.f / 512) + EPS) * MLA_C;
;             bf16* qrow = qm + (long)col * 1536 + h * 192;
;             if (c0 < 128) {
; #pragma unroll
;               for (int m = 0; m < 4; ++m) { const f32x4 v = acc[ai][bj][m][n];
;                 st_bf4(qrow + c0 + m * 16 + fq * 4, v[0] * sc, v[1] * sc, v[2] * sc, v[3] * sc); }
;               __builtin_amdgcn_sched_barrier(0);
;             } else {
;               const int s = col - MP; const int pos = samp ? PAST + (s & 31) : (col & (SEQ - 1));
; #pragma unroll
;               for (int pr = 0; pr < 2; ++pr) {
;                 const f32x4 x1 = acc[ai][bj][2 * pr][n], x2 = acc[ai][bj][2 * pr + 1][n];
;                 float y1[4], y2[4];
; #pragma unroll
;                 for (int j = 0; j < 4; ++j) { const int i = pr * 16 + fq * 4 + j; float c, sn; rope_cs(pos, i, c, sn);
;                   const float a = x1[j] * sc, b = x2[j] * sc; y1[j] = a * c - b * sn; y2[j] = a * sn + b * c; }
;                 const int i0 = pr * 16 + fq * 4;
;                 st_bf4(qrow + 128 + i0, y1[0], y1[1], y1[2], y1[3]); st_bf4(qrow + 160 + i0, y2[0], y2[1], y2[2], y2[3]);
;                 __builtin_amdgcn_sched_barrier(0);
	v_pk_mul_f32 v[38:39], v[44:45], v[34:35]
	s_nop 0
	v_sub_f32_e32 v47, v38, v39
	v_mov_b32_e32 v38, v45
	v_mov_b32_e32 v39, v44
	v_pk_mul_f32 v[34:35], v[38:39], v[34:35]
	v_mov_b32_e32 v38, v40
	v_add_f32_e32 v48, v34, v35
	v_cvt_f32_ubyte0_e32 v34, v139
	v_mul_f32_e32 v35, 0xbed49a78, v34
	v_cmp_gt_f32_e64 s[0:1], s4, v35
	v_mov_b32_e32 v39, v36
	v_pk_mul_f32 v[38:39], v[38:39], v[50:51] op_sel_hi:[1,0]
	v_cndmask_b32_e64 v35, 0, v191, s[0:1]
	v_fmac_f32_e32 v35, 0xbed49a78, v34
	v_exp_f32_e32 v34, v35
	v_cndmask_b32_e64 v35, 0, v190, s[0:1]
	v_mov_b32_e32 v36, v41
	v_pk_mul_f32 v[36:37], v[36:37], v[50:51] op_sel_hi:[1,0]
	v_ldexp_f32 v34, v34, v35
	v_mul_f32_e32 v34, v34, v51
	v_mul_f32_e32 v35, 0.15915494, v34
	v_rndne_f32_e32 v35, v35
	v_fmac_f32_e32 v34, 0xc0c90000, v35
	v_fmac_f32_e32 v34, 0xbafdaa22, v35
	v_mul_f32_e32 v34, 0.15915494, v34
	v_sin_f32_e32 v35, v34
	v_cos_f32_e32 v34, v34
	s_nop 0
	v_pk_mul_f32 v[44:45], v[34:35], v[38:39]
	s_nop 0
	v_sub_f32_e32 v40, v44, v45
	v_mov_b32_e32 v44, v35
	v_mov_b32_e32 v45, v34
	v_pk_mul_f32 v[34:35], v[44:45], v[38:39]
	s_nop 0
	v_add_f32_e32 v44, v34, v35
	v_cvt_f32_ubyte0_e32 v34, v143
	v_mul_f32_e32 v35, 0xbed49a78, v34
	v_cmp_gt_f32_e64 s[0:1], s4, v35
	s_nop 1
	v_cndmask_b32_e64 v35, 0, v191, s[0:1]
	v_fmac_f32_e32 v35, 0xbed49a78, v34
	v_exp_f32_e32 v34, v35
	v_cndmask_b32_e64 v35, 0, v190, s[0:1]
	v_ldexp_f32 v34, v34, v35
	v_mul_f32_e32 v34, v34, v51
	v_mul_f32_e32 v35, 0.15915494, v34
	v_rndne_f32_e32 v35, v35
	v_fmac_f32_e32 v34, 0xc0c90000, v35
	v_fmac_f32_e32 v34, 0xbafdaa22, v35
	v_mul_f32_e32 v34, 0.15915494, v34
	v_sin_f32_e32 v35, v34
	v_cos_f32_e32 v34, v34
	s_nop 0
	v_pk_mul_f32 v[38:39], v[34:35], v[36:37]
	s_nop 0
	v_sub_f32_e32 v41, v38, v39
	v_mov_b32_e32 v38, v35
	v_mov_b32_e32 v39, v34
	v_pk_mul_f32 v[34:35], v[38:39], v[36:37]
	s_nop 0
	v_add_f32_e32 v36, v34, v35
	v_cvt_pk_bf16_f32 v34, v52, v47
	v_cvt_pk_bf16_f32 v35, v40, v41
	global_store_dwordx2 v[42:43], v[34:35], off offset:288
	v_cvt_pk_bf16_f32 v34, v46, v48
	v_cvt_pk_bf16_f32 v35, v44, v36
	global_store_dwordx2 v[42:43], v[34:35], off offset:352
.LBB0_779:
	s_andn2_saveexec_b64 s[0:1], s[6:7]
	s_cbranch_execz .LBB0_781
	v_lshl_add_u64 v[52:53], v[66:67], 1, v[52:53]
	v_lshl_add_u64 v[52:53], v[52:53], 0, v[32:33]
	v_mul_f32_e32 v46, v46, v50
	v_mul_f32_e32 v47, v47, v50
	v_mul_f32_e32 v42, v42, v50
	v_mul_f32_e32 v43, v43, v50
	v_mul_f32_e32 v38, v38, v50
	v_mul_f32_e32 v39, v39, v50
	v_mul_f32_e32 v34, v34, v50
	v_mul_f32_e32 v35, v35, v50
	v_mul_f32_e32 v48, v48, v50
	v_mul_f32_e32 v49, v49, v50
	v_cvt_pk_bf16_f32 v46, v46, v47
	v_cvt_pk_bf16_f32 v47, v48, v49
	global_store_dwordx2 v[52:53], v[46:47], off
	v_mul_f32_e32 v44, v44, v50
	v_mul_f32_e32 v45, v45, v50
	v_cvt_pk_bf16_f32 v42, v42, v43
	v_cvt_pk_bf16_f32 v43, v44, v45
	global_store_dwordx2 v[52:53], v[42:43], off offset:32
	v_mul_f32_e32 v40, v40, v50
	v_mul_f32_e32 v41, v41, v50
	v_cvt_pk_bf16_f32 v38, v38, v39
	v_cvt_pk_bf16_f32 v39, v40, v41
	global_store_dwordx2 v[52:53], v[38:39], off offset:64
	v_mul_f32_e32 v36, v36, v50
	v_mul_f32_e32 v37, v37, v50
	v_cvt_pk_bf16_f32 v34, v34, v35
	v_cvt_pk_bf16_f32 v35, v36, v37
	global_store_dwordx2 v[52:53], v[34:35], off offset:96
.LBB0_781:
	s_or_b64 exec, exec, s[0:1]
	global_load_dword v34, v[98:99], off
	s_mov_b32 s0, 0x800000
	v_lshl_add_u64 v[36:37], v[68:69], 0, v[100:101]
	s_waitcnt vmcnt(0) lgkmcnt(0)
	v_fmamk_f32 v34, v34, 0x3b000000, v186
	v_mul_f32_e32 v35, 0x4b800000, v34
	v_cmp_gt_f32_e64 s[0:1], s0, v34
	s_nop 1
	v_cndmask_b32_e64 v34, v34, v35, s[0:1]
	v_rsq_f32_e32 v34, v34
	s_nop 0
	v_mul_f32_e32 v35, 0x45800000, v34
	v_cndmask_b32_e64 v34, v34, v35, s[0:1]
	v_mul_f32_e32 v34, 0x3dd53b94, v34
	s_and_saveexec_b64 s[0:1], vcc
	s_xor_b64 s[6:7], exec, s[0:1]
	s_cbranch_execz .LBB0_783
	v_mul_f32_e32 v38, 0xbed49a78, v150
	s_mov_b32 s4, 0xc2fc0000
	v_cmp_gt_f32_e64 s[0:1], s4, v38
	v_cvt_f32_u32_e32 v35, v103
	v_mov_b32_e32 v41, v24
	v_cndmask_b32_e64 v39, 0, v191, s[0:1]
	v_fmac_f32_e32 v39, 0xbed49a78, v150
	v_exp_f32_e32 v39, v39
	v_cvt_f32_ubyte0_e32 v24, v149
	v_cndmask_b32_e64 v38, 0, v190, s[0:1]
	v_mov_b32_e32 v40, v28
	v_mul_f32_e32 v28, 0xbed49a78, v24
	v_ldexp_f32 v38, v39, v38
	v_cmp_gt_f32_e64 s[0:1], s4, v28
	v_mul_f32_e32 v38, v38, v35
	v_mul_f32_e32 v39, 0.15915494, v38
	v_cndmask_b32_e64 v28, 0, v191, s[0:1]
	v_fmac_f32_e32 v28, 0xbed49a78, v24
	v_rndne_f32_e32 v39, v39
	v_exp_f32_e32 v24, v28
	v_fmac_f32_e32 v38, 0xc0c90000, v39
	v_fmac_f32_e32 v38, 0xbafdaa22, v39
	v_mul_f32_e32 v38, 0.15915494, v38
	v_cndmask_b32_e64 v28, 0, v190, s[0:1]
	v_sin_f32_e32 v39, v38
	v_cos_f32_e32 v38, v38
	v_ldexp_f32 v24, v24, v28
	v_mul_f32_e32 v24, v24, v35
	v_mul_f32_e32 v28, 0.15915494, v24
	v_pk_mul_f32 v[40:41], v[40:41], v[34:35] op_sel_hi:[1,0]
	v_rndne_f32_e32 v28, v28
	v_pk_mul_f32 v[42:43], v[38:39], v[40:41]
	v_fmac_f32_e32 v24, 0xc0c90000, v28
	v_sub_f32_e32 v44, v42, v43
	v_mov_b32_e32 v42, v39
	v_mov_b32_e32 v43, v38
	v_fmac_f32_e32 v24, 0xbafdaa22, v28
	v_pk_mul_f32 v[38:39], v[42:43], v[40:41]
	v_mul_f32_e32 v24, 0.15915494, v24
	v_add_f32_e32 v40, v38, v39
	v_sin_f32_e32 v39, v24
	v_cos_f32_e32 v38, v24
	v_mov_b32_e32 v24, v29
	v_pk_mul_f32 v[24:25], v[24:25], v[34:35] op_sel_hi:[1,0]
	s_nop 0
	v_pk_mul_f32 v[28:29], v[38:39], v[24:25]
	s_nop 0
	v_sub_f32_e32 v41, v28, v29
	v_mov_b32_e32 v28, v39
	v_mov_b32_e32 v29, v38
	v_pk_mul_f32 v[24:25], v[28:29], v[24:25]
	v_mov_b32_e32 v28, v30
	v_add_f32_e32 v42, v24, v25
	v_cvt_f32_ubyte0_e32 v24, v148
	v_mul_f32_e32 v25, 0xbed49a78, v24
	v_cmp_gt_f32_e64 s[0:1], s4, v25
	v_mov_b32_e32 v29, v26
; DEVI void rope_cs(int pos, int i, float& c, float& s) {
;   float fr = exp2f(-(float)i * (13.287712379549449f / 32.f));
;   float a = (float)pos * fr;
;   float n = rintf(a * 0.15915494309189535f);
;   float r = fmaf(-n, 6.28125f, a);
;   r = fmaf(-n, 0.0019353071795864769f, r);
;   s = __sinf(r); c = __cosf(r);
; DEVI void run_phase(const int ph, const Params& P, char* shmc, const int wave_u) {
;     ...
;               const int s = col - MP; const int pos = samp ? PAST + (s & 31) : (col & (SEQ - 1));
; #pragma unroll
;               for (int pr = 0; pr < 2; ++pr) {
;                 const f32x4 x1 = acc[ai][bj][2 * pr][n], x2 = acc[ai][bj][2 * pr + 1][n];
;                 float y1[4], y2[4];
; #pragma unroll
;                 for (int j = 0; j < 4; ++j) { const int i = pr * 16 + fq * 4 + j; float c, sn; rope_cs(pos, i, c, sn);
;                   const float a = x1[j] * sc, b = x2[j] * sc; y1[j] = a * c - b * sn; y2[j] = a * sn + b * c; }
;                 const int i0 = pr * 16 + fq * 4;
;                 st_bf4(qrow + 128 + i0, y1[0], y1[1], y1[2], y1[3]); st_bf4(qrow + 160 + i0, y2[0], y2[1], y2[2], y2[3]);
;                 __builtin_amdgcn_sched_barrier(0);
	v_pk_mul_f32 v[28:29], v[28:29], v[34:35] op_sel_hi:[1,0]
	v_cndmask_b32_e64 v25, 0, v191, s[0:1]
	v_fmac_f32_e32 v25, 0xbed49a78, v24
	v_exp_f32_e32 v24, v25
	v_cndmask_b32_e64 v25, 0, v190, s[0:1]
	v_mov_b32_e32 v26, v31
	v_pk_mul_f32 v[26:27], v[26:27], v[34:35] op_sel_hi:[1,0]
	v_ldexp_f32 v24, v24, v25
	v_mul_f32_e32 v24, v24, v35
	v_mul_f32_e32 v25, 0.15915494, v24
	v_rndne_f32_e32 v25, v25
	v_fmac_f32_e32 v24, 0xc0c90000, v25
	v_fmac_f32_e32 v24, 0xbafdaa22, v25
	v_mul_f32_e32 v24, 0.15915494, v24
	v_sin_f32_e32 v25, v24
	v_cos_f32_e32 v24, v24
	s_nop 0
	v_pk_mul_f32 v[38:39], v[24:25], v[28:29]
	s_nop 0
	v_sub_f32_e32 v30, v38, v39
	v_mov_b32_e32 v38, v25
	v_mov_b32_e32 v39, v24
	v_pk_mul_f32 v[24:25], v[38:39], v[28:29]
	s_nop 0
	v_add_f32_e32 v38, v24, v25
	v_cvt_f32_ubyte0_e32 v24, v145
	v_mul_f32_e32 v25, 0xbed49a78, v24
	v_cmp_gt_f32_e64 s[0:1], s4, v25
	s_nop 1
	v_cndmask_b32_e64 v25, 0, v191, s[0:1]
	v_fmac_f32_e32 v25, 0xbed49a78, v24
	v_exp_f32_e32 v24, v25
	v_cndmask_b32_e64 v25, 0, v190, s[0:1]
	v_ldexp_f32 v24, v24, v25
	v_mul_f32_e32 v24, v24, v35
	v_mul_f32_e32 v25, 0.15915494, v24
	v_rndne_f32_e32 v25, v25
	v_fmac_f32_e32 v24, 0xc0c90000, v25
	v_fmac_f32_e32 v24, 0xbafdaa22, v25
	v_mul_f32_e32 v24, 0.15915494, v24
	v_sin_f32_e32 v25, v24
	v_cos_f32_e32 v24, v24
	s_nop 0
	v_pk_mul_f32 v[28:29], v[24:25], v[26:27]
	s_nop 0
	v_sub_f32_e32 v31, v28, v29
	v_mov_b32_e32 v28, v25
	v_mov_b32_e32 v29, v24
	v_pk_mul_f32 v[24:25], v[28:29], v[26:27]
	v_cvt_pk_bf16_f32 v26, v44, v41
	v_cvt_pk_bf16_f32 v27, v30, v31
	s_nop 0
	v_add_f32_e32 v28, v24, v25
	v_lshl_add_u64 v[24:25], v[36:37], 0, v[32:33]
	global_store_dwordx2 v[24:25], v[26:27], off offset:256
	v_cvt_pk_bf16_f32 v26, v40, v42
	v_cvt_pk_bf16_f32 v27, v38, v28
	global_store_dwordx2 v[24:25], v[26:27], off offset:320
	v_cvt_f32_ubyte0_e32 v26, v144
	v_mul_f32_e32 v27, 0xbed49a78, v26
	v_cmp_gt_f32_e64 s[0:1], s4, v27
	v_mov_b32_e32 v29, v16
	v_cvt_f32_ubyte0_e32 v16, v142
	v_cndmask_b32_e64 v27, 0, v191, s[0:1]
	v_fmac_f32_e32 v27, 0xbed49a78, v26
	v_exp_f32_e32 v26, v27
	v_cndmask_b32_e64 v27, 0, v190, s[0:1]
	v_mov_b32_e32 v28, v20
	v_mul_f32_e32 v20, 0xbed49a78, v16
	v_ldexp_f32 v26, v26, v27
	v_cmp_gt_f32_e64 s[0:1], s4, v20
	v_mul_f32_e32 v26, v26, v35
	v_mul_f32_e32 v27, 0.15915494, v26
	v_cndmask_b32_e64 v20, 0, v191, s[0:1]
	v_fmac_f32_e32 v20, 0xbed49a78, v16
	v_rndne_f32_e32 v27, v27
	v_exp_f32_e32 v16, v20
	v_fmac_f32_e32 v26, 0xc0c90000, v27
	v_fmac_f32_e32 v26, 0xbafdaa22, v27
	v_mul_f32_e32 v26, 0.15915494, v26
	v_cndmask_b32_e64 v20, 0, v190, s[0:1]
	v_sin_f32_e32 v27, v26
	v_cos_f32_e32 v26, v26
	v_ldexp_f32 v16, v16, v20
	v_mul_f32_e32 v16, v16, v35
	v_mul_f32_e32 v20, 0.15915494, v16
	v_pk_mul_f32 v[28:29], v[28:29], v[34:35] op_sel_hi:[1,0]
	v_rndne_f32_e32 v20, v20
	v_pk_mul_f32 v[30:31], v[26:27], v[28:29]
	v_fmac_f32_e32 v16, 0xc0c90000, v20
	v_sub_f32_e32 v36, v30, v31
	v_mov_b32_e32 v30, v27
	v_mov_b32_e32 v31, v26
	v_fmac_f32_e32 v16, 0xbafdaa22, v20
	v_pk_mul_f32 v[26:27], v[30:31], v[28:29]
	v_mul_f32_e32 v16, 0.15915494, v16
	v_add_f32_e32 v28, v26, v27
	v_sin_f32_e32 v27, v16
	v_cos_f32_e32 v26, v16
	v_mov_b32_e32 v16, v21
	v_pk_mul_f32 v[16:17], v[16:17], v[34:35] op_sel_hi:[1,0]
	s_nop 0
	v_pk_mul_f32 v[20:21], v[26:27], v[16:17]
	s_nop 0
	v_sub_f32_e32 v29, v20, v21
	v_mov_b32_e32 v20, v27
	v_mov_b32_e32 v21, v26
	v_pk_mul_f32 v[16:17], v[20:21], v[16:17]
	v_mov_b32_e32 v20, v22
	v_add_f32_e32 v30, v16, v17
	v_cvt_f32_ubyte0_e32 v16, v139
	v_mul_f32_e32 v17, 0xbed49a78, v16
	v_cmp_gt_f32_e64 s[0:1], s4, v17
	v_mov_b32_e32 v21, v18
	v_pk_mul_f32 v[20:21], v[20:21], v[34:35] op_sel_hi:[1,0]
	v_cndmask_b32_e64 v17, 0, v191, s[0:1]
	v_fmac_f32_e32 v17, 0xbed49a78, v16
	v_exp_f32_e32 v16, v17
	v_cndmask_b32_e64 v17, 0, v190, s[0:1]
	v_mov_b32_e32 v18, v23
	v_pk_mul_f32 v[18:19], v[18:19], v[34:35] op_sel_hi:[1,0]
	v_ldexp_f32 v16, v16, v17
	v_mul_f32_e32 v16, v16, v35
	v_mul_f32_e32 v17, 0.15915494, v16
	v_rndne_f32_e32 v17, v17
	v_fmac_f32_e32 v16, 0xc0c90000, v17
	v_fmac_f32_e32 v16, 0xbafdaa22, v17
	v_mul_f32_e32 v16, 0.15915494, v16
	v_sin_f32_e32 v17, v16
	v_cos_f32_e32 v16, v16
	s_nop 0
	v_pk_mul_f32 v[26:27], v[16:17], v[20:21]
	s_nop 0
	v_sub_f32_e32 v22, v26, v27
	v_mov_b32_e32 v26, v17
	v_mov_b32_e32 v27, v16
	v_pk_mul_f32 v[16:17], v[26:27], v[20:21]
	s_nop 0
	v_add_f32_e32 v26, v16, v17
	v_cvt_f32_ubyte0_e32 v16, v143
	v_mul_f32_e32 v17, 0xbed49a78, v16
	v_cmp_gt_f32_e64 s[0:1], s4, v17
	s_nop 1
	v_cndmask_b32_e64 v17, 0, v191, s[0:1]
	v_fmac_f32_e32 v17, 0xbed49a78, v16
	v_exp_f32_e32 v16, v17
	v_cndmask_b32_e64 v17, 0, v190, s[0:1]
	v_ldexp_f32 v16, v16, v17
	v_mul_f32_e32 v16, v16, v35
	v_mul_f32_e32 v17, 0.15915494, v16
	v_rndne_f32_e32 v17, v17
	v_fmac_f32_e32 v16, 0xc0c90000, v17
	v_fmac_f32_e32 v16, 0xbafdaa22, v17
	v_mul_f32_e32 v16, 0.15915494, v16
	v_sin_f32_e32 v17, v16
	v_cos_f32_e32 v16, v16
	s_nop 0
	v_pk_mul_f32 v[20:21], v[16:17], v[18:19]
	s_nop 0
	v_sub_f32_e32 v23, v20, v21
	v_mov_b32_e32 v20, v17
	v_mov_b32_e32 v21, v16
	v_pk_mul_f32 v[16:17], v[20:21], v[18:19]
	s_nop 0
	v_add_f32_e32 v18, v16, v17
	v_cvt_pk_bf16_f32 v16, v36, v29
	v_cvt_pk_bf16_f32 v17, v22, v23
	global_store_dwordx2 v[24:25], v[16:17], off offset:288
	v_cvt_pk_bf16_f32 v16, v28, v30
	v_cvt_pk_bf16_f32 v17, v26, v18
	global_store_dwordx2 v[24:25], v[16:17], off offset:352
; DEVI int RSI(int row) { return ((row >> 3) << 5) | (row & 7); }
; DEVI void rope_cs(int pos, int i, float& c, float& s) {
;   float fr = exp2f(-(float)i * (13.287712379549449f / 32.f));
;   float a = (float)pos * fr;
;   float n = rintf(a * 0.15915494309189535f);
;   float r = fmaf(-n, 6.28125f, a);
;   r = fmaf(-n, 0.0019353071795864769f, r);
;   s = __sinf(r); c = __cosf(r);
; DEVI void run_phase(const int ph, const Params& P, char* shmc, const int wave_u) {
;     ...
;             const float sc = rsqrtf(ssq[RSI(col)] * (1.f / 512) + EPS) * MLA_C;
;             bf16* qrow = qm + (long)col * 1536 + h * 192;
;             if (c0 < 128) {
; #pragma unroll
;               for (int m = 0; m < 4; ++m) { const f32x4 v = acc[ai][bj][m][n];
;                 st_bf4(qrow + c0 + m * 16 + fq * 4, v[0] * sc, v[1] * sc, v[2] * sc, v[3] * sc); }
;               __builtin_amdgcn_sched_barrier(0);
;             } else {
;               const int s = col - MP; const int pos = samp ? PAST + (s & 31) : (col & (SEQ - 1));
; #pragma unroll
;               for (int pr = 0; pr < 2; ++pr) {
;                 const f32x4 x1 = acc[ai][bj][2 * pr][n], x2 = acc[ai][bj][2 * pr + 1][n];
;                 float y1[4], y2[4];
; #pragma unroll
;                 for (int j = 0; j < 4; ++j) { const int i = pr * 16 + fq * 4 + j; float c, sn; rope_cs(pos, i, c, sn);
;                   const float a = x1[j] * sc, b = x2[j] * sc; y1[j] = a * c - b * sn; y2[j] = a * sn + b * c; }
;                 const int i0 = pr * 16 + fq * 4;
;                 st_bf4(qrow + 128 + i0, y1[0], y1[1], y1[2], y1[3]); st_bf4(qrow + 160 + i0, y2[0], y2[1], y2[2], y2[3]);
;                 __builtin_amdgcn_sched_barrier(0);
.LBB0_783:
	s_andn2_saveexec_b64 s[0:1], s[6:7]
	s_cbranch_execz .LBB0_785
	v_lshl_add_u64 v[36:37], v[66:67], 1, v[36:37]
	v_lshl_add_u64 v[36:37], v[36:37], 0, v[32:33]
	v_mul_f32_e32 v28, v28, v34
	v_mul_f32_e32 v29, v29, v34
	v_mul_f32_e32 v24, v24, v34
	v_mul_f32_e32 v25, v25, v34
	v_mul_f32_e32 v20, v20, v34
	v_mul_f32_e32 v21, v21, v34
	v_mul_f32_e32 v16, v16, v34
	v_mul_f32_e32 v17, v17, v34
	v_mul_f32_e32 v30, v30, v34
	v_mul_f32_e32 v31, v31, v34
	v_cvt_pk_bf16_f32 v28, v28, v29
	v_cvt_pk_bf16_f32 v29, v30, v31
	global_store_dwordx2 v[36:37], v[28:29], off
	v_mul_f32_e32 v26, v26, v34
	v_mul_f32_e32 v27, v27, v34
	v_cvt_pk_bf16_f32 v24, v24, v25
	v_cvt_pk_bf16_f32 v25, v26, v27
	global_store_dwordx2 v[36:37], v[24:25], off offset:32
	v_mul_f32_e32 v22, v22, v34
	v_mul_f32_e32 v23, v23, v34
	v_cvt_pk_bf16_f32 v20, v20, v21
	v_cvt_pk_bf16_f32 v21, v22, v23
	global_store_dwordx2 v[36:37], v[20:21], off offset:64
	v_mul_f32_e32 v18, v18, v34
	v_mul_f32_e32 v19, v19, v34
	v_cvt_pk_bf16_f32 v16, v16, v17
	v_cvt_pk_bf16_f32 v17, v18, v19
	global_store_dwordx2 v[36:37], v[16:17], off offset:96
.LBB0_785:
	s_or_b64 exec, exec, s[0:1]
	global_load_dword v16, v[84:85], off
	s_mov_b32 s0, 0x800000
	v_lshl_add_u64 v[18:19], v[68:69], 0, v[82:83]
	s_waitcnt vmcnt(0) lgkmcnt(0)
	v_fmamk_f32 v16, v16, 0x3b000000, v186
	v_mul_f32_e32 v17, 0x4b800000, v16
	v_cmp_gt_f32_e64 s[0:1], s0, v16
	s_nop 1
	v_cndmask_b32_e64 v16, v16, v17, s[0:1]
	v_rsq_f32_e32 v16, v16
	s_nop 0
	v_mul_f32_e32 v17, 0x45800000, v16
	v_cndmask_b32_e64 v16, v16, v17, s[0:1]
	v_mul_f32_e32 v16, 0x3dd53b94, v16
	s_and_saveexec_b64 s[0:1], vcc
	s_xor_b64 s[0:1], exec, s[0:1]
	s_cbranch_execz .LBB0_787
	v_mul_f32_e32 v17, 0xbed49a78, v150
	s_mov_b32 s4, 0xc2fc0000
	v_cmp_gt_f32_e32 vcc, s4, v17
	v_cvt_f32_u32_e32 v26, v87
	v_mov_b32_e32 v23, v8
	v_cndmask_b32_e32 v20, 0, v191, vcc
	v_fmac_f32_e32 v20, 0xbed49a78, v150
	v_exp_f32_e32 v20, v20
	v_cndmask_b32_e32 v17, 0, v190, vcc
	v_cvt_f32_ubyte0_e32 v8, v149
	v_mov_b32_e32 v22, v12
	v_ldexp_f32 v17, v20, v17
	v_mul_f32_e32 v12, 0xbed49a78, v8
	v_mul_f32_e32 v17, v17, v26
	v_cmp_gt_f32_e32 vcc, s4, v12
	v_mul_f32_e32 v20, 0.15915494, v17
	v_rndne_f32_e32 v20, v20
	v_cndmask_b32_e32 v12, 0, v191, vcc
	v_fmac_f32_e32 v12, 0xbed49a78, v8
	v_fmac_f32_e32 v17, 0xc0c90000, v20
	v_exp_f32_e32 v8, v12
	v_fmac_f32_e32 v17, 0xbafdaa22, v20
	v_mul_f32_e32 v17, 0.15915494, v17
	v_sin_f32_e32 v21, v17
	v_cos_f32_e32 v20, v17
	v_cndmask_b32_e32 v12, 0, v190, vcc
	v_ldexp_f32 v8, v8, v12
	v_mul_f32_e32 v8, v8, v26
	v_pk_mul_f32 v[22:23], v[22:23], v[16:17] op_sel_hi:[1,0]
	v_mul_f32_e32 v12, 0.15915494, v8
	v_pk_mul_f32 v[24:25], v[20:21], v[22:23]
	v_rndne_f32_e32 v12, v12
	v_sub_f32_e32 v17, v24, v25
	v_mov_b32_e32 v24, v21
	v_mov_b32_e32 v25, v20
	v_fmac_f32_e32 v8, 0xc0c90000, v12
	v_pk_mul_f32 v[20:21], v[24:25], v[22:23]
	v_fmac_f32_e32 v8, 0xbafdaa22, v12
	v_mul_f32_e32 v8, 0.15915494, v8
	v_add_f32_e32 v24, v20, v21
	v_cvt_f32_ubyte0_e32 v20, v148
	v_sin_f32_e32 v23, v8
	v_cos_f32_e32 v22, v8
	v_mul_f32_e32 v21, 0xbed49a78, v20
	v_cmp_gt_f32_e32 vcc, s4, v21
	v_mov_b32_e32 v8, v13
	v_pk_mul_f32 v[8:9], v[8:9], v[16:17] op_sel_hi:[1,0]
	v_cndmask_b32_e32 v21, 0, v191, vcc
	v_fmac_f32_e32 v21, 0xbed49a78, v20
	v_pk_mul_f32 v[12:13], v[22:23], v[8:9]
	v_exp_f32_e32 v20, v21
	v_sub_f32_e32 v25, v12, v13
	v_mov_b32_e32 v12, v23
	v_mov_b32_e32 v13, v22
	v_pk_mul_f32 v[8:9], v[12:13], v[8:9]
	v_mov_b32_e32 v12, v14
	v_add_f32_e32 v22, v8, v9
	v_cndmask_b32_e32 v8, 0, v190, vcc
	v_ldexp_f32 v8, v20, v8
	v_mul_f32_e32 v8, v8, v26
	v_mul_f32_e32 v9, 0.15915494, v8
	v_rndne_f32_e32 v9, v9
	v_fmac_f32_e32 v8, 0xc0c90000, v9
	v_fmac_f32_e32 v8, 0xbafdaa22, v9
	v_mul_f32_e32 v8, 0.15915494, v8
	v_sin_f32_e32 v9, v8
	v_cos_f32_e32 v8, v8
	v_mov_b32_e32 v13, v10
	v_pk_mul_f32 v[12:13], v[12:13], v[16:17] op_sel_hi:[1,0]
	s_nop 0
	v_pk_mul_f32 v[20:21], v[8:9], v[12:13]
	s_nop 0
	v_sub_f32_e32 v14, v20, v21
	v_mov_b32_e32 v20, v9
	v_cvt_f32_ubyte0_e32 v9, v145
	v_mul_f32_e32 v10, 0xbed49a78, v9
	v_cmp_gt_f32_e32 vcc, s4, v10
	v_mov_b32_e32 v21, v8
	s_nop 0
	v_cndmask_b32_e32 v10, 0, v191, vcc
	v_fmac_f32_e32 v10, 0xbed49a78, v9
	v_exp_f32_e32 v10, v10
	v_pk_mul_f32 v[8:9], v[20:21], v[12:13]
	v_cndmask_b32_e32 v12, 0, v190, vcc
	v_add_f32_e32 v20, v8, v9
	v_ldexp_f32 v10, v10, v12
	v_mul_f32_e32 v10, v10, v26
	v_mul_f32_e32 v12, 0.15915494, v10
	v_rndne_f32_e32 v12, v12
	v_fmac_f32_e32 v10, 0xc0c90000, v12
	v_fmac_f32_e32 v10, 0xbafdaa22, v12
	v_mul_f32_e32 v10, 0.15915494, v10
	v_sin_f32_e32 v13, v10
	v_cos_f32_e32 v12, v10
	v_mov_b32_e32 v10, v15
	v_pk_mul_f32 v[8:9], v[10:11], v[16:17] op_sel_hi:[1,0]
	s_nop 0
	v_pk_mul_f32 v[10:11], v[12:13], v[8:9]
	s_nop 0
	v_sub_f32_e32 v15, v10, v11
	v_mov_b32_e32 v10, v13
; DEVI void rope_cs(int pos, int i, float& c, float& s) {
;   float fr = exp2f(-(float)i * (13.287712379549449f / 32.f));
;   float a = (float)pos * fr;
;   float n = rintf(a * 0.15915494309189535f);
;   float r = fmaf(-n, 6.28125f, a);
;   r = fmaf(-n, 0.0019353071795864769f, r);
;   s = __sinf(r); c = __cosf(r);
; DEVI void run_phase(const int ph, const Params& P, char* shmc, const int wave_u) {
;     ...
;             if (c0 < 128) {
; #pragma unroll
;               for (int m = 0; m < 4; ++m) { const f32x4 v = acc[ai][bj][m][n];
;                 st_bf4(qrow + c0 + m * 16 + fq * 4, v[0] * sc, v[1] * sc, v[2] * sc, v[3] * sc); }
;               __builtin_amdgcn_sched_barrier(0);
;             } else {
;               const int s = col - MP; const int pos = samp ? PAST + (s & 31) : (col & (SEQ - 1));
; #pragma unroll
;               for (int pr = 0; pr < 2; ++pr) {
;                 const f32x4 x1 = acc[ai][bj][2 * pr][n], x2 = acc[ai][bj][2 * pr + 1][n];
;                 float y1[4], y2[4];
; #pragma unroll
;                 for (int j = 0; j < 4; ++j) { const int i = pr * 16 + fq * 4 + j; float c, sn; rope_cs(pos, i, c, sn);
;                   const float a = x1[j] * sc, b = x2[j] * sc; y1[j] = a * c - b * sn; y2[j] = a * sn + b * c; }
;                 const int i0 = pr * 16 + fq * 4;
;                 st_bf4(qrow + 128 + i0, y1[0], y1[1], y1[2], y1[3]); st_bf4(qrow + 160 + i0, y2[0], y2[1], y2[2], y2[3]);
;                 __builtin_amdgcn_sched_barrier(0);
	v_mov_b32_e32 v11, v12
	v_pk_mul_f32 v[8:9], v[10:11], v[8:9]
	v_cvt_pk_bf16_f32 v10, v17, v25
	v_cvt_pk_bf16_f32 v11, v14, v15
	s_nop 0
	v_add_f32_e32 v12, v8, v9
	v_lshl_add_u64 v[8:9], v[18:19], 0, v[32:33]
	global_store_dwordx2 v[8:9], v[10:11], off offset:256
	v_cvt_pk_bf16_f32 v10, v24, v22
	v_cvt_pk_bf16_f32 v11, v20, v12
	global_store_dwordx2 v[8:9], v[10:11], off offset:320
	v_cvt_f32_ubyte0_e32 v10, v144
	v_mul_f32_e32 v11, 0xbed49a78, v10
	v_cmp_gt_f32_e32 vcc, s4, v11
	v_mov_b32_e32 v13, v0
	v_cvt_f32_ubyte0_e32 v0, v142
	v_cndmask_b32_e32 v11, 0, v191, vcc
	v_fmac_f32_e32 v11, 0xbed49a78, v10
	v_exp_f32_e32 v10, v11
	v_cndmask_b32_e32 v11, 0, v190, vcc
	v_mov_b32_e32 v12, v4
	v_mul_f32_e32 v4, 0xbed49a78, v0
	v_ldexp_f32 v10, v10, v11
	v_mul_f32_e32 v10, v10, v26
	v_cmp_gt_f32_e32 vcc, s4, v4
	v_mul_f32_e32 v11, 0.15915494, v10
	v_rndne_f32_e32 v11, v11
	v_cndmask_b32_e32 v4, 0, v191, vcc
	v_fmac_f32_e32 v4, 0xbed49a78, v0
	v_fmac_f32_e32 v10, 0xc0c90000, v11
	v_exp_f32_e32 v0, v4
	v_fmac_f32_e32 v10, 0xbafdaa22, v11
	v_mul_f32_e32 v10, 0.15915494, v10
	v_sin_f32_e32 v11, v10
	v_cos_f32_e32 v10, v10
	v_cndmask_b32_e32 v4, 0, v190, vcc
	v_ldexp_f32 v0, v0, v4
	v_mul_f32_e32 v0, v0, v26
	v_pk_mul_f32 v[12:13], v[12:13], v[16:17] op_sel_hi:[1,0]
	v_mul_f32_e32 v4, 0.15915494, v0
	v_pk_mul_f32 v[14:15], v[10:11], v[12:13]
	v_rndne_f32_e32 v4, v4
	v_sub_f32_e32 v17, v14, v15
	v_mov_b32_e32 v14, v11
	v_mov_b32_e32 v15, v10
	v_fmac_f32_e32 v0, 0xc0c90000, v4
	v_pk_mul_f32 v[10:11], v[14:15], v[12:13]
	v_fmac_f32_e32 v0, 0xbafdaa22, v4
	v_mul_f32_e32 v0, 0.15915494, v0
	v_add_f32_e32 v14, v10, v11
	v_cvt_f32_ubyte0_e32 v10, v139
	v_sin_f32_e32 v13, v0
	v_cos_f32_e32 v12, v0
	v_mul_f32_e32 v11, 0xbed49a78, v10
	v_cmp_gt_f32_e32 vcc, s4, v11
	v_mov_b32_e32 v0, v5
	v_pk_mul_f32 v[0:1], v[0:1], v[16:17] op_sel_hi:[1,0]
	v_cndmask_b32_e32 v11, 0, v191, vcc
	v_fmac_f32_e32 v11, 0xbed49a78, v10
	v_pk_mul_f32 v[4:5], v[12:13], v[0:1]
	v_exp_f32_e32 v10, v11
	v_sub_f32_e32 v15, v4, v5
	v_mov_b32_e32 v4, v13
	v_mov_b32_e32 v5, v12
	v_pk_mul_f32 v[0:1], v[4:5], v[0:1]
	v_mov_b32_e32 v4, v6
	v_add_f32_e32 v12, v0, v1
	v_cndmask_b32_e32 v0, 0, v190, vcc
	v_ldexp_f32 v0, v10, v0
	v_mul_f32_e32 v0, v0, v26
	v_mul_f32_e32 v1, 0.15915494, v0
	v_rndne_f32_e32 v1, v1
	v_fmac_f32_e32 v0, 0xc0c90000, v1
	v_fmac_f32_e32 v0, 0xbafdaa22, v1
	v_mul_f32_e32 v0, 0.15915494, v0
	v_sin_f32_e32 v1, v0
	v_cos_f32_e32 v0, v0
	v_mov_b32_e32 v5, v2
	v_pk_mul_f32 v[4:5], v[4:5], v[16:17] op_sel_hi:[1,0]
	s_nop 0
	v_pk_mul_f32 v[10:11], v[0:1], v[4:5]
	s_nop 0
	v_sub_f32_e32 v6, v10, v11
	v_mov_b32_e32 v10, v1
	v_cvt_f32_ubyte0_e32 v1, v143
	v_mul_f32_e32 v2, 0xbed49a78, v1
	v_cmp_gt_f32_e32 vcc, s4, v2
	v_mov_b32_e32 v11, v0
	s_nop 0
	v_cndmask_b32_e32 v2, 0, v191, vcc
	v_fmac_f32_e32 v2, 0xbed49a78, v1
	v_exp_f32_e32 v2, v2
	v_pk_mul_f32 v[0:1], v[10:11], v[4:5]
	v_cndmask_b32_e32 v4, 0, v190, vcc
	v_add_f32_e32 v10, v0, v1
	v_ldexp_f32 v2, v2, v4
	v_mul_f32_e32 v2, v2, v26
	v_mul_f32_e32 v4, 0.15915494, v2
	v_rndne_f32_e32 v4, v4
	v_fmac_f32_e32 v2, 0xc0c90000, v4
	v_fmac_f32_e32 v2, 0xbafdaa22, v4
	v_mul_f32_e32 v2, 0.15915494, v2
	v_sin_f32_e32 v5, v2
	v_cos_f32_e32 v4, v2
	v_mov_b32_e32 v2, v7
	v_pk_mul_f32 v[0:1], v[2:3], v[16:17] op_sel_hi:[1,0]
	s_nop 0
	v_pk_mul_f32 v[2:3], v[4:5], v[0:1]
	s_nop 0
	v_sub_f32_e32 v7, v2, v3
	v_mov_b32_e32 v2, v5
	v_mov_b32_e32 v3, v4
	v_pk_mul_f32 v[0:1], v[2:3], v[0:1]
	s_nop 0
	v_add_f32_e32 v2, v0, v1
	v_cvt_pk_bf16_f32 v0, v17, v15
	v_cvt_pk_bf16_f32 v1, v6, v7
	global_store_dwordx2 v[8:9], v[0:1], off offset:288
	v_cvt_pk_bf16_f32 v0, v14, v12
	v_cvt_pk_bf16_f32 v1, v10, v2
	global_store_dwordx2 v[8:9], v[0:1], off offset:352
.LBB0_787:
	s_andn2_saveexec_b64 s[0:1], s[0:1]
	s_cbranch_execz .LBB0_480
	v_lshl_add_u64 v[18:19], v[66:67], 1, v[18:19]
	v_lshl_add_u64 v[18:19], v[18:19], 0, v[32:33]
	v_mul_f32_e32 v12, v12, v16
	v_mul_f32_e32 v13, v13, v16
	v_mul_f32_e32 v8, v8, v16
	v_mul_f32_e32 v9, v9, v16
	v_mul_f32_e32 v4, v4, v16
	v_mul_f32_e32 v5, v5, v16
	v_mul_f32_e32 v0, v0, v16
	v_mul_f32_e32 v1, v1, v16
	v_mul_f32_e32 v14, v14, v16
	v_mul_f32_e32 v15, v15, v16
	v_cvt_pk_bf16_f32 v12, v12, v13
	v_cvt_pk_bf16_f32 v13, v14, v15
	global_store_dwordx2 v[18:19], v[12:13], off
	v_mul_f32_e32 v10, v10, v16
	v_mul_f32_e32 v11, v11, v16
	v_cvt_pk_bf16_f32 v8, v8, v9
	v_cvt_pk_bf16_f32 v9, v10, v11
	global_store_dwordx2 v[18:19], v[8:9], off offset:32
	v_mul_f32_e32 v6, v6, v16
	v_mul_f32_e32 v7, v7, v16
	v_cvt_pk_bf16_f32 v4, v4, v5
	v_cvt_pk_bf16_f32 v5, v6, v7
	global_store_dwordx2 v[18:19], v[4:5], off offset:64
	v_mul_f32_e32 v2, v2, v16
	v_mul_f32_e32 v3, v3, v16
	v_cvt_pk_bf16_f32 v0, v0, v1
	v_cvt_pk_bf16_f32 v1, v2, v3
	global_store_dwordx2 v[18:19], v[0:1], off offset:96
	s_branch .LBB0_480

; #define TJ_LOAD(tile_) do { const int n0_ = ((tile_) % ntn) * 64, k0_ = ((tile_) / ntn) * 64; const int sc_ = srccol<CM>(n0_ + cb); \
;     a = f32x4{0, 0, 0, 0}; b = f32x4{0, 0, 0, 0}; \
;     if (sc_ >= 0) { const float* s_ = src + (long)(k0_ + kk) * srcld + sc_; a = *(const f32x4*)s_; b = *(const f32x4*)(s_ + 4); } \
;     gg = g ? g[k0_ + kk] : 1.f; } while (0)
; template <int CM>
; DEVI void transpose_job(const float* __restrict__ src, int srcld, const float* __restrict__ g, bf16* __restrict__ dst,
;                         int K, int Ndst, unsigned short* lds, const int wave_u, const int vb, const int nvb) {
;     ...
;     const int n0 = (tile % ntn) * 64, k0 = (tile / ntn) * 64;
;     { u32x4 w = {cvtpk(a[0] * gg, a[1] * gg), cvtpk(a[2] * gg, a[3] * gg), cvtpk(b[0] * gg, b[1] * gg), cvtpk(b[2] * gg, b[3] * gg)};
;       *reinterpret_cast<u32x4*>(lds + kk * 72 + cb) = w; }
;     if (tile + nvb < ntiles) TJ_LOAD(tile + nvb);
;     __syncthreads();
;     { const int nn = tid >> 3, kb = (tid & 7) * 8; unsigned short e[8];
; #pragma unroll
;       for (int i = 0; i < 8; ++i) e[i] = lds[(kb + i) * 72 + nn];
;       u32x4 w = {(unsigned)e[0] | ((unsigned)e[1] << 16), (unsigned)e[2] | ((unsigned)e[3] << 16),
;                  (unsigned)e[4] | ((unsigned)e[5] << 16), (unsigned)e[6] | ((unsigned)e[7] << 16)};
;       *reinterpret_cast<u32x4*>(dst + (long)(n0 + nn) * K + k0 + kb) = w; }
;     __syncthreads();
.LBB0_816:
	s_mul_hi_i32 s8, s70, 0x3e0f83e1
	s_waitcnt lgkmcnt(0)
	s_barrier
	ds_read_u16 v11, v19
	ds_read_u16 v13, v19 offset:144
	ds_read_u16 v14, v19 offset:288
	ds_read_u16 v15, v19 offset:432
	ds_read_u16 v20, v19 offset:576
	ds_read_u16 v21, v19 offset:720
	ds_read_u16 v22, v19 offset:864
	ds_read_u16 v23, v19 offset:1008
	s_lshr_b32 s9, s8, 31
	s_ashr_i32 s8, s8, 5
	s_add_i32 s9, s8, s9
	s_lshl_b32 s8, s9, 6
	s_mulk_i32 s9, 0xdf00
	s_mov_b32 s4, 0x5040100
	s_add_i32 s9, s9, s12
	s_waitcnt lgkmcnt(0)
	v_perm_b32 v23, v23, v22, s4
	v_perm_b32 v22, v21, v20, s4
	v_perm_b32 v21, v15, v14, s4
	v_add_u32_e32 v14, s9, v16
	v_ashrrev_i32_e32 v15, 31, v14
	v_lshlrev_b64 v[14:15], 12, v[14:15]
	v_lshl_add_u64 v[14:15], s[66:67], 0, v[14:15]
	s_ashr_i32 s9, s8, 31
	v_perm_b32 v20, v13, v11, s4
	v_lshl_add_u64 v[14:15], s[8:9], 1, v[14:15]
	v_mov_b32_e32 v11, v33
	v_readlane_b32 s4, v254, 29
	v_lshl_add_u64 v[14:15], v[14:15], 0, v[10:11]
	s_add_i32 s12, s12, s4
	s_andn2_b64 vcc, exec, s[6:7]
	s_mov_b32 s70, s13
	global_store_dwordx4 v[14:15], v[20:23], off
	s_waitcnt lgkmcnt(0)
	s_barrier
	s_cbranch_vccz .LBB0_835

; #define TJ_LOAD(tile_) do { const int n0_ = ((tile_) % ntn) * 64, k0_ = ((tile_) / ntn) * 64; const int sc_ = srccol<CM>(n0_ + cb); \
;     a = f32x4{0, 0, 0, 0}; b = f32x4{0, 0, 0, 0}; \
;     if (sc_ >= 0) { const float* s_ = src + (long)(k0_ + kk) * srcld + sc_; a = *(const f32x4*)s_; b = *(const f32x4*)(s_ + 4); } \
;     gg = g ? g[k0_ + kk] : 1.f; } while (0)
; template <int CM>
; DEVI void transpose_job(const float* __restrict__ src, int srcld, const float* __restrict__ g, bf16* __restrict__ dst,
;                         int K, int Ndst, unsigned short* lds, const int wave_u, const int vb, const int nvb) {
;     ...
;     const int n0 = (tile % ntn) * 64, k0 = (tile / ntn) * 64;
;     { u32x4 w = {cvtpk(a[0] * gg, a[1] * gg), cvtpk(a[2] * gg, a[3] * gg), cvtpk(b[0] * gg, b[1] * gg), cvtpk(b[2] * gg, b[3] * gg)};
;       *reinterpret_cast<u32x4*>(lds + kk * 72 + cb) = w; }
;     if (tile + nvb < ntiles) TJ_LOAD(tile + nvb);
;     __syncthreads();
;     { const int nn = tid >> 3, kb = (tid & 7) * 8; unsigned short e[8];
; #pragma unroll
;       for (int i = 0; i < 8; ++i) e[i] = lds[(kb + i) * 72 + nn];
;       u32x4 w = {(unsigned)e[0] | ((unsigned)e[1] << 16), (unsigned)e[2] | ((unsigned)e[3] << 16),
;                  (unsigned)e[4] | ((unsigned)e[5] << 16), (unsigned)e[6] | ((unsigned)e[7] << 16)};
;       *reinterpret_cast<u32x4*>(dst + (long)(n0 + nn) * K + k0 + kb) = w; }
;     __syncthreads();
.LBB0_851:
	s_mul_hi_i32 s8, s70, 0x2aaaaaab
	s_waitcnt lgkmcnt(0)
	s_barrier
	ds_read_u16 v11, v18
	ds_read_u16 v13, v18 offset:144
	ds_read_u16 v14, v18 offset:288
	ds_read_u16 v15, v18 offset:432
	ds_read_u16 v19, v18 offset:576
	ds_read_u16 v20, v18 offset:720
	ds_read_u16 v21, v18 offset:864
	ds_read_u16 v22, v18 offset:1008
	s_lshr_b32 s9, s8, 31
	s_ashr_i32 s8, s8, 2
	s_add_i32 s9, s8, s9
	s_lshl_b32 s8, s9, 6
	s_mulk_i32 s9, 0xfa00
	s_mov_b32 s4, 0x5040100
	s_add_i32 s9, s9, s12
	s_waitcnt lgkmcnt(0)
	v_perm_b32 v23, v22, v21, s4
	v_perm_b32 v21, v15, v14, s4
	v_add_u32_e32 v14, s9, v9
	v_perm_b32 v22, v20, v19, s4
	v_perm_b32 v20, v13, v11, s4
	v_ashrrev_i32_e32 v15, 31, v14
	v_readlane_b32 s4, v255, 19
	v_lshlrev_b64 v[14:15], 10, v[14:15]
	v_readlane_b32 s5, v255, 20
	s_ashr_i32 s9, s8, 31
	v_mov_b32_e32 v11, v33
	v_lshl_add_u64 v[14:15], s[4:5], 0, v[14:15]
	v_lshl_add_u64 v[14:15], s[8:9], 1, v[14:15]
	v_readlane_b32 s4, v254, 29
	v_lshl_add_u64 v[14:15], v[14:15], 0, v[10:11]
	s_add_i32 s12, s12, s4
	s_andn2_b64 vcc, exec, s[6:7]
	s_mov_b32 s70, s13
	global_store_dwordx4 v[14:15], v[20:23], off
	s_waitcnt lgkmcnt(0)
	s_barrier
	s_cbranch_vccz .LBB0_865

; #define TJ_LOAD(tile_) do { const int n0_ = ((tile_) % ntn) * 64, k0_ = ((tile_) / ntn) * 64; const int sc_ = srccol<CM>(n0_ + cb); \
;     a = f32x4{0, 0, 0, 0}; b = f32x4{0, 0, 0, 0}; \
;     if (sc_ >= 0) { const float* s_ = src + (long)(k0_ + kk) * srcld + sc_; a = *(const f32x4*)s_; b = *(const f32x4*)(s_ + 4); } \
;     gg = g ? g[k0_ + kk] : 1.f; } while (0)
; template <int CM>
; DEVI void transpose_job(const float* __restrict__ src, int srcld, const float* __restrict__ g, bf16* __restrict__ dst,
;                         int K, int Ndst, unsigned short* lds, const int wave_u, const int vb, const int nvb) {
;     ...
;     const int n0 = (tile % ntn) * 64, k0 = (tile / ntn) * 64;
;     { u32x4 w = {cvtpk(a[0] * gg, a[1] * gg), cvtpk(a[2] * gg, a[3] * gg), cvtpk(b[0] * gg, b[1] * gg), cvtpk(b[2] * gg, b[3] * gg)};
;       *reinterpret_cast<u32x4*>(lds + kk * 72 + cb) = w; }
;     if (tile + nvb < ntiles) TJ_LOAD(tile + nvb);
;     __syncthreads();
;     { const int nn = tid >> 3, kb = (tid & 7) * 8; unsigned short e[8];
; #pragma unroll
;       for (int i = 0; i < 8; ++i) e[i] = lds[(kb + i) * 72 + nn];
;       u32x4 w = {(unsigned)e[0] | ((unsigned)e[1] << 16), (unsigned)e[2] | ((unsigned)e[3] << 16),
;                  (unsigned)e[4] | ((unsigned)e[5] << 16), (unsigned)e[6] | ((unsigned)e[7] << 16)};
;       *reinterpret_cast<u32x4*>(dst + (long)(n0 + nn) * K + k0 + kb) = w; }
;     __syncthreads();
.LBB0_871:
	s_ashr_i32 s39, s13, 31
	s_waitcnt lgkmcnt(0)
	s_barrier
	ds_read_u16 v8, v12
	ds_read_u16 v13, v12 offset:144
	ds_read_u16 v14, v12 offset:288
	ds_read_u16 v15, v12 offset:432
	ds_read_u16 v16, v12 offset:576
	ds_read_u16 v18, v12 offset:720
	ds_read_u16 v17, v12 offset:864
	ds_read_u16 v19, v12 offset:1008
	s_lshr_b32 s39, s39, 28
	s_add_i32 s13, s13, s39
	s_ashr_i32 s13, s13, 4
	s_mov_b32 s4, 0x5040100
	s_lshl_b32 s68, s13, 6
	s_waitcnt lgkmcnt(4)
	v_perm_b32 v15, v15, v14, s4
	v_perm_b32 v14, v13, v8, s4
	v_add_u32_e32 v8, s12, v9
	s_lshl_b32 s13, s13, 10
	s_waitcnt lgkmcnt(2)
	v_perm_b32 v16, v18, v16, s4
	v_subrev_u32_e32 v18, s13, v8
	s_waitcnt lgkmcnt(0)
	v_perm_b32 v17, v19, v17, s4
	v_ashrrev_i32_e32 v19, 31, v18
	v_readlane_b32 s4, v255, 44
	v_lshlrev_b64 v[18:19], 10, v[18:19]
	v_readlane_b32 s5, v255, 45
	s_ashr_i32 s69, s68, 31
	s_andn2_b64 vcc, exec, s[8:9]
	v_lshl_add_u64 v[18:19], s[4:5], 0, v[18:19]
	v_lshl_add_u64 v[18:19], s[68:69], 1, v[18:19]
	v_readlane_b32 s4, v254, 29
	v_lshl_add_u64 v[18:19], v[18:19], 0, v[32:33]
	s_add_i32 s12, s12, s4
	s_mov_b32 s13, s38
	global_store_dwordx4 v[18:19], v[14:17], off
	s_waitcnt lgkmcnt(0)
	s_barrier
	s_cbranch_vccz .LBB0_875

; #define TJ_LOAD(tile_) do { const int n0_ = ((tile_) % ntn) * 64, k0_ = ((tile_) / ntn) * 64; const int sc_ = srccol<CM>(n0_ + cb); \
;     a = f32x4{0, 0, 0, 0}; b = f32x4{0, 0, 0, 0}; \
;     if (sc_ >= 0) { const float* s_ = src + (long)(k0_ + kk) * srcld + sc_; a = *(const f32x4*)s_; b = *(const f32x4*)(s_ + 4); } \
;     gg = g ? g[k0_ + kk] : 1.f; } while (0)
; template <int CM>
; DEVI void transpose_job(const float* __restrict__ src, int srcld, const float* __restrict__ g, bf16* __restrict__ dst,
;                         int K, int Ndst, unsigned short* lds, const int wave_u, const int vb, const int nvb) {
;     ...
;     const int n0 = (tile % ntn) * 64, k0 = (tile / ntn) * 64;
;     { u32x4 w = {cvtpk(a[0] * gg, a[1] * gg), cvtpk(a[2] * gg, a[3] * gg), cvtpk(b[0] * gg, b[1] * gg), cvtpk(b[2] * gg, b[3] * gg)};
;       *reinterpret_cast<u32x4*>(lds + kk * 72 + cb) = w; }
;     if (tile + nvb < ntiles) TJ_LOAD(tile + nvb);
;     __syncthreads();
;     { const int nn = tid >> 3, kb = (tid & 7) * 8; unsigned short e[8];
; #pragma unroll
;       for (int i = 0; i < 8; ++i) e[i] = lds[(kb + i) * 72 + nn];
;       u32x4 w = {(unsigned)e[0] | ((unsigned)e[1] << 16), (unsigned)e[2] | ((unsigned)e[3] << 16),
;                  (unsigned)e[4] | ((unsigned)e[5] << 16), (unsigned)e[6] | ((unsigned)e[7] << 16)};
;       *reinterpret_cast<u32x4*>(dst + (long)(n0 + nn) * K + k0 + kb) = w; }
;     __syncthreads();
.LBB0_882:
	s_ashr_i32 s13, s9, 31
	s_waitcnt lgkmcnt(0)
	s_barrier
	ds_read_u16 v8, v12
	ds_read_u16 v13, v12 offset:144
	ds_read_u16 v14, v12 offset:288
	ds_read_u16 v15, v12 offset:432
	ds_read_u16 v16, v12 offset:576
	ds_read_u16 v18, v12 offset:720
	ds_read_u16 v17, v12 offset:864
	ds_read_u16 v19, v12 offset:1008
	s_lshr_b32 s13, s13, 28
	s_add_i32 s9, s9, s13
	s_ashr_i32 s9, s9, 4
	s_mov_b32 s4, 0x5040100
	s_lshl_b32 s38, s9, 6
	s_waitcnt lgkmcnt(4)
	v_perm_b32 v15, v15, v14, s4
	v_perm_b32 v14, v13, v8, s4
	v_add_u32_e32 v8, s8, v9
	s_lshl_b32 s9, s9, 10
	s_waitcnt lgkmcnt(2)
	v_perm_b32 v16, v18, v16, s4
	v_subrev_u32_e32 v18, s9, v8
	s_waitcnt lgkmcnt(0)
	v_perm_b32 v17, v19, v17, s4
	v_ashrrev_i32_e32 v19, 31, v18
	v_lshlrev_b64 v[18:19], 10, v[18:19]
	v_lshl_add_u64 v[18:19], s[0:1], 0, v[18:19]
	s_ashr_i32 s39, s38, 31
	v_lshl_add_u64 v[18:19], s[38:39], 1, v[18:19]
	v_readlane_b32 s4, v254, 29
	v_lshl_add_u64 v[18:19], v[18:19], 0, v[32:33]
	s_add_i32 s8, s8, s4
	s_andn2_b64 vcc, exec, s[6:7]
	s_mov_b32 s9, s12
	global_store_dwordx4 v[18:19], v[14:17], off
	s_waitcnt lgkmcnt(0)
	s_barrier
	s_cbranch_vccz .LBB0_886

; #define TJ_LOAD(tile_) do { const int n0_ = ((tile_) % ntn) * 64, k0_ = ((tile_) / ntn) * 64; const int sc_ = srccol<CM>(n0_ + cb); \
;     a = f32x4{0, 0, 0, 0}; b = f32x4{0, 0, 0, 0}; \
;     if (sc_ >= 0) { const float* s_ = src + (long)(k0_ + kk) * srcld + sc_; a = *(const f32x4*)s_; b = *(const f32x4*)(s_ + 4); } \
;     gg = g ? g[k0_ + kk] : 1.f; } while (0)
; template <int CM>
; DEVI void transpose_job(const float* __restrict__ src, int srcld, const float* __restrict__ g, bf16* __restrict__ dst,
;                         int K, int Ndst, unsigned short* lds, const int wave_u, const int vb, const int nvb) {
;     ...
;     const int n0 = (tile % ntn) * 64, k0 = (tile / ntn) * 64;
;     { u32x4 w = {cvtpk(a[0] * gg, a[1] * gg), cvtpk(a[2] * gg, a[3] * gg), cvtpk(b[0] * gg, b[1] * gg), cvtpk(b[2] * gg, b[3] * gg)};
;       *reinterpret_cast<u32x4*>(lds + kk * 72 + cb) = w; }
;     if (tile + nvb < ntiles) TJ_LOAD(tile + nvb);
;     __syncthreads();
;     { const int nn = tid >> 3, kb = (tid & 7) * 8; unsigned short e[8];
; #pragma unroll
;       for (int i = 0; i < 8; ++i) e[i] = lds[(kb + i) * 72 + nn];
;       u32x4 w = {(unsigned)e[0] | ((unsigned)e[1] << 16), (unsigned)e[2] | ((unsigned)e[3] << 16),
;                  (unsigned)e[4] | ((unsigned)e[5] << 16), (unsigned)e[6] | ((unsigned)e[7] << 16)};
;       *reinterpret_cast<u32x4*>(dst + (long)(n0 + nn) * K + k0 + kb) = w; }
;     __syncthreads();
.LBB0_893:
	s_ashr_i32 s39, s13, 31
	s_waitcnt lgkmcnt(0)
	s_barrier
	ds_read_u16 v8, v12
	ds_read_u16 v13, v12 offset:144
	ds_read_u16 v14, v12 offset:288
	ds_read_u16 v15, v12 offset:432
	ds_read_u16 v16, v12 offset:576
	ds_read_u16 v18, v12 offset:720
	ds_read_u16 v17, v12 offset:864
	ds_read_u16 v19, v12 offset:1008
	s_lshr_b32 s39, s39, 27
	s_add_i32 s13, s13, s39
	s_ashr_i32 s13, s13, 5
	s_mov_b32 s4, 0x5040100
	s_lshl_b32 s68, s13, 6
	s_waitcnt lgkmcnt(4)
	v_perm_b32 v15, v15, v14, s4
	v_perm_b32 v14, v13, v8, s4
	v_add_u32_e32 v8, s12, v9
	s_lshl_b32 s13, s13, 11
	s_waitcnt lgkmcnt(2)
	v_perm_b32 v16, v18, v16, s4
	v_subrev_u32_e32 v18, s13, v8
	s_waitcnt lgkmcnt(0)
	v_perm_b32 v17, v19, v17, s4
	v_ashrrev_i32_e32 v19, 31, v18
	v_readlane_b32 s4, v255, 21
	v_lshlrev_b64 v[18:19], 12, v[18:19]
	v_readlane_b32 s5, v255, 22
	s_ashr_i32 s69, s68, 31
	s_andn2_b64 vcc, exec, s[8:9]
	v_lshl_add_u64 v[18:19], s[4:5], 0, v[18:19]
	v_lshl_add_u64 v[18:19], s[68:69], 1, v[18:19]
	v_readlane_b32 s4, v254, 29
	v_lshl_add_u64 v[18:19], v[18:19], 0, v[32:33]
	s_add_i32 s12, s12, s4
	s_mov_b32 s13, s38
	global_store_dwordx4 v[18:19], v[14:17], off
	s_waitcnt lgkmcnt(0)
	s_barrier
	s_cbranch_vccz .LBB0_897

; #define TJ_LOAD(tile_) do { const int n0_ = ((tile_) % ntn) * 64, k0_ = ((tile_) / ntn) * 64; const int sc_ = srccol<CM>(n0_ + cb); \
;     a = f32x4{0, 0, 0, 0}; b = f32x4{0, 0, 0, 0}; \
;     if (sc_ >= 0) { const float* s_ = src + (long)(k0_ + kk) * srcld + sc_; a = *(const f32x4*)s_; b = *(const f32x4*)(s_ + 4); } \
;     gg = g ? g[k0_ + kk] : 1.f; } while (0)
; template <int CM>
; DEVI void transpose_job(const float* __restrict__ src, int srcld, const float* __restrict__ g, bf16* __restrict__ dst,
;                         int K, int Ndst, unsigned short* lds, const int wave_u, const int vb, const int nvb) {
;     ...
;     const int n0 = (tile % ntn) * 64, k0 = (tile / ntn) * 64;
;     { u32x4 w = {cvtpk(a[0] * gg, a[1] * gg), cvtpk(a[2] * gg, a[3] * gg), cvtpk(b[0] * gg, b[1] * gg), cvtpk(b[2] * gg, b[3] * gg)};
;       *reinterpret_cast<u32x4*>(lds + kk * 72 + cb) = w; }
;     if (tile + nvb < ntiles) TJ_LOAD(tile + nvb);
;     __syncthreads();
;     { const int nn = tid >> 3, kb = (tid & 7) * 8; unsigned short e[8];
; #pragma unroll
;       for (int i = 0; i < 8; ++i) e[i] = lds[(kb + i) * 72 + nn];
;       u32x4 w = {(unsigned)e[0] | ((unsigned)e[1] << 16), (unsigned)e[2] | ((unsigned)e[3] << 16),
;                  (unsigned)e[4] | ((unsigned)e[5] << 16), (unsigned)e[6] | ((unsigned)e[7] << 16)};
;       *reinterpret_cast<u32x4*>(dst + (long)(n0 + nn) * K + k0 + kb) = w; }
;     __syncthreads();
.LBB0_904:
	s_ashr_i32 s9, s7, 31
	s_waitcnt lgkmcnt(0)
	s_barrier
	ds_read_u16 v8, v12
	ds_read_u16 v13, v12 offset:144
	ds_read_u16 v14, v12 offset:288
	ds_read_u16 v15, v12 offset:432
	ds_read_u16 v16, v12 offset:576
	ds_read_u16 v18, v12 offset:720
	ds_read_u16 v17, v12 offset:864
	ds_read_u16 v19, v12 offset:1008
	s_lshr_b32 s9, s9, 27
	s_add_i32 s7, s7, s9
	s_ashr_i32 s7, s7, 5
	s_mov_b32 s4, 0x5040100
	s_lshl_b32 s12, s7, 6
	s_waitcnt lgkmcnt(4)
	v_perm_b32 v15, v15, v14, s4
	v_perm_b32 v14, v13, v8, s4
	v_add_u32_e32 v8, s6, v9
	s_lshl_b32 s7, s7, 11
	s_waitcnt lgkmcnt(2)
	v_perm_b32 v16, v18, v16, s4
	v_subrev_u32_e32 v18, s7, v8
	s_waitcnt lgkmcnt(0)
	v_perm_b32 v17, v19, v17, s4
	v_ashrrev_i32_e32 v19, 31, v18
	v_readlane_b32 s16, v255, 23
	v_lshlrev_b64 v[18:19], 12, v[18:19]
	v_readlane_b32 s17, v255, 24
	s_ashr_i32 s13, s12, 31
	v_readlane_b32 s4, v254, 29
	v_lshl_add_u64 v[18:19], s[16:17], 0, v[18:19]
	v_lshl_add_u64 v[18:19], s[12:13], 1, v[18:19]
	v_lshl_add_u64 v[18:19], v[18:19], 0, v[32:33]
	s_add_i32 s6, s6, s4
	s_andn2_b64 vcc, exec, s[0:1]
	s_mov_b32 s7, s8
	global_store_dwordx4 v[18:19], v[14:17], off
	s_waitcnt lgkmcnt(0)
	s_barrier
	s_cbranch_vccz .LBB0_908

; DEVI int RSI(int row) { return ((row >> 3) << 5) | (row & 7); }
; DEVI void run_phase(const int ph, const Params& P, char* shmc, const int wave_u) {
;     ...
;       for (int row = blockIdx.x * 8 + wid; row < MT; row += G * 8) {
;         const float* xr = row < MP ? P.x_p + (long)row * DM : P.x_s + (long)(row - MP) * DM;
;         float ss = 0.f;
; #pragma unroll
;         for (int i = 0; i < 4; ++i) { const int c = (i * 64 + lane) * 8;
;           f32x4 a = *(const f32x4*)(xr + c), b = *(const f32x4*)(xr + c + 4);
; #pragma unroll
;           for (int j = 0; j < 4; ++j) ss += a[j] * a[j] + b[j] * b[j];
;           u32x4 w = {cvtpk(a[0], a[1]), cvtpk(a[2], a[3]), cvtpk(b[0], b[1]), cvtpk(b[2], b[3])};
;           *reinterpret_cast<u32x4*>(xb + (long)row * DM + c) = w; }
;         ss = wave_sum(ss, lane);
;         if (lane == 0) { rs0[RSI(row)] = rsqrtf(ss * (1.f / DM) + EPS); ssq[RSI(row)] = 0.f; }
.LBB0_913:
	s_or_b64 exec, exec, s[12:13]
	v_lshl_add_u64 v[30:31], v[10:11], 0, v[32:33]
	global_load_dwordx4 v[22:25], v[30:31], off
	global_load_dwordx4 v[26:29], v[30:31], off offset:16
	v_lshlrev_b64 v[12:13], 12, v[12:13]
	v_lshl_add_u64 v[54:55], v[2:3], 0, v[12:13]
	v_mov_b32_e32 v7, v33
	v_lshl_add_u64 v[12:13], v[10:11], 0, v[6:7]
	s_waitcnt lgkmcnt(0)
	v_mov_b32_e32 v9, v33
	s_waitcnt vmcnt(0)
	v_cvt_pk_bf16_f32 v34, v22, v23
	v_cvt_pk_bf16_f32 v35, v24, v25
	s_waitcnt vmcnt(0)
	v_cvt_pk_bf16_f32 v36, v26, v27
	v_cvt_pk_bf16_f32 v37, v28, v29
	global_store_dwordx4 v[54:55], v[34:37], off
	global_load_dwordx4 v[34:37], v[30:31], off offset:2048
	s_nop 0
	global_load_dwordx4 v[38:41], v[30:31], off offset:2064
	v_lshl_add_u64 v[30:31], v[10:11], 0, v[8:9]
	v_mul_f32_e32 v7, v26, v26
	v_mul_f32_e32 v9, v27, v27
	v_mul_f32_e32 v26, v28, v28
	v_fmac_f32_e32 v7, v22, v22
	v_fmac_f32_e32 v9, v23, v23
	v_mul_f32_e32 v27, v29, v29
	v_fmac_f32_e32 v26, v24, v24
	v_add_f32_e32 v7, v7, v9
	v_fmac_f32_e32 v27, v25, v25
	v_add_f32_e32 v7, v26, v7
	v_add_f32_e32 v7, v27, v7
	s_waitcnt vmcnt(0)
	v_cvt_pk_bf16_f32 v42, v34, v35
	v_cvt_pk_bf16_f32 v43, v36, v37
	v_cvt_pk_bf16_f32 v44, v38, v39
	v_cvt_pk_bf16_f32 v45, v40, v41
	global_store_dwordx4 v[54:55], v[42:45], off offset:1024
	global_load_dwordx4 v[42:45], v[12:13], off
	s_nop 0
	global_load_dwordx4 v[46:49], v[12:13], off offset:16
	v_mul_f32_e32 v9, v38, v38
	v_mul_f32_e32 v22, v39, v39
	v_fmac_f32_e32 v9, v34, v34
	v_mul_f32_e32 v23, v40, v40
	v_fmac_f32_e32 v22, v35, v35
	v_add_f32_e32 v7, v7, v9
	v_mul_f32_e32 v24, v41, v41
	v_fmac_f32_e32 v23, v36, v36
	v_add_f32_e32 v7, v22, v7
	v_fmac_f32_e32 v24, v37, v37
	v_add_f32_e32 v7, v23, v7
	v_add_f32_e32 v7, v24, v7
	s_waitcnt vmcnt(0)
	v_cvt_pk_bf16_f32 v10, v42, v43
	v_cvt_pk_bf16_f32 v11, v44, v45
	v_cvt_pk_bf16_f32 v12, v46, v47
	v_cvt_pk_bf16_f32 v13, v48, v49
	global_store_dwordx4 v[54:55], v[10:13], off offset:2048
	global_load_dwordx4 v[10:13], v[30:31], off offset:16
	s_nop 0
	global_load_dwordx4 v[50:53], v[30:31], off
	v_mul_f32_e32 v9, v46, v46
	v_mul_f32_e32 v22, v47, v47
	v_fmac_f32_e32 v9, v42, v42
	v_mul_f32_e32 v23, v48, v48
	v_fmac_f32_e32 v22, v43, v43
	v_add_f32_e32 v7, v7, v9
	v_mul_f32_e32 v24, v49, v49
	v_fmac_f32_e32 v23, v44, v44
	v_add_f32_e32 v7, v22, v7
	v_fmac_f32_e32 v24, v45, v45
	v_add_f32_e32 v7, v23, v7
	v_add_f32_e32 v7, v24, v7
	s_waitcnt vmcnt(0)
	v_mul_f32_e32 v9, v10, v10
	v_mul_f32_e32 v22, v11, v11
	v_fmac_f32_e32 v9, v50, v50
	v_mul_f32_e32 v23, v12, v12
	v_fmac_f32_e32 v22, v51, v51
	v_add_f32_e32 v7, v7, v9
	v_mul_f32_e32 v24, v13, v13
	v_fmac_f32_e32 v23, v52, v52
	v_add_f32_e32 v7, v22, v7
	v_add_f32_e32 v7, v23, v7
	v_fmac_f32_e32 v24, v53, v53
	v_add_f32_e32 v7, v24, v7
	ds_bpermute_b32 v9, v14, v7
	v_cvt_pk_bf16_f32 v22, v50, v51
	v_cvt_pk_bf16_f32 v23, v52, v53
	v_cvt_pk_bf16_f32 v24, v10, v11
	v_cvt_pk_bf16_f32 v25, v12, v13
	s_waitcnt lgkmcnt(0)
	v_add_f32_e32 v7, v7, v9
	ds_bpermute_b32 v9, v15, v7
	global_store_dwordx4 v[54:55], v[22:25], off offset:3072
	s_waitcnt lgkmcnt(0)
	v_add_f32_e32 v7, v7, v9
	ds_bpermute_b32 v9, v16, v7
	s_waitcnt lgkmcnt(0)
	v_add_f32_e32 v7, v7, v9
	ds_bpermute_b32 v9, v17, v7
	s_waitcnt lgkmcnt(0)
	v_add_f32_e32 v7, v7, v9
	ds_bpermute_b32 v9, v18, v7
	s_waitcnt lgkmcnt(0)
	v_add_f32_e32 v7, v7, v9
	ds_bpermute_b32 v9, v19, v7
	s_and_saveexec_b64 s[12:13], vcc
	s_cbranch_execz .LBB0_910
	s_waitcnt lgkmcnt(0)
	v_add_f32_e32 v7, v7, v9
	v_fmamk_f32 v7, v7, 0x3a000000, v186
	s_mov_b32 s0, 0x800000
	v_mul_f32_e32 v9, 0x4b800000, v7
	v_cmp_gt_f32_e64 s[0:1], s0, v7
	s_movk_i32 s4, 0xffe0
	v_and_or_b32 v10, v21, s4, v20
	v_cndmask_b32_e64 v7, v7, v9, s[0:1]
	v_rsq_f32_e32 v7, v7
	v_ashrrev_i32_e32 v11, 31, v10
	v_lshlrev_b64 v[10:11], 2, v[10:11]
	v_mul_f32_e32 v9, 0x45800000, v7
	v_cndmask_b32_e64 v7, v7, v9, s[0:1]
	v_readlane_b32 s0, v255, 35
	v_readlane_b32 s1, v255, 36
	s_nop 1
	v_lshl_add_u64 v[12:13], s[0:1], 0, v[10:11]
	v_readlane_b32 s0, v255, 25
	v_readlane_b32 s1, v255, 26
	global_store_dword v[12:13], v7, off
	s_nop 0
	v_lshl_add_u64 v[10:11], s[0:1], 0, v[10:11]
	global_store_dword v[10:11], v33, off
	s_branch .LBB0_910

; DEVI void convert_job(const float* __restrict__ src, bf16* __restrict__ dst, long total, long blen, long dstb, const int wave_u,
;                       const int vb, const int nvb) {
;     ...
;     for (int u = 0; u < 4; ++u) { const long i = i0 + u * step;
;       if (i < total) { a[u] = *(const f32x4*)(src + i); c[u] = *(const f32x4*)(src + i + 4); } }
; #pragma unroll
;     for (int u = 0; u < 4; ++u) { const long i = i0 + u * step;
;       if (i < total) { const long b = i / blen, off = i - b * blen;
;         u32x4 w = {cvtpk(a[u][0], a[u][1]), cvtpk(a[u][2], a[u][3]), cvtpk(c[u][0], c[u][1]), cvtpk(c[u][2], c[u][3])};
;         *reinterpret_cast<u32x4*>(dst + b * dstb + off) = w; } }
.LBB0_924:
	s_or_b64 exec, exec, s[8:9]
	v_ashrrev_i32_e32 v32, 31, v43
	v_lshrrev_b32_e32 v32, 10, v32
	v_lshl_add_u64 v[50:51], v[42:43], 0, v[32:33]
	v_and_b32_e32 v50, 0xffc00000, v50
	v_and_b32_e32 v32, 0x7fffffff, v51
	v_sub_co_u32_e64 v42, s[8:9], v42, v50
	s_waitcnt vmcnt(0)
	v_cvt_pk_bf16_f32 v28, v28, v29
	v_cvt_pk_bf16_f32 v29, v30, v31
	v_cvt_pk_bf16_f32 v30, v24, v25
	v_cvt_pk_bf16_f32 v31, v26, v27
	s_nop 0
	v_subb_co_u32_e64 v43, s[8:9], v43, v32, s[8:9]
	v_readlane_b32 s8, v255, 15
	v_readlane_b32 s9, v255, 16
	s_nop 1
	v_lshl_add_u64 v[24:25], v[42:43], 1, s[8:9]
	global_store_dwordx4 v[24:25], v[28:31], off
	s_and_saveexec_b64 s[8:9], vcc
	s_cbranch_execz .LBB0_927
	v_ashrrev_i32_e32 v24, 31, v45
	v_lshrrev_b32_e32 v32, 10, v24
	v_lshl_add_u64 v[24:25], v[44:45], 0, v[32:33]
	v_and_b32_e32 v24, 0xffc00000, v24
	v_and_b32_e32 v25, 0x7fffffff, v25
	v_sub_co_u32_e32 v28, vcc, v44, v24
	v_readlane_b32 s16, v255, 15
	s_nop 0
	v_subb_co_u32_e32 v29, vcc, v45, v25, vcc
	v_readlane_b32 s17, v255, 16
	v_cvt_pk_bf16_f32 v24, v0, v1
	v_cvt_pk_bf16_f32 v25, v2, v3
	v_cvt_pk_bf16_f32 v26, v8, v9
	v_cvt_pk_bf16_f32 v27, v10, v11
	s_nop 1
	v_lshl_add_u64 v[28:29], v[28:29], 1, s[16:17]
	global_store_dwordx4 v[28:29], v[24:27], off
	s_or_b64 exec, exec, s[8:9]
	s_and_saveexec_b64 s[8:9], s[0:1]
	s_cbranch_execnz .LBB0_928

; DEVI void convert_job(const float* __restrict__ src, bf16* __restrict__ dst, long total, long blen, long dstb, const int wave_u,
;                       const int vb, const int nvb) {
;     ...
;     for (int u = 0; u < 4; ++u) { const long i = i0 + u * step;
;       if (i < total) { a[u] = *(const f32x4*)(src + i); c[u] = *(const f32x4*)(src + i + 4); } }
; #pragma unroll
;     for (int u = 0; u < 4; ++u) { const long i = i0 + u * step;
;       if (i < total) { const long b = i / blen, off = i - b * blen;
;         u32x4 w = {cvtpk(a[u][0], a[u][1]), cvtpk(a[u][2], a[u][3]), cvtpk(c[u][0], c[u][1]), cvtpk(c[u][2], c[u][3])};
;         *reinterpret_cast<u32x4*>(dst + b * dstb + off) = w; } }
.LBB0_928:
	v_ashrrev_i32_e32 v24, 31, v47
	v_lshrrev_b32_e32 v32, 10, v24
	v_lshl_add_u64 v[24:25], v[46:47], 0, v[32:33]
	v_and_b32_e32 v24, 0xffc00000, v24
	v_and_b32_e32 v25, 0x7fffffff, v25
	v_sub_co_u32_e32 v28, vcc, v46, v24
	v_readlane_b32 s0, v255, 15
	s_nop 0
	v_subb_co_u32_e32 v29, vcc, v47, v25, vcc
	v_readlane_b32 s1, v255, 16
	v_cvt_pk_bf16_f32 v24, v4, v5
	v_cvt_pk_bf16_f32 v25, v6, v7
	v_cvt_pk_bf16_f32 v26, v16, v17
	v_cvt_pk_bf16_f32 v27, v18, v19
	s_nop 1
	v_lshl_add_u64 v[28:29], v[28:29], 1, s[0:1]
	global_store_dwordx4 v[28:29], v[24:27], off
	s_or_b64 exec, exec, s[8:9]
	s_and_saveexec_b64 s[0:1], s[6:7]
	s_cbranch_execz .LBB0_917
.LBB0_929:
	v_ashrrev_i32_e32 v24, 31, v49
	v_lshrrev_b32_e32 v32, 10, v24
	v_lshl_add_u64 v[24:25], v[48:49], 0, v[32:33]
	v_and_b32_e32 v24, 0xffc00000, v24
	v_and_b32_e32 v25, 0x7fffffff, v25
	v_sub_co_u32_e32 v28, vcc, v48, v24
	v_readlane_b32 s6, v255, 15
	s_nop 0
	v_subb_co_u32_e32 v29, vcc, v49, v25, vcc
	v_readlane_b32 s7, v255, 16
	v_cvt_pk_bf16_f32 v24, v12, v13
	v_cvt_pk_bf16_f32 v25, v14, v15
	v_cvt_pk_bf16_f32 v26, v20, v21
	v_cvt_pk_bf16_f32 v27, v22, v23
	s_nop 1
	v_lshl_add_u64 v[28:29], v[28:29], 1, s[6:7]
	global_store_dwordx4 v[28:29], v[24:27], off
	s_branch .LBB0_917

; DEVI void convert_job(const float* __restrict__ src, bf16* __restrict__ dst, long total, long blen, long dstb, const int wave_u,
;                       const int vb, const int nvb) {
;     ...
;     for (int u = 0; u < 4; ++u) { const long i = i0 + u * step;
;       if (i < total) { a[u] = *(const f32x4*)(src + i); c[u] = *(const f32x4*)(src + i + 4); } }
; #pragma unroll
;     for (int u = 0; u < 4; ++u) { const long i = i0 + u * step;
;       if (i < total) { const long b = i / blen, off = i - b * blen;
;         u32x4 w = {cvtpk(a[u][0], a[u][1]), cvtpk(a[u][2], a[u][3]), cvtpk(c[u][0], c[u][1]), cvtpk(c[u][2], c[u][3])};
;         *reinterpret_cast<u32x4*>(dst + b * dstb + off) = w; } }
.LBB0_939:
	s_or_b64 exec, exec, s[8:9]
	v_ashrrev_i32_e32 v32, 31, v43
	v_lshrrev_b32_e32 v32, 15, v32
	v_lshl_add_u64 v[50:51], v[42:43], 0, v[32:33]
	v_and_b32_e32 v50, 0xfffe0000, v50
	v_and_b32_e32 v32, 0x7fffffff, v51
	v_sub_co_u32_e64 v42, s[8:9], v42, v50
	s_waitcnt vmcnt(0)
	v_cvt_pk_bf16_f32 v28, v28, v29
	v_cvt_pk_bf16_f32 v29, v30, v31
	v_cvt_pk_bf16_f32 v30, v24, v25
	v_cvt_pk_bf16_f32 v31, v26, v27
	s_nop 0
	v_subb_co_u32_e64 v43, s[8:9], v43, v32, s[8:9]
	v_lshl_add_u64 v[24:25], v[42:43], 1, s[38:39]
	global_store_dwordx4 v[24:25], v[28:31], off
	s_and_saveexec_b64 s[8:9], vcc
	s_cbranch_execz .LBB0_942
	v_ashrrev_i32_e32 v24, 31, v45
	v_lshrrev_b32_e32 v32, 15, v24
	v_lshl_add_u64 v[24:25], v[44:45], 0, v[32:33]
	v_and_b32_e32 v24, 0xfffe0000, v24
	v_and_b32_e32 v25, 0x7fffffff, v25
	v_sub_co_u32_e32 v28, vcc, v44, v24
	v_cvt_pk_bf16_f32 v24, v0, v1
	s_nop 1
	v_subb_co_u32_e32 v29, vcc, v45, v25, vcc
	v_lshl_add_u64 v[28:29], v[28:29], 1, s[38:39]
	v_cvt_pk_bf16_f32 v25, v2, v3
	v_cvt_pk_bf16_f32 v26, v8, v9
	v_cvt_pk_bf16_f32 v27, v10, v11
	global_store_dwordx4 v[28:29], v[24:27], off
	s_or_b64 exec, exec, s[8:9]
	s_and_saveexec_b64 s[8:9], s[0:1]
	s_cbranch_execnz .LBB0_943

; DEVI void convert_job(const float* __restrict__ src, bf16* __restrict__ dst, long total, long blen, long dstb, const int wave_u,
;                       const int vb, const int nvb) {
;     ...
;     for (int u = 0; u < 4; ++u) { const long i = i0 + u * step;
;       if (i < total) { a[u] = *(const f32x4*)(src + i); c[u] = *(const f32x4*)(src + i + 4); } }
; #pragma unroll
;     for (int u = 0; u < 4; ++u) { const long i = i0 + u * step;
;       if (i < total) { const long b = i / blen, off = i - b * blen;
;         u32x4 w = {cvtpk(a[u][0], a[u][1]), cvtpk(a[u][2], a[u][3]), cvtpk(c[u][0], c[u][1]), cvtpk(c[u][2], c[u][3])};
;         *reinterpret_cast<u32x4*>(dst + b * dstb + off) = w; } }
.LBB0_943:
	v_ashrrev_i32_e32 v24, 31, v47
	v_lshrrev_b32_e32 v32, 15, v24
	v_lshl_add_u64 v[24:25], v[46:47], 0, v[32:33]
	v_and_b32_e32 v24, 0xfffe0000, v24
	v_and_b32_e32 v25, 0x7fffffff, v25
	v_sub_co_u32_e32 v28, vcc, v46, v24
	v_cvt_pk_bf16_f32 v24, v4, v5
	s_nop 1
	v_subb_co_u32_e32 v29, vcc, v47, v25, vcc
	v_lshl_add_u64 v[28:29], v[28:29], 1, s[38:39]
	v_cvt_pk_bf16_f32 v25, v6, v7
	v_cvt_pk_bf16_f32 v26, v16, v17
	v_cvt_pk_bf16_f32 v27, v18, v19
	global_store_dwordx4 v[28:29], v[24:27], off
	s_or_b64 exec, exec, s[8:9]
	s_and_saveexec_b64 s[0:1], s[6:7]
	s_cbranch_execz .LBB0_932
.LBB0_944:
	v_ashrrev_i32_e32 v24, 31, v49
	v_lshrrev_b32_e32 v32, 15, v24
	v_lshl_add_u64 v[24:25], v[48:49], 0, v[32:33]
	v_and_b32_e32 v24, 0xfffe0000, v24
	v_and_b32_e32 v25, 0x7fffffff, v25
	v_sub_co_u32_e32 v28, vcc, v48, v24
	v_cvt_pk_bf16_f32 v24, v12, v13
	s_nop 1
	v_subb_co_u32_e32 v29, vcc, v49, v25, vcc
	v_lshl_add_u64 v[28:29], v[28:29], 1, s[38:39]
	v_cvt_pk_bf16_f32 v25, v14, v15
	v_cvt_pk_bf16_f32 v26, v20, v21
	v_cvt_pk_bf16_f32 v27, v22, v23
	global_store_dwordx4 v[28:29], v[24:27], off
	s_branch .LBB0_932

; DEVI void zero_job(bf16* __restrict__ dst, long total, long blen, long dstb, const int wave_u) {
;     ...
;   for (long i = ((long)blockIdx.x * 512 + tidc) * 8; i < total; i += (long)gridDim.x * 512 * 8) {
;     const long b = i / blen, off = i - b * blen;
;     unsigned z_ = 0; asm volatile("" : "+v"(z_));
;     *reinterpret_cast<u32x4*>(dst + b * dstb + off) = u32x4{z_, z_, z_, z_};
;   }
.LBB0_947:
	v_ashrrev_i32_e32 v5, 31, v1
	v_lshrrev_b32_e32 v32, 17, v5
	s_waitcnt lgkmcnt(0)
	v_lshl_add_u64 v[8:9], v[0:1], 0, v[32:33]
	v_lshl_add_u64 v[0:1], v[0:1], 0, s[12:13]
	v_ashrrev_i64 v[8:9], 15, v[8:9]
	v_mov_b32_e32 v4, v33
	v_cmp_lt_i64_e32 vcc, s[20:21], v[0:1]
	v_mad_u64_u32 v[10:11], s[8:9], v8, s18, v[2:3]
	v_lshl_add_u64 v[2:3], v[2:3], 0, s[16:17]
	v_mov_b32_e32 v5, v4
	v_mov_b32_e32 v6, v4
	v_mov_b32_e32 v7, v4
	s_or_b64 s[6:7], vcc, s[6:7]
	v_mad_i32_i24 v11, v9, s18, v11
	global_store_dwordx4 v[10:11], v[4:7], off
	s_andn2_b64 exec, exec, s[6:7]
	s_cbranch_execnz .LBB0_947

; DEVI void zero_job(bf16* __restrict__ dst, long total, long blen, long dstb, const int wave_u) {
;     ...
;   for (long i = ((long)blockIdx.x * 512 + tidc) * 8; i < total; i += (long)gridDim.x * 512 * 8) {
;     const long b = i / blen, off = i - b * blen;
;     unsigned z_ = 0; asm volatile("" : "+v"(z_));
;     *reinterpret_cast<u32x4*>(dst + b * dstb + off) = u32x4{z_, z_, z_, z_};
;   }
.LBB0_959:
	v_ashrrev_i32_e32 v5, 31, v1
	v_lshrrev_b32_e32 v32, 21, v5
	s_waitcnt lgkmcnt(0)
	v_lshl_add_u64 v[8:9], v[0:1], 0, v[32:33]
	v_lshl_add_u64 v[0:1], v[0:1], 0, s[12:13]
	v_ashrrev_i64 v[8:9], 11, v[8:9]
	s_mov_b64 s[8:9], 0x7fff
	v_mov_b32_e32 v4, v33
	v_cmp_lt_i64_e32 vcc, s[8:9], v[0:1]
	v_mad_u64_u32 v[10:11], s[8:9], v8, s18, v[2:3]
	v_lshl_add_u64 v[2:3], v[2:3], 0, s[16:17]
	v_mov_b32_e32 v5, v4
	v_mov_b32_e32 v6, v4
	v_mov_b32_e32 v7, v4
	s_or_b64 s[6:7], vcc, s[6:7]
	v_mad_i32_i24 v11, v9, s18, v11
	global_store_dwordx4 v[10:11], v[4:7], off
	s_andn2_b64 exec, exec, s[6:7]
	s_cbranch_execnz .LBB0_959

; DEVI int RSI(int row) { return ((row >> 3) << 5) | (row & 7); }
; DEVI void run_phase(const int ph, const Params& P, char* shmc, const int wave_u) {
;     ...
;       GEMM_IDS
;       const bool samp = bcol >= MP;
;       EPI_SC4(rs0)
;       if (brow < 1024) {
;         EPI_LOOP({ const float sc = sc4[bj][n] * SB_C; st_bf4(sbq + (long)col * 1024 + row, v[0] * sc, v[1] * sc, v[2] * sc, v[3] * sc); })
;       } else if (brow < 3072) {
;         const bool isk = brow < 2048; const int fb = isk ? 1024 : 2048;
;         bf16* dp = isk ? sbk_p : sbv_p; bf16* ds = isk ? sbk_s : sbv_s;
;         float* op = out + (isk ? O_SBK_P : O_SBV_P); float* os = out + (isk ? O_SBK_S : O_SBV_S);
;         EPI_LOOP({ const float sc = sc4[bj][n]; const int f = row - fb; const float a = v[0] * sc, b = v[1] * sc, c = v[2] * sc, d = v[3] * sc;
;           if (!samp) { st_bf4(dp + (long)col * 1024 + f, a, b, c, d); st_f4(op + (long)col * 1024 + f, a, b, c, d); }
;           else { const int s = col - MP; st_bf4(ds + ((long)(s >> 5) * SKS + 1024 + (s & 31)) * 1024 + f, a, b, c, d); st_f4(os + (long)s * 1024 + f, a, b, c, d); } })
;       } else if (brow < 3584) {
;         float ssl[2][2] = {{0.f, 0.f}, {0.f, 0.f}};
;         EPI_LOOP({ const float sc = sc4[bj][n]; const int f = row - 3072; const float a = v[0] * sc, b = v[1] * sc, c = v[2] * sc, d = v[3] * sc;
;           st_bf4(cq + (long)col * 512 + f, a, b, c, d); ssl[bj][n] += a * a + b * b + c * c + d * d; })
; #pragma unroll
;         for (int bj = 0; bj < 2; ++bj)
; #pragma unroll
;           for (int n = 0; n < 2; ++n) { float s = ssl[bj][n]; s += shflx(s, 16, lane); s += shflx(s, 32, lane);
;             if (fq == 0) unsafeAtomicAdd(&ssq[RSI(bcol + bj * 128 + wc * 32 + n * 16 + fr)], s); }
;       } else if (brow < 4096) {
;         EPI_LOOP({ const float sc = sc4[bj][n]; const int f = row - 3584;
;           float* o = samp ? out + O_CKV_S + (long)(col - MP) * 512 + f : out + O_CKV_P + (long)col * 512 + f;
;           st_f4(o, v[0] * sc, v[1] * sc, v[2] * sc, v[3] * sc); })
;       } else if (brow < 8192) {
;         EPI_LOOP({ const float sc = sc4[bj][n]; const int f = row - 4096;
;           st_bf4(gates + (long)col * 4096 + f, sigmoidf_(v[0] * sc), sigmoidf_(v[1] * sc), sigmoidf_(v[2] * sc), sigmoidf_(v[3] * sc)); })
;       } else {
;         if (wr == 0) {
.LBB0_977:
	s_or_b64 exec, exec, s[6:7]
	v_mbcnt_lo_u32_b32 v137, -1, 0
	v_mbcnt_hi_u32_b32 v137, -1, v137
	s_movk_i32 s1, 0xfda0
	v_or_b32_e32 v132, s5, v137
	v_lshrrev_b32_e32 v32, 1, v132
	v_and_b32_e32 v170, 15, v137
	v_and_b32_e32 v32, 0x60, v32
	v_or3_b32 v134, v170, s8, v32
	v_and_b32_e32 v130, 7, v137
	v_lshlrev_b32_e32 v131, 2, v134
	v_and_or_b32 v130, v131, s1, v130
	v_readlane_b32 s6, v255, 35
	v_ashrrev_i32_e32 v131, 31, v130
	v_readlane_b32 s7, v255, 36
	v_bfe_u32 v168, v137, 4, 2
	v_ashrrev_i32_e32 v169, 8, v132
	v_lshl_add_u64 v[144:145], v[130:131], 2, s[6:7]
	global_load_dword v142, v[144:145], off
	global_load_dword v140, v[144:145], off offset:256
	global_load_dword v138, v[144:145], off offset:2048
	global_load_dword v136, v[144:145], off offset:2304
	s_cmp_gt_i32 s73, 3
	s_mov_b64 s[6:7], -1
	s_cbranch_scc0 .LBB0_1152
	s_cmp_gt_i32 s70, 63
	s_cselect_b64 s[6:7], -1, 0
	s_cmp_lt_i32 s70, 64
	s_cselect_b64 s[12:13], -1, 0
	s_cmp_gt_u32 s73, 11
	s_mov_b64 s[38:39], -1
	s_cbranch_scc0 .LBB0_1021
	s_cmp_gt_u32 s73, 13
	s_cbranch_scc0 .LBB0_1010
	s_cmp_gt_u32 s73, 15
	s_cbranch_scc0 .LBB0_1007
	s_cmp_gt_u32 s73, 31
	s_cbranch_scc0 .LBB0_1004
	v_cmp_gt_u32_e32 vcc, s95, v132
	s_and_saveexec_b64 s[18:19], vcc
	s_cbranch_execz .LBB0_1003
	v_or3_b32 v132, s8, v32, v170
	s_mov_b64 s[8:9], -1
	s_and_b64 vcc, exec, s[12:13]
	s_cbranch_vccz .LBB0_985
	v_ashrrev_i32_e32 v133, 31, v132
	s_mov_b64 s[8:9], 0
	v_mov_b64_e32 v[144:145], v[132:133]

; DEVI void rope_cs(int pos, int i, float& c, float& s) {
;   float fr = exp2f(-(float)i * (13.287712379549449f / 32.f));
;   float a = (float)pos * fr;
;   float n = rintf(a * 0.15915494309189535f);
;   float r = fmaf(-n, 6.28125f, a);
;   r = fmaf(-n, 0.0019353071795864769f, r);
;   s = __sinf(r); c = __cosf(r);
; DEVI void run_phase(const int ph, const Params& P, char* shmc, const int wave_u) {
;     ...
;               const int col = bcol + bj * 128 + wc * 32 + n * 16 + fr; const float sc = sc4[bj][n];
;               const int s = col - MP; const int pos = samp ? PAST + (s & 31) : (col & (SEQ - 1));
;               float* o = samp ? out + O_KR_S + (long)s * 64 : out + O_KR_P + (long)col * 64;
;               bf16* ob = samp ? kr_s + ((long)(s >> 5) * SKS + 1024 + (s & 31)) * 64 : kr_p + (long)col * 64;
; #pragma unroll
;               for (int pr = 0; pr < 2; ++pr) {
;                 const f32x4 x1 = acc[0][bj][2 * pr][n], x2 = acc[0][bj][2 * pr + 1][n];
;                 float y1[4], y2[4];
; #pragma unroll
;                 for (int j = 0; j < 4; ++j) { const int i = pr * 16 + fq * 4 + j; float c, sn; rope_cs(pos, i, c, sn);
;                   const float a = x1[j] * sc, b = x2[j] * sc; y1[j] = a * c - b * sn; y2[j] = a * sn + b * c; }
.LBB0_988:
	v_lshlrev_b32_e32 v150, 2, v168
	v_or_b32_e32 v133, 16, v150
	v_cvt_f32_ubyte0_e32 v133, v133
	v_mul_f32_e32 v135, 0xbed49a78, v133
	s_mov_b32 s4, 0xc2fc0000
	v_cmp_gt_f32_e32 vcc, s4, v135
	v_cndmask_b32_e64 v148, v132, v32, s[6:7]
	v_cvt_f32_ubyte0_e32 v32, v150
	v_cndmask_b32_e32 v135, 0, v191, vcc
	v_fmac_f32_e32 v135, 0xbed49a78, v133
	v_exp_f32_e32 v133, v135
	v_mul_f32_e32 v139, 0xbed49a78, v32
	v_cndmask_b32_e32 v135, 0, v190, vcc
	v_cmp_gt_f32_e32 vcc, s4, v139
	v_or_b32_e32 v155, 0x400, v170
	v_ldexp_f32 v133, v133, v135
	v_cndmask_b32_e32 v139, 0, v191, vcc
	v_and_b32_e32 v135, 0xf6f, v132
	v_fmac_f32_e32 v139, 0xbed49a78, v32
	v_cndmask_b32_e64 v135, v135, v155, s[6:7]
	v_exp_f32_e32 v32, v139
	v_cvt_f32_u32_e32 v151, v135
	v_cndmask_b32_e32 v135, 0, v190, vcc
	s_waitcnt vmcnt(0) lgkmcnt(0)
	v_pk_mul_f32 v[160:161], v[126:127], v[142:143] op_sel_hi:[1,0]
	v_ldexp_f32 v135, v32, v135
	v_mul_f32_e32 v32, v135, v151
	v_mul_f32_e32 v139, 0.15915494, v32
	v_rndne_f32_e32 v139, v139
	v_fmac_f32_e32 v32, 0xc0c90000, v139
	v_fmac_f32_e32 v32, 0xbafdaa22, v139
	v_or_b32_e32 v139, 1, v150
	v_cvt_f32_ubyte0_e32 v139, v139
	v_mul_f32_e32 v141, 0xbed49a78, v139
	v_cmp_gt_f32_e32 vcc, s4, v141
	v_mul_f32_e32 v32, 0.15915494, v32
	v_sin_f32_e32 v152, v32
	v_cndmask_b32_e32 v141, 0, v191, vcc
	v_fmac_f32_e32 v141, 0xbed49a78, v139
	v_exp_f32_e32 v139, v141
	v_cos_f32_e32 v158, v32
	v_cndmask_b32_e32 v32, 0, v190, vcc
	v_pk_mul_f32 v[162:163], v[118:119], v[142:143] op_sel_hi:[1,0]
	v_ldexp_f32 v139, v139, v32
	v_mul_f32_e32 v32, v139, v151
	v_mul_f32_e32 v141, 0.15915494, v32
	v_rndne_f32_e32 v141, v141
	v_fmac_f32_e32 v32, 0xc0c90000, v141
	v_fmac_f32_e32 v32, 0xbafdaa22, v141
	v_mul_f32_e32 v32, 0.15915494, v32
	v_sin_f32_e32 v153, v32
	v_cos_f32_e32 v159, v32
	v_or_b32_e32 v32, 2, v150
	v_cvt_f32_ubyte0_e32 v32, v32
	v_mul_f32_e32 v141, 0xbed49a78, v32
	v_cmp_gt_f32_e32 vcc, s4, v141
	v_pk_mul_f32 v[156:157], v[162:163], v[152:153]
	s_and_b64 s[38:39], s[6:7], exec
	v_cndmask_b32_e32 v141, 0, v191, vcc
	v_fmac_f32_e32 v141, 0xbed49a78, v32
	v_exp_f32_e32 v32, v141
	v_cndmask_b32_e32 v141, 0, v190, vcc
	v_pk_fma_f32 v[156:157], v[160:161], v[158:159], v[156:157] neg_lo:[0,0,1] neg_hi:[0,0,1]
	v_pk_mul_f32 v[158:159], v[162:163], v[158:159]
	v_ldexp_f32 v141, v32, v141
	v_mul_f32_e32 v32, v141, v151
	v_mul_f32_e32 v143, 0.15915494, v32
	v_rndne_f32_e32 v143, v143
	v_fmac_f32_e32 v32, 0xc0c90000, v143
	v_fmac_f32_e32 v32, 0xbafdaa22, v143
	v_or_b32_e32 v143, 3, v150
	v_cvt_f32_ubyte0_e32 v143, v143
	v_pk_fma_f32 v[160:161], v[160:161], v[152:153], v[158:159]
	v_mul_f32_e32 v152, 0xbed49a78, v143
	v_cmp_gt_f32_e32 vcc, s4, v152
	v_mul_f32_e32 v32, 0.15915494, v32
	v_cos_f32_e32 v162, v32
	v_cndmask_b32_e32 v152, 0, v191, vcc
	v_fmac_f32_e32 v152, 0xbed49a78, v143
	v_exp_f32_e32 v143, v152
	v_sin_f32_e32 v152, v32
	v_cndmask_b32_e32 v32, 0, v190, vcc
	s_mov_b32 s1, 0x12d00000
	v_ldexp_f32 v143, v143, v32
	v_mul_f32_e32 v32, v143, v151
	v_mul_f32_e32 v153, 0.15915494, v32
	v_rndne_f32_e32 v153, v153
	v_fmac_f32_e32 v32, 0xc0c90000, v153
	v_fmac_f32_e32 v32, 0xbafdaa22, v153
	v_mul_f32_e32 v32, 0.15915494, v32
	s_cselect_b32 s1, s1, 0x12400000
	v_readlane_b32 s16, v255, 13
	v_sin_f32_e32 v153, v32
	v_readlane_b32 s17, v255, 14
	s_add_u32 s38, s16, s1
	v_cos_f32_e32 v163, v32
	s_addc_u32 s39, s17, 0
	v_ashrrev_i32_e32 v149, 31, v148
	v_lshlrev_b64 v[148:149], 8, v[148:149]
	s_add_u32 s8, s66, s8
	v_pk_mul_f32 v[166:167], v[120:121], v[142:143] op_sel_hi:[1,0]
	v_lshl_add_u64 v[148:149], s[38:39], 0, v[148:149]
	s_addc_u32 s9, s67, s9
	v_lshlrev_b64 v[144:145], 7, v[144:145]
	v_pk_mul_f32 v[164:165], v[128:129], v[142:143] op_sel_hi:[1,0]
	v_pk_mul_f32 v[158:159], v[166:167], v[152:153]
	v_lshlrev_b32_e32 v32, 4, v168
	v_lshl_add_u64 v[144:145], s[8:9], 0, v[144:145]
	v_pk_fma_f32 v[158:159], v[164:165], v[162:163], v[158:159] neg_lo:[0,0,1] neg_hi:[0,0,1]
	v_pk_mul_f32 v[162:163], v[166:167], v[162:163]
; DEVI void rope_cs(int pos, int i, float& c, float& s) {
;   float fr = exp2f(-(float)i * (13.287712379549449f / 32.f));
;   float a = (float)pos * fr;
;   float n = rintf(a * 0.15915494309189535f);
;   float r = fmaf(-n, 6.28125f, a);
;   r = fmaf(-n, 0.0019353071795864769f, r);
;   s = __sinf(r); c = __cosf(r);
; DEVI void run_phase(const int ph, const Params& P, char* shmc, const int wave_u) {
;     ...
;               for (int pr = 0; pr < 2; ++pr) {
;                 const f32x4 x1 = acc[0][bj][2 * pr][n], x2 = acc[0][bj][2 * pr + 1][n];
;                 float y1[4], y2[4];
; #pragma unroll
;                 for (int j = 0; j < 4; ++j) { const int i = pr * 16 + fq * 4 + j; float c, sn; rope_cs(pos, i, c, sn);
;                   const float a = x1[j] * sc, b = x2[j] * sc; y1[j] = a * c - b * sn; y2[j] = a * sn + b * c; }
;                 const int i0 = pr * 16 + fq * 4;
;                 st_f4(o + i0, y1[0], y1[1], y1[2], y1[3]); st_f4(o + 32 + i0, y2[0], y2[1], y2[2], y2[3]);
;                 st_bf4(ob + i0, y1[0], y1[1], y1[2], y1[3]); st_bf4(ob + 32 + i0, y2[0], y2[1], y2[2], y2[3]);
;                 __builtin_amdgcn_sched_barrier(0);
	v_lshl_add_u64 v[148:149], v[148:149], 0, v[32:33]
	v_lshlrev_b32_e32 v32, 3, v168
	v_pk_fma_f32 v[162:163], v[164:165], v[152:153], v[162:163]
	global_store_dwordx4 v[148:149], v[156:159], off
	global_store_dwordx4 v[148:149], v[160:163], off offset:128
	v_lshl_add_u64 v[144:145], v[144:145], 0, v[32:33]
	v_cvt_pk_bf16_f32 v152, v156, v157
	v_cvt_pk_bf16_f32 v153, v158, v159
	global_store_dwordx2 v[144:145], v[152:153], off
	v_cvt_pk_bf16_f32 v152, v160, v161
	v_cvt_pk_bf16_f32 v153, v162, v163
	global_store_dwordx2 v[144:145], v[152:153], off offset:64
	v_mul_f32_e32 v32, v133, v151
	v_mul_f32_e32 v152, 0.15915494, v32
	v_rndne_f32_e32 v152, v152
	v_fmac_f32_e32 v32, 0xc0c90000, v152
	v_fmac_f32_e32 v32, 0xbafdaa22, v152
	v_or_b32_e32 v152, 17, v150
	v_cvt_f32_ubyte0_e32 v152, v152
	v_mul_f32_e32 v153, 0xbed49a78, v152
	v_cmp_gt_f32_e32 vcc, s4, v153
	v_mul_f32_e32 v32, 0.15915494, v32
	v_sin_f32_e32 v158, v32
	v_cndmask_b32_e32 v153, 0, v191, vcc
	v_fmac_f32_e32 v153, 0xbed49a78, v152
	v_exp_f32_e32 v152, v153
	v_cos_f32_e32 v160, v32
	v_cndmask_b32_e32 v32, 0, v190, vcc
	v_pk_mul_f32 v[164:165], v[102:103], v[142:143] op_sel_hi:[1,0]
	v_ldexp_f32 v152, v152, v32
	v_mul_f32_e32 v32, v152, v151
	v_mul_f32_e32 v153, 0.15915494, v32
	v_rndne_f32_e32 v153, v153
	v_fmac_f32_e32 v32, 0xc0c90000, v153
	v_fmac_f32_e32 v32, 0xbafdaa22, v153
	v_mul_f32_e32 v32, 0.15915494, v32
	v_sin_f32_e32 v159, v32
	v_cos_f32_e32 v161, v32
	v_or_b32_e32 v32, 18, v150
	v_cvt_f32_ubyte0_e32 v32, v32
	v_mul_f32_e32 v153, 0xbed49a78, v32
	v_cmp_gt_f32_e32 vcc, s4, v153
	v_pk_mul_f32 v[162:163], v[110:111], v[142:143] op_sel_hi:[1,0]
	v_pk_mul_f32 v[156:157], v[164:165], v[158:159]
	v_cndmask_b32_e32 v153, 0, v191, vcc
	v_fmac_f32_e32 v153, 0xbed49a78, v32
	v_exp_f32_e32 v32, v153
	v_cndmask_b32_e32 v153, 0, v190, vcc
	v_pk_fma_f32 v[156:157], v[162:163], v[160:161], v[156:157] neg_lo:[0,0,1] neg_hi:[0,0,1]
	v_pk_mul_f32 v[160:161], v[164:165], v[160:161]
	v_ldexp_f32 v153, v32, v153
	v_mul_f32_e32 v32, v153, v151
	v_mul_f32_e32 v154, 0.15915494, v32
	v_rndne_f32_e32 v154, v154
	v_fmac_f32_e32 v32, 0xc0c90000, v154
	v_fmac_f32_e32 v32, 0xbafdaa22, v154
	v_or_b32_e32 v154, 19, v150
	v_cvt_f32_ubyte0_e32 v154, v154
	v_pk_fma_f32 v[160:161], v[162:163], v[158:159], v[160:161]
	v_mul_f32_e32 v158, 0xbed49a78, v154
	v_cmp_gt_f32_e32 vcc, s4, v158
	v_mul_f32_e32 v32, 0.15915494, v32
	v_sin_f32_e32 v162, v32
	v_cndmask_b32_e32 v158, 0, v191, vcc
	v_fmac_f32_e32 v158, 0xbed49a78, v154
	v_exp_f32_e32 v154, v158
	v_cos_f32_e32 v164, v32
	v_cndmask_b32_e32 v32, 0, v190, vcc
	v_pk_mul_f32 v[172:173], v[104:105], v[142:143] op_sel_hi:[1,0]
	v_ldexp_f32 v154, v154, v32
	v_mul_f32_e32 v32, v154, v151
	v_mul_f32_e32 v151, 0.15915494, v32
	v_rndne_f32_e32 v151, v151
	v_fmac_f32_e32 v32, 0xc0c90000, v151
	v_fmac_f32_e32 v32, 0xbafdaa22, v151
	v_mul_f32_e32 v32, 0.15915494, v32
	v_sin_f32_e32 v163, v32
	v_cos_f32_e32 v165, v32
	v_pk_mul_f32 v[166:167], v[112:113], v[142:143] op_sel_hi:[1,0]
	v_pk_mul_f32 v[158:159], v[172:173], v[162:163]
	s_nop 0
	v_pk_fma_f32 v[158:159], v[166:167], v[164:165], v[158:159] neg_lo:[0,0,1] neg_hi:[0,0,1]
	v_pk_mul_f32 v[164:165], v[172:173], v[164:165]
	s_nop 0
	v_pk_fma_f32 v[162:163], v[166:167], v[162:163], v[164:165]
	global_store_dwordx4 v[148:149], v[156:159], off offset:64
	global_store_dwordx4 v[148:149], v[160:163], off offset:192
	v_cvt_pk_bf16_f32 v148, v156, v157
	v_cvt_pk_bf16_f32 v149, v158, v159
	global_store_dwordx2 v[144:145], v[148:149], off offset:32
	v_cvt_pk_bf16_f32 v148, v160, v161
	v_cvt_pk_bf16_f32 v149, v162, v163
	global_store_dwordx2 v[144:145], v[148:149], off offset:96
	v_cndmask_b32_e64 v32, 0, 1, s[12:13]
	v_or_b32_e32 v144, 16, v132
	v_cmp_ne_u32_e64 s[8:9], 1, v32
	s_andn2_b64 vcc, exec, s[12:13]
	s_mov_b64 s[38:39], -1
	s_cbranch_vccnz .LBB0_990
	v_ashrrev_i32_e32 v145, 31, v144
	s_mov_b64 s[38:39], 0
	v_mov_b64_e32 v[148:149], v[144:145]

; DEVI void rope_cs(int pos, int i, float& c, float& s) {
;   float fr = exp2f(-(float)i * (13.287712379549449f / 32.f));
;   float a = (float)pos * fr;
;   float n = rintf(a * 0.15915494309189535f);
;   float r = fmaf(-n, 6.28125f, a);
;   r = fmaf(-n, 0.0019353071795864769f, r);
;   s = __sinf(r); c = __cosf(r);
; DEVI void run_phase(const int ph, const Params& P, char* shmc, const int wave_u) {
;     ...
;             for (int n = 0; n < 2; ++n) {
;               const int col = bcol + bj * 128 + wc * 32 + n * 16 + fr; const float sc = sc4[bj][n];
;               const int s = col - MP; const int pos = samp ? PAST + (s & 31) : (col & (SEQ - 1));
;               float* o = samp ? out + O_KR_S + (long)s * 64 : out + O_KR_P + (long)col * 64;
;               bf16* ob = samp ? kr_s + ((long)(s >> 5) * SKS + 1024 + (s & 31)) * 64 : kr_p + (long)col * 64;
; #pragma unroll
;               for (int pr = 0; pr < 2; ++pr) {
;                 const f32x4 x1 = acc[0][bj][2 * pr][n], x2 = acc[0][bj][2 * pr + 1][n];
;                 float y1[4], y2[4];
; #pragma unroll
;                 for (int j = 0; j < 4; ++j) { const int i = pr * 16 + fq * 4 + j; float c, sn; rope_cs(pos, i, c, sn);
;                   const float a = x1[j] * sc, b = x2[j] * sc; y1[j] = a * c - b * sn; y2[j] = a * sn + b * c; }
;                 const int i0 = pr * 16 + fq * 4;
;                 st_f4(o + i0, y1[0], y1[1], y1[2], y1[3]); st_f4(o + 32 + i0, y2[0], y2[1], y2[2], y2[3]);
;                 st_bf4(ob + i0, y1[0], y1[1], y1[2], y1[3]); st_bf4(ob + 32 + i0, y2[0], y2[1], y2[2], y2[3]);
;                 __builtin_amdgcn_sched_barrier(0);
.LBB0_993:
	v_or_b32_e32 v157, 0x410, v170
	v_and_b32_e32 v145, 0xf7f, v144
	v_cndmask_b32_e64 v151, v145, v157, s[6:7]
	v_cvt_f32_u32_e32 v171, v151
	v_cndmask_b32_e64 v144, v144, v32, s[6:7]
	v_pk_mul_f32 v[166:167], v[114:115], v[140:141] op_sel_hi:[1,0]
	v_pk_mul_f32 v[164:165], v[122:123], v[140:141] op_sel_hi:[1,0]
	v_mul_f32_e32 v32, v135, v171
	v_mul_f32_e32 v151, 0.15915494, v32
	v_rndne_f32_e32 v151, v151
	v_fmac_f32_e32 v32, 0xc0c90000, v151
	v_fmac_f32_e32 v32, 0xbafdaa22, v151
	v_mul_f32_e32 v32, 0.15915494, v32
	v_sin_f32_e32 v160, v32
	v_cos_f32_e32 v162, v32
	v_mul_f32_e32 v32, v139, v171
	v_mul_f32_e32 v151, 0.15915494, v32
	v_rndne_f32_e32 v151, v151
	v_fmac_f32_e32 v32, 0xc0c90000, v151
	v_fmac_f32_e32 v32, 0xbafdaa22, v151
	v_mul_f32_e32 v32, 0.15915494, v32
	v_sin_f32_e32 v161, v32
	v_cos_f32_e32 v163, v32
	v_mul_f32_e32 v32, v141, v171
	v_mul_f32_e32 v151, 0.15915494, v32
	v_rndne_f32_e32 v151, v151
	v_fmac_f32_e32 v32, 0xc0c90000, v151
	v_pk_mul_f32 v[158:159], v[166:167], v[160:161]
	v_fmac_f32_e32 v32, 0xbafdaa22, v151
	v_pk_fma_f32 v[158:159], v[164:165], v[162:163], v[158:159] neg_lo:[0,0,1] neg_hi:[0,0,1]
	v_pk_mul_f32 v[162:163], v[166:167], v[162:163]
	v_mul_f32_e32 v32, 0.15915494, v32
	v_pk_fma_f32 v[162:163], v[164:165], v[160:161], v[162:163]
	v_sin_f32_e32 v164, v32
	v_cos_f32_e32 v166, v32
	v_mul_f32_e32 v32, v143, v171
	v_mul_f32_e32 v151, 0.15915494, v32
	v_rndne_f32_e32 v151, v151
	v_fmac_f32_e32 v32, 0xc0c90000, v151
	v_fmac_f32_e32 v32, 0xbafdaa22, v151
	v_mul_f32_e32 v32, 0.15915494, v32
	v_sin_f32_e32 v165, v32
	v_readlane_b32 s16, v255, 13
	v_cos_f32_e32 v167, v32
	v_readlane_b32 s17, v255, 14
	s_add_u32 s68, s16, s68
	v_ashrrev_i32_e32 v145, 31, v144
	s_addc_u32 s69, s17, s69
	v_lshlrev_b64 v[144:145], 8, v[144:145]
	v_pk_mul_f32 v[174:175], v[116:117], v[140:141] op_sel_hi:[1,0]
	v_lshl_add_u64 v[144:145], s[68:69], 0, v[144:145]
	s_add_u32 s68, s66, s70
	v_pk_mul_f32 v[172:173], v[124:125], v[140:141] op_sel_hi:[1,0]
	v_pk_mul_f32 v[160:161], v[174:175], v[164:165]
	s_addc_u32 s69, s67, s71
	v_lshlrev_b64 v[148:149], 7, v[148:149]
	v_pk_fma_f32 v[160:161], v[172:173], v[166:167], v[160:161] neg_lo:[0,0,1] neg_hi:[0,0,1]
	v_pk_mul_f32 v[166:167], v[174:175], v[166:167]
	v_lshlrev_b32_e32 v32, 2, v150
	v_lshl_add_u64 v[148:149], s[68:69], 0, v[148:149]
	v_pk_fma_f32 v[164:165], v[172:173], v[164:165], v[166:167]
	v_lshl_add_u64 v[166:167], v[144:145], 0, v[32:33]
	v_lshlrev_b32_e32 v144, 1, v150
	v_mov_b32_e32 v145, v33
	global_store_dwordx4 v[166:167], v[158:161], off
	global_store_dwordx4 v[166:167], v[162:165], off offset:128
	v_lshl_add_u64 v[172:173], v[148:149], 0, v[144:145]
	v_cvt_pk_bf16_f32 v148, v158, v159
	v_cvt_pk_bf16_f32 v149, v160, v161
	global_store_dwordx2 v[172:173], v[148:149], off
	v_cvt_pk_bf16_f32 v148, v162, v163
	v_cvt_pk_bf16_f32 v149, v164, v165
	global_store_dwordx2 v[172:173], v[148:149], off offset:64
	v_mul_f32_e32 v145, v133, v171
	v_mul_f32_e32 v148, 0.15915494, v145
	v_rndne_f32_e32 v148, v148
	v_fmac_f32_e32 v145, 0xc0c90000, v148
	v_fmac_f32_e32 v145, 0xbafdaa22, v148
	v_mul_f32_e32 v145, 0.15915494, v145
	v_sin_f32_e32 v150, v145
	v_cos_f32_e32 v158, v145
	v_mul_f32_e32 v145, v152, v171
	v_mul_f32_e32 v148, 0.15915494, v145
	v_rndne_f32_e32 v148, v148
	v_fmac_f32_e32 v145, 0xc0c90000, v148
	v_fmac_f32_e32 v145, 0xbafdaa22, v148
	v_mul_f32_e32 v145, 0.15915494, v145
	v_sin_f32_e32 v151, v145
	v_cos_f32_e32 v159, v145
	v_pk_mul_f32 v[162:163], v[98:99], v[140:141] op_sel_hi:[1,0]
	v_pk_mul_f32 v[160:161], v[106:107], v[140:141] op_sel_hi:[1,0]
	v_pk_mul_f32 v[148:149], v[162:163], v[150:151]
	v_mul_f32_e32 v145, v153, v171
	v_pk_fma_f32 v[148:149], v[160:161], v[158:159], v[148:149] neg_lo:[0,0,1] neg_hi:[0,0,1]
	v_pk_mul_f32 v[158:159], v[162:163], v[158:159]
	v_pk_mul_f32 v[174:175], v[100:101], v[140:141] op_sel_hi:[1,0]
	v_pk_fma_f32 v[158:159], v[160:161], v[150:151], v[158:159]
	v_mul_f32_e32 v150, 0.15915494, v145
	v_rndne_f32_e32 v150, v150
	v_fmac_f32_e32 v145, 0xc0c90000, v150
	v_fmac_f32_e32 v145, 0xbafdaa22, v150
	v_mul_f32_e32 v145, 0.15915494, v145
	v_sin_f32_e32 v160, v145
	v_cos_f32_e32 v162, v145
	v_mul_f32_e32 v145, v154, v171
	v_mul_f32_e32 v150, 0.15915494, v145
	v_rndne_f32_e32 v150, v150
	v_fmac_f32_e32 v145, 0xc0c90000, v150
	v_fmac_f32_e32 v145, 0xbafdaa22, v150
	v_mul_f32_e32 v145, 0.15915494, v145
	v_sin_f32_e32 v161, v145
	v_cos_f32_e32 v163, v145
	v_pk_mul_f32 v[164:165], v[108:109], v[140:141] op_sel_hi:[1,0]
	v_pk_mul_f32 v[150:151], v[174:175], v[160:161]
	s_nop 0
	v_pk_fma_f32 v[150:151], v[164:165], v[162:163], v[150:151] neg_lo:[0,0,1] neg_hi:[0,0,1]
	v_pk_mul_f32 v[162:163], v[174:175], v[162:163]
	s_nop 0
	v_pk_fma_f32 v[160:161], v[164:165], v[160:161], v[162:163]
	global_store_dwordx4 v[166:167], v[148:151], off offset:64
	global_store_dwordx4 v[166:167], v[158:161], off offset:192
	s_nop 0
	v_cvt_pk_bf16_f32 v148, v148, v149
	v_cvt_pk_bf16_f32 v149, v150, v151
	global_store_dwordx2 v[172:173], v[148:149], off offset:32
	v_cvt_pk_bf16_f32 v148, v158, v159
	v_cvt_pk_bf16_f32 v149, v160, v161
	global_store_dwordx2 v[172:173], v[148:149], off offset:96
	v_or_b32_e32 v148, 0x80, v132
	s_and_b64 vcc, exec, s[8:9]
	s_mov_b64 s[68:69], -1
	s_cbranch_vccnz .LBB0_995
	v_ashrrev_i32_e32 v149, 31, v148
	s_mov_b64 s[68:69], 0
	v_mov_b64_e32 v[150:151], v[148:149]

; DEVI void rope_cs(int pos, int i, float& c, float& s) {
;   float fr = exp2f(-(float)i * (13.287712379549449f / 32.f));
;   float a = (float)pos * fr;
;   float n = rintf(a * 0.15915494309189535f);
;   float r = fmaf(-n, 6.28125f, a);
;   r = fmaf(-n, 0.0019353071795864769f, r);
;   s = __sinf(r); c = __cosf(r);
; DEVI void run_phase(const int ph, const Params& P, char* shmc, const int wave_u) {
;     ...
;             for (int n = 0; n < 2; ++n) {
;               const int col = bcol + bj * 128 + wc * 32 + n * 16 + fr; const float sc = sc4[bj][n];
;               const int s = col - MP; const int pos = samp ? PAST + (s & 31) : (col & (SEQ - 1));
;               float* o = samp ? out + O_KR_S + (long)s * 64 : out + O_KR_P + (long)col * 64;
;               bf16* ob = samp ? kr_s + ((long)(s >> 5) * SKS + 1024 + (s & 31)) * 64 : kr_p + (long)col * 64;
; #pragma unroll
;               for (int pr = 0; pr < 2; ++pr) {
;                 const f32x4 x1 = acc[0][bj][2 * pr][n], x2 = acc[0][bj][2 * pr + 1][n];
;                 float y1[4], y2[4];
; #pragma unroll
;                 for (int j = 0; j < 4; ++j) { const int i = pr * 16 + fq * 4 + j; float c, sn; rope_cs(pos, i, c, sn);
;                   const float a = x1[j] * sc, b = x2[j] * sc; y1[j] = a * c - b * sn; y2[j] = a * sn + b * c; }
;                 const int i0 = pr * 16 + fq * 4;
;                 st_f4(o + i0, y1[0], y1[1], y1[2], y1[3]); st_f4(o + 32 + i0, y2[0], y2[1], y2[2], y2[3]);
;                 st_bf4(ob + i0, y1[0], y1[1], y1[2], y1[3]); st_bf4(ob + 32 + i0, y2[0], y2[1], y2[2], y2[3]);
;                 __builtin_amdgcn_sched_barrier(0);
.LBB0_998:
	v_and_b32_e32 v149, 0xfef, v148
	v_cndmask_b32_e64 v155, v149, v155, s[6:7]
	v_readlane_b32 s16, v255, 13
	v_cndmask_b32_e64 v148, v148, v145, s[6:7]
	v_cvt_f32_u32_e32 v155, v155
	v_readlane_b32 s17, v255, 14
	s_add_u32 s38, s16, s38
	v_ashrrev_i32_e32 v149, 31, v148
	s_addc_u32 s39, s17, s39
	v_lshlrev_b64 v[148:149], 8, v[148:149]
	v_lshl_add_u64 v[162:163], s[38:39], 0, v[148:149]
	s_add_u32 s38, s66, s70
	s_addc_u32 s39, s67, s71
	v_lshlrev_b64 v[148:149], 7, v[150:151]
	v_mul_f32_e32 v145, v135, v155
	v_lshl_add_u64 v[164:165], s[38:39], 0, v[148:149]
	v_mul_f32_e32 v148, 0.15915494, v145
	v_rndne_f32_e32 v148, v148
	v_fmac_f32_e32 v145, 0xc0c90000, v148
	v_fmac_f32_e32 v145, 0xbafdaa22, v148
	v_mul_f32_e32 v145, 0.15915494, v145
	v_sin_f32_e32 v150, v145
	v_cos_f32_e32 v158, v145
	v_mul_f32_e32 v145, v139, v155
	v_mul_f32_e32 v148, 0.15915494, v145
	v_rndne_f32_e32 v148, v148
	v_fmac_f32_e32 v145, 0xc0c90000, v148
	v_fmac_f32_e32 v145, 0xbafdaa22, v148
	v_mul_f32_e32 v145, 0.15915494, v145
	v_sin_f32_e32 v151, v145
	v_cos_f32_e32 v159, v145
	v_pk_mul_f32 v[166:167], v[86:87], v[138:139] op_sel_hi:[1,0]
	v_pk_mul_f32 v[160:161], v[94:95], v[138:139] op_sel_hi:[1,0]
	v_pk_mul_f32 v[148:149], v[166:167], v[150:151]
	v_mul_f32_e32 v145, v141, v155
	v_pk_fma_f32 v[148:149], v[160:161], v[158:159], v[148:149] neg_lo:[0,0,1] neg_hi:[0,0,1]
	v_pk_mul_f32 v[158:159], v[166:167], v[158:159]
	v_pk_mul_f32 v[174:175], v[88:89], v[138:139] op_sel_hi:[1,0]
	v_pk_fma_f32 v[158:159], v[160:161], v[150:151], v[158:159]
	v_mul_f32_e32 v150, 0.15915494, v145
	v_rndne_f32_e32 v150, v150
	v_fmac_f32_e32 v145, 0xc0c90000, v150
	v_fmac_f32_e32 v145, 0xbafdaa22, v150
	v_mul_f32_e32 v145, 0.15915494, v145
	v_sin_f32_e32 v160, v145
	v_cos_f32_e32 v166, v145
	v_mul_f32_e32 v145, v143, v155
	v_mul_f32_e32 v150, 0.15915494, v145
	v_rndne_f32_e32 v150, v150
	v_fmac_f32_e32 v145, 0xc0c90000, v150
	v_fmac_f32_e32 v145, 0xbafdaa22, v150
	v_mul_f32_e32 v145, 0.15915494, v145
	v_sin_f32_e32 v161, v145
	v_cos_f32_e32 v167, v145
	v_pk_mul_f32 v[172:173], v[96:97], v[138:139] op_sel_hi:[1,0]
	v_lshl_add_u64 v[162:163], v[162:163], 0, v[32:33]
	v_pk_mul_f32 v[150:151], v[174:175], v[160:161]
	v_mov_b32_e32 v145, v33
	v_pk_fma_f32 v[150:151], v[172:173], v[166:167], v[150:151] neg_lo:[0,0,1] neg_hi:[0,0,1]
	v_pk_mul_f32 v[166:167], v[174:175], v[166:167]
	v_lshl_add_u64 v[164:165], v[164:165], 0, v[144:145]
	v_pk_fma_f32 v[160:161], v[172:173], v[160:161], v[166:167]
	global_store_dwordx4 v[162:163], v[148:151], off
	global_store_dwordx4 v[162:163], v[158:161], off offset:128
	s_nop 0
	v_cvt_pk_bf16_f32 v148, v148, v149
	v_cvt_pk_bf16_f32 v149, v150, v151
	global_store_dwordx2 v[164:165], v[148:149], off
	v_cvt_pk_bf16_f32 v148, v158, v159
	v_cvt_pk_bf16_f32 v149, v160, v161
	global_store_dwordx2 v[164:165], v[148:149], off offset:64
	v_mul_f32_e32 v145, v133, v155
	v_mul_f32_e32 v148, 0.15915494, v145
	v_rndne_f32_e32 v148, v148
	v_fmac_f32_e32 v145, 0xc0c90000, v148
	v_fmac_f32_e32 v145, 0xbafdaa22, v148
	v_mul_f32_e32 v145, 0.15915494, v145
	v_sin_f32_e32 v150, v145
	v_cos_f32_e32 v158, v145
	v_mul_f32_e32 v145, v152, v155
	v_mul_f32_e32 v148, 0.15915494, v145
	v_rndne_f32_e32 v148, v148
	v_fmac_f32_e32 v145, 0xc0c90000, v148
	v_fmac_f32_e32 v145, 0xbafdaa22, v148
	v_mul_f32_e32 v145, 0.15915494, v145
	v_sin_f32_e32 v151, v145
	v_cos_f32_e32 v159, v145
	v_pk_mul_f32 v[166:167], v[70:71], v[138:139] op_sel_hi:[1,0]
	v_pk_mul_f32 v[160:161], v[78:79], v[138:139] op_sel_hi:[1,0]
	v_pk_mul_f32 v[148:149], v[166:167], v[150:151]
	v_mul_f32_e32 v145, v153, v155
	v_pk_fma_f32 v[148:149], v[160:161], v[158:159], v[148:149] neg_lo:[0,0,1] neg_hi:[0,0,1]
	v_pk_mul_f32 v[158:159], v[166:167], v[158:159]
	v_pk_mul_f32 v[174:175], v[72:73], v[138:139] op_sel_hi:[1,0]
	v_pk_fma_f32 v[158:159], v[160:161], v[150:151], v[158:159]
	v_mul_f32_e32 v150, 0.15915494, v145
	v_rndne_f32_e32 v150, v150
	v_fmac_f32_e32 v145, 0xc0c90000, v150
	v_fmac_f32_e32 v145, 0xbafdaa22, v150
	v_mul_f32_e32 v145, 0.15915494, v145
	v_sin_f32_e32 v160, v145
	v_cos_f32_e32 v166, v145
	v_mul_f32_e32 v145, v154, v155
	v_mul_f32_e32 v150, 0.15915494, v145
	v_rndne_f32_e32 v150, v150
	v_fmac_f32_e32 v145, 0xc0c90000, v150
	v_fmac_f32_e32 v145, 0xbafdaa22, v150
	v_mul_f32_e32 v145, 0.15915494, v145
	v_sin_f32_e32 v161, v145
	v_cos_f32_e32 v167, v145
	v_pk_mul_f32 v[172:173], v[80:81], v[138:139] op_sel_hi:[1,0]
	v_pk_mul_f32 v[150:151], v[174:175], v[160:161]
	s_nop 0
	v_pk_fma_f32 v[150:151], v[172:173], v[166:167], v[150:151] neg_lo:[0,0,1] neg_hi:[0,0,1]
	v_pk_mul_f32 v[166:167], v[174:175], v[166:167]
	s_nop 0
	v_pk_fma_f32 v[160:161], v[172:173], v[160:161], v[166:167]
	global_store_dwordx4 v[162:163], v[148:151], off offset:64
	global_store_dwordx4 v[162:163], v[158:161], off offset:192
	s_nop 0
	v_cvt_pk_bf16_f32 v148, v148, v149
	v_cvt_pk_bf16_f32 v149, v150, v151
	global_store_dwordx2 v[164:165], v[148:149], off offset:32
	v_cvt_pk_bf16_f32 v148, v158, v159
	v_cvt_pk_bf16_f32 v149, v160, v161
	global_store_dwordx2 v[164:165], v[148:149], off offset:96
	v_or_b32_e32 v148, 0x90, v132
	s_and_b64 vcc, exec, s[8:9]
	s_mov_b64 s[8:9], -1
	s_cbranch_vccnz .LBB0_1000
	v_ashrrev_i32_e32 v149, 31, v148
	s_mov_b64 s[8:9], 0
	v_mov_b64_e32 v[150:151], v[148:149]

; DEVI void rope_cs(int pos, int i, float& c, float& s) {
;   float fr = exp2f(-(float)i * (13.287712379549449f / 32.f));
;   float a = (float)pos * fr;
;   float n = rintf(a * 0.15915494309189535f);
;   float r = fmaf(-n, 6.28125f, a);
;   r = fmaf(-n, 0.0019353071795864769f, r);
;   s = __sinf(r); c = __cosf(r);
; DEVI void run_phase(const int ph, const Params& P, char* shmc, const int wave_u) {
;     ...
;             for (int n = 0; n < 2; ++n) {
;               const int col = bcol + bj * 128 + wc * 32 + n * 16 + fr; const float sc = sc4[bj][n];
;               const int s = col - MP; const int pos = samp ? PAST + (s & 31) : (col & (SEQ - 1));
;               float* o = samp ? out + O_KR_S + (long)s * 64 : out + O_KR_P + (long)col * 64;
;               bf16* ob = samp ? kr_s + ((long)(s >> 5) * SKS + 1024 + (s & 31)) * 64 : kr_p + (long)col * 64;
; #pragma unroll
;               for (int pr = 0; pr < 2; ++pr) {
;                 const f32x4 x1 = acc[0][bj][2 * pr][n], x2 = acc[0][bj][2 * pr + 1][n];
;                 float y1[4], y2[4];
; #pragma unroll
;                 for (int j = 0; j < 4; ++j) { const int i = pr * 16 + fq * 4 + j; float c, sn; rope_cs(pos, i, c, sn);
;                   const float a = x1[j] * sc, b = x2[j] * sc; y1[j] = a * c - b * sn; y2[j] = a * sn + b * c; }
;                 const int i0 = pr * 16 + fq * 4;
;                 st_f4(o + i0, y1[0], y1[1], y1[2], y1[3]); st_f4(o + 32 + i0, y2[0], y2[1], y2[2], y2[3]);
;                 st_bf4(ob + i0, y1[0], y1[1], y1[2], y1[3]); st_bf4(ob + 32 + i0, y2[0], y2[1], y2[2], y2[3]);
;                 __builtin_amdgcn_sched_barrier(0);
.LBB0_1002:
	v_and_b32_e32 v145, 0xfff, v148
	v_cndmask_b32_e64 v145, v145, v157, s[6:7]
	v_cvt_f32_u32_e32 v155, v145
	v_cndmask_b32_e64 v148, v148, v132, s[6:7]
	v_readlane_b32 s16, v255, 13
	v_readlane_b32 s17, v255, 14
	v_mul_f32_e32 v132, v135, v155
	v_mul_f32_e32 v135, 0.15915494, v132
	v_rndne_f32_e32 v135, v135
	v_fmac_f32_e32 v132, 0xc0c90000, v135
	s_add_u32 s38, s16, s68
	v_ashrrev_i32_e32 v149, 31, v148
	v_fmac_f32_e32 v132, 0xbafdaa22, v135
	s_addc_u32 s39, s17, s69
	v_lshlrev_b64 v[148:149], 8, v[148:149]
	v_mul_f32_e32 v132, 0.15915494, v132
	v_lshl_add_u64 v[160:161], s[38:39], 0, v[148:149]
	v_lshlrev_b64 v[148:149], 7, v[150:151]
	v_sin_f32_e32 v150, v132
	v_cos_f32_e32 v156, v132
	v_mul_f32_e32 v132, v139, v155
	v_mul_f32_e32 v135, 0.15915494, v132
	v_rndne_f32_e32 v135, v135
	v_fmac_f32_e32 v132, 0xc0c90000, v135
	v_fmac_f32_e32 v132, 0xbafdaa22, v135
	v_mul_f32_e32 v132, 0.15915494, v132
	v_sin_f32_e32 v151, v132
	v_cos_f32_e32 v157, v132
	v_mul_f32_e32 v132, v141, v155
	v_mul_f32_e32 v135, 0.15915494, v132
	s_add_u32 s8, s66, s8
	v_rndne_f32_e32 v135, v135
	s_addc_u32 s9, s67, s9
	v_pk_mul_f32 v[164:165], v[82:83], v[136:137] op_sel_hi:[1,0]
	v_fmac_f32_e32 v132, 0xc0c90000, v135
	v_lshl_add_u64 v[162:163], s[8:9], 0, v[148:149]
	v_pk_mul_f32 v[158:159], v[90:91], v[136:137] op_sel_hi:[1,0]
	v_pk_mul_f32 v[148:149], v[164:165], v[150:151]
	v_fmac_f32_e32 v132, 0xbafdaa22, v135
	v_pk_fma_f32 v[148:149], v[158:159], v[156:157], v[148:149] neg_lo:[0,0,1] neg_hi:[0,0,1]
	v_pk_mul_f32 v[156:157], v[164:165], v[156:157]
	v_mul_f32_e32 v132, 0.15915494, v132
	v_pk_fma_f32 v[156:157], v[158:159], v[150:151], v[156:157]
	v_sin_f32_e32 v158, v132
	v_cos_f32_e32 v164, v132
	v_mul_f32_e32 v132, v143, v155
	v_mul_f32_e32 v135, 0.15915494, v132
	v_rndne_f32_e32 v135, v135
	v_fmac_f32_e32 v132, 0xc0c90000, v135
	v_fmac_f32_e32 v132, 0xbafdaa22, v135
	v_mul_f32_e32 v132, 0.15915494, v132
	v_sin_f32_e32 v159, v132
	v_cos_f32_e32 v165, v132
	v_pk_mul_f32 v[172:173], v[84:85], v[136:137] op_sel_hi:[1,0]
	v_pk_mul_f32 v[166:167], v[92:93], v[136:137] op_sel_hi:[1,0]
	v_pk_mul_f32 v[150:151], v[172:173], v[158:159]
	v_lshl_add_u64 v[160:161], v[160:161], 0, v[32:33]
	v_pk_fma_f32 v[150:151], v[166:167], v[164:165], v[150:151] neg_lo:[0,0,1] neg_hi:[0,0,1]
	v_pk_mul_f32 v[164:165], v[172:173], v[164:165]
	v_mov_b32_e32 v145, v33
	v_pk_fma_f32 v[158:159], v[166:167], v[158:159], v[164:165]
	global_store_dwordx4 v[160:161], v[148:151], off
	global_store_dwordx4 v[160:161], v[156:159], off offset:128
	v_lshl_add_u64 v[144:145], v[162:163], 0, v[144:145]
	v_cvt_pk_bf16_f32 v148, v148, v149
	v_cvt_pk_bf16_f32 v149, v150, v151
	global_store_dwordx2 v[144:145], v[148:149], off
	v_cvt_pk_bf16_f32 v148, v156, v157
	v_cvt_pk_bf16_f32 v149, v158, v159
	global_store_dwordx2 v[144:145], v[148:149], off offset:64
	v_mul_f32_e32 v32, v133, v155
	v_mul_f32_e32 v132, 0.15915494, v32
	v_rndne_f32_e32 v132, v132
	v_fmac_f32_e32 v32, 0xc0c90000, v132
	v_fmac_f32_e32 v32, 0xbafdaa22, v132
	v_mul_f32_e32 v32, 0.15915494, v32
	v_sin_f32_e32 v132, v32
	v_cos_f32_e32 v150, v32
	v_mul_f32_e32 v32, v152, v155
	v_mul_f32_e32 v133, 0.15915494, v32
	v_rndne_f32_e32 v133, v133
	v_fmac_f32_e32 v32, 0xc0c90000, v133
	v_fmac_f32_e32 v32, 0xbafdaa22, v133
	v_mul_f32_e32 v32, 0.15915494, v32
	v_sin_f32_e32 v133, v32
	v_cos_f32_e32 v151, v32
	v_pk_mul_f32 v[158:159], v[66:67], v[136:137] op_sel_hi:[1,0]
	v_pk_mul_f32 v[156:157], v[74:75], v[136:137] op_sel_hi:[1,0]
	v_pk_mul_f32 v[148:149], v[158:159], v[132:133]
	v_mul_f32_e32 v32, v153, v155
	v_pk_fma_f32 v[148:149], v[156:157], v[150:151], v[148:149] neg_lo:[0,0,1] neg_hi:[0,0,1]
	v_pk_mul_f32 v[150:151], v[158:159], v[150:151]
	v_pk_mul_f32 v[158:159], v[68:69], v[136:137] op_sel_hi:[1,0]
	v_pk_fma_f32 v[156:157], v[156:157], v[132:133], v[150:151]
	v_mul_f32_e32 v132, 0.15915494, v32
	v_rndne_f32_e32 v132, v132
	v_fmac_f32_e32 v32, 0xc0c90000, v132
	v_fmac_f32_e32 v32, 0xbafdaa22, v132
	v_mul_f32_e32 v32, 0.15915494, v32
	v_sin_f32_e32 v132, v32
	v_cos_f32_e32 v152, v32
	v_mul_f32_e32 v32, v154, v155
	v_mul_f32_e32 v133, 0.15915494, v32
	v_rndne_f32_e32 v133, v133
	v_fmac_f32_e32 v32, 0xc0c90000, v133
	v_fmac_f32_e32 v32, 0xbafdaa22, v133
	v_mul_f32_e32 v32, 0.15915494, v32
	v_sin_f32_e32 v133, v32
	v_cos_f32_e32 v153, v32
	v_pk_mul_f32 v[154:155], v[76:77], v[136:137] op_sel_hi:[1,0]
	v_pk_mul_f32 v[150:151], v[158:159], v[132:133]
	s_nop 0
	v_pk_fma_f32 v[150:151], v[154:155], v[152:153], v[150:151] neg_lo:[0,0,1] neg_hi:[0,0,1]
	v_pk_mul_f32 v[152:153], v[158:159], v[152:153]
	s_nop 0
	v_pk_fma_f32 v[158:159], v[154:155], v[132:133], v[152:153]
	global_store_dwordx4 v[160:161], v[148:151], off offset:64
	global_store_dwordx4 v[160:161], v[156:159], off offset:192
	v_cvt_pk_bf16_f32 v132, v148, v149
	v_cvt_pk_bf16_f32 v133, v150, v151
	global_store_dwordx2 v[144:145], v[132:133], off offset:32
	v_cvt_pk_bf16_f32 v132, v156, v157
	v_cvt_pk_bf16_f32 v133, v158, v159
	global_store_dwordx2 v[144:145], v[132:133], off offset:96

; DEVI float sigmoidf_(float x) { return fminf(__builtin_amdgcn_rcpf(1.f + __builtin_amdgcn_exp2f(-LOG2E * x)), 1.f); }
; #define EPI_LOOP(...) _Pragma("unroll") for(int ai=0;ai<2;++ai) _Pragma("unroll") for(int bj=0;bj<2;++bj) \
;   _Pragma("unroll") for(int m=0;m<4;++m) _Pragma("unroll") for(int n=0;n<2;++n) { \
;     const int row=brow+ai*128+wr*64+m*16+fq*4; const int col=bcol+bj*128+wc*32+n*16+fr; \
;     f32x4& v=acc[ai][bj][m][n]; __VA_ARGS__ if (n == 1 && (m & 1)) __builtin_amdgcn_sched_barrier(0); }
; DEVI void st_bf4(bf16* p, float a, float b, float c, float d) {
;   u32x2 w = {cvtpk(a, b), cvtpk(c, d)}; *reinterpret_cast<u32x2*>(p) = w;
; }
; DEVI void run_phase(const int ph, const Params& P, char* shmc, const int wave_u) {
;     ...
;       } else if (brow < 8192) {
;         EPI_LOOP({ const float sc = sc4[bj][n]; const int f = row - 4096;
;           st_bf4(gates + (long)col * 4096 + f, sigmoidf_(v[0] * sc), sigmoidf_(v[1] * sc), sigmoidf_(v[2] * sc), sigmoidf_(v[3] * sc)); })
.LBB0_1004:
	s_andn2_b64 vcc, exec, s[38:39]
	v_mbcnt_lo_u32_b32 v194, -1, 0
	v_mbcnt_hi_u32_b32 v194, -1, v194
	v_bfe_u32 v194, v194, 4, 1
	v_mul_u32_u24_e32 v194, 24, v194
	v_mov_b32_e32 v195, 0
	s_cbranch_vccnz .LBB0_1006
	v_lshl_add_u32 v32, v169, 6, s0
	v_lshl_or_b32 v132, v168, 2, v32
	v_readlane_b32 s8, v255, 13
	v_ashrrev_i32_e32 v133, 31, v132
	v_readlane_b32 s9, v255, 14
	v_ashrrev_i32_e32 v135, 31, v134
	s_waitcnt vmcnt(0) lgkmcnt(0)
	v_mul_f32_e32 v32, v126, v142
	v_lshl_add_u64 v[150:151], v[132:133], 1, s[8:9]
	v_lshlrev_b64 v[132:133], 13, v[134:135]
	v_mul_f32_e32 v135, v127, v142
	v_mul_f32_e32 v139, v128, v142
	v_mul_f32_e32 v141, v129, v142
	v_mul_f32_e32 v32, 0xbfb8aa3b, v32
	v_mul_f32_e32 v135, 0xbfb8aa3b, v135
	v_mul_f32_e32 v139, 0xbfb8aa3b, v139
	v_mul_f32_e32 v141, 0xbfb8aa3b, v141
	v_exp_f32_e32 v32, v32
	v_exp_f32_e32 v135, v135
	v_exp_f32_e32 v139, v139
	v_exp_f32_e32 v141, v141
	v_add_f32_e32 v32, 1.0, v32
	v_add_f32_e32 v135, 1.0, v135
	v_add_f32_e32 v139, 1.0, v139
	v_add_f32_e32 v141, 1.0, v141
	v_rcp_f32_e32 v32, v32
	v_rcp_f32_e32 v135, v135
	v_rcp_f32_e32 v139, v139
	v_rcp_f32_e32 v141, v141
	v_min_f32_e32 v32, 1.0, v32
	v_min_f32_e32 v135, 1.0, v135
	v_min_f32_e32 v139, 1.0, v139
	v_min_f32_e32 v141, 1.0, v141
	v_cvt_pk_bf16_f32 v144, v32, v135
	v_cvt_pk_bf16_f32 v145, v139, v141
	v_mul_f32_e32 v32, v122, v140
	v_mul_f32_e32 v135, v123, v140
	v_mul_f32_e32 v139, v124, v140
	v_mul_f32_e32 v141, v125, v140
	v_mul_f32_e32 v32, 0xbfb8aa3b, v32
	v_mul_f32_e32 v135, 0xbfb8aa3b, v135
	v_mul_f32_e32 v139, 0xbfb8aa3b, v139
	v_mul_f32_e32 v141, 0xbfb8aa3b, v141
	v_exp_f32_e32 v32, v32
	v_exp_f32_e32 v135, v135
	v_exp_f32_e32 v139, v139
	v_exp_f32_e32 v141, v141
	v_add_f32_e32 v32, 1.0, v32
	v_add_f32_e32 v135, 1.0, v135
	v_add_f32_e32 v139, 1.0, v139
	v_add_f32_e32 v141, 1.0, v141
	v_rcp_f32_e32 v32, v32
	v_rcp_f32_e32 v135, v135
	v_rcp_f32_e32 v139, v139
	v_rcp_f32_e32 v141, v141
	v_lshl_add_u64 v[132:133], v[150:151], 0, v[132:133]
	s_movk_i32 s1, 0xe000
	v_add_co_u32_e32 v148, vcc, s1, v132
	v_min_f32_e32 v32, 1.0, v32
	s_nop 0
	v_addc_co_u32_e32 v149, vcc, -1, v133, vcc
	v_min_f32_e32 v135, 1.0, v135
	v_min_f32_e32 v139, 1.0, v139
	v_min_f32_e32 v141, 1.0, v141
	v_mov_b32_e32 v156, v144
	v_mov_b32_e32 v157, v145
	v_lshl_add_u64 v[178:179], v[148:149], 0, v[194:195]
	v_cvt_pk_bf16_f32 v148, v32, v135
	v_cvt_pk_bf16_f32 v149, v139, v141
	v_mul_f32_e32 v32, v118, v142
	v_mul_f32_e32 v135, v119, v142
	v_mul_f32_e32 v139, v120, v142
	v_mul_f32_e32 v141, v121, v142
	v_mul_f32_e32 v32, 0xbfb8aa3b, v32
	v_mul_f32_e32 v135, 0xbfb8aa3b, v135
	v_mul_f32_e32 v139, 0xbfb8aa3b, v139
	v_mul_f32_e32 v141, 0xbfb8aa3b, v141
	v_exp_f32_e32 v32, v32
	v_exp_f32_e32 v135, v135
	v_exp_f32_e32 v139, v139
	v_exp_f32_e32 v141, v141
	v_or_b32_e32 v144, 16, v134
	v_add_f32_e32 v32, 1.0, v32
	v_add_f32_e32 v135, 1.0, v135
	v_add_f32_e32 v139, 1.0, v139
	v_add_f32_e32 v141, 1.0, v141
	v_ashrrev_i32_e32 v145, 31, v144
	v_rcp_f32_e32 v32, v32
	v_rcp_f32_e32 v135, v135
	v_rcp_f32_e32 v139, v139
	v_rcp_f32_e32 v141, v141
	v_lshlrev_b64 v[144:145], 13, v[144:145]
	v_lshl_add_u64 v[144:145], v[150:151], 0, v[144:145]
	v_add_co_u32_e32 v152, vcc, s1, v144
	v_min_f32_e32 v32, 1.0, v32
	s_nop 0
	v_addc_co_u32_e32 v153, vcc, -1, v145, vcc
	v_min_f32_e32 v135, 1.0, v135
	v_min_f32_e32 v139, 1.0, v139
	v_min_f32_e32 v141, 1.0, v141
	v_mov_b32_e32 v160, v148
	v_mov_b32_e32 v161, v149
	v_lshl_add_u64 v[180:181], v[152:153], 0, v[194:195]
	v_cvt_pk_bf16_f32 v148, v32, v135
	v_cvt_pk_bf16_f32 v149, v139, v141
	v_mul_f32_e32 v32, v114, v140
	v_mul_f32_e32 v135, v115, v140
	v_mul_f32_e32 v139, v116, v140
	v_mul_f32_e32 v141, v117, v140
	v_mul_f32_e32 v32, 0xbfb8aa3b, v32
	v_mul_f32_e32 v135, 0xbfb8aa3b, v135
	v_mul_f32_e32 v139, 0xbfb8aa3b, v139
	v_mul_f32_e32 v141, 0xbfb8aa3b, v141
	v_exp_f32_e32 v32, v32
	v_exp_f32_e32 v135, v135
	v_exp_f32_e32 v139, v139
	v_exp_f32_e32 v141, v141
	s_movk_i32 s4, 0xe020
	v_add_f32_e32 v32, 1.0, v32
	v_add_f32_e32 v135, 1.0, v135
	v_add_f32_e32 v139, 1.0, v139
	v_add_f32_e32 v141, 1.0, v141
	v_add_co_u32_e32 v152, vcc, s4, v132
	v_rcp_f32_e32 v32, v32
	v_rcp_f32_e32 v135, v135
	v_rcp_f32_e32 v139, v139
	v_rcp_f32_e32 v141, v141
	v_addc_co_u32_e32 v153, vcc, -1, v133, vcc
	v_mov_b32_e32 v158, v148
	v_mov_b32_e32 v159, v149
	s_nop 1
	v_permlane16_swap_b32_e32 v156, v158
	v_permlane16_swap_b32_e32 v157, v159
	global_store_dwordx4 v[178:179], v[156:159], off
	v_add_co_u32_e32 v152, vcc, s4, v144
	v_min_f32_e32 v32, 1.0, v32
	s_nop 0
	v_addc_co_u32_e32 v153, vcc, -1, v145, vcc
	v_min_f32_e32 v135, 1.0, v135
	v_min_f32_e32 v139, 1.0, v139
	v_min_f32_e32 v141, 1.0, v141
	v_cvt_pk_bf16_f32 v148, v32, v135
	v_cvt_pk_bf16_f32 v149, v139, v141
	v_mov_b32_e32 v162, v148
	v_mov_b32_e32 v163, v149
	s_nop 1
	v_permlane16_swap_b32_e32 v160, v162
	v_permlane16_swap_b32_e32 v161, v163
	global_store_dwordx4 v[180:181], v[160:163], off
	v_mul_f32_e32 v32, v110, v142
	v_mul_f32_e32 v135, v111, v142
	v_mul_f32_e32 v139, v112, v142
	v_mul_f32_e32 v141, v113, v142
	v_mul_f32_e32 v32, 0xbfb8aa3b, v32
	v_mul_f32_e32 v135, 0xbfb8aa3b, v135
	v_mul_f32_e32 v139, 0xbfb8aa3b, v139
	v_mul_f32_e32 v141, 0xbfb8aa3b, v141
	v_exp_f32_e32 v32, v32
	v_exp_f32_e32 v135, v135
	v_exp_f32_e32 v139, v139
	v_exp_f32_e32 v141, v141
	v_add_f32_e32 v32, 1.0, v32
	v_add_f32_e32 v135, 1.0, v135
	v_add_f32_e32 v139, 1.0, v139
	v_add_f32_e32 v141, 1.0, v141
	v_rcp_f32_e32 v32, v32
	v_rcp_f32_e32 v135, v135
	v_rcp_f32_e32 v139, v139
	v_rcp_f32_e32 v141, v141
	v_min_f32_e32 v32, 1.0, v32
	v_min_f32_e32 v135, 1.0, v135
	v_min_f32_e32 v139, 1.0, v139
	v_min_f32_e32 v141, 1.0, v141
; DEVI float sigmoidf_(float x) { return fminf(__builtin_amdgcn_rcpf(1.f + __builtin_amdgcn_exp2f(-LOG2E * x)), 1.f); }
; #define EPI_LOOP(...) _Pragma("unroll") for(int ai=0;ai<2;++ai) _Pragma("unroll") for(int bj=0;bj<2;++bj) \
;   _Pragma("unroll") for(int m=0;m<4;++m) _Pragma("unroll") for(int n=0;n<2;++n) { \
;     const int row=brow+ai*128+wr*64+m*16+fq*4; const int col=bcol+bj*128+wc*32+n*16+fr; \
;     f32x4& v=acc[ai][bj][m][n]; __VA_ARGS__ if (n == 1 && (m & 1)) __builtin_amdgcn_sched_barrier(0); }
; DEVI void st_bf4(bf16* p, float a, float b, float c, float d) {
;   u32x2 w = {cvtpk(a, b), cvtpk(c, d)}; *reinterpret_cast<u32x2*>(p) = w;
; }
; DEVI void run_phase(const int ph, const Params& P, char* shmc, const int wave_u) {
;     ...
;       } else if (brow < 8192) {
;         EPI_LOOP({ const float sc = sc4[bj][n]; const int f = row - 4096;
;           st_bf4(gates + (long)col * 4096 + f, sigmoidf_(v[0] * sc), sigmoidf_(v[1] * sc), sigmoidf_(v[2] * sc), sigmoidf_(v[3] * sc)); })
	v_cvt_pk_bf16_f32 v148, v32, v135
	v_cvt_pk_bf16_f32 v149, v139, v141
	v_mul_f32_e32 v32, v106, v140
	v_mul_f32_e32 v135, v107, v140
	v_mul_f32_e32 v139, v108, v140
	v_mul_f32_e32 v141, v109, v140
	v_mul_f32_e32 v32, 0xbfb8aa3b, v32
	v_mul_f32_e32 v135, 0xbfb8aa3b, v135
	v_mul_f32_e32 v139, 0xbfb8aa3b, v139
	v_mul_f32_e32 v141, 0xbfb8aa3b, v141
	v_exp_f32_e32 v32, v32
	v_exp_f32_e32 v135, v135
	v_exp_f32_e32 v139, v139
	v_exp_f32_e32 v141, v141
	v_add_f32_e32 v32, 1.0, v32
	v_add_f32_e32 v135, 1.0, v135
	v_add_f32_e32 v139, 1.0, v139
	v_add_f32_e32 v141, 1.0, v141
	v_rcp_f32_e32 v32, v32
	v_rcp_f32_e32 v135, v135
	v_rcp_f32_e32 v139, v139
	v_rcp_f32_e32 v141, v141
	s_movk_i32 s8, 0xe040
	v_add_co_u32_e32 v152, vcc, s8, v132
	v_min_f32_e32 v32, 1.0, v32
	s_nop 0
	v_addc_co_u32_e32 v153, vcc, -1, v133, vcc
	v_min_f32_e32 v135, 1.0, v135
	v_min_f32_e32 v139, 1.0, v139
	v_min_f32_e32 v141, 1.0, v141
	v_mov_b32_e32 v164, v148
	v_mov_b32_e32 v165, v149
	v_lshl_add_u64 v[182:183], v[152:153], 0, v[194:195]
	v_cvt_pk_bf16_f32 v148, v32, v135
	v_cvt_pk_bf16_f32 v149, v139, v141
	v_mul_f32_e32 v32, v102, v142
	v_mul_f32_e32 v135, v103, v142
	v_mul_f32_e32 v139, v104, v142
	v_mul_f32_e32 v141, v105, v142
	v_mul_f32_e32 v32, 0xbfb8aa3b, v32
	v_mul_f32_e32 v135, 0xbfb8aa3b, v135
	v_mul_f32_e32 v139, 0xbfb8aa3b, v139
	v_mul_f32_e32 v141, 0xbfb8aa3b, v141
	v_exp_f32_e32 v32, v32
	v_exp_f32_e32 v135, v135
	v_exp_f32_e32 v139, v139
	v_exp_f32_e32 v141, v141
	v_add_f32_e32 v32, 1.0, v32
	v_add_f32_e32 v135, 1.0, v135
	v_add_f32_e32 v139, 1.0, v139
	v_add_f32_e32 v141, 1.0, v141
	v_rcp_f32_e32 v32, v32
	v_rcp_f32_e32 v135, v135
	v_rcp_f32_e32 v139, v139
	v_rcp_f32_e32 v141, v141
	v_add_co_u32_e32 v152, vcc, s8, v144
	v_min_f32_e32 v32, 1.0, v32
	s_nop 0
	v_addc_co_u32_e32 v153, vcc, -1, v145, vcc
	v_min_f32_e32 v135, 1.0, v135
	v_min_f32_e32 v139, 1.0, v139
	v_min_f32_e32 v141, 1.0, v141
	v_mov_b32_e32 v172, v148
	v_mov_b32_e32 v173, v149
	v_lshl_add_u64 v[192:193], v[152:153], 0, v[194:195]
	v_cvt_pk_bf16_f32 v148, v32, v135
	v_cvt_pk_bf16_f32 v149, v139, v141
	v_mul_f32_e32 v32, v98, v140
	v_mul_f32_e32 v135, v99, v140
	v_mul_f32_e32 v139, v100, v140
	v_mul_f32_e32 v141, v101, v140
	v_mul_f32_e32 v32, 0xbfb8aa3b, v32
	v_mul_f32_e32 v135, 0xbfb8aa3b, v135
	v_mul_f32_e32 v139, 0xbfb8aa3b, v139
	v_mul_f32_e32 v141, 0xbfb8aa3b, v141
	v_exp_f32_e32 v32, v32
	v_exp_f32_e32 v135, v135
	v_exp_f32_e32 v139, v139
	v_exp_f32_e32 v141, v141
	s_movk_i32 s9, 0xe060
	v_add_f32_e32 v32, 1.0, v32
	v_add_f32_e32 v135, 1.0, v135
	v_add_f32_e32 v139, 1.0, v139
	v_add_f32_e32 v141, 1.0, v141
	v_add_co_u32_e32 v152, vcc, s9, v132
	v_rcp_f32_e32 v32, v32
	v_rcp_f32_e32 v135, v135
	v_rcp_f32_e32 v139, v139
	v_rcp_f32_e32 v141, v141
	v_addc_co_u32_e32 v153, vcc, -1, v133, vcc
	v_mov_b32_e32 v166, v148
	v_mov_b32_e32 v167, v149
	s_nop 1
	v_permlane16_swap_b32_e32 v164, v166
	v_permlane16_swap_b32_e32 v165, v167
	global_store_dwordx4 v[182:183], v[164:167], off
	v_add_co_u32_e32 v152, vcc, s9, v144
	v_min_f32_e32 v32, 1.0, v32
	s_nop 0
	v_addc_co_u32_e32 v153, vcc, -1, v145, vcc
	v_min_f32_e32 v135, 1.0, v135
	v_min_f32_e32 v139, 1.0, v139
	v_min_f32_e32 v141, 1.0, v141
	v_cvt_pk_bf16_f32 v148, v32, v135
	v_cvt_pk_bf16_f32 v149, v139, v141
	v_mov_b32_e32 v174, v148
	v_mov_b32_e32 v175, v149
	s_nop 1
	v_permlane16_swap_b32_e32 v172, v174
	v_permlane16_swap_b32_e32 v173, v175
	global_store_dwordx4 v[192:193], v[172:175], off
	v_mul_f32_e32 v32, v94, v138
	v_mul_f32_e32 v135, v95, v138
	v_mul_f32_e32 v139, v96, v138
	v_mul_f32_e32 v141, v97, v138
	v_mul_f32_e32 v32, 0xbfb8aa3b, v32
	v_mul_f32_e32 v135, 0xbfb8aa3b, v135
	v_mul_f32_e32 v139, 0xbfb8aa3b, v139
	v_mul_f32_e32 v141, 0xbfb8aa3b, v141
	v_exp_f32_e32 v32, v32
	v_exp_f32_e32 v135, v135
	v_exp_f32_e32 v139, v139
	v_exp_f32_e32 v141, v141
	v_add_f32_e32 v32, 1.0, v32
	v_add_f32_e32 v135, 1.0, v135
	v_add_f32_e32 v139, 1.0, v139
	v_add_f32_e32 v141, 1.0, v141
	v_rcp_f32_e32 v32, v32
	v_rcp_f32_e32 v135, v135
	v_rcp_f32_e32 v139, v139
	v_rcp_f32_e32 v141, v141
	v_min_f32_e32 v32, 1.0, v32
	v_min_f32_e32 v135, 1.0, v135
	v_min_f32_e32 v139, 1.0, v139
	v_min_f32_e32 v141, 1.0, v141
	v_cvt_pk_bf16_f32 v152, v32, v135
	v_cvt_pk_bf16_f32 v153, v139, v141
	v_mul_f32_e32 v32, v90, v136
	v_mul_f32_e32 v135, v91, v136
	v_mul_f32_e32 v139, v92, v136
	v_mul_f32_e32 v141, v93, v136
	v_mul_f32_e32 v32, 0xbfb8aa3b, v32
	v_mul_f32_e32 v135, 0xbfb8aa3b, v135
	v_mul_f32_e32 v139, 0xbfb8aa3b, v139
	v_mul_f32_e32 v141, 0xbfb8aa3b, v141
	v_exp_f32_e32 v32, v32
	v_exp_f32_e32 v135, v135
	v_exp_f32_e32 v139, v139
	v_exp_f32_e32 v141, v141
	v_or_b32_e32 v148, 0x80, v134
	v_ashrrev_i32_e32 v149, 31, v148
	v_lshlrev_b64 v[148:149], 13, v[148:149]
	v_lshl_add_u64 v[148:149], v[150:151], 0, v[148:149]
	v_add_f32_e32 v32, 1.0, v32
	v_add_f32_e32 v135, 1.0, v135
	v_add_f32_e32 v139, 1.0, v139
	v_add_f32_e32 v141, 1.0, v141
	v_add_co_u32_e32 v154, vcc, s1, v148
	v_rcp_f32_e32 v32, v32
	v_rcp_f32_e32 v135, v135
	v_rcp_f32_e32 v139, v139
	v_rcp_f32_e32 v141, v141
	v_addc_co_u32_e32 v155, vcc, -1, v149, vcc
	v_mov_b32_e32 v156, v152
	v_mov_b32_e32 v157, v153
	v_lshl_add_u64 v[178:179], v[154:155], 0, v[194:195]
	v_or_b32_e32 v152, 0x90, v134
	v_ashrrev_i32_e32 v153, 31, v152
	v_lshlrev_b64 v[152:153], 13, v[152:153]
	v_min_f32_e32 v32, 1.0, v32
	v_min_f32_e32 v135, 1.0, v135
	v_min_f32_e32 v139, 1.0, v139
	v_min_f32_e32 v141, 1.0, v141
	v_lshl_add_u64 v[150:151], v[150:151], 0, v[152:153]
	v_cvt_pk_bf16_f32 v152, v32, v135
	v_cvt_pk_bf16_f32 v153, v139, v141
	v_mul_f32_e32 v32, v86, v138
	v_mul_f32_e32 v135, v87, v138
	v_mul_f32_e32 v139, v88, v138
; DEVI float sigmoidf_(float x) { return fminf(__builtin_amdgcn_rcpf(1.f + __builtin_amdgcn_exp2f(-LOG2E * x)), 1.f); }
; #define EPI_LOOP(...) _Pragma("unroll") for(int ai=0;ai<2;++ai) _Pragma("unroll") for(int bj=0;bj<2;++bj) \
;   _Pragma("unroll") for(int m=0;m<4;++m) _Pragma("unroll") for(int n=0;n<2;++n) { \
;     const int row=brow+ai*128+wr*64+m*16+fq*4; const int col=bcol+bj*128+wc*32+n*16+fr; \
;     f32x4& v=acc[ai][bj][m][n]; __VA_ARGS__ if (n == 1 && (m & 1)) __builtin_amdgcn_sched_barrier(0); }
; DEVI void run_phase(const int ph, const Params& P, char* shmc, const int wave_u) {
;     ...
;       } else if (brow < 8192) {
;         EPI_LOOP({ const float sc = sc4[bj][n]; const int f = row - 4096;
;           st_bf4(gates + (long)col * 4096 + f, sigmoidf_(v[0] * sc), sigmoidf_(v[1] * sc), sigmoidf_(v[2] * sc), sigmoidf_(v[3] * sc)); })
	v_mul_f32_e32 v141, v89, v138
	v_mul_f32_e32 v32, 0xbfb8aa3b, v32
	v_mul_f32_e32 v135, 0xbfb8aa3b, v135
	v_mul_f32_e32 v139, 0xbfb8aa3b, v139
	v_mul_f32_e32 v141, 0xbfb8aa3b, v141
	v_exp_f32_e32 v32, v32
	v_exp_f32_e32 v135, v135
	v_exp_f32_e32 v139, v139
	v_exp_f32_e32 v141, v141
	v_add_f32_e32 v32, 1.0, v32
	v_add_f32_e32 v135, 1.0, v135
	v_add_f32_e32 v139, 1.0, v139
	v_add_f32_e32 v141, 1.0, v141
	v_rcp_f32_e32 v32, v32
	v_rcp_f32_e32 v135, v135
	v_rcp_f32_e32 v139, v139
	v_rcp_f32_e32 v141, v141
	v_add_co_u32_e32 v154, vcc, s1, v150
	v_min_f32_e32 v32, 1.0, v32
	s_nop 0
	v_addc_co_u32_e32 v155, vcc, -1, v151, vcc
	v_min_f32_e32 v135, 1.0, v135
	v_min_f32_e32 v139, 1.0, v139
	v_min_f32_e32 v141, 1.0, v141
	v_mov_b32_e32 v160, v152
	v_mov_b32_e32 v161, v153
	v_lshl_add_u64 v[180:181], v[154:155], 0, v[194:195]
	v_cvt_pk_bf16_f32 v152, v32, v135
	v_cvt_pk_bf16_f32 v153, v139, v141
	v_mul_f32_e32 v32, v82, v136
	v_mul_f32_e32 v135, v83, v136
	v_mul_f32_e32 v139, v84, v136
	v_mul_f32_e32 v141, v85, v136
	v_mul_f32_e32 v32, 0xbfb8aa3b, v32
	v_mul_f32_e32 v135, 0xbfb8aa3b, v135
	v_mul_f32_e32 v139, 0xbfb8aa3b, v139
	v_mul_f32_e32 v141, 0xbfb8aa3b, v141
	v_exp_f32_e32 v32, v32
	v_exp_f32_e32 v135, v135
	v_exp_f32_e32 v139, v139
	v_exp_f32_e32 v141, v141
	v_add_f32_e32 v32, 1.0, v32
	v_add_f32_e32 v135, 1.0, v135
	v_add_f32_e32 v139, 1.0, v139
	v_add_f32_e32 v141, 1.0, v141
	v_add_co_u32_e32 v154, vcc, s4, v148
	v_rcp_f32_e32 v32, v32
	v_rcp_f32_e32 v135, v135
	v_rcp_f32_e32 v139, v139
	v_rcp_f32_e32 v141, v141
	v_addc_co_u32_e32 v155, vcc, -1, v149, vcc
	v_mov_b32_e32 v158, v152
	v_mov_b32_e32 v159, v153
	s_nop 1
	v_permlane16_swap_b32_e32 v156, v158
	v_permlane16_swap_b32_e32 v157, v159
	global_store_dwordx4 v[178:179], v[156:159], off
	v_add_co_u32_e32 v154, vcc, s4, v150
	v_min_f32_e32 v32, 1.0, v32
	s_nop 0
	v_addc_co_u32_e32 v155, vcc, -1, v151, vcc
	v_min_f32_e32 v135, 1.0, v135
	v_min_f32_e32 v139, 1.0, v139
	v_min_f32_e32 v141, 1.0, v141
	v_cvt_pk_bf16_f32 v152, v32, v135
	v_cvt_pk_bf16_f32 v153, v139, v141
	v_mov_b32_e32 v162, v152
	v_mov_b32_e32 v163, v153
	s_nop 1
	v_permlane16_swap_b32_e32 v160, v162
	v_permlane16_swap_b32_e32 v161, v163
	global_store_dwordx4 v[180:181], v[160:163], off
	v_mul_f32_e32 v32, v78, v138
	v_mul_f32_e32 v135, v79, v138
	v_mul_f32_e32 v139, v80, v138
	v_mul_f32_e32 v141, v81, v138
	v_mul_f32_e32 v32, 0xbfb8aa3b, v32
	v_mul_f32_e32 v135, 0xbfb8aa3b, v135
	v_mul_f32_e32 v139, 0xbfb8aa3b, v139
	v_mul_f32_e32 v141, 0xbfb8aa3b, v141
	v_exp_f32_e32 v32, v32
	v_exp_f32_e32 v135, v135
	v_exp_f32_e32 v139, v139
	v_exp_f32_e32 v141, v141
	v_add_f32_e32 v32, 1.0, v32
	v_add_f32_e32 v135, 1.0, v135
	v_add_f32_e32 v139, 1.0, v139
	v_add_f32_e32 v141, 1.0, v141
	v_rcp_f32_e32 v32, v32
	v_rcp_f32_e32 v135, v135
	v_rcp_f32_e32 v139, v139
	v_rcp_f32_e32 v141, v141
	v_min_f32_e32 v32, 1.0, v32
	v_min_f32_e32 v135, 1.0, v135
	v_min_f32_e32 v139, 1.0, v139
	v_min_f32_e32 v141, 1.0, v141
	v_cvt_pk_bf16_f32 v152, v32, v135
	v_cvt_pk_bf16_f32 v153, v139, v141
	v_mul_f32_e32 v32, v74, v136
	v_mul_f32_e32 v135, v75, v136
	v_mul_f32_e32 v139, v76, v136
	v_mul_f32_e32 v141, v77, v136
	v_mul_f32_e32 v32, 0xbfb8aa3b, v32
	v_mul_f32_e32 v135, 0xbfb8aa3b, v135
	v_mul_f32_e32 v139, 0xbfb8aa3b, v139
	v_mul_f32_e32 v141, 0xbfb8aa3b, v141
	v_exp_f32_e32 v32, v32
	v_exp_f32_e32 v135, v135
	v_exp_f32_e32 v139, v139
	v_exp_f32_e32 v141, v141
	v_add_f32_e32 v32, 1.0, v32
	v_add_f32_e32 v135, 1.0, v135
	v_add_f32_e32 v139, 1.0, v139
	v_add_f32_e32 v141, 1.0, v141
	v_rcp_f32_e32 v32, v32
	v_rcp_f32_e32 v135, v135
	v_rcp_f32_e32 v139, v139
	v_rcp_f32_e32 v141, v141
	v_add_co_u32_e32 v154, vcc, s8, v148
	v_min_f32_e32 v32, 1.0, v32
	s_nop 0
	v_addc_co_u32_e32 v155, vcc, -1, v149, vcc
	v_min_f32_e32 v135, 1.0, v135
	v_min_f32_e32 v139, 1.0, v139
	v_min_f32_e32 v141, 1.0, v141
	v_mov_b32_e32 v164, v152
	v_mov_b32_e32 v165, v153
	v_lshl_add_u64 v[182:183], v[154:155], 0, v[194:195]
	v_cvt_pk_bf16_f32 v152, v32, v135
	v_cvt_pk_bf16_f32 v153, v139, v141
	v_mul_f32_e32 v32, v70, v138
	v_mul_f32_e32 v135, v71, v138
	v_mul_f32_e32 v139, v72, v138
	v_mul_f32_e32 v141, v73, v138
	v_mul_f32_e32 v32, 0xbfb8aa3b, v32
	v_mul_f32_e32 v135, 0xbfb8aa3b, v135
	v_mul_f32_e32 v139, 0xbfb8aa3b, v139
	v_mul_f32_e32 v141, 0xbfb8aa3b, v141
	v_exp_f32_e32 v32, v32
	v_exp_f32_e32 v135, v135
	v_exp_f32_e32 v139, v139
	v_exp_f32_e32 v141, v141
	v_add_f32_e32 v32, 1.0, v32
	v_add_f32_e32 v135, 1.0, v135
	v_add_f32_e32 v139, 1.0, v139
	v_add_f32_e32 v141, 1.0, v141
	v_rcp_f32_e32 v32, v32
	v_rcp_f32_e32 v135, v135
	v_rcp_f32_e32 v139, v139
	v_rcp_f32_e32 v141, v141
	v_add_co_u32_e32 v154, vcc, s8, v150
	v_min_f32_e32 v32, 1.0, v32
	s_nop 0
	v_addc_co_u32_e32 v155, vcc, -1, v151, vcc
	v_min_f32_e32 v135, 1.0, v135
	v_min_f32_e32 v139, 1.0, v139
	v_min_f32_e32 v141, 1.0, v141
	v_mov_b32_e32 v172, v152
	v_mov_b32_e32 v173, v153
	v_lshl_add_u64 v[192:193], v[154:155], 0, v[194:195]
	v_cvt_pk_bf16_f32 v152, v32, v135
	v_cvt_pk_bf16_f32 v153, v139, v141
	v_mul_f32_e32 v32, v66, v136
	v_mul_f32_e32 v135, v67, v136
	v_mul_f32_e32 v139, v68, v136
	v_mul_f32_e32 v141, v69, v136
	v_mul_f32_e32 v32, 0xbfb8aa3b, v32
	v_mul_f32_e32 v135, 0xbfb8aa3b, v135
	v_mul_f32_e32 v139, 0xbfb8aa3b, v139
	v_mul_f32_e32 v141, 0xbfb8aa3b, v141
	v_exp_f32_e32 v32, v32
	v_exp_f32_e32 v135, v135
	v_exp_f32_e32 v139, v139
	v_exp_f32_e32 v141, v141
	v_add_f32_e32 v32, 1.0, v32
	v_add_f32_e32 v135, 1.0, v135
	v_add_f32_e32 v139, 1.0, v139
	v_add_f32_e32 v141, 1.0, v141
	v_add_co_u32_e32 v154, vcc, s9, v148
	v_rcp_f32_e32 v32, v32
	v_rcp_f32_e32 v135, v135
	v_rcp_f32_e32 v139, v139
	v_rcp_f32_e32 v141, v141
; DEVI float sigmoidf_(float x) { return fminf(__builtin_amdgcn_rcpf(1.f + __builtin_amdgcn_exp2f(-LOG2E * x)), 1.f); }
; #define EPI_LOOP(...) _Pragma("unroll") for(int ai=0;ai<2;++ai) _Pragma("unroll") for(int bj=0;bj<2;++bj) \
;   _Pragma("unroll") for(int m=0;m<4;++m) _Pragma("unroll") for(int n=0;n<2;++n) { \
;     const int row=brow+ai*128+wr*64+m*16+fq*4; const int col=bcol+bj*128+wc*32+n*16+fr; \
;     f32x4& v=acc[ai][bj][m][n]; __VA_ARGS__ if (n == 1 && (m & 1)) __builtin_amdgcn_sched_barrier(0); }
; DEVI void run_phase(const int ph, const Params& P, char* shmc, const int wave_u) {
;     ...
;       } else if (brow < 8192) {
;         EPI_LOOP({ const float sc = sc4[bj][n]; const int f = row - 4096;
;           st_bf4(gates + (long)col * 4096 + f, sigmoidf_(v[0] * sc), sigmoidf_(v[1] * sc), sigmoidf_(v[2] * sc), sigmoidf_(v[3] * sc)); })
	v_addc_co_u32_e32 v155, vcc, -1, v149, vcc
	v_mov_b32_e32 v166, v152
	v_mov_b32_e32 v167, v153
	s_nop 1
	v_permlane16_swap_b32_e32 v164, v166
	v_permlane16_swap_b32_e32 v165, v167
	global_store_dwordx4 v[182:183], v[164:167], off
	v_add_co_u32_e32 v154, vcc, s9, v150
	v_min_f32_e32 v32, 1.0, v32
	s_nop 0
	v_addc_co_u32_e32 v155, vcc, -1, v151, vcc
	v_min_f32_e32 v135, 1.0, v135
	v_min_f32_e32 v139, 1.0, v139
	v_min_f32_e32 v141, 1.0, v141
	v_cvt_pk_bf16_f32 v152, v32, v135
	v_cvt_pk_bf16_f32 v153, v139, v141
	v_mov_b32_e32 v174, v152
	v_mov_b32_e32 v175, v153
	s_nop 1
	v_permlane16_swap_b32_e32 v172, v174
	v_permlane16_swap_b32_e32 v173, v175
	global_store_dwordx4 v[192:193], v[172:175], off
	v_mul_f32_e32 v32, v62, v142
	v_mul_f32_e32 v135, v63, v142
	v_mul_f32_e32 v139, v64, v142
	v_mul_f32_e32 v141, v65, v142
	v_mul_f32_e32 v32, 0xbfb8aa3b, v32
	v_mul_f32_e32 v135, 0xbfb8aa3b, v135
	v_mul_f32_e32 v139, 0xbfb8aa3b, v139
	v_mul_f32_e32 v141, 0xbfb8aa3b, v141
	v_exp_f32_e32 v32, v32
	v_exp_f32_e32 v135, v135
	v_exp_f32_e32 v139, v139
	v_exp_f32_e32 v141, v141
	v_add_f32_e32 v32, 1.0, v32
	v_add_f32_e32 v135, 1.0, v135
	v_add_f32_e32 v139, 1.0, v139
	v_add_f32_e32 v141, 1.0, v141
	v_rcp_f32_e32 v32, v32
	v_rcp_f32_e32 v135, v135
	v_rcp_f32_e32 v139, v139
	v_rcp_f32_e32 v141, v141
	v_min_f32_e32 v32, 1.0, v32
	v_min_f32_e32 v135, 1.0, v135
	v_min_f32_e32 v139, 1.0, v139
	v_min_f32_e32 v141, 1.0, v141
	v_cvt_pk_bf16_f32 v152, v32, v135
	v_cvt_pk_bf16_f32 v153, v139, v141
	v_mul_f32_e32 v32, v58, v140
	v_mul_f32_e32 v135, v59, v140
	v_mul_f32_e32 v139, v60, v140
	v_mul_f32_e32 v141, v61, v140
	v_mul_f32_e32 v32, 0xbfb8aa3b, v32
	v_mul_f32_e32 v135, 0xbfb8aa3b, v135
	v_mul_f32_e32 v139, 0xbfb8aa3b, v139
	v_mul_f32_e32 v141, 0xbfb8aa3b, v141
	v_exp_f32_e32 v32, v32
	v_exp_f32_e32 v135, v135
	v_exp_f32_e32 v139, v139
	v_exp_f32_e32 v141, v141
	v_add_f32_e32 v32, 1.0, v32
	v_add_f32_e32 v135, 1.0, v135
	v_add_f32_e32 v139, 1.0, v139
	v_add_f32_e32 v141, 1.0, v141
	v_rcp_f32_e32 v32, v32
	v_rcp_f32_e32 v135, v135
	v_rcp_f32_e32 v139, v139
	v_rcp_f32_e32 v141, v141
	s_movk_i32 s1, 0xe100
	v_add_co_u32_e32 v154, vcc, s1, v132
	v_min_f32_e32 v32, 1.0, v32
	s_nop 0
	v_addc_co_u32_e32 v155, vcc, -1, v133, vcc
	v_min_f32_e32 v135, 1.0, v135
	v_min_f32_e32 v139, 1.0, v139
	v_min_f32_e32 v141, 1.0, v141
	v_mov_b32_e32 v156, v152
	v_mov_b32_e32 v157, v153
	v_lshl_add_u64 v[178:179], v[154:155], 0, v[194:195]
	v_cvt_pk_bf16_f32 v152, v32, v135
	v_cvt_pk_bf16_f32 v153, v139, v141
	v_mul_f32_e32 v32, v54, v142
	v_mul_f32_e32 v135, v55, v142
	v_mul_f32_e32 v139, v56, v142
	v_mul_f32_e32 v141, v57, v142
	v_mul_f32_e32 v32, 0xbfb8aa3b, v32
	v_mul_f32_e32 v135, 0xbfb8aa3b, v135
	v_mul_f32_e32 v139, 0xbfb8aa3b, v139
	v_mul_f32_e32 v141, 0xbfb8aa3b, v141
	v_exp_f32_e32 v32, v32
	v_exp_f32_e32 v135, v135
	v_exp_f32_e32 v139, v139
	v_exp_f32_e32 v141, v141
	v_add_f32_e32 v32, 1.0, v32
	v_add_f32_e32 v135, 1.0, v135
	v_add_f32_e32 v139, 1.0, v139
	v_add_f32_e32 v141, 1.0, v141
	v_rcp_f32_e32 v32, v32
	v_rcp_f32_e32 v135, v135
	v_rcp_f32_e32 v139, v139
	v_rcp_f32_e32 v141, v141
	v_add_co_u32_e32 v154, vcc, s1, v144
	v_min_f32_e32 v32, 1.0, v32
	s_nop 0
	v_addc_co_u32_e32 v155, vcc, -1, v145, vcc
	v_min_f32_e32 v135, 1.0, v135
	v_min_f32_e32 v139, 1.0, v139
	v_min_f32_e32 v141, 1.0, v141
	v_mov_b32_e32 v160, v152
	v_mov_b32_e32 v161, v153
	v_lshl_add_u64 v[180:181], v[154:155], 0, v[194:195]
	v_cvt_pk_bf16_f32 v152, v32, v135
	v_cvt_pk_bf16_f32 v153, v139, v141
	v_mul_f32_e32 v32, v50, v140
	v_mul_f32_e32 v135, v51, v140
	v_mul_f32_e32 v139, v52, v140
	v_mul_f32_e32 v141, v53, v140
	v_mul_f32_e32 v32, 0xbfb8aa3b, v32
	v_mul_f32_e32 v135, 0xbfb8aa3b, v135
	v_mul_f32_e32 v139, 0xbfb8aa3b, v139
	v_mul_f32_e32 v141, 0xbfb8aa3b, v141
	v_exp_f32_e32 v32, v32
	v_exp_f32_e32 v135, v135
	v_exp_f32_e32 v139, v139
	v_exp_f32_e32 v141, v141
	s_movk_i32 s4, 0xe120
	v_add_f32_e32 v32, 1.0, v32
	v_add_f32_e32 v135, 1.0, v135
	v_add_f32_e32 v139, 1.0, v139
	v_add_f32_e32 v141, 1.0, v141
	v_add_co_u32_e32 v154, vcc, s4, v132
	v_rcp_f32_e32 v32, v32
	v_rcp_f32_e32 v135, v135
	v_rcp_f32_e32 v139, v139
	v_rcp_f32_e32 v141, v141
	v_addc_co_u32_e32 v155, vcc, -1, v133, vcc
	v_mov_b32_e32 v158, v152
	v_mov_b32_e32 v159, v153
	s_nop 1
	v_permlane16_swap_b32_e32 v156, v158
	v_permlane16_swap_b32_e32 v157, v159
	global_store_dwordx4 v[178:179], v[156:159], off
	v_add_co_u32_e32 v154, vcc, s4, v144
	v_min_f32_e32 v32, 1.0, v32
	s_nop 0
	v_addc_co_u32_e32 v155, vcc, -1, v145, vcc
	v_min_f32_e32 v135, 1.0, v135
	v_min_f32_e32 v139, 1.0, v139
	v_min_f32_e32 v141, 1.0, v141
	v_cvt_pk_bf16_f32 v152, v32, v135
	v_cvt_pk_bf16_f32 v153, v139, v141
	v_mov_b32_e32 v162, v152
	v_mov_b32_e32 v163, v153
	s_nop 1
	v_permlane16_swap_b32_e32 v160, v162
	v_permlane16_swap_b32_e32 v161, v163
	global_store_dwordx4 v[180:181], v[160:163], off
	v_mul_f32_e32 v32, v46, v142
	v_mul_f32_e32 v135, v47, v142
	v_mul_f32_e32 v139, v48, v142
	v_mul_f32_e32 v141, v49, v142
	v_mul_f32_e32 v32, 0xbfb8aa3b, v32
	v_mul_f32_e32 v135, 0xbfb8aa3b, v135
	v_mul_f32_e32 v139, 0xbfb8aa3b, v139
	v_mul_f32_e32 v141, 0xbfb8aa3b, v141
	v_exp_f32_e32 v32, v32
	v_exp_f32_e32 v135, v135
	v_exp_f32_e32 v139, v139
	v_exp_f32_e32 v141, v141
	v_add_f32_e32 v32, 1.0, v32
	v_add_f32_e32 v135, 1.0, v135
	v_add_f32_e32 v139, 1.0, v139
	v_add_f32_e32 v141, 1.0, v141
	v_rcp_f32_e32 v32, v32
	v_rcp_f32_e32 v135, v135
	v_rcp_f32_e32 v139, v139
	v_rcp_f32_e32 v141, v141
	v_min_f32_e32 v32, 1.0, v32
	v_min_f32_e32 v135, 1.0, v135
	v_min_f32_e32 v139, 1.0, v139
	v_min_f32_e32 v141, 1.0, v141
	v_cvt_pk_bf16_f32 v152, v32, v135
	v_cvt_pk_bf16_f32 v153, v139, v141
; DEVI float sigmoidf_(float x) { return fminf(__builtin_amdgcn_rcpf(1.f + __builtin_amdgcn_exp2f(-LOG2E * x)), 1.f); }
; #define EPI_LOOP(...) _Pragma("unroll") for(int ai=0;ai<2;++ai) _Pragma("unroll") for(int bj=0;bj<2;++bj) \
;   _Pragma("unroll") for(int m=0;m<4;++m) _Pragma("unroll") for(int n=0;n<2;++n) { \
;     const int row=brow+ai*128+wr*64+m*16+fq*4; const int col=bcol+bj*128+wc*32+n*16+fr; \
;     f32x4& v=acc[ai][bj][m][n]; __VA_ARGS__ if (n == 1 && (m & 1)) __builtin_amdgcn_sched_barrier(0); }
; DEVI void run_phase(const int ph, const Params& P, char* shmc, const int wave_u) {
;     ...
;       } else if (brow < 8192) {
;         EPI_LOOP({ const float sc = sc4[bj][n]; const int f = row - 4096;
;           st_bf4(gates + (long)col * 4096 + f, sigmoidf_(v[0] * sc), sigmoidf_(v[1] * sc), sigmoidf_(v[2] * sc), sigmoidf_(v[3] * sc)); })
	v_mul_f32_e32 v32, v42, v140
	v_mul_f32_e32 v135, v43, v140
	v_mul_f32_e32 v139, v44, v140
	v_mul_f32_e32 v141, v45, v140
	v_mul_f32_e32 v32, 0xbfb8aa3b, v32
	v_mul_f32_e32 v135, 0xbfb8aa3b, v135
	v_mul_f32_e32 v139, 0xbfb8aa3b, v139
	v_mul_f32_e32 v141, 0xbfb8aa3b, v141
	v_exp_f32_e32 v32, v32
	v_exp_f32_e32 v135, v135
	v_exp_f32_e32 v139, v139
	v_exp_f32_e32 v141, v141
	v_add_f32_e32 v32, 1.0, v32
	v_add_f32_e32 v135, 1.0, v135
	v_add_f32_e32 v139, 1.0, v139
	v_add_f32_e32 v141, 1.0, v141
	v_rcp_f32_e32 v32, v32
	v_rcp_f32_e32 v135, v135
	v_rcp_f32_e32 v139, v139
	v_rcp_f32_e32 v141, v141
	s_movk_i32 s8, 0xe140
	v_add_co_u32_e32 v154, vcc, s8, v132
	v_min_f32_e32 v32, 1.0, v32
	s_nop 0
	v_addc_co_u32_e32 v155, vcc, -1, v133, vcc
	v_min_f32_e32 v135, 1.0, v135
	v_min_f32_e32 v139, 1.0, v139
	v_min_f32_e32 v141, 1.0, v141
	v_mov_b32_e32 v164, v152
	v_mov_b32_e32 v165, v153
	v_lshl_add_u64 v[182:183], v[154:155], 0, v[194:195]
	v_cvt_pk_bf16_f32 v152, v32, v135
	v_cvt_pk_bf16_f32 v153, v139, v141
	v_mul_f32_e32 v32, v38, v142
	v_mul_f32_e32 v135, v39, v142
	v_mul_f32_e32 v139, v40, v142
	v_mul_f32_e32 v141, v41, v142
	v_mul_f32_e32 v32, 0xbfb8aa3b, v32
	v_mul_f32_e32 v135, 0xbfb8aa3b, v135
	v_mul_f32_e32 v139, 0xbfb8aa3b, v139
	v_mul_f32_e32 v141, 0xbfb8aa3b, v141
	v_exp_f32_e32 v32, v32
	v_exp_f32_e32 v135, v135
	v_exp_f32_e32 v139, v139
	v_exp_f32_e32 v141, v141
	v_add_f32_e32 v32, 1.0, v32
	v_add_f32_e32 v135, 1.0, v135
	v_add_f32_e32 v139, 1.0, v139
	v_add_f32_e32 v141, 1.0, v141
	v_add_co_u32_e32 v154, vcc, s8, v144
	v_rcp_f32_e32 v32, v32
	v_rcp_f32_e32 v135, v135
	v_rcp_f32_e32 v139, v139
	v_rcp_f32_e32 v141, v141
	v_addc_co_u32_e32 v155, vcc, -1, v145, vcc
	s_movk_i32 s9, 0xe160
	v_add_co_u32_e32 v132, vcc, s9, v132
	v_mov_b32_e32 v172, v152
	v_mov_b32_e32 v173, v153
	v_lshl_add_u64 v[192:193], v[154:155], 0, v[194:195]
	s_nop 0
	v_addc_co_u32_e32 v133, vcc, -1, v133, vcc
	v_min_f32_e32 v32, 1.0, v32
	v_min_f32_e32 v135, 1.0, v135
	v_min_f32_e32 v139, 1.0, v139
	v_min_f32_e32 v141, 1.0, v141
	v_cvt_pk_bf16_f32 v152, v32, v135
	v_cvt_pk_bf16_f32 v153, v139, v141
	v_mov_b32_e32 v166, v152
	v_mov_b32_e32 v167, v153
	s_nop 1
	v_permlane16_swap_b32_e32 v164, v166
	v_permlane16_swap_b32_e32 v165, v167
	global_store_dwordx4 v[182:183], v[164:167], off
	v_mul_f32_e32 v132, v35, v140
	v_mul_f32_e32 v133, v36, v140
	v_mul_f32_e32 v32, v34, v140
	v_mul_f32_e32 v132, 0xbfb8aa3b, v132
	v_mul_f32_e32 v133, 0xbfb8aa3b, v133
	v_mul_f32_e32 v135, v37, v140
	v_mul_f32_e32 v32, 0xbfb8aa3b, v32
	v_exp_f32_e32 v132, v132
	v_exp_f32_e32 v133, v133
	v_mul_f32_e32 v135, 0xbfb8aa3b, v135
	v_exp_f32_e32 v32, v32
	v_exp_f32_e32 v135, v135
	v_add_f32_e32 v132, 1.0, v132
	v_add_f32_e32 v133, 1.0, v133
	v_add_f32_e32 v32, 1.0, v32
	v_rcp_f32_e32 v132, v132
	v_rcp_f32_e32 v133, v133
	v_add_f32_e32 v135, 1.0, v135
	v_rcp_f32_e32 v32, v32
	v_rcp_f32_e32 v135, v135
	v_add_co_u32_e32 v144, vcc, s9, v144
	v_min_f32_e32 v132, 1.0, v132
	v_min_f32_e32 v133, 1.0, v133
	v_addc_co_u32_e32 v145, vcc, -1, v145, vcc
	v_min_f32_e32 v32, 1.0, v32
	v_min_f32_e32 v135, 1.0, v135
	v_cvt_pk_bf16_f32 v132, v32, v132
	v_cvt_pk_bf16_f32 v133, v133, v135
	v_mov_b32_e32 v174, v132
	v_mov_b32_e32 v175, v133
	s_nop 1
	v_permlane16_swap_b32_e32 v172, v174
	v_permlane16_swap_b32_e32 v173, v175
	global_store_dwordx4 v[192:193], v[172:175], off
	v_mul_f32_e32 v132, v29, v138
	v_mul_f32_e32 v133, v30, v138
	v_mul_f32_e32 v32, v28, v138
	v_mul_f32_e32 v132, 0xbfb8aa3b, v132
	v_mul_f32_e32 v133, 0xbfb8aa3b, v133
	v_mul_f32_e32 v135, v31, v138
	v_mul_f32_e32 v32, 0xbfb8aa3b, v32
	v_exp_f32_e32 v132, v132
	v_exp_f32_e32 v133, v133
	v_mul_f32_e32 v135, 0xbfb8aa3b, v135
	v_exp_f32_e32 v32, v32
	v_exp_f32_e32 v135, v135
	v_add_f32_e32 v132, 1.0, v132
	v_add_f32_e32 v133, 1.0, v133
	v_add_f32_e32 v32, 1.0, v32
	v_rcp_f32_e32 v132, v132
	v_rcp_f32_e32 v133, v133
	v_add_f32_e32 v135, 1.0, v135
	v_rcp_f32_e32 v32, v32
	v_rcp_f32_e32 v135, v135
	v_min_f32_e32 v132, 1.0, v132
	v_min_f32_e32 v133, 1.0, v133
	v_add_co_u32_e32 v144, vcc, s1, v148
	v_min_f32_e32 v32, 1.0, v32
	v_min_f32_e32 v135, 1.0, v135
	v_cvt_pk_bf16_f32 v132, v32, v132
	v_cvt_pk_bf16_f32 v133, v133, v135
	v_addc_co_u32_e32 v145, vcc, -1, v149, vcc
	v_mov_b32_e32 v156, v132
	v_mov_b32_e32 v157, v133
	v_lshl_add_u64 v[178:179], v[144:145], 0, v[194:195]
	v_mul_f32_e32 v132, v25, v136
	v_mul_f32_e32 v133, v26, v136
	v_mul_f32_e32 v32, v24, v136
	v_mul_f32_e32 v132, 0xbfb8aa3b, v132
	v_mul_f32_e32 v133, 0xbfb8aa3b, v133
	v_mul_f32_e32 v135, v27, v136
	v_mul_f32_e32 v32, 0xbfb8aa3b, v32
	v_exp_f32_e32 v132, v132
	v_exp_f32_e32 v133, v133
	v_mul_f32_e32 v135, 0xbfb8aa3b, v135
	v_exp_f32_e32 v32, v32
	v_exp_f32_e32 v135, v135
	v_add_f32_e32 v132, 1.0, v132
	v_add_f32_e32 v133, 1.0, v133
	v_add_f32_e32 v32, 1.0, v32
	v_rcp_f32_e32 v132, v132
	v_rcp_f32_e32 v133, v133
	v_add_f32_e32 v135, 1.0, v135
	v_rcp_f32_e32 v32, v32
	v_rcp_f32_e32 v135, v135
	v_min_f32_e32 v132, 1.0, v132
	v_min_f32_e32 v133, 1.0, v133
	v_add_co_u32_e32 v144, vcc, s1, v150
	v_min_f32_e32 v32, 1.0, v32
	v_min_f32_e32 v135, 1.0, v135
	v_cvt_pk_bf16_f32 v132, v32, v132
	v_cvt_pk_bf16_f32 v133, v133, v135
	v_addc_co_u32_e32 v145, vcc, -1, v151, vcc
	v_mov_b32_e32 v160, v132
	v_mov_b32_e32 v161, v133
	v_lshl_add_u64 v[180:181], v[144:145], 0, v[194:195]
	v_mul_f32_e32 v132, v21, v138
	v_mul_f32_e32 v133, v22, v138
	v_mul_f32_e32 v32, v20, v138
	v_mul_f32_e32 v132, 0xbfb8aa3b, v132
	v_mul_f32_e32 v133, 0xbfb8aa3b, v133
	v_mul_f32_e32 v135, v23, v138
	v_mul_f32_e32 v32, 0xbfb8aa3b, v32
	v_exp_f32_e32 v132, v132
	v_exp_f32_e32 v133, v133
	v_mul_f32_e32 v135, 0xbfb8aa3b, v135
; DEVI float sigmoidf_(float x) { return fminf(__builtin_amdgcn_rcpf(1.f + __builtin_amdgcn_exp2f(-LOG2E * x)), 1.f); }
; #define EPI_LOOP(...) _Pragma("unroll") for(int ai=0;ai<2;++ai) _Pragma("unroll") for(int bj=0;bj<2;++bj) \
;   _Pragma("unroll") for(int m=0;m<4;++m) _Pragma("unroll") for(int n=0;n<2;++n) { \
;     const int row=brow+ai*128+wr*64+m*16+fq*4; const int col=bcol+bj*128+wc*32+n*16+fr; \
;     f32x4& v=acc[ai][bj][m][n]; __VA_ARGS__ if (n == 1 && (m & 1)) __builtin_amdgcn_sched_barrier(0); }
; DEVI void run_phase(const int ph, const Params& P, char* shmc, const int wave_u) {
;     ...
;       } else if (brow < 8192) {
;         EPI_LOOP({ const float sc = sc4[bj][n]; const int f = row - 4096;
;           st_bf4(gates + (long)col * 4096 + f, sigmoidf_(v[0] * sc), sigmoidf_(v[1] * sc), sigmoidf_(v[2] * sc), sigmoidf_(v[3] * sc)); })
	v_exp_f32_e32 v32, v32
	v_exp_f32_e32 v135, v135
	v_add_f32_e32 v132, 1.0, v132
	v_add_f32_e32 v133, 1.0, v133
	v_add_f32_e32 v32, 1.0, v32
	v_rcp_f32_e32 v132, v132
	v_rcp_f32_e32 v133, v133
	v_add_f32_e32 v135, 1.0, v135
	v_rcp_f32_e32 v32, v32
	v_rcp_f32_e32 v135, v135
	v_min_f32_e32 v132, 1.0, v132
	v_min_f32_e32 v133, 1.0, v133
	v_add_co_u32_e32 v144, vcc, s4, v148
	v_min_f32_e32 v32, 1.0, v32
	v_min_f32_e32 v135, 1.0, v135
	v_cvt_pk_bf16_f32 v132, v32, v132
	v_cvt_pk_bf16_f32 v133, v133, v135
	v_addc_co_u32_e32 v145, vcc, -1, v149, vcc
	v_mov_b32_e32 v158, v132
	v_mov_b32_e32 v159, v133
	s_nop 1
	v_permlane16_swap_b32_e32 v156, v158
	v_permlane16_swap_b32_e32 v157, v159
	global_store_dwordx4 v[178:179], v[156:159], off
	v_mul_f32_e32 v132, v17, v136
	v_mul_f32_e32 v133, v18, v136
	v_mul_f32_e32 v32, v16, v136
	v_mul_f32_e32 v132, 0xbfb8aa3b, v132
	v_mul_f32_e32 v133, 0xbfb8aa3b, v133
	v_mul_f32_e32 v135, v19, v136
	v_mul_f32_e32 v32, 0xbfb8aa3b, v32
	v_exp_f32_e32 v132, v132
	v_exp_f32_e32 v133, v133
	v_mul_f32_e32 v135, 0xbfb8aa3b, v135
	v_exp_f32_e32 v32, v32
	v_exp_f32_e32 v135, v135
	v_add_f32_e32 v132, 1.0, v132
	v_add_f32_e32 v133, 1.0, v133
	v_add_f32_e32 v32, 1.0, v32
	v_rcp_f32_e32 v132, v132
	v_rcp_f32_e32 v133, v133
	v_add_f32_e32 v135, 1.0, v135
	v_rcp_f32_e32 v32, v32
	v_rcp_f32_e32 v135, v135
	v_add_co_u32_e32 v144, vcc, s4, v150
	v_min_f32_e32 v132, 1.0, v132
	v_min_f32_e32 v133, 1.0, v133
	v_addc_co_u32_e32 v145, vcc, -1, v151, vcc
	v_min_f32_e32 v32, 1.0, v32
	v_min_f32_e32 v135, 1.0, v135
	v_cvt_pk_bf16_f32 v132, v32, v132
	v_cvt_pk_bf16_f32 v133, v133, v135
	v_mov_b32_e32 v162, v132
	v_mov_b32_e32 v163, v133
	s_nop 1
	v_permlane16_swap_b32_e32 v160, v162
	v_permlane16_swap_b32_e32 v161, v163
	global_store_dwordx4 v[180:181], v[160:163], off
	v_mul_f32_e32 v132, v13, v138
	v_mul_f32_e32 v133, v14, v138
	v_mul_f32_e32 v32, v12, v138
	v_mul_f32_e32 v132, 0xbfb8aa3b, v132
	v_mul_f32_e32 v133, 0xbfb8aa3b, v133
	v_mul_f32_e32 v135, v15, v138
	v_mul_f32_e32 v32, 0xbfb8aa3b, v32
	v_exp_f32_e32 v132, v132
	v_exp_f32_e32 v133, v133
	v_mul_f32_e32 v135, 0xbfb8aa3b, v135
	v_exp_f32_e32 v32, v32
	v_exp_f32_e32 v135, v135
	v_add_f32_e32 v132, 1.0, v132
	v_add_f32_e32 v133, 1.0, v133
	v_add_f32_e32 v32, 1.0, v32
	v_rcp_f32_e32 v132, v132
	v_rcp_f32_e32 v133, v133
	v_add_f32_e32 v135, 1.0, v135
	v_rcp_f32_e32 v32, v32
	v_rcp_f32_e32 v135, v135
	v_min_f32_e32 v132, 1.0, v132
	v_min_f32_e32 v133, 1.0, v133
	v_add_co_u32_e32 v144, vcc, s8, v148
	v_min_f32_e32 v32, 1.0, v32
	v_min_f32_e32 v135, 1.0, v135
	v_cvt_pk_bf16_f32 v132, v32, v132
	v_cvt_pk_bf16_f32 v133, v133, v135
	v_addc_co_u32_e32 v145, vcc, -1, v149, vcc
	v_mov_b32_e32 v164, v132
	v_mov_b32_e32 v165, v133
	v_lshl_add_u64 v[182:183], v[144:145], 0, v[194:195]
	v_mul_f32_e32 v132, v9, v136
	v_mul_f32_e32 v133, v10, v136
	v_mul_f32_e32 v32, v8, v136
	v_mul_f32_e32 v132, 0xbfb8aa3b, v132
	v_mul_f32_e32 v133, 0xbfb8aa3b, v133
	v_mul_f32_e32 v135, v11, v136
	v_mul_f32_e32 v32, 0xbfb8aa3b, v32
	v_exp_f32_e32 v132, v132
	v_exp_f32_e32 v133, v133
	v_mul_f32_e32 v135, 0xbfb8aa3b, v135
	v_exp_f32_e32 v32, v32
	v_exp_f32_e32 v135, v135
	v_add_f32_e32 v132, 1.0, v132
	v_add_f32_e32 v133, 1.0, v133
	v_add_f32_e32 v32, 1.0, v32
	v_rcp_f32_e32 v132, v132
	v_rcp_f32_e32 v133, v133
	v_add_f32_e32 v135, 1.0, v135
	v_rcp_f32_e32 v32, v32
	v_rcp_f32_e32 v135, v135
	v_min_f32_e32 v132, 1.0, v132
	v_min_f32_e32 v133, 1.0, v133
	v_add_co_u32_e32 v144, vcc, s8, v150
	v_min_f32_e32 v32, 1.0, v32
	v_min_f32_e32 v135, 1.0, v135
	v_cvt_pk_bf16_f32 v132, v32, v132
	v_cvt_pk_bf16_f32 v133, v133, v135
	v_addc_co_u32_e32 v145, vcc, -1, v151, vcc
	v_mov_b32_e32 v172, v132
	v_mov_b32_e32 v173, v133
	v_lshl_add_u64 v[192:193], v[144:145], 0, v[194:195]
	v_mul_f32_e32 v132, v5, v138
	v_mul_f32_e32 v133, v6, v138
	v_mul_f32_e32 v32, v4, v138
	v_mul_f32_e32 v132, 0xbfb8aa3b, v132
	v_mul_f32_e32 v133, 0xbfb8aa3b, v133
	v_mul_f32_e32 v135, v7, v138
	v_mul_f32_e32 v32, 0xbfb8aa3b, v32
	v_exp_f32_e32 v132, v132
	v_exp_f32_e32 v133, v133
	v_mul_f32_e32 v135, 0xbfb8aa3b, v135
	v_exp_f32_e32 v32, v32
	v_exp_f32_e32 v135, v135
	v_add_f32_e32 v132, 1.0, v132
	v_add_f32_e32 v133, 1.0, v133
	v_add_f32_e32 v32, 1.0, v32
	v_rcp_f32_e32 v132, v132
	v_rcp_f32_e32 v133, v133
	v_add_f32_e32 v135, 1.0, v135
	v_rcp_f32_e32 v32, v32
	v_rcp_f32_e32 v135, v135
	v_min_f32_e32 v132, 1.0, v132
	v_min_f32_e32 v133, 1.0, v133
	v_add_co_u32_e32 v144, vcc, s9, v148
	v_min_f32_e32 v32, 1.0, v32
	v_min_f32_e32 v135, 1.0, v135
	v_cvt_pk_bf16_f32 v132, v32, v132
	v_cvt_pk_bf16_f32 v133, v133, v135
	v_addc_co_u32_e32 v145, vcc, -1, v149, vcc
	v_mov_b32_e32 v166, v132
	v_mov_b32_e32 v167, v133
	s_nop 1
	v_permlane16_swap_b32_e32 v164, v166
	v_permlane16_swap_b32_e32 v165, v167
	global_store_dwordx4 v[182:183], v[164:167], off
	v_mul_f32_e32 v132, v1, v136
	v_mul_f32_e32 v133, v2, v136
	v_mul_f32_e32 v32, v0, v136
	v_mul_f32_e32 v132, 0xbfb8aa3b, v132
	v_mul_f32_e32 v133, 0xbfb8aa3b, v133
	v_mul_f32_e32 v135, v3, v136
	v_mul_f32_e32 v32, 0xbfb8aa3b, v32
	v_exp_f32_e32 v132, v132
	v_exp_f32_e32 v133, v133
	v_mul_f32_e32 v135, 0xbfb8aa3b, v135
	v_exp_f32_e32 v32, v32
	v_exp_f32_e32 v135, v135
	v_add_f32_e32 v132, 1.0, v132
	v_add_f32_e32 v133, 1.0, v133
	v_add_f32_e32 v32, 1.0, v32
	v_rcp_f32_e32 v132, v132
	v_rcp_f32_e32 v133, v133
	v_add_f32_e32 v135, 1.0, v135
	v_rcp_f32_e32 v32, v32
	v_rcp_f32_e32 v135, v135
	v_add_co_u32_e32 v144, vcc, 0xffffe160, v150
	v_min_f32_e32 v132, 1.0, v132
	v_min_f32_e32 v133, 1.0, v133
	v_addc_co_u32_e32 v145, vcc, -1, v151, vcc
	v_min_f32_e32 v32, 1.0, v32
	v_min_f32_e32 v135, 1.0, v135
	v_cvt_pk_bf16_f32 v132, v32, v132
	v_cvt_pk_bf16_f32 v133, v133, v135
	v_mov_b32_e32 v174, v132
	v_mov_b32_e32 v175, v133
	s_nop 1
	v_permlane16_swap_b32_e32 v172, v174
	v_permlane16_swap_b32_e32 v173, v175
	global_store_dwordx4 v[192:193], v[172:175], off

; #define EPI_LOOP(...) _Pragma("unroll") for(int ai=0;ai<2;++ai) _Pragma("unroll") for(int bj=0;bj<2;++bj) \
;   _Pragma("unroll") for(int m=0;m<4;++m) _Pragma("unroll") for(int n=0;n<2;++n) { \
;     const int row=brow+ai*128+wr*64+m*16+fq*4; const int col=bcol+bj*128+wc*32+n*16+fr; \
;     f32x4& v=acc[ai][bj][m][n]; __VA_ARGS__ if (n == 1 && (m & 1)) __builtin_amdgcn_sched_barrier(0); }
; DEVI void run_phase(const int ph, const Params& P, char* shmc, const int wave_u) {
;     ...
;       } else if (brow < 4096) {
;         EPI_LOOP({ const float sc = sc4[bj][n]; const int f = row - 3584;
;           float* o = samp ? out + O_CKV_S + (long)(col - MP) * 512 + f : out + O_CKV_P + (long)col * 512 + f;
;           st_f4(o, v[0] * sc, v[1] * sc, v[2] * sc, v[3] * sc); })
.LBB0_1007:
	s_andn2_b64 vcc, exec, s[38:39]
	s_cbranch_vccnz .LBB0_1009
	s_add_i32 s1, s0, 0xfffff200
	v_lshl_or_b32 v32, v168, 2, s1
	s_and_b64 s[8:9], s[6:7], exec
	s_mov_b32 s1, 0x12c00000
	v_lshl_add_u32 v132, v169, 6, v32
	v_add_u32_e32 v32, 0xffffc000, v134
	s_cselect_b32 s1, s1, 0x10400000
	v_readlane_b32 s8, v255, 13
	v_cndmask_b32_e64 v144, v134, v32, s[6:7]
	v_readlane_b32 s9, v255, 14
	s_add_u32 s8, s8, s1
	v_ashrrev_i32_e32 v133, 31, v132
	s_addc_u32 s9, s9, 0
	v_ashrrev_i32_e32 v145, 31, v144
	v_lshl_add_u64 v[132:133], v[132:133], 2, s[8:9]
	v_lshlrev_b64 v[144:145], 11, v[144:145]
	v_lshl_add_u64 v[144:145], v[132:133], 0, v[144:145]
	s_waitcnt vmcnt(0) lgkmcnt(0)
; #define EPI_LOOP(...) _Pragma("unroll") for(int ai=0;ai<2;++ai) _Pragma("unroll") for(int bj=0;bj<2;++bj) \
;   _Pragma("unroll") for(int m=0;m<4;++m) _Pragma("unroll") for(int n=0;n<2;++n) { \
;     const int row=brow+ai*128+wr*64+m*16+fq*4; const int col=bcol+bj*128+wc*32+n*16+fr; \
;     f32x4& v=acc[ai][bj][m][n]; __VA_ARGS__ if (n == 1 && (m & 1)) __builtin_amdgcn_sched_barrier(0); }
; DEVI void run_phase(const int ph, const Params& P, char* shmc, const int wave_u) {
;     ...
;       } else if (brow < 4096) {
;         EPI_LOOP({ const float sc = sc4[bj][n]; const int f = row - 3584;
;           float* o = samp ? out + O_CKV_S + (long)(col - MP) * 512 + f : out + O_CKV_P + (long)col * 512 + f;
;           st_f4(o, v[0] * sc, v[1] * sc, v[2] * sc, v[3] * sc); })
	v_pk_mul_f32 v[150:151], v[128:129], v[142:143] op_sel_hi:[1,0]
	v_pk_mul_f32 v[148:149], v[126:127], v[142:143] op_sel_hi:[1,0]
	v_or_b32_e32 v32, 16, v134
	v_add_u32_e32 v135, 0xffffc010, v134
	global_store_dwordx4 v[144:145], v[148:151], off
	s_nop 1
	v_cndmask_b32_e64 v148, v32, v135, s[6:7]
	v_ashrrev_i32_e32 v149, 31, v148
	v_lshlrev_b64 v[148:149], 11, v[148:149]
	v_lshl_add_u64 v[152:153], v[132:133], 0, v[148:149]
	v_pk_mul_f32 v[150:151], v[124:125], v[140:141] op_sel_hi:[1,0]
	v_pk_mul_f32 v[148:149], v[122:123], v[140:141] op_sel_hi:[1,0]
	global_store_dwordx4 v[152:153], v[148:151], off
	s_nop 1
	v_pk_mul_f32 v[150:151], v[120:121], v[142:143] op_sel_hi:[1,0]
	v_pk_mul_f32 v[148:149], v[118:119], v[142:143] op_sel_hi:[1,0]
	global_store_dwordx4 v[144:145], v[148:151], off offset:64
	s_nop 1
	v_pk_mul_f32 v[150:151], v[116:117], v[140:141] op_sel_hi:[1,0]
	v_pk_mul_f32 v[148:149], v[114:115], v[140:141] op_sel_hi:[1,0]
	global_store_dwordx4 v[152:153], v[148:151], off offset:64
	s_nop 1
	v_pk_mul_f32 v[150:151], v[112:113], v[142:143] op_sel_hi:[1,0]
	v_pk_mul_f32 v[148:149], v[110:111], v[142:143] op_sel_hi:[1,0]
	global_store_dwordx4 v[144:145], v[148:151], off offset:128
	s_nop 1
	v_pk_mul_f32 v[150:151], v[108:109], v[140:141] op_sel_hi:[1,0]
	v_pk_mul_f32 v[148:149], v[106:107], v[140:141] op_sel_hi:[1,0]
	global_store_dwordx4 v[152:153], v[148:151], off offset:128
	s_nop 1
	v_pk_mul_f32 v[150:151], v[104:105], v[142:143] op_sel_hi:[1,0]
	v_pk_mul_f32 v[148:149], v[102:103], v[142:143] op_sel_hi:[1,0]
	global_store_dwordx4 v[144:145], v[148:151], off offset:192
	s_nop 1
	v_pk_mul_f32 v[150:151], v[100:101], v[140:141] op_sel_hi:[1,0]
	v_pk_mul_f32 v[148:149], v[98:99], v[140:141] op_sel_hi:[1,0]
	global_store_dwordx4 v[152:153], v[148:151], off offset:192
	v_or_b32_e32 v32, 0x80, v134
	v_add_u32_e32 v135, 0xffffc080, v134
	v_cndmask_b32_e64 v148, v32, v135, s[6:7]
	v_ashrrev_i32_e32 v149, 31, v148
	v_lshlrev_b64 v[148:149], 11, v[148:149]
	v_lshl_add_u64 v[154:155], v[132:133], 0, v[148:149]
	v_pk_mul_f32 v[150:151], v[96:97], v[138:139] op_sel_hi:[1,0]
	v_pk_mul_f32 v[148:149], v[94:95], v[138:139] op_sel_hi:[1,0]
	v_or_b32_e32 v32, 0x90, v134
	v_add_u32_e32 v135, 0xffffc090, v134
	global_store_dwordx4 v[154:155], v[148:151], off
	s_nop 1
	v_cndmask_b32_e64 v148, v32, v135, s[6:7]
	v_ashrrev_i32_e32 v149, 31, v148
	v_lshlrev_b64 v[148:149], 11, v[148:149]
	v_lshl_add_u64 v[132:133], v[132:133], 0, v[148:149]
	v_pk_mul_f32 v[150:151], v[92:93], v[136:137] op_sel_hi:[1,0]
	v_pk_mul_f32 v[148:149], v[90:91], v[136:137] op_sel_hi:[1,0]
	global_store_dwordx4 v[132:133], v[148:151], off
	s_nop 1
	v_pk_mul_f32 v[150:151], v[88:89], v[138:139] op_sel_hi:[1,0]
	v_pk_mul_f32 v[148:149], v[86:87], v[138:139] op_sel_hi:[1,0]
	global_store_dwordx4 v[154:155], v[148:151], off offset:64
	s_nop 1
	v_pk_mul_f32 v[150:151], v[84:85], v[136:137] op_sel_hi:[1,0]
	v_pk_mul_f32 v[148:149], v[82:83], v[136:137] op_sel_hi:[1,0]
	global_store_dwordx4 v[132:133], v[148:151], off offset:64
	s_nop 1
	v_pk_mul_f32 v[150:151], v[80:81], v[138:139] op_sel_hi:[1,0]
	v_pk_mul_f32 v[148:149], v[78:79], v[138:139] op_sel_hi:[1,0]
	global_store_dwordx4 v[154:155], v[148:151], off offset:128
	s_nop 1
	v_pk_mul_f32 v[150:151], v[76:77], v[136:137] op_sel_hi:[1,0]
	v_pk_mul_f32 v[148:149], v[74:75], v[136:137] op_sel_hi:[1,0]
	global_store_dwordx4 v[132:133], v[148:151], off offset:128
	s_nop 1
	v_pk_mul_f32 v[150:151], v[72:73], v[138:139] op_sel_hi:[1,0]
	v_pk_mul_f32 v[148:149], v[70:71], v[138:139] op_sel_hi:[1,0]
	global_store_dwordx4 v[154:155], v[148:151], off offset:192
	s_nop 1
	v_pk_mul_f32 v[150:151], v[68:69], v[136:137] op_sel_hi:[1,0]
	v_pk_mul_f32 v[148:149], v[66:67], v[136:137] op_sel_hi:[1,0]
	global_store_dwordx4 v[132:133], v[148:151], off offset:192
	s_nop 1
	v_pk_mul_f32 v[150:151], v[64:65], v[142:143] op_sel_hi:[1,0]
	v_pk_mul_f32 v[148:149], v[62:63], v[142:143] op_sel_hi:[1,0]
	global_store_dwordx4 v[144:145], v[148:151], off offset:512
	s_nop 1
	v_pk_mul_f32 v[150:151], v[60:61], v[140:141] op_sel_hi:[1,0]
	v_pk_mul_f32 v[148:149], v[58:59], v[140:141] op_sel_hi:[1,0]
	global_store_dwordx4 v[152:153], v[148:151], off offset:512
	s_nop 1
	v_pk_mul_f32 v[150:151], v[56:57], v[142:143] op_sel_hi:[1,0]
	v_pk_mul_f32 v[148:149], v[54:55], v[142:143] op_sel_hi:[1,0]
	global_store_dwordx4 v[144:145], v[148:151], off offset:576
	s_nop 1
	v_pk_mul_f32 v[150:151], v[52:53], v[140:141] op_sel_hi:[1,0]
	v_pk_mul_f32 v[148:149], v[50:51], v[140:141] op_sel_hi:[1,0]
	global_store_dwordx4 v[152:153], v[148:151], off offset:576
	s_nop 1
	v_pk_mul_f32 v[150:151], v[48:49], v[142:143] op_sel_hi:[1,0]
	v_pk_mul_f32 v[148:149], v[46:47], v[142:143] op_sel_hi:[1,0]
	global_store_dwordx4 v[144:145], v[148:151], off offset:640
	s_nop 1
	v_pk_mul_f32 v[150:151], v[44:45], v[140:141] op_sel_hi:[1,0]
	v_pk_mul_f32 v[148:149], v[42:43], v[140:141] op_sel_hi:[1,0]
	global_store_dwordx4 v[152:153], v[148:151], off offset:640
	s_nop 1
	v_pk_mul_f32 v[150:151], v[40:41], v[142:143] op_sel_hi:[1,0]
	v_pk_mul_f32 v[148:149], v[38:39], v[142:143] op_sel_hi:[1,0]
	global_store_dwordx4 v[144:145], v[148:151], off offset:704
	s_nop 1
	v_pk_mul_f32 v[150:151], v[36:37], v[140:141] op_sel_hi:[1,0]
	v_pk_mul_f32 v[148:149], v[34:35], v[140:141] op_sel_hi:[1,0]
	global_store_dwordx4 v[152:153], v[148:151], off offset:704
	s_nop 1
	v_pk_mul_f32 v[150:151], v[30:31], v[138:139] op_sel_hi:[1,0]
	v_pk_mul_f32 v[148:149], v[28:29], v[138:139] op_sel_hi:[1,0]
	global_store_dwordx4 v[154:155], v[148:151], off offset:512
	s_nop 1
	v_pk_mul_f32 v[150:151], v[26:27], v[136:137] op_sel_hi:[1,0]
	v_pk_mul_f32 v[148:149], v[24:25], v[136:137] op_sel_hi:[1,0]
	global_store_dwordx4 v[132:133], v[148:151], off offset:512
	s_nop 1
	v_pk_mul_f32 v[150:151], v[22:23], v[138:139] op_sel_hi:[1,0]
	v_pk_mul_f32 v[148:149], v[20:21], v[138:139] op_sel_hi:[1,0]
	global_store_dwordx4 v[154:155], v[148:151], off offset:576
	s_nop 1
	v_pk_mul_f32 v[150:151], v[18:19], v[136:137] op_sel_hi:[1,0]
	v_pk_mul_f32 v[148:149], v[16:17], v[136:137] op_sel_hi:[1,0]
	global_store_dwordx4 v[132:133], v[148:151], off offset:576
	s_nop 1
	v_pk_mul_f32 v[150:151], v[14:15], v[138:139] op_sel_hi:[1,0]
	v_pk_mul_f32 v[148:149], v[12:13], v[138:139] op_sel_hi:[1,0]
	global_store_dwordx4 v[154:155], v[148:151], off offset:640
	s_nop 1
	v_pk_mul_f32 v[150:151], v[10:11], v[136:137] op_sel_hi:[1,0]
	v_pk_mul_f32 v[148:149], v[8:9], v[136:137] op_sel_hi:[1,0]
	global_store_dwordx4 v[132:133], v[148:151], off offset:640
	s_nop 1
	v_pk_mul_f32 v[150:151], v[6:7], v[138:139] op_sel_hi:[1,0]
	v_pk_mul_f32 v[148:149], v[4:5], v[138:139] op_sel_hi:[1,0]
	global_store_dwordx4 v[154:155], v[148:151], off offset:704
	s_nop 1
	v_pk_mul_f32 v[150:151], v[2:3], v[136:137] op_sel_hi:[1,0]
	v_pk_mul_f32 v[148:149], v[0:1], v[136:137] op_sel_hi:[1,0]
	global_store_dwordx4 v[132:133], v[148:151], off offset:704

; DEVI int RSI(int row) { return ((row >> 3) << 5) | (row & 7); }
; DEVI float shflx(float v, int o, int lane) { return __int_as_float(__builtin_amdgcn_ds_bpermute((lane ^ o) << 2, __float_as_int(v))); }
; #define EPI_LOOP(...) _Pragma("unroll") for(int ai=0;ai<2;++ai) _Pragma("unroll") for(int bj=0;bj<2;++bj) \
;   _Pragma("unroll") for(int m=0;m<4;++m) _Pragma("unroll") for(int n=0;n<2;++n) { \
;     const int row=brow+ai*128+wr*64+m*16+fq*4; const int col=bcol+bj*128+wc*32+n*16+fr; \
;     f32x4& v=acc[ai][bj][m][n]; __VA_ARGS__ if (n == 1 && (m & 1)) __builtin_amdgcn_sched_barrier(0); }
; DEVI void run_phase(const int ph, const Params& P, char* shmc, const int wave_u) {
;     ...
;       } else if (brow < 3584) {
;         float ssl[2][2] = {{0.f, 0.f}, {0.f, 0.f}};
;         EPI_LOOP({ const float sc = sc4[bj][n]; const int f = row - 3072; const float a = v[0] * sc, b = v[1] * sc, c = v[2] * sc, d = v[3] * sc;
;           st_bf4(cq + (long)col * 512 + f, a, b, c, d); ssl[bj][n] += a * a + b * b + c * c + d * d; })
; #pragma unroll
;         for (int bj = 0; bj < 2; ++bj)
; #pragma unroll
;           for (int n = 0; n < 2; ++n) { float s = ssl[bj][n]; s += shflx(s, 16, lane); s += shflx(s, 32, lane);
;             if (fq == 0) unsafeAtomicAdd(&ssq[RSI(bcol + bj * 128 + wc * 32 + n * 16 + fr)], s); }
.LBB0_1010:
	s_andn2_b64 vcc, exec, s[38:39]
	s_cbranch_vccnz .LBB0_1020
	v_lshl_add_u32 v132, v169, 6, s0
	v_lshl_or_b32 v132, v168, 2, v132
	v_readlane_b32 s6, v255, 33
	v_ashrrev_i32_e32 v133, 31, v132
	v_readlane_b32 s7, v255, 34
	v_ashrrev_i32_e32 v135, 31, v134
	s_movk_i32 s1, 0xe800
	v_lshl_add_u64 v[150:151], v[132:133], 1, s[6:7]
	v_lshlrev_b64 v[132:133], 10, v[134:135]
	v_lshl_add_u64 v[132:133], v[150:151], 0, v[132:133]
	v_add_co_u32_e32 v148, vcc, s1, v132
	v_and_b32_e32 v32, 63, v137
	s_waitcnt vmcnt(0) lgkmcnt(0)
	v_mul_f32_e32 v137, v126, v142
	v_mul_f32_e32 v139, v127, v142
	v_cvt_pk_bf16_f32 v144, v137, v139
	v_addc_co_u32_e32 v149, vcc, -1, v133, vcc
	v_mul_f32_e32 v141, v128, v142
	v_mul_f32_e32 v143, v129, v142
	v_cvt_pk_bf16_f32 v145, v141, v143
	global_store_dwordx2 v[148:149], v[144:145], off
	v_or_b32_e32 v144, 16, v134
	v_ashrrev_i32_e32 v145, 31, v144
	v_lshlrev_b64 v[144:145], 10, v[144:145]
	v_mul_f32_e32 v135, v139, v139
	v_lshl_add_u64 v[144:145], v[150:151], 0, v[144:145]
	v_fmac_f32_e32 v135, v137, v137
	v_add_co_u32_e32 v156, vcc, s1, v144
	v_fmac_f32_e32 v135, v141, v141
	v_mul_f32_e32 v152, v122, v140
	v_mul_f32_e32 v154, v123, v140
	v_cvt_pk_bf16_f32 v148, v152, v154
	v_addc_co_u32_e32 v157, vcc, -1, v145, vcc
	v_mul_f32_e32 v139, v119, v142
	v_fmac_f32_e32 v135, v143, v143
	v_mul_f32_e32 v153, v124, v140
	v_mul_f32_e32 v143, v125, v140
	v_cvt_pk_bf16_f32 v149, v153, v143
	global_store_dwordx2 v[156:157], v[148:149], off
	v_mul_f32_e32 v137, v118, v142
	v_cvt_pk_bf16_f32 v148, v137, v139
	s_movk_i32 s4, 0xe820
	v_mul_f32_e32 v139, v139, v139
	v_mul_f32_e32 v141, v120, v142
	v_add_co_u32_e32 v156, vcc, s4, v132
	v_fmac_f32_e32 v139, v137, v137
	v_mul_f32_e32 v155, v121, v142
	v_addc_co_u32_e32 v157, vcc, -1, v133, vcc
	v_fmac_f32_e32 v139, v141, v141
	v_cvt_pk_bf16_f32 v149, v141, v155
	global_store_dwordx2 v[156:157], v[148:149], off
	v_fmac_f32_e32 v139, v155, v155
	v_add_co_u32_e32 v156, vcc, s4, v144
	v_add_f32_e32 v135, v135, v139
	v_mul_f32_e32 v160, v114, v140
	v_mul_f32_e32 v162, v115, v140
	v_mul_f32_e32 v161, v116, v140
	v_mul_f32_e32 v159, v117, v140
	v_addc_co_u32_e32 v157, vcc, -1, v145, vcc
	v_cvt_pk_bf16_f32 v148, v160, v162
	v_cvt_pk_bf16_f32 v149, v161, v159
	global_store_dwordx2 v[156:157], v[148:149], off
	v_mul_f32_e32 v139, v111, v142
	v_mul_f32_e32 v137, v110, v142
	v_cvt_pk_bf16_f32 v148, v137, v139
	s_movk_i32 s6, 0xe840
	v_mul_f32_e32 v139, v139, v139
	v_mul_f32_e32 v141, v112, v142
	v_add_co_u32_e32 v156, vcc, s6, v132
	v_fmac_f32_e32 v139, v137, v137
	v_mul_f32_e32 v155, v113, v142
	v_addc_co_u32_e32 v157, vcc, -1, v133, vcc
	v_fmac_f32_e32 v139, v141, v141
	v_cvt_pk_bf16_f32 v149, v141, v155
	global_store_dwordx2 v[156:157], v[148:149], off
	v_fmac_f32_e32 v139, v155, v155
	v_add_co_u32_e32 v156, vcc, s6, v144
	v_add_f32_e32 v135, v139, v135
	v_mul_f32_e32 v179, v106, v140
	v_mul_f32_e32 v181, v107, v140
	v_cvt_pk_bf16_f32 v148, v179, v181
	v_addc_co_u32_e32 v157, vcc, -1, v145, vcc
	v_mul_f32_e32 v139, v103, v142
	v_mul_f32_e32 v180, v108, v140
	v_mul_f32_e32 v177, v109, v140
	v_cvt_pk_bf16_f32 v149, v180, v177
	global_store_dwordx2 v[156:157], v[148:149], off
	v_mul_f32_e32 v137, v102, v142
	v_cvt_pk_bf16_f32 v148, v137, v139
	s_movk_i32 s7, 0xe860
	v_mul_f32_e32 v139, v139, v139
	v_mul_f32_e32 v141, v104, v142
	v_add_co_u32_e32 v156, vcc, s7, v132
	v_fmac_f32_e32 v139, v137, v137
	v_mul_f32_e32 v155, v105, v142
	v_addc_co_u32_e32 v157, vcc, -1, v133, vcc
	v_fmac_f32_e32 v139, v141, v141
	v_cvt_pk_bf16_f32 v149, v141, v155
	global_store_dwordx2 v[156:157], v[148:149], off
	v_fmac_f32_e32 v139, v155, v155
	v_add_co_u32_e32 v156, vcc, s7, v144
	v_add_f32_e32 v210, v139, v135
	v_mul_f32_e32 v195, v98, v140
	v_mul_f32_e32 v197, v99, v140
	v_mul_f32_e32 v196, v100, v140
	v_mul_f32_e32 v194, v101, v140
	v_addc_co_u32_e32 v157, vcc, -1, v145, vcc
	v_cvt_pk_bf16_f32 v148, v195, v197
	v_cvt_pk_bf16_f32 v149, v196, v194
	global_store_dwordx2 v[156:157], v[148:149], off
	v_or_b32_e32 v148, 0x80, v134
	v_ashrrev_i32_e32 v149, 31, v148
	v_lshlrev_b64 v[148:149], 10, v[148:149]
	v_lshl_add_u64 v[148:149], v[150:151], 0, v[148:149]
	v_add_co_u32_e32 v164, vcc, s1, v148
	v_mul_f32_e32 v171, v94, v138
	v_mul_f32_e32 v173, v95, v138
	v_cvt_pk_bf16_f32 v156, v171, v173
	v_addc_co_u32_e32 v165, vcc, -1, v149, vcc
	v_mul_f32_e32 v172, v96, v138
	v_mul_f32_e32 v167, v97, v138
	v_cvt_pk_bf16_f32 v157, v172, v167
	global_store_dwordx2 v[164:165], v[156:157], off
	v_or_b32_e32 v156, 0x90, v134
	v_ashrrev_i32_e32 v157, 31, v156
	v_lshlrev_b64 v[156:157], 10, v[156:157]
	v_lshl_add_u64 v[150:151], v[150:151], 0, v[156:157]
	v_add_co_u32_e32 v164, vcc, s1, v150
	v_mul_f32_e32 v137, v90, v136
	s_nop 0
	v_addc_co_u32_e32 v165, vcc, -1, v151, vcc
	v_mul_f32_e32 v141, v91, v136
	v_mul_f32_e32 v139, v92, v136
	v_mul_f32_e32 v135, v93, v136
	v_cvt_pk_bf16_f32 v156, v137, v141
	v_cvt_pk_bf16_f32 v157, v139, v135
	global_store_dwordx2 v[164:165], v[156:157], off
	v_add_co_u32_e32 v164, vcc, s4, v148
	v_mul_f32_e32 v183, v86, v138
	s_nop 0
	v_addc_co_u32_e32 v165, vcc, -1, v149, vcc
	v_mul_f32_e32 v193, v87, v138
	v_mul_f32_e32 v192, v88, v138
	v_mul_f32_e32 v182, v89, v138
	v_cvt_pk_bf16_f32 v156, v183, v193
	v_cvt_pk_bf16_f32 v157, v192, v182
	v_add_co_u32_e32 v174, vcc, s4, v150
	global_store_dwordx2 v[164:165], v[156:157], off
	v_mul_f32_e32 v156, v82, v136
	v_mul_f32_e32 v158, v83, v136
	v_mul_f32_e32 v157, v84, v136
	v_mul_f32_e32 v155, v85, v136
	v_addc_co_u32_e32 v175, vcc, -1, v151, vcc
	v_cvt_pk_bf16_f32 v164, v156, v158
	v_cvt_pk_bf16_f32 v165, v157, v155
	global_store_dwordx2 v[174:175], v[164:165], off
; DEVI int RSI(int row) { return ((row >> 3) << 5) | (row & 7); }
; DEVI float shflx(float v, int o, int lane) { return __int_as_float(__builtin_amdgcn_ds_bpermute((lane ^ o) << 2, __float_as_int(v))); }
; #define EPI_LOOP(...) _Pragma("unroll") for(int ai=0;ai<2;++ai) _Pragma("unroll") for(int bj=0;bj<2;++bj) \
;   _Pragma("unroll") for(int m=0;m<4;++m) _Pragma("unroll") for(int n=0;n<2;++n) { \
;     const int row=brow+ai*128+wr*64+m*16+fq*4; const int col=bcol+bj*128+wc*32+n*16+fr; \
;     f32x4& v=acc[ai][bj][m][n]; __VA_ARGS__ if (n == 1 && (m & 1)) __builtin_amdgcn_sched_barrier(0); }
; DEVI void run_phase(const int ph, const Params& P, char* shmc, const int wave_u) {
;     ...
;       } else if (brow < 3584) {
;         float ssl[2][2] = {{0.f, 0.f}, {0.f, 0.f}};
;         EPI_LOOP({ const float sc = sc4[bj][n]; const int f = row - 3072; const float a = v[0] * sc, b = v[1] * sc, c = v[2] * sc, d = v[3] * sc;
;           st_bf4(cq + (long)col * 512 + f, a, b, c, d); ssl[bj][n] += a * a + b * b + c * c + d * d; })
; #pragma unroll
;         for (int bj = 0; bj < 2; ++bj)
; #pragma unroll
;           for (int n = 0; n < 2; ++n) { float s = ssl[bj][n]; s += shflx(s, 16, lane); s += shflx(s, 32, lane);
;             if (fq == 0) unsafeAtomicAdd(&ssq[RSI(bcol + bj * 128 + wc * 32 + n * 16 + fr)], s); }
	v_add_co_u32_e32 v174, vcc, s6, v148
	v_mul_f32_e32 v199, v78, v138
	s_nop 0
	v_addc_co_u32_e32 v175, vcc, -1, v149, vcc
	v_add_co_u32_e32 v202, vcc, s6, v150
	v_mul_f32_e32 v201, v79, v138
	s_nop 0
	v_addc_co_u32_e32 v203, vcc, -1, v151, vcc
	v_mul_f32_e32 v200, v80, v138
	v_mul_f32_e32 v198, v81, v138
	v_cvt_pk_bf16_f32 v164, v199, v201
	v_cvt_pk_bf16_f32 v165, v200, v198
	v_add_co_u32_e32 v206, vcc, s7, v148
	global_store_dwordx2 v[174:175], v[164:165], off
	v_mul_f32_e32 v164, v74, v136
	v_mul_f32_e32 v166, v75, v136
	v_mul_f32_e32 v165, v76, v136
	v_mul_f32_e32 v163, v77, v136
	v_cvt_pk_bf16_f32 v174, v164, v166
	v_cvt_pk_bf16_f32 v175, v165, v163
	v_addc_co_u32_e32 v207, vcc, -1, v149, vcc
	global_store_dwordx2 v[202:203], v[174:175], off
	v_mul_f32_e32 v203, v70, v138
	v_mul_f32_e32 v205, v71, v138
	v_mul_f32_e32 v204, v72, v138
	v_mul_f32_e32 v202, v73, v138
	v_cvt_pk_bf16_f32 v174, v203, v205
	v_cvt_pk_bf16_f32 v175, v204, v202
	v_add_co_u32_e32 v208, vcc, s7, v150
	global_store_dwordx2 v[206:207], v[174:175], off
	v_mul_f32_e32 v175, v66, v136
	v_mul_f32_e32 v178, v67, v136
	v_mul_f32_e32 v176, v68, v136
	v_mul_f32_e32 v174, v69, v136
	v_addc_co_u32_e32 v209, vcc, -1, v151, vcc
	v_cvt_pk_bf16_f32 v206, v175, v178
	v_cvt_pk_bf16_f32 v207, v176, v174
	global_store_dwordx2 v[208:209], v[206:207], off
	s_movk_i32 s1, 0xe900
	v_add_co_u32_e32 v208, vcc, s1, v132
	v_mul_f32_e32 v211, v62, v142
	v_mul_f32_e32 v212, v63, v142
	v_cvt_pk_bf16_f32 v206, v211, v212
	v_addc_co_u32_e32 v209, vcc, -1, v133, vcc
	v_mul_f32_e32 v213, v64, v142
	v_mul_f32_e32 v214, v65, v142
	v_cvt_pk_bf16_f32 v207, v213, v214
	global_store_dwordx2 v[208:209], v[206:207], off
	v_mul_f32_e32 v206, v212, v212
	v_fmac_f32_e32 v206, v211, v211
	v_fmac_f32_e32 v206, v213, v213
	v_fmac_f32_e32 v206, v214, v214
	v_add_co_u32_e32 v214, vcc, s1, v144
	s_movk_i32 s4, 0xe920
	s_nop 0
	v_addc_co_u32_e32 v215, vcc, -1, v145, vcc
	v_add_f32_e32 v207, v206, v210
	v_mul_f32_e32 v208, v58, v140
	v_mul_f32_e32 v212, v59, v140
	v_mul_f32_e32 v209, v60, v140
	v_mul_f32_e32 v206, v61, v140
	v_cvt_pk_bf16_f32 v210, v208, v212
	v_cvt_pk_bf16_f32 v211, v209, v206
	global_store_dwordx2 v[214:215], v[210:211], off
	v_add_co_u32_e32 v214, vcc, s4, v132
	v_mul_f32_e32 v213, v54, v142
	v_mul_f32_e32 v216, v55, v142
	v_cvt_pk_bf16_f32 v210, v213, v216
	v_addc_co_u32_e32 v215, vcc, -1, v133, vcc
	v_mul_f32_e32 v217, v56, v142
	v_mul_f32_e32 v218, v57, v142
	v_cvt_pk_bf16_f32 v211, v217, v218
	global_store_dwordx2 v[214:215], v[210:211], off
	v_mul_f32_e32 v210, v216, v216
	v_fmac_f32_e32 v210, v213, v213
	v_fmac_f32_e32 v210, v217, v217
	v_fmac_f32_e32 v210, v218, v218
	v_add_co_u32_e32 v214, vcc, s4, v144
	v_add_f32_e32 v207, v210, v207
	v_mul_f32_e32 v219, v50, v140
	v_mul_f32_e32 v221, v51, v140
	v_mul_f32_e32 v220, v52, v140
	v_mul_f32_e32 v218, v53, v140
	v_addc_co_u32_e32 v215, vcc, -1, v145, vcc
	v_cvt_pk_bf16_f32 v210, v219, v221
	v_cvt_pk_bf16_f32 v211, v220, v218
	global_store_dwordx2 v[214:215], v[210:211], off
	s_movk_i32 s6, 0xe940
	v_add_co_u32_e32 v214, vcc, s6, v132
	v_mul_f32_e32 v213, v46, v142
	v_mul_f32_e32 v216, v47, v142
	v_cvt_pk_bf16_f32 v210, v213, v216
	v_addc_co_u32_e32 v215, vcc, -1, v133, vcc
	v_mul_f32_e32 v217, v48, v142
	v_mul_f32_e32 v222, v49, v142
	v_cvt_pk_bf16_f32 v211, v217, v222
	global_store_dwordx2 v[214:215], v[210:211], off
	v_mul_f32_e32 v210, v216, v216
	v_fmac_f32_e32 v210, v213, v213
	v_add_co_u32_e32 v214, vcc, s6, v144
	v_fmac_f32_e32 v210, v217, v217
	s_nop 0
	v_addc_co_u32_e32 v215, vcc, -1, v145, vcc
	s_movk_i32 s7, 0xe960
	v_fmac_f32_e32 v210, v222, v222
	v_add_co_u32_e32 v132, vcc, s7, v132
	v_add_f32_e32 v207, v210, v207
	v_mul_f32_e32 v229, v42, v140
	v_mul_f32_e32 v231, v43, v140
	v_mul_f32_e32 v230, v44, v140
	v_mul_f32_e32 v228, v45, v140
	v_cvt_pk_bf16_f32 v210, v229, v231
	v_cvt_pk_bf16_f32 v211, v230, v228
	global_store_dwordx2 v[214:215], v[210:211], off
	v_mul_f32_e32 v214, v39, v142
	v_addc_co_u32_e32 v133, vcc, -1, v133, vcc
	v_mul_f32_e32 v213, v38, v142
	v_mul_f32_e32 v215, v40, v142
	v_mul_f32_e32 v216, v41, v142
	v_cvt_pk_bf16_f32 v210, v213, v214
	v_cvt_pk_bf16_f32 v211, v215, v216
	global_store_dwordx2 v[132:133], v[210:211], off
	v_mul_f32_e32 v132, v214, v214
	v_fmac_f32_e32 v132, v213, v213
	v_fmac_f32_e32 v132, v215, v215
	v_add_co_u32_e32 v144, vcc, s7, v144
	v_fmac_f32_e32 v132, v216, v216
	v_mul_f32_e32 v237, v34, v140
	v_mul_f32_e32 v242, v35, v140
	v_mul_f32_e32 v238, v36, v140
	v_mul_f32_e32 v236, v37, v140
	v_addc_co_u32_e32 v145, vcc, -1, v145, vcc
	v_add_f32_e32 v250, v132, v207
	v_cvt_pk_bf16_f32 v132, v237, v242
	v_cvt_pk_bf16_f32 v133, v238, v236
	global_store_dwordx2 v[144:145], v[132:133], off
	v_add_co_u32_e32 v144, vcc, s1, v148
	v_mul_f32_e32 v223, v28, v138
	s_nop 0
	v_addc_co_u32_e32 v145, vcc, -1, v149, vcc
	v_add_co_u32_e32 v214, vcc, s1, v150
	v_mul_f32_e32 v226, v29, v138
	v_mul_f32_e32 v224, v30, v138
	v_mul_f32_e32 v222, v31, v138
	v_cvt_pk_bf16_f32 v132, v223, v226
	v_cvt_pk_bf16_f32 v133, v224, v222
	v_addc_co_u32_e32 v215, vcc, -1, v151, vcc
	global_store_dwordx2 v[144:145], v[132:133], off
	v_mul_f32_e32 v133, v24, v136
	v_mul_f32_e32 v145, v25, v136
	v_mul_f32_e32 v144, v26, v136
	v_mul_f32_e32 v132, v27, v136
	v_cvt_pk_bf16_f32 v210, v133, v145
	v_cvt_pk_bf16_f32 v211, v144, v132
	global_store_dwordx2 v[214:215], v[210:211], off
	v_add_co_u32_e32 v214, vcc, s4, v148
	v_mul_f32_e32 v233, v20, v138
	s_nop 0
	v_addc_co_u32_e32 v215, vcc, -1, v149, vcc
	v_mul_f32_e32 v235, v21, v138
	v_mul_f32_e32 v234, v22, v138
	v_mul_f32_e32 v232, v23, v138
	v_cvt_pk_bf16_f32 v210, v233, v235
; DEVI int RSI(int row) { return ((row >> 3) << 5) | (row & 7); }
; DEVI float shflx(float v, int o, int lane) { return __int_as_float(__builtin_amdgcn_ds_bpermute((lane ^ o) << 2, __float_as_int(v))); }
; #define EPI_LOOP(...) _Pragma("unroll") for(int ai=0;ai<2;++ai) _Pragma("unroll") for(int bj=0;bj<2;++bj) \
;   _Pragma("unroll") for(int m=0;m<4;++m) _Pragma("unroll") for(int n=0;n<2;++n) { \
;     const int row=brow+ai*128+wr*64+m*16+fq*4; const int col=bcol+bj*128+wc*32+n*16+fr; \
;     f32x4& v=acc[ai][bj][m][n]; __VA_ARGS__ if (n == 1 && (m & 1)) __builtin_amdgcn_sched_barrier(0); }
; DEVI void run_phase(const int ph, const Params& P, char* shmc, const int wave_u) {
;     ...
;       } else if (brow < 3584) {
;         float ssl[2][2] = {{0.f, 0.f}, {0.f, 0.f}};
;         EPI_LOOP({ const float sc = sc4[bj][n]; const int f = row - 3072; const float a = v[0] * sc, b = v[1] * sc, c = v[2] * sc, d = v[3] * sc;
;           st_bf4(cq + (long)col * 512 + f, a, b, c, d); ssl[bj][n] += a * a + b * b + c * c + d * d; })
; #pragma unroll
;         for (int bj = 0; bj < 2; ++bj)
; #pragma unroll
;           for (int n = 0; n < 2; ++n) { float s = ssl[bj][n]; s += shflx(s, 16, lane); s += shflx(s, 32, lane);
;             if (fq == 0) unsafeAtomicAdd(&ssq[RSI(bcol + bj * 128 + wc * 32 + n * 16 + fr)], s); }
	v_cvt_pk_bf16_f32 v211, v234, v232
	v_add_co_u32_e32 v216, vcc, s4, v150
	global_store_dwordx2 v[214:215], v[210:211], off
	v_mul_f32_e32 v210, v16, v136
	v_mul_f32_e32 v213, v17, v136
	v_mul_f32_e32 v211, v18, v136
	v_mul_f32_e32 v207, v19, v136
	v_addc_co_u32_e32 v217, vcc, -1, v151, vcc
	v_cvt_pk_bf16_f32 v214, v210, v213
	v_cvt_pk_bf16_f32 v215, v211, v207
	global_store_dwordx2 v[216:217], v[214:215], off
	v_add_co_u32_e32 v216, vcc, s6, v148
	v_mul_f32_e32 v240, v12, v138
	s_nop 0
	v_addc_co_u32_e32 v217, vcc, -1, v149, vcc
	v_add_co_u32_e32 v246, vcc, s6, v150
	v_mul_f32_e32 v243, v13, v138
	s_nop 0
	v_addc_co_u32_e32 v247, vcc, -1, v151, vcc
	v_add_co_u32_e32 v148, vcc, s7, v148
	v_mul_f32_e32 v241, v14, v138
	v_mul_f32_e32 v239, v15, v138
	v_cvt_pk_bf16_f32 v214, v240, v243
	v_cvt_pk_bf16_f32 v215, v241, v239
	v_addc_co_u32_e32 v149, vcc, -1, v149, vcc
	global_store_dwordx2 v[216:217], v[214:215], off
	v_mul_f32_e32 v215, v8, v136
	v_mul_f32_e32 v217, v9, v136
	v_mul_f32_e32 v216, v10, v136
	v_mul_f32_e32 v214, v11, v136
	v_cvt_pk_bf16_f32 v244, v215, v217
	v_cvt_pk_bf16_f32 v245, v216, v214
	v_add_co_u32_e32 v150, vcc, 0xffffe960, v150
	global_store_dwordx2 v[246:247], v[244:245], off
	v_mul_f32_e32 v245, v4, v138
	v_mul_f32_e32 v247, v5, v138
	v_mul_f32_e32 v246, v6, v138
	v_mul_f32_e32 v244, v7, v138
	v_cvt_pk_bf16_f32 v248, v245, v247
	v_cvt_pk_bf16_f32 v249, v246, v244
	global_store_dwordx2 v[148:149], v[248:249], off
	v_mul_f32_e32 v149, v0, v136
	v_mul_f32_e32 v227, v1, v136
	v_mul_f32_e32 v225, v2, v136
	v_mul_f32_e32 v148, v3, v136
	v_addc_co_u32_e32 v151, vcc, -1, v151, vcc
	v_cvt_pk_bf16_f32 v248, v149, v227
	v_cvt_pk_bf16_f32 v249, v225, v148
	global_store_dwordx2 v[150:151], v[248:249], off
	v_lshlrev_b32_e32 v151, 2, v32
	v_xor_b32_e32 v150, 64, v151
	ds_bpermute_b32 v248, v150, v250
	v_xor_b32_e32 v151, 0x80, v151
	v_readlane_b32 s6, v255, 25
	v_readlane_b32 s7, v255, 26
	v_cmp_gt_u32_e32 vcc, 16, v32
	s_waitcnt lgkmcnt(0)
	v_add_f32_e32 v248, v250, v248
	ds_bpermute_b32 v249, v151, v248
	v_lshl_add_u64 v[130:131], v[130:131], 2, s[6:7]
	s_and_saveexec_b64 s[6:7], vcc
	s_cbranch_execz .LBB0_1013
	s_waitcnt lgkmcnt(0)
	v_add_f32_e32 v32, v248, v249
	global_atomic_add_f32 v[130:131], v32, off
.LBB0_1013:
	s_or_b64 exec, exec, s[6:7]
	v_mul_f32_e32 v32, v154, v154
	v_fmac_f32_e32 v32, v152, v152
	v_fmac_f32_e32 v32, v153, v153
	v_fmac_f32_e32 v32, v143, v143
	v_mul_f32_e32 v143, v162, v162
	v_fmac_f32_e32 v143, v160, v160
	v_fmac_f32_e32 v143, v161, v161
	v_fmac_f32_e32 v143, v159, v159
	v_add_f32_e32 v32, v32, v143
	v_mul_f32_e32 v143, v181, v181
	v_fmac_f32_e32 v143, v179, v179
	v_fmac_f32_e32 v143, v180, v180
	v_fmac_f32_e32 v143, v177, v177
	v_add_f32_e32 v32, v143, v32
	v_mul_f32_e32 v143, v197, v197
	v_fmac_f32_e32 v143, v195, v195
	v_fmac_f32_e32 v143, v196, v196
	v_fmac_f32_e32 v143, v194, v194
	v_add_f32_e32 v32, v143, v32
	v_mul_f32_e32 v143, v212, v212
	v_fmac_f32_e32 v143, v208, v208
	v_fmac_f32_e32 v143, v209, v209
	v_fmac_f32_e32 v143, v206, v206
	v_add_f32_e32 v32, v143, v32
	v_mul_f32_e32 v143, v221, v221
	v_fmac_f32_e32 v143, v219, v219
	v_fmac_f32_e32 v143, v220, v220
	v_fmac_f32_e32 v143, v218, v218
	v_add_f32_e32 v32, v143, v32
	v_mul_f32_e32 v143, v231, v231
	v_fmac_f32_e32 v143, v229, v229
	v_fmac_f32_e32 v143, v230, v230
	v_fmac_f32_e32 v143, v228, v228
	v_add_f32_e32 v32, v143, v32
	v_mul_f32_e32 v143, v242, v242
	v_fmac_f32_e32 v143, v237, v237
	v_fmac_f32_e32 v143, v238, v238
	v_fmac_f32_e32 v143, v236, v236
	v_add_f32_e32 v32, v143, v32
	ds_bpermute_b32 v143, v150, v32
	s_waitcnt lgkmcnt(0)
	v_add_f32_e32 v32, v32, v143
	ds_bpermute_b32 v143, v151, v32
	s_and_saveexec_b64 s[6:7], vcc
	s_cbranch_execz .LBB0_1015
	s_waitcnt lgkmcnt(0)
	v_add_f32_e32 v32, v32, v143
	global_atomic_add_f32 v[130:131], v32, off offset:256
.LBB0_1015:
	s_or_b64 exec, exec, s[6:7]
	v_mul_f32_e32 v32, v173, v173
	s_waitcnt lgkmcnt(0)
	v_mul_f32_e32 v143, v193, v193
	v_fmac_f32_e32 v32, v171, v171
	v_fmac_f32_e32 v143, v183, v183
	v_fmac_f32_e32 v32, v172, v172
	v_fmac_f32_e32 v143, v192, v192
	v_fmac_f32_e32 v32, v167, v167
	v_fmac_f32_e32 v143, v182, v182
	v_add_f32_e32 v32, v32, v143
	v_mul_f32_e32 v143, v201, v201
	v_fmac_f32_e32 v143, v199, v199
	v_fmac_f32_e32 v143, v200, v200
	v_fmac_f32_e32 v143, v198, v198
	v_add_f32_e32 v32, v143, v32
	v_mul_f32_e32 v143, v205, v205
	v_fmac_f32_e32 v143, v203, v203
	v_fmac_f32_e32 v143, v204, v204
	v_fmac_f32_e32 v143, v202, v202
	v_add_f32_e32 v32, v143, v32
	v_mul_f32_e32 v143, v226, v226
	v_fmac_f32_e32 v143, v223, v223
	v_fmac_f32_e32 v143, v224, v224
	v_fmac_f32_e32 v143, v222, v222
	v_add_f32_e32 v32, v143, v32
	v_mul_f32_e32 v143, v235, v235
	v_fmac_f32_e32 v143, v233, v233
	v_fmac_f32_e32 v143, v234, v234
	v_fmac_f32_e32 v143, v232, v232
	v_add_f32_e32 v32, v143, v32
	v_mul_f32_e32 v143, v243, v243
	v_fmac_f32_e32 v143, v240, v240
	v_fmac_f32_e32 v143, v241, v241
	v_fmac_f32_e32 v143, v239, v239
	v_add_f32_e32 v32, v143, v32
	v_mul_f32_e32 v143, v247, v247
	v_fmac_f32_e32 v143, v245, v245
	v_fmac_f32_e32 v143, v246, v246
	v_fmac_f32_e32 v143, v244, v244
	v_add_f32_e32 v32, v143, v32
	ds_bpermute_b32 v143, v150, v32
	s_waitcnt lgkmcnt(0)
	v_add_f32_e32 v32, v32, v143
	ds_bpermute_b32 v143, v151, v32
	s_and_saveexec_b64 s[6:7], vcc
	s_cbranch_execz .LBB0_1017
	s_waitcnt lgkmcnt(0)
	v_add_f32_e32 v32, v32, v143
	global_atomic_add_f32 v[130:131], v32, off offset:2048
.LBB0_1017:
	s_or_b64 exec, exec, s[6:7]
	v_mul_f32_e32 v32, v141, v141
	v_fmac_f32_e32 v32, v137, v137
	v_fmac_f32_e32 v32, v139, v139
	v_fmac_f32_e32 v32, v135, v135
	v_mul_f32_e32 v135, v158, v158
	v_fmac_f32_e32 v135, v156, v156
	v_fmac_f32_e32 v135, v157, v157
	v_fmac_f32_e32 v135, v155, v155
	v_add_f32_e32 v32, v32, v135
	v_mul_f32_e32 v135, v166, v166
	v_fmac_f32_e32 v135, v164, v164
	v_fmac_f32_e32 v135, v165, v165
	v_fmac_f32_e32 v135, v163, v163
	v_add_f32_e32 v32, v135, v32
	v_mul_f32_e32 v135, v178, v178
	v_fmac_f32_e32 v135, v175, v175
	v_fmac_f32_e32 v135, v176, v176
	v_fmac_f32_e32 v135, v174, v174
	v_add_f32_e32 v32, v135, v32
	v_mul_f32_e32 v135, v145, v145
	v_fmac_f32_e32 v135, v133, v133
	v_fmac_f32_e32 v135, v144, v144
	v_fmac_f32_e32 v135, v132, v132
	v_mul_f32_e32 v132, v213, v213
	v_fmac_f32_e32 v132, v210, v210
	v_fmac_f32_e32 v132, v211, v211
	v_add_f32_e32 v32, v135, v32
	v_fmac_f32_e32 v132, v207, v207
	v_add_f32_e32 v32, v132, v32
	v_mul_f32_e32 v132, v217, v217
	v_fmac_f32_e32 v132, v215, v215
	v_fmac_f32_e32 v132, v216, v216
	v_fmac_f32_e32 v132, v214, v214
	v_add_f32_e32 v32, v132, v32
	v_mul_f32_e32 v132, v227, v227
	v_fmac_f32_e32 v132, v149, v149
	v_fmac_f32_e32 v132, v225, v225
	v_fmac_f32_e32 v132, v148, v148
	v_add_f32_e32 v32, v132, v32
	ds_bpermute_b32 v132, v150, v32
	s_waitcnt lgkmcnt(0)
	v_add_f32_e32 v32, v32, v132
	ds_bpermute_b32 v132, v151, v32
	s_and_saveexec_b64 s[6:7], vcc
	s_cbranch_execz .LBB0_1019
	s_waitcnt lgkmcnt(0)
	v_add_f32_e32 v32, v32, v132
	global_atomic_add_f32 v[130:131], v32, off offset:2304

; #define EPI_LOOP(...) _Pragma("unroll") for(int ai=0;ai<2;++ai) _Pragma("unroll") for(int bj=0;bj<2;++bj) \
;   _Pragma("unroll") for(int m=0;m<4;++m) _Pragma("unroll") for(int n=0;n<2;++n) { \
;     const int row=brow+ai*128+wr*64+m*16+fq*4; const int col=bcol+bj*128+wc*32+n*16+fr; \
;     f32x4& v=acc[ai][bj][m][n]; __VA_ARGS__ if (n == 1 && (m & 1)) __builtin_amdgcn_sched_barrier(0); }
; DEVI void run_phase(const int ph, const Params& P, char* shmc, const int wave_u) {
;     ...
;       } else if (brow < 3072) {
;         const bool isk = brow < 2048; const int fb = isk ? 1024 : 2048;
;         bf16* dp = isk ? sbk_p : sbv_p; bf16* ds = isk ? sbk_s : sbv_s;
;         float* op = out + (isk ? O_SBK_P : O_SBV_P); float* os = out + (isk ? O_SBK_S : O_SBV_S);
;         EPI_LOOP({ const float sc = sc4[bj][n]; const int f = row - fb; const float a = v[0] * sc, b = v[1] * sc, c = v[2] * sc, d = v[3] * sc;
;           if (!samp) { st_bf4(dp + (long)col * 1024 + f, a, b, c, d); st_f4(op + (long)col * 1024 + f, a, b, c, d); }
;           else { const int s = col - MP; st_bf4(ds + ((long)(s >> 5) * SKS + 1024 + (s & 31)) * 1024 + f, a, b, c, d); st_f4(os + (long)s * 1024 + f, a, b, c, d); } })
.LBB0_1021:
	s_andn2_b64 vcc, exec, s[38:39]
	v_mbcnt_lo_u32_b32 v212, -1, 0
	v_mbcnt_hi_u32_b32 v212, -1, v212
	v_bfe_u32 v212, v212, 4, 1
	v_mul_u32_u24_e32 v212, 24, v212
	v_mov_b32_e32 v213, 0
	s_cbranch_vccnz .LBB0_1151
	s_cmp_lt_u32 s73, 8
	s_cselect_b64 s[6:7], -1, 0
	s_and_b64 s[8:9], s[6:7], exec
	v_readlane_b32 s4, v255, 28
	s_cselect_b32 s69, s4, s85
	v_readlane_b32 s4, v255, 27
	s_cselect_b32 s68, s4, s84
	v_readlane_b32 s4, v255, 30
	v_readlane_b32 s8, v255, 32
	s_mov_b32 s38, 0x8400000
	s_movk_i32 s1, 0xfc00
	s_cselect_b32 s9, s4, s8
	v_readlane_b32 s4, v255, 29
	v_readlane_b32 s8, v255, 31
	s_cselect_b32 s38, s38, 0xc400000
	v_readlane_b32 s16, v255, 13
	s_cselect_b32 s1, s1, 0xfffff800
	s_cselect_b32 s8, s4, s8
	v_readlane_b32 s17, v255, 14
	s_add_u32 s70, s16, s38
	s_addc_u32 s71, s17, 0
	s_and_b64 s[6:7], s[6:7], exec
	s_mov_b32 s6, 0x12800000
	s_cselect_b32 s6, s6, 0x12a00000
	s_add_u32 s38, s16, s6
	s_addc_u32 s39, s17, 0
	s_add_i32 s1, s1, s0
	v_lshl_add_u32 v32, v169, 6, s1
	v_lshl_or_b32 v130, v168, 2, v32
	v_ashrrev_i32_e32 v131, 31, v130
	v_lshlrev_b64 v[148:149], 1, v[130:131]
	v_lshlrev_b64 v[154:155], 2, v[130:131]
	v_cndmask_b32_e64 v32, 0, 1, s[12:13]
	v_lshl_add_u64 v[150:151], s[68:69], 0, v[148:149]
	v_lshl_add_u64 v[144:145], s[70:71], 0, v[154:155]
	s_waitcnt vmcnt(0) lgkmcnt(0)
	v_pk_mul_f32 v[130:131], v[126:127], v[142:143] op_sel_hi:[1,0]
	v_pk_mul_f32 v[132:133], v[128:129], v[142:143] op_sel_hi:[1,0]
	v_cmp_ne_u32_e64 s[6:7], 1, v32
	s_andn2_b64 vcc, exec, s[12:13]
	s_mov_b64 s[12:13], -1
	s_cbranch_vccnz .LBB0_1024
	v_ashrrev_i32_e32 v135, 31, v134
	v_lshlrev_b64 v[152:153], 11, v[134:135]
	v_lshl_add_u64 v[152:153], v[150:151], 0, v[152:153]
	v_cvt_pk_bf16_f32 v156, v130, v131
	v_cvt_pk_bf16_f32 v157, v132, v133
	v_mov_b32_e32 v180, v156
	v_mov_b32_e32 v181, v157
	v_lshl_add_u64 v[204:205], v[152:153], 0, v[212:213]
	v_lshlrev_b64 v[152:153], 12, v[134:135]
	v_lshl_add_u64 v[152:153], v[144:145], 0, v[152:153]
	s_mov_b64 s[12:13], 0
	global_store_dwordx4 v[152:153], v[130:133], off
.LBB0_1024:
	v_lshl_add_u64 v[152:153], s[8:9], 0, v[148:149]
	v_lshl_add_u64 v[148:149], s[38:39], 0, v[154:155]
	v_add_u32_e32 v154, 0xffffc000, v134
	s_andn2_b64 vcc, exec, s[12:13]
	v_lshrrev_b32_e32 v171, 5, v154
	v_ashrrev_i32_e32 v155, 31, v154
	s_cbranch_vccnz .LBB0_1026
	v_mul_i32_i24_e32 v32, 0x440, v171
	v_ashrrev_i32_e32 v157, 31, v32
	v_or_b32_e32 v156, v32, v170
	v_lshlrev_b64 v[156:157], 11, v[156:157]
	v_lshl_add_u64 v[156:157], v[152:153], 0, v[156:157]
	v_add_co_u32_e32 v156, vcc, 0x200000, v156
	v_cvt_pk_bf16_f32 v158, v130, v131
	v_cvt_pk_bf16_f32 v159, v132, v133
	s_nop 1
	v_addc_co_u32_e32 v157, vcc, 0, v157, vcc
	v_mov_b32_e32 v180, v158
	v_mov_b32_e32 v181, v159
	v_lshl_add_u64 v[204:205], v[156:157], 0, v[212:213]
	v_lshlrev_b64 v[156:157], 12, v[154:155]
	v_lshl_add_u64 v[156:157], v[148:149], 0, v[156:157]
	global_store_dwordx4 v[156:157], v[130:133], off
.LBB0_1026:
	v_or_b32_e32 v156, 16, v134
	s_nop 0
	v_pk_mul_f32 v[130:131], v[122:123], v[140:141] op_sel_hi:[1,0]
	v_pk_mul_f32 v[132:133], v[124:125], v[140:141] op_sel_hi:[1,0]
	s_mov_b64 s[8:9], -1
	s_and_b64 vcc, exec, s[6:7]
	v_ashrrev_i32_e32 v157, 31, v156
	s_cbranch_vccnz .LBB0_1028
	v_lshlrev_b64 v[158:159], 11, v[156:157]
	v_lshl_add_u64 v[158:159], v[150:151], 0, v[158:159]
	v_cvt_pk_bf16_f32 v160, v130, v131
	v_cvt_pk_bf16_f32 v161, v132, v133
	v_mov_b32_e32 v192, v160
	v_mov_b32_e32 v193, v161
	v_lshl_add_u64 v[206:207], v[158:159], 0, v[212:213]
	v_lshlrev_b64 v[158:159], 12, v[156:157]
	v_lshl_add_u64 v[158:159], v[144:145], 0, v[158:159]
	s_mov_b64 s[8:9], 0
	global_store_dwordx4 v[158:159], v[130:133], off
.LBB0_1028:
	v_add_u32_e32 v158, 0xffffc010, v134
	v_or_b32_e32 v32, 16, v170
	s_andn2_b64 vcc, exec, s[8:9]
	v_lshrrev_b32_e32 v172, 5, v158
	v_ashrrev_i32_e32 v159, 31, v158
	s_cbranch_vccnz .LBB0_1030
	v_mul_i32_i24_e32 v135, 0x440, v172
	v_ashrrev_i32_e32 v161, 31, v135
	v_or_b32_e32 v160, v135, v32
	v_lshlrev_b64 v[160:161], 11, v[160:161]
	v_lshl_add_u64 v[160:161], v[152:153], 0, v[160:161]
	v_add_co_u32_e32 v160, vcc, 0x200000, v160
	v_cvt_pk_bf16_f32 v162, v130, v131
	v_cvt_pk_bf16_f32 v163, v132, v133
	s_nop 1
	v_addc_co_u32_e32 v161, vcc, 0, v161, vcc
	v_mov_b32_e32 v192, v162
	v_mov_b32_e32 v193, v163
	v_lshl_add_u64 v[206:207], v[160:161], 0, v[212:213]
	v_lshlrev_b64 v[160:161], 12, v[158:159]
	v_lshl_add_u64 v[160:161], v[148:149], 0, v[160:161]
	global_store_dwordx4 v[160:161], v[130:133], off
.LBB0_1030:
	v_mov_b32_e32 v143, v142
	s_nop 0
	v_pk_mul_f32 v[130:131], v[118:119], v[142:143]
	v_pk_mul_f32 v[132:133], v[120:121], v[142:143]
	s_and_b64 vcc, exec, s[6:7]
	s_mov_b64 s[8:9], -1
	s_cbranch_vccnz .LBB0_1032
	v_ashrrev_i32_e32 v135, 31, v134
	v_lshlrev_b64 v[160:161], 11, v[134:135]
	v_lshl_add_u64 v[160:161], v[150:151], 0, v[160:161]
	v_cvt_pk_bf16_f32 v162, v130, v131
	v_cvt_pk_bf16_f32 v163, v132, v133
	v_mov_b32_e32 v182, v162
	v_mov_b32_e32 v183, v163
	s_nop 1
	v_permlane16_swap_b32_e32 v180, v182
	v_permlane16_swap_b32_e32 v181, v183
	global_store_dwordx4 v[204:205], v[180:183], off
	v_lshlrev_b64 v[160:161], 12, v[134:135]
	v_lshl_add_u64 v[160:161], v[144:145], 0, v[160:161]
	s_mov_b64 s[8:9], 0
	global_store_dwordx4 v[160:161], v[130:133], off offset:64
; #define EPI_LOOP(...) _Pragma("unroll") for(int ai=0;ai<2;++ai) _Pragma("unroll") for(int bj=0;bj<2;++bj) \
;   _Pragma("unroll") for(int m=0;m<4;++m) _Pragma("unroll") for(int n=0;n<2;++n) { \
;     const int row=brow+ai*128+wr*64+m*16+fq*4; const int col=bcol+bj*128+wc*32+n*16+fr; \
;     f32x4& v=acc[ai][bj][m][n]; __VA_ARGS__ if (n == 1 && (m & 1)) __builtin_amdgcn_sched_barrier(0); }
; DEVI void run_phase(const int ph, const Params& P, char* shmc, const int wave_u) {
;     ...
;       } else if (brow < 3072) {
;         const bool isk = brow < 2048; const int fb = isk ? 1024 : 2048;
;         bf16* dp = isk ? sbk_p : sbv_p; bf16* ds = isk ? sbk_s : sbv_s;
;         float* op = out + (isk ? O_SBK_P : O_SBV_P); float* os = out + (isk ? O_SBK_S : O_SBV_S);
;         EPI_LOOP({ const float sc = sc4[bj][n]; const int f = row - fb; const float a = v[0] * sc, b = v[1] * sc, c = v[2] * sc, d = v[3] * sc;
;           if (!samp) { st_bf4(dp + (long)col * 1024 + f, a, b, c, d); st_f4(op + (long)col * 1024 + f, a, b, c, d); }
;           else { const int s = col - MP; st_bf4(ds + ((long)(s >> 5) * SKS + 1024 + (s & 31)) * 1024 + f, a, b, c, d); st_f4(os + (long)s * 1024 + f, a, b, c, d); } })
.LBB0_1032:
	s_andn2_b64 vcc, exec, s[8:9]
	s_cbranch_vccnz .LBB0_1034
	v_mul_i32_i24_e32 v135, 0x440, v171
	v_ashrrev_i32_e32 v161, 31, v135
	v_or_b32_e32 v160, v135, v170
	v_lshlrev_b64 v[160:161], 11, v[160:161]
	v_lshl_add_u64 v[160:161], v[152:153], 0, v[160:161]
	v_add_co_u32_e32 v160, vcc, 0x200000, v160
	v_cvt_pk_bf16_f32 v162, v130, v131
	v_cvt_pk_bf16_f32 v163, v132, v133
	s_nop 1
	v_addc_co_u32_e32 v161, vcc, 0, v161, vcc
	v_mov_b32_e32 v182, v162
	v_mov_b32_e32 v183, v163
	s_nop 1
	v_permlane16_swap_b32_e32 v180, v182
	v_permlane16_swap_b32_e32 v181, v183
	global_store_dwordx4 v[204:205], v[180:183], off
	v_lshlrev_b64 v[160:161], 12, v[154:155]
	v_lshl_add_u64 v[160:161], v[148:149], 0, v[160:161]
	global_store_dwordx4 v[160:161], v[130:133], off offset:64
.LBB0_1034:
	v_mov_b32_e32 v141, v140
	s_nop 0
	v_pk_mul_f32 v[130:131], v[114:115], v[140:141]
	v_pk_mul_f32 v[132:133], v[116:117], v[140:141]
	s_and_b64 vcc, exec, s[6:7]
	s_mov_b64 s[8:9], -1
	s_cbranch_vccnz .LBB0_1036
	v_lshlrev_b64 v[160:161], 11, v[156:157]
	v_lshl_add_u64 v[160:161], v[150:151], 0, v[160:161]
	v_cvt_pk_bf16_f32 v162, v130, v131
	v_cvt_pk_bf16_f32 v163, v132, v133
	v_mov_b32_e32 v194, v162
	v_mov_b32_e32 v195, v163
	s_nop 1
	v_permlane16_swap_b32_e32 v192, v194
	v_permlane16_swap_b32_e32 v193, v195
	global_store_dwordx4 v[206:207], v[192:195], off
	v_lshlrev_b64 v[160:161], 12, v[156:157]
	v_lshl_add_u64 v[160:161], v[144:145], 0, v[160:161]
	s_mov_b64 s[8:9], 0
	global_store_dwordx4 v[160:161], v[130:133], off offset:64
.LBB0_1036:
	s_andn2_b64 vcc, exec, s[8:9]
	s_cbranch_vccnz .LBB0_1038
	v_mul_i32_i24_e32 v135, 0x440, v172
	v_ashrrev_i32_e32 v161, 31, v135
	v_or_b32_e32 v160, v135, v32
	v_lshlrev_b64 v[160:161], 11, v[160:161]
	v_lshl_add_u64 v[160:161], v[152:153], 0, v[160:161]
	v_add_co_u32_e32 v160, vcc, 0x200000, v160
	v_cvt_pk_bf16_f32 v162, v130, v131
	v_cvt_pk_bf16_f32 v163, v132, v133
	s_nop 1
	v_addc_co_u32_e32 v161, vcc, 0, v161, vcc
	v_mov_b32_e32 v194, v162
	v_mov_b32_e32 v195, v163
	s_nop 1
	v_permlane16_swap_b32_e32 v192, v194
	v_permlane16_swap_b32_e32 v193, v195
	global_store_dwordx4 v[206:207], v[192:195], off
	v_lshlrev_b64 v[160:161], 12, v[158:159]
	v_lshl_add_u64 v[160:161], v[148:149], 0, v[160:161]
	global_store_dwordx4 v[160:161], v[130:133], off offset:64
.LBB0_1038:
	s_nop 1
	v_pk_mul_f32 v[130:131], v[110:111], v[142:143]
	v_pk_mul_f32 v[132:133], v[112:113], v[142:143]
	s_and_b64 vcc, exec, s[6:7]
	s_mov_b64 s[8:9], -1
	s_cbranch_vccnz .LBB0_1040
	v_ashrrev_i32_e32 v135, 31, v134
	v_lshlrev_b64 v[160:161], 11, v[134:135]
	v_lshl_add_u64 v[160:161], v[150:151], 0, v[160:161]
	v_cvt_pk_bf16_f32 v162, v130, v131
	v_cvt_pk_bf16_f32 v163, v132, v133
	v_mov_b32_e32 v196, v162
	v_mov_b32_e32 v197, v163
	v_lshl_add_u64 v[208:209], v[160:161], 0, v[212:213]
	v_lshlrev_b64 v[160:161], 12, v[134:135]
	v_lshl_add_u64 v[160:161], v[144:145], 0, v[160:161]
	s_mov_b64 s[8:9], 0
	global_store_dwordx4 v[160:161], v[130:133], off offset:128
.LBB0_1040:
	s_andn2_b64 vcc, exec, s[8:9]
	s_cbranch_vccnz .LBB0_1042
	v_mul_i32_i24_e32 v135, 0x440, v171
	v_ashrrev_i32_e32 v161, 31, v135
	v_or_b32_e32 v160, v135, v170
	v_lshlrev_b64 v[160:161], 11, v[160:161]
	v_lshl_add_u64 v[160:161], v[152:153], 0, v[160:161]
	v_add_co_u32_e32 v160, vcc, 0x200000, v160
	v_cvt_pk_bf16_f32 v162, v130, v131
	v_cvt_pk_bf16_f32 v163, v132, v133
	s_nop 1
	v_addc_co_u32_e32 v161, vcc, 0, v161, vcc
	v_mov_b32_e32 v196, v162
	v_mov_b32_e32 v197, v163
	v_lshl_add_u64 v[208:209], v[160:161], 0, v[212:213]
	v_lshlrev_b64 v[160:161], 12, v[154:155]
	v_lshl_add_u64 v[160:161], v[148:149], 0, v[160:161]
	global_store_dwordx4 v[160:161], v[130:133], off offset:128
.LBB0_1042:
	s_nop 1
	v_pk_mul_f32 v[130:131], v[106:107], v[140:141]
	v_pk_mul_f32 v[132:133], v[108:109], v[140:141]
	s_and_b64 vcc, exec, s[6:7]
	s_mov_b64 s[8:9], -1
	s_cbranch_vccnz .LBB0_1044
	v_lshlrev_b64 v[160:161], 11, v[156:157]
	v_lshl_add_u64 v[160:161], v[150:151], 0, v[160:161]
	v_cvt_pk_bf16_f32 v162, v130, v131
	v_cvt_pk_bf16_f32 v163, v132, v133
	v_mov_b32_e32 v200, v162
	v_mov_b32_e32 v201, v163
	v_lshl_add_u64 v[210:211], v[160:161], 0, v[212:213]
	v_lshlrev_b64 v[160:161], 12, v[156:157]
	v_lshl_add_u64 v[160:161], v[144:145], 0, v[160:161]
	s_mov_b64 s[8:9], 0
	global_store_dwordx4 v[160:161], v[130:133], off offset:128
.LBB0_1044:
	s_andn2_b64 vcc, exec, s[8:9]
	s_cbranch_vccnz .LBB0_1046
	v_mul_i32_i24_e32 v135, 0x440, v172
	v_ashrrev_i32_e32 v161, 31, v135
	v_or_b32_e32 v160, v135, v32
	v_lshlrev_b64 v[160:161], 11, v[160:161]
	v_lshl_add_u64 v[160:161], v[152:153], 0, v[160:161]
	v_add_co_u32_e32 v160, vcc, 0x200000, v160
	v_cvt_pk_bf16_f32 v162, v130, v131
	v_cvt_pk_bf16_f32 v163, v132, v133
	s_nop 1
	v_addc_co_u32_e32 v161, vcc, 0, v161, vcc
	v_mov_b32_e32 v200, v162
	v_mov_b32_e32 v201, v163
	v_lshl_add_u64 v[210:211], v[160:161], 0, v[212:213]
	v_lshlrev_b64 v[160:161], 12, v[158:159]
	v_lshl_add_u64 v[160:161], v[148:149], 0, v[160:161]
	global_store_dwordx4 v[160:161], v[130:133], off offset:128
.LBB0_1046:
	s_nop 1
	v_pk_mul_f32 v[130:131], v[102:103], v[142:143]
	v_pk_mul_f32 v[132:133], v[104:105], v[142:143]
	s_and_b64 vcc, exec, s[6:7]
	s_mov_b64 s[8:9], -1
	s_cbranch_vccnz .LBB0_1048
	v_ashrrev_i32_e32 v135, 31, v134
	v_lshlrev_b64 v[160:161], 11, v[134:135]
	v_lshl_add_u64 v[160:161], v[150:151], 0, v[160:161]
	v_cvt_pk_bf16_f32 v162, v130, v131
	v_cvt_pk_bf16_f32 v163, v132, v133
	v_mov_b32_e32 v198, v162
	v_mov_b32_e32 v199, v163
	s_nop 1
	v_permlane16_swap_b32_e32 v196, v198
	v_permlane16_swap_b32_e32 v197, v199
	global_store_dwordx4 v[208:209], v[196:199], off offset:64
	v_lshlrev_b64 v[160:161], 12, v[134:135]
	v_lshl_add_u64 v[160:161], v[144:145], 0, v[160:161]
	s_mov_b64 s[8:9], 0
	global_store_dwordx4 v[160:161], v[130:133], off offset:192
; #define EPI_LOOP(...) _Pragma("unroll") for(int ai=0;ai<2;++ai) _Pragma("unroll") for(int bj=0;bj<2;++bj) \
;   _Pragma("unroll") for(int m=0;m<4;++m) _Pragma("unroll") for(int n=0;n<2;++n) { \
;     const int row=brow+ai*128+wr*64+m*16+fq*4; const int col=bcol+bj*128+wc*32+n*16+fr; \
;     f32x4& v=acc[ai][bj][m][n]; __VA_ARGS__ if (n == 1 && (m & 1)) __builtin_amdgcn_sched_barrier(0); }
; DEVI void run_phase(const int ph, const Params& P, char* shmc, const int wave_u) {
;     ...
;       } else if (brow < 3072) {
;         const bool isk = brow < 2048; const int fb = isk ? 1024 : 2048;
;         bf16* dp = isk ? sbk_p : sbv_p; bf16* ds = isk ? sbk_s : sbv_s;
;         float* op = out + (isk ? O_SBK_P : O_SBV_P); float* os = out + (isk ? O_SBK_S : O_SBV_S);
;         EPI_LOOP({ const float sc = sc4[bj][n]; const int f = row - fb; const float a = v[0] * sc, b = v[1] * sc, c = v[2] * sc, d = v[3] * sc;
;           if (!samp) { st_bf4(dp + (long)col * 1024 + f, a, b, c, d); st_f4(op + (long)col * 1024 + f, a, b, c, d); }
;           else { const int s = col - MP; st_bf4(ds + ((long)(s >> 5) * SKS + 1024 + (s & 31)) * 1024 + f, a, b, c, d); st_f4(os + (long)s * 1024 + f, a, b, c, d); } })
.LBB0_1048:
	s_andn2_b64 vcc, exec, s[8:9]
	s_cbranch_vccnz .LBB0_1050
	v_mul_i32_i24_e32 v135, 0x440, v171
	v_ashrrev_i32_e32 v161, 31, v135
	v_or_b32_e32 v160, v135, v170
	v_lshlrev_b64 v[160:161], 11, v[160:161]
	v_lshl_add_u64 v[160:161], v[152:153], 0, v[160:161]
	v_add_co_u32_e32 v160, vcc, 0x200000, v160
	v_cvt_pk_bf16_f32 v162, v130, v131
	v_cvt_pk_bf16_f32 v163, v132, v133
	s_nop 1
	v_addc_co_u32_e32 v161, vcc, 0, v161, vcc
	v_mov_b32_e32 v198, v162
	v_mov_b32_e32 v199, v163
	s_nop 1
	v_permlane16_swap_b32_e32 v196, v198
	v_permlane16_swap_b32_e32 v197, v199
	global_store_dwordx4 v[208:209], v[196:199], off offset:64
	v_lshlrev_b64 v[160:161], 12, v[154:155]
	v_lshl_add_u64 v[160:161], v[148:149], 0, v[160:161]
	global_store_dwordx4 v[160:161], v[130:133], off offset:192
.LBB0_1050:
	s_nop 1
	v_pk_mul_f32 v[130:131], v[98:99], v[140:141]
	v_pk_mul_f32 v[132:133], v[100:101], v[140:141]
	s_and_b64 vcc, exec, s[6:7]
	s_mov_b64 s[8:9], -1
	s_cbranch_vccnz .LBB0_1052
	v_lshlrev_b64 v[160:161], 11, v[156:157]
	v_lshl_add_u64 v[160:161], v[150:151], 0, v[160:161]
	v_cvt_pk_bf16_f32 v162, v130, v131
	v_cvt_pk_bf16_f32 v163, v132, v133
	v_mov_b32_e32 v202, v162
	v_mov_b32_e32 v203, v163
	s_nop 1
	v_permlane16_swap_b32_e32 v200, v202
	v_permlane16_swap_b32_e32 v201, v203
	global_store_dwordx4 v[210:211], v[200:203], off offset:64
	v_lshlrev_b64 v[160:161], 12, v[156:157]
	v_lshl_add_u64 v[160:161], v[144:145], 0, v[160:161]
	s_mov_b64 s[8:9], 0
	global_store_dwordx4 v[160:161], v[130:133], off offset:192
.LBB0_1052:
	s_andn2_b64 vcc, exec, s[8:9]
	s_cbranch_vccnz .LBB0_1054
	v_mul_i32_i24_e32 v135, 0x440, v172
	v_ashrrev_i32_e32 v161, 31, v135
	v_or_b32_e32 v160, v135, v32
	v_lshlrev_b64 v[160:161], 11, v[160:161]
	v_lshl_add_u64 v[160:161], v[152:153], 0, v[160:161]
	v_add_co_u32_e32 v160, vcc, 0x200000, v160
	v_cvt_pk_bf16_f32 v162, v130, v131
	v_cvt_pk_bf16_f32 v163, v132, v133
	s_nop 1
	v_addc_co_u32_e32 v161, vcc, 0, v161, vcc
	v_mov_b32_e32 v202, v162
	v_mov_b32_e32 v203, v163
	s_nop 1
	v_permlane16_swap_b32_e32 v200, v202
	v_permlane16_swap_b32_e32 v201, v203
	global_store_dwordx4 v[210:211], v[200:203], off offset:64
	v_lshlrev_b64 v[160:161], 12, v[158:159]
	v_lshl_add_u64 v[160:161], v[148:149], 0, v[160:161]
	global_store_dwordx4 v[160:161], v[130:133], off offset:192
.LBB0_1054:
	v_or_b32_e32 v162, 0x80, v134
	s_nop 0
	v_pk_mul_f32 v[130:131], v[94:95], v[138:139] op_sel_hi:[1,0]
	v_pk_mul_f32 v[132:133], v[96:97], v[138:139] op_sel_hi:[1,0]
	s_mov_b64 s[8:9], -1
	s_and_b64 vcc, exec, s[6:7]
	v_ashrrev_i32_e32 v163, 31, v162
	s_cbranch_vccnz .LBB0_1056
	v_lshlrev_b64 v[160:161], 11, v[162:163]
	v_lshl_add_u64 v[160:161], v[150:151], 0, v[160:161]
	v_cvt_pk_bf16_f32 v164, v130, v131
	v_cvt_pk_bf16_f32 v165, v132, v133
	v_mov_b32_e32 v180, v164
	v_mov_b32_e32 v181, v165
	v_lshl_add_u64 v[204:205], v[160:161], 0, v[212:213]
	v_lshlrev_b64 v[160:161], 12, v[162:163]
	v_lshl_add_u64 v[160:161], v[144:145], 0, v[160:161]
	s_mov_b64 s[8:9], 0
	global_store_dwordx4 v[160:161], v[130:133], off
.LBB0_1056:
	v_add_u32_e32 v160, 0xffffc080, v134
	s_andn2_b64 vcc, exec, s[8:9]
	v_lshrrev_b32_e32 v173, 5, v160
	v_ashrrev_i32_e32 v161, 31, v160
	s_cbranch_vccnz .LBB0_1058
	v_mul_i32_i24_e32 v135, 0x440, v173
	v_ashrrev_i32_e32 v165, 31, v135
	v_or_b32_e32 v164, v135, v170
	v_lshlrev_b64 v[164:165], 11, v[164:165]
	v_lshl_add_u64 v[164:165], v[152:153], 0, v[164:165]
	v_add_co_u32_e32 v164, vcc, 0x200000, v164
	v_cvt_pk_bf16_f32 v166, v130, v131
	v_cvt_pk_bf16_f32 v167, v132, v133
	s_nop 1
	v_addc_co_u32_e32 v165, vcc, 0, v165, vcc
	v_mov_b32_e32 v180, v166
	v_mov_b32_e32 v181, v167
	v_lshl_add_u64 v[204:205], v[164:165], 0, v[212:213]
	v_lshlrev_b64 v[164:165], 12, v[160:161]
	v_lshl_add_u64 v[164:165], v[148:149], 0, v[164:165]
	global_store_dwordx4 v[164:165], v[130:133], off
.LBB0_1058:
	v_or_b32_e32 v166, 0x90, v134
	s_nop 0
	v_pk_mul_f32 v[130:131], v[90:91], v[136:137] op_sel_hi:[1,0]
	v_pk_mul_f32 v[132:133], v[92:93], v[136:137] op_sel_hi:[1,0]
	s_mov_b64 s[8:9], -1
	s_and_b64 vcc, exec, s[6:7]
	v_ashrrev_i32_e32 v167, 31, v166
	s_cbranch_vccnz .LBB0_1060
	v_lshlrev_b64 v[164:165], 11, v[166:167]
	v_lshl_add_u64 v[164:165], v[150:151], 0, v[164:165]
	v_cvt_pk_bf16_f32 v174, v130, v131
	v_cvt_pk_bf16_f32 v175, v132, v133
	v_mov_b32_e32 v192, v174
	v_mov_b32_e32 v193, v175
	v_lshl_add_u64 v[206:207], v[164:165], 0, v[212:213]
	v_lshlrev_b64 v[164:165], 12, v[166:167]
	v_lshl_add_u64 v[164:165], v[144:145], 0, v[164:165]
	s_mov_b64 s[8:9], 0
	global_store_dwordx4 v[164:165], v[130:133], off
.LBB0_1060:
	v_add_u32_e32 v164, 0xffffc090, v134
	s_andn2_b64 vcc, exec, s[8:9]
	v_lshrrev_b32_e32 v174, 5, v164
	v_ashrrev_i32_e32 v165, 31, v164
	s_cbranch_vccnz .LBB0_1062
	v_mul_i32_i24_e32 v135, 0x440, v174
	v_ashrrev_i32_e32 v177, 31, v135
	v_or_b32_e32 v176, v135, v32
	v_lshlrev_b64 v[176:177], 11, v[176:177]
	v_lshl_add_u64 v[176:177], v[152:153], 0, v[176:177]
	v_add_co_u32_e32 v176, vcc, 0x200000, v176
	v_cvt_pk_bf16_f32 v178, v130, v131
	v_cvt_pk_bf16_f32 v179, v132, v133
	s_nop 1
	v_addc_co_u32_e32 v177, vcc, 0, v177, vcc
	v_mov_b32_e32 v192, v178
	v_mov_b32_e32 v193, v179
	v_lshl_add_u64 v[206:207], v[176:177], 0, v[212:213]
	v_lshlrev_b64 v[176:177], 12, v[164:165]
	v_lshl_add_u64 v[176:177], v[148:149], 0, v[176:177]
	global_store_dwordx4 v[176:177], v[130:133], off
; #define EPI_LOOP(...) _Pragma("unroll") for(int ai=0;ai<2;++ai) _Pragma("unroll") for(int bj=0;bj<2;++bj) \
;   _Pragma("unroll") for(int m=0;m<4;++m) _Pragma("unroll") for(int n=0;n<2;++n) { \
;     const int row=brow+ai*128+wr*64+m*16+fq*4; const int col=bcol+bj*128+wc*32+n*16+fr; \
;     f32x4& v=acc[ai][bj][m][n]; __VA_ARGS__ if (n == 1 && (m & 1)) __builtin_amdgcn_sched_barrier(0); }
; DEVI void run_phase(const int ph, const Params& P, char* shmc, const int wave_u) {
;     ...
;       } else if (brow < 3072) {
;         const bool isk = brow < 2048; const int fb = isk ? 1024 : 2048;
;         bf16* dp = isk ? sbk_p : sbv_p; bf16* ds = isk ? sbk_s : sbv_s;
;         float* op = out + (isk ? O_SBK_P : O_SBV_P); float* os = out + (isk ? O_SBK_S : O_SBV_S);
;         EPI_LOOP({ const float sc = sc4[bj][n]; const int f = row - fb; const float a = v[0] * sc, b = v[1] * sc, c = v[2] * sc, d = v[3] * sc;
;           if (!samp) { st_bf4(dp + (long)col * 1024 + f, a, b, c, d); st_f4(op + (long)col * 1024 + f, a, b, c, d); }
;           else { const int s = col - MP; st_bf4(ds + ((long)(s >> 5) * SKS + 1024 + (s & 31)) * 1024 + f, a, b, c, d); st_f4(os + (long)s * 1024 + f, a, b, c, d); } })
.LBB0_1062:
	v_mov_b32_e32 v139, v138
	s_nop 0
	v_pk_mul_f32 v[130:131], v[86:87], v[138:139]
	v_pk_mul_f32 v[132:133], v[88:89], v[138:139]
	s_and_b64 vcc, exec, s[6:7]
	s_mov_b64 s[8:9], -1
	s_cbranch_vccnz .LBB0_1064
	v_lshlrev_b64 v[176:177], 11, v[162:163]
	v_lshl_add_u64 v[176:177], v[150:151], 0, v[176:177]
	v_cvt_pk_bf16_f32 v178, v130, v131
	v_cvt_pk_bf16_f32 v179, v132, v133
	v_mov_b32_e32 v182, v178
	v_mov_b32_e32 v183, v179
	s_nop 1
	v_permlane16_swap_b32_e32 v180, v182
	v_permlane16_swap_b32_e32 v181, v183
	global_store_dwordx4 v[204:205], v[180:183], off
	v_lshlrev_b64 v[176:177], 12, v[162:163]
	v_lshl_add_u64 v[176:177], v[144:145], 0, v[176:177]
	s_mov_b64 s[8:9], 0
	global_store_dwordx4 v[176:177], v[130:133], off offset:64
.LBB0_1064:
	s_andn2_b64 vcc, exec, s[8:9]
	s_cbranch_vccnz .LBB0_1066
	v_mul_i32_i24_e32 v135, 0x440, v173
	v_ashrrev_i32_e32 v177, 31, v135
	v_or_b32_e32 v176, v135, v170
	v_lshlrev_b64 v[176:177], 11, v[176:177]
	v_lshl_add_u64 v[176:177], v[152:153], 0, v[176:177]
	v_add_co_u32_e32 v176, vcc, 0x200000, v176
	v_cvt_pk_bf16_f32 v178, v130, v131
	v_cvt_pk_bf16_f32 v179, v132, v133
	s_nop 1
	v_addc_co_u32_e32 v177, vcc, 0, v177, vcc
	v_mov_b32_e32 v182, v178
	v_mov_b32_e32 v183, v179
	s_nop 1
	v_permlane16_swap_b32_e32 v180, v182
	v_permlane16_swap_b32_e32 v181, v183
	global_store_dwordx4 v[204:205], v[180:183], off
	v_lshlrev_b64 v[176:177], 12, v[160:161]
	v_lshl_add_u64 v[176:177], v[148:149], 0, v[176:177]
	global_store_dwordx4 v[176:177], v[130:133], off offset:64
.LBB0_1066:
	v_mov_b32_e32 v137, v136
	s_nop 0
	v_pk_mul_f32 v[130:131], v[82:83], v[136:137]
	v_pk_mul_f32 v[132:133], v[84:85], v[136:137]
	s_and_b64 vcc, exec, s[6:7]
	s_mov_b64 s[8:9], -1
	s_cbranch_vccnz .LBB0_1068
	v_lshlrev_b64 v[176:177], 11, v[166:167]
	v_lshl_add_u64 v[176:177], v[150:151], 0, v[176:177]
	v_cvt_pk_bf16_f32 v178, v130, v131
	v_cvt_pk_bf16_f32 v179, v132, v133
	v_mov_b32_e32 v194, v178
	v_mov_b32_e32 v195, v179
	s_nop 1
	v_permlane16_swap_b32_e32 v192, v194
	v_permlane16_swap_b32_e32 v193, v195
	global_store_dwordx4 v[206:207], v[192:195], off
	v_lshlrev_b64 v[176:177], 12, v[166:167]
	v_lshl_add_u64 v[176:177], v[144:145], 0, v[176:177]
	s_mov_b64 s[8:9], 0
	global_store_dwordx4 v[176:177], v[130:133], off offset:64
.LBB0_1068:
	s_andn2_b64 vcc, exec, s[8:9]
	s_cbranch_vccnz .LBB0_1070
	v_mul_i32_i24_e32 v135, 0x440, v174
	v_ashrrev_i32_e32 v177, 31, v135
	v_or_b32_e32 v176, v135, v32
	v_lshlrev_b64 v[176:177], 11, v[176:177]
	v_lshl_add_u64 v[176:177], v[152:153], 0, v[176:177]
	v_add_co_u32_e32 v176, vcc, 0x200000, v176
	v_cvt_pk_bf16_f32 v178, v130, v131
	v_cvt_pk_bf16_f32 v179, v132, v133
	s_nop 1
	v_addc_co_u32_e32 v177, vcc, 0, v177, vcc
	v_mov_b32_e32 v194, v178
	v_mov_b32_e32 v195, v179
	s_nop 1
	v_permlane16_swap_b32_e32 v192, v194
	v_permlane16_swap_b32_e32 v193, v195
	global_store_dwordx4 v[206:207], v[192:195], off
	v_lshlrev_b64 v[176:177], 12, v[164:165]
	v_lshl_add_u64 v[176:177], v[148:149], 0, v[176:177]
	global_store_dwordx4 v[176:177], v[130:133], off offset:64
.LBB0_1070:
	s_nop 1
	v_pk_mul_f32 v[130:131], v[78:79], v[138:139]
	v_pk_mul_f32 v[132:133], v[80:81], v[138:139]
	s_and_b64 vcc, exec, s[6:7]
	s_mov_b64 s[8:9], -1
	s_cbranch_vccnz .LBB0_1072
	v_lshlrev_b64 v[176:177], 11, v[162:163]
	v_lshl_add_u64 v[176:177], v[150:151], 0, v[176:177]
	v_cvt_pk_bf16_f32 v178, v130, v131
	v_cvt_pk_bf16_f32 v179, v132, v133
	v_mov_b32_e32 v196, v178
	v_mov_b32_e32 v197, v179
	v_lshl_add_u64 v[208:209], v[176:177], 0, v[212:213]
	v_lshlrev_b64 v[176:177], 12, v[162:163]
	v_lshl_add_u64 v[176:177], v[144:145], 0, v[176:177]
	s_mov_b64 s[8:9], 0
	global_store_dwordx4 v[176:177], v[130:133], off offset:128
.LBB0_1072:
	s_andn2_b64 vcc, exec, s[8:9]
	s_cbranch_vccnz .LBB0_1074
	v_mul_i32_i24_e32 v135, 0x440, v173
	v_ashrrev_i32_e32 v177, 31, v135
	v_or_b32_e32 v176, v135, v170
	v_lshlrev_b64 v[176:177], 11, v[176:177]
	v_lshl_add_u64 v[176:177], v[152:153], 0, v[176:177]
	v_add_co_u32_e32 v176, vcc, 0x200000, v176
	v_cvt_pk_bf16_f32 v178, v130, v131
	v_cvt_pk_bf16_f32 v179, v132, v133
	s_nop 1
	v_addc_co_u32_e32 v177, vcc, 0, v177, vcc
	v_mov_b32_e32 v196, v178
	v_mov_b32_e32 v197, v179
	v_lshl_add_u64 v[208:209], v[176:177], 0, v[212:213]
	v_lshlrev_b64 v[176:177], 12, v[160:161]
	v_lshl_add_u64 v[176:177], v[148:149], 0, v[176:177]
	global_store_dwordx4 v[176:177], v[130:133], off offset:128
.LBB0_1074:
	s_nop 1
	v_pk_mul_f32 v[130:131], v[74:75], v[136:137]
	v_pk_mul_f32 v[132:133], v[76:77], v[136:137]
	s_and_b64 vcc, exec, s[6:7]
	s_mov_b64 s[8:9], -1
	s_cbranch_vccnz .LBB0_1076
	v_lshlrev_b64 v[176:177], 11, v[166:167]
	v_lshl_add_u64 v[176:177], v[150:151], 0, v[176:177]
	v_cvt_pk_bf16_f32 v178, v130, v131
	v_cvt_pk_bf16_f32 v179, v132, v133
	v_mov_b32_e32 v200, v178
	v_mov_b32_e32 v201, v179
	v_lshl_add_u64 v[210:211], v[176:177], 0, v[212:213]
	v_lshlrev_b64 v[176:177], 12, v[166:167]
	v_lshl_add_u64 v[176:177], v[144:145], 0, v[176:177]
	s_mov_b64 s[8:9], 0
	global_store_dwordx4 v[176:177], v[130:133], off offset:128
.LBB0_1076:
	s_andn2_b64 vcc, exec, s[8:9]
	s_cbranch_vccnz .LBB0_1078
	v_mul_i32_i24_e32 v135, 0x440, v174
	v_ashrrev_i32_e32 v177, 31, v135
	v_or_b32_e32 v176, v135, v32
	v_lshlrev_b64 v[176:177], 11, v[176:177]
	v_lshl_add_u64 v[176:177], v[152:153], 0, v[176:177]
	v_add_co_u32_e32 v176, vcc, 0x200000, v176
	v_cvt_pk_bf16_f32 v178, v130, v131
	v_cvt_pk_bf16_f32 v179, v132, v133
	s_nop 1
	v_addc_co_u32_e32 v177, vcc, 0, v177, vcc
	v_mov_b32_e32 v200, v178
	v_mov_b32_e32 v201, v179
	v_lshl_add_u64 v[210:211], v[176:177], 0, v[212:213]
	v_lshlrev_b64 v[176:177], 12, v[164:165]
	v_lshl_add_u64 v[176:177], v[148:149], 0, v[176:177]
	global_store_dwordx4 v[176:177], v[130:133], off offset:128
; #define EPI_LOOP(...) _Pragma("unroll") for(int ai=0;ai<2;++ai) _Pragma("unroll") for(int bj=0;bj<2;++bj) \
;   _Pragma("unroll") for(int m=0;m<4;++m) _Pragma("unroll") for(int n=0;n<2;++n) { \
;     const int row=brow+ai*128+wr*64+m*16+fq*4; const int col=bcol+bj*128+wc*32+n*16+fr; \
;     f32x4& v=acc[ai][bj][m][n]; __VA_ARGS__ if (n == 1 && (m & 1)) __builtin_amdgcn_sched_barrier(0); }
; DEVI void run_phase(const int ph, const Params& P, char* shmc, const int wave_u) {
;     ...
;       } else if (brow < 3072) {
;         const bool isk = brow < 2048; const int fb = isk ? 1024 : 2048;
;         bf16* dp = isk ? sbk_p : sbv_p; bf16* ds = isk ? sbk_s : sbv_s;
;         float* op = out + (isk ? O_SBK_P : O_SBV_P); float* os = out + (isk ? O_SBK_S : O_SBV_S);
;         EPI_LOOP({ const float sc = sc4[bj][n]; const int f = row - fb; const float a = v[0] * sc, b = v[1] * sc, c = v[2] * sc, d = v[3] * sc;
;           if (!samp) { st_bf4(dp + (long)col * 1024 + f, a, b, c, d); st_f4(op + (long)col * 1024 + f, a, b, c, d); }
;           else { const int s = col - MP; st_bf4(ds + ((long)(s >> 5) * SKS + 1024 + (s & 31)) * 1024 + f, a, b, c, d); st_f4(os + (long)s * 1024 + f, a, b, c, d); } })
.LBB0_1078:
	s_nop 1
	v_pk_mul_f32 v[130:131], v[70:71], v[138:139]
	v_pk_mul_f32 v[132:133], v[72:73], v[138:139]
	s_and_b64 vcc, exec, s[6:7]
	s_mov_b64 s[8:9], -1
	s_cbranch_vccnz .LBB0_1080
	v_lshlrev_b64 v[176:177], 11, v[162:163]
	v_lshl_add_u64 v[176:177], v[150:151], 0, v[176:177]
	v_cvt_pk_bf16_f32 v178, v130, v131
	v_cvt_pk_bf16_f32 v179, v132, v133
	v_mov_b32_e32 v198, v178
	v_mov_b32_e32 v199, v179
	s_nop 1
	v_permlane16_swap_b32_e32 v196, v198
	v_permlane16_swap_b32_e32 v197, v199
	global_store_dwordx4 v[208:209], v[196:199], off offset:64
	v_lshlrev_b64 v[176:177], 12, v[162:163]
	v_lshl_add_u64 v[176:177], v[144:145], 0, v[176:177]
	s_mov_b64 s[8:9], 0
	global_store_dwordx4 v[176:177], v[130:133], off offset:192
.LBB0_1080:
	s_andn2_b64 vcc, exec, s[8:9]
	s_cbranch_vccnz .LBB0_1082
	v_mul_i32_i24_e32 v135, 0x440, v173
	v_ashrrev_i32_e32 v177, 31, v135
	v_or_b32_e32 v176, v135, v170
	v_lshlrev_b64 v[176:177], 11, v[176:177]
	v_lshl_add_u64 v[176:177], v[152:153], 0, v[176:177]
	v_add_co_u32_e32 v176, vcc, 0x200000, v176
	v_cvt_pk_bf16_f32 v178, v130, v131
	v_cvt_pk_bf16_f32 v179, v132, v133
	s_nop 1
	v_addc_co_u32_e32 v177, vcc, 0, v177, vcc
	v_mov_b32_e32 v198, v178
	v_mov_b32_e32 v199, v179
	s_nop 1
	v_permlane16_swap_b32_e32 v196, v198
	v_permlane16_swap_b32_e32 v197, v199
	global_store_dwordx4 v[208:209], v[196:199], off offset:64
	v_lshlrev_b64 v[176:177], 12, v[160:161]
	v_lshl_add_u64 v[176:177], v[148:149], 0, v[176:177]
	global_store_dwordx4 v[176:177], v[130:133], off offset:192
.LBB0_1082:
	s_nop 1
	v_pk_mul_f32 v[130:131], v[66:67], v[136:137]
	v_pk_mul_f32 v[132:133], v[68:69], v[136:137]
	s_and_b64 vcc, exec, s[6:7]
	s_mov_b64 s[8:9], -1
	s_cbranch_vccnz .LBB0_1084
	v_lshlrev_b64 v[176:177], 11, v[166:167]
	v_lshl_add_u64 v[176:177], v[150:151], 0, v[176:177]
	v_cvt_pk_bf16_f32 v178, v130, v131
	v_cvt_pk_bf16_f32 v179, v132, v133
	v_mov_b32_e32 v202, v178
	v_mov_b32_e32 v203, v179
	s_nop 1
	v_permlane16_swap_b32_e32 v200, v202
	v_permlane16_swap_b32_e32 v201, v203
	global_store_dwordx4 v[210:211], v[200:203], off offset:64
	v_lshlrev_b64 v[176:177], 12, v[166:167]
	v_lshl_add_u64 v[176:177], v[144:145], 0, v[176:177]
	s_mov_b64 s[8:9], 0
	global_store_dwordx4 v[176:177], v[130:133], off offset:192
.LBB0_1084:
	s_andn2_b64 vcc, exec, s[8:9]
	s_cbranch_vccnz .LBB0_1086
	v_mul_i32_i24_e32 v135, 0x440, v174
	v_ashrrev_i32_e32 v177, 31, v135
	v_or_b32_e32 v176, v135, v32
	v_lshlrev_b64 v[176:177], 11, v[176:177]
	v_lshl_add_u64 v[176:177], v[152:153], 0, v[176:177]
	v_add_co_u32_e32 v176, vcc, 0x200000, v176
	v_cvt_pk_bf16_f32 v178, v130, v131
	v_cvt_pk_bf16_f32 v179, v132, v133
	s_nop 1
	v_addc_co_u32_e32 v177, vcc, 0, v177, vcc
	v_mov_b32_e32 v202, v178
	v_mov_b32_e32 v203, v179
	s_nop 1
	v_permlane16_swap_b32_e32 v200, v202
	v_permlane16_swap_b32_e32 v201, v203
	global_store_dwordx4 v[210:211], v[200:203], off offset:64
	v_lshlrev_b64 v[176:177], 12, v[164:165]
	v_lshl_add_u64 v[176:177], v[148:149], 0, v[176:177]
	global_store_dwordx4 v[176:177], v[130:133], off offset:192
.LBB0_1086:
	s_nop 1
	v_pk_mul_f32 v[130:131], v[62:63], v[142:143]
	v_pk_mul_f32 v[132:133], v[64:65], v[142:143]
	s_and_b64 vcc, exec, s[6:7]
	s_mov_b64 s[8:9], -1
	s_cbranch_vccnz .LBB0_1088
	v_ashrrev_i32_e32 v135, 31, v134
	v_lshlrev_b64 v[176:177], 11, v[134:135]
	v_lshl_add_u64 v[176:177], v[150:151], 0, v[176:177]
	v_cvt_pk_bf16_f32 v178, v130, v131
	v_cvt_pk_bf16_f32 v179, v132, v133
	v_mov_b32_e32 v180, v178
	v_mov_b32_e32 v181, v179
	v_lshl_add_u64 v[204:205], v[176:177], 0, v[212:213]
	v_lshlrev_b64 v[176:177], 12, v[134:135]
	v_lshl_add_u64 v[176:177], v[144:145], 0, v[176:177]
	s_mov_b64 s[8:9], 0
	global_store_dwordx4 v[176:177], v[130:133], off offset:512
.LBB0_1088:
	s_andn2_b64 vcc, exec, s[8:9]
	s_cbranch_vccnz .LBB0_1090
	v_mul_i32_i24_e32 v135, 0x440, v171
	v_ashrrev_i32_e32 v177, 31, v135
	v_or_b32_e32 v176, v135, v170
	v_lshlrev_b64 v[176:177], 11, v[176:177]
	v_lshl_add_u64 v[176:177], v[152:153], 0, v[176:177]
	v_add_co_u32_e32 v176, vcc, 0x200000, v176
	v_cvt_pk_bf16_f32 v178, v130, v131
	v_cvt_pk_bf16_f32 v179, v132, v133
	s_nop 1
	v_addc_co_u32_e32 v177, vcc, 0, v177, vcc
	v_mov_b32_e32 v180, v178
	v_mov_b32_e32 v181, v179
	v_lshl_add_u64 v[204:205], v[176:177], 0, v[212:213]
	v_lshlrev_b64 v[176:177], 12, v[154:155]
	v_lshl_add_u64 v[176:177], v[148:149], 0, v[176:177]
	global_store_dwordx4 v[176:177], v[130:133], off offset:512
.LBB0_1090:
	s_nop 1
	v_pk_mul_f32 v[130:131], v[58:59], v[140:141]
	v_pk_mul_f32 v[132:133], v[60:61], v[140:141]
	s_and_b64 vcc, exec, s[6:7]
	s_mov_b64 s[8:9], -1
	s_cbranch_vccnz .LBB0_1092
	v_lshlrev_b64 v[176:177], 11, v[156:157]
	v_lshl_add_u64 v[176:177], v[150:151], 0, v[176:177]
	v_cvt_pk_bf16_f32 v178, v130, v131
	v_cvt_pk_bf16_f32 v179, v132, v133
	v_mov_b32_e32 v192, v178
	v_mov_b32_e32 v193, v179
	v_lshl_add_u64 v[206:207], v[176:177], 0, v[212:213]
	v_lshlrev_b64 v[176:177], 12, v[156:157]
	v_lshl_add_u64 v[176:177], v[144:145], 0, v[176:177]
	s_mov_b64 s[8:9], 0
	global_store_dwordx4 v[176:177], v[130:133], off offset:512
.LBB0_1092:
	s_andn2_b64 vcc, exec, s[8:9]
	s_cbranch_vccnz .LBB0_1094
	v_mul_i32_i24_e32 v135, 0x440, v172
	v_ashrrev_i32_e32 v177, 31, v135
	v_or_b32_e32 v176, v135, v32
	v_lshlrev_b64 v[176:177], 11, v[176:177]
	v_lshl_add_u64 v[176:177], v[152:153], 0, v[176:177]
	v_add_co_u32_e32 v176, vcc, 0x200000, v176
	v_cvt_pk_bf16_f32 v178, v130, v131
	v_cvt_pk_bf16_f32 v179, v132, v133
	s_nop 1
	v_addc_co_u32_e32 v177, vcc, 0, v177, vcc
	v_mov_b32_e32 v192, v178
	v_mov_b32_e32 v193, v179
	v_lshl_add_u64 v[206:207], v[176:177], 0, v[212:213]
	v_lshlrev_b64 v[176:177], 12, v[158:159]
	v_lshl_add_u64 v[176:177], v[148:149], 0, v[176:177]
	global_store_dwordx4 v[176:177], v[130:133], off offset:512
; #define EPI_LOOP(...) _Pragma("unroll") for(int ai=0;ai<2;++ai) _Pragma("unroll") for(int bj=0;bj<2;++bj) \
;   _Pragma("unroll") for(int m=0;m<4;++m) _Pragma("unroll") for(int n=0;n<2;++n) { \
;     const int row=brow+ai*128+wr*64+m*16+fq*4; const int col=bcol+bj*128+wc*32+n*16+fr; \
;     f32x4& v=acc[ai][bj][m][n]; __VA_ARGS__ if (n == 1 && (m & 1)) __builtin_amdgcn_sched_barrier(0); }
; DEVI void run_phase(const int ph, const Params& P, char* shmc, const int wave_u) {
;     ...
;       } else if (brow < 3072) {
;         const bool isk = brow < 2048; const int fb = isk ? 1024 : 2048;
;         bf16* dp = isk ? sbk_p : sbv_p; bf16* ds = isk ? sbk_s : sbv_s;
;         float* op = out + (isk ? O_SBK_P : O_SBV_P); float* os = out + (isk ? O_SBK_S : O_SBV_S);
;         EPI_LOOP({ const float sc = sc4[bj][n]; const int f = row - fb; const float a = v[0] * sc, b = v[1] * sc, c = v[2] * sc, d = v[3] * sc;
;           if (!samp) { st_bf4(dp + (long)col * 1024 + f, a, b, c, d); st_f4(op + (long)col * 1024 + f, a, b, c, d); }
;           else { const int s = col - MP; st_bf4(ds + ((long)(s >> 5) * SKS + 1024 + (s & 31)) * 1024 + f, a, b, c, d); st_f4(os + (long)s * 1024 + f, a, b, c, d); } })
.LBB0_1094:
	s_nop 1
	v_pk_mul_f32 v[130:131], v[54:55], v[142:143]
	v_pk_mul_f32 v[132:133], v[56:57], v[142:143]
	s_and_b64 vcc, exec, s[6:7]
	s_mov_b64 s[8:9], -1
	s_cbranch_vccnz .LBB0_1096
	v_ashrrev_i32_e32 v135, 31, v134
	v_lshlrev_b64 v[176:177], 11, v[134:135]
	v_lshl_add_u64 v[176:177], v[150:151], 0, v[176:177]
	v_cvt_pk_bf16_f32 v178, v130, v131
	v_cvt_pk_bf16_f32 v179, v132, v133
	v_mov_b32_e32 v182, v178
	v_mov_b32_e32 v183, v179
	s_nop 1
	v_permlane16_swap_b32_e32 v180, v182
	v_permlane16_swap_b32_e32 v181, v183
	global_store_dwordx4 v[204:205], v[180:183], off offset:256
	v_lshlrev_b64 v[176:177], 12, v[134:135]
	v_lshl_add_u64 v[176:177], v[144:145], 0, v[176:177]
	s_mov_b64 s[8:9], 0
	global_store_dwordx4 v[176:177], v[130:133], off offset:576
.LBB0_1096:
	s_andn2_b64 vcc, exec, s[8:9]
	s_cbranch_vccnz .LBB0_1098
	v_mul_i32_i24_e32 v135, 0x440, v171
	v_ashrrev_i32_e32 v177, 31, v135
	v_or_b32_e32 v176, v135, v170
	v_lshlrev_b64 v[176:177], 11, v[176:177]
	v_lshl_add_u64 v[176:177], v[152:153], 0, v[176:177]
	v_add_co_u32_e32 v176, vcc, 0x200000, v176
	v_cvt_pk_bf16_f32 v178, v130, v131
	v_cvt_pk_bf16_f32 v179, v132, v133
	s_nop 1
	v_addc_co_u32_e32 v177, vcc, 0, v177, vcc
	v_mov_b32_e32 v182, v178
	v_mov_b32_e32 v183, v179
	s_nop 1
	v_permlane16_swap_b32_e32 v180, v182
	v_permlane16_swap_b32_e32 v181, v183
	global_store_dwordx4 v[204:205], v[180:183], off offset:256
	v_lshlrev_b64 v[176:177], 12, v[154:155]
	v_lshl_add_u64 v[176:177], v[148:149], 0, v[176:177]
	global_store_dwordx4 v[176:177], v[130:133], off offset:576
.LBB0_1098:
	s_nop 1
	v_pk_mul_f32 v[130:131], v[50:51], v[140:141]
	v_pk_mul_f32 v[132:133], v[52:53], v[140:141]
	s_and_b64 vcc, exec, s[6:7]
	s_mov_b64 s[8:9], -1
	s_cbranch_vccnz .LBB0_1100
	v_lshlrev_b64 v[176:177], 11, v[156:157]
	v_lshl_add_u64 v[176:177], v[150:151], 0, v[176:177]
	v_cvt_pk_bf16_f32 v178, v130, v131
	v_cvt_pk_bf16_f32 v179, v132, v133
	v_mov_b32_e32 v194, v178
	v_mov_b32_e32 v195, v179
	s_nop 1
	v_permlane16_swap_b32_e32 v192, v194
	v_permlane16_swap_b32_e32 v193, v195
	global_store_dwordx4 v[206:207], v[192:195], off offset:256
	v_lshlrev_b64 v[176:177], 12, v[156:157]
	v_lshl_add_u64 v[176:177], v[144:145], 0, v[176:177]
	s_mov_b64 s[8:9], 0
	global_store_dwordx4 v[176:177], v[130:133], off offset:576
.LBB0_1100:
	s_andn2_b64 vcc, exec, s[8:9]
	s_cbranch_vccnz .LBB0_1102
	v_mul_i32_i24_e32 v135, 0x440, v172
	v_ashrrev_i32_e32 v177, 31, v135
	v_or_b32_e32 v176, v135, v32
	v_lshlrev_b64 v[176:177], 11, v[176:177]
	v_lshl_add_u64 v[176:177], v[152:153], 0, v[176:177]
	v_add_co_u32_e32 v176, vcc, 0x200000, v176
	v_cvt_pk_bf16_f32 v178, v130, v131
	v_cvt_pk_bf16_f32 v179, v132, v133
	s_nop 1
	v_addc_co_u32_e32 v177, vcc, 0, v177, vcc
	v_mov_b32_e32 v194, v178
	v_mov_b32_e32 v195, v179
	s_nop 1
	v_permlane16_swap_b32_e32 v192, v194
	v_permlane16_swap_b32_e32 v193, v195
	global_store_dwordx4 v[206:207], v[192:195], off offset:256
	v_lshlrev_b64 v[176:177], 12, v[158:159]
	v_lshl_add_u64 v[176:177], v[148:149], 0, v[176:177]
	global_store_dwordx4 v[176:177], v[130:133], off offset:576
.LBB0_1102:
	s_nop 1
	v_pk_mul_f32 v[130:131], v[46:47], v[142:143]
	v_pk_mul_f32 v[132:133], v[48:49], v[142:143]
	s_and_b64 vcc, exec, s[6:7]
	s_mov_b64 s[8:9], -1
	s_cbranch_vccnz .LBB0_1104
	v_ashrrev_i32_e32 v135, 31, v134
	v_lshlrev_b64 v[176:177], 11, v[134:135]
	v_lshl_add_u64 v[176:177], v[150:151], 0, v[176:177]
	v_cvt_pk_bf16_f32 v178, v130, v131
	v_cvt_pk_bf16_f32 v179, v132, v133
	v_mov_b32_e32 v196, v178
	v_mov_b32_e32 v197, v179
	v_lshl_add_u64 v[208:209], v[176:177], 0, v[212:213]
	v_lshlrev_b64 v[176:177], 12, v[134:135]
	v_lshl_add_u64 v[176:177], v[144:145], 0, v[176:177]
	s_mov_b64 s[8:9], 0
	global_store_dwordx4 v[176:177], v[130:133], off offset:640
.LBB0_1104:
	s_andn2_b64 vcc, exec, s[8:9]
	s_cbranch_vccnz .LBB0_1106
	v_mul_i32_i24_e32 v135, 0x440, v171
	v_ashrrev_i32_e32 v177, 31, v135
	v_or_b32_e32 v176, v135, v170
	v_lshlrev_b64 v[176:177], 11, v[176:177]
	v_lshl_add_u64 v[176:177], v[152:153], 0, v[176:177]
	v_add_co_u32_e32 v176, vcc, 0x200000, v176
	v_cvt_pk_bf16_f32 v178, v130, v131
	v_cvt_pk_bf16_f32 v179, v132, v133
	s_nop 1
	v_addc_co_u32_e32 v177, vcc, 0, v177, vcc
	v_mov_b32_e32 v196, v178
	v_mov_b32_e32 v197, v179
	v_lshl_add_u64 v[208:209], v[176:177], 0, v[212:213]
	v_lshlrev_b64 v[176:177], 12, v[154:155]
	v_lshl_add_u64 v[176:177], v[148:149], 0, v[176:177]
	global_store_dwordx4 v[176:177], v[130:133], off offset:640
.LBB0_1106:
	s_nop 1
	v_pk_mul_f32 v[130:131], v[42:43], v[140:141]
	v_pk_mul_f32 v[132:133], v[44:45], v[140:141]
	s_and_b64 vcc, exec, s[6:7]
	s_mov_b64 s[8:9], -1
	s_cbranch_vccnz .LBB0_1108
	v_lshlrev_b64 v[176:177], 11, v[156:157]
	v_lshl_add_u64 v[176:177], v[150:151], 0, v[176:177]
	v_cvt_pk_bf16_f32 v178, v130, v131
	v_cvt_pk_bf16_f32 v179, v132, v133
	v_mov_b32_e32 v200, v178
	v_mov_b32_e32 v201, v179
	v_lshl_add_u64 v[210:211], v[176:177], 0, v[212:213]
	v_lshlrev_b64 v[176:177], 12, v[156:157]
	v_lshl_add_u64 v[176:177], v[144:145], 0, v[176:177]
	s_mov_b64 s[8:9], 0
	global_store_dwordx4 v[176:177], v[130:133], off offset:640
.LBB0_1108:
	s_andn2_b64 vcc, exec, s[8:9]
	s_cbranch_vccnz .LBB0_1110
	v_mul_i32_i24_e32 v135, 0x440, v172
	v_ashrrev_i32_e32 v177, 31, v135
	v_or_b32_e32 v176, v135, v32
	v_lshlrev_b64 v[176:177], 11, v[176:177]
	v_lshl_add_u64 v[176:177], v[152:153], 0, v[176:177]
	v_add_co_u32_e32 v176, vcc, 0x200000, v176
	v_cvt_pk_bf16_f32 v178, v130, v131
	v_cvt_pk_bf16_f32 v179, v132, v133
	s_nop 1
	v_addc_co_u32_e32 v177, vcc, 0, v177, vcc
	v_mov_b32_e32 v200, v178
	v_mov_b32_e32 v201, v179
	v_lshl_add_u64 v[210:211], v[176:177], 0, v[212:213]
	v_lshlrev_b64 v[176:177], 12, v[158:159]
	v_lshl_add_u64 v[176:177], v[148:149], 0, v[176:177]
	global_store_dwordx4 v[176:177], v[130:133], off offset:640
; #define EPI_LOOP(...) _Pragma("unroll") for(int ai=0;ai<2;++ai) _Pragma("unroll") for(int bj=0;bj<2;++bj) \
;   _Pragma("unroll") for(int m=0;m<4;++m) _Pragma("unroll") for(int n=0;n<2;++n) { \
;     const int row=brow+ai*128+wr*64+m*16+fq*4; const int col=bcol+bj*128+wc*32+n*16+fr; \
;     f32x4& v=acc[ai][bj][m][n]; __VA_ARGS__ if (n == 1 && (m & 1)) __builtin_amdgcn_sched_barrier(0); }
; DEVI void run_phase(const int ph, const Params& P, char* shmc, const int wave_u) {
;     ...
;       } else if (brow < 3072) {
;         const bool isk = brow < 2048; const int fb = isk ? 1024 : 2048;
;         bf16* dp = isk ? sbk_p : sbv_p; bf16* ds = isk ? sbk_s : sbv_s;
;         float* op = out + (isk ? O_SBK_P : O_SBV_P); float* os = out + (isk ? O_SBK_S : O_SBV_S);
;         EPI_LOOP({ const float sc = sc4[bj][n]; const int f = row - fb; const float a = v[0] * sc, b = v[1] * sc, c = v[2] * sc, d = v[3] * sc;
;           if (!samp) { st_bf4(dp + (long)col * 1024 + f, a, b, c, d); st_f4(op + (long)col * 1024 + f, a, b, c, d); }
;           else { const int s = col - MP; st_bf4(ds + ((long)(s >> 5) * SKS + 1024 + (s & 31)) * 1024 + f, a, b, c, d); st_f4(os + (long)s * 1024 + f, a, b, c, d); } })
.LBB0_1110:
	s_nop 1
	v_pk_mul_f32 v[130:131], v[38:39], v[142:143]
	v_pk_mul_f32 v[132:133], v[40:41], v[142:143]
	s_and_b64 vcc, exec, s[6:7]
	s_mov_b64 s[8:9], -1
	s_cbranch_vccnz .LBB0_1112
	v_ashrrev_i32_e32 v135, 31, v134
	v_lshlrev_b64 v[176:177], 11, v[134:135]
	v_lshl_add_u64 v[176:177], v[150:151], 0, v[176:177]
	v_cvt_pk_bf16_f32 v178, v130, v131
	v_cvt_pk_bf16_f32 v179, v132, v133
	v_mov_b32_e32 v198, v178
	v_mov_b32_e32 v199, v179
	s_nop 1
	v_permlane16_swap_b32_e32 v196, v198
	v_permlane16_swap_b32_e32 v197, v199
	global_store_dwordx4 v[208:209], v[196:199], off offset:320
	v_lshlrev_b64 v[176:177], 12, v[134:135]
	v_lshl_add_u64 v[176:177], v[144:145], 0, v[176:177]
	s_mov_b64 s[8:9], 0
	global_store_dwordx4 v[176:177], v[130:133], off offset:704
.LBB0_1112:
	s_andn2_b64 vcc, exec, s[8:9]
	s_cbranch_vccnz .LBB0_1114
	v_mul_i32_i24_e32 v135, 0x440, v171
	v_ashrrev_i32_e32 v177, 31, v135
	v_or_b32_e32 v176, v135, v170
	v_lshlrev_b64 v[176:177], 11, v[176:177]
	v_lshl_add_u64 v[176:177], v[152:153], 0, v[176:177]
	v_add_co_u32_e32 v176, vcc, 0x200000, v176
	v_lshlrev_b64 v[154:155], 12, v[154:155]
	s_nop 0
	v_addc_co_u32_e32 v177, vcc, 0, v177, vcc
	v_lshl_add_u64 v[154:155], v[148:149], 0, v[154:155]
	v_cvt_pk_bf16_f32 v178, v130, v131
	v_cvt_pk_bf16_f32 v179, v132, v133
	v_mov_b32_e32 v198, v178
	v_mov_b32_e32 v199, v179
	s_nop 1
	v_permlane16_swap_b32_e32 v196, v198
	v_permlane16_swap_b32_e32 v197, v199
	global_store_dwordx4 v[208:209], v[196:199], off offset:320
	global_store_dwordx4 v[154:155], v[130:133], off offset:704
.LBB0_1114:
	s_nop 1
	v_pk_mul_f32 v[130:131], v[34:35], v[140:141]
	v_pk_mul_f32 v[132:133], v[36:37], v[140:141]
	s_and_b64 vcc, exec, s[6:7]
	s_mov_b64 s[8:9], -1
	s_cbranch_vccnz .LBB0_1116
	v_lshlrev_b64 v[154:155], 11, v[156:157]
	v_lshl_add_u64 v[154:155], v[150:151], 0, v[154:155]
	v_cvt_pk_bf16_f32 v176, v130, v131
	v_cvt_pk_bf16_f32 v177, v132, v133
	v_mov_b32_e32 v202, v176
	v_mov_b32_e32 v203, v177
	s_nop 1
	v_permlane16_swap_b32_e32 v200, v202
	v_permlane16_swap_b32_e32 v201, v203
	global_store_dwordx4 v[210:211], v[200:203], off offset:320
	v_lshlrev_b64 v[154:155], 12, v[156:157]
	v_lshl_add_u64 v[154:155], v[144:145], 0, v[154:155]
	s_mov_b64 s[8:9], 0
	global_store_dwordx4 v[154:155], v[130:133], off offset:704
.LBB0_1116:
	s_andn2_b64 vcc, exec, s[8:9]
	s_cbranch_vccnz .LBB0_1118
	v_mul_i32_i24_e32 v135, 0x440, v172
	v_ashrrev_i32_e32 v155, 31, v135
	v_or_b32_e32 v154, v135, v32
	v_lshlrev_b64 v[154:155], 11, v[154:155]
	v_lshl_add_u64 v[154:155], v[152:153], 0, v[154:155]
	v_add_co_u32_e32 v154, vcc, 0x200000, v154
	v_cvt_pk_bf16_f32 v156, v130, v131
	v_cvt_pk_bf16_f32 v157, v132, v133
	s_nop 1
	v_addc_co_u32_e32 v155, vcc, 0, v155, vcc
	v_mov_b32_e32 v202, v156
	v_mov_b32_e32 v203, v157
	s_nop 1
	v_permlane16_swap_b32_e32 v200, v202
	v_permlane16_swap_b32_e32 v201, v203
	global_store_dwordx4 v[210:211], v[200:203], off offset:320
	v_lshlrev_b64 v[154:155], 12, v[158:159]
	v_lshl_add_u64 v[154:155], v[148:149], 0, v[154:155]
	global_store_dwordx4 v[154:155], v[130:133], off offset:704
.LBB0_1118:
	s_nop 1
	v_pk_mul_f32 v[130:131], v[28:29], v[138:139]
	v_pk_mul_f32 v[132:133], v[30:31], v[138:139]
	s_and_b64 vcc, exec, s[6:7]
	s_mov_b64 s[8:9], -1
	s_cbranch_vccnz .LBB0_1120
	v_lshlrev_b64 v[154:155], 11, v[162:163]
	v_lshl_add_u64 v[154:155], v[150:151], 0, v[154:155]
	v_cvt_pk_bf16_f32 v156, v130, v131
	v_cvt_pk_bf16_f32 v157, v132, v133
	v_mov_b32_e32 v180, v156
	v_mov_b32_e32 v181, v157
	v_lshl_add_u64 v[204:205], v[154:155], 0, v[212:213]
	v_lshlrev_b64 v[154:155], 12, v[162:163]
	v_lshl_add_u64 v[154:155], v[144:145], 0, v[154:155]
	s_mov_b64 s[8:9], 0
	global_store_dwordx4 v[154:155], v[130:133], off offset:512
.LBB0_1120:
	s_andn2_b64 vcc, exec, s[8:9]
	s_cbranch_vccnz .LBB0_1122
	v_mul_i32_i24_e32 v135, 0x440, v173
	v_ashrrev_i32_e32 v155, 31, v135
	v_or_b32_e32 v154, v135, v170
	v_lshlrev_b64 v[154:155], 11, v[154:155]
	v_lshl_add_u64 v[154:155], v[152:153], 0, v[154:155]
	v_add_co_u32_e32 v154, vcc, 0x200000, v154
	v_cvt_pk_bf16_f32 v156, v130, v131
	v_cvt_pk_bf16_f32 v157, v132, v133
	s_nop 1
	v_addc_co_u32_e32 v155, vcc, 0, v155, vcc
	v_mov_b32_e32 v180, v156
	v_mov_b32_e32 v181, v157
	v_lshl_add_u64 v[204:205], v[154:155], 0, v[212:213]
	v_lshlrev_b64 v[154:155], 12, v[160:161]
	v_lshl_add_u64 v[154:155], v[148:149], 0, v[154:155]
	global_store_dwordx4 v[154:155], v[130:133], off offset:512
.LBB0_1122:
	s_nop 1
	v_pk_mul_f32 v[130:131], v[24:25], v[136:137]
	v_pk_mul_f32 v[132:133], v[26:27], v[136:137]
	s_and_b64 vcc, exec, s[6:7]
	s_mov_b64 s[8:9], -1
	s_cbranch_vccnz .LBB0_1124
	v_lshlrev_b64 v[154:155], 11, v[166:167]
	v_lshl_add_u64 v[154:155], v[150:151], 0, v[154:155]
	v_cvt_pk_bf16_f32 v156, v130, v131
	v_cvt_pk_bf16_f32 v157, v132, v133
	v_mov_b32_e32 v192, v156
	v_mov_b32_e32 v193, v157
	v_lshl_add_u64 v[206:207], v[154:155], 0, v[212:213]
	v_lshlrev_b64 v[154:155], 12, v[166:167]
	v_lshl_add_u64 v[154:155], v[144:145], 0, v[154:155]
	s_mov_b64 s[8:9], 0
	global_store_dwordx4 v[154:155], v[130:133], off offset:512
.LBB0_1124:
	s_andn2_b64 vcc, exec, s[8:9]
	s_cbranch_vccnz .LBB0_1126
	v_mul_i32_i24_e32 v135, 0x440, v174
	v_ashrrev_i32_e32 v155, 31, v135
	v_or_b32_e32 v154, v135, v32
	v_lshlrev_b64 v[154:155], 11, v[154:155]
	v_lshl_add_u64 v[154:155], v[152:153], 0, v[154:155]
	v_add_co_u32_e32 v154, vcc, 0x200000, v154
	v_cvt_pk_bf16_f32 v156, v130, v131
	v_cvt_pk_bf16_f32 v157, v132, v133
	s_nop 1
	v_addc_co_u32_e32 v155, vcc, 0, v155, vcc
	v_mov_b32_e32 v192, v156
	v_mov_b32_e32 v193, v157
	v_lshl_add_u64 v[206:207], v[154:155], 0, v[212:213]
	v_lshlrev_b64 v[154:155], 12, v[164:165]
	v_lshl_add_u64 v[154:155], v[148:149], 0, v[154:155]
	global_store_dwordx4 v[154:155], v[130:133], off offset:512
; #define EPI_LOOP(...) _Pragma("unroll") for(int ai=0;ai<2;++ai) _Pragma("unroll") for(int bj=0;bj<2;++bj) \
;   _Pragma("unroll") for(int m=0;m<4;++m) _Pragma("unroll") for(int n=0;n<2;++n) { \
;     const int row=brow+ai*128+wr*64+m*16+fq*4; const int col=bcol+bj*128+wc*32+n*16+fr; \
;     f32x4& v=acc[ai][bj][m][n]; __VA_ARGS__ if (n == 1 && (m & 1)) __builtin_amdgcn_sched_barrier(0); }
; DEVI void run_phase(const int ph, const Params& P, char* shmc, const int wave_u) {
;     ...
;       } else if (brow < 3072) {
;         const bool isk = brow < 2048; const int fb = isk ? 1024 : 2048;
;         bf16* dp = isk ? sbk_p : sbv_p; bf16* ds = isk ? sbk_s : sbv_s;
;         float* op = out + (isk ? O_SBK_P : O_SBV_P); float* os = out + (isk ? O_SBK_S : O_SBV_S);
;         EPI_LOOP({ const float sc = sc4[bj][n]; const int f = row - fb; const float a = v[0] * sc, b = v[1] * sc, c = v[2] * sc, d = v[3] * sc;
;           if (!samp) { st_bf4(dp + (long)col * 1024 + f, a, b, c, d); st_f4(op + (long)col * 1024 + f, a, b, c, d); }
;           else { const int s = col - MP; st_bf4(ds + ((long)(s >> 5) * SKS + 1024 + (s & 31)) * 1024 + f, a, b, c, d); st_f4(os + (long)s * 1024 + f, a, b, c, d); } })
.LBB0_1126:
	s_nop 1
	v_pk_mul_f32 v[130:131], v[20:21], v[138:139]
	v_pk_mul_f32 v[132:133], v[22:23], v[138:139]
	s_and_b64 vcc, exec, s[6:7]
	s_mov_b64 s[8:9], -1
	s_cbranch_vccnz .LBB0_1128
	v_lshlrev_b64 v[154:155], 11, v[162:163]
	v_lshl_add_u64 v[154:155], v[150:151], 0, v[154:155]
	v_cvt_pk_bf16_f32 v156, v130, v131
	v_cvt_pk_bf16_f32 v157, v132, v133
	v_mov_b32_e32 v182, v156
	v_mov_b32_e32 v183, v157
	s_nop 1
	v_permlane16_swap_b32_e32 v180, v182
	v_permlane16_swap_b32_e32 v181, v183
	global_store_dwordx4 v[204:205], v[180:183], off offset:256
	v_lshlrev_b64 v[154:155], 12, v[162:163]
	v_lshl_add_u64 v[154:155], v[144:145], 0, v[154:155]
	s_mov_b64 s[8:9], 0
	global_store_dwordx4 v[154:155], v[130:133], off offset:576
.LBB0_1128:
	s_andn2_b64 vcc, exec, s[8:9]
	s_cbranch_vccnz .LBB0_1130
	v_mul_i32_i24_e32 v135, 0x440, v173
	v_ashrrev_i32_e32 v155, 31, v135
	v_or_b32_e32 v154, v135, v170
	v_lshlrev_b64 v[154:155], 11, v[154:155]
	v_lshl_add_u64 v[154:155], v[152:153], 0, v[154:155]
	v_add_co_u32_e32 v154, vcc, 0x200000, v154
	v_cvt_pk_bf16_f32 v156, v130, v131
	v_cvt_pk_bf16_f32 v157, v132, v133
	s_nop 1
	v_addc_co_u32_e32 v155, vcc, 0, v155, vcc
	v_mov_b32_e32 v182, v156
	v_mov_b32_e32 v183, v157
	s_nop 1
	v_permlane16_swap_b32_e32 v180, v182
	v_permlane16_swap_b32_e32 v181, v183
	global_store_dwordx4 v[204:205], v[180:183], off offset:256
	v_lshlrev_b64 v[154:155], 12, v[160:161]
	v_lshl_add_u64 v[154:155], v[148:149], 0, v[154:155]
	global_store_dwordx4 v[154:155], v[130:133], off offset:576
.LBB0_1130:
	s_nop 1
	v_pk_mul_f32 v[130:131], v[16:17], v[136:137]
	v_pk_mul_f32 v[132:133], v[18:19], v[136:137]
	s_and_b64 vcc, exec, s[6:7]
	s_mov_b64 s[8:9], -1
	s_cbranch_vccnz .LBB0_1132
	v_lshlrev_b64 v[154:155], 11, v[166:167]
	v_lshl_add_u64 v[154:155], v[150:151], 0, v[154:155]
	v_cvt_pk_bf16_f32 v156, v130, v131
	v_cvt_pk_bf16_f32 v157, v132, v133
	v_mov_b32_e32 v194, v156
	v_mov_b32_e32 v195, v157
	s_nop 1
	v_permlane16_swap_b32_e32 v192, v194
	v_permlane16_swap_b32_e32 v193, v195
	global_store_dwordx4 v[206:207], v[192:195], off offset:256
	v_lshlrev_b64 v[154:155], 12, v[166:167]
	v_lshl_add_u64 v[154:155], v[144:145], 0, v[154:155]
	s_mov_b64 s[8:9], 0
	global_store_dwordx4 v[154:155], v[130:133], off offset:576
.LBB0_1132:
	s_andn2_b64 vcc, exec, s[8:9]
	s_cbranch_vccnz .LBB0_1134
	v_mul_i32_i24_e32 v135, 0x440, v174
	v_ashrrev_i32_e32 v155, 31, v135
	v_or_b32_e32 v154, v135, v32
	v_lshlrev_b64 v[154:155], 11, v[154:155]
	v_lshl_add_u64 v[154:155], v[152:153], 0, v[154:155]
	v_add_co_u32_e32 v154, vcc, 0x200000, v154
	v_cvt_pk_bf16_f32 v156, v130, v131
	v_cvt_pk_bf16_f32 v157, v132, v133
	s_nop 1
	v_addc_co_u32_e32 v155, vcc, 0, v155, vcc
	v_mov_b32_e32 v194, v156
	v_mov_b32_e32 v195, v157
	s_nop 1
	v_permlane16_swap_b32_e32 v192, v194
	v_permlane16_swap_b32_e32 v193, v195
	global_store_dwordx4 v[206:207], v[192:195], off offset:256
	v_lshlrev_b64 v[154:155], 12, v[164:165]
	v_lshl_add_u64 v[154:155], v[148:149], 0, v[154:155]
	global_store_dwordx4 v[154:155], v[130:133], off offset:576
.LBB0_1134:
	s_nop 1
	v_pk_mul_f32 v[130:131], v[12:13], v[138:139]
	v_pk_mul_f32 v[132:133], v[14:15], v[138:139]
	s_and_b64 vcc, exec, s[6:7]
	s_mov_b64 s[8:9], -1
	s_cbranch_vccnz .LBB0_1136
	v_lshlrev_b64 v[154:155], 11, v[162:163]
	v_lshl_add_u64 v[154:155], v[150:151], 0, v[154:155]
	v_cvt_pk_bf16_f32 v156, v130, v131
	v_cvt_pk_bf16_f32 v157, v132, v133
	v_mov_b32_e32 v196, v156
	v_mov_b32_e32 v197, v157
	v_lshl_add_u64 v[208:209], v[154:155], 0, v[212:213]
	v_lshlrev_b64 v[154:155], 12, v[162:163]
	v_lshl_add_u64 v[154:155], v[144:145], 0, v[154:155]
	s_mov_b64 s[8:9], 0
	global_store_dwordx4 v[154:155], v[130:133], off offset:640
.LBB0_1136:
	s_andn2_b64 vcc, exec, s[8:9]
	s_cbranch_vccnz .LBB0_1138
	v_mul_i32_i24_e32 v135, 0x440, v173
	v_ashrrev_i32_e32 v155, 31, v135
	v_or_b32_e32 v154, v135, v170
	v_lshlrev_b64 v[154:155], 11, v[154:155]
	v_lshl_add_u64 v[154:155], v[152:153], 0, v[154:155]
	v_add_co_u32_e32 v154, vcc, 0x200000, v154
	v_cvt_pk_bf16_f32 v156, v130, v131
	v_cvt_pk_bf16_f32 v157, v132, v133
	s_nop 1
	v_addc_co_u32_e32 v155, vcc, 0, v155, vcc
	v_mov_b32_e32 v196, v156
	v_mov_b32_e32 v197, v157
	v_lshl_add_u64 v[208:209], v[154:155], 0, v[212:213]
	v_lshlrev_b64 v[154:155], 12, v[160:161]
	v_lshl_add_u64 v[154:155], v[148:149], 0, v[154:155]
	global_store_dwordx4 v[154:155], v[130:133], off offset:640
; #define EPI_LOOP(...) _Pragma("unroll") for(int ai=0;ai<2;++ai) _Pragma("unroll") for(int bj=0;bj<2;++bj) \
;   _Pragma("unroll") for(int m=0;m<4;++m) _Pragma("unroll") for(int n=0;n<2;++n) { \
;     const int row=brow+ai*128+wr*64+m*16+fq*4; const int col=bcol+bj*128+wc*32+n*16+fr; \
;     f32x4& v=acc[ai][bj][m][n]; __VA_ARGS__ if (n == 1 && (m & 1)) __builtin_amdgcn_sched_barrier(0); }
; DEVI void run_phase(const int ph, const Params& P, char* shmc, const int wave_u) {
;     ...
;       } else if (brow < 3072) {
;         const bool isk = brow < 2048; const int fb = isk ? 1024 : 2048;
;         bf16* dp = isk ? sbk_p : sbv_p; bf16* ds = isk ? sbk_s : sbv_s;
;         float* op = out + (isk ? O_SBK_P : O_SBV_P); float* os = out + (isk ? O_SBK_S : O_SBV_S);
;         EPI_LOOP({ const float sc = sc4[bj][n]; const int f = row - fb; const float a = v[0] * sc, b = v[1] * sc, c = v[2] * sc, d = v[3] * sc;
;           if (!samp) { st_bf4(dp + (long)col * 1024 + f, a, b, c, d); st_f4(op + (long)col * 1024 + f, a, b, c, d); }
;           else { const int s = col - MP; st_bf4(ds + ((long)(s >> 5) * SKS + 1024 + (s & 31)) * 1024 + f, a, b, c, d); st_f4(os + (long)s * 1024 + f, a, b, c, d); } })
.LBB0_1138:
	s_nop 1
	v_pk_mul_f32 v[130:131], v[8:9], v[136:137]
	v_pk_mul_f32 v[132:133], v[10:11], v[136:137]
	s_and_b64 vcc, exec, s[6:7]
	s_mov_b64 s[8:9], -1
	s_cbranch_vccnz .LBB0_1140
	v_lshlrev_b64 v[154:155], 11, v[166:167]
	v_lshl_add_u64 v[154:155], v[150:151], 0, v[154:155]
	v_cvt_pk_bf16_f32 v156, v130, v131
	v_cvt_pk_bf16_f32 v157, v132, v133
	v_mov_b32_e32 v200, v156
	v_mov_b32_e32 v201, v157
	v_lshl_add_u64 v[210:211], v[154:155], 0, v[212:213]
	v_lshlrev_b64 v[154:155], 12, v[166:167]
	v_lshl_add_u64 v[154:155], v[144:145], 0, v[154:155]
	s_mov_b64 s[8:9], 0
	global_store_dwordx4 v[154:155], v[130:133], off offset:640
.LBB0_1140:
	s_andn2_b64 vcc, exec, s[8:9]
	s_cbranch_vccnz .LBB0_1142
	v_mul_i32_i24_e32 v135, 0x440, v174
	v_ashrrev_i32_e32 v155, 31, v135
	v_or_b32_e32 v154, v135, v32
	v_lshlrev_b64 v[154:155], 11, v[154:155]
	v_lshl_add_u64 v[154:155], v[152:153], 0, v[154:155]
	v_add_co_u32_e32 v154, vcc, 0x200000, v154
	v_cvt_pk_bf16_f32 v156, v130, v131
	v_cvt_pk_bf16_f32 v157, v132, v133
	s_nop 1
	v_addc_co_u32_e32 v155, vcc, 0, v155, vcc
	v_mov_b32_e32 v200, v156
	v_mov_b32_e32 v201, v157
	v_lshl_add_u64 v[210:211], v[154:155], 0, v[212:213]
	v_lshlrev_b64 v[154:155], 12, v[164:165]
	v_lshl_add_u64 v[154:155], v[148:149], 0, v[154:155]
	global_store_dwordx4 v[154:155], v[130:133], off offset:640
.LBB0_1142:
	s_nop 1
	v_pk_mul_f32 v[130:131], v[4:5], v[138:139]
	v_pk_mul_f32 v[132:133], v[6:7], v[138:139]
	s_and_b64 vcc, exec, s[6:7]
	s_mov_b64 s[8:9], -1
	s_cbranch_vccnz .LBB0_1144
	v_lshlrev_b64 v[154:155], 11, v[162:163]
	v_lshl_add_u64 v[154:155], v[150:151], 0, v[154:155]
	v_cvt_pk_bf16_f32 v156, v130, v131
	v_cvt_pk_bf16_f32 v157, v132, v133
	v_mov_b32_e32 v198, v156
	v_mov_b32_e32 v199, v157
	s_nop 1
	v_permlane16_swap_b32_e32 v196, v198
	v_permlane16_swap_b32_e32 v197, v199
	global_store_dwordx4 v[208:209], v[196:199], off offset:320
	v_lshlrev_b64 v[154:155], 12, v[162:163]
	v_lshl_add_u64 v[154:155], v[144:145], 0, v[154:155]
	s_mov_b64 s[8:9], 0
	global_store_dwordx4 v[154:155], v[130:133], off offset:704
.LBB0_1144:
	s_andn2_b64 vcc, exec, s[8:9]
	s_cbranch_vccnz .LBB0_1146
	v_mul_i32_i24_e32 v135, 0x440, v173
	v_ashrrev_i32_e32 v155, 31, v135
	v_or_b32_e32 v154, v135, v170
	v_lshlrev_b64 v[154:155], 11, v[154:155]
	v_lshl_add_u64 v[154:155], v[152:153], 0, v[154:155]
	v_add_co_u32_e32 v154, vcc, 0x200000, v154
	v_cvt_pk_bf16_f32 v156, v130, v131
	v_cvt_pk_bf16_f32 v157, v132, v133
	s_nop 1
	v_addc_co_u32_e32 v155, vcc, 0, v155, vcc
	v_mov_b32_e32 v198, v156
	v_mov_b32_e32 v199, v157
	s_nop 1
	v_permlane16_swap_b32_e32 v196, v198
	v_permlane16_swap_b32_e32 v197, v199
	global_store_dwordx4 v[208:209], v[196:199], off offset:320
	v_lshlrev_b64 v[154:155], 12, v[160:161]
	v_lshl_add_u64 v[154:155], v[148:149], 0, v[154:155]
	global_store_dwordx4 v[154:155], v[130:133], off offset:704
.LBB0_1146:
	s_nop 1
	v_pk_mul_f32 v[130:131], v[0:1], v[136:137]
	v_pk_mul_f32 v[132:133], v[2:3], v[136:137]
	s_and_b64 vcc, exec, s[6:7]
	s_mov_b64 s[6:7], -1
	s_cbranch_vccnz .LBB0_1148
	v_lshlrev_b64 v[154:155], 11, v[166:167]
	v_lshl_add_u64 v[150:151], v[150:151], 0, v[154:155]
	v_cvt_pk_bf16_f32 v154, v130, v131
	v_cvt_pk_bf16_f32 v155, v132, v133
	v_mov_b32_e32 v202, v154
	v_mov_b32_e32 v203, v155
	s_nop 1
	v_permlane16_swap_b32_e32 v200, v202
	v_permlane16_swap_b32_e32 v201, v203
	global_store_dwordx4 v[210:211], v[200:203], off offset:320
	v_lshlrev_b64 v[150:151], 12, v[166:167]
	v_lshl_add_u64 v[144:145], v[144:145], 0, v[150:151]
	s_mov_b64 s[6:7], 0
	global_store_dwordx4 v[144:145], v[130:133], off offset:704
.LBB0_1148:
	s_andn2_b64 vcc, exec, s[6:7]
	s_cbranch_vccnz .LBB0_1150
	v_mul_i32_i24_e32 v135, 0x440, v174
	v_ashrrev_i32_e32 v145, 31, v135
	v_or_b32_e32 v144, v135, v32
	v_lshlrev_b64 v[144:145], 11, v[144:145]
	v_lshl_add_u64 v[144:145], v[152:153], 0, v[144:145]
	v_add_co_u32_e32 v144, vcc, 0x200000, v144
	v_cvt_pk_bf16_f32 v150, v130, v131
	v_cvt_pk_bf16_f32 v151, v132, v133
	s_nop 1
	v_addc_co_u32_e32 v145, vcc, 0, v145, vcc
	v_mov_b32_e32 v202, v150
	v_mov_b32_e32 v203, v151
	s_nop 1
	v_permlane16_swap_b32_e32 v200, v202
	v_permlane16_swap_b32_e32 v201, v203
	global_store_dwordx4 v[210:211], v[200:203], off offset:320
	v_lshlrev_b64 v[144:145], 12, v[164:165]
	v_lshl_add_u64 v[144:145], v[148:149], 0, v[144:145]
	global_store_dwordx4 v[144:145], v[130:133], off offset:704

; #define EPI_LOOP(...) _Pragma("unroll") for(int ai=0;ai<2;++ai) _Pragma("unroll") for(int bj=0;bj<2;++bj) \
;   _Pragma("unroll") for(int m=0;m<4;++m) _Pragma("unroll") for(int n=0;n<2;++n) { \
;     const int row=brow+ai*128+wr*64+m*16+fq*4; const int col=bcol+bj*128+wc*32+n*16+fr; \
;     f32x4& v=acc[ai][bj][m][n]; __VA_ARGS__ if (n == 1 && (m & 1)) __builtin_amdgcn_sched_barrier(0); }
; DEVI void run_phase(const int ph, const Params& P, char* shmc, const int wave_u) {
;     ...
;       if (brow < 1024) {
;         EPI_LOOP({ const float sc = sc4[bj][n] * SB_C; st_bf4(sbq + (long)col * 1024 + row, v[0] * sc, v[1] * sc, v[2] * sc, v[3] * sc); })
.LBB0_1152:
	s_andn2_b64 vcc, exec, s[6:7]
	v_mbcnt_lo_u32_b32 v174, -1, 0
	v_mbcnt_hi_u32_b32 v174, -1, v174
	v_bfe_u32 v174, v174, 4, 1
	v_mul_u32_u24_e32 v174, 24, v174
	v_mov_b32_e32 v175, 0
	s_cbranch_vccnz .LBB0_966
	v_lshl_add_u32 v32, v169, 6, s0
	v_lshl_or_b32 v130, v168, 2, v32
	v_ashrrev_i32_e32 v131, 31, v130
	s_waitcnt vmcnt(0) lgkmcnt(0)
	v_mul_f32_e32 v32, 0x3e0293ee, v142
	v_ashrrev_i32_e32 v135, 31, v134
	v_lshl_add_u64 v[144:145], v[130:131], 1, s[82:83]
	v_lshlrev_b64 v[132:133], 11, v[134:135]
	v_mul_f32_e32 v126, v126, v32
	v_lshl_add_u64 v[142:143], v[144:145], 0, v[132:133]
	v_mul_f32_e32 v127, v127, v32
	v_cvt_pk_bf16_f32 v126, v126, v127
	v_mul_f32_e32 v128, v128, v32
	v_mul_f32_e32 v129, v129, v32
	v_cvt_pk_bf16_f32 v127, v128, v129
	v_mov_b32_e32 v148, v126
	v_mov_b32_e32 v149, v127
	v_lshl_add_u64 v[164:165], v[142:143], 0, v[174:175]
	v_or_b32_e32 v126, 16, v134
	v_ashrrev_i32_e32 v127, 31, v126
	v_mul_f32_e32 v131, 0x3e0293ee, v140
	v_lshlrev_b64 v[126:127], 11, v[126:127]
	v_lshl_add_u64 v[128:129], v[144:145], 0, v[126:127]
	v_mul_f32_e32 v122, v122, v131
	v_mul_f32_e32 v123, v123, v131
	v_mul_f32_e32 v118, v118, v32
	v_mul_f32_e32 v119, v119, v32
	v_mul_f32_e32 v114, v114, v131
	v_mul_f32_e32 v115, v115, v131
	v_mul_f32_e32 v124, v124, v131
	v_mul_f32_e32 v125, v125, v131
	v_cvt_pk_bf16_f32 v122, v122, v123
	v_cvt_pk_bf16_f32 v123, v124, v125
	v_mov_b32_e32 v152, v122
	v_mov_b32_e32 v153, v123
	v_lshl_add_u64 v[166:167], v[128:129], 0, v[174:175]
	v_mul_f32_e32 v120, v120, v32
	v_mul_f32_e32 v121, v121, v32
	v_cvt_pk_bf16_f32 v118, v118, v119
	v_cvt_pk_bf16_f32 v119, v120, v121
	v_mov_b32_e32 v150, v118
	v_mov_b32_e32 v151, v119
	s_nop 1
	v_permlane16_swap_b32_e32 v148, v150
	v_permlane16_swap_b32_e32 v149, v151
	global_store_dwordx4 v[164:165], v[148:151], off
	v_mul_f32_e32 v116, v116, v131
	v_mul_f32_e32 v117, v117, v131
	v_cvt_pk_bf16_f32 v114, v114, v115
	v_cvt_pk_bf16_f32 v115, v116, v117
	v_mov_b32_e32 v154, v114
	v_mov_b32_e32 v155, v115
	s_nop 1
	v_permlane16_swap_b32_e32 v152, v154
	v_permlane16_swap_b32_e32 v153, v155
	global_store_dwordx4 v[166:167], v[152:155], off
	v_mul_f32_e32 v110, v110, v32
	v_mul_f32_e32 v111, v111, v32
	v_mul_f32_e32 v106, v106, v131
	v_mul_f32_e32 v107, v107, v131
	v_mul_f32_e32 v102, v102, v32
	v_mul_f32_e32 v103, v103, v32
	v_mul_f32_e32 v98, v98, v131
	v_mul_f32_e32 v99, v99, v131
	v_mul_f32_e32 v112, v112, v32
	v_mul_f32_e32 v113, v113, v32
	v_cvt_pk_bf16_f32 v110, v110, v111
	v_cvt_pk_bf16_f32 v111, v112, v113
	v_mov_b32_e32 v156, v110
	v_mov_b32_e32 v157, v111
	v_lshl_add_u64 v[170:171], v[142:143], 0, v[174:175]
	v_mul_f32_e32 v108, v108, v131
	v_mul_f32_e32 v109, v109, v131
	v_cvt_pk_bf16_f32 v106, v106, v107
	v_cvt_pk_bf16_f32 v107, v108, v109
	v_mov_b32_e32 v160, v106
	v_mov_b32_e32 v161, v107
	v_lshl_add_u64 v[172:173], v[128:129], 0, v[174:175]
	v_mul_f32_e32 v104, v104, v32
	v_mul_f32_e32 v105, v105, v32
	v_cvt_pk_bf16_f32 v102, v102, v103
	v_cvt_pk_bf16_f32 v103, v104, v105
	v_mov_b32_e32 v158, v102
	v_mov_b32_e32 v159, v103
	s_nop 1
	v_permlane16_swap_b32_e32 v156, v158
	v_permlane16_swap_b32_e32 v157, v159
	global_store_dwordx4 v[170:171], v[156:159], off offset:64
	v_mul_f32_e32 v100, v100, v131
	v_mul_f32_e32 v101, v101, v131
	v_cvt_pk_bf16_f32 v98, v98, v99
	v_cvt_pk_bf16_f32 v99, v100, v101
	v_mov_b32_e32 v162, v98
	v_mov_b32_e32 v163, v99
	s_nop 1
	v_permlane16_swap_b32_e32 v160, v162
	v_permlane16_swap_b32_e32 v161, v163
	global_store_dwordx4 v[172:173], v[160:163], off offset:64
	v_or_b32_e32 v98, 0x80, v134
	v_mul_f32_e32 v102, 0x3e0293ee, v138
	v_ashrrev_i32_e32 v99, 31, v98
	v_lshlrev_b64 v[98:99], 11, v[98:99]
	v_mul_f32_e32 v94, v94, v102
	v_lshl_add_u64 v[100:101], v[144:145], 0, v[98:99]
	v_mul_f32_e32 v95, v95, v102
	v_cvt_pk_bf16_f32 v94, v94, v95
	v_mul_f32_e32 v96, v96, v102
	v_mul_f32_e32 v97, v97, v102
	v_cvt_pk_bf16_f32 v95, v96, v97
	v_mov_b32_e32 v148, v94
	v_mov_b32_e32 v149, v95
	v_lshl_add_u64 v[164:165], v[100:101], 0, v[174:175]
	v_or_b32_e32 v94, 0x90, v134
	v_ashrrev_i32_e32 v95, 31, v94
	v_mul_f32_e32 v103, 0x3e0293ee, v136
	v_lshlrev_b64 v[94:95], 11, v[94:95]
	v_lshl_add_u64 v[96:97], v[144:145], 0, v[94:95]
	v_mul_f32_e32 v90, v90, v103
	v_mul_f32_e32 v91, v91, v103
	v_mul_f32_e32 v86, v86, v102
	v_mul_f32_e32 v87, v87, v102
	v_mul_f32_e32 v82, v82, v103
	v_mul_f32_e32 v83, v83, v103
	v_mul_f32_e32 v92, v92, v103
	v_mul_f32_e32 v93, v93, v103
	v_cvt_pk_bf16_f32 v90, v90, v91
	v_cvt_pk_bf16_f32 v91, v92, v93
	v_mov_b32_e32 v152, v90
	v_mov_b32_e32 v153, v91
	v_lshl_add_u64 v[166:167], v[96:97], 0, v[174:175]
	v_mul_f32_e32 v88, v88, v102
	v_mul_f32_e32 v89, v89, v102
	v_cvt_pk_bf16_f32 v86, v86, v87
	v_cvt_pk_bf16_f32 v87, v88, v89
	v_mov_b32_e32 v150, v86
	v_mov_b32_e32 v151, v87
	s_nop 1
	v_permlane16_swap_b32_e32 v148, v150
	v_permlane16_swap_b32_e32 v149, v151
	global_store_dwordx4 v[164:165], v[148:151], off
	v_mul_f32_e32 v84, v84, v103
	v_mul_f32_e32 v85, v85, v103
	v_cvt_pk_bf16_f32 v82, v82, v83
	v_cvt_pk_bf16_f32 v83, v84, v85
	v_mov_b32_e32 v154, v82
	v_mov_b32_e32 v155, v83
	s_nop 1
	v_permlane16_swap_b32_e32 v152, v154
	v_permlane16_swap_b32_e32 v153, v155
	global_store_dwordx4 v[166:167], v[152:155], off
	v_mul_f32_e32 v78, v78, v102
	v_mul_f32_e32 v79, v79, v102
	v_mul_f32_e32 v74, v74, v103
	v_mul_f32_e32 v75, v75, v103
	v_mul_f32_e32 v70, v70, v102
	v_mul_f32_e32 v71, v71, v102
	v_mul_f32_e32 v66, v66, v103
	v_mul_f32_e32 v67, v67, v103
	v_mul_f32_e32 v80, v80, v102
	v_mul_f32_e32 v81, v81, v102
	v_cvt_pk_bf16_f32 v78, v78, v79
	v_cvt_pk_bf16_f32 v79, v80, v81
	v_mov_b32_e32 v156, v78
	v_mov_b32_e32 v157, v79
; #define EPI_LOOP(...) _Pragma("unroll") for(int ai=0;ai<2;++ai) _Pragma("unroll") for(int bj=0;bj<2;++bj) \
;   _Pragma("unroll") for(int m=0;m<4;++m) _Pragma("unroll") for(int n=0;n<2;++n) { \
;     const int row=brow+ai*128+wr*64+m*16+fq*4; const int col=bcol+bj*128+wc*32+n*16+fr; \
;     f32x4& v=acc[ai][bj][m][n]; __VA_ARGS__ if (n == 1 && (m & 1)) __builtin_amdgcn_sched_barrier(0); }
; DEVI void run_phase(const int ph, const Params& P, char* shmc, const int wave_u) {
;     ...
;       if (brow < 1024) {
;         EPI_LOOP({ const float sc = sc4[bj][n] * SB_C; st_bf4(sbq + (long)col * 1024 + row, v[0] * sc, v[1] * sc, v[2] * sc, v[3] * sc); })
	v_lshl_add_u64 v[170:171], v[100:101], 0, v[174:175]
	v_mul_f32_e32 v76, v76, v103
	v_mul_f32_e32 v77, v77, v103
	v_cvt_pk_bf16_f32 v74, v74, v75
	v_cvt_pk_bf16_f32 v75, v76, v77
	v_mov_b32_e32 v160, v74
	v_mov_b32_e32 v161, v75
	v_lshl_add_u64 v[172:173], v[96:97], 0, v[174:175]
	v_mul_f32_e32 v72, v72, v102
	v_mul_f32_e32 v73, v73, v102
	v_cvt_pk_bf16_f32 v70, v70, v71
	v_cvt_pk_bf16_f32 v71, v72, v73
	v_mov_b32_e32 v158, v70
	v_mov_b32_e32 v159, v71
	s_nop 1
	v_permlane16_swap_b32_e32 v156, v158
	v_permlane16_swap_b32_e32 v157, v159
	global_store_dwordx4 v[170:171], v[156:159], off offset:64
	v_mul_f32_e32 v68, v68, v103
	v_mul_f32_e32 v69, v69, v103
	v_cvt_pk_bf16_f32 v66, v66, v67
	v_cvt_pk_bf16_f32 v67, v68, v69
	v_mov_b32_e32 v162, v66
	v_mov_b32_e32 v163, v67
	s_nop 1
	v_permlane16_swap_b32_e32 v160, v162
	v_permlane16_swap_b32_e32 v161, v163
	global_store_dwordx4 v[172:173], v[160:163], off offset:64
	v_add_u32_e32 v66, 0x80, v130
	v_ashrrev_i32_e32 v67, 31, v66
	v_lshl_add_u64 v[66:67], v[66:67], 1, s[82:83]
	v_mul_f32_e32 v62, v62, v32
	v_mul_f32_e32 v63, v63, v32
	v_lshl_add_u64 v[68:69], v[66:67], 0, v[132:133]
	v_mul_f32_e32 v64, v64, v32
	v_mul_f32_e32 v65, v65, v32
	v_cvt_pk_bf16_f32 v62, v62, v63
	v_cvt_pk_bf16_f32 v63, v64, v65
	v_mul_f32_e32 v58, v58, v131
	v_mov_b32_e32 v148, v62
	v_mov_b32_e32 v149, v63
	v_lshl_add_u64 v[164:165], v[68:69], 0, v[174:175]
	v_lshl_add_u64 v[62:63], v[66:67], 0, v[126:127]
	v_mul_f32_e32 v59, v59, v131
	v_cvt_pk_bf16_f32 v58, v58, v59
	v_mul_f32_e32 v60, v60, v131
	v_mul_f32_e32 v61, v61, v131
	v_cvt_pk_bf16_f32 v59, v60, v61
	v_mov_b32_e32 v152, v58
	v_mov_b32_e32 v153, v59
	v_lshl_add_u64 v[166:167], v[62:63], 0, v[174:175]
	v_add_u32_e32 v58, 0x90, v130
	v_ashrrev_i32_e32 v59, 31, v58
	v_lshl_add_u64 v[58:59], v[58:59], 1, s[82:83]
	v_mul_f32_e32 v54, v54, v32
	v_mul_f32_e32 v55, v55, v32
	v_lshl_add_u64 v[60:61], v[58:59], 0, v[132:133]
	v_mul_f32_e32 v56, v56, v32
	v_mul_f32_e32 v57, v57, v32
	v_cvt_pk_bf16_f32 v54, v54, v55
	v_cvt_pk_bf16_f32 v55, v56, v57
	v_mov_b32_e32 v150, v54
	v_mov_b32_e32 v151, v55
	s_nop 1
	v_permlane16_swap_b32_e32 v148, v150
	v_permlane16_swap_b32_e32 v149, v151
	global_store_dwordx4 v[164:165], v[148:151], off
	v_lshl_add_u64 v[54:55], v[58:59], 0, v[126:127]
	v_mul_f32_e32 v50, v50, v131
	v_mul_f32_e32 v51, v51, v131
	v_mul_f32_e32 v52, v52, v131
	v_mul_f32_e32 v53, v53, v131
	v_cvt_pk_bf16_f32 v50, v50, v51
	v_cvt_pk_bf16_f32 v51, v52, v53
	v_mov_b32_e32 v154, v50
	v_mov_b32_e32 v155, v51
	s_nop 1
	v_permlane16_swap_b32_e32 v152, v154
	v_permlane16_swap_b32_e32 v153, v155
	global_store_dwordx4 v[166:167], v[152:155], off
	v_add_u32_e32 v50, 0xa0, v130
	v_ashrrev_i32_e32 v51, 31, v50
	v_lshl_add_u64 v[50:51], v[50:51], 1, s[82:83]
	v_mul_f32_e32 v46, v46, v32
	v_mul_f32_e32 v47, v47, v32
	v_lshl_add_u64 v[52:53], v[50:51], 0, v[132:133]
	v_mul_f32_e32 v48, v48, v32
	v_mul_f32_e32 v49, v49, v32
	v_cvt_pk_bf16_f32 v46, v46, v47
	v_cvt_pk_bf16_f32 v47, v48, v49
	v_mul_f32_e32 v42, v42, v131
	v_mov_b32_e32 v156, v46
	v_mov_b32_e32 v157, v47
	v_lshl_add_u64 v[170:171], v[52:53], 0, v[174:175]
	v_lshl_add_u64 v[46:47], v[50:51], 0, v[126:127]
	v_mul_f32_e32 v43, v43, v131
	v_cvt_pk_bf16_f32 v42, v42, v43
	v_mul_f32_e32 v44, v44, v131
	v_mul_f32_e32 v45, v45, v131
	v_cvt_pk_bf16_f32 v43, v44, v45
	v_mov_b32_e32 v160, v42
	v_mov_b32_e32 v161, v43
	v_lshl_add_u64 v[172:173], v[46:47], 0, v[174:175]
	v_add_u32_e32 v42, 0xb0, v130
	v_ashrrev_i32_e32 v43, 31, v42
	v_lshl_add_u64 v[42:43], v[42:43], 1, s[82:83]
	v_mul_f32_e32 v38, v38, v32
	v_mul_f32_e32 v39, v39, v32
	v_lshl_add_u64 v[44:45], v[42:43], 0, v[132:133]
	v_mul_f32_e32 v40, v40, v32
; #define EPI_LOOP(...) _Pragma("unroll") for(int ai=0;ai<2;++ai) _Pragma("unroll") for(int bj=0;bj<2;++bj) \
;   _Pragma("unroll") for(int m=0;m<4;++m) _Pragma("unroll") for(int n=0;n<2;++n) { \
;     const int row=brow+ai*128+wr*64+m*16+fq*4; const int col=bcol+bj*128+wc*32+n*16+fr; \
;     f32x4& v=acc[ai][bj][m][n]; __VA_ARGS__ if (n == 1 && (m & 1)) __builtin_amdgcn_sched_barrier(0); }
; DEVI void run_phase(const int ph, const Params& P, char* shmc, const int wave_u) {
;     ...
;       if (brow < 1024) {
;         EPI_LOOP({ const float sc = sc4[bj][n] * SB_C; st_bf4(sbq + (long)col * 1024 + row, v[0] * sc, v[1] * sc, v[2] * sc, v[3] * sc); })
	v_mul_f32_e32 v32, v41, v32
	v_cvt_pk_bf16_f32 v38, v38, v39
	v_cvt_pk_bf16_f32 v39, v40, v32
	v_mov_b32_e32 v158, v38
	v_mov_b32_e32 v159, v39
	s_nop 1
	v_permlane16_swap_b32_e32 v156, v158
	v_permlane16_swap_b32_e32 v157, v159
	global_store_dwordx4 v[170:171], v[156:159], off
	v_lshl_add_u64 v[38:39], v[42:43], 0, v[126:127]
	v_mul_f32_e32 v32, v34, v131
	v_mul_f32_e32 v34, v35, v131
	v_mul_f32_e32 v35, v36, v131
	v_mul_f32_e32 v36, v37, v131
	v_cvt_pk_bf16_f32 v34, v32, v34
	v_cvt_pk_bf16_f32 v35, v35, v36
	v_mov_b32_e32 v162, v34
	v_mov_b32_e32 v163, v35
	s_nop 1
	v_permlane16_swap_b32_e32 v160, v162
	v_permlane16_swap_b32_e32 v161, v163
	global_store_dwordx4 v[172:173], v[160:163], off
	v_mul_f32_e32 v28, v28, v102
	v_mul_f32_e32 v29, v29, v102
	v_lshl_add_u64 v[34:35], v[66:67], 0, v[98:99]
	v_mul_f32_e32 v30, v30, v102
	v_mul_f32_e32 v31, v31, v102
	v_cvt_pk_bf16_f32 v28, v28, v29
	v_cvt_pk_bf16_f32 v29, v30, v31
	v_mul_f32_e32 v24, v24, v103
	v_mul_f32_e32 v25, v25, v103
	v_mov_b32_e32 v148, v28
	v_mov_b32_e32 v149, v29
	v_lshl_add_u64 v[164:165], v[34:35], 0, v[174:175]
	v_lshl_add_u64 v[28:29], v[66:67], 0, v[94:95]
	v_mul_f32_e32 v26, v26, v103
	v_mul_f32_e32 v27, v27, v103
	v_cvt_pk_bf16_f32 v24, v24, v25
	v_cvt_pk_bf16_f32 v25, v26, v27
	v_mul_f32_e32 v20, v20, v102
	v_mul_f32_e32 v21, v21, v102
	v_mov_b32_e32 v152, v24
	v_mov_b32_e32 v153, v25
	v_lshl_add_u64 v[166:167], v[28:29], 0, v[174:175]
	v_lshl_add_u64 v[24:25], v[58:59], 0, v[98:99]
	v_mul_f32_e32 v22, v22, v102
	v_mul_f32_e32 v23, v23, v102
	v_cvt_pk_bf16_f32 v20, v20, v21
	v_cvt_pk_bf16_f32 v21, v22, v23
	v_mov_b32_e32 v150, v20
	v_mov_b32_e32 v151, v21
	s_nop 1
	v_permlane16_swap_b32_e32 v148, v150
	v_permlane16_swap_b32_e32 v149, v151
	global_store_dwordx4 v[164:165], v[148:151], off
	v_lshl_add_u64 v[20:21], v[58:59], 0, v[94:95]
	v_mul_f32_e32 v16, v16, v103
	v_mul_f32_e32 v17, v17, v103
	v_mul_f32_e32 v18, v18, v103
	v_mul_f32_e32 v19, v19, v103
	v_cvt_pk_bf16_f32 v16, v16, v17
	v_cvt_pk_bf16_f32 v17, v18, v19
	v_mov_b32_e32 v154, v16
	v_mov_b32_e32 v155, v17
	s_nop 1
	v_permlane16_swap_b32_e32 v152, v154
	v_permlane16_swap_b32_e32 v153, v155
	global_store_dwordx4 v[166:167], v[152:155], off
	v_mul_f32_e32 v12, v12, v102
	v_mul_f32_e32 v13, v13, v102
	v_lshl_add_u64 v[16:17], v[50:51], 0, v[98:99]
	v_mul_f32_e32 v14, v14, v102
	v_mul_f32_e32 v15, v15, v102
	v_cvt_pk_bf16_f32 v12, v12, v13
	v_cvt_pk_bf16_f32 v13, v14, v15
	v_mul_f32_e32 v8, v8, v103
	v_mul_f32_e32 v9, v9, v103
	v_mov_b32_e32 v156, v12
	v_mov_b32_e32 v157, v13
	v_lshl_add_u64 v[170:171], v[16:17], 0, v[174:175]
	v_lshl_add_u64 v[12:13], v[50:51], 0, v[94:95]
	v_mul_f32_e32 v10, v10, v103
	v_mul_f32_e32 v11, v11, v103
	v_cvt_pk_bf16_f32 v8, v8, v9
	v_cvt_pk_bf16_f32 v9, v10, v11
	v_mul_f32_e32 v4, v4, v102
	v_mul_f32_e32 v5, v5, v102
	v_mov_b32_e32 v160, v8
	v_mov_b32_e32 v161, v9
	v_lshl_add_u64 v[172:173], v[12:13], 0, v[174:175]
	v_lshl_add_u64 v[8:9], v[42:43], 0, v[98:99]
	v_mul_f32_e32 v6, v6, v102
	v_mul_f32_e32 v7, v7, v102
	v_cvt_pk_bf16_f32 v4, v4, v5
	v_cvt_pk_bf16_f32 v5, v6, v7
	v_mov_b32_e32 v158, v4
	v_mov_b32_e32 v159, v5
	s_nop 1
	v_permlane16_swap_b32_e32 v156, v158
	v_permlane16_swap_b32_e32 v157, v159
	global_store_dwordx4 v[170:171], v[156:159], off
	v_lshl_add_u64 v[4:5], v[42:43], 0, v[94:95]
	v_mul_f32_e32 v0, v0, v103
	v_mul_f32_e32 v1, v1, v103
	v_mul_f32_e32 v2, v2, v103
	v_mul_f32_e32 v3, v3, v103
	v_cvt_pk_bf16_f32 v0, v0, v1
	v_cvt_pk_bf16_f32 v1, v2, v3
	v_mov_b32_e32 v162, v0
	v_mov_b32_e32 v163, v1
	s_nop 1
	v_permlane16_swap_b32_e32 v160, v162
	v_permlane16_swap_b32_e32 v161, v163
	global_store_dwordx4 v[172:173], v[160:163], off
	s_branch .LBB0_966

; DEVI void convert_job(const float* __restrict__ src, bf16* __restrict__ dst, long total, long blen, long dstb, const int wave_u,
;                       const int vb, const int nvb) {
;     ...
;   for (long i0 = ((long)vb * 512 + tidc) * 8; i0 < total; i0 += step * 4) {
;     f32x4 a[4], c[4];
; #pragma unroll
;     for (int u = 0; u < 4; ++u) { const long i = i0 + u * step;
;       if (i < total) { a[u] = *(const f32x4*)(src + i); c[u] = *(const f32x4*)(src + i + 4); } }
; #pragma unroll
;     for (int u = 0; u < 4; ++u) { const long i = i0 + u * step;
;       if (i < total) { const long b = i / blen, off = i - b * blen;
;         u32x4 w = {cvtpk(a[u][0], a[u][1]), cvtpk(a[u][2], a[u][3]), cvtpk(c[u][0], c[u][1]), cvtpk(c[u][2], c[u][3])};
;         *reinterpret_cast<u32x4*>(dst + b * dstb + off) = w; } }
.LBB0_1161:
	s_or_b64 exec, exec, s[70:71]
	v_ashrrev_i32_e32 v32, 31, v51
	v_lshrrev_b32_e32 v32, 12, v32
	v_lshl_add_u64 v[50:51], v[50:51], 0, v[32:33]
	v_ashrrev_i64 v[50:51], 20, v[50:51]
	s_waitcnt vmcnt(0)
	v_cvt_pk_bf16_f32 v28, v28, v29
	v_cvt_pk_bf16_f32 v29, v30, v31
	v_cvt_pk_bf16_f32 v30, v24, v25
	v_cvt_pk_bf16_f32 v31, v26, v27
	v_lshlrev_b64 v[24:25], 17, v[50:51]
	v_lshl_add_u64 v[26:27], s[68:69], 0, v[40:41]
	v_lshl_add_u64 v[24:25], v[26:27], 0, v[24:25]
	v_add_co_u32_e32 v24, vcc, 0xc0c8000, v24
	s_nop 1
	v_addc_co_u32_e32 v25, vcc, 0, v25, vcc
	global_store_dwordx4 v[24:25], v[28:31], off
	s_and_saveexec_b64 s[70:71], s[0:1]
	s_cbranch_execz .LBB0_1164
	v_ashrrev_i32_e32 v24, 31, v53
	v_lshrrev_b32_e32 v32, 12, v24
	v_lshl_add_u64 v[24:25], v[52:53], 0, v[32:33]
	v_ashrrev_i64 v[28:29], 20, v[24:25]
	v_lshlrev_b64 v[28:29], 17, v[28:29]
	v_lshl_add_u64 v[30:31], s[68:69], 0, v[34:35]
	v_lshl_add_u64 v[28:29], v[30:31], 0, v[28:29]
	v_cvt_pk_bf16_f32 v24, v0, v1
	v_cvt_pk_bf16_f32 v25, v2, v3
	v_cvt_pk_bf16_f32 v26, v8, v9
	v_cvt_pk_bf16_f32 v27, v10, v11
	global_store_dwordx4 v[28:29], v[24:27], off
	s_or_b64 exec, exec, s[70:71]
	s_and_saveexec_b64 s[0:1], s[6:7]
	s_cbranch_execnz .LBB0_1165

; DEVI void convert_job(const float* __restrict__ src, bf16* __restrict__ dst, long total, long blen, long dstb, const int wave_u,
;                       const int vb, const int nvb) {
;     ...
;   for (long i0 = ((long)vb * 512 + tidc) * 8; i0 < total; i0 += step * 4) {
;     f32x4 a[4], c[4];
; #pragma unroll
;     for (int u = 0; u < 4; ++u) { const long i = i0 + u * step;
;       if (i < total) { a[u] = *(const f32x4*)(src + i); c[u] = *(const f32x4*)(src + i + 4); } }
; #pragma unroll
;     for (int u = 0; u < 4; ++u) { const long i = i0 + u * step;
;       if (i < total) { const long b = i / blen, off = i - b * blen;
;         u32x4 w = {cvtpk(a[u][0], a[u][1]), cvtpk(a[u][2], a[u][3]), cvtpk(c[u][0], c[u][1]), cvtpk(c[u][2], c[u][3])};
;         *reinterpret_cast<u32x4*>(dst + b * dstb + off) = w; } }
.LBB0_1165:
	v_ashrrev_i32_e32 v24, 31, v55
	v_lshrrev_b32_e32 v32, 12, v24
	v_lshl_add_u64 v[24:25], v[54:55], 0, v[32:33]
	v_ashrrev_i64 v[28:29], 20, v[24:25]
	v_lshlrev_b64 v[28:29], 17, v[28:29]
	v_lshl_add_u64 v[30:31], s[68:69], 0, v[42:43]
	v_lshl_add_u64 v[28:29], v[30:31], 0, v[28:29]
	v_cvt_pk_bf16_f32 v24, v4, v5
	v_cvt_pk_bf16_f32 v25, v6, v7
	v_cvt_pk_bf16_f32 v26, v16, v17
	v_cvt_pk_bf16_f32 v27, v18, v19
	global_store_dwordx4 v[28:29], v[24:27], off
	s_or_b64 exec, exec, s[0:1]
	s_and_saveexec_b64 s[0:1], s[8:9]
	s_cbranch_execz .LBB0_1154
.LBB0_1166:
	v_ashrrev_i32_e32 v24, 31, v57
	v_lshrrev_b32_e32 v32, 12, v24
	v_lshl_add_u64 v[24:25], v[56:57], 0, v[32:33]
	v_ashrrev_i64 v[28:29], 20, v[24:25]
	v_lshlrev_b64 v[28:29], 17, v[28:29]
	v_lshl_add_u64 v[30:31], s[68:69], 0, v[48:49]
	v_lshl_add_u64 v[28:29], v[30:31], 0, v[28:29]
	v_cvt_pk_bf16_f32 v24, v12, v13
	v_cvt_pk_bf16_f32 v25, v14, v15
	v_cvt_pk_bf16_f32 v26, v20, v21
	v_cvt_pk_bf16_f32 v27, v22, v23
	global_store_dwordx4 v[28:29], v[24:27], off
	s_branch .LBB0_1154

; DEVI void convert_job(const float* __restrict__ src, bf16* __restrict__ dst, long total, long blen, long dstb, const int wave_u,
;                       const int vb, const int nvb) {
;     ...
;   for (long i0 = ((long)vb * 512 + tidc) * 8; i0 < total; i0 += step * 4) {
;     f32x4 a[4], c[4];
; #pragma unroll
;     for (int u = 0; u < 4; ++u) { const long i = i0 + u * step;
;       if (i < total) { a[u] = *(const f32x4*)(src + i); c[u] = *(const f32x4*)(src + i + 4); } }
; #pragma unroll
;     for (int u = 0; u < 4; ++u) { const long i = i0 + u * step;
;       if (i < total) { const long b = i / blen, off = i - b * blen;
;         u32x4 w = {cvtpk(a[u][0], a[u][1]), cvtpk(a[u][2], a[u][3]), cvtpk(c[u][0], c[u][1]), cvtpk(c[u][2], c[u][3])};
;         *reinterpret_cast<u32x4*>(dst + b * dstb + off) = w; } }
.LBB0_1176:
	s_or_b64 exec, exec, s[70:71]
	v_ashrrev_i32_e32 v32, 31, v51
	v_lshrrev_b32_e32 v32, 12, v32
	v_lshl_add_u64 v[50:51], v[50:51], 0, v[32:33]
	v_ashrrev_i64 v[50:51], 20, v[50:51]
	s_waitcnt vmcnt(0)
	v_cvt_pk_bf16_f32 v28, v28, v29
	v_cvt_pk_bf16_f32 v29, v30, v31
	v_cvt_pk_bf16_f32 v30, v24, v25
	v_cvt_pk_bf16_f32 v31, v26, v27
	v_lshlrev_b64 v[24:25], 17, v[50:51]
	v_lshl_add_u64 v[26:27], s[68:69], 0, v[40:41]
	v_lshl_add_u64 v[24:25], v[26:27], 0, v[24:25]
	v_add_co_u32_e32 v24, vcc, 0x102c8000, v24
	s_nop 1
	v_addc_co_u32_e32 v25, vcc, 0, v25, vcc
	global_store_dwordx4 v[24:25], v[28:31], off
	s_and_saveexec_b64 s[70:71], s[0:1]
	s_cbranch_execz .LBB0_1179
	v_ashrrev_i32_e32 v24, 31, v53
	v_lshrrev_b32_e32 v32, 12, v24
	v_lshl_add_u64 v[24:25], v[52:53], 0, v[32:33]
	v_ashrrev_i64 v[28:29], 20, v[24:25]
	v_lshlrev_b64 v[28:29], 17, v[28:29]
	v_lshl_add_u64 v[30:31], s[68:69], 0, v[34:35]
	v_lshl_add_u64 v[28:29], v[30:31], 0, v[28:29]
	v_cvt_pk_bf16_f32 v24, v0, v1
	v_cvt_pk_bf16_f32 v25, v2, v3
	v_cvt_pk_bf16_f32 v26, v8, v9
	v_cvt_pk_bf16_f32 v27, v10, v11
	global_store_dwordx4 v[28:29], v[24:27], off
	s_or_b64 exec, exec, s[70:71]
	s_and_saveexec_b64 s[0:1], s[6:7]
	s_cbranch_execnz .LBB0_1180

; DEVI void convert_job(const float* __restrict__ src, bf16* __restrict__ dst, long total, long blen, long dstb, const int wave_u,
;                       const int vb, const int nvb) {
;     ...
;   for (long i0 = ((long)vb * 512 + tidc) * 8; i0 < total; i0 += step * 4) {
;     f32x4 a[4], c[4];
; #pragma unroll
;     for (int u = 0; u < 4; ++u) { const long i = i0 + u * step;
;       if (i < total) { a[u] = *(const f32x4*)(src + i); c[u] = *(const f32x4*)(src + i + 4); } }
; #pragma unroll
;     for (int u = 0; u < 4; ++u) { const long i = i0 + u * step;
;       if (i < total) { const long b = i / blen, off = i - b * blen;
;         u32x4 w = {cvtpk(a[u][0], a[u][1]), cvtpk(a[u][2], a[u][3]), cvtpk(c[u][0], c[u][1]), cvtpk(c[u][2], c[u][3])};
;         *reinterpret_cast<u32x4*>(dst + b * dstb + off) = w; } }
.LBB0_1191:
	s_or_b64 exec, exec, s[8:9]
	v_ashrrev_i32_e32 v32, 31, v43
	v_lshrrev_b32_e32 v32, 9, v32
	v_lshl_add_u64 v[50:51], v[42:43], 0, v[32:33]
	v_and_b32_e32 v50, 0xff800000, v50
	v_and_b32_e32 v32, 0x7fffffff, v51
	v_sub_co_u32_e64 v42, s[8:9], v42, v50
	s_waitcnt vmcnt(0)
	v_cvt_pk_bf16_f32 v28, v28, v29
	v_cvt_pk_bf16_f32 v29, v30, v31
	v_cvt_pk_bf16_f32 v30, v24, v25
	v_cvt_pk_bf16_f32 v31, v26, v27
	s_nop 0
	v_subb_co_u32_e64 v43, s[8:9], v43, v32, s[8:9]
	v_lshl_add_u64 v[24:25], v[42:43], 1, s[38:39]
	global_store_dwordx4 v[24:25], v[28:31], off
	s_and_saveexec_b64 s[8:9], vcc
	s_cbranch_execz .LBB0_1194
	v_ashrrev_i32_e32 v24, 31, v45
	v_lshrrev_b32_e32 v32, 9, v24
	v_lshl_add_u64 v[24:25], v[44:45], 0, v[32:33]
	v_and_b32_e32 v24, 0xff800000, v24
	v_and_b32_e32 v25, 0x7fffffff, v25
	v_sub_co_u32_e32 v28, vcc, v44, v24
	v_cvt_pk_bf16_f32 v24, v0, v1
	s_nop 1
	v_subb_co_u32_e32 v29, vcc, v45, v25, vcc
	v_lshl_add_u64 v[28:29], v[28:29], 1, s[38:39]
	v_cvt_pk_bf16_f32 v25, v2, v3
	v_cvt_pk_bf16_f32 v26, v8, v9
	v_cvt_pk_bf16_f32 v27, v10, v11
	global_store_dwordx4 v[28:29], v[24:27], off
	s_or_b64 exec, exec, s[8:9]
	s_and_saveexec_b64 s[8:9], s[0:1]
	s_cbranch_execnz .LBB0_1195

; DEVI void convert_job(const float* __restrict__ src, bf16* __restrict__ dst, long total, long blen, long dstb, const int wave_u,
;                       const int vb, const int nvb) {
;     ...
;   for (long i0 = ((long)vb * 512 + tidc) * 8; i0 < total; i0 += step * 4) {
;     f32x4 a[4], c[4];
; #pragma unroll
;     for (int u = 0; u < 4; ++u) { const long i = i0 + u * step;
;       if (i < total) { a[u] = *(const f32x4*)(src + i); c[u] = *(const f32x4*)(src + i + 4); } }
; #pragma unroll
;     for (int u = 0; u < 4; ++u) { const long i = i0 + u * step;
;       if (i < total) { const long b = i / blen, off = i - b * blen;
;         u32x4 w = {cvtpk(a[u][0], a[u][1]), cvtpk(a[u][2], a[u][3]), cvtpk(c[u][0], c[u][1]), cvtpk(c[u][2], c[u][3])};
;         *reinterpret_cast<u32x4*>(dst + b * dstb + off) = w; } }
.LBB0_1195:
	v_ashrrev_i32_e32 v24, 31, v47
	v_lshrrev_b32_e32 v32, 9, v24
	v_lshl_add_u64 v[24:25], v[46:47], 0, v[32:33]
	v_and_b32_e32 v24, 0xff800000, v24
	v_and_b32_e32 v25, 0x7fffffff, v25
	v_sub_co_u32_e32 v28, vcc, v46, v24
	v_cvt_pk_bf16_f32 v24, v4, v5
	s_nop 1
	v_subb_co_u32_e32 v29, vcc, v47, v25, vcc
	v_lshl_add_u64 v[28:29], v[28:29], 1, s[38:39]
	v_cvt_pk_bf16_f32 v25, v6, v7
	v_cvt_pk_bf16_f32 v26, v16, v17
	v_cvt_pk_bf16_f32 v27, v18, v19
	global_store_dwordx4 v[28:29], v[24:27], off
	s_or_b64 exec, exec, s[8:9]
	s_and_saveexec_b64 s[0:1], s[6:7]
	s_cbranch_execz .LBB0_1184
.LBB0_1196:
	v_ashrrev_i32_e32 v24, 31, v49
	v_lshrrev_b32_e32 v32, 9, v24
	v_lshl_add_u64 v[24:25], v[48:49], 0, v[32:33]
	v_and_b32_e32 v24, 0xff800000, v24
	v_and_b32_e32 v25, 0x7fffffff, v25
	v_sub_co_u32_e32 v28, vcc, v48, v24
	v_cvt_pk_bf16_f32 v24, v12, v13
	s_nop 1
	v_subb_co_u32_e32 v29, vcc, v49, v25, vcc
	v_lshl_add_u64 v[28:29], v[28:29], 1, s[38:39]
	v_cvt_pk_bf16_f32 v25, v14, v15
	v_cvt_pk_bf16_f32 v26, v20, v21
	v_cvt_pk_bf16_f32 v27, v22, v23
	global_store_dwordx4 v[28:29], v[24:27], off
	s_branch .LBB0_1184

; DEVI void convert_job(const float* __restrict__ src, bf16* __restrict__ dst, long total, long blen, long dstb, const int wave_u,
;                       const int vb, const int nvb) {
;     ...
;   for (long i0 = ((long)vb * 512 + tidc) * 8; i0 < total; i0 += step * 4) {
;     f32x4 a[4], c[4];
; #pragma unroll
;     for (int u = 0; u < 4; ++u) { const long i = i0 + u * step;
;       if (i < total) { a[u] = *(const f32x4*)(src + i); c[u] = *(const f32x4*)(src + i + 4); } }
; #pragma unroll
;     for (int u = 0; u < 4; ++u) { const long i = i0 + u * step;
;       if (i < total) { const long b = i / blen, off = i - b * blen;
;         u32x4 w = {cvtpk(a[u][0], a[u][1]), cvtpk(a[u][2], a[u][3]), cvtpk(c[u][0], c[u][1]), cvtpk(c[u][2], c[u][3])};
;         *reinterpret_cast<u32x4*>(dst + b * dstb + off) = w; } }
.LBB0_1206:
	s_or_b64 exec, exec, s[68:69]
	v_ashrrev_i32_e32 v32, 31, v51
	v_lshrrev_b32_e32 v32, 16, v32
	v_lshl_add_u64 v[50:51], v[50:51], 0, v[32:33]
	v_ashrrev_i64 v[50:51], 16, v[50:51]
	s_waitcnt vmcnt(0)
	v_cvt_pk_bf16_f32 v28, v28, v29
	v_cvt_pk_bf16_f32 v29, v30, v31
	v_cvt_pk_bf16_f32 v30, v24, v25
	v_cvt_pk_bf16_f32 v31, v26, v27
	v_lshlrev_b64 v[24:25], 13, v[50:51]
	v_lshl_add_u64 v[26:27], s[66:67], 0, v[40:41]
	v_lshl_add_u64 v[24:25], v[26:27], 0, v[24:25]
	v_add_co_u32_e32 v24, vcc, 0x1dbc8000, v24
	s_nop 1
	v_addc_co_u32_e32 v25, vcc, 0, v25, vcc
	global_store_dwordx4 v[24:25], v[28:31], off
	s_and_saveexec_b64 s[68:69], s[0:1]
	s_cbranch_execz .LBB0_1209
	v_ashrrev_i32_e32 v24, 31, v53
	v_lshrrev_b32_e32 v32, 16, v24
	v_lshl_add_u64 v[24:25], v[52:53], 0, v[32:33]
	v_ashrrev_i64 v[28:29], 16, v[24:25]
	v_lshlrev_b64 v[28:29], 13, v[28:29]
	v_lshl_add_u64 v[30:31], s[66:67], 0, v[34:35]
	v_lshl_add_u64 v[28:29], v[30:31], 0, v[28:29]
	v_cvt_pk_bf16_f32 v24, v0, v1
	v_cvt_pk_bf16_f32 v25, v2, v3
	v_cvt_pk_bf16_f32 v26, v8, v9
	v_cvt_pk_bf16_f32 v27, v10, v11
	global_store_dwordx4 v[28:29], v[24:27], off
	s_or_b64 exec, exec, s[68:69]
	s_and_saveexec_b64 s[0:1], s[6:7]
	s_cbranch_execnz .LBB0_1210

; DEVI void convert_job(const float* __restrict__ src, bf16* __restrict__ dst, long total, long blen, long dstb, const int wave_u,
;                       const int vb, const int nvb) {
;     ...
;   for (long i0 = ((long)vb * 512 + tidc) * 8; i0 < total; i0 += step * 4) {
;     f32x4 a[4], c[4];
; #pragma unroll
;     for (int u = 0; u < 4; ++u) { const long i = i0 + u * step;
;       if (i < total) { a[u] = *(const f32x4*)(src + i); c[u] = *(const f32x4*)(src + i + 4); } }
; #pragma unroll
;     for (int u = 0; u < 4; ++u) { const long i = i0 + u * step;
;       if (i < total) { const long b = i / blen, off = i - b * blen;
;         u32x4 w = {cvtpk(a[u][0], a[u][1]), cvtpk(a[u][2], a[u][3]), cvtpk(c[u][0], c[u][1]), cvtpk(c[u][2], c[u][3])};
;         *reinterpret_cast<u32x4*>(dst + b * dstb + off) = w; } }
.LBB0_1210:
	v_ashrrev_i32_e32 v24, 31, v55
	v_lshrrev_b32_e32 v32, 16, v24
	v_lshl_add_u64 v[24:25], v[54:55], 0, v[32:33]
	v_ashrrev_i64 v[28:29], 16, v[24:25]
	v_lshlrev_b64 v[28:29], 13, v[28:29]
	v_lshl_add_u64 v[30:31], s[66:67], 0, v[42:43]
	v_lshl_add_u64 v[28:29], v[30:31], 0, v[28:29]
	v_cvt_pk_bf16_f32 v24, v4, v5
	v_cvt_pk_bf16_f32 v25, v6, v7
	v_cvt_pk_bf16_f32 v26, v16, v17
	v_cvt_pk_bf16_f32 v27, v18, v19
	global_store_dwordx4 v[28:29], v[24:27], off
	s_or_b64 exec, exec, s[0:1]
	s_and_saveexec_b64 s[0:1], s[8:9]
	s_cbranch_execz .LBB0_1199
.LBB0_1211:
	v_ashrrev_i32_e32 v24, 31, v57
	v_lshrrev_b32_e32 v32, 16, v24
	v_lshl_add_u64 v[24:25], v[56:57], 0, v[32:33]
	v_ashrrev_i64 v[28:29], 16, v[24:25]
	v_lshlrev_b64 v[28:29], 13, v[28:29]
	v_lshl_add_u64 v[30:31], s[66:67], 0, v[48:49]
	v_lshl_add_u64 v[28:29], v[30:31], 0, v[28:29]
	v_cvt_pk_bf16_f32 v24, v12, v13
	v_cvt_pk_bf16_f32 v25, v14, v15
	v_cvt_pk_bf16_f32 v26, v20, v21
	v_cvt_pk_bf16_f32 v27, v22, v23
	global_store_dwordx4 v[28:29], v[24:27], off
	s_branch .LBB0_1199

; DEVI void run_phase(const int ph, const Params& P, char* shmc, const int wave_u) {
;     ...
;     for (int i = blockIdx.x * 512 + tq; i < MS * 2048 / 4; i += G * 512) {
;       const long o = (long)i * 4;
;       f32x4 sacc = *(const f32x4*)(Mp + o);
; #pragma unroll
;       for (int sl = 1; sl < 8; ++sl) { const f32x4 x = *(const f32x4*)(Mp + (long)sl * MS * 2048 + o); sacc[0] += x[0]; sacc[1] += x[1]; sacc[2] += x[2]; sacc[3] += x[3]; }
;       st_bf4(merged + (long)MP * 2048 + o, sacc[0], sacc[1], sacc[2], sacc[3]);
;     }
.LBB0_1254:
	v_lshl_add_u64 v[6:7], s[0:1], 0, v[4:5]
	v_add_co_u32_e32 v8, vcc, 0x124c8000, v6
	s_mov_b32 s4, 0x12cc8000
	s_nop 0
	v_addc_co_u32_e32 v9, vcc, 0, v7, vcc
	v_add_co_u32_e32 v12, vcc, 0x128c8000, v6
	global_load_dwordx4 v[8:11], v[8:9], off
	s_nop 0
	v_addc_co_u32_e32 v13, vcc, 0, v7, vcc
	global_load_dwordx4 v[12:15], v[12:13], off
	v_add_u32_e32 v0, s12, v0
	v_lshl_add_u64 v[4:5], v[4:5], 0, s[18:19]
	s_waitcnt vmcnt(0) lgkmcnt(0)
	v_add_f32_e32 v1, v8, v12
	v_add_co_u32_e32 v8, vcc, s4, v6
	v_add_f32_e32 v12, v9, v13
	s_nop 0
	v_addc_co_u32_e32 v9, vcc, 0, v7, vcc
	v_add_f32_e32 v13, v10, v14
	v_add_f32_e32 v14, v11, v15
	global_load_dwordx4 v[8:11], v[8:9], off
	s_mov_b32 s4, 0x130c8000
	s_waitcnt vmcnt(0) lgkmcnt(0)
	v_add_f32_e32 v1, v1, v8
	v_add_co_u32_e32 v8, vcc, s4, v6
	v_add_f32_e32 v12, v12, v9
	s_nop 0
	v_addc_co_u32_e32 v9, vcc, 0, v7, vcc
	v_add_f32_e32 v13, v13, v10
	v_add_f32_e32 v14, v14, v11
	global_load_dwordx4 v[8:11], v[8:9], off
	s_mov_b32 s4, 0x134c8000
	s_waitcnt vmcnt(0) lgkmcnt(0)
	v_add_f32_e32 v1, v1, v8
	v_add_co_u32_e32 v8, vcc, s4, v6
	v_add_f32_e32 v12, v12, v9
	s_nop 0
	v_addc_co_u32_e32 v9, vcc, 0, v7, vcc
	v_add_f32_e32 v13, v13, v10
	v_add_f32_e32 v14, v14, v11
	global_load_dwordx4 v[8:11], v[8:9], off
	s_mov_b32 s4, 0x138c8000
	s_waitcnt vmcnt(0) lgkmcnt(0)
	v_add_f32_e32 v1, v1, v8
	v_add_co_u32_e32 v8, vcc, s4, v6
	v_add_f32_e32 v12, v12, v9
	s_nop 0
	v_addc_co_u32_e32 v9, vcc, 0, v7, vcc
	v_add_f32_e32 v13, v13, v10
	v_add_f32_e32 v14, v14, v11
	global_load_dwordx4 v[8:11], v[8:9], off
	s_mov_b32 s4, 0x13cc8000
	s_waitcnt vmcnt(0) lgkmcnt(0)
	v_add_f32_e32 v1, v1, v8
	v_add_co_u32_e32 v8, vcc, s4, v6
	v_add_f32_e32 v12, v12, v9
	s_nop 0
	v_addc_co_u32_e32 v9, vcc, 0, v7, vcc
	v_add_f32_e32 v13, v13, v10
	v_add_f32_e32 v14, v14, v11
	global_load_dwordx4 v[8:11], v[8:9], off
	s_mov_b32 s4, 0x140c8000
	v_add_co_u32_e32 v6, vcc, s4, v6
	s_mov_b32 s4, 0x3ffff
	s_nop 0
	v_addc_co_u32_e32 v7, vcc, 0, v7, vcc
	v_cmp_lt_i32_e32 vcc, s4, v0
	s_or_b64 s[8:9], vcc, s[8:9]
	s_waitcnt vmcnt(0) lgkmcnt(0)
	v_add_f32_e32 v1, v1, v8
	v_add_f32_e32 v12, v12, v9
	global_load_dwordx4 v[6:9], v[6:7], off
	v_add_f32_e32 v11, v14, v11
	v_add_f32_e32 v10, v13, v10
	s_waitcnt vmcnt(0) lgkmcnt(0)
	v_add_f32_e32 v1, v1, v6
	v_add_f32_e32 v12, v12, v7
	v_add_f32_e32 v9, v11, v9
	v_lshl_add_u64 v[6:7], s[0:1], 0, v[2:3]
	v_lshl_add_u64 v[2:3], v[2:3], 0, s[16:17]
	v_add_f32_e32 v10, v10, v8
	v_cvt_pk_bf16_f32 v8, v1, v12
	v_cvt_pk_bf16_f32 v9, v10, v9
	global_store_dwordx2 v[6:7], v[8:9], off
	s_andn2_b64 exec, exec, s[8:9]
	s_cbranch_execnz .LBB0_1254
